# K-loop rescheduling in all GEMMs + LDS-DMA staging for the up-projection GEMM + s_setprio 1 during K-loops
# speedup vs baseline: 1.0207x; 1.0066x over previous
; DI int BIDX() { int b = blockIdx.x; asm volatile("" : "+s"(b)); return b; }
; DI int tile_groups(int MT, int NT) { return (MT >> 6) * ((NT + 7) >> 3) * 512; }
; DI void load_rstd(float (&rs)[4], const float* ssq, int row0, int lr) {
; #pragma unroll
;   for (int mt = 0; mt < 4; ++mt) {
;     const float4* q = (const float4*)(ssq + (size_t)(row0 + mt * 16 + lr) * 16);
;     const float4 a = q[0], b = q[1], c = q[2], d = q[3];
;     const float s = ((a.x + a.y) + (a.z + a.w)) + ((b.x + b.y) + (b.z + b.w)) + ((c.x + c.y) + (c.z + c.w)) + ((d.x + d.y) + (d.z + d.w));
;     rs[mt] = rsqrtf(s * (1.0f / 1024.0f) + EPS);
;   }
; }
; DI void phase_proj(const Params& P, int l, char* smem) {
;     ...
;   for (int vb = BIDX(); vb < tile_groups(128, 63); vb += gridDim.x) {
;     int tm, tn; if (!tile_of(vb, 128, 63, tm, tn)) continue;
;     const int m0 = tm * 128, n0 = tn * 128;
;     f32x4 acc[4][4]; zero_acc(acc);
;     const int row0 = m0 + wm * 64, col0 = n0 + wn * 64;
;     float rs[4]; load_rstd(rs, ssq, row0, lr);
;     if (n0 >= PW) {
.LBB0_637:
	s_ashr_i32 s1, s28, 9
	s_lshr_b32 s2, s1, 29
	s_add_i32 s2, s1, s2
	s_lshl_b32 s2, s2, 3
	s_and_b32 s4, s2, 0xffffffc0
	s_and_b32 s2, s26, 56
	s_bfe_u32 s5, s28, 0x30003
	s_or_b32 s2, s2, s5
	s_lshl_b32 s1, s1, 3
	s_or_b32 s2, s2, s4
	s_sub_i32 s1, s1, s4
	s_bfe_u32 s4, s28, 0x30006
	s_or_b32 s1, s1, s4
	s_cmpk_lt_i32 s2, 0x80
	s_cselect_b64 s[4:5], -1, 0
	s_cmp_lt_i32 s1, 63
	s_cselect_b64 s[16:17], -1, 0
	s_and_b64 s[4:5], s[4:5], s[16:17]
	s_andn2_b64 vcc, exec, s[4:5]
	s_cbranch_vccnz .LBB0_636
	s_lshl_b32 s18, s2, 7
	v_add_u32_e32 v99, s18, v101
	s_waitcnt vmcnt(0)
	v_or_b32_e32 v70, v99, v97
	v_ashrrev_i32_e32 v71, 31, v70
	v_readlane_b32 s20, v253, 13
	v_lshlrev_b64 v[0:1], 6, v[70:71]
	v_readlane_b32 s21, v253, 14
	v_or_b32_e32 v68, 16, v70
	v_ashrrev_i32_e32 v69, 31, v68
	v_lshl_add_u64 v[12:13], s[20:21], 0, v[0:1]
	global_load_dwordx4 v[0:3], v[12:13], off offset:48
	global_load_dwordx4 v[4:7], v[12:13], off offset:32
	global_load_dwordx4 v[8:11], v[12:13], off offset:16
	s_nop 0
	global_load_dwordx4 v[12:15], v[12:13], off
	s_mov_b32 s2, 0x358637bd
	s_mov_b32 s22, 0x3a800000
	v_or_b32_e32 v66, 32, v70
	v_ashrrev_i32_e32 v67, 31, v66
	v_or_b32_e32 v64, 48, v70
	v_ashrrev_i32_e32 v65, 31, v64
	s_ashr_i32 s19, s18, 31
	s_lshl_b32 s16, s1, 7
	v_or_b32_e32 v94, s16, v85
	s_waitcnt vmcnt(1)
	v_mov_b32_e32 v18, v9
	s_waitcnt vmcnt(0)
	v_mov_b32_e32 v16, v13
	v_mov_b32_e32 v17, v14
	v_mov_b32_e32 v19, v10
	v_mov_b32_e32 v13, v15
	v_mov_b32_e32 v9, v11
	v_pk_add_f32 v[12:13], v[16:17], v[12:13]
	v_pk_add_f32 v[8:9], v[18:19], v[8:9]
	v_pk_add_f32 v[10:11], v[12:13], v[12:13] op_sel:[0,1] op_sel_hi:[1,0]
	v_pk_add_f32 v[8:9], v[8:9], v[8:9] op_sel:[0,1] op_sel_hi:[1,0]
	v_mov_b32_e32 v11, v0
	v_mov_b32_e32 v9, v1
	v_pk_add_f32 v[0:1], v[10:11], v[8:9]
	v_mov_b32_e32 v8, v5
	v_pk_add_f32 v[4:5], v[4:5], v[8:9]
	s_nop 0
	v_mov_b32_e32 v5, v2
	v_mov_b32_e32 v2, v7
	v_pk_add_f32 v[6:7], v[6:7], v[2:3]
	s_nop 0
	v_mov_b32_e32 v7, v3
	v_pk_add_f32 v[2:3], v[4:5], v[6:7]
	s_nop 0
	v_pk_add_f32 v[16:17], v[0:1], v[2:3]
	v_lshlrev_b64 v[0:1], 6, v[68:69]
	v_lshl_add_u64 v[12:13], s[20:21], 0, v[0:1]
	global_load_dwordx4 v[0:3], v[12:13], off offset:48
	global_load_dwordx4 v[4:7], v[12:13], off offset:32
	global_load_dwordx4 v[8:11], v[12:13], off offset:16
	s_nop 0
	global_load_dwordx4 v[12:15], v[12:13], off
	s_waitcnt vmcnt(1)
	v_mov_b32_e32 v20, v9
	s_waitcnt vmcnt(0)
	v_mov_b32_e32 v18, v13
	v_mov_b32_e32 v19, v14
	v_mov_b32_e32 v21, v10
	v_mov_b32_e32 v13, v15
	v_mov_b32_e32 v9, v11
	v_pk_add_f32 v[12:13], v[18:19], v[12:13]
	v_pk_add_f32 v[8:9], v[20:21], v[8:9]
	v_pk_add_f32 v[10:11], v[12:13], v[12:13] op_sel:[0,1] op_sel_hi:[1,0]
	v_pk_add_f32 v[8:9], v[8:9], v[8:9] op_sel:[0,1] op_sel_hi:[1,0]
	v_mov_b32_e32 v11, v0
	v_mov_b32_e32 v9, v1
	v_pk_add_f32 v[0:1], v[10:11], v[8:9]
	v_mov_b32_e32 v8, v5
	v_pk_add_f32 v[4:5], v[4:5], v[8:9]
	s_nop 0
	v_mov_b32_e32 v5, v2
	v_mov_b32_e32 v2, v7
	v_pk_add_f32 v[6:7], v[6:7], v[2:3]
	s_nop 0
	v_mov_b32_e32 v7, v3
	v_pk_add_f32 v[2:3], v[4:5], v[6:7]
	s_nop 0
	v_pk_add_f32 v[0:1], v[0:1], v[2:3]
	v_mov_b32_e32 v3, v16
	v_mov_b32_e32 v2, v0
	v_mov_b32_e32 v16, v1
	v_pk_add_f32 v[0:1], v[2:3], v[16:17]
	v_mov_b64_e32 v[16:17], s[2:3]
	v_pk_fma_f32 v[0:1], v[0:1], s[22:23], v[16:17] op_sel_hi:[1,0,0]
	s_mov_b32 s2, 0x800000
	v_mul_f32_e32 v2, 0x4b800000, v1
	v_cmp_gt_f32_e64 s[4:5], s2, v1
	v_cmp_gt_f32_e32 vcc, s2, v0
	s_nop 0
	v_cndmask_b32_e64 v1, v1, v2, s[4:5]
	v_rsq_f32_e32 v1, v1
	s_nop 0
	v_mul_f32_e32 v2, 0x45800000, v1
	v_cndmask_b32_e64 v98, v1, v2, s[4:5]
	v_mul_f32_e32 v1, 0x4b800000, v0
	v_cndmask_b32_e32 v0, v0, v1, vcc
	v_rsq_f32_e32 v0, v0
	s_nop 0
	v_mul_f32_e32 v1, 0x45800000, v0
	v_cndmask_b32_e32 v96, v0, v1, vcc
	v_lshlrev_b64 v[0:1], 6, v[66:67]
	v_lshl_add_u64 v[12:13], s[20:21], 0, v[0:1]
	global_load_dwordx4 v[0:3], v[12:13], off offset:48
	global_load_dwordx4 v[4:7], v[12:13], off offset:32
	global_load_dwordx4 v[8:11], v[12:13], off offset:16
	s_nop 0
	global_load_dwordx4 v[12:15], v[12:13], off
	s_waitcnt vmcnt(1)
	v_mov_b32_e32 v20, v9
	s_waitcnt vmcnt(0)
	v_mov_b32_e32 v18, v13
	v_mov_b32_e32 v19, v14
	v_mov_b32_e32 v21, v10
	v_mov_b32_e32 v13, v15
	v_mov_b32_e32 v9, v11
	v_pk_add_f32 v[12:13], v[18:19], v[12:13]
	v_pk_add_f32 v[8:9], v[20:21], v[8:9]
	v_pk_add_f32 v[10:11], v[12:13], v[12:13] op_sel:[0,1] op_sel_hi:[1,0]
	v_pk_add_f32 v[8:9], v[8:9], v[8:9] op_sel:[0,1] op_sel_hi:[1,0]
	v_mov_b32_e32 v11, v0
	v_mov_b32_e32 v9, v1
	v_pk_add_f32 v[0:1], v[10:11], v[8:9]
	v_mov_b32_e32 v8, v5
	v_pk_add_f32 v[4:5], v[4:5], v[8:9]
	s_nop 0
	v_mov_b32_e32 v5, v2
	v_mov_b32_e32 v2, v7
	v_pk_add_f32 v[6:7], v[6:7], v[2:3]
	s_nop 0
	v_mov_b32_e32 v7, v3
	v_pk_add_f32 v[2:3], v[4:5], v[6:7]
	s_nop 0
	v_pk_add_f32 v[18:19], v[0:1], v[2:3]
	v_lshlrev_b64 v[0:1], 6, v[64:65]
	v_lshl_add_u64 v[12:13], s[20:21], 0, v[0:1]
	global_load_dwordx4 v[0:3], v[12:13], off offset:48
	global_load_dwordx4 v[4:7], v[12:13], off offset:32
	global_load_dwordx4 v[8:11], v[12:13], off offset:16
	s_nop 0
	global_load_dwordx4 v[12:15], v[12:13], off
	s_waitcnt vmcnt(1)
	v_mov_b32_e32 v22, v9
	s_waitcnt vmcnt(0)
	v_mov_b32_e32 v20, v13
	v_mov_b32_e32 v21, v14
	v_mov_b32_e32 v23, v10
	v_mov_b32_e32 v13, v15
	v_mov_b32_e32 v9, v11
	v_pk_add_f32 v[12:13], v[20:21], v[12:13]
	v_pk_add_f32 v[8:9], v[22:23], v[8:9]
	v_pk_add_f32 v[10:11], v[12:13], v[12:13] op_sel:[0,1] op_sel_hi:[1,0]
	v_pk_add_f32 v[8:9], v[8:9], v[8:9] op_sel:[0,1] op_sel_hi:[1,0]
	v_mov_b32_e32 v11, v0
	v_mov_b32_e32 v9, v1
	v_pk_add_f32 v[0:1], v[10:11], v[8:9]
	v_mov_b32_e32 v8, v5
	v_pk_add_f32 v[4:5], v[4:5], v[8:9]
	s_nop 0
	v_mov_b32_e32 v5, v2
	v_mov_b32_e32 v2, v7
	v_pk_add_f32 v[6:7], v[6:7], v[2:3]
	s_nop 0
	v_mov_b32_e32 v7, v3
	v_pk_add_f32 v[2:3], v[4:5], v[6:7]
	s_nop 0
	v_pk_add_f32 v[0:1], v[0:1], v[2:3]
	v_mov_b32_e32 v3, v18
	v_mov_b32_e32 v2, v0
	v_mov_b32_e32 v18, v1
	v_pk_add_f32 v[0:1], v[2:3], v[18:19]
	s_nop 0
	v_pk_fma_f32 v[0:1], v[0:1], s[22:23], v[16:17] op_sel_hi:[1,0,0]
	s_nop 0
	v_mul_f32_e32 v2, 0x4b800000, v1
	v_cmp_gt_f32_e64 s[4:5], s2, v1
	v_cmp_gt_f32_e32 vcc, s2, v0
	s_nop 0
	v_cndmask_b32_e64 v1, v1, v2, s[4:5]
	v_rsq_f32_e32 v1, v1
	s_nop 0
	v_mul_f32_e32 v2, 0x45800000, v1
	v_cndmask_b32_e64 v102, v1, v2, s[4:5]
	v_mul_f32_e32 v1, 0x4b800000, v0
	v_cndmask_b32_e32 v0, v0, v1, vcc
	v_rsq_f32_e32 v0, v0
	s_lshl_b64 s[4:5], s[18:19], 11
	v_readlane_b32 s18, v253, 11
	v_readlane_b32 s19, v253, 12
	s_add_u32 s18, s18, s4
	v_mul_f32_e32 v1, 0x45800000, v0
	s_addc_u32 s19, s19, s5
	v_cndmask_b32_e32 v100, v0, v1, vcc
	s_cmp_lt_i32 s1, 51
	s_mov_b64 s[4:5], -1
	s_cbranch_scc0 .LBB0_691
; DI int TIDX() { int t = threadIdx.x; asm volatile("" : "+v"(t)); return t; }
; #define GL_LOAD(s_, kt_) if (VAR != 1) { a##s_##0 = GL_A(0, kt_); a##s_##1 = GL_A(1, kt_); a##s_##2 = GL_A(2, kt_); a##s_##3 = GL_A(3, kt_); b##s_##0 = GL_B(0, kt_); b##s_##1 = GL_B(1, kt_); b##s_##2 = GL_B(2, kt_); b##s_##3 = GL_B(3, kt_); }
; #define LDS_STORE(s_, buf_) if (VAR != 2) { LDS_ST1(sA, 0, buf_, a##s_##0) LDS_ST1(sA, 1, buf_, a##s_##1) LDS_ST1(sA, 2, buf_, a##s_##2) LDS_ST1(sA, 3, buf_, a##s_##3) LDS_ST1(sB, 0, buf_, b##s_##0) LDS_ST1(sB, 1, buf_, b##s_##1) LDS_ST1(sB, 2, buf_, b##s_##2) LDS_ST1(sB, 3, buf_, b##s_##3) }
;   const int tid = TIDX(), lane = tid & 63, wid = tid >> 6, wm = wid >> 1, wn = wid & 1, lr = lane & 15, g = lane >> 4;
;   char* sA = smem; char* sB = smem + 2 * LTILE;
;   uint4 a00 = {}, a01 = {}, a02 = {}, a03 = {}, b00 = {}, b01 = {}, b02 = {}, b03 = {}, a10 = {}, a11 = {}, a12 = {}, a13 = {}, b10 = {}, b11 = {}, b12 = {}, b13 = {};
;   constexpr int nk = NK;
;   const int sw0 = (g ^ ((lr >> 1) & 7)) << 4, sw1 = sw0 ^ 64;
;   const int r0 = tid >> 3, kc = tid & 7, kcs = kc ^ ((r0 >> 1) & 7);
;     ...
;   GL_LOAD(0, 0)
;   GL_LOAD(1, 1)
;   LDS_STORE(0, 0)
;   if (VAR != 4) __syncthreads();
; #pragma unroll
;   for (int kt = 0; kt < nk; kt += 2) {
;     if (kt + 2 < nk) { GL_LOAD(0, kt + 2) }
;     MMA_TILE(0)
	v_mov_b32_e32 v56, v148
	s_ashr_i32 s17, s16, 31
	s_lshl_b64 s[4:5], s[16:17], 11
	v_ashrrev_i32_e32 v16, 3, v56
	v_readlane_b32 s1, v252, 19
	v_ashrrev_i32_e32 v17, 31, v16
	s_add_u32 s4, s1, s4
	v_readlane_b32 s1, v252, 20
	v_lshlrev_b64 v[8:9], 11, v[16:17]
	v_lshlrev_b32_e32 v17, 4, v56
	v_add_u32_e32 v18, 32, v16
	s_addc_u32 s5, s1, s5
	v_lshl_add_u64 v[0:1], s[18:19], 0, v[8:9]
	v_and_b32_e32 v150, 0x70, v17
	v_ashrrev_i32_e32 v19, 31, v18
	v_add_u32_e32 v20, 64, v16
	v_lshl_add_u64 v[0:1], v[0:1], 0, v[150:151]
	v_lshlrev_b64 v[10:11], 11, v[18:19]
	v_ashrrev_i32_e32 v21, 31, v20
	v_add_u32_e32 v54, 0x60, v16
	v_lshl_add_u64 v[8:9], s[4:5], 0, v[8:9]
	global_load_dwordx4 v[22:25], v[0:1], off
	v_lshl_add_u64 v[2:3], s[18:19], 0, v[10:11]
	v_lshlrev_b64 v[12:13], 11, v[20:21]
	v_ashrrev_i32_e32 v55, 31, v54
	v_lshl_add_u64 v[8:9], v[8:9], 0, v[150:151]
	v_lshl_add_u64 v[2:3], v[2:3], 0, v[150:151]
	v_lshl_add_u64 v[4:5], s[18:19], 0, v[12:13]
	v_lshlrev_b64 v[14:15], 11, v[54:55]
	global_load_dwordx4 v[38:41], v[8:9], off
	global_load_dwordx4 v[26:29], v[2:3], off
	v_lshl_add_u64 v[4:5], v[4:5], 0, v[150:151]
	v_lshl_add_u64 v[6:7], s[18:19], 0, v[14:15]
	global_load_dwordx4 v[30:33], v[4:5], off
	v_lshl_add_u64 v[6:7], v[6:7], 0, v[150:151]
	v_lshl_add_u64 v[10:11], s[4:5], 0, v[10:11]
	global_load_dwordx4 v[34:37], v[6:7], off
	v_lshl_add_u64 v[10:11], v[10:11], 0, v[150:151]
	v_lshl_add_u64 v[12:13], s[4:5], 0, v[12:13]
	global_load_dwordx4 v[42:45], v[10:11], off
	v_lshl_add_u64 v[12:13], v[12:13], 0, v[150:151]
	v_lshl_add_u64 v[14:15], s[4:5], 0, v[14:15]
	global_load_dwordx4 v[46:49], v[12:13], off
	v_lshl_add_u64 v[14:15], v[14:15], 0, v[150:151]
	global_load_dwordx4 v[50:53], v[14:15], off
	v_lshlrev_b32_e32 v21, 3, v56
	v_and_b32_e32 v62, 48, v56
	s_movk_i32 s1, 0x70
	v_and_b32_e32 v19, 15, v56
	v_lshrrev_b32_e32 v55, 1, v56
	v_lshlrev_b32_e32 v57, 7, v56
	v_and_b32_e32 v63, 0x70, v21
	v_bitop3_b32 v95, v21, v62, s1 bitop3:0x6c
	v_bitop3_b32 v21, v17, s1, v56 bitop3:0x48
	v_and_or_b32 v103, v55, s29, v19
	v_and_b32_e32 v150, 0x2780, v57
	v_lshl_or_b32 v19, v20, 7, v21
	v_lshl_or_b32 v20, v54, 7, v21
	global_load_dwordx4 v[54:57], v[0:1], off offset:128
	global_load_dwordx4 v[58:61], v[8:9], off offset:128
	global_load_dwordx4 v[72:75], v[2:3], off offset:128
	global_load_dwordx4 v[76:79], v[4:5], off offset:128
	global_load_dwordx4 v[80:83], v[6:7], off offset:128
	global_load_dwordx4 v[104:107], v[10:11], off offset:128
	global_load_dwordx4 v[108:111], v[12:13], off offset:128
	global_load_dwordx4 v[112:115], v[14:15], off offset:128
	v_lshl_or_b32 v17, v16, 7, v21
	v_or_b32_e32 v16, v150, v95
	v_lshlrev_b32_e32 v103, 7, v103
	v_lshl_or_b32 v18, v18, 7, v21
	v_bitop3_b32 v21, v103, v63, v62 bitop3:0xf6
	s_movk_i32 s1, 0x1ff
	v_cmp_lt_i32_e32 vcc, s1, v94
	s_mov_b64 s[22:23], -1
	s_mov_b64 s[20:21], 0
	s_waitcnt vmcnt(15)
	ds_write_b128 v17, v[22:25]
	s_waitcnt vmcnt(14)
	ds_write_b128 v17, v[38:41] offset:32768
	s_waitcnt vmcnt(13)
	ds_write_b128 v18, v[26:29]
	s_waitcnt vmcnt(12)
	ds_write_b128 v19, v[30:33]
	s_waitcnt vmcnt(11)
	ds_write_b128 v20, v[34:37]
	s_waitcnt vmcnt(10)
	ds_write_b128 v18, v[42:45] offset:32768
	s_waitcnt vmcnt(9)
	ds_write_b128 v19, v[46:49] offset:32768
	s_waitcnt vmcnt(8)
	ds_write_b128 v20, v[50:53] offset:32768
	s_waitcnt lgkmcnt(0)
	s_barrier
	s_setprio 1
	ds_read_b128 v[22:25], v16 offset:32768
	ds_read_b128 v[30:33], v21
	s_waitcnt lgkmcnt(0)
	v_mfma_f32_16x16x32_f16 v[38:41], v[22:25], v[30:33], 0
	ds_read_b128 v[26:29], v16 offset:34816
	s_waitcnt lgkmcnt(0)
	v_mfma_f32_16x16x32_f16 v[46:49], v[26:29], v[30:33], 0
	ds_read_b128 v[34:37], v21 offset:2048
	ds_read_b128 v[42:45], v16 offset:36864
	s_waitcnt lgkmcnt(0)
	v_mfma_f32_16x16x32_f16 v[116:119], v[42:45], v[30:33], 0
	ds_read_b128 v[50:53], v16 offset:38912
	s_waitcnt lgkmcnt(0)
	v_mfma_f32_16x16x32_f16 v[120:123], v[50:53], v[30:33], 0
	ds_read_b128 v[30:33], v21 offset:4096
	v_mfma_f32_16x16x32_f16 v[124:127], v[22:25], v[34:37], 0
	ds_read_b128 v[136:139], v21 offset:6144
	s_waitcnt lgkmcnt(0)
	v_mfma_f32_16x16x32_f16 v[162:165], v[22:25], v[136:139], 0
	v_mfma_f32_16x16x32_f16 v[128:131], v[26:29], v[34:37], 0
	v_mfma_f32_16x16x32_f16 v[132:135], v[42:45], v[34:37], 0
	v_mfma_f32_16x16x32_f16 v[34:37], v[50:53], v[34:37], 0
	v_mfma_f32_16x16x32_f16 v[140:143], v[22:25], v[30:33], 0
	v_xor_b32_e32 v22, 64, v95
	v_or_b32_e32 v22, v150, v22
	v_mfma_f32_16x16x32_f16 v[144:147], v[26:29], v[30:33], 0
	v_mfma_f32_16x16x32_f16 v[154:157], v[42:45], v[30:33], 0
	v_mfma_f32_16x16x32_f16 v[158:161], v[50:53], v[30:33], 0
	v_bitop3_b32 v32, v103, v95, 64 bitop3:0xf6
	ds_read_b128 v[166:169], v32
	ds_read_b128 v[192:195], v22 offset:36864
	s_waitcnt lgkmcnt(0)
	v_mfma_f32_16x16x32_f16 v[116:119], v[192:195], v[166:169], v[116:119]
	ds_read_b128 v[188:191], v32 offset:2048
	ds_read_b128 v[196:199], v22 offset:38912
	s_waitcnt lgkmcnt(0)
	v_mfma_f32_16x16x32_f16 v[120:123], v[196:199], v[166:169], v[120:123]
	s_waitcnt vmcnt(7)
	ds_write_b128 v17, v[54:57] offset:16384
	s_waitcnt vmcnt(5)
	ds_write_b128 v18, v[72:75] offset:16384
	v_mfma_f32_16x16x32_f16 v[132:135], v[192:195], v[188:191], v[132:135]
	s_waitcnt vmcnt(4)
	ds_write_b128 v19, v[76:79] offset:16384
	s_waitcnt vmcnt(3)
	ds_write_b128 v20, v[80:83] offset:16384
	v_mfma_f32_16x16x32_f16 v[34:37], v[196:199], v[188:191], v[34:37]
	ds_write_b128 v17, v[58:61] offset:49152
	s_waitcnt vmcnt(2)
	ds_write_b128 v18, v[104:107] offset:49152
	s_waitcnt vmcnt(1)
	ds_write_b128 v19, v[108:111] offset:49152
	s_waitcnt vmcnt(0)
; #define GL_LOAD(s_, kt_) if (VAR != 1) { a##s_##0 = GL_A(0, kt_); a##s_##1 = GL_A(1, kt_); a##s_##2 = GL_A(2, kt_); a##s_##3 = GL_A(3, kt_); b##s_##0 = GL_B(0, kt_); b##s_##1 = GL_B(1, kt_); b##s_##2 = GL_B(2, kt_); b##s_##3 = GL_B(3, kt_); }
; #define LDS_STORE(s_, buf_) if (VAR != 2) { LDS_ST1(sA, 0, buf_, a##s_##0) LDS_ST1(sA, 1, buf_, a##s_##1) LDS_ST1(sA, 2, buf_, a##s_##2) LDS_ST1(sA, 3, buf_, a##s_##3) LDS_ST1(sB, 0, buf_, b##s_##0) LDS_ST1(sB, 1, buf_, b##s_##1) LDS_ST1(sB, 2, buf_, b##s_##2) LDS_ST1(sB, 3, buf_, b##s_##3) }
;     ...
;   GL_LOAD(0, 0)
;   GL_LOAD(1, 1)
;   LDS_STORE(0, 0)
;   if (VAR != 4) __syncthreads();
; #pragma unroll
;   for (int kt = 0; kt < nk; kt += 2) {
;     if (kt + 2 < nk) { GL_LOAD(0, kt + 2) }
;     MMA_TILE(0)
;     LDS_STORE(1, 1)
;     if (VAR != 4) __syncthreads();
;     if (kt + 3 < nk) { GL_LOAD(1, kt + 3) }
;     MMA_TILE(1)
;     if (kt + 2 < nk) { LDS_STORE(0, 0) }
;     if (VAR != 4) __syncthreads();
	ds_write_b128 v20, v[112:115] offset:49152
	v_mfma_f32_16x16x32_f16 v[24:27], v[26:29], v[136:139], 0
	v_mfma_f32_16x16x32_f16 v[28:31], v[42:45], v[136:139], 0
	ds_read_b128 v[42:45], v22 offset:32768
	v_mfma_f32_16x16x32_f16 v[50:53], v[50:53], v[136:139], 0
	ds_read_b128 v[136:139], v22 offset:34816
	s_waitcnt lgkmcnt(1)
	v_mfma_f32_16x16x32_f16 v[38:41], v[42:45], v[166:169], v[38:41]
	v_mfma_f32_16x16x32_f16 v[124:127], v[42:45], v[188:191], v[124:127]
	s_waitcnt lgkmcnt(0)
	v_mfma_f32_16x16x32_f16 v[46:49], v[136:139], v[166:169], v[46:49]
	ds_read_b128 v[166:169], v32 offset:4096
	v_mfma_f32_16x16x32_f16 v[128:131], v[136:139], v[188:191], v[128:131]
	ds_read_b128 v[188:191], v32 offset:6144
	s_waitcnt lgkmcnt(1)
	v_mfma_f32_16x16x32_f16 v[140:143], v[42:45], v[166:169], v[140:143]
	s_waitcnt lgkmcnt(0)
	v_mfma_f32_16x16x32_f16 v[42:45], v[42:45], v[188:191], v[162:165]
	s_nop 2
	global_load_dwordx4 v[162:165], v[0:1], off offset:256
	v_mfma_f32_16x16x32_f16 v[144:147], v[136:139], v[166:169], v[144:147]
	v_mfma_f32_16x16x32_f16 v[24:27], v[136:139], v[188:191], v[24:27]
	v_mfma_f32_16x16x32_f16 v[154:157], v[192:195], v[166:169], v[154:157]
	v_mfma_f32_16x16x32_f16 v[158:161], v[196:199], v[166:169], v[158:161]
	global_load_dwordx4 v[166:169], v[2:3], off offset:256
	global_load_dwordx4 v[200:203], v[4:5], off offset:256
	global_load_dwordx4 v[204:207], v[6:7], off offset:256
	global_load_dwordx4 v[136:139], v[8:9], off offset:256
	global_load_dwordx4 v[208:211], v[10:11], off offset:256
	global_load_dwordx4 v[212:215], v[12:13], off offset:256
	global_load_dwordx4 v[220:223], v[14:15], off offset:256
	s_waitcnt lgkmcnt(0)
	s_barrier
	v_mfma_f32_16x16x32_f16 v[28:31], v[192:195], v[188:191], v[28:31]
	ds_read_b128 v[54:57], v16 offset:49152
	v_mfma_f32_16x16x32_f16 v[50:53], v[196:199], v[188:191], v[50:53]
	ds_read_b128 v[58:61], v16 offset:51200
	ds_read_b128 v[72:75], v21 offset:16384
	s_waitcnt lgkmcnt(0)
	v_mfma_f32_16x16x32_f16 v[38:41], v[54:57], v[72:75], v[38:41]
	ds_read_b128 v[76:79], v21 offset:18432
	s_waitcnt lgkmcnt(0)
	v_mfma_f32_16x16x32_f16 v[112:115], v[54:57], v[76:79], v[124:127]
	ds_read_b128 v[80:83], v16 offset:53248
	v_mfma_f32_16x16x32_f16 v[46:49], v[58:61], v[72:75], v[46:49]
	ds_read_b128 v[104:107], v16 offset:55296
	s_waitcnt lgkmcnt(1)
	v_mfma_f32_16x16x32_f16 v[108:111], v[80:83], v[72:75], v[116:119]
	v_mfma_f32_16x16x32_f16 v[116:119], v[58:61], v[76:79], v[128:131]
	ds_read_b128 v[124:127], v21 offset:22528
	s_waitcnt lgkmcnt(1)
	v_mfma_f32_16x16x32_f16 v[72:75], v[104:107], v[72:75], v[120:123]
	v_mfma_f32_16x16x32_f16 v[120:123], v[80:83], v[76:79], v[132:135]
	v_mfma_f32_16x16x32_f16 v[34:37], v[104:107], v[76:79], v[34:37]
	ds_read_b128 v[76:79], v21 offset:20480
	s_waitcnt lgkmcnt(0)
	v_mfma_f32_16x16x32_f16 v[128:131], v[54:57], v[76:79], v[140:143]
	v_mfma_f32_16x16x32_f16 v[42:45], v[54:57], v[124:127], v[42:45]
	ds_read_b128 v[54:57], v22 offset:49152
	v_mfma_f32_16x16x32_f16 v[132:135], v[58:61], v[76:79], v[144:147]
	s_nop 2
	ds_read_b128 v[144:147], v22 offset:55296
	v_mfma_f32_16x16x32_f16 v[24:27], v[58:61], v[124:127], v[24:27]
	ds_read_b128 v[58:61], v22 offset:51200
	s_waitcnt vmcnt(7)
	ds_write_b128 v17, v[162:165]
	v_mfma_f32_16x16x32_f16 v[140:143], v[80:83], v[76:79], v[154:157]
	s_waitcnt vmcnt(6)
	ds_write_b128 v18, v[166:169]
	v_mfma_f32_16x16x32_f16 v[28:31], v[80:83], v[124:127], v[28:31]
	ds_read_b128 v[80:83], v32 offset:16384
	v_mfma_f32_16x16x32_f16 v[76:79], v[104:107], v[76:79], v[158:161]
	s_waitcnt vmcnt(5)
	ds_write_b128 v19, v[200:203]
	v_mfma_f32_16x16x32_f16 v[50:53], v[104:107], v[124:127], v[50:53]
	ds_read_b128 v[104:107], v32 offset:18432
	s_waitcnt lgkmcnt(2)
	v_mfma_f32_16x16x32_f16 v[38:41], v[54:57], v[80:83], v[38:41]
	ds_read_b128 v[124:127], v22 offset:53248
	v_mfma_f32_16x16x32_f16 v[46:49], v[58:61], v[80:83], v[46:49]
	s_waitcnt lgkmcnt(0)
	v_mfma_f32_16x16x32_f16 v[108:111], v[124:127], v[80:83], v[108:111]
	v_mfma_f32_16x16x32_f16 v[72:75], v[144:147], v[80:83], v[72:75]
	v_mfma_f32_16x16x32_f16 v[80:83], v[54:57], v[104:107], v[112:115]
	s_waitcnt vmcnt(4)
	ds_write_b128 v20, v[204:207]
	s_waitcnt vmcnt(3)
	ds_write_b128 v17, v[136:139] offset:32768
	s_waitcnt vmcnt(2)
	ds_write_b128 v18, v[208:211] offset:32768
	s_waitcnt vmcnt(1)
	ds_write_b128 v19, v[212:215] offset:32768
	v_mfma_f32_16x16x32_f16 v[112:115], v[58:61], v[104:107], v[116:119]
	s_waitcnt vmcnt(0)
	ds_write_b128 v20, v[220:223] offset:32768
	v_mfma_f32_16x16x32_f16 v[116:119], v[124:127], v[104:107], v[120:123]
	s_nop 2
	ds_read_b128 v[120:123], v32 offset:22528
	v_mfma_f32_16x16x32_f16 v[34:37], v[144:147], v[104:107], v[34:37]
	ds_read_b128 v[104:107], v32 offset:20480
	s_waitcnt lgkmcnt(0)
	v_mfma_f32_16x16x32_f16 v[128:131], v[54:57], v[104:107], v[128:131]
	v_mfma_f32_16x16x32_f16 v[42:45], v[54:57], v[120:123], v[42:45]
	global_load_dwordx4 v[54:57], v[0:1], off offset:384
	v_mfma_f32_16x16x32_f16 v[132:135], v[58:61], v[104:107], v[132:135]
	v_mfma_f32_16x16x32_f16 v[24:27], v[58:61], v[120:123], v[24:27]
	v_mfma_f32_16x16x32_f16 v[140:143], v[124:127], v[104:107], v[140:143]
	v_mfma_f32_16x16x32_f16 v[28:31], v[124:127], v[120:123], v[28:31]
	v_mfma_f32_16x16x32_f16 v[76:79], v[144:147], v[104:107], v[76:79]
	global_load_dwordx4 v[104:107], v[2:3], off offset:384
	global_load_dwordx4 v[154:157], v[4:5], off offset:384
	global_load_dwordx4 v[158:161], v[6:7], off offset:384
	global_load_dwordx4 v[58:61], v[8:9], off offset:384
	global_load_dwordx4 v[188:191], v[10:11], off offset:384
	global_load_dwordx4 v[192:195], v[12:13], off offset:384
	global_load_dwordx4 v[196:199], v[14:15], off offset:384
	s_waitcnt lgkmcnt(0)
	s_barrier
; #define GL_LOAD(s_, kt_) if (VAR != 1) { a##s_##0 = GL_A(0, kt_); a##s_##1 = GL_A(1, kt_); a##s_##2 = GL_A(2, kt_); a##s_##3 = GL_A(3, kt_); b##s_##0 = GL_B(0, kt_); b##s_##1 = GL_B(1, kt_); b##s_##2 = GL_B(2, kt_); b##s_##3 = GL_B(3, kt_); }
; #define LDS_STORE(s_, buf_) if (VAR != 2) { LDS_ST1(sA, 0, buf_, a##s_##0) LDS_ST1(sA, 1, buf_, a##s_##1) LDS_ST1(sA, 2, buf_, a##s_##2) LDS_ST1(sA, 3, buf_, a##s_##3) LDS_ST1(sB, 0, buf_, b##s_##0) LDS_ST1(sB, 1, buf_, b##s_##1) LDS_ST1(sB, 2, buf_, b##s_##2) LDS_ST1(sB, 3, buf_, b##s_##3) }
;     ...
;   GL_LOAD(0, 0)
;   GL_LOAD(1, 1)
;   LDS_STORE(0, 0)
;   if (VAR != 4) __syncthreads();
; #pragma unroll
;   for (int kt = 0; kt < nk; kt += 2) {
;     if (kt + 2 < nk) { GL_LOAD(0, kt + 2) }
;     MMA_TILE(0)
;     LDS_STORE(1, 1)
;     if (VAR != 4) __syncthreads();
;     if (kt + 3 < nk) { GL_LOAD(1, kt + 3) }
;     MMA_TILE(1)
;     if (kt + 2 < nk) { LDS_STORE(0, 0) }
;     if (VAR != 4) __syncthreads();
	v_mfma_f32_16x16x32_f16 v[50:53], v[144:147], v[120:123], v[50:53]
	ds_read_b128 v[124:127], v16 offset:32768
	ds_read_b128 v[136:139], v21
	s_waitcnt lgkmcnt(0)
	v_mfma_f32_16x16x32_f16 v[38:41], v[124:127], v[136:139], v[38:41]
	ds_read_b128 v[120:123], v16 offset:34816
	ds_read_b128 v[144:147], v21 offset:2048
	s_waitcnt lgkmcnt(0)
	v_mfma_f32_16x16x32_f16 v[80:83], v[124:127], v[144:147], v[80:83]
	ds_read_b128 v[162:165], v16 offset:36864
	v_mfma_f32_16x16x32_f16 v[46:49], v[120:123], v[136:139], v[46:49]
	ds_read_b128 v[166:169], v16 offset:38912
	v_mfma_f32_16x16x32_f16 v[112:115], v[120:123], v[144:147], v[112:115]
	s_waitcnt lgkmcnt(1)
	v_mfma_f32_16x16x32_f16 v[108:111], v[162:165], v[136:139], v[108:111]
	v_mfma_f32_16x16x32_f16 v[116:119], v[162:165], v[144:147], v[116:119]
	s_waitcnt lgkmcnt(0)
	v_mfma_f32_16x16x32_f16 v[72:75], v[166:169], v[136:139], v[72:75]
	ds_read_b128 v[136:139], v21 offset:4096
	v_mfma_f32_16x16x32_f16 v[34:37], v[166:169], v[144:147], v[34:37]
	ds_read_b128 v[144:147], v21 offset:6144
	s_waitcnt lgkmcnt(1)
	v_mfma_f32_16x16x32_f16 v[128:131], v[124:127], v[136:139], v[128:131]
	s_waitcnt lgkmcnt(0)
	v_mfma_f32_16x16x32_f16 v[42:45], v[124:127], v[144:147], v[42:45]
	ds_read_b128 v[124:127], v22 offset:34816
	v_mfma_f32_16x16x32_f16 v[132:135], v[120:123], v[136:139], v[132:135]
	v_mfma_f32_16x16x32_f16 v[24:27], v[120:123], v[144:147], v[24:27]
	ds_read_b128 v[120:123], v22 offset:32768
	v_mfma_f32_16x16x32_f16 v[140:143], v[162:165], v[136:139], v[140:143]
	s_waitcnt vmcnt(7)
	ds_write_b128 v17, v[54:57] offset:16384
	s_waitcnt vmcnt(6)
	ds_write_b128 v18, v[104:107] offset:16384
	v_mfma_f32_16x16x32_f16 v[28:31], v[162:165], v[144:147], v[28:31]
	ds_read_b128 v[162:165], v22 offset:36864
	s_waitcnt vmcnt(5)
	ds_write_b128 v19, v[154:157] offset:16384
	v_mfma_f32_16x16x32_f16 v[76:79], v[166:169], v[136:139], v[76:79]
	ds_read_b128 v[136:139], v32
	v_mfma_f32_16x16x32_f16 v[50:53], v[166:169], v[144:147], v[50:53]
	ds_read_b128 v[144:147], v32 offset:2048
	s_waitcnt lgkmcnt(1)
	v_mfma_f32_16x16x32_f16 v[38:41], v[120:123], v[136:139], v[38:41]
	ds_read_b128 v[166:169], v22 offset:38912
	s_waitcnt lgkmcnt(1)
	v_mfma_f32_16x16x32_f16 v[80:83], v[120:123], v[144:147], v[80:83]
	s_waitcnt vmcnt(4)
	ds_write_b128 v20, v[158:161] offset:16384
	v_mfma_f32_16x16x32_f16 v[46:49], v[124:127], v[136:139], v[46:49]
	s_waitcnt vmcnt(3)
	ds_write_b128 v17, v[58:61] offset:49152
	v_mfma_f32_16x16x32_f16 v[112:115], v[124:127], v[144:147], v[112:115]
	s_waitcnt vmcnt(2)
	ds_write_b128 v18, v[188:191] offset:49152
	v_mfma_f32_16x16x32_f16 v[108:111], v[162:165], v[136:139], v[108:111]
	s_waitcnt vmcnt(1)
	ds_write_b128 v19, v[192:195] offset:49152
	v_mfma_f32_16x16x32_f16 v[116:119], v[162:165], v[144:147], v[116:119]
	s_waitcnt vmcnt(0)
	ds_write_b128 v20, v[196:199] offset:49152
	s_waitcnt lgkmcnt(5)
	v_mfma_f32_16x16x32_f16 v[72:75], v[166:169], v[136:139], v[72:75]
	ds_read_b128 v[136:139], v32 offset:4096
	v_mfma_f32_16x16x32_f16 v[34:37], v[166:169], v[144:147], v[34:37]
	ds_read_b128 v[144:147], v32 offset:6144
	s_waitcnt lgkmcnt(1)
	v_mfma_f32_16x16x32_f16 v[128:131], v[120:123], v[136:139], v[128:131]
	s_waitcnt lgkmcnt(0)
	v_mfma_f32_16x16x32_f16 v[42:45], v[120:123], v[144:147], v[42:45]
	global_load_dwordx4 v[120:123], v[0:1], off offset:512
	v_mfma_f32_16x16x32_f16 v[132:135], v[124:127], v[136:139], v[132:135]
	v_mfma_f32_16x16x32_f16 v[24:27], v[124:127], v[144:147], v[24:27]
	v_mfma_f32_16x16x32_f16 v[140:143], v[162:165], v[136:139], v[140:143]
	v_mfma_f32_16x16x32_f16 v[28:31], v[162:165], v[144:147], v[28:31]
	v_mfma_f32_16x16x32_f16 v[76:79], v[166:169], v[136:139], v[76:79]
	global_load_dwordx4 v[136:139], v[2:3], off offset:512
	global_load_dwordx4 v[200:203], v[4:5], off offset:512
	global_load_dwordx4 v[204:207], v[6:7], off offset:512
	global_load_dwordx4 v[124:127], v[8:9], off offset:512
	global_load_dwordx4 v[208:211], v[10:11], off offset:512
	global_load_dwordx4 v[212:215], v[12:13], off offset:512
	global_load_dwordx4 v[220:223], v[14:15], off offset:512
	s_waitcnt lgkmcnt(0)
	s_barrier
	v_mfma_f32_16x16x32_f16 v[50:53], v[166:169], v[144:147], v[50:53]
	ds_read_b128 v[54:57], v16 offset:49152
	ds_read_b128 v[104:107], v21 offset:16384
	s_waitcnt lgkmcnt(0)
	v_mfma_f32_16x16x32_f16 v[38:41], v[54:57], v[104:107], v[38:41]
	ds_read_b128 v[58:61], v16 offset:51200
	ds_read_b128 v[144:147], v21 offset:18432
	s_waitcnt lgkmcnt(0)
	v_mfma_f32_16x16x32_f16 v[80:83], v[54:57], v[144:147], v[80:83]
	ds_read_b128 v[154:157], v16 offset:53248
	v_mfma_f32_16x16x32_f16 v[46:49], v[58:61], v[104:107], v[46:49]
	ds_read_b128 v[158:161], v16 offset:55296
	s_waitcnt lgkmcnt(1)
	v_mfma_f32_16x16x32_f16 v[108:111], v[154:157], v[104:107], v[108:111]
	s_waitcnt lgkmcnt(0)
	v_mfma_f32_16x16x32_f16 v[72:75], v[158:161], v[104:107], v[72:75]
	v_mfma_f32_16x16x32_f16 v[104:107], v[58:61], v[144:147], v[112:115]
	v_mfma_f32_16x16x32_f16 v[112:115], v[154:157], v[144:147], v[116:119]
	s_nop 2
	ds_read_b128 v[116:119], v21 offset:20480
	v_mfma_f32_16x16x32_f16 v[34:37], v[158:161], v[144:147], v[34:37]
	ds_read_b128 v[144:147], v21 offset:22528
	s_waitcnt lgkmcnt(1)
	v_mfma_f32_16x16x32_f16 v[128:131], v[54:57], v[116:119], v[128:131]
	s_waitcnt lgkmcnt(0)
	v_mfma_f32_16x16x32_f16 v[42:45], v[54:57], v[144:147], v[42:45]
	ds_read_b128 v[54:57], v22 offset:49152
	v_mfma_f32_16x16x32_f16 v[132:135], v[58:61], v[116:119], v[132:135]
	v_mfma_f32_16x16x32_f16 v[24:27], v[58:61], v[144:147], v[24:27]
	ds_read_b128 v[58:61], v22 offset:51200
	v_mfma_f32_16x16x32_f16 v[140:143], v[154:157], v[116:119], v[140:143]
	s_waitcnt vmcnt(7)
; #define GL_LOAD(s_, kt_) if (VAR != 1) { a##s_##0 = GL_A(0, kt_); a##s_##1 = GL_A(1, kt_); a##s_##2 = GL_A(2, kt_); a##s_##3 = GL_A(3, kt_); b##s_##0 = GL_B(0, kt_); b##s_##1 = GL_B(1, kt_); b##s_##2 = GL_B(2, kt_); b##s_##3 = GL_B(3, kt_); }
; #define LDS_STORE(s_, buf_) if (VAR != 2) { LDS_ST1(sA, 0, buf_, a##s_##0) LDS_ST1(sA, 1, buf_, a##s_##1) LDS_ST1(sA, 2, buf_, a##s_##2) LDS_ST1(sA, 3, buf_, a##s_##3) LDS_ST1(sB, 0, buf_, b##s_##0) LDS_ST1(sB, 1, buf_, b##s_##1) LDS_ST1(sB, 2, buf_, b##s_##2) LDS_ST1(sB, 3, buf_, b##s_##3) }
;     ...
;   GL_LOAD(0, 0)
;   GL_LOAD(1, 1)
;   LDS_STORE(0, 0)
;   if (VAR != 4) __syncthreads();
; #pragma unroll
;   for (int kt = 0; kt < nk; kt += 2) {
;     if (kt + 2 < nk) { GL_LOAD(0, kt + 2) }
;     MMA_TILE(0)
;     LDS_STORE(1, 1)
;     if (VAR != 4) __syncthreads();
;     if (kt + 3 < nk) { GL_LOAD(1, kt + 3) }
;     MMA_TILE(1)
;     if (kt + 2 < nk) { LDS_STORE(0, 0) }
;     if (VAR != 4) __syncthreads();
	ds_write_b128 v17, v[120:123]
	s_waitcnt vmcnt(6)
	ds_write_b128 v18, v[136:139]
	v_mfma_f32_16x16x32_f16 v[28:31], v[154:157], v[144:147], v[28:31]
	ds_read_b128 v[154:157], v22 offset:53248
	s_waitcnt vmcnt(5)
	ds_write_b128 v19, v[200:203]
	v_mfma_f32_16x16x32_f16 v[76:79], v[158:161], v[116:119], v[76:79]
	ds_read_b128 v[116:119], v32 offset:16384
	v_mfma_f32_16x16x32_f16 v[50:53], v[158:161], v[144:147], v[50:53]
	ds_read_b128 v[144:147], v32 offset:18432
	s_waitcnt lgkmcnt(1)
	v_mfma_f32_16x16x32_f16 v[38:41], v[54:57], v[116:119], v[38:41]
	ds_read_b128 v[158:161], v22 offset:55296
	s_waitcnt lgkmcnt(1)
	v_mfma_f32_16x16x32_f16 v[80:83], v[54:57], v[144:147], v[80:83]
	s_waitcnt vmcnt(4)
	ds_write_b128 v20, v[204:207]
	v_mfma_f32_16x16x32_f16 v[46:49], v[58:61], v[116:119], v[46:49]
	s_waitcnt vmcnt(3)
	ds_write_b128 v17, v[124:127] offset:32768
	v_mfma_f32_16x16x32_f16 v[104:107], v[58:61], v[144:147], v[104:107]
	s_waitcnt vmcnt(2)
	ds_write_b128 v18, v[208:211] offset:32768
	v_mfma_f32_16x16x32_f16 v[108:111], v[154:157], v[116:119], v[108:111]
	s_waitcnt vmcnt(1)
	ds_write_b128 v19, v[212:215] offset:32768
	v_mfma_f32_16x16x32_f16 v[112:115], v[154:157], v[144:147], v[112:115]
	s_waitcnt vmcnt(0)
	ds_write_b128 v20, v[220:223] offset:32768
	s_waitcnt lgkmcnt(5)
	v_mfma_f32_16x16x32_f16 v[72:75], v[158:161], v[116:119], v[72:75]
	ds_read_b128 v[116:119], v32 offset:20480
	v_mfma_f32_16x16x32_f16 v[34:37], v[158:161], v[144:147], v[34:37]
	ds_read_b128 v[144:147], v32 offset:22528
	s_waitcnt lgkmcnt(1)
	v_mfma_f32_16x16x32_f16 v[128:131], v[54:57], v[116:119], v[128:131]
	s_waitcnt lgkmcnt(0)
	v_mfma_f32_16x16x32_f16 v[42:45], v[54:57], v[144:147], v[42:45]
	global_load_dwordx4 v[54:57], v[0:1], off offset:640
	v_mfma_f32_16x16x32_f16 v[132:135], v[58:61], v[116:119], v[132:135]
	v_mfma_f32_16x16x32_f16 v[24:27], v[58:61], v[144:147], v[24:27]
	v_mfma_f32_16x16x32_f16 v[140:143], v[154:157], v[116:119], v[140:143]
	v_mfma_f32_16x16x32_f16 v[28:31], v[154:157], v[144:147], v[28:31]
	v_mfma_f32_16x16x32_f16 v[76:79], v[158:161], v[116:119], v[76:79]
	global_load_dwordx4 v[116:119], v[2:3], off offset:640
	global_load_dwordx4 v[162:165], v[4:5], off offset:640
	global_load_dwordx4 v[166:169], v[6:7], off offset:640
	global_load_dwordx4 v[58:61], v[8:9], off offset:640
	global_load_dwordx4 v[188:191], v[10:11], off offset:640
	global_load_dwordx4 v[192:195], v[12:13], off offset:640
	global_load_dwordx4 v[196:199], v[14:15], off offset:640
	s_waitcnt lgkmcnt(0)
	s_barrier
	v_mfma_f32_16x16x32_f16 v[50:53], v[158:161], v[144:147], v[50:53]
	ds_read_b128 v[120:123], v16 offset:32768
	ds_read_b128 v[136:139], v21
	s_waitcnt lgkmcnt(0)
	v_mfma_f32_16x16x32_f16 v[38:41], v[120:123], v[136:139], v[38:41]
	ds_read_b128 v[124:127], v16 offset:34816
	ds_read_b128 v[144:147], v21 offset:2048
	s_waitcnt lgkmcnt(0)
	v_mfma_f32_16x16x32_f16 v[80:83], v[120:123], v[144:147], v[80:83]
	ds_read_b128 v[154:157], v16 offset:36864
	v_mfma_f32_16x16x32_f16 v[46:49], v[124:127], v[136:139], v[46:49]
	ds_read_b128 v[158:161], v16 offset:38912
	v_mfma_f32_16x16x32_f16 v[104:107], v[124:127], v[144:147], v[104:107]
	s_waitcnt lgkmcnt(1)
	v_mfma_f32_16x16x32_f16 v[108:111], v[154:157], v[136:139], v[108:111]
	v_mfma_f32_16x16x32_f16 v[112:115], v[154:157], v[144:147], v[112:115]
	s_waitcnt lgkmcnt(0)
	v_mfma_f32_16x16x32_f16 v[72:75], v[158:161], v[136:139], v[72:75]
	ds_read_b128 v[136:139], v21 offset:4096
	v_mfma_f32_16x16x32_f16 v[34:37], v[158:161], v[144:147], v[34:37]
	ds_read_b128 v[144:147], v21 offset:6144
	s_waitcnt lgkmcnt(1)
	v_mfma_f32_16x16x32_f16 v[128:131], v[120:123], v[136:139], v[128:131]
	s_waitcnt lgkmcnt(0)
	v_mfma_f32_16x16x32_f16 v[42:45], v[120:123], v[144:147], v[42:45]
	ds_read_b128 v[120:123], v22 offset:32768
	v_mfma_f32_16x16x32_f16 v[132:135], v[124:127], v[136:139], v[132:135]
	v_mfma_f32_16x16x32_f16 v[24:27], v[124:127], v[144:147], v[24:27]
	ds_read_b128 v[124:127], v22 offset:34816
	v_mfma_f32_16x16x32_f16 v[140:143], v[154:157], v[136:139], v[140:143]
	s_waitcnt vmcnt(7)
	ds_write_b128 v17, v[54:57] offset:16384
	s_waitcnt vmcnt(6)
	ds_write_b128 v18, v[116:119] offset:16384
	v_mfma_f32_16x16x32_f16 v[28:31], v[154:157], v[144:147], v[28:31]
	ds_read_b128 v[154:157], v22 offset:36864
	s_waitcnt vmcnt(5)
	ds_write_b128 v19, v[162:165] offset:16384
	v_mfma_f32_16x16x32_f16 v[76:79], v[158:161], v[136:139], v[76:79]
	ds_read_b128 v[136:139], v32
	v_mfma_f32_16x16x32_f16 v[50:53], v[158:161], v[144:147], v[50:53]
	ds_read_b128 v[144:147], v32 offset:2048
	s_waitcnt lgkmcnt(1)
	v_mfma_f32_16x16x32_f16 v[38:41], v[120:123], v[136:139], v[38:41]
	ds_read_b128 v[158:161], v22 offset:38912
	s_waitcnt lgkmcnt(1)
	v_mfma_f32_16x16x32_f16 v[80:83], v[120:123], v[144:147], v[80:83]
	s_waitcnt vmcnt(4)
	ds_write_b128 v20, v[166:169] offset:16384
	v_mfma_f32_16x16x32_f16 v[46:49], v[124:127], v[136:139], v[46:49]
	s_waitcnt vmcnt(3)
	ds_write_b128 v17, v[58:61] offset:49152
	v_mfma_f32_16x16x32_f16 v[104:107], v[124:127], v[144:147], v[104:107]
	s_waitcnt vmcnt(2)
	ds_write_b128 v18, v[188:191] offset:49152
	v_mfma_f32_16x16x32_f16 v[108:111], v[154:157], v[136:139], v[108:111]
	s_waitcnt vmcnt(1)
	ds_write_b128 v19, v[192:195] offset:49152
	v_mfma_f32_16x16x32_f16 v[112:115], v[154:157], v[144:147], v[112:115]
	s_waitcnt vmcnt(0)
	ds_write_b128 v20, v[196:199] offset:49152
	s_waitcnt lgkmcnt(5)
	v_mfma_f32_16x16x32_f16 v[72:75], v[158:161], v[136:139], v[72:75]
	ds_read_b128 v[136:139], v32 offset:4096
	v_mfma_f32_16x16x32_f16 v[34:37], v[158:161], v[144:147], v[34:37]
	ds_read_b128 v[144:147], v32 offset:6144
	s_waitcnt lgkmcnt(1)
	v_mfma_f32_16x16x32_f16 v[128:131], v[120:123], v[136:139], v[128:131]
	s_waitcnt lgkmcnt(0)
	v_mfma_f32_16x16x32_f16 v[42:45], v[120:123], v[144:147], v[42:45]
	global_load_dwordx4 v[120:123], v[0:1], off offset:768
	v_mfma_f32_16x16x32_f16 v[132:135], v[124:127], v[136:139], v[132:135]
	v_mfma_f32_16x16x32_f16 v[24:27], v[124:127], v[144:147], v[24:27]
	v_mfma_f32_16x16x32_f16 v[140:143], v[154:157], v[136:139], v[140:143]
	v_mfma_f32_16x16x32_f16 v[28:31], v[154:157], v[144:147], v[28:31]
	v_mfma_f32_16x16x32_f16 v[76:79], v[158:161], v[136:139], v[76:79]
	global_load_dwordx4 v[136:139], v[2:3], off offset:768
	global_load_dwordx4 v[200:203], v[4:5], off offset:768
	global_load_dwordx4 v[204:207], v[6:7], off offset:768
	global_load_dwordx4 v[124:127], v[8:9], off offset:768
	global_load_dwordx4 v[208:211], v[10:11], off offset:768
	global_load_dwordx4 v[212:215], v[12:13], off offset:768
	global_load_dwordx4 v[220:223], v[14:15], off offset:768
	s_waitcnt lgkmcnt(0)
	s_barrier
; #define GL_LOAD(s_, kt_) if (VAR != 1) { a##s_##0 = GL_A(0, kt_); a##s_##1 = GL_A(1, kt_); a##s_##2 = GL_A(2, kt_); a##s_##3 = GL_A(3, kt_); b##s_##0 = GL_B(0, kt_); b##s_##1 = GL_B(1, kt_); b##s_##2 = GL_B(2, kt_); b##s_##3 = GL_B(3, kt_); }
; #define LDS_STORE(s_, buf_) if (VAR != 2) { LDS_ST1(sA, 0, buf_, a##s_##0) LDS_ST1(sA, 1, buf_, a##s_##1) LDS_ST1(sA, 2, buf_, a##s_##2) LDS_ST1(sA, 3, buf_, a##s_##3) LDS_ST1(sB, 0, buf_, b##s_##0) LDS_ST1(sB, 1, buf_, b##s_##1) LDS_ST1(sB, 2, buf_, b##s_##2) LDS_ST1(sB, 3, buf_, b##s_##3) }
;     ...
;   for (int kt = 0; kt < nk; kt += 2) {
;     if (kt + 2 < nk) { GL_LOAD(0, kt + 2) }
;     MMA_TILE(0)
;     LDS_STORE(1, 1)
;     if (VAR != 4) __syncthreads();
;     if (kt + 3 < nk) { GL_LOAD(1, kt + 3) }
;     MMA_TILE(1)
;     if (kt + 2 < nk) { LDS_STORE(0, 0) }
;     if (VAR != 4) __syncthreads();
	v_mfma_f32_16x16x32_f16 v[50:53], v[158:161], v[144:147], v[50:53]
	ds_read_b128 v[54:57], v16 offset:49152
	ds_read_b128 v[116:119], v21 offset:16384
	s_waitcnt lgkmcnt(0)
	v_mfma_f32_16x16x32_f16 v[38:41], v[54:57], v[116:119], v[38:41]
	ds_read_b128 v[58:61], v16 offset:51200
	ds_read_b128 v[144:147], v21 offset:18432
	s_waitcnt lgkmcnt(0)
	v_mfma_f32_16x16x32_f16 v[80:83], v[54:57], v[144:147], v[80:83]
	ds_read_b128 v[154:157], v16 offset:53248
	v_mfma_f32_16x16x32_f16 v[46:49], v[58:61], v[116:119], v[46:49]
	ds_read_b128 v[158:161], v16 offset:55296
	v_mfma_f32_16x16x32_f16 v[104:107], v[58:61], v[144:147], v[104:107]
	s_waitcnt lgkmcnt(1)
	v_mfma_f32_16x16x32_f16 v[108:111], v[154:157], v[116:119], v[108:111]
	v_mfma_f32_16x16x32_f16 v[112:115], v[154:157], v[144:147], v[112:115]
	s_waitcnt lgkmcnt(0)
	v_mfma_f32_16x16x32_f16 v[72:75], v[158:161], v[116:119], v[72:75]
	ds_read_b128 v[116:119], v21 offset:20480
	v_mfma_f32_16x16x32_f16 v[34:37], v[158:161], v[144:147], v[34:37]
	ds_read_b128 v[144:147], v21 offset:22528
	s_waitcnt lgkmcnt(1)
	v_mfma_f32_16x16x32_f16 v[128:131], v[54:57], v[116:119], v[128:131]
	s_waitcnt lgkmcnt(0)
	v_mfma_f32_16x16x32_f16 v[42:45], v[54:57], v[144:147], v[42:45]
	ds_read_b128 v[54:57], v22 offset:49152
	v_mfma_f32_16x16x32_f16 v[132:135], v[58:61], v[116:119], v[132:135]
	v_mfma_f32_16x16x32_f16 v[24:27], v[58:61], v[144:147], v[24:27]
	ds_read_b128 v[58:61], v22 offset:51200
	v_mfma_f32_16x16x32_f16 v[140:143], v[154:157], v[116:119], v[140:143]
	s_waitcnt vmcnt(7)
	ds_write_b128 v17, v[120:123]
	s_waitcnt vmcnt(6)
	ds_write_b128 v18, v[136:139]
	v_mfma_f32_16x16x32_f16 v[28:31], v[154:157], v[144:147], v[28:31]
	ds_read_b128 v[154:157], v22 offset:53248
	s_waitcnt vmcnt(5)
	ds_write_b128 v19, v[200:203]
	v_mfma_f32_16x16x32_f16 v[76:79], v[158:161], v[116:119], v[76:79]
	ds_read_b128 v[116:119], v32 offset:16384
	v_mfma_f32_16x16x32_f16 v[50:53], v[158:161], v[144:147], v[50:53]
	ds_read_b128 v[144:147], v32 offset:18432
	s_waitcnt lgkmcnt(1)
	v_mfma_f32_16x16x32_f16 v[38:41], v[54:57], v[116:119], v[38:41]
	ds_read_b128 v[158:161], v22 offset:55296
	s_waitcnt lgkmcnt(1)
	v_mfma_f32_16x16x32_f16 v[80:83], v[54:57], v[144:147], v[80:83]
	s_waitcnt vmcnt(4)
	ds_write_b128 v20, v[204:207]
	v_mfma_f32_16x16x32_f16 v[46:49], v[58:61], v[116:119], v[46:49]
	s_waitcnt vmcnt(3)
	ds_write_b128 v17, v[124:127] offset:32768
	v_mfma_f32_16x16x32_f16 v[104:107], v[58:61], v[144:147], v[104:107]
	s_waitcnt vmcnt(2)
	ds_write_b128 v18, v[208:211] offset:32768
	v_mfma_f32_16x16x32_f16 v[108:111], v[154:157], v[116:119], v[108:111]
	s_waitcnt vmcnt(1)
	ds_write_b128 v19, v[212:215] offset:32768
	v_mfma_f32_16x16x32_f16 v[112:115], v[154:157], v[144:147], v[112:115]
	s_waitcnt vmcnt(0)
	ds_write_b128 v20, v[220:223] offset:32768
	s_waitcnt lgkmcnt(5)
	v_mfma_f32_16x16x32_f16 v[72:75], v[158:161], v[116:119], v[72:75]
	ds_read_b128 v[116:119], v32 offset:20480
	v_mfma_f32_16x16x32_f16 v[34:37], v[158:161], v[144:147], v[34:37]
	ds_read_b128 v[144:147], v32 offset:22528
	s_waitcnt lgkmcnt(1)
	v_mfma_f32_16x16x32_f16 v[128:131], v[54:57], v[116:119], v[128:131]
	s_waitcnt lgkmcnt(0)
	v_mfma_f32_16x16x32_f16 v[42:45], v[54:57], v[144:147], v[42:45]
	global_load_dwordx4 v[54:57], v[0:1], off offset:896
	v_mfma_f32_16x16x32_f16 v[132:135], v[58:61], v[116:119], v[132:135]
	v_mfma_f32_16x16x32_f16 v[24:27], v[58:61], v[144:147], v[24:27]
	v_mfma_f32_16x16x32_f16 v[140:143], v[154:157], v[116:119], v[140:143]
	v_mfma_f32_16x16x32_f16 v[28:31], v[154:157], v[144:147], v[28:31]
	v_mfma_f32_16x16x32_f16 v[76:79], v[158:161], v[116:119], v[76:79]
	global_load_dwordx4 v[116:119], v[2:3], off offset:896
	global_load_dwordx4 v[162:165], v[4:5], off offset:896
	global_load_dwordx4 v[166:169], v[6:7], off offset:896
	global_load_dwordx4 v[58:61], v[8:9], off offset:896
	global_load_dwordx4 v[188:191], v[10:11], off offset:896
	global_load_dwordx4 v[192:195], v[12:13], off offset:896
	global_load_dwordx4 v[196:199], v[14:15], off offset:896
	s_waitcnt lgkmcnt(0)
	s_barrier
	v_mfma_f32_16x16x32_f16 v[50:53], v[158:161], v[144:147], v[50:53]
	ds_read_b128 v[120:123], v16 offset:32768
	ds_read_b128 v[136:139], v21
	s_waitcnt lgkmcnt(0)
	v_mfma_f32_16x16x32_f16 v[38:41], v[120:123], v[136:139], v[38:41]
	ds_read_b128 v[124:127], v16 offset:34816
	ds_read_b128 v[144:147], v21 offset:2048
	s_waitcnt lgkmcnt(0)
	v_mfma_f32_16x16x32_f16 v[80:83], v[120:123], v[144:147], v[80:83]
	ds_read_b128 v[154:157], v16 offset:36864
	v_mfma_f32_16x16x32_f16 v[46:49], v[124:127], v[136:139], v[46:49]
	ds_read_b128 v[158:161], v16 offset:38912
	v_mfma_f32_16x16x32_f16 v[104:107], v[124:127], v[144:147], v[104:107]
	s_waitcnt lgkmcnt(1)
	v_mfma_f32_16x16x32_f16 v[108:111], v[154:157], v[136:139], v[108:111]
	v_mfma_f32_16x16x32_f16 v[112:115], v[154:157], v[144:147], v[112:115]
	s_waitcnt lgkmcnt(0)
	v_mfma_f32_16x16x32_f16 v[72:75], v[158:161], v[136:139], v[72:75]
	ds_read_b128 v[136:139], v21 offset:4096
	v_mfma_f32_16x16x32_f16 v[34:37], v[158:161], v[144:147], v[34:37]
	ds_read_b128 v[144:147], v21 offset:6144
	s_waitcnt lgkmcnt(1)
	v_mfma_f32_16x16x32_f16 v[128:131], v[120:123], v[136:139], v[128:131]
	s_waitcnt lgkmcnt(0)
	v_mfma_f32_16x16x32_f16 v[42:45], v[120:123], v[144:147], v[42:45]
	ds_read_b128 v[120:123], v22 offset:32768
	v_mfma_f32_16x16x32_f16 v[132:135], v[124:127], v[136:139], v[132:135]
	v_mfma_f32_16x16x32_f16 v[24:27], v[124:127], v[144:147], v[24:27]
	ds_read_b128 v[124:127], v22 offset:34816
	v_mfma_f32_16x16x32_f16 v[140:143], v[154:157], v[136:139], v[140:143]
	s_waitcnt vmcnt(7)
	ds_write_b128 v17, v[54:57] offset:16384
	s_waitcnt vmcnt(6)
; #define GL_LOAD(s_, kt_) if (VAR != 1) { a##s_##0 = GL_A(0, kt_); a##s_##1 = GL_A(1, kt_); a##s_##2 = GL_A(2, kt_); a##s_##3 = GL_A(3, kt_); b##s_##0 = GL_B(0, kt_); b##s_##1 = GL_B(1, kt_); b##s_##2 = GL_B(2, kt_); b##s_##3 = GL_B(3, kt_); }
; #define LDS_STORE(s_, buf_) if (VAR != 2) { LDS_ST1(sA, 0, buf_, a##s_##0) LDS_ST1(sA, 1, buf_, a##s_##1) LDS_ST1(sA, 2, buf_, a##s_##2) LDS_ST1(sA, 3, buf_, a##s_##3) LDS_ST1(sB, 0, buf_, b##s_##0) LDS_ST1(sB, 1, buf_, b##s_##1) LDS_ST1(sB, 2, buf_, b##s_##2) LDS_ST1(sB, 3, buf_, b##s_##3) }
;     ...
;   for (int kt = 0; kt < nk; kt += 2) {
;     if (kt + 2 < nk) { GL_LOAD(0, kt + 2) }
;     MMA_TILE(0)
;     LDS_STORE(1, 1)
;     if (VAR != 4) __syncthreads();
;     if (kt + 3 < nk) { GL_LOAD(1, kt + 3) }
;     MMA_TILE(1)
;     if (kt + 2 < nk) { LDS_STORE(0, 0) }
;     if (VAR != 4) __syncthreads();
	ds_write_b128 v18, v[116:119] offset:16384
	v_mfma_f32_16x16x32_f16 v[28:31], v[154:157], v[144:147], v[28:31]
	ds_read_b128 v[154:157], v22 offset:36864
	s_waitcnt vmcnt(5)
	ds_write_b128 v19, v[162:165] offset:16384
	v_mfma_f32_16x16x32_f16 v[76:79], v[158:161], v[136:139], v[76:79]
	ds_read_b128 v[136:139], v32
	v_mfma_f32_16x16x32_f16 v[50:53], v[158:161], v[144:147], v[50:53]
	ds_read_b128 v[144:147], v32 offset:2048
	s_waitcnt lgkmcnt(1)
	v_mfma_f32_16x16x32_f16 v[38:41], v[120:123], v[136:139], v[38:41]
	ds_read_b128 v[158:161], v22 offset:38912
	s_waitcnt lgkmcnt(1)
	v_mfma_f32_16x16x32_f16 v[80:83], v[120:123], v[144:147], v[80:83]
	s_waitcnt vmcnt(4)
	ds_write_b128 v20, v[166:169] offset:16384
	v_mfma_f32_16x16x32_f16 v[46:49], v[124:127], v[136:139], v[46:49]
	s_waitcnt vmcnt(3)
	ds_write_b128 v17, v[58:61] offset:49152
	v_mfma_f32_16x16x32_f16 v[104:107], v[124:127], v[144:147], v[104:107]
	s_waitcnt vmcnt(2)
	ds_write_b128 v18, v[188:191] offset:49152
	v_mfma_f32_16x16x32_f16 v[108:111], v[154:157], v[136:139], v[108:111]
	s_waitcnt vmcnt(1)
	ds_write_b128 v19, v[192:195] offset:49152
	v_mfma_f32_16x16x32_f16 v[112:115], v[154:157], v[144:147], v[112:115]
	s_waitcnt vmcnt(0)
	ds_write_b128 v20, v[196:199] offset:49152
	s_waitcnt lgkmcnt(5)
	v_mfma_f32_16x16x32_f16 v[72:75], v[158:161], v[136:139], v[72:75]
	ds_read_b128 v[136:139], v32 offset:4096
	v_mfma_f32_16x16x32_f16 v[34:37], v[158:161], v[144:147], v[34:37]
	ds_read_b128 v[144:147], v32 offset:6144
	s_waitcnt lgkmcnt(1)
	v_mfma_f32_16x16x32_f16 v[128:131], v[120:123], v[136:139], v[128:131]
	s_waitcnt lgkmcnt(0)
	v_mfma_f32_16x16x32_f16 v[42:45], v[120:123], v[144:147], v[42:45]
	global_load_dwordx4 v[120:123], v[0:1], off offset:1024
	v_mfma_f32_16x16x32_f16 v[132:135], v[124:127], v[136:139], v[132:135]
	v_mfma_f32_16x16x32_f16 v[24:27], v[124:127], v[144:147], v[24:27]
	v_mfma_f32_16x16x32_f16 v[140:143], v[154:157], v[136:139], v[140:143]
	v_mfma_f32_16x16x32_f16 v[28:31], v[154:157], v[144:147], v[28:31]
	v_mfma_f32_16x16x32_f16 v[76:79], v[158:161], v[136:139], v[76:79]
	global_load_dwordx4 v[136:139], v[2:3], off offset:1024
	global_load_dwordx4 v[200:203], v[4:5], off offset:1024
	global_load_dwordx4 v[204:207], v[6:7], off offset:1024
	global_load_dwordx4 v[124:127], v[8:9], off offset:1024
	global_load_dwordx4 v[208:211], v[10:11], off offset:1024
	global_load_dwordx4 v[212:215], v[12:13], off offset:1024
	global_load_dwordx4 v[220:223], v[14:15], off offset:1024
	s_waitcnt lgkmcnt(0)
	s_barrier
	v_mfma_f32_16x16x32_f16 v[50:53], v[158:161], v[144:147], v[50:53]
	ds_read_b128 v[54:57], v16 offset:49152
	ds_read_b128 v[116:119], v21 offset:16384
	s_waitcnt lgkmcnt(0)
	v_mfma_f32_16x16x32_f16 v[38:41], v[54:57], v[116:119], v[38:41]
	ds_read_b128 v[58:61], v16 offset:51200
	ds_read_b128 v[144:147], v21 offset:18432
	s_waitcnt lgkmcnt(0)
	v_mfma_f32_16x16x32_f16 v[80:83], v[54:57], v[144:147], v[80:83]
	ds_read_b128 v[154:157], v16 offset:53248
	v_mfma_f32_16x16x32_f16 v[46:49], v[58:61], v[116:119], v[46:49]
	ds_read_b128 v[158:161], v16 offset:55296
	v_mfma_f32_16x16x32_f16 v[104:107], v[58:61], v[144:147], v[104:107]
	s_waitcnt lgkmcnt(1)
	v_mfma_f32_16x16x32_f16 v[108:111], v[154:157], v[116:119], v[108:111]
	v_mfma_f32_16x16x32_f16 v[112:115], v[154:157], v[144:147], v[112:115]
	s_waitcnt lgkmcnt(0)
	v_mfma_f32_16x16x32_f16 v[72:75], v[158:161], v[116:119], v[72:75]
	ds_read_b128 v[116:119], v21 offset:20480
	v_mfma_f32_16x16x32_f16 v[34:37], v[158:161], v[144:147], v[34:37]
	ds_read_b128 v[144:147], v21 offset:22528
	s_waitcnt lgkmcnt(1)
	v_mfma_f32_16x16x32_f16 v[128:131], v[54:57], v[116:119], v[128:131]
	s_waitcnt lgkmcnt(0)
	v_mfma_f32_16x16x32_f16 v[42:45], v[54:57], v[144:147], v[42:45]
	ds_read_b128 v[54:57], v22 offset:49152
	v_mfma_f32_16x16x32_f16 v[132:135], v[58:61], v[116:119], v[132:135]
	v_mfma_f32_16x16x32_f16 v[24:27], v[58:61], v[144:147], v[24:27]
	ds_read_b128 v[58:61], v22 offset:51200
	v_mfma_f32_16x16x32_f16 v[140:143], v[154:157], v[116:119], v[140:143]
	s_waitcnt vmcnt(7)
	ds_write_b128 v17, v[120:123]
	s_waitcnt vmcnt(6)
	ds_write_b128 v18, v[136:139]
	v_mfma_f32_16x16x32_f16 v[28:31], v[154:157], v[144:147], v[28:31]
	ds_read_b128 v[154:157], v22 offset:53248
	s_waitcnt vmcnt(5)
	ds_write_b128 v19, v[200:203]
	v_mfma_f32_16x16x32_f16 v[76:79], v[158:161], v[116:119], v[76:79]
	ds_read_b128 v[116:119], v32 offset:16384
	v_mfma_f32_16x16x32_f16 v[50:53], v[158:161], v[144:147], v[50:53]
	ds_read_b128 v[144:147], v32 offset:18432
	s_waitcnt lgkmcnt(1)
	v_mfma_f32_16x16x32_f16 v[38:41], v[54:57], v[116:119], v[38:41]
	ds_read_b128 v[158:161], v22 offset:55296
	s_waitcnt lgkmcnt(1)
	v_mfma_f32_16x16x32_f16 v[80:83], v[54:57], v[144:147], v[80:83]
	s_waitcnt vmcnt(4)
	ds_write_b128 v20, v[204:207]
	v_mfma_f32_16x16x32_f16 v[46:49], v[58:61], v[116:119], v[46:49]
	s_waitcnt vmcnt(3)
	ds_write_b128 v17, v[124:127] offset:32768
	v_mfma_f32_16x16x32_f16 v[104:107], v[58:61], v[144:147], v[104:107]
	s_waitcnt vmcnt(2)
	ds_write_b128 v18, v[208:211] offset:32768
	v_mfma_f32_16x16x32_f16 v[108:111], v[154:157], v[116:119], v[108:111]
	s_waitcnt vmcnt(1)
	ds_write_b128 v19, v[212:215] offset:32768
	v_mfma_f32_16x16x32_f16 v[112:115], v[154:157], v[144:147], v[112:115]
	s_waitcnt vmcnt(0)
	ds_write_b128 v20, v[220:223] offset:32768
	s_waitcnt lgkmcnt(5)
	v_mfma_f32_16x16x32_f16 v[72:75], v[158:161], v[116:119], v[72:75]
	ds_read_b128 v[116:119], v32 offset:20480
	v_mfma_f32_16x16x32_f16 v[34:37], v[158:161], v[144:147], v[34:37]
	ds_read_b128 v[144:147], v32 offset:22528
	s_waitcnt lgkmcnt(1)
	v_mfma_f32_16x16x32_f16 v[128:131], v[54:57], v[116:119], v[128:131]
	s_waitcnt lgkmcnt(0)
	v_mfma_f32_16x16x32_f16 v[42:45], v[54:57], v[144:147], v[42:45]
	global_load_dwordx4 v[54:57], v[0:1], off offset:1152
	v_mfma_f32_16x16x32_f16 v[132:135], v[58:61], v[116:119], v[132:135]
	v_mfma_f32_16x16x32_f16 v[24:27], v[58:61], v[144:147], v[24:27]
	v_mfma_f32_16x16x32_f16 v[140:143], v[154:157], v[116:119], v[140:143]
	v_mfma_f32_16x16x32_f16 v[28:31], v[154:157], v[144:147], v[28:31]
	v_mfma_f32_16x16x32_f16 v[76:79], v[158:161], v[116:119], v[76:79]
	global_load_dwordx4 v[116:119], v[2:3], off offset:1152
	global_load_dwordx4 v[162:165], v[4:5], off offset:1152
	global_load_dwordx4 v[166:169], v[6:7], off offset:1152
	global_load_dwordx4 v[58:61], v[8:9], off offset:1152
	global_load_dwordx4 v[188:191], v[10:11], off offset:1152
	global_load_dwordx4 v[192:195], v[12:13], off offset:1152
	global_load_dwordx4 v[196:199], v[14:15], off offset:1152
	s_waitcnt lgkmcnt(0)
	s_barrier
; #define GL_LOAD(s_, kt_) if (VAR != 1) { a##s_##0 = GL_A(0, kt_); a##s_##1 = GL_A(1, kt_); a##s_##2 = GL_A(2, kt_); a##s_##3 = GL_A(3, kt_); b##s_##0 = GL_B(0, kt_); b##s_##1 = GL_B(1, kt_); b##s_##2 = GL_B(2, kt_); b##s_##3 = GL_B(3, kt_); }
; #define LDS_STORE(s_, buf_) if (VAR != 2) { LDS_ST1(sA, 0, buf_, a##s_##0) LDS_ST1(sA, 1, buf_, a##s_##1) LDS_ST1(sA, 2, buf_, a##s_##2) LDS_ST1(sA, 3, buf_, a##s_##3) LDS_ST1(sB, 0, buf_, b##s_##0) LDS_ST1(sB, 1, buf_, b##s_##1) LDS_ST1(sB, 2, buf_, b##s_##2) LDS_ST1(sB, 3, buf_, b##s_##3) }
;     ...
;   for (int kt = 0; kt < nk; kt += 2) {
;     if (kt + 2 < nk) { GL_LOAD(0, kt + 2) }
;     MMA_TILE(0)
;     LDS_STORE(1, 1)
;     if (VAR != 4) __syncthreads();
;     if (kt + 3 < nk) { GL_LOAD(1, kt + 3) }
;     MMA_TILE(1)
;     if (kt + 2 < nk) { LDS_STORE(0, 0) }
;     if (VAR != 4) __syncthreads();
	v_mfma_f32_16x16x32_f16 v[50:53], v[158:161], v[144:147], v[50:53]
	ds_read_b128 v[120:123], v16 offset:32768
	ds_read_b128 v[136:139], v21
	s_waitcnt lgkmcnt(0)
	v_mfma_f32_16x16x32_f16 v[38:41], v[120:123], v[136:139], v[38:41]
	ds_read_b128 v[124:127], v16 offset:34816
	ds_read_b128 v[144:147], v21 offset:2048
	s_waitcnt lgkmcnt(0)
	v_mfma_f32_16x16x32_f16 v[80:83], v[120:123], v[144:147], v[80:83]
	ds_read_b128 v[154:157], v16 offset:36864
	v_mfma_f32_16x16x32_f16 v[46:49], v[124:127], v[136:139], v[46:49]
	ds_read_b128 v[158:161], v16 offset:38912
	v_mfma_f32_16x16x32_f16 v[104:107], v[124:127], v[144:147], v[104:107]
	s_waitcnt lgkmcnt(1)
	v_mfma_f32_16x16x32_f16 v[108:111], v[154:157], v[136:139], v[108:111]
	v_mfma_f32_16x16x32_f16 v[112:115], v[154:157], v[144:147], v[112:115]
	s_waitcnt lgkmcnt(0)
	v_mfma_f32_16x16x32_f16 v[72:75], v[158:161], v[136:139], v[72:75]
	ds_read_b128 v[136:139], v21 offset:4096
	v_mfma_f32_16x16x32_f16 v[34:37], v[158:161], v[144:147], v[34:37]
	ds_read_b128 v[144:147], v21 offset:6144
	s_waitcnt lgkmcnt(1)
	v_mfma_f32_16x16x32_f16 v[128:131], v[120:123], v[136:139], v[128:131]
	s_waitcnt lgkmcnt(0)
	v_mfma_f32_16x16x32_f16 v[42:45], v[120:123], v[144:147], v[42:45]
	ds_read_b128 v[120:123], v22 offset:32768
	v_mfma_f32_16x16x32_f16 v[132:135], v[124:127], v[136:139], v[132:135]
	v_mfma_f32_16x16x32_f16 v[24:27], v[124:127], v[144:147], v[24:27]
	ds_read_b128 v[124:127], v22 offset:34816
	v_mfma_f32_16x16x32_f16 v[140:143], v[154:157], v[136:139], v[140:143]
	s_waitcnt vmcnt(7)
	ds_write_b128 v17, v[54:57] offset:16384
	s_waitcnt vmcnt(6)
	ds_write_b128 v18, v[116:119] offset:16384
	v_mfma_f32_16x16x32_f16 v[28:31], v[154:157], v[144:147], v[28:31]
	ds_read_b128 v[154:157], v22 offset:36864
	s_waitcnt vmcnt(5)
	ds_write_b128 v19, v[162:165] offset:16384
	v_mfma_f32_16x16x32_f16 v[76:79], v[158:161], v[136:139], v[76:79]
	ds_read_b128 v[136:139], v32
	v_mfma_f32_16x16x32_f16 v[50:53], v[158:161], v[144:147], v[50:53]
	ds_read_b128 v[144:147], v32 offset:2048
	s_waitcnt lgkmcnt(1)
	v_mfma_f32_16x16x32_f16 v[38:41], v[120:123], v[136:139], v[38:41]
	ds_read_b128 v[158:161], v22 offset:38912
	s_waitcnt lgkmcnt(1)
	v_mfma_f32_16x16x32_f16 v[80:83], v[120:123], v[144:147], v[80:83]
	s_waitcnt vmcnt(4)
	ds_write_b128 v20, v[166:169] offset:16384
	v_mfma_f32_16x16x32_f16 v[46:49], v[124:127], v[136:139], v[46:49]
	s_waitcnt vmcnt(3)
	ds_write_b128 v17, v[58:61] offset:49152
	v_mfma_f32_16x16x32_f16 v[104:107], v[124:127], v[144:147], v[104:107]
	s_waitcnt vmcnt(2)
	ds_write_b128 v18, v[188:191] offset:49152
	v_mfma_f32_16x16x32_f16 v[108:111], v[154:157], v[136:139], v[108:111]
	s_waitcnt vmcnt(1)
	ds_write_b128 v19, v[192:195] offset:49152
	v_mfma_f32_16x16x32_f16 v[112:115], v[154:157], v[144:147], v[112:115]
	s_waitcnt vmcnt(0)
	ds_write_b128 v20, v[196:199] offset:49152
	s_waitcnt lgkmcnt(5)
	v_mfma_f32_16x16x32_f16 v[72:75], v[158:161], v[136:139], v[72:75]
	ds_read_b128 v[136:139], v32 offset:4096
	v_mfma_f32_16x16x32_f16 v[34:37], v[158:161], v[144:147], v[34:37]
	ds_read_b128 v[144:147], v32 offset:6144
	s_waitcnt lgkmcnt(1)
	v_mfma_f32_16x16x32_f16 v[128:131], v[120:123], v[136:139], v[128:131]
	s_waitcnt lgkmcnt(0)
	v_mfma_f32_16x16x32_f16 v[42:45], v[120:123], v[144:147], v[42:45]
	global_load_dwordx4 v[120:123], v[0:1], off offset:1280
	v_mfma_f32_16x16x32_f16 v[132:135], v[124:127], v[136:139], v[132:135]
	v_mfma_f32_16x16x32_f16 v[24:27], v[124:127], v[144:147], v[24:27]
	v_mfma_f32_16x16x32_f16 v[140:143], v[154:157], v[136:139], v[140:143]
	v_mfma_f32_16x16x32_f16 v[28:31], v[154:157], v[144:147], v[28:31]
	v_mfma_f32_16x16x32_f16 v[76:79], v[158:161], v[136:139], v[76:79]
	global_load_dwordx4 v[136:139], v[2:3], off offset:1280
	global_load_dwordx4 v[200:203], v[4:5], off offset:1280
	global_load_dwordx4 v[204:207], v[6:7], off offset:1280
	global_load_dwordx4 v[124:127], v[8:9], off offset:1280
	global_load_dwordx4 v[208:211], v[10:11], off offset:1280
	global_load_dwordx4 v[212:215], v[12:13], off offset:1280
	global_load_dwordx4 v[220:223], v[14:15], off offset:1280
	s_waitcnt lgkmcnt(0)
	s_barrier
	v_mfma_f32_16x16x32_f16 v[50:53], v[158:161], v[144:147], v[50:53]
	ds_read_b128 v[54:57], v16 offset:49152
	ds_read_b128 v[116:119], v21 offset:16384
	s_waitcnt lgkmcnt(0)
	v_mfma_f32_16x16x32_f16 v[38:41], v[54:57], v[116:119], v[38:41]
	ds_read_b128 v[58:61], v16 offset:51200
	ds_read_b128 v[144:147], v21 offset:18432
	s_waitcnt lgkmcnt(0)
	v_mfma_f32_16x16x32_f16 v[80:83], v[54:57], v[144:147], v[80:83]
	ds_read_b128 v[154:157], v16 offset:53248
	v_mfma_f32_16x16x32_f16 v[46:49], v[58:61], v[116:119], v[46:49]
	ds_read_b128 v[158:161], v16 offset:55296
	v_mfma_f32_16x16x32_f16 v[104:107], v[58:61], v[144:147], v[104:107]
	s_waitcnt lgkmcnt(1)
	v_mfma_f32_16x16x32_f16 v[108:111], v[154:157], v[116:119], v[108:111]
	v_mfma_f32_16x16x32_f16 v[112:115], v[154:157], v[144:147], v[112:115]
	s_waitcnt lgkmcnt(0)
	v_mfma_f32_16x16x32_f16 v[72:75], v[158:161], v[116:119], v[72:75]
	ds_read_b128 v[116:119], v21 offset:20480
	v_mfma_f32_16x16x32_f16 v[34:37], v[158:161], v[144:147], v[34:37]
	ds_read_b128 v[144:147], v21 offset:22528
	s_waitcnt lgkmcnt(1)
	v_mfma_f32_16x16x32_f16 v[128:131], v[54:57], v[116:119], v[128:131]
	s_waitcnt lgkmcnt(0)
	v_mfma_f32_16x16x32_f16 v[42:45], v[54:57], v[144:147], v[42:45]
	ds_read_b128 v[54:57], v22 offset:49152
	v_mfma_f32_16x16x32_f16 v[132:135], v[58:61], v[116:119], v[132:135]
	v_mfma_f32_16x16x32_f16 v[24:27], v[58:61], v[144:147], v[24:27]
	ds_read_b128 v[58:61], v22 offset:51200
	v_mfma_f32_16x16x32_f16 v[140:143], v[154:157], v[116:119], v[140:143]
	s_waitcnt vmcnt(7)
; #define GL_LOAD(s_, kt_) if (VAR != 1) { a##s_##0 = GL_A(0, kt_); a##s_##1 = GL_A(1, kt_); a##s_##2 = GL_A(2, kt_); a##s_##3 = GL_A(3, kt_); b##s_##0 = GL_B(0, kt_); b##s_##1 = GL_B(1, kt_); b##s_##2 = GL_B(2, kt_); b##s_##3 = GL_B(3, kt_); }
; #define LDS_STORE(s_, buf_) if (VAR != 2) { LDS_ST1(sA, 0, buf_, a##s_##0) LDS_ST1(sA, 1, buf_, a##s_##1) LDS_ST1(sA, 2, buf_, a##s_##2) LDS_ST1(sA, 3, buf_, a##s_##3) LDS_ST1(sB, 0, buf_, b##s_##0) LDS_ST1(sB, 1, buf_, b##s_##1) LDS_ST1(sB, 2, buf_, b##s_##2) LDS_ST1(sB, 3, buf_, b##s_##3) }
;     ...
;   for (int kt = 0; kt < nk; kt += 2) {
;     if (kt + 2 < nk) { GL_LOAD(0, kt + 2) }
;     MMA_TILE(0)
;     LDS_STORE(1, 1)
;     if (VAR != 4) __syncthreads();
;     if (kt + 3 < nk) { GL_LOAD(1, kt + 3) }
;     MMA_TILE(1)
;     if (kt + 2 < nk) { LDS_STORE(0, 0) }
;     if (VAR != 4) __syncthreads();
	ds_write_b128 v17, v[120:123]
	s_waitcnt vmcnt(6)
	ds_write_b128 v18, v[136:139]
	v_mfma_f32_16x16x32_f16 v[28:31], v[154:157], v[144:147], v[28:31]
	ds_read_b128 v[154:157], v22 offset:53248
	s_waitcnt vmcnt(5)
	ds_write_b128 v19, v[200:203]
	v_mfma_f32_16x16x32_f16 v[76:79], v[158:161], v[116:119], v[76:79]
	ds_read_b128 v[116:119], v32 offset:16384
	v_mfma_f32_16x16x32_f16 v[50:53], v[158:161], v[144:147], v[50:53]
	ds_read_b128 v[144:147], v32 offset:18432
	s_waitcnt lgkmcnt(1)
	v_mfma_f32_16x16x32_f16 v[38:41], v[54:57], v[116:119], v[38:41]
	ds_read_b128 v[158:161], v22 offset:55296
	s_waitcnt lgkmcnt(1)
	v_mfma_f32_16x16x32_f16 v[80:83], v[54:57], v[144:147], v[80:83]
	s_waitcnt vmcnt(4)
	ds_write_b128 v20, v[204:207]
	v_mfma_f32_16x16x32_f16 v[46:49], v[58:61], v[116:119], v[46:49]
	s_waitcnt vmcnt(3)
	ds_write_b128 v17, v[124:127] offset:32768
	v_mfma_f32_16x16x32_f16 v[104:107], v[58:61], v[144:147], v[104:107]
	s_waitcnt vmcnt(2)
	ds_write_b128 v18, v[208:211] offset:32768
	v_mfma_f32_16x16x32_f16 v[108:111], v[154:157], v[116:119], v[108:111]
	s_waitcnt vmcnt(1)
	ds_write_b128 v19, v[212:215] offset:32768
	v_mfma_f32_16x16x32_f16 v[112:115], v[154:157], v[144:147], v[112:115]
	s_waitcnt vmcnt(0)
	ds_write_b128 v20, v[220:223] offset:32768
	s_waitcnt lgkmcnt(5)
	v_mfma_f32_16x16x32_f16 v[72:75], v[158:161], v[116:119], v[72:75]
	ds_read_b128 v[116:119], v32 offset:20480
	v_mfma_f32_16x16x32_f16 v[34:37], v[158:161], v[144:147], v[34:37]
	ds_read_b128 v[144:147], v32 offset:22528
	s_waitcnt lgkmcnt(1)
	v_mfma_f32_16x16x32_f16 v[128:131], v[54:57], v[116:119], v[128:131]
	s_waitcnt lgkmcnt(0)
	v_mfma_f32_16x16x32_f16 v[42:45], v[54:57], v[144:147], v[42:45]
	global_load_dwordx4 v[54:57], v[0:1], off offset:1408
	v_mfma_f32_16x16x32_f16 v[132:135], v[58:61], v[116:119], v[132:135]
	v_mfma_f32_16x16x32_f16 v[24:27], v[58:61], v[144:147], v[24:27]
	v_mfma_f32_16x16x32_f16 v[140:143], v[154:157], v[116:119], v[140:143]
	v_mfma_f32_16x16x32_f16 v[28:31], v[154:157], v[144:147], v[28:31]
	v_mfma_f32_16x16x32_f16 v[76:79], v[158:161], v[116:119], v[76:79]
	global_load_dwordx4 v[116:119], v[2:3], off offset:1408
	global_load_dwordx4 v[162:165], v[4:5], off offset:1408
	global_load_dwordx4 v[166:169], v[6:7], off offset:1408
	global_load_dwordx4 v[58:61], v[8:9], off offset:1408
	global_load_dwordx4 v[188:191], v[10:11], off offset:1408
	global_load_dwordx4 v[192:195], v[12:13], off offset:1408
	global_load_dwordx4 v[196:199], v[14:15], off offset:1408
	s_waitcnt lgkmcnt(0)
	s_barrier
	v_mfma_f32_16x16x32_f16 v[50:53], v[158:161], v[144:147], v[50:53]
	ds_read_b128 v[120:123], v16 offset:32768
	ds_read_b128 v[136:139], v21
	s_waitcnt lgkmcnt(0)
	v_mfma_f32_16x16x32_f16 v[38:41], v[120:123], v[136:139], v[38:41]
	ds_read_b128 v[124:127], v16 offset:34816
	ds_read_b128 v[144:147], v21 offset:2048
	s_waitcnt lgkmcnt(0)
	v_mfma_f32_16x16x32_f16 v[80:83], v[120:123], v[144:147], v[80:83]
	ds_read_b128 v[154:157], v16 offset:36864
	v_mfma_f32_16x16x32_f16 v[46:49], v[124:127], v[136:139], v[46:49]
	ds_read_b128 v[158:161], v16 offset:38912
	v_mfma_f32_16x16x32_f16 v[104:107], v[124:127], v[144:147], v[104:107]
	s_waitcnt lgkmcnt(1)
	v_mfma_f32_16x16x32_f16 v[108:111], v[154:157], v[136:139], v[108:111]
	v_mfma_f32_16x16x32_f16 v[112:115], v[154:157], v[144:147], v[112:115]
	s_waitcnt lgkmcnt(0)
	v_mfma_f32_16x16x32_f16 v[72:75], v[158:161], v[136:139], v[72:75]
	ds_read_b128 v[136:139], v21 offset:4096
	v_mfma_f32_16x16x32_f16 v[34:37], v[158:161], v[144:147], v[34:37]
	ds_read_b128 v[144:147], v21 offset:6144
	s_waitcnt lgkmcnt(1)
	v_mfma_f32_16x16x32_f16 v[128:131], v[120:123], v[136:139], v[128:131]
	s_waitcnt lgkmcnt(0)
	v_mfma_f32_16x16x32_f16 v[42:45], v[120:123], v[144:147], v[42:45]
	ds_read_b128 v[120:123], v22 offset:32768
	v_mfma_f32_16x16x32_f16 v[132:135], v[124:127], v[136:139], v[132:135]
	v_mfma_f32_16x16x32_f16 v[24:27], v[124:127], v[144:147], v[24:27]
	ds_read_b128 v[124:127], v22 offset:34816
	v_mfma_f32_16x16x32_f16 v[140:143], v[154:157], v[136:139], v[140:143]
	s_waitcnt vmcnt(7)
	ds_write_b128 v17, v[54:57] offset:16384
	s_waitcnt vmcnt(6)
	ds_write_b128 v18, v[116:119] offset:16384
	v_mfma_f32_16x16x32_f16 v[28:31], v[154:157], v[144:147], v[28:31]
	ds_read_b128 v[154:157], v22 offset:36864
	s_waitcnt vmcnt(5)
	ds_write_b128 v19, v[162:165] offset:16384
	v_mfma_f32_16x16x32_f16 v[76:79], v[158:161], v[136:139], v[76:79]
	ds_read_b128 v[136:139], v32
	v_mfma_f32_16x16x32_f16 v[50:53], v[158:161], v[144:147], v[50:53]
	ds_read_b128 v[144:147], v32 offset:2048
	s_waitcnt lgkmcnt(1)
	v_mfma_f32_16x16x32_f16 v[38:41], v[120:123], v[136:139], v[38:41]
	ds_read_b128 v[158:161], v22 offset:38912
	s_waitcnt lgkmcnt(1)
	v_mfma_f32_16x16x32_f16 v[80:83], v[120:123], v[144:147], v[80:83]
	s_waitcnt vmcnt(4)
	ds_write_b128 v20, v[166:169] offset:16384
	v_mfma_f32_16x16x32_f16 v[46:49], v[124:127], v[136:139], v[46:49]
	s_waitcnt vmcnt(3)
	ds_write_b128 v17, v[58:61] offset:49152
	v_mfma_f32_16x16x32_f16 v[104:107], v[124:127], v[144:147], v[104:107]
	s_waitcnt vmcnt(2)
	ds_write_b128 v18, v[188:191] offset:49152
	v_mfma_f32_16x16x32_f16 v[108:111], v[154:157], v[136:139], v[108:111]
	s_waitcnt vmcnt(1)
	ds_write_b128 v19, v[192:195] offset:49152
	v_mfma_f32_16x16x32_f16 v[112:115], v[154:157], v[144:147], v[112:115]
	s_waitcnt vmcnt(0)
	ds_write_b128 v20, v[196:199] offset:49152
	s_waitcnt lgkmcnt(5)
	v_mfma_f32_16x16x32_f16 v[72:75], v[158:161], v[136:139], v[72:75]
	ds_read_b128 v[136:139], v32 offset:4096
	v_mfma_f32_16x16x32_f16 v[34:37], v[158:161], v[144:147], v[34:37]
	ds_read_b128 v[144:147], v32 offset:6144
	s_waitcnt lgkmcnt(1)
	v_mfma_f32_16x16x32_f16 v[128:131], v[120:123], v[136:139], v[128:131]
	s_waitcnt lgkmcnt(0)
	v_mfma_f32_16x16x32_f16 v[42:45], v[120:123], v[144:147], v[42:45]
	global_load_dwordx4 v[120:123], v[0:1], off offset:1536
	v_mfma_f32_16x16x32_f16 v[132:135], v[124:127], v[136:139], v[132:135]
	v_mfma_f32_16x16x32_f16 v[24:27], v[124:127], v[144:147], v[24:27]
	v_mfma_f32_16x16x32_f16 v[140:143], v[154:157], v[136:139], v[140:143]
	v_mfma_f32_16x16x32_f16 v[28:31], v[154:157], v[144:147], v[28:31]
	v_mfma_f32_16x16x32_f16 v[76:79], v[158:161], v[136:139], v[76:79]
	global_load_dwordx4 v[136:139], v[2:3], off offset:1536
	global_load_dwordx4 v[200:203], v[4:5], off offset:1536
	global_load_dwordx4 v[204:207], v[6:7], off offset:1536
	global_load_dwordx4 v[124:127], v[8:9], off offset:1536
	global_load_dwordx4 v[208:211], v[10:11], off offset:1536
	global_load_dwordx4 v[212:215], v[12:13], off offset:1536
	global_load_dwordx4 v[220:223], v[14:15], off offset:1536
	s_waitcnt lgkmcnt(0)
	s_barrier
; #define GL_LOAD(s_, kt_) if (VAR != 1) { a##s_##0 = GL_A(0, kt_); a##s_##1 = GL_A(1, kt_); a##s_##2 = GL_A(2, kt_); a##s_##3 = GL_A(3, kt_); b##s_##0 = GL_B(0, kt_); b##s_##1 = GL_B(1, kt_); b##s_##2 = GL_B(2, kt_); b##s_##3 = GL_B(3, kt_); }
; #define LDS_STORE(s_, buf_) if (VAR != 2) { LDS_ST1(sA, 0, buf_, a##s_##0) LDS_ST1(sA, 1, buf_, a##s_##1) LDS_ST1(sA, 2, buf_, a##s_##2) LDS_ST1(sA, 3, buf_, a##s_##3) LDS_ST1(sB, 0, buf_, b##s_##0) LDS_ST1(sB, 1, buf_, b##s_##1) LDS_ST1(sB, 2, buf_, b##s_##2) LDS_ST1(sB, 3, buf_, b##s_##3) }
;     ...
;   for (int kt = 0; kt < nk; kt += 2) {
;     if (kt + 2 < nk) { GL_LOAD(0, kt + 2) }
;     MMA_TILE(0)
;     LDS_STORE(1, 1)
;     if (VAR != 4) __syncthreads();
;     if (kt + 3 < nk) { GL_LOAD(1, kt + 3) }
;     MMA_TILE(1)
;     if (kt + 2 < nk) { LDS_STORE(0, 0) }
;     if (VAR != 4) __syncthreads();
	v_mfma_f32_16x16x32_f16 v[50:53], v[158:161], v[144:147], v[50:53]
	ds_read_b128 v[54:57], v16 offset:49152
	ds_read_b128 v[116:119], v21 offset:16384
	s_waitcnt lgkmcnt(0)
	v_mfma_f32_16x16x32_f16 v[38:41], v[54:57], v[116:119], v[38:41]
	ds_read_b128 v[58:61], v16 offset:51200
	ds_read_b128 v[144:147], v21 offset:18432
	s_waitcnt lgkmcnt(0)
	v_mfma_f32_16x16x32_f16 v[80:83], v[54:57], v[144:147], v[80:83]
	ds_read_b128 v[154:157], v16 offset:53248
	v_mfma_f32_16x16x32_f16 v[46:49], v[58:61], v[116:119], v[46:49]
	ds_read_b128 v[158:161], v16 offset:55296
	v_mfma_f32_16x16x32_f16 v[104:107], v[58:61], v[144:147], v[104:107]
	s_waitcnt lgkmcnt(1)
	v_mfma_f32_16x16x32_f16 v[108:111], v[154:157], v[116:119], v[108:111]
	v_mfma_f32_16x16x32_f16 v[112:115], v[154:157], v[144:147], v[112:115]
	s_waitcnt lgkmcnt(0)
	v_mfma_f32_16x16x32_f16 v[72:75], v[158:161], v[116:119], v[72:75]
	ds_read_b128 v[116:119], v21 offset:20480
	v_mfma_f32_16x16x32_f16 v[34:37], v[158:161], v[144:147], v[34:37]
	ds_read_b128 v[144:147], v21 offset:22528
	s_waitcnt lgkmcnt(1)
	v_mfma_f32_16x16x32_f16 v[128:131], v[54:57], v[116:119], v[128:131]
	s_waitcnt lgkmcnt(0)
	v_mfma_f32_16x16x32_f16 v[42:45], v[54:57], v[144:147], v[42:45]
	ds_read_b128 v[54:57], v22 offset:49152
	v_mfma_f32_16x16x32_f16 v[132:135], v[58:61], v[116:119], v[132:135]
	v_mfma_f32_16x16x32_f16 v[24:27], v[58:61], v[144:147], v[24:27]
	ds_read_b128 v[58:61], v22 offset:51200
	v_mfma_f32_16x16x32_f16 v[140:143], v[154:157], v[116:119], v[140:143]
	s_waitcnt vmcnt(7)
	ds_write_b128 v17, v[120:123]
	s_waitcnt vmcnt(6)
	ds_write_b128 v18, v[136:139]
	v_mfma_f32_16x16x32_f16 v[28:31], v[154:157], v[144:147], v[28:31]
	ds_read_b128 v[154:157], v22 offset:53248
	s_waitcnt vmcnt(5)
	ds_write_b128 v19, v[200:203]
	v_mfma_f32_16x16x32_f16 v[76:79], v[158:161], v[116:119], v[76:79]
	ds_read_b128 v[116:119], v32 offset:16384
	v_mfma_f32_16x16x32_f16 v[50:53], v[158:161], v[144:147], v[50:53]
	ds_read_b128 v[144:147], v32 offset:18432
	s_waitcnt lgkmcnt(1)
	v_mfma_f32_16x16x32_f16 v[38:41], v[54:57], v[116:119], v[38:41]
	ds_read_b128 v[158:161], v22 offset:55296
	s_waitcnt lgkmcnt(1)
	v_mfma_f32_16x16x32_f16 v[80:83], v[54:57], v[144:147], v[80:83]
	s_waitcnt vmcnt(4)
	ds_write_b128 v20, v[204:207]
	v_mfma_f32_16x16x32_f16 v[46:49], v[58:61], v[116:119], v[46:49]
	s_waitcnt vmcnt(3)
	ds_write_b128 v17, v[124:127] offset:32768
	v_mfma_f32_16x16x32_f16 v[104:107], v[58:61], v[144:147], v[104:107]
	s_waitcnt vmcnt(2)
	ds_write_b128 v18, v[208:211] offset:32768
	v_mfma_f32_16x16x32_f16 v[108:111], v[154:157], v[116:119], v[108:111]
	s_waitcnt vmcnt(1)
	ds_write_b128 v19, v[212:215] offset:32768
	v_mfma_f32_16x16x32_f16 v[112:115], v[154:157], v[144:147], v[112:115]
	s_waitcnt vmcnt(0)
	ds_write_b128 v20, v[220:223] offset:32768
	s_waitcnt lgkmcnt(5)
	v_mfma_f32_16x16x32_f16 v[72:75], v[158:161], v[116:119], v[72:75]
	ds_read_b128 v[116:119], v32 offset:20480
	v_mfma_f32_16x16x32_f16 v[34:37], v[158:161], v[144:147], v[34:37]
	ds_read_b128 v[144:147], v32 offset:22528
	s_waitcnt lgkmcnt(1)
	v_mfma_f32_16x16x32_f16 v[128:131], v[54:57], v[116:119], v[128:131]
	s_waitcnt lgkmcnt(0)
	v_mfma_f32_16x16x32_f16 v[42:45], v[54:57], v[144:147], v[42:45]
	global_load_dwordx4 v[54:57], v[0:1], off offset:1664
	v_mfma_f32_16x16x32_f16 v[132:135], v[58:61], v[116:119], v[132:135]
	v_mfma_f32_16x16x32_f16 v[24:27], v[58:61], v[144:147], v[24:27]
	v_mfma_f32_16x16x32_f16 v[140:143], v[154:157], v[116:119], v[140:143]
	v_mfma_f32_16x16x32_f16 v[28:31], v[154:157], v[144:147], v[28:31]
	v_mfma_f32_16x16x32_f16 v[76:79], v[158:161], v[116:119], v[76:79]
	global_load_dwordx4 v[116:119], v[2:3], off offset:1664
	global_load_dwordx4 v[162:165], v[4:5], off offset:1664
	global_load_dwordx4 v[166:169], v[6:7], off offset:1664
	global_load_dwordx4 v[58:61], v[8:9], off offset:1664
	global_load_dwordx4 v[188:191], v[10:11], off offset:1664
	global_load_dwordx4 v[192:195], v[12:13], off offset:1664
	global_load_dwordx4 v[196:199], v[14:15], off offset:1664
	s_waitcnt lgkmcnt(0)
	s_barrier
	v_mfma_f32_16x16x32_f16 v[50:53], v[158:161], v[144:147], v[50:53]
	ds_read_b128 v[120:123], v16 offset:32768
	ds_read_b128 v[136:139], v21
	s_waitcnt lgkmcnt(0)
	v_mfma_f32_16x16x32_f16 v[38:41], v[120:123], v[136:139], v[38:41]
	ds_read_b128 v[124:127], v16 offset:34816
	ds_read_b128 v[144:147], v21 offset:2048
	s_waitcnt lgkmcnt(0)
	v_mfma_f32_16x16x32_f16 v[80:83], v[120:123], v[144:147], v[80:83]
	ds_read_b128 v[154:157], v16 offset:36864
	v_mfma_f32_16x16x32_f16 v[46:49], v[124:127], v[136:139], v[46:49]
	ds_read_b128 v[158:161], v16 offset:38912
	v_mfma_f32_16x16x32_f16 v[104:107], v[124:127], v[144:147], v[104:107]
	s_waitcnt lgkmcnt(1)
	v_mfma_f32_16x16x32_f16 v[108:111], v[154:157], v[136:139], v[108:111]
	v_mfma_f32_16x16x32_f16 v[112:115], v[154:157], v[144:147], v[112:115]
	s_waitcnt lgkmcnt(0)
	v_mfma_f32_16x16x32_f16 v[72:75], v[158:161], v[136:139], v[72:75]
	ds_read_b128 v[136:139], v21 offset:4096
	v_mfma_f32_16x16x32_f16 v[34:37], v[158:161], v[144:147], v[34:37]
	ds_read_b128 v[144:147], v21 offset:6144
	s_waitcnt lgkmcnt(1)
	v_mfma_f32_16x16x32_f16 v[128:131], v[120:123], v[136:139], v[128:131]
	s_waitcnt lgkmcnt(0)
	v_mfma_f32_16x16x32_f16 v[42:45], v[120:123], v[144:147], v[42:45]
	ds_read_b128 v[120:123], v22 offset:32768
	v_mfma_f32_16x16x32_f16 v[132:135], v[124:127], v[136:139], v[132:135]
	v_mfma_f32_16x16x32_f16 v[24:27], v[124:127], v[144:147], v[24:27]
	ds_read_b128 v[124:127], v22 offset:34816
	v_mfma_f32_16x16x32_f16 v[140:143], v[154:157], v[136:139], v[140:143]
	s_waitcnt vmcnt(7)
	ds_write_b128 v17, v[54:57] offset:16384
	s_waitcnt vmcnt(6)
; #define GL_LOAD(s_, kt_) if (VAR != 1) { a##s_##0 = GL_A(0, kt_); a##s_##1 = GL_A(1, kt_); a##s_##2 = GL_A(2, kt_); a##s_##3 = GL_A(3, kt_); b##s_##0 = GL_B(0, kt_); b##s_##1 = GL_B(1, kt_); b##s_##2 = GL_B(2, kt_); b##s_##3 = GL_B(3, kt_); }
; #define LDS_STORE(s_, buf_) if (VAR != 2) { LDS_ST1(sA, 0, buf_, a##s_##0) LDS_ST1(sA, 1, buf_, a##s_##1) LDS_ST1(sA, 2, buf_, a##s_##2) LDS_ST1(sA, 3, buf_, a##s_##3) LDS_ST1(sB, 0, buf_, b##s_##0) LDS_ST1(sB, 1, buf_, b##s_##1) LDS_ST1(sB, 2, buf_, b##s_##2) LDS_ST1(sB, 3, buf_, b##s_##3) }
;     ...
;   for (int kt = 0; kt < nk; kt += 2) {
;     if (kt + 2 < nk) { GL_LOAD(0, kt + 2) }
;     MMA_TILE(0)
;     LDS_STORE(1, 1)
;     if (VAR != 4) __syncthreads();
;     if (kt + 3 < nk) { GL_LOAD(1, kt + 3) }
;     MMA_TILE(1)
;     if (kt + 2 < nk) { LDS_STORE(0, 0) }
;     if (VAR != 4) __syncthreads();
	ds_write_b128 v18, v[116:119] offset:16384
	v_mfma_f32_16x16x32_f16 v[28:31], v[154:157], v[144:147], v[28:31]
	ds_read_b128 v[154:157], v22 offset:36864
	s_waitcnt vmcnt(5)
	ds_write_b128 v19, v[162:165] offset:16384
	v_mfma_f32_16x16x32_f16 v[76:79], v[158:161], v[136:139], v[76:79]
	ds_read_b128 v[136:139], v32
	v_mfma_f32_16x16x32_f16 v[50:53], v[158:161], v[144:147], v[50:53]
	ds_read_b128 v[144:147], v32 offset:2048
	s_waitcnt lgkmcnt(1)
	v_mfma_f32_16x16x32_f16 v[38:41], v[120:123], v[136:139], v[38:41]
	ds_read_b128 v[158:161], v22 offset:38912
	s_waitcnt lgkmcnt(1)
	v_mfma_f32_16x16x32_f16 v[80:83], v[120:123], v[144:147], v[80:83]
	s_waitcnt vmcnt(4)
	ds_write_b128 v20, v[166:169] offset:16384
	v_mfma_f32_16x16x32_f16 v[46:49], v[124:127], v[136:139], v[46:49]
	s_waitcnt vmcnt(3)
	ds_write_b128 v17, v[58:61] offset:49152
	v_mfma_f32_16x16x32_f16 v[104:107], v[124:127], v[144:147], v[104:107]
	s_waitcnt vmcnt(2)
	ds_write_b128 v18, v[188:191] offset:49152
	v_mfma_f32_16x16x32_f16 v[108:111], v[154:157], v[136:139], v[108:111]
	s_waitcnt vmcnt(1)
	ds_write_b128 v19, v[192:195] offset:49152
	v_mfma_f32_16x16x32_f16 v[112:115], v[154:157], v[144:147], v[112:115]
	s_waitcnt vmcnt(0)
	ds_write_b128 v20, v[196:199] offset:49152
	s_waitcnt lgkmcnt(5)
	v_mfma_f32_16x16x32_f16 v[72:75], v[158:161], v[136:139], v[72:75]
	ds_read_b128 v[136:139], v32 offset:4096
	v_mfma_f32_16x16x32_f16 v[34:37], v[158:161], v[144:147], v[34:37]
	ds_read_b128 v[144:147], v32 offset:6144
	s_waitcnt lgkmcnt(1)
	v_mfma_f32_16x16x32_f16 v[128:131], v[120:123], v[136:139], v[128:131]
	s_waitcnt lgkmcnt(0)
	v_mfma_f32_16x16x32_f16 v[42:45], v[120:123], v[144:147], v[42:45]
	global_load_dwordx4 v[120:123], v[0:1], off offset:1792
	v_mfma_f32_16x16x32_f16 v[132:135], v[124:127], v[136:139], v[132:135]
	v_mfma_f32_16x16x32_f16 v[24:27], v[124:127], v[144:147], v[24:27]
	v_mfma_f32_16x16x32_f16 v[140:143], v[154:157], v[136:139], v[140:143]
	v_mfma_f32_16x16x32_f16 v[28:31], v[154:157], v[144:147], v[28:31]
	v_mfma_f32_16x16x32_f16 v[76:79], v[158:161], v[136:139], v[76:79]
	global_load_dwordx4 v[136:139], v[2:3], off offset:1792
	global_load_dwordx4 v[200:203], v[4:5], off offset:1792
	global_load_dwordx4 v[204:207], v[6:7], off offset:1792
	global_load_dwordx4 v[124:127], v[8:9], off offset:1792
	global_load_dwordx4 v[208:211], v[10:11], off offset:1792
	global_load_dwordx4 v[212:215], v[12:13], off offset:1792
	global_load_dwordx4 v[220:223], v[14:15], off offset:1792
	s_waitcnt lgkmcnt(0)
	s_barrier
	v_mfma_f32_16x16x32_f16 v[50:53], v[158:161], v[144:147], v[50:53]
	ds_read_b128 v[54:57], v16 offset:49152
	ds_read_b128 v[116:119], v21 offset:16384
	s_waitcnt lgkmcnt(0)
	v_mfma_f32_16x16x32_f16 v[38:41], v[54:57], v[116:119], v[38:41]
	ds_read_b128 v[58:61], v16 offset:51200
	ds_read_b128 v[144:147], v21 offset:18432
	s_waitcnt lgkmcnt(0)
	v_mfma_f32_16x16x32_f16 v[80:83], v[54:57], v[144:147], v[80:83]
	ds_read_b128 v[154:157], v16 offset:53248
	v_mfma_f32_16x16x32_f16 v[46:49], v[58:61], v[116:119], v[46:49]
	ds_read_b128 v[158:161], v16 offset:55296
	v_mfma_f32_16x16x32_f16 v[104:107], v[58:61], v[144:147], v[104:107]
	s_waitcnt lgkmcnt(1)
	v_mfma_f32_16x16x32_f16 v[108:111], v[154:157], v[116:119], v[108:111]
	v_mfma_f32_16x16x32_f16 v[112:115], v[154:157], v[144:147], v[112:115]
	s_waitcnt lgkmcnt(0)
	v_mfma_f32_16x16x32_f16 v[72:75], v[158:161], v[116:119], v[72:75]
	ds_read_b128 v[116:119], v21 offset:20480
	v_mfma_f32_16x16x32_f16 v[34:37], v[158:161], v[144:147], v[34:37]
	ds_read_b128 v[144:147], v21 offset:22528
	s_waitcnt lgkmcnt(1)
	v_mfma_f32_16x16x32_f16 v[128:131], v[54:57], v[116:119], v[128:131]
	s_waitcnt lgkmcnt(0)
	v_mfma_f32_16x16x32_f16 v[42:45], v[54:57], v[144:147], v[42:45]
	ds_read_b128 v[54:57], v22 offset:49152
	v_mfma_f32_16x16x32_f16 v[132:135], v[58:61], v[116:119], v[132:135]
	v_mfma_f32_16x16x32_f16 v[24:27], v[58:61], v[144:147], v[24:27]
	ds_read_b128 v[58:61], v22 offset:51200
	v_mfma_f32_16x16x32_f16 v[140:143], v[154:157], v[116:119], v[140:143]
	s_waitcnt vmcnt(7)
	ds_write_b128 v17, v[120:123]
	s_waitcnt vmcnt(6)
	ds_write_b128 v18, v[136:139]
	v_mfma_f32_16x16x32_f16 v[28:31], v[154:157], v[144:147], v[28:31]
	ds_read_b128 v[154:157], v22 offset:53248
	s_waitcnt vmcnt(5)
	ds_write_b128 v19, v[200:203]
	v_mfma_f32_16x16x32_f16 v[76:79], v[158:161], v[116:119], v[76:79]
	ds_read_b128 v[116:119], v32 offset:16384
	v_mfma_f32_16x16x32_f16 v[50:53], v[158:161], v[144:147], v[50:53]
	ds_read_b128 v[144:147], v32 offset:18432
	s_waitcnt lgkmcnt(1)
	v_mfma_f32_16x16x32_f16 v[38:41], v[54:57], v[116:119], v[38:41]
	ds_read_b128 v[158:161], v22 offset:55296
	s_waitcnt lgkmcnt(1)
	v_mfma_f32_16x16x32_f16 v[80:83], v[54:57], v[144:147], v[80:83]
	s_waitcnt vmcnt(4)
	ds_write_b128 v20, v[204:207]
	v_mfma_f32_16x16x32_f16 v[46:49], v[58:61], v[116:119], v[46:49]
	s_waitcnt vmcnt(3)
	ds_write_b128 v17, v[124:127] offset:32768
	v_mfma_f32_16x16x32_f16 v[104:107], v[58:61], v[144:147], v[104:107]
	s_waitcnt vmcnt(2)
	ds_write_b128 v18, v[208:211] offset:32768
	v_mfma_f32_16x16x32_f16 v[108:111], v[154:157], v[116:119], v[108:111]
	s_waitcnt vmcnt(1)
	ds_write_b128 v19, v[212:215] offset:32768
	v_mfma_f32_16x16x32_f16 v[112:115], v[154:157], v[144:147], v[112:115]
	s_waitcnt vmcnt(0)
	ds_write_b128 v20, v[220:223] offset:32768
	s_waitcnt lgkmcnt(5)
	v_mfma_f32_16x16x32_f16 v[72:75], v[158:161], v[116:119], v[72:75]
	ds_read_b128 v[116:119], v32 offset:20480
	v_mfma_f32_16x16x32_f16 v[34:37], v[158:161], v[144:147], v[34:37]
	ds_read_b128 v[144:147], v32 offset:22528
	s_waitcnt lgkmcnt(1)
	v_mfma_f32_16x16x32_f16 v[128:131], v[54:57], v[116:119], v[128:131]
	s_waitcnt lgkmcnt(0)
	v_mfma_f32_16x16x32_f16 v[42:45], v[54:57], v[144:147], v[42:45]
	global_load_dwordx4 v[54:57], v[0:1], off offset:1920
	global_load_dwordx4 v[0:3], v[2:3], off offset:1920
	v_mfma_f32_16x16x32_f16 v[132:135], v[58:61], v[116:119], v[132:135]
	v_mfma_f32_16x16x32_f16 v[24:27], v[58:61], v[144:147], v[24:27]
	v_mfma_f32_16x16x32_f16 v[140:143], v[154:157], v[116:119], v[140:143]
	v_mfma_f32_16x16x32_f16 v[28:31], v[154:157], v[144:147], v[28:31]
	v_mfma_f32_16x16x32_f16 v[76:79], v[158:161], v[116:119], v[76:79]
	global_load_dwordx4 v[116:119], v[4:5], off offset:1920
	global_load_dwordx4 v[4:7], v[6:7], off offset:1920
	global_load_dwordx4 v[58:61], v[8:9], off offset:1920
	global_load_dwordx4 v[8:11], v[10:11], off offset:1920
	global_load_dwordx4 v[162:165], v[12:13], off offset:1920
	global_load_dwordx4 v[12:15], v[14:15], off offset:1920
	s_waitcnt lgkmcnt(0)
	s_barrier
; #define GL_LOAD(s_, kt_) if (VAR != 1) { a##s_##0 = GL_A(0, kt_); a##s_##1 = GL_A(1, kt_); a##s_##2 = GL_A(2, kt_); a##s_##3 = GL_A(3, kt_); b##s_##0 = GL_B(0, kt_); b##s_##1 = GL_B(1, kt_); b##s_##2 = GL_B(2, kt_); b##s_##3 = GL_B(3, kt_); }
; #define LDS_STORE(s_, buf_) if (VAR != 2) { LDS_ST1(sA, 0, buf_, a##s_##0) LDS_ST1(sA, 1, buf_, a##s_##1) LDS_ST1(sA, 2, buf_, a##s_##2) LDS_ST1(sA, 3, buf_, a##s_##3) LDS_ST1(sB, 0, buf_, b##s_##0) LDS_ST1(sB, 1, buf_, b##s_##1) LDS_ST1(sB, 2, buf_, b##s_##2) LDS_ST1(sB, 3, buf_, b##s_##3) }
;     ...
;     MMA_TILE(0)
;     LDS_STORE(1, 1)
;     if (VAR != 4) __syncthreads();
;     if (kt + 3 < nk) { GL_LOAD(1, kt + 3) }
;     MMA_TILE(1)
;     if (kt + 2 < nk) { LDS_STORE(0, 0) }
;     if (VAR != 4) __syncthreads();
	ds_read_b128 v[120:123], v16 offset:32768
	v_mfma_f32_16x16x32_f16 v[50:53], v[158:161], v[144:147], v[50:53]
	ds_read_b128 v[124:127], v16 offset:34816
	ds_read_b128 v[136:139], v21
	ds_read_b128 v[144:147], v21 offset:2048
	ds_read_b128 v[154:157], v16 offset:36864
	ds_read_b128 v[158:161], v16 offset:38912
	s_waitcnt lgkmcnt(3)
	v_mfma_f32_16x16x32_f16 v[38:41], v[120:123], v[136:139], v[38:41]
	v_mfma_f32_16x16x32_f16 v[46:49], v[124:127], v[136:139], v[46:49]
	s_waitcnt lgkmcnt(1)
	v_mfma_f32_16x16x32_f16 v[108:111], v[154:157], v[136:139], v[108:111]
	s_waitcnt lgkmcnt(0)
	v_mfma_f32_16x16x32_f16 v[72:75], v[158:161], v[136:139], v[72:75]
	v_mfma_f32_16x16x32_f16 v[80:83], v[120:123], v[144:147], v[80:83]
	v_mfma_f32_16x16x32_f16 v[104:107], v[124:127], v[144:147], v[104:107]
	v_mfma_f32_16x16x32_f16 v[112:115], v[154:157], v[144:147], v[112:115]
	v_mfma_f32_16x16x32_f16 v[34:37], v[158:161], v[144:147], v[34:37]
	ds_read_b128 v[136:139], v21 offset:4096
	ds_read_b128 v[144:147], v21 offset:6144
	s_waitcnt lgkmcnt(1)
	v_mfma_f32_16x16x32_f16 v[128:131], v[120:123], v[136:139], v[128:131]
	v_mfma_f32_16x16x32_f16 v[132:135], v[124:127], v[136:139], v[132:135]
	v_mfma_f32_16x16x32_f16 v[140:143], v[154:157], v[136:139], v[140:143]
	v_mfma_f32_16x16x32_f16 v[76:79], v[158:161], v[136:139], v[76:79]
	s_waitcnt lgkmcnt(0)
	v_mfma_f32_16x16x32_f16 v[42:45], v[120:123], v[144:147], v[42:45]
	ds_read_b128 v[120:123], v22 offset:32768
	v_mfma_f32_16x16x32_f16 v[24:27], v[124:127], v[144:147], v[24:27]
	v_mfma_f32_16x16x32_f16 v[28:31], v[154:157], v[144:147], v[28:31]
	v_mfma_f32_16x16x32_f16 v[50:53], v[158:161], v[144:147], v[50:53]
	ds_read_b128 v[124:127], v22 offset:34816
	ds_read_b128 v[136:139], v32
	ds_read_b128 v[144:147], v32 offset:2048
	ds_read_b128 v[154:157], v22 offset:36864
	ds_read_b128 v[158:161], v22 offset:38912
	s_waitcnt lgkmcnt(3)
	v_mfma_f32_16x16x32_f16 v[38:41], v[120:123], v[136:139], v[38:41]
	v_mfma_f32_16x16x32_f16 v[46:49], v[124:127], v[136:139], v[46:49]
	s_waitcnt lgkmcnt(1)
	v_mfma_f32_16x16x32_f16 v[108:111], v[154:157], v[136:139], v[108:111]
	s_waitcnt lgkmcnt(0)
	v_mfma_f32_16x16x32_f16 v[72:75], v[158:161], v[136:139], v[72:75]
	v_mfma_f32_16x16x32_f16 v[80:83], v[120:123], v[144:147], v[80:83]
	v_mfma_f32_16x16x32_f16 v[104:107], v[124:127], v[144:147], v[104:107]
	v_mfma_f32_16x16x32_f16 v[112:115], v[154:157], v[144:147], v[112:115]
	v_mfma_f32_16x16x32_f16 v[34:37], v[158:161], v[144:147], v[34:37]
	ds_read_b128 v[136:139], v32 offset:4096
	ds_read_b128 v[144:147], v32 offset:6144
	s_waitcnt vmcnt(7)
	ds_write_b128 v17, v[54:57] offset:16384
	s_waitcnt vmcnt(6)
	ds_write_b128 v18, v[0:3] offset:16384
	s_waitcnt vmcnt(5)
	ds_write_b128 v19, v[116:119] offset:16384
	s_waitcnt vmcnt(4)
	ds_write_b128 v20, v[4:7] offset:16384
	s_waitcnt vmcnt(3)
	ds_write_b128 v17, v[58:61] offset:49152
	s_waitcnt vmcnt(2)
	ds_write_b128 v18, v[8:11] offset:49152
	s_waitcnt vmcnt(1)
	ds_write_b128 v19, v[162:165] offset:49152
	s_waitcnt vmcnt(0)
	ds_write_b128 v20, v[12:15] offset:49152
	s_waitcnt lgkmcnt(0)
	s_barrier
; #define LDS_STORE(s_, buf_) if (VAR != 2) { LDS_ST1(sA, 0, buf_, a##s_##0) LDS_ST1(sA, 1, buf_, a##s_##1) LDS_ST1(sA, 2, buf_, a##s_##2) LDS_ST1(sA, 3, buf_, a##s_##3) LDS_ST1(sB, 0, buf_, b##s_##0) LDS_ST1(sB, 1, buf_, b##s_##1) LDS_ST1(sB, 2, buf_, b##s_##2) LDS_ST1(sB, 3, buf_, b##s_##3) }
;     ...
;     MMA_TILE(1)
;     if (kt + 2 < nk) { LDS_STORE(0, 0) }
;     if (VAR != 4) __syncthreads();
; DI void phase_proj(const Params& P, int l, char* smem) {
;     ...
; #pragma unroll
;       for (int mt = 0; mt < 4; ++mt)
; #pragma unroll
;         for (int nt = 0; nt < 4; ++nt) acc[mt][nt] *= rs[mt];
;       const float* gain = nullptr; bool rope = false; float sc = 1.f; bool sig = false;
;       constexpr float QS = 0.125f * 1.4426950408889634f;
;       if (col0 < C_AK) { gain = P.a_q_norm + l * 64; rope = true; sc = QS; }
;       else if (col0 < C_BQ) { gain = P.a_k_norm + l * 64; rope = true; }
;       else if (col0 < C_BK) { sc = QS; }
;       else if (col0 < C_CQ) { }
;       else if (col0 < C_CK) { gain = P.c_q_norm + l * 64; rope = true; sc = QS; }
;       else if (col0 < C_IQ) { gain = P.c_k_norm + l * 64; rope = true; }
;       else if (col0 < C_IK) { rope = true; sc = 0.125f; }
;       else if (col0 < C_IW) { gain = P.idx_k_norm + l * 64; rope = true; }
;       else if (col0 < C_GL) { sc = 0.5f; }
;       else { sig = true; }
	ds_read_b128 v[0:3], v16 offset:49152
	v_mfma_f32_16x16x32_f16 v[4:7], v[158:161], v[144:147], v[50:53]
	ds_read_b128 v[8:11], v16 offset:51200
	ds_read_b128 v[12:15], v21 offset:16384
	s_nop 0
	ds_read_b128 v[50:53], v21 offset:18432
	ds_read_b128 v[54:57], v16 offset:53248
	ds_read_b128 v[16:19], v16 offset:55296
	s_waitcnt lgkmcnt(3)
	v_mfma_f32_16x16x32_f16 v[38:41], v[0:3], v[12:15], v[38:41]
	v_mfma_f32_16x16x32_f16 v[46:49], v[8:11], v[12:15], v[46:49]
	s_waitcnt lgkmcnt(1)
	v_mfma_f32_16x16x32_f16 v[58:61], v[54:57], v[12:15], v[108:111]
	s_waitcnt lgkmcnt(0)
	v_mfma_f32_16x16x32_f16 v[12:15], v[16:19], v[12:15], v[72:75]
	v_mfma_f32_16x16x32_f16 v[72:75], v[0:3], v[50:53], v[80:83]
	v_mfma_f32_16x16x32_f16 v[80:83], v[8:11], v[50:53], v[104:107]
	v_mfma_f32_16x16x32_f16 v[104:107], v[54:57], v[50:53], v[112:115]
	v_mfma_f32_16x16x32_f16 v[34:37], v[16:19], v[50:53], v[34:37]
	ds_read_b128 v[50:53], v21 offset:20480
	ds_read_b128 v[108:111], v21 offset:22528
	v_mfma_f32_16x16x32_f16 v[128:131], v[120:123], v[136:139], v[128:131]
	v_mfma_f32_16x16x32_f16 v[132:135], v[124:127], v[136:139], v[132:135]
	v_mfma_f32_16x16x32_f16 v[140:143], v[154:157], v[136:139], v[140:143]
	v_mfma_f32_16x16x32_f16 v[42:45], v[120:123], v[144:147], v[42:45]
	v_mfma_f32_16x16x32_f16 v[24:27], v[124:127], v[144:147], v[24:27]
	v_mfma_f32_16x16x32_f16 v[28:31], v[154:157], v[144:147], v[28:31]
	v_mfma_f32_16x16x32_f16 v[76:79], v[158:161], v[136:139], v[76:79]
	s_waitcnt lgkmcnt(1)
	v_mfma_f32_16x16x32_f16 v[112:115], v[0:3], v[50:53], v[128:131]
	v_mfma_f32_16x16x32_f16 v[116:119], v[8:11], v[50:53], v[132:135]
	v_mfma_f32_16x16x32_f16 v[120:123], v[54:57], v[50:53], v[140:143]
	s_nop 1
	ds_read_b128 v[132:135], v22 offset:49152
	s_waitcnt lgkmcnt(1)
	v_mfma_f32_16x16x32_f16 v[0:3], v[0:3], v[108:111], v[42:45]
	v_mfma_f32_16x16x32_f16 v[124:127], v[8:11], v[108:111], v[24:27]
	v_mfma_f32_16x16x32_f16 v[128:131], v[54:57], v[108:111], v[28:31]
	v_mfma_f32_16x16x32_f16 v[108:111], v[16:19], v[108:111], v[4:7]
	ds_read_b128 v[136:139], v22 offset:51200
	s_nop 1
	ds_read_b128 v[4:7], v32 offset:16384
	ds_read_b128 v[8:11], v32 offset:18432
	ds_read_b128 v[140:143], v22 offset:53248
	ds_read_b128 v[144:147], v22 offset:55296
	v_mfma_f32_16x16x32_f16 v[76:79], v[16:19], v[50:53], v[76:79]
	s_waitcnt lgkmcnt(3)
	v_mfma_f32_16x16x32_f16 v[28:31], v[132:135], v[4:7], v[38:41]
	v_mfma_f32_16x16x32_f16 v[24:27], v[136:139], v[4:7], v[46:49]
	s_waitcnt lgkmcnt(1)
	v_mfma_f32_16x16x32_f16 v[60:63], v[140:143], v[4:7], v[58:61]
	s_waitcnt lgkmcnt(0)
	v_mfma_f32_16x16x32_f16 v[56:59], v[144:147], v[4:7], v[12:15]
	v_mfma_f32_16x16x32_f16 v[48:51], v[144:147], v[8:11], v[34:37]
	ds_read_b128 v[4:7], v32 offset:20480
	s_nop 1
	ds_read_b128 v[32:35], v32 offset:22528
	s_waitcnt lgkmcnt(0)
	s_barrier
	s_setprio 0
	v_mfma_f32_16x16x32_f16 v[20:23], v[132:135], v[8:11], v[72:75]
	v_mfma_f32_16x16x32_f16 v[16:19], v[136:139], v[8:11], v[80:83]
	s_nop 1
	v_mov_b32_e32 v72, 0x3e38aa3b
	v_mfma_f32_16x16x32_f16 v[52:55], v[140:143], v[8:11], v[104:107]
	v_mfma_f32_16x16x32_f16 v[12:15], v[132:135], v[4:7], v[112:115]
	v_mfma_f32_16x16x32_f16 v[8:11], v[136:139], v[4:7], v[116:119]
	v_mfma_f32_16x16x32_f16 v[44:47], v[140:143], v[4:7], v[120:123]
	v_mfma_f32_16x16x32_f16 v[40:43], v[144:147], v[4:7], v[76:79]
	s_nop 1
	v_mov_b64_e32 v[122:123], s[14:15]
	v_mfma_f32_16x16x32_f16 v[4:7], v[132:135], v[32:35], v[0:3]
	v_mfma_f32_16x16x32_f16 v[0:3], v[136:139], v[32:35], v[124:127]
	v_mfma_f32_16x16x32_f16 v[36:39], v[140:143], v[32:35], v[128:131]
	v_mfma_f32_16x16x32_f16 v[32:35], v[144:147], v[32:35], v[108:111]
	s_and_saveexec_b64 s[4:5], vcc
	s_cbranch_execz .LBB0_654
	s_cmpk_lt_u32 s16, 0x400
	s_cbranch_scc1 .LBB0_649
	s_cmpk_lt_u32 s16, 0x600
	s_cbranch_scc1 .LBB0_650
	s_cmpk_lt_u32 s16, 0x800
	s_cbranch_scc1 .LBB0_651
	s_cmpk_lt_u32 s16, 0xa00
	s_cbranch_scc1 .LBB0_693
	s_cmpk_lt_u32 s16, 0xc00
	s_cbranch_scc1 .LBB0_694
	s_cmpk_lt_u32 s16, 0xd00
	s_cbranch_scc1 .LBB0_695
	s_movk_i32 s1, 0xd3f
	v_cmp_lt_u32_e32 vcc, s1, v94
	v_mov_b32_e32 v72, 1.0
	v_mov_b64_e32 v[122:123], s[6:7]
	s_and_saveexec_b64 s[24:25], vcc
	s_cmpk_gt_u32 s16, 0xd7f
	s_cselect_b64 s[20:21], -1, 0
	v_cndmask_b32_e64 v72, 0.5, 1.0, s[20:21]
	v_mov_b64_e32 v[122:123], 0
	s_xor_b64 s[22:23], exec, -1
	s_and_b64 s[20:21], s[20:21], exec
	s_or_b64 exec, exec, s[24:25]
	v_readlane_b32 s30, v252, 17
	v_readlane_b32 s31, v252, 18
	s_branch .LBB0_653

; #define GL_LOAD(s_, kt_) if (VAR != 1) { a##s_##0 = GL_A(0, kt_); a##s_##1 = GL_A(1, kt_); a##s_##2 = GL_A(2, kt_); a##s_##3 = GL_A(3, kt_); b##s_##0 = GL_B(0, kt_); b##s_##1 = GL_B(1, kt_); b##s_##2 = GL_B(2, kt_); b##s_##3 = GL_B(3, kt_); }
; #define LDS_STORE(s_, buf_) if (VAR != 2) { LDS_ST1(sA, 0, buf_, a##s_##0) LDS_ST1(sA, 1, buf_, a##s_##1) LDS_ST1(sA, 2, buf_, a##s_##2) LDS_ST1(sA, 3, buf_, a##s_##3) LDS_ST1(sB, 0, buf_, b##s_##0) LDS_ST1(sB, 1, buf_, b##s_##1) LDS_ST1(sB, 2, buf_, b##s_##2) LDS_ST1(sB, 3, buf_, b##s_##3) }
;     ...
;   GL_LOAD(0, 0)
;   GL_LOAD(1, 1)
;   LDS_STORE(0, 0)
;   if (VAR != 4) __syncthreads();
; #pragma unroll
;   for (int kt = 0; kt < nk; kt += 2) {
;     if (kt + 2 < nk) { GL_LOAD(0, kt + 2) }
;     MMA_TILE(0)
;     LDS_STORE(1, 1)
;     if (VAR != 4) __syncthreads();
;     if (kt + 3 < nk) { GL_LOAD(1, kt + 3) }
;     MMA_TILE(1)
; DI void phase_proj(const Params& P, int l, char* smem) {
;     ...
;     if (n0 >= PW) {
;       gemm_kloop<false, false, 16>(acc, xb + (size_t)m0 * DM, DM, Wt + (size_t)n0 * DM, DM, smem);
;       const int cb = col0 - PW;
;       const int br = cb >> 9, c0 = cb & 511;
;       const int b = row0 >> 12, s0 = row0 & 4095;
.LBB0_691:
	s_and_b64 vcc, exec, s[4:5]
	s_cbranch_vccz .LBB0_636
	v_mov_b32_e32 v18, v148
	s_mov_b32 s17, s27
	s_lshl_b64 s[4:5], s[16:17], 11
	v_ashrrev_i32_e32 v16, 3, v18
	v_readlane_b32 s1, v252, 19
	v_ashrrev_i32_e32 v17, 31, v16
	v_add_u32_e32 v54, 64, v16
	s_add_u32 s4, s1, s4
	v_readlane_b32 s1, v252, 20
	v_lshlrev_b64 v[6:7], 11, v[16:17]
	v_lshlrev_b32_e32 v17, 4, v18
	v_add_u32_e32 v20, 32, v16
	v_ashrrev_i32_e32 v55, 31, v54
	s_addc_u32 s5, s1, s5
	v_lshl_add_u64 v[0:1], s[18:19], 0, v[6:7]
	v_and_b32_e32 v150, 0x70, v17
	v_ashrrev_i32_e32 v21, 31, v20
	v_lshlrev_b64 v[12:13], 11, v[54:55]
	v_lshl_add_u64 v[0:1], v[0:1], 0, v[150:151]
	v_lshlrev_b64 v[10:11], 11, v[20:21]
	v_lshl_add_u64 v[4:5], s[18:19], 0, v[12:13]
	v_add_u32_e32 v56, 0x60, v16
	v_lshl_add_u64 v[6:7], s[4:5], 0, v[6:7]
	global_load_dwordx4 v[22:25], v[0:1], off
	v_lshl_add_u64 v[2:3], s[18:19], 0, v[10:11]
	v_lshl_add_u64 v[4:5], v[4:5], 0, v[150:151]
	v_ashrrev_i32_e32 v57, 31, v56
	v_lshl_add_u64 v[6:7], v[6:7], 0, v[150:151]
	v_lshl_add_u64 v[2:3], v[2:3], 0, v[150:151]
	global_load_dwordx4 v[30:33], v[4:5], off
	global_load_dwordx4 v[38:41], v[6:7], off
	v_lshlrev_b64 v[14:15], 11, v[56:57]
	global_load_dwordx4 v[26:29], v[2:3], off
	v_lshl_add_u64 v[8:9], s[18:19], 0, v[14:15]
	v_lshl_add_u64 v[8:9], v[8:9], 0, v[150:151]
	v_lshl_add_u64 v[10:11], s[4:5], 0, v[10:11]
	global_load_dwordx4 v[34:37], v[8:9], off
	v_lshl_add_u64 v[10:11], v[10:11], 0, v[150:151]
	v_lshl_add_u64 v[12:13], s[4:5], 0, v[12:13]
	global_load_dwordx4 v[42:45], v[10:11], off
	v_lshl_add_u64 v[12:13], v[12:13], 0, v[150:151]
	v_lshl_add_u64 v[14:15], s[4:5], 0, v[14:15]
	global_load_dwordx4 v[46:49], v[12:13], off
	v_lshl_add_u64 v[14:15], v[14:15], 0, v[150:151]
	global_load_dwordx4 v[50:53], v[14:15], off
	v_and_b32_e32 v19, 15, v18
	v_lshrrev_b32_e32 v55, 1, v18
	v_lshlrev_b32_e32 v21, 3, v18
	s_movk_i32 s1, 0x70
	v_and_or_b32 v55, v55, s29, v19
	v_and_b32_e32 v82, 48, v18
	v_and_b32_e32 v57, 0x70, v21
	v_bitop3_b32 v17, v17, s1, v18 bitop3:0x48
	v_lshlrev_b32_e32 v95, 7, v55
	v_lshlrev_b32_e32 v83, 7, v18
	v_lshl_or_b32 v18, v16, 7, v17
	v_lshl_or_b32 v19, v20, 7, v17
	v_lshl_or_b32 v20, v54, 7, v17
	v_lshl_or_b32 v17, v56, 7, v17
	v_bitop3_b32 v16, v95, v57, v82 bitop3:0xf6
	global_load_dwordx4 v[54:57], v[0:1], off offset:128
	global_load_dwordx4 v[58:61], v[6:7], off offset:128
	global_load_dwordx4 v[62:65], v[2:3], off offset:128
	global_load_dwordx4 v[66:69], v[4:5], off offset:128
	global_load_dwordx4 v[70:73], v[8:9], off offset:128
	global_load_dwordx4 v[74:77], v[10:11], off offset:128
	global_load_dwordx4 v[78:81], v[12:13], off offset:128
	global_load_dwordx4 v[104:107], v[14:15], off offset:128
	v_bitop3_b32 v21, v21, v82, s1 bitop3:0x6c
	v_add_u32_e32 v94, 0xffffe680, v94
	s_movk_i32 s1, 0x1c0
	v_and_or_b32 v103, v175, 64, v84
	s_mov_b64 s[4:5], 0x60
	s_waitcnt vmcnt(15)
	ds_write_b128 v18, v[22:25]
	s_waitcnt vmcnt(13)
	ds_write_b128 v18, v[38:41] offset:32768
	s_waitcnt vmcnt(12)
	ds_write_b128 v19, v[26:29]
	ds_write_b128 v20, v[30:33]
	s_waitcnt vmcnt(11)
	ds_write_b128 v17, v[34:37]
	s_waitcnt vmcnt(10)
	ds_write_b128 v19, v[42:45] offset:32768
	s_waitcnt vmcnt(9)
	ds_write_b128 v20, v[46:49] offset:32768
	s_waitcnt vmcnt(8)
	ds_write_b128 v17, v[50:53] offset:32768
	s_waitcnt lgkmcnt(0)
	s_barrier
	s_setprio 1
	ds_read_b128 v[22:25], v16
	v_and_b32_e32 v26, 0x2780, v83
	v_or_b32_e32 v28, v26, v21
	ds_read_b128 v[30:33], v28 offset:32768
	s_waitcnt lgkmcnt(0)
	v_mfma_f32_16x16x32_f16 v[42:45], v[22:25], v[30:33], 0
	ds_read_b128 v[34:37], v16 offset:2048
	s_waitcnt lgkmcnt(0)
	v_mfma_f32_16x16x32_f16 v[116:119], v[34:37], v[30:33], 0
	ds_read_b128 v[38:41], v28 offset:34816
	ds_read_b128 v[128:131], v16 offset:4096
	s_waitcnt lgkmcnt(0)
	v_mfma_f32_16x16x32_f16 v[136:139], v[128:131], v[30:33], 0
	ds_read_b128 v[50:53], v28 offset:36864
	ds_read_b128 v[132:135], v16 offset:6144
	s_waitcnt lgkmcnt(0)
	v_mfma_f32_16x16x32_f16 v[154:157], v[132:135], v[30:33], 0
	ds_read_b128 v[108:111], v28 offset:38912
	v_mfma_f32_16x16x32_f16 v[46:49], v[22:25], v[38:41], 0
	v_bitop3_b32 v29, v95, v21, 64 bitop3:0xf6
	v_mfma_f32_16x16x32_f16 v[112:115], v[22:25], v[50:53], 0
	ds_read_b128 v[158:161], v29
	s_waitcnt lgkmcnt(1)
	v_mfma_f32_16x16x32_f16 v[22:25], v[22:25], v[108:111], 0
	ds_read_b128 v[162:165], v29 offset:2048
	v_mfma_f32_16x16x32_f16 v[120:123], v[34:37], v[38:41], 0
	v_xor_b32_e32 v21, 64, v21
	v_mfma_f32_16x16x32_f16 v[124:127], v[34:37], v[50:53], 0
	v_ashrrev_i32_e32 v95, 12, v99
	v_mfma_f32_16x16x32_f16 v[34:37], v[34:37], v[108:111], 0
	v_and_b32_e32 v99, 0xfc0, v99
	v_mfma_f32_16x16x32_f16 v[140:143], v[128:131], v[38:41], 0
	v_lshlrev_b32_e32 v150, 1, v99
	v_or_b32_e32 v32, v26, v21
	v_mfma_f32_16x16x32_f16 v[144:147], v[128:131], v[50:53], 0
	ds_read_b128 v[166:169], v32 offset:34816
	ds_read_b128 v[188:191], v32 offset:36864
	v_mfma_f32_16x16x32_f16 v[128:131], v[128:131], v[108:111], 0
	ds_read_b128 v[192:195], v32 offset:38912
	s_waitcnt vmcnt(7)
	ds_write_b128 v18, v[54:57] offset:16384
	v_mfma_f32_16x16x32_f16 v[38:41], v[132:135], v[38:41], 0
	s_waitcnt vmcnt(5)
	ds_write_b128 v19, v[62:65] offset:16384
	v_mfma_f32_16x16x32_f16 v[50:53], v[132:135], v[50:53], 0
	s_waitcnt vmcnt(4)
	ds_write_b128 v20, v[66:69] offset:16384
	v_mfma_f32_16x16x32_f16 v[108:111], v[132:135], v[108:111], 0
	ds_read_b128 v[132:135], v32 offset:32768
	s_waitcnt lgkmcnt(6)
	v_mfma_f32_16x16x32_f16 v[46:49], v[158:161], v[166:169], v[46:49]
	s_waitcnt vmcnt(3)
	ds_write_b128 v17, v[70:73] offset:16384
	s_waitcnt lgkmcnt(6)
; #define GL_LOAD(s_, kt_) if (VAR != 1) { a##s_##0 = GL_A(0, kt_); a##s_##1 = GL_A(1, kt_); a##s_##2 = GL_A(2, kt_); a##s_##3 = GL_A(3, kt_); b##s_##0 = GL_B(0, kt_); b##s_##1 = GL_B(1, kt_); b##s_##2 = GL_B(2, kt_); b##s_##3 = GL_B(3, kt_); }
; #define LDS_STORE(s_, buf_) if (VAR != 2) { LDS_ST1(sA, 0, buf_, a##s_##0) LDS_ST1(sA, 1, buf_, a##s_##1) LDS_ST1(sA, 2, buf_, a##s_##2) LDS_ST1(sA, 3, buf_, a##s_##3) LDS_ST1(sB, 0, buf_, b##s_##0) LDS_ST1(sB, 1, buf_, b##s_##1) LDS_ST1(sB, 2, buf_, b##s_##2) LDS_ST1(sB, 3, buf_, b##s_##3) }
;     ...
;   for (int kt = 0; kt < nk; kt += 2) {
;     if (kt + 2 < nk) { GL_LOAD(0, kt + 2) }
;     MMA_TILE(0)
;     LDS_STORE(1, 1)
;     if (VAR != 4) __syncthreads();
;     if (kt + 3 < nk) { GL_LOAD(1, kt + 3) }
;     MMA_TILE(1)
;     if (kt + 2 < nk) { LDS_STORE(0, 0) }
;     if (VAR != 4) __syncthreads();
	v_mfma_f32_16x16x32_f16 v[112:115], v[158:161], v[188:191], v[112:115]
	ds_write_b128 v18, v[58:61] offset:49152
	s_waitcnt lgkmcnt(6)
	v_mfma_f32_16x16x32_f16 v[22:25], v[158:161], v[192:195], v[22:25]
	s_waitcnt vmcnt(2)
	ds_write_b128 v19, v[74:77] offset:49152
	v_mfma_f32_16x16x32_f16 v[120:123], v[162:165], v[166:169], v[120:123]
	s_waitcnt vmcnt(1)
	ds_write_b128 v20, v[78:81] offset:49152
	v_mfma_f32_16x16x32_f16 v[124:127], v[162:165], v[188:191], v[124:127]
	s_waitcnt vmcnt(0)
	ds_write_b128 v17, v[104:107] offset:49152
	v_mfma_f32_16x16x32_f16 v[34:37], v[162:165], v[192:195], v[34:37]
	s_waitcnt lgkmcnt(5)
	v_mfma_f32_16x16x32_f16 v[42:45], v[158:161], v[132:135], v[42:45]
	ds_read_b128 v[158:161], v29 offset:4096
	v_mfma_f32_16x16x32_f16 v[116:119], v[162:165], v[132:135], v[116:119]
	ds_read_b128 v[162:165], v29 offset:6144
	s_waitcnt lgkmcnt(1)
	v_mfma_f32_16x16x32_f16 v[136:139], v[158:161], v[132:135], v[136:139]
	v_mfma_f32_16x16x32_f16 v[140:143], v[158:161], v[166:169], v[140:143]
	s_waitcnt lgkmcnt(0)
	v_mfma_f32_16x16x32_f16 v[132:135], v[162:165], v[132:135], v[154:157]
	s_nop 2
	global_load_dwordx4 v[154:157], v[0:1], off offset:256
	v_mfma_f32_16x16x32_f16 v[38:41], v[162:165], v[166:169], v[38:41]
	v_mfma_f32_16x16x32_f16 v[144:147], v[158:161], v[188:191], v[144:147]
	v_mfma_f32_16x16x32_f16 v[128:131], v[158:161], v[192:195], v[128:131]
	global_load_dwordx4 v[158:161], v[2:3], off offset:256
	global_load_dwordx4 v[196:199], v[4:5], off offset:256
	global_load_dwordx4 v[200:203], v[8:9], off offset:256
	global_load_dwordx4 v[166:169], v[6:7], off offset:256
	global_load_dwordx4 v[204:207], v[10:11], off offset:256
	global_load_dwordx4 v[208:211], v[12:13], off offset:256
	global_load_dwordx4 v[212:215], v[14:15], off offset:256
	s_waitcnt lgkmcnt(0)
	s_barrier
	v_mfma_f32_16x16x32_f16 v[58:61], v[162:165], v[192:195], v[108:111]
	ds_read_b128 v[54:57], v16 offset:16384
	v_mfma_f32_16x16x32_f16 v[50:53], v[162:165], v[188:191], v[50:53]
	ds_read_b128 v[62:65], v28 offset:49152
	s_waitcnt lgkmcnt(0)
	v_mfma_f32_16x16x32_f16 v[42:45], v[54:57], v[62:65], v[42:45]
	ds_read_b128 v[66:69], v16 offset:18432
	ds_read_b128 v[70:73], v28 offset:51200
	s_waitcnt lgkmcnt(0)
	v_mfma_f32_16x16x32_f16 v[46:49], v[54:57], v[70:73], v[46:49]
	ds_read_b128 v[74:77], v28 offset:53248
	s_waitcnt lgkmcnt(0)
	v_mfma_f32_16x16x32_f16 v[104:107], v[54:57], v[74:77], v[112:115]
	ds_read_b128 v[78:81], v28 offset:55296
	s_waitcnt lgkmcnt(0)
	v_mfma_f32_16x16x32_f16 v[22:25], v[54:57], v[78:81], v[22:25]
	v_mfma_f32_16x16x32_f16 v[54:57], v[66:69], v[62:65], v[116:119]
	s_nop 2
	ds_read_b128 v[116:119], v16 offset:22528
	v_mfma_f32_16x16x32_f16 v[108:111], v[66:69], v[70:73], v[120:123]
	v_mfma_f32_16x16x32_f16 v[112:115], v[66:69], v[74:77], v[124:127]
	v_mfma_f32_16x16x32_f16 v[34:37], v[66:69], v[78:81], v[34:37]
	ds_read_b128 v[66:69], v16 offset:20480
	s_waitcnt lgkmcnt(0)
	v_mfma_f32_16x16x32_f16 v[124:127], v[66:69], v[70:73], v[140:143]
	v_mfma_f32_16x16x32_f16 v[120:123], v[66:69], v[62:65], v[136:139]
	v_mfma_f32_16x16x32_f16 v[38:41], v[116:119], v[70:73], v[38:41]
	ds_read_b128 v[70:73], v29 offset:16384
	v_mfma_f32_16x16x32_f16 v[62:65], v[116:119], v[62:65], v[132:135]
	s_nop 2
	ds_read_b128 v[132:135], v32 offset:55296
	s_waitcnt vmcnt(7)
	ds_write_b128 v18, v[154:157]
	v_mfma_f32_16x16x32_f16 v[136:139], v[66:69], v[74:77], v[144:147]
	s_waitcnt vmcnt(6)
	ds_write_b128 v19, v[158:161]
	s_waitcnt vmcnt(5)
	ds_write_b128 v20, v[196:199]
	v_mfma_f32_16x16x32_f16 v[66:69], v[66:69], v[78:81], v[128:131]
	s_nop 2
	ds_read_b128 v[128:131], v32 offset:53248
	v_mfma_f32_16x16x32_f16 v[50:53], v[116:119], v[74:77], v[50:53]
	ds_read_b128 v[74:77], v32 offset:49152
	v_mfma_f32_16x16x32_f16 v[58:61], v[116:119], v[78:81], v[58:61]
	ds_read_b128 v[78:81], v29 offset:18432
	s_waitcnt lgkmcnt(1)
	v_mfma_f32_16x16x32_f16 v[42:45], v[70:73], v[74:77], v[42:45]
	ds_read_b128 v[116:119], v32 offset:51200
	s_waitcnt lgkmcnt(0)
	v_mfma_f32_16x16x32_f16 v[46:49], v[70:73], v[116:119], v[46:49]
	s_waitcnt vmcnt(4)
	ds_write_b128 v17, v[200:203]
	v_mfma_f32_16x16x32_f16 v[54:57], v[78:81], v[74:77], v[54:57]
	s_waitcnt vmcnt(3)
	ds_write_b128 v18, v[166:169] offset:32768
	v_mfma_f32_16x16x32_f16 v[104:107], v[70:73], v[128:131], v[104:107]
	v_mfma_f32_16x16x32_f16 v[22:25], v[70:73], v[132:135], v[22:25]
	v_mfma_f32_16x16x32_f16 v[70:73], v[78:81], v[116:119], v[108:111]
	s_waitcnt vmcnt(2)
	ds_write_b128 v19, v[204:207] offset:32768
	s_waitcnt vmcnt(1)
	ds_write_b128 v20, v[208:211] offset:32768
	s_waitcnt vmcnt(0)
	ds_write_b128 v17, v[212:215] offset:32768
	v_mfma_f32_16x16x32_f16 v[108:111], v[78:81], v[128:131], v[112:115]
	s_nop 2
	ds_read_b128 v[112:115], v29 offset:22528
	v_mfma_f32_16x16x32_f16 v[34:37], v[78:81], v[132:135], v[34:37]
	ds_read_b128 v[78:81], v29 offset:20480
	s_waitcnt lgkmcnt(0)
	v_mfma_f32_16x16x32_f16 v[120:123], v[78:81], v[74:77], v[120:123]
	v_mfma_f32_16x16x32_f16 v[124:127], v[78:81], v[116:119], v[124:127]
	v_mfma_f32_16x16x32_f16 v[62:65], v[112:115], v[74:77], v[62:65]
	global_load_dwordx4 v[74:77], v[0:1], off offset:384
	v_mfma_f32_16x16x32_f16 v[38:41], v[112:115], v[116:119], v[38:41]
	v_mfma_f32_16x16x32_f16 v[136:139], v[78:81], v[128:131], v[136:139]
	v_mfma_f32_16x16x32_f16 v[66:69], v[78:81], v[132:135], v[66:69]
	global_load_dwordx4 v[78:81], v[2:3], off offset:384
	global_load_dwordx4 v[140:143], v[4:5], off offset:384
	v_mfma_f32_16x16x32_f16 v[50:53], v[112:115], v[128:131], v[50:53]
	global_load_dwordx4 v[144:147], v[8:9], off offset:384
	global_load_dwordx4 v[116:119], v[6:7], off offset:384
	global_load_dwordx4 v[162:165], v[10:11], off offset:384
	global_load_dwordx4 v[188:191], v[12:13], off offset:384
	global_load_dwordx4 v[192:195], v[14:15], off offset:384
	s_waitcnt lgkmcnt(0)
	s_barrier
; #define GL_LOAD(s_, kt_) if (VAR != 1) { a##s_##0 = GL_A(0, kt_); a##s_##1 = GL_A(1, kt_); a##s_##2 = GL_A(2, kt_); a##s_##3 = GL_A(3, kt_); b##s_##0 = GL_B(0, kt_); b##s_##1 = GL_B(1, kt_); b##s_##2 = GL_B(2, kt_); b##s_##3 = GL_B(3, kt_); }
; #define LDS_STORE(s_, buf_) if (VAR != 2) { LDS_ST1(sA, 0, buf_, a##s_##0) LDS_ST1(sA, 1, buf_, a##s_##1) LDS_ST1(sA, 2, buf_, a##s_##2) LDS_ST1(sA, 3, buf_, a##s_##3) LDS_ST1(sB, 0, buf_, b##s_##0) LDS_ST1(sB, 1, buf_, b##s_##1) LDS_ST1(sB, 2, buf_, b##s_##2) LDS_ST1(sB, 3, buf_, b##s_##3) }
;     ...
;   for (int kt = 0; kt < nk; kt += 2) {
;     if (kt + 2 < nk) { GL_LOAD(0, kt + 2) }
;     MMA_TILE(0)
;     LDS_STORE(1, 1)
;     if (VAR != 4) __syncthreads();
;     if (kt + 3 < nk) { GL_LOAD(1, kt + 3) }
;     MMA_TILE(1)
;     if (kt + 2 < nk) { LDS_STORE(0, 0) }
;     if (VAR != 4) __syncthreads();
	v_mfma_f32_16x16x32_f16 v[58:61], v[112:115], v[132:135], v[58:61]
	ds_read_b128 v[128:131], v16
	ds_read_b128 v[112:115], v28 offset:32768
	s_waitcnt lgkmcnt(0)
	v_mfma_f32_16x16x32_f16 v[42:45], v[128:131], v[112:115], v[42:45]
	ds_read_b128 v[132:135], v16 offset:2048
	ds_read_b128 v[154:157], v28 offset:34816
	s_waitcnt lgkmcnt(0)
	v_mfma_f32_16x16x32_f16 v[46:49], v[128:131], v[154:157], v[46:49]
	ds_read_b128 v[158:161], v28 offset:36864
	v_mfma_f32_16x16x32_f16 v[54:57], v[132:135], v[112:115], v[54:57]
	ds_read_b128 v[166:169], v28 offset:38912
	v_mfma_f32_16x16x32_f16 v[70:73], v[132:135], v[154:157], v[70:73]
	s_waitcnt lgkmcnt(1)
	v_mfma_f32_16x16x32_f16 v[104:107], v[128:131], v[158:161], v[104:107]
	s_waitcnt lgkmcnt(0)
	v_mfma_f32_16x16x32_f16 v[22:25], v[128:131], v[166:169], v[22:25]
	ds_read_b128 v[128:131], v16 offset:4096
	v_mfma_f32_16x16x32_f16 v[108:111], v[132:135], v[158:161], v[108:111]
	v_mfma_f32_16x16x32_f16 v[34:37], v[132:135], v[166:169], v[34:37]
	ds_read_b128 v[132:135], v16 offset:6144
	s_waitcnt lgkmcnt(1)
	v_mfma_f32_16x16x32_f16 v[120:123], v[128:131], v[112:115], v[120:123]
	v_mfma_f32_16x16x32_f16 v[124:127], v[128:131], v[154:157], v[124:127]
	s_waitcnt lgkmcnt(0)
	v_mfma_f32_16x16x32_f16 v[62:65], v[132:135], v[112:115], v[62:65]
	ds_read_b128 v[112:115], v29
	v_mfma_f32_16x16x32_f16 v[38:41], v[132:135], v[154:157], v[38:41]
	ds_read_b128 v[154:157], v32 offset:34816
	s_waitcnt vmcnt(7)
	ds_write_b128 v18, v[74:77] offset:16384
	v_mfma_f32_16x16x32_f16 v[136:139], v[128:131], v[158:161], v[136:139]
	s_waitcnt vmcnt(6)
	ds_write_b128 v19, v[78:81] offset:16384
	s_waitcnt vmcnt(5)
	ds_write_b128 v20, v[140:143] offset:16384
	v_mfma_f32_16x16x32_f16 v[66:69], v[128:131], v[166:169], v[66:69]
	ds_read_b128 v[128:131], v32 offset:32768
	s_waitcnt vmcnt(4)
	ds_write_b128 v17, v[144:147] offset:16384
	v_mfma_f32_16x16x32_f16 v[50:53], v[132:135], v[158:161], v[50:53]
	ds_read_b128 v[158:161], v32 offset:36864
	v_mfma_f32_16x16x32_f16 v[58:61], v[132:135], v[166:169], v[58:61]
	ds_read_b128 v[132:135], v29 offset:2048
	s_waitcnt lgkmcnt(3)
	v_mfma_f32_16x16x32_f16 v[42:45], v[112:115], v[128:131], v[42:45]
	ds_read_b128 v[166:169], v32 offset:38912
	v_mfma_f32_16x16x32_f16 v[46:49], v[112:115], v[154:157], v[46:49]
	s_waitcnt vmcnt(3)
	ds_write_b128 v18, v[116:119] offset:49152
	s_waitcnt lgkmcnt(2)
	v_mfma_f32_16x16x32_f16 v[54:57], v[132:135], v[128:131], v[54:57]
	s_waitcnt vmcnt(2)
	ds_write_b128 v19, v[162:165] offset:49152
	v_mfma_f32_16x16x32_f16 v[70:73], v[132:135], v[154:157], v[70:73]
	s_waitcnt vmcnt(1)
	ds_write_b128 v20, v[188:191] offset:49152
	v_mfma_f32_16x16x32_f16 v[104:107], v[112:115], v[158:161], v[104:107]
	s_waitcnt vmcnt(0)
	ds_write_b128 v17, v[192:195] offset:49152
	s_waitcnt lgkmcnt(4)
	v_mfma_f32_16x16x32_f16 v[22:25], v[112:115], v[166:169], v[22:25]
	ds_read_b128 v[112:115], v29 offset:4096
	v_mfma_f32_16x16x32_f16 v[108:111], v[132:135], v[158:161], v[108:111]
	v_mfma_f32_16x16x32_f16 v[34:37], v[132:135], v[166:169], v[34:37]
	ds_read_b128 v[132:135], v29 offset:6144
	s_waitcnt lgkmcnt(1)
	v_mfma_f32_16x16x32_f16 v[120:123], v[112:115], v[128:131], v[120:123]
	v_mfma_f32_16x16x32_f16 v[124:127], v[112:115], v[154:157], v[124:127]
	s_waitcnt lgkmcnt(0)
	v_mfma_f32_16x16x32_f16 v[62:65], v[132:135], v[128:131], v[62:65]
	v_mfma_f32_16x16x32_f16 v[38:41], v[132:135], v[154:157], v[38:41]
	v_mfma_f32_16x16x32_f16 v[136:139], v[112:115], v[158:161], v[136:139]
	v_mfma_f32_16x16x32_f16 v[66:69], v[112:115], v[166:169], v[66:69]
	global_load_dwordx4 v[112:115], v[0:1], off offset:512
	global_load_dwordx4 v[128:131], v[2:3], off offset:512
	global_load_dwordx4 v[196:199], v[4:5], off offset:512
	global_load_dwordx4 v[200:203], v[8:9], off offset:512
	global_load_dwordx4 v[154:157], v[6:7], off offset:512
	global_load_dwordx4 v[204:207], v[10:11], off offset:512
	global_load_dwordx4 v[208:211], v[12:13], off offset:512
	global_load_dwordx4 v[212:215], v[14:15], off offset:512
	s_waitcnt lgkmcnt(0)
	s_barrier
	v_mfma_f32_16x16x32_f16 v[50:53], v[132:135], v[158:161], v[50:53]
	ds_read_b128 v[74:77], v16 offset:16384
	v_mfma_f32_16x16x32_f16 v[58:61], v[132:135], v[166:169], v[58:61]
	ds_read_b128 v[78:81], v28 offset:49152
	s_waitcnt lgkmcnt(0)
	v_mfma_f32_16x16x32_f16 v[42:45], v[74:77], v[78:81], v[42:45]
	ds_read_b128 v[116:119], v16 offset:18432
	ds_read_b128 v[132:135], v28 offset:51200
	s_waitcnt lgkmcnt(0)
	v_mfma_f32_16x16x32_f16 v[46:49], v[74:77], v[132:135], v[46:49]
	ds_read_b128 v[140:143], v28 offset:53248
	v_mfma_f32_16x16x32_f16 v[54:57], v[116:119], v[78:81], v[54:57]
	ds_read_b128 v[144:147], v28 offset:55296
	v_mfma_f32_16x16x32_f16 v[70:73], v[116:119], v[132:135], v[70:73]
	s_waitcnt lgkmcnt(1)
	v_mfma_f32_16x16x32_f16 v[104:107], v[74:77], v[140:143], v[104:107]
	s_waitcnt lgkmcnt(0)
	v_mfma_f32_16x16x32_f16 v[22:25], v[74:77], v[144:147], v[22:25]
	v_mfma_f32_16x16x32_f16 v[74:77], v[116:119], v[140:143], v[108:111]
	s_nop 2
	ds_read_b128 v[108:111], v16 offset:20480
	v_mfma_f32_16x16x32_f16 v[34:37], v[116:119], v[144:147], v[34:37]
	ds_read_b128 v[116:119], v16 offset:22528
	s_waitcnt lgkmcnt(1)
	v_mfma_f32_16x16x32_f16 v[120:123], v[108:111], v[78:81], v[120:123]
	v_mfma_f32_16x16x32_f16 v[124:127], v[108:111], v[132:135], v[124:127]
	s_waitcnt lgkmcnt(0)
	v_mfma_f32_16x16x32_f16 v[62:65], v[116:119], v[78:81], v[62:65]
	ds_read_b128 v[78:81], v29 offset:16384
	v_mfma_f32_16x16x32_f16 v[38:41], v[116:119], v[132:135], v[38:41]
	ds_read_b128 v[132:135], v32 offset:51200
	s_waitcnt vmcnt(7)
	ds_write_b128 v18, v[112:115]
	v_mfma_f32_16x16x32_f16 v[136:139], v[108:111], v[140:143], v[136:139]
	s_waitcnt vmcnt(6)
; #define GL_LOAD(s_, kt_) if (VAR != 1) { a##s_##0 = GL_A(0, kt_); a##s_##1 = GL_A(1, kt_); a##s_##2 = GL_A(2, kt_); a##s_##3 = GL_A(3, kt_); b##s_##0 = GL_B(0, kt_); b##s_##1 = GL_B(1, kt_); b##s_##2 = GL_B(2, kt_); b##s_##3 = GL_B(3, kt_); }
; #define LDS_STORE(s_, buf_) if (VAR != 2) { LDS_ST1(sA, 0, buf_, a##s_##0) LDS_ST1(sA, 1, buf_, a##s_##1) LDS_ST1(sA, 2, buf_, a##s_##2) LDS_ST1(sA, 3, buf_, a##s_##3) LDS_ST1(sB, 0, buf_, b##s_##0) LDS_ST1(sB, 1, buf_, b##s_##1) LDS_ST1(sB, 2, buf_, b##s_##2) LDS_ST1(sB, 3, buf_, b##s_##3) }
;     ...
;   for (int kt = 0; kt < nk; kt += 2) {
;     if (kt + 2 < nk) { GL_LOAD(0, kt + 2) }
;     MMA_TILE(0)
;     LDS_STORE(1, 1)
;     if (VAR != 4) __syncthreads();
;     if (kt + 3 < nk) { GL_LOAD(1, kt + 3) }
;     MMA_TILE(1)
;     if (kt + 2 < nk) { LDS_STORE(0, 0) }
;     if (VAR != 4) __syncthreads();
	ds_write_b128 v19, v[128:131]
	s_waitcnt vmcnt(5)
	ds_write_b128 v20, v[196:199]
	v_mfma_f32_16x16x32_f16 v[66:69], v[108:111], v[144:147], v[66:69]
	ds_read_b128 v[108:111], v32 offset:49152
	s_waitcnt vmcnt(4)
	ds_write_b128 v17, v[200:203]
	v_mfma_f32_16x16x32_f16 v[50:53], v[116:119], v[140:143], v[50:53]
	ds_read_b128 v[140:143], v32 offset:53248
	v_mfma_f32_16x16x32_f16 v[58:61], v[116:119], v[144:147], v[58:61]
	ds_read_b128 v[116:119], v29 offset:18432
	s_waitcnt lgkmcnt(3)
	v_mfma_f32_16x16x32_f16 v[42:45], v[78:81], v[108:111], v[42:45]
	ds_read_b128 v[144:147], v32 offset:55296
	v_mfma_f32_16x16x32_f16 v[46:49], v[78:81], v[132:135], v[46:49]
	s_waitcnt vmcnt(3)
	ds_write_b128 v18, v[154:157] offset:32768
	s_waitcnt lgkmcnt(2)
	v_mfma_f32_16x16x32_f16 v[54:57], v[116:119], v[108:111], v[54:57]
	s_waitcnt vmcnt(2)
	ds_write_b128 v19, v[204:207] offset:32768
	v_mfma_f32_16x16x32_f16 v[70:73], v[116:119], v[132:135], v[70:73]
	s_waitcnt vmcnt(1)
	ds_write_b128 v20, v[208:211] offset:32768
	v_mfma_f32_16x16x32_f16 v[104:107], v[78:81], v[140:143], v[104:107]
	s_waitcnt vmcnt(0)
	ds_write_b128 v17, v[212:215] offset:32768
	s_waitcnt lgkmcnt(4)
	v_mfma_f32_16x16x32_f16 v[22:25], v[78:81], v[144:147], v[22:25]
	ds_read_b128 v[78:81], v29 offset:20480
	v_mfma_f32_16x16x32_f16 v[74:77], v[116:119], v[140:143], v[74:77]
	v_mfma_f32_16x16x32_f16 v[34:37], v[116:119], v[144:147], v[34:37]
	ds_read_b128 v[116:119], v29 offset:22528
	s_waitcnt lgkmcnt(1)
	v_mfma_f32_16x16x32_f16 v[120:123], v[78:81], v[108:111], v[120:123]
	v_mfma_f32_16x16x32_f16 v[124:127], v[78:81], v[132:135], v[124:127]
	s_waitcnt lgkmcnt(0)
	v_mfma_f32_16x16x32_f16 v[62:65], v[116:119], v[108:111], v[62:65]
	v_mfma_f32_16x16x32_f16 v[38:41], v[116:119], v[132:135], v[38:41]
	v_mfma_f32_16x16x32_f16 v[136:139], v[78:81], v[140:143], v[136:139]
	v_mfma_f32_16x16x32_f16 v[66:69], v[78:81], v[144:147], v[66:69]
	global_load_dwordx4 v[78:81], v[0:1], off offset:640
	global_load_dwordx4 v[108:111], v[2:3], off offset:640
	global_load_dwordx4 v[158:161], v[4:5], off offset:640
	global_load_dwordx4 v[162:165], v[8:9], off offset:640
	global_load_dwordx4 v[132:135], v[6:7], off offset:640
	global_load_dwordx4 v[166:169], v[10:11], off offset:640
	global_load_dwordx4 v[188:191], v[12:13], off offset:640
	global_load_dwordx4 v[192:195], v[14:15], off offset:640
	s_waitcnt lgkmcnt(0)
	s_barrier
	v_mfma_f32_16x16x32_f16 v[50:53], v[116:119], v[140:143], v[50:53]
	ds_read_b128 v[112:115], v16
	v_mfma_f32_16x16x32_f16 v[58:61], v[116:119], v[144:147], v[58:61]
	ds_read_b128 v[116:119], v28 offset:32768
	s_waitcnt lgkmcnt(0)
	v_mfma_f32_16x16x32_f16 v[42:45], v[112:115], v[116:119], v[42:45]
	ds_read_b128 v[128:131], v16 offset:2048
	ds_read_b128 v[140:143], v28 offset:34816
	s_waitcnt lgkmcnt(0)
	v_mfma_f32_16x16x32_f16 v[46:49], v[112:115], v[140:143], v[46:49]
	ds_read_b128 v[144:147], v28 offset:36864
	v_mfma_f32_16x16x32_f16 v[54:57], v[128:131], v[116:119], v[54:57]
	ds_read_b128 v[154:157], v28 offset:38912
	v_mfma_f32_16x16x32_f16 v[70:73], v[128:131], v[140:143], v[70:73]
	s_waitcnt lgkmcnt(1)
	v_mfma_f32_16x16x32_f16 v[104:107], v[112:115], v[144:147], v[104:107]
	s_waitcnt lgkmcnt(0)
	v_mfma_f32_16x16x32_f16 v[22:25], v[112:115], v[154:157], v[22:25]
	ds_read_b128 v[112:115], v16 offset:4096
	v_mfma_f32_16x16x32_f16 v[74:77], v[128:131], v[144:147], v[74:77]
	v_mfma_f32_16x16x32_f16 v[34:37], v[128:131], v[154:157], v[34:37]
	ds_read_b128 v[128:131], v16 offset:6144
	s_waitcnt lgkmcnt(1)
	v_mfma_f32_16x16x32_f16 v[120:123], v[112:115], v[116:119], v[120:123]
	v_mfma_f32_16x16x32_f16 v[124:127], v[112:115], v[140:143], v[124:127]
	s_waitcnt lgkmcnt(0)
	v_mfma_f32_16x16x32_f16 v[62:65], v[128:131], v[116:119], v[62:65]
	ds_read_b128 v[116:119], v32 offset:32768
	v_mfma_f32_16x16x32_f16 v[38:41], v[128:131], v[140:143], v[38:41]
	ds_read_b128 v[140:143], v32 offset:34816
	s_waitcnt vmcnt(7)
	ds_write_b128 v18, v[78:81] offset:16384
	v_mfma_f32_16x16x32_f16 v[136:139], v[112:115], v[144:147], v[136:139]
	s_waitcnt vmcnt(6)
	ds_write_b128 v19, v[108:111] offset:16384
	s_waitcnt vmcnt(5)
	ds_write_b128 v20, v[158:161] offset:16384
	v_mfma_f32_16x16x32_f16 v[66:69], v[112:115], v[154:157], v[66:69]
	ds_read_b128 v[112:115], v29
	s_waitcnt vmcnt(4)
	ds_write_b128 v17, v[162:165] offset:16384
	v_mfma_f32_16x16x32_f16 v[50:53], v[128:131], v[144:147], v[50:53]
	ds_read_b128 v[144:147], v32 offset:36864
	v_mfma_f32_16x16x32_f16 v[58:61], v[128:131], v[154:157], v[58:61]
	ds_read_b128 v[128:131], v29 offset:2048
	s_waitcnt lgkmcnt(3)
	v_mfma_f32_16x16x32_f16 v[42:45], v[112:115], v[116:119], v[42:45]
	ds_read_b128 v[154:157], v32 offset:38912
	v_mfma_f32_16x16x32_f16 v[46:49], v[112:115], v[140:143], v[46:49]
	s_waitcnt vmcnt(3)
	ds_write_b128 v18, v[132:135] offset:49152
	s_waitcnt lgkmcnt(2)
	v_mfma_f32_16x16x32_f16 v[54:57], v[128:131], v[116:119], v[54:57]
	s_waitcnt vmcnt(2)
	ds_write_b128 v19, v[166:169] offset:49152
	v_mfma_f32_16x16x32_f16 v[70:73], v[128:131], v[140:143], v[70:73]
	s_waitcnt vmcnt(1)
	ds_write_b128 v20, v[188:191] offset:49152
	v_mfma_f32_16x16x32_f16 v[104:107], v[112:115], v[144:147], v[104:107]
	s_waitcnt vmcnt(0)
	ds_write_b128 v17, v[192:195] offset:49152
	s_waitcnt lgkmcnt(4)
	v_mfma_f32_16x16x32_f16 v[22:25], v[112:115], v[154:157], v[22:25]
	ds_read_b128 v[112:115], v29 offset:4096
	v_mfma_f32_16x16x32_f16 v[74:77], v[128:131], v[144:147], v[74:77]
	v_mfma_f32_16x16x32_f16 v[34:37], v[128:131], v[154:157], v[34:37]
	ds_read_b128 v[128:131], v29 offset:6144
	s_waitcnt lgkmcnt(1)
	v_mfma_f32_16x16x32_f16 v[120:123], v[112:115], v[116:119], v[120:123]
	v_mfma_f32_16x16x32_f16 v[124:127], v[112:115], v[140:143], v[124:127]
	s_waitcnt lgkmcnt(0)
	v_mfma_f32_16x16x32_f16 v[62:65], v[128:131], v[116:119], v[62:65]
	v_mfma_f32_16x16x32_f16 v[38:41], v[128:131], v[140:143], v[38:41]
	v_mfma_f32_16x16x32_f16 v[136:139], v[112:115], v[144:147], v[136:139]
	v_mfma_f32_16x16x32_f16 v[66:69], v[112:115], v[154:157], v[66:69]
	global_load_dwordx4 v[112:115], v[0:1], off offset:768
	global_load_dwordx4 v[116:119], v[2:3], off offset:768
	global_load_dwordx4 v[196:199], v[4:5], off offset:768
	global_load_dwordx4 v[200:203], v[8:9], off offset:768
	global_load_dwordx4 v[140:143], v[6:7], off offset:768
	global_load_dwordx4 v[204:207], v[10:11], off offset:768
	global_load_dwordx4 v[208:211], v[12:13], off offset:768
	global_load_dwordx4 v[212:215], v[14:15], off offset:768
	s_waitcnt lgkmcnt(0)
	s_barrier
; #define GL_LOAD(s_, kt_) if (VAR != 1) { a##s_##0 = GL_A(0, kt_); a##s_##1 = GL_A(1, kt_); a##s_##2 = GL_A(2, kt_); a##s_##3 = GL_A(3, kt_); b##s_##0 = GL_B(0, kt_); b##s_##1 = GL_B(1, kt_); b##s_##2 = GL_B(2, kt_); b##s_##3 = GL_B(3, kt_); }
; #define LDS_STORE(s_, buf_) if (VAR != 2) { LDS_ST1(sA, 0, buf_, a##s_##0) LDS_ST1(sA, 1, buf_, a##s_##1) LDS_ST1(sA, 2, buf_, a##s_##2) LDS_ST1(sA, 3, buf_, a##s_##3) LDS_ST1(sB, 0, buf_, b##s_##0) LDS_ST1(sB, 1, buf_, b##s_##1) LDS_ST1(sB, 2, buf_, b##s_##2) LDS_ST1(sB, 3, buf_, b##s_##3) }
;     ...
;   for (int kt = 0; kt < nk; kt += 2) {
;     if (kt + 2 < nk) { GL_LOAD(0, kt + 2) }
;     MMA_TILE(0)
;     LDS_STORE(1, 1)
;     if (VAR != 4) __syncthreads();
;     if (kt + 3 < nk) { GL_LOAD(1, kt + 3) }
;     MMA_TILE(1)
;     if (kt + 2 < nk) { LDS_STORE(0, 0) }
;     if (VAR != 4) __syncthreads();
	v_mfma_f32_16x16x32_f16 v[50:53], v[128:131], v[144:147], v[50:53]
	ds_read_b128 v[78:81], v16 offset:16384
	v_mfma_f32_16x16x32_f16 v[58:61], v[128:131], v[154:157], v[58:61]
	ds_read_b128 v[108:111], v28 offset:49152
	s_waitcnt lgkmcnt(0)
	v_mfma_f32_16x16x32_f16 v[42:45], v[78:81], v[108:111], v[42:45]
	ds_read_b128 v[128:131], v16 offset:18432
	ds_read_b128 v[132:135], v28 offset:51200
	s_waitcnt lgkmcnt(0)
	v_mfma_f32_16x16x32_f16 v[46:49], v[78:81], v[132:135], v[46:49]
	ds_read_b128 v[144:147], v28 offset:53248
	v_mfma_f32_16x16x32_f16 v[54:57], v[128:131], v[108:111], v[54:57]
	ds_read_b128 v[154:157], v28 offset:55296
	v_mfma_f32_16x16x32_f16 v[70:73], v[128:131], v[132:135], v[70:73]
	s_waitcnt lgkmcnt(1)
	v_mfma_f32_16x16x32_f16 v[104:107], v[78:81], v[144:147], v[104:107]
	s_waitcnt lgkmcnt(0)
	v_mfma_f32_16x16x32_f16 v[22:25], v[78:81], v[154:157], v[22:25]
	ds_read_b128 v[78:81], v16 offset:20480
	v_mfma_f32_16x16x32_f16 v[74:77], v[128:131], v[144:147], v[74:77]
	v_mfma_f32_16x16x32_f16 v[34:37], v[128:131], v[154:157], v[34:37]
	ds_read_b128 v[128:131], v16 offset:22528
	s_waitcnt lgkmcnt(1)
	v_mfma_f32_16x16x32_f16 v[120:123], v[78:81], v[108:111], v[120:123]
	v_mfma_f32_16x16x32_f16 v[124:127], v[78:81], v[132:135], v[124:127]
	s_waitcnt lgkmcnt(0)
	v_mfma_f32_16x16x32_f16 v[62:65], v[128:131], v[108:111], v[62:65]
	ds_read_b128 v[108:111], v32 offset:49152
	v_mfma_f32_16x16x32_f16 v[38:41], v[128:131], v[132:135], v[38:41]
	ds_read_b128 v[132:135], v32 offset:51200
	s_waitcnt vmcnt(7)
	ds_write_b128 v18, v[112:115]
	v_mfma_f32_16x16x32_f16 v[136:139], v[78:81], v[144:147], v[136:139]
	s_waitcnt vmcnt(6)
	ds_write_b128 v19, v[116:119]
	s_waitcnt vmcnt(5)
	ds_write_b128 v20, v[196:199]
	v_mfma_f32_16x16x32_f16 v[66:69], v[78:81], v[154:157], v[66:69]
	ds_read_b128 v[78:81], v29 offset:16384
	s_waitcnt vmcnt(4)
	ds_write_b128 v17, v[200:203]
	v_mfma_f32_16x16x32_f16 v[50:53], v[128:131], v[144:147], v[50:53]
	ds_read_b128 v[144:147], v32 offset:53248
	v_mfma_f32_16x16x32_f16 v[58:61], v[128:131], v[154:157], v[58:61]
	ds_read_b128 v[128:131], v29 offset:18432
	s_waitcnt lgkmcnt(3)
	v_mfma_f32_16x16x32_f16 v[42:45], v[78:81], v[108:111], v[42:45]
	ds_read_b128 v[154:157], v32 offset:55296
	v_mfma_f32_16x16x32_f16 v[46:49], v[78:81], v[132:135], v[46:49]
	s_waitcnt vmcnt(3)
	ds_write_b128 v18, v[140:143] offset:32768
	s_waitcnt lgkmcnt(2)
	v_mfma_f32_16x16x32_f16 v[54:57], v[128:131], v[108:111], v[54:57]
	s_waitcnt vmcnt(2)
	ds_write_b128 v19, v[204:207] offset:32768
	v_mfma_f32_16x16x32_f16 v[70:73], v[128:131], v[132:135], v[70:73]
	s_waitcnt vmcnt(1)
	ds_write_b128 v20, v[208:211] offset:32768
	v_mfma_f32_16x16x32_f16 v[104:107], v[78:81], v[144:147], v[104:107]
	s_waitcnt vmcnt(0)
	ds_write_b128 v17, v[212:215] offset:32768
	s_waitcnt lgkmcnt(4)
	v_mfma_f32_16x16x32_f16 v[22:25], v[78:81], v[154:157], v[22:25]
	ds_read_b128 v[78:81], v29 offset:20480
	v_mfma_f32_16x16x32_f16 v[74:77], v[128:131], v[144:147], v[74:77]
	v_mfma_f32_16x16x32_f16 v[34:37], v[128:131], v[154:157], v[34:37]
	ds_read_b128 v[128:131], v29 offset:22528
	s_waitcnt lgkmcnt(1)
	v_mfma_f32_16x16x32_f16 v[120:123], v[78:81], v[108:111], v[120:123]
	v_mfma_f32_16x16x32_f16 v[124:127], v[78:81], v[132:135], v[124:127]
	s_waitcnt lgkmcnt(0)
	v_mfma_f32_16x16x32_f16 v[62:65], v[128:131], v[108:111], v[62:65]
	v_mfma_f32_16x16x32_f16 v[38:41], v[128:131], v[132:135], v[38:41]
	v_mfma_f32_16x16x32_f16 v[136:139], v[78:81], v[144:147], v[136:139]
	v_mfma_f32_16x16x32_f16 v[66:69], v[78:81], v[154:157], v[66:69]
	global_load_dwordx4 v[78:81], v[0:1], off offset:896
	global_load_dwordx4 v[108:111], v[2:3], off offset:896
	global_load_dwordx4 v[158:161], v[4:5], off offset:896
	global_load_dwordx4 v[162:165], v[8:9], off offset:896
	global_load_dwordx4 v[132:135], v[6:7], off offset:896
	global_load_dwordx4 v[166:169], v[10:11], off offset:896
	global_load_dwordx4 v[188:191], v[12:13], off offset:896
	global_load_dwordx4 v[192:195], v[14:15], off offset:896
	s_waitcnt lgkmcnt(0)
	s_barrier
	v_mfma_f32_16x16x32_f16 v[50:53], v[128:131], v[144:147], v[50:53]
	ds_read_b128 v[112:115], v16
	v_mfma_f32_16x16x32_f16 v[58:61], v[128:131], v[154:157], v[58:61]
	ds_read_b128 v[116:119], v28 offset:32768
	s_waitcnt lgkmcnt(0)
	v_mfma_f32_16x16x32_f16 v[42:45], v[112:115], v[116:119], v[42:45]
	ds_read_b128 v[128:131], v16 offset:2048
	ds_read_b128 v[140:143], v28 offset:34816
	s_waitcnt lgkmcnt(0)
	v_mfma_f32_16x16x32_f16 v[46:49], v[112:115], v[140:143], v[46:49]
	ds_read_b128 v[144:147], v28 offset:36864
	v_mfma_f32_16x16x32_f16 v[54:57], v[128:131], v[116:119], v[54:57]
	ds_read_b128 v[154:157], v28 offset:38912
	v_mfma_f32_16x16x32_f16 v[70:73], v[128:131], v[140:143], v[70:73]
	s_waitcnt lgkmcnt(1)
	v_mfma_f32_16x16x32_f16 v[104:107], v[112:115], v[144:147], v[104:107]
	s_waitcnt lgkmcnt(0)
	v_mfma_f32_16x16x32_f16 v[22:25], v[112:115], v[154:157], v[22:25]
	ds_read_b128 v[112:115], v16 offset:4096
	v_mfma_f32_16x16x32_f16 v[74:77], v[128:131], v[144:147], v[74:77]
	v_mfma_f32_16x16x32_f16 v[34:37], v[128:131], v[154:157], v[34:37]
	ds_read_b128 v[128:131], v16 offset:6144
	s_waitcnt lgkmcnt(1)
	v_mfma_f32_16x16x32_f16 v[120:123], v[112:115], v[116:119], v[120:123]
	v_mfma_f32_16x16x32_f16 v[124:127], v[112:115], v[140:143], v[124:127]
	s_waitcnt lgkmcnt(0)
	v_mfma_f32_16x16x32_f16 v[62:65], v[128:131], v[116:119], v[62:65]
	ds_read_b128 v[116:119], v32 offset:32768
	v_mfma_f32_16x16x32_f16 v[38:41], v[128:131], v[140:143], v[38:41]
	ds_read_b128 v[140:143], v32 offset:34816
	s_waitcnt vmcnt(7)
; #define GL_LOAD(s_, kt_) if (VAR != 1) { a##s_##0 = GL_A(0, kt_); a##s_##1 = GL_A(1, kt_); a##s_##2 = GL_A(2, kt_); a##s_##3 = GL_A(3, kt_); b##s_##0 = GL_B(0, kt_); b##s_##1 = GL_B(1, kt_); b##s_##2 = GL_B(2, kt_); b##s_##3 = GL_B(3, kt_); }
; #define LDS_STORE(s_, buf_) if (VAR != 2) { LDS_ST1(sA, 0, buf_, a##s_##0) LDS_ST1(sA, 1, buf_, a##s_##1) LDS_ST1(sA, 2, buf_, a##s_##2) LDS_ST1(sA, 3, buf_, a##s_##3) LDS_ST1(sB, 0, buf_, b##s_##0) LDS_ST1(sB, 1, buf_, b##s_##1) LDS_ST1(sB, 2, buf_, b##s_##2) LDS_ST1(sB, 3, buf_, b##s_##3) }
;     ...
;   for (int kt = 0; kt < nk; kt += 2) {
;     if (kt + 2 < nk) { GL_LOAD(0, kt + 2) }
;     MMA_TILE(0)
;     LDS_STORE(1, 1)
;     if (VAR != 4) __syncthreads();
;     if (kt + 3 < nk) { GL_LOAD(1, kt + 3) }
;     MMA_TILE(1)
;     if (kt + 2 < nk) { LDS_STORE(0, 0) }
;     if (VAR != 4) __syncthreads();
	ds_write_b128 v18, v[78:81] offset:16384
	v_mfma_f32_16x16x32_f16 v[136:139], v[112:115], v[144:147], v[136:139]
	s_waitcnt vmcnt(6)
	ds_write_b128 v19, v[108:111] offset:16384
	s_waitcnt vmcnt(5)
	ds_write_b128 v20, v[158:161] offset:16384
	v_mfma_f32_16x16x32_f16 v[66:69], v[112:115], v[154:157], v[66:69]
	ds_read_b128 v[112:115], v29
	s_waitcnt vmcnt(4)
	ds_write_b128 v17, v[162:165] offset:16384
	v_mfma_f32_16x16x32_f16 v[50:53], v[128:131], v[144:147], v[50:53]
	ds_read_b128 v[144:147], v32 offset:36864
	v_mfma_f32_16x16x32_f16 v[58:61], v[128:131], v[154:157], v[58:61]
	ds_read_b128 v[128:131], v29 offset:2048
	s_waitcnt lgkmcnt(3)
	v_mfma_f32_16x16x32_f16 v[42:45], v[112:115], v[116:119], v[42:45]
	ds_read_b128 v[154:157], v32 offset:38912
	v_mfma_f32_16x16x32_f16 v[46:49], v[112:115], v[140:143], v[46:49]
	s_waitcnt vmcnt(3)
	ds_write_b128 v18, v[132:135] offset:49152
	s_waitcnt lgkmcnt(2)
	v_mfma_f32_16x16x32_f16 v[54:57], v[128:131], v[116:119], v[54:57]
	s_waitcnt vmcnt(2)
	ds_write_b128 v19, v[166:169] offset:49152
	v_mfma_f32_16x16x32_f16 v[70:73], v[128:131], v[140:143], v[70:73]
	s_waitcnt vmcnt(1)
	ds_write_b128 v20, v[188:191] offset:49152
	v_mfma_f32_16x16x32_f16 v[104:107], v[112:115], v[144:147], v[104:107]
	s_waitcnt vmcnt(0)
	ds_write_b128 v17, v[192:195] offset:49152
	s_waitcnt lgkmcnt(4)
	v_mfma_f32_16x16x32_f16 v[22:25], v[112:115], v[154:157], v[22:25]
	ds_read_b128 v[112:115], v29 offset:4096
	v_mfma_f32_16x16x32_f16 v[74:77], v[128:131], v[144:147], v[74:77]
	v_mfma_f32_16x16x32_f16 v[34:37], v[128:131], v[154:157], v[34:37]
	ds_read_b128 v[128:131], v29 offset:6144
	s_waitcnt lgkmcnt(1)
	v_mfma_f32_16x16x32_f16 v[120:123], v[112:115], v[116:119], v[120:123]
	v_mfma_f32_16x16x32_f16 v[124:127], v[112:115], v[140:143], v[124:127]
	s_waitcnt lgkmcnt(0)
	v_mfma_f32_16x16x32_f16 v[62:65], v[128:131], v[116:119], v[62:65]
	v_mfma_f32_16x16x32_f16 v[38:41], v[128:131], v[140:143], v[38:41]
	v_mfma_f32_16x16x32_f16 v[136:139], v[112:115], v[144:147], v[136:139]
	v_mfma_f32_16x16x32_f16 v[66:69], v[112:115], v[154:157], v[66:69]
	global_load_dwordx4 v[112:115], v[0:1], off offset:1024
	global_load_dwordx4 v[116:119], v[2:3], off offset:1024
	global_load_dwordx4 v[196:199], v[4:5], off offset:1024
	global_load_dwordx4 v[200:203], v[8:9], off offset:1024
	global_load_dwordx4 v[140:143], v[6:7], off offset:1024
	global_load_dwordx4 v[204:207], v[10:11], off offset:1024
	global_load_dwordx4 v[208:211], v[12:13], off offset:1024
	global_load_dwordx4 v[212:215], v[14:15], off offset:1024
	s_waitcnt lgkmcnt(0)
	s_barrier
	v_mfma_f32_16x16x32_f16 v[50:53], v[128:131], v[144:147], v[50:53]
	ds_read_b128 v[78:81], v16 offset:16384
	v_mfma_f32_16x16x32_f16 v[58:61], v[128:131], v[154:157], v[58:61]
	ds_read_b128 v[108:111], v28 offset:49152
	s_waitcnt lgkmcnt(0)
	v_mfma_f32_16x16x32_f16 v[42:45], v[78:81], v[108:111], v[42:45]
	ds_read_b128 v[128:131], v16 offset:18432
	ds_read_b128 v[132:135], v28 offset:51200
	s_waitcnt lgkmcnt(0)
	v_mfma_f32_16x16x32_f16 v[46:49], v[78:81], v[132:135], v[46:49]
	ds_read_b128 v[144:147], v28 offset:53248
	v_mfma_f32_16x16x32_f16 v[54:57], v[128:131], v[108:111], v[54:57]
	ds_read_b128 v[154:157], v28 offset:55296
	v_mfma_f32_16x16x32_f16 v[70:73], v[128:131], v[132:135], v[70:73]
	s_waitcnt lgkmcnt(1)
	v_mfma_f32_16x16x32_f16 v[104:107], v[78:81], v[144:147], v[104:107]
	s_waitcnt lgkmcnt(0)
	v_mfma_f32_16x16x32_f16 v[22:25], v[78:81], v[154:157], v[22:25]
	ds_read_b128 v[78:81], v16 offset:20480
	v_mfma_f32_16x16x32_f16 v[74:77], v[128:131], v[144:147], v[74:77]
	v_mfma_f32_16x16x32_f16 v[34:37], v[128:131], v[154:157], v[34:37]
	ds_read_b128 v[128:131], v16 offset:22528
	s_waitcnt lgkmcnt(1)
	v_mfma_f32_16x16x32_f16 v[120:123], v[78:81], v[108:111], v[120:123]
	v_mfma_f32_16x16x32_f16 v[124:127], v[78:81], v[132:135], v[124:127]
	s_waitcnt lgkmcnt(0)
	v_mfma_f32_16x16x32_f16 v[62:65], v[128:131], v[108:111], v[62:65]
	ds_read_b128 v[108:111], v32 offset:49152
	v_mfma_f32_16x16x32_f16 v[38:41], v[128:131], v[132:135], v[38:41]
	ds_read_b128 v[132:135], v32 offset:51200
	s_waitcnt vmcnt(7)
	ds_write_b128 v18, v[112:115]
	v_mfma_f32_16x16x32_f16 v[136:139], v[78:81], v[144:147], v[136:139]
	s_waitcnt vmcnt(6)
	ds_write_b128 v19, v[116:119]
	s_waitcnt vmcnt(5)
	ds_write_b128 v20, v[196:199]
	v_mfma_f32_16x16x32_f16 v[66:69], v[78:81], v[154:157], v[66:69]
	ds_read_b128 v[78:81], v29 offset:16384
	s_waitcnt vmcnt(4)
	ds_write_b128 v17, v[200:203]
	v_mfma_f32_16x16x32_f16 v[50:53], v[128:131], v[144:147], v[50:53]
	ds_read_b128 v[144:147], v32 offset:53248
	v_mfma_f32_16x16x32_f16 v[58:61], v[128:131], v[154:157], v[58:61]
	ds_read_b128 v[128:131], v29 offset:18432
	s_waitcnt lgkmcnt(3)
	v_mfma_f32_16x16x32_f16 v[42:45], v[78:81], v[108:111], v[42:45]
	ds_read_b128 v[154:157], v32 offset:55296
	v_mfma_f32_16x16x32_f16 v[46:49], v[78:81], v[132:135], v[46:49]
	s_waitcnt vmcnt(3)
	ds_write_b128 v18, v[140:143] offset:32768
	s_waitcnt lgkmcnt(2)
	v_mfma_f32_16x16x32_f16 v[54:57], v[128:131], v[108:111], v[54:57]
	s_waitcnt vmcnt(2)
	ds_write_b128 v19, v[204:207] offset:32768
	v_mfma_f32_16x16x32_f16 v[70:73], v[128:131], v[132:135], v[70:73]
	s_waitcnt vmcnt(1)
	ds_write_b128 v20, v[208:211] offset:32768
	v_mfma_f32_16x16x32_f16 v[104:107], v[78:81], v[144:147], v[104:107]
	s_waitcnt vmcnt(0)
	ds_write_b128 v17, v[212:215] offset:32768
	s_waitcnt lgkmcnt(4)
	v_mfma_f32_16x16x32_f16 v[22:25], v[78:81], v[154:157], v[22:25]
	ds_read_b128 v[78:81], v29 offset:20480
	v_mfma_f32_16x16x32_f16 v[74:77], v[128:131], v[144:147], v[74:77]
	v_mfma_f32_16x16x32_f16 v[34:37], v[128:131], v[154:157], v[34:37]
	ds_read_b128 v[128:131], v29 offset:22528
	s_waitcnt lgkmcnt(1)
	v_mfma_f32_16x16x32_f16 v[120:123], v[78:81], v[108:111], v[120:123]
	v_mfma_f32_16x16x32_f16 v[124:127], v[78:81], v[132:135], v[124:127]
	s_waitcnt lgkmcnt(0)
	v_mfma_f32_16x16x32_f16 v[62:65], v[128:131], v[108:111], v[62:65]
	v_mfma_f32_16x16x32_f16 v[38:41], v[128:131], v[132:135], v[38:41]
	v_mfma_f32_16x16x32_f16 v[136:139], v[78:81], v[144:147], v[136:139]
	v_mfma_f32_16x16x32_f16 v[66:69], v[78:81], v[154:157], v[66:69]
	global_load_dwordx4 v[78:81], v[0:1], off offset:1152
	global_load_dwordx4 v[108:111], v[2:3], off offset:1152
	global_load_dwordx4 v[158:161], v[4:5], off offset:1152
	global_load_dwordx4 v[162:165], v[8:9], off offset:1152
	global_load_dwordx4 v[132:135], v[6:7], off offset:1152
	global_load_dwordx4 v[166:169], v[10:11], off offset:1152
	global_load_dwordx4 v[188:191], v[12:13], off offset:1152
	global_load_dwordx4 v[192:195], v[14:15], off offset:1152
	s_waitcnt lgkmcnt(0)
	s_barrier
; #define GL_LOAD(s_, kt_) if (VAR != 1) { a##s_##0 = GL_A(0, kt_); a##s_##1 = GL_A(1, kt_); a##s_##2 = GL_A(2, kt_); a##s_##3 = GL_A(3, kt_); b##s_##0 = GL_B(0, kt_); b##s_##1 = GL_B(1, kt_); b##s_##2 = GL_B(2, kt_); b##s_##3 = GL_B(3, kt_); }
; #define LDS_STORE(s_, buf_) if (VAR != 2) { LDS_ST1(sA, 0, buf_, a##s_##0) LDS_ST1(sA, 1, buf_, a##s_##1) LDS_ST1(sA, 2, buf_, a##s_##2) LDS_ST1(sA, 3, buf_, a##s_##3) LDS_ST1(sB, 0, buf_, b##s_##0) LDS_ST1(sB, 1, buf_, b##s_##1) LDS_ST1(sB, 2, buf_, b##s_##2) LDS_ST1(sB, 3, buf_, b##s_##3) }
;     ...
;   for (int kt = 0; kt < nk; kt += 2) {
;     if (kt + 2 < nk) { GL_LOAD(0, kt + 2) }
;     MMA_TILE(0)
;     LDS_STORE(1, 1)
;     if (VAR != 4) __syncthreads();
;     if (kt + 3 < nk) { GL_LOAD(1, kt + 3) }
;     MMA_TILE(1)
;     if (kt + 2 < nk) { LDS_STORE(0, 0) }
;     if (VAR != 4) __syncthreads();
	v_mfma_f32_16x16x32_f16 v[50:53], v[128:131], v[144:147], v[50:53]
	ds_read_b128 v[112:115], v16
	v_mfma_f32_16x16x32_f16 v[58:61], v[128:131], v[154:157], v[58:61]
	ds_read_b128 v[116:119], v28 offset:32768
	s_waitcnt lgkmcnt(0)
	v_mfma_f32_16x16x32_f16 v[42:45], v[112:115], v[116:119], v[42:45]
	ds_read_b128 v[128:131], v16 offset:2048
	ds_read_b128 v[140:143], v28 offset:34816
	s_waitcnt lgkmcnt(0)
	v_mfma_f32_16x16x32_f16 v[46:49], v[112:115], v[140:143], v[46:49]
	ds_read_b128 v[144:147], v28 offset:36864
	v_mfma_f32_16x16x32_f16 v[54:57], v[128:131], v[116:119], v[54:57]
	ds_read_b128 v[154:157], v28 offset:38912
	v_mfma_f32_16x16x32_f16 v[70:73], v[128:131], v[140:143], v[70:73]
	s_waitcnt lgkmcnt(1)
	v_mfma_f32_16x16x32_f16 v[104:107], v[112:115], v[144:147], v[104:107]
	s_waitcnt lgkmcnt(0)
	v_mfma_f32_16x16x32_f16 v[22:25], v[112:115], v[154:157], v[22:25]
	ds_read_b128 v[112:115], v16 offset:4096
	v_mfma_f32_16x16x32_f16 v[74:77], v[128:131], v[144:147], v[74:77]
	v_mfma_f32_16x16x32_f16 v[34:37], v[128:131], v[154:157], v[34:37]
	ds_read_b128 v[128:131], v16 offset:6144
	s_waitcnt lgkmcnt(1)
	v_mfma_f32_16x16x32_f16 v[120:123], v[112:115], v[116:119], v[120:123]
	v_mfma_f32_16x16x32_f16 v[124:127], v[112:115], v[140:143], v[124:127]
	s_waitcnt lgkmcnt(0)
	v_mfma_f32_16x16x32_f16 v[62:65], v[128:131], v[116:119], v[62:65]
	ds_read_b128 v[116:119], v32 offset:32768
	v_mfma_f32_16x16x32_f16 v[38:41], v[128:131], v[140:143], v[38:41]
	ds_read_b128 v[140:143], v32 offset:34816
	s_waitcnt vmcnt(7)
	ds_write_b128 v18, v[78:81] offset:16384
	v_mfma_f32_16x16x32_f16 v[136:139], v[112:115], v[144:147], v[136:139]
	s_waitcnt vmcnt(6)
	ds_write_b128 v19, v[108:111] offset:16384
	s_waitcnt vmcnt(5)
	ds_write_b128 v20, v[158:161] offset:16384
	v_mfma_f32_16x16x32_f16 v[66:69], v[112:115], v[154:157], v[66:69]
	ds_read_b128 v[112:115], v29
	s_waitcnt vmcnt(4)
	ds_write_b128 v17, v[162:165] offset:16384
	v_mfma_f32_16x16x32_f16 v[50:53], v[128:131], v[144:147], v[50:53]
	ds_read_b128 v[144:147], v32 offset:36864
	v_mfma_f32_16x16x32_f16 v[58:61], v[128:131], v[154:157], v[58:61]
	ds_read_b128 v[128:131], v29 offset:2048
	s_waitcnt lgkmcnt(3)
	v_mfma_f32_16x16x32_f16 v[42:45], v[112:115], v[116:119], v[42:45]
	ds_read_b128 v[154:157], v32 offset:38912
	v_mfma_f32_16x16x32_f16 v[46:49], v[112:115], v[140:143], v[46:49]
	s_waitcnt vmcnt(3)
	ds_write_b128 v18, v[132:135] offset:49152
	s_waitcnt lgkmcnt(2)
	v_mfma_f32_16x16x32_f16 v[54:57], v[128:131], v[116:119], v[54:57]
	s_waitcnt vmcnt(2)
	ds_write_b128 v19, v[166:169] offset:49152
	v_mfma_f32_16x16x32_f16 v[70:73], v[128:131], v[140:143], v[70:73]
	s_waitcnt vmcnt(1)
	ds_write_b128 v20, v[188:191] offset:49152
	v_mfma_f32_16x16x32_f16 v[104:107], v[112:115], v[144:147], v[104:107]
	s_waitcnt vmcnt(0)
	ds_write_b128 v17, v[192:195] offset:49152
	s_waitcnt lgkmcnt(4)
	v_mfma_f32_16x16x32_f16 v[22:25], v[112:115], v[154:157], v[22:25]
	ds_read_b128 v[112:115], v29 offset:4096
	v_mfma_f32_16x16x32_f16 v[74:77], v[128:131], v[144:147], v[74:77]
	v_mfma_f32_16x16x32_f16 v[34:37], v[128:131], v[154:157], v[34:37]
	ds_read_b128 v[128:131], v29 offset:6144
	s_waitcnt lgkmcnt(1)
	v_mfma_f32_16x16x32_f16 v[120:123], v[112:115], v[116:119], v[120:123]
	v_mfma_f32_16x16x32_f16 v[124:127], v[112:115], v[140:143], v[124:127]
	s_waitcnt lgkmcnt(0)
	v_mfma_f32_16x16x32_f16 v[62:65], v[128:131], v[116:119], v[62:65]
	v_mfma_f32_16x16x32_f16 v[38:41], v[128:131], v[140:143], v[38:41]
	v_mfma_f32_16x16x32_f16 v[136:139], v[112:115], v[144:147], v[136:139]
	v_mfma_f32_16x16x32_f16 v[66:69], v[112:115], v[154:157], v[66:69]
	global_load_dwordx4 v[112:115], v[0:1], off offset:1280
	global_load_dwordx4 v[116:119], v[2:3], off offset:1280
	global_load_dwordx4 v[196:199], v[4:5], off offset:1280
	global_load_dwordx4 v[200:203], v[8:9], off offset:1280
	global_load_dwordx4 v[140:143], v[6:7], off offset:1280
	global_load_dwordx4 v[204:207], v[10:11], off offset:1280
	global_load_dwordx4 v[208:211], v[12:13], off offset:1280
	global_load_dwordx4 v[212:215], v[14:15], off offset:1280
	s_waitcnt lgkmcnt(0)
	s_barrier
	v_mfma_f32_16x16x32_f16 v[50:53], v[128:131], v[144:147], v[50:53]
	ds_read_b128 v[78:81], v16 offset:16384
	v_mfma_f32_16x16x32_f16 v[58:61], v[128:131], v[154:157], v[58:61]
	ds_read_b128 v[108:111], v28 offset:49152
	s_waitcnt lgkmcnt(0)
	v_mfma_f32_16x16x32_f16 v[42:45], v[78:81], v[108:111], v[42:45]
	ds_read_b128 v[128:131], v16 offset:18432
	ds_read_b128 v[132:135], v28 offset:51200
	s_waitcnt lgkmcnt(0)
	v_mfma_f32_16x16x32_f16 v[46:49], v[78:81], v[132:135], v[46:49]
	ds_read_b128 v[144:147], v28 offset:53248
	v_mfma_f32_16x16x32_f16 v[54:57], v[128:131], v[108:111], v[54:57]
	ds_read_b128 v[154:157], v28 offset:55296
	v_mfma_f32_16x16x32_f16 v[70:73], v[128:131], v[132:135], v[70:73]
	s_waitcnt lgkmcnt(1)
	v_mfma_f32_16x16x32_f16 v[104:107], v[78:81], v[144:147], v[104:107]
	s_waitcnt lgkmcnt(0)
	v_mfma_f32_16x16x32_f16 v[22:25], v[78:81], v[154:157], v[22:25]
	ds_read_b128 v[78:81], v16 offset:20480
	v_mfma_f32_16x16x32_f16 v[74:77], v[128:131], v[144:147], v[74:77]
	v_mfma_f32_16x16x32_f16 v[34:37], v[128:131], v[154:157], v[34:37]
	ds_read_b128 v[128:131], v16 offset:22528
	s_waitcnt lgkmcnt(1)
	v_mfma_f32_16x16x32_f16 v[120:123], v[78:81], v[108:111], v[120:123]
	v_mfma_f32_16x16x32_f16 v[124:127], v[78:81], v[132:135], v[124:127]
	s_waitcnt lgkmcnt(0)
	v_mfma_f32_16x16x32_f16 v[62:65], v[128:131], v[108:111], v[62:65]
	ds_read_b128 v[108:111], v32 offset:49152
	v_mfma_f32_16x16x32_f16 v[38:41], v[128:131], v[132:135], v[38:41]
	ds_read_b128 v[132:135], v32 offset:51200
	s_waitcnt vmcnt(7)
; #define GL_LOAD(s_, kt_) if (VAR != 1) { a##s_##0 = GL_A(0, kt_); a##s_##1 = GL_A(1, kt_); a##s_##2 = GL_A(2, kt_); a##s_##3 = GL_A(3, kt_); b##s_##0 = GL_B(0, kt_); b##s_##1 = GL_B(1, kt_); b##s_##2 = GL_B(2, kt_); b##s_##3 = GL_B(3, kt_); }
; #define LDS_STORE(s_, buf_) if (VAR != 2) { LDS_ST1(sA, 0, buf_, a##s_##0) LDS_ST1(sA, 1, buf_, a##s_##1) LDS_ST1(sA, 2, buf_, a##s_##2) LDS_ST1(sA, 3, buf_, a##s_##3) LDS_ST1(sB, 0, buf_, b##s_##0) LDS_ST1(sB, 1, buf_, b##s_##1) LDS_ST1(sB, 2, buf_, b##s_##2) LDS_ST1(sB, 3, buf_, b##s_##3) }
;     ...
;   for (int kt = 0; kt < nk; kt += 2) {
;     if (kt + 2 < nk) { GL_LOAD(0, kt + 2) }
;     MMA_TILE(0)
;     LDS_STORE(1, 1)
;     if (VAR != 4) __syncthreads();
;     if (kt + 3 < nk) { GL_LOAD(1, kt + 3) }
;     MMA_TILE(1)
;     if (kt + 2 < nk) { LDS_STORE(0, 0) }
;     if (VAR != 4) __syncthreads();
	ds_write_b128 v18, v[112:115]
	v_mfma_f32_16x16x32_f16 v[136:139], v[78:81], v[144:147], v[136:139]
	s_waitcnt vmcnt(6)
	ds_write_b128 v19, v[116:119]
	s_waitcnt vmcnt(5)
	ds_write_b128 v20, v[196:199]
	v_mfma_f32_16x16x32_f16 v[66:69], v[78:81], v[154:157], v[66:69]
	ds_read_b128 v[78:81], v29 offset:16384
	s_waitcnt vmcnt(4)
	ds_write_b128 v17, v[200:203]
	v_mfma_f32_16x16x32_f16 v[50:53], v[128:131], v[144:147], v[50:53]
	ds_read_b128 v[144:147], v32 offset:53248
	v_mfma_f32_16x16x32_f16 v[58:61], v[128:131], v[154:157], v[58:61]
	ds_read_b128 v[128:131], v29 offset:18432
	s_waitcnt lgkmcnt(3)
	v_mfma_f32_16x16x32_f16 v[42:45], v[78:81], v[108:111], v[42:45]
	ds_read_b128 v[154:157], v32 offset:55296
	v_mfma_f32_16x16x32_f16 v[46:49], v[78:81], v[132:135], v[46:49]
	s_waitcnt vmcnt(3)
	ds_write_b128 v18, v[140:143] offset:32768
	s_waitcnt lgkmcnt(2)
	v_mfma_f32_16x16x32_f16 v[54:57], v[128:131], v[108:111], v[54:57]
	s_waitcnt vmcnt(2)
	ds_write_b128 v19, v[204:207] offset:32768
	v_mfma_f32_16x16x32_f16 v[70:73], v[128:131], v[132:135], v[70:73]
	s_waitcnt vmcnt(1)
	ds_write_b128 v20, v[208:211] offset:32768
	v_mfma_f32_16x16x32_f16 v[104:107], v[78:81], v[144:147], v[104:107]
	s_waitcnt vmcnt(0)
	ds_write_b128 v17, v[212:215] offset:32768
	s_waitcnt lgkmcnt(4)
	v_mfma_f32_16x16x32_f16 v[22:25], v[78:81], v[154:157], v[22:25]
	ds_read_b128 v[78:81], v29 offset:20480
	v_mfma_f32_16x16x32_f16 v[74:77], v[128:131], v[144:147], v[74:77]
	v_mfma_f32_16x16x32_f16 v[34:37], v[128:131], v[154:157], v[34:37]
	ds_read_b128 v[128:131], v29 offset:22528
	s_waitcnt lgkmcnt(1)
	v_mfma_f32_16x16x32_f16 v[120:123], v[78:81], v[108:111], v[120:123]
	v_mfma_f32_16x16x32_f16 v[124:127], v[78:81], v[132:135], v[124:127]
	s_waitcnt lgkmcnt(0)
	v_mfma_f32_16x16x32_f16 v[62:65], v[128:131], v[108:111], v[62:65]
	v_mfma_f32_16x16x32_f16 v[38:41], v[128:131], v[132:135], v[38:41]
	v_mfma_f32_16x16x32_f16 v[136:139], v[78:81], v[144:147], v[136:139]
	v_mfma_f32_16x16x32_f16 v[66:69], v[78:81], v[154:157], v[66:69]
	global_load_dwordx4 v[78:81], v[0:1], off offset:1408
	global_load_dwordx4 v[108:111], v[2:3], off offset:1408
	global_load_dwordx4 v[158:161], v[4:5], off offset:1408
	global_load_dwordx4 v[162:165], v[8:9], off offset:1408
	global_load_dwordx4 v[132:135], v[6:7], off offset:1408
	global_load_dwordx4 v[166:169], v[10:11], off offset:1408
	global_load_dwordx4 v[188:191], v[12:13], off offset:1408
	global_load_dwordx4 v[192:195], v[14:15], off offset:1408
	s_waitcnt lgkmcnt(0)
	s_barrier
	v_mfma_f32_16x16x32_f16 v[50:53], v[128:131], v[144:147], v[50:53]
	ds_read_b128 v[112:115], v16
	v_mfma_f32_16x16x32_f16 v[58:61], v[128:131], v[154:157], v[58:61]
	ds_read_b128 v[116:119], v28 offset:32768
	s_waitcnt lgkmcnt(0)
	v_mfma_f32_16x16x32_f16 v[42:45], v[112:115], v[116:119], v[42:45]
	ds_read_b128 v[128:131], v16 offset:2048
	ds_read_b128 v[140:143], v28 offset:34816
	s_waitcnt lgkmcnt(0)
	v_mfma_f32_16x16x32_f16 v[46:49], v[112:115], v[140:143], v[46:49]
	ds_read_b128 v[144:147], v28 offset:36864
	v_mfma_f32_16x16x32_f16 v[54:57], v[128:131], v[116:119], v[54:57]
	ds_read_b128 v[154:157], v28 offset:38912
	v_mfma_f32_16x16x32_f16 v[70:73], v[128:131], v[140:143], v[70:73]
	s_waitcnt lgkmcnt(1)
	v_mfma_f32_16x16x32_f16 v[104:107], v[112:115], v[144:147], v[104:107]
	s_waitcnt lgkmcnt(0)
	v_mfma_f32_16x16x32_f16 v[22:25], v[112:115], v[154:157], v[22:25]
	ds_read_b128 v[112:115], v16 offset:4096
	v_mfma_f32_16x16x32_f16 v[74:77], v[128:131], v[144:147], v[74:77]
	v_mfma_f32_16x16x32_f16 v[34:37], v[128:131], v[154:157], v[34:37]
	ds_read_b128 v[128:131], v16 offset:6144
	s_waitcnt lgkmcnt(1)
	v_mfma_f32_16x16x32_f16 v[120:123], v[112:115], v[116:119], v[120:123]
	v_mfma_f32_16x16x32_f16 v[124:127], v[112:115], v[140:143], v[124:127]
	s_waitcnt lgkmcnt(0)
	v_mfma_f32_16x16x32_f16 v[62:65], v[128:131], v[116:119], v[62:65]
	ds_read_b128 v[116:119], v32 offset:32768
	v_mfma_f32_16x16x32_f16 v[38:41], v[128:131], v[140:143], v[38:41]
	ds_read_b128 v[140:143], v32 offset:34816
	s_waitcnt vmcnt(7)
	ds_write_b128 v18, v[78:81] offset:16384
	v_mfma_f32_16x16x32_f16 v[136:139], v[112:115], v[144:147], v[136:139]
	s_waitcnt vmcnt(6)
	ds_write_b128 v19, v[108:111] offset:16384
	s_waitcnt vmcnt(5)
	ds_write_b128 v20, v[158:161] offset:16384
	v_mfma_f32_16x16x32_f16 v[66:69], v[112:115], v[154:157], v[66:69]
	ds_read_b128 v[112:115], v29
	s_waitcnt vmcnt(4)
	ds_write_b128 v17, v[162:165] offset:16384
	v_mfma_f32_16x16x32_f16 v[50:53], v[128:131], v[144:147], v[50:53]
	ds_read_b128 v[144:147], v32 offset:36864
	v_mfma_f32_16x16x32_f16 v[58:61], v[128:131], v[154:157], v[58:61]
	ds_read_b128 v[128:131], v29 offset:2048
	s_waitcnt lgkmcnt(3)
	v_mfma_f32_16x16x32_f16 v[42:45], v[112:115], v[116:119], v[42:45]
	ds_read_b128 v[154:157], v32 offset:38912
	v_mfma_f32_16x16x32_f16 v[46:49], v[112:115], v[140:143], v[46:49]
	s_waitcnt vmcnt(3)
	ds_write_b128 v18, v[132:135] offset:49152
	s_waitcnt lgkmcnt(2)
	v_mfma_f32_16x16x32_f16 v[54:57], v[128:131], v[116:119], v[54:57]
	s_waitcnt vmcnt(2)
	ds_write_b128 v19, v[166:169] offset:49152
	v_mfma_f32_16x16x32_f16 v[70:73], v[128:131], v[140:143], v[70:73]
	s_waitcnt vmcnt(1)
	ds_write_b128 v20, v[188:191] offset:49152
	v_mfma_f32_16x16x32_f16 v[104:107], v[112:115], v[144:147], v[104:107]
	s_waitcnt vmcnt(0)
	ds_write_b128 v17, v[192:195] offset:49152
	s_waitcnt lgkmcnt(4)
	v_mfma_f32_16x16x32_f16 v[22:25], v[112:115], v[154:157], v[22:25]
	ds_read_b128 v[112:115], v29 offset:4096
	v_mfma_f32_16x16x32_f16 v[74:77], v[128:131], v[144:147], v[74:77]
	v_mfma_f32_16x16x32_f16 v[34:37], v[128:131], v[154:157], v[34:37]
	ds_read_b128 v[128:131], v29 offset:6144
	s_waitcnt lgkmcnt(1)
	v_mfma_f32_16x16x32_f16 v[120:123], v[112:115], v[116:119], v[120:123]
	v_mfma_f32_16x16x32_f16 v[124:127], v[112:115], v[140:143], v[124:127]
	s_waitcnt lgkmcnt(0)
	v_mfma_f32_16x16x32_f16 v[62:65], v[128:131], v[116:119], v[62:65]
	v_mfma_f32_16x16x32_f16 v[38:41], v[128:131], v[140:143], v[38:41]
	v_mfma_f32_16x16x32_f16 v[136:139], v[112:115], v[144:147], v[136:139]
	v_mfma_f32_16x16x32_f16 v[66:69], v[112:115], v[154:157], v[66:69]
	global_load_dwordx4 v[112:115], v[0:1], off offset:1536
	global_load_dwordx4 v[116:119], v[2:3], off offset:1536
	global_load_dwordx4 v[196:199], v[4:5], off offset:1536
	global_load_dwordx4 v[200:203], v[8:9], off offset:1536
	global_load_dwordx4 v[140:143], v[6:7], off offset:1536
	global_load_dwordx4 v[204:207], v[10:11], off offset:1536
	global_load_dwordx4 v[208:211], v[12:13], off offset:1536
	global_load_dwordx4 v[212:215], v[14:15], off offset:1536
	s_waitcnt lgkmcnt(0)
	s_barrier
; #define GL_LOAD(s_, kt_) if (VAR != 1) { a##s_##0 = GL_A(0, kt_); a##s_##1 = GL_A(1, kt_); a##s_##2 = GL_A(2, kt_); a##s_##3 = GL_A(3, kt_); b##s_##0 = GL_B(0, kt_); b##s_##1 = GL_B(1, kt_); b##s_##2 = GL_B(2, kt_); b##s_##3 = GL_B(3, kt_); }
; #define LDS_STORE(s_, buf_) if (VAR != 2) { LDS_ST1(sA, 0, buf_, a##s_##0) LDS_ST1(sA, 1, buf_, a##s_##1) LDS_ST1(sA, 2, buf_, a##s_##2) LDS_ST1(sA, 3, buf_, a##s_##3) LDS_ST1(sB, 0, buf_, b##s_##0) LDS_ST1(sB, 1, buf_, b##s_##1) LDS_ST1(sB, 2, buf_, b##s_##2) LDS_ST1(sB, 3, buf_, b##s_##3) }
;     ...
;   for (int kt = 0; kt < nk; kt += 2) {
;     if (kt + 2 < nk) { GL_LOAD(0, kt + 2) }
;     MMA_TILE(0)
;     LDS_STORE(1, 1)
;     if (VAR != 4) __syncthreads();
;     if (kt + 3 < nk) { GL_LOAD(1, kt + 3) }
;     MMA_TILE(1)
;     if (kt + 2 < nk) { LDS_STORE(0, 0) }
;     if (VAR != 4) __syncthreads();
	v_mfma_f32_16x16x32_f16 v[50:53], v[128:131], v[144:147], v[50:53]
	ds_read_b128 v[78:81], v16 offset:16384
	v_mfma_f32_16x16x32_f16 v[58:61], v[128:131], v[154:157], v[58:61]
	ds_read_b128 v[108:111], v28 offset:49152
	s_waitcnt lgkmcnt(0)
	v_mfma_f32_16x16x32_f16 v[42:45], v[78:81], v[108:111], v[42:45]
	ds_read_b128 v[128:131], v16 offset:18432
	ds_read_b128 v[132:135], v28 offset:51200
	s_waitcnt lgkmcnt(0)
	v_mfma_f32_16x16x32_f16 v[46:49], v[78:81], v[132:135], v[46:49]
	ds_read_b128 v[144:147], v28 offset:53248
	v_mfma_f32_16x16x32_f16 v[54:57], v[128:131], v[108:111], v[54:57]
	ds_read_b128 v[154:157], v28 offset:55296
	v_mfma_f32_16x16x32_f16 v[70:73], v[128:131], v[132:135], v[70:73]
	s_waitcnt lgkmcnt(1)
	v_mfma_f32_16x16x32_f16 v[104:107], v[78:81], v[144:147], v[104:107]
	s_waitcnt lgkmcnt(0)
	v_mfma_f32_16x16x32_f16 v[22:25], v[78:81], v[154:157], v[22:25]
	ds_read_b128 v[78:81], v16 offset:20480
	v_mfma_f32_16x16x32_f16 v[74:77], v[128:131], v[144:147], v[74:77]
	v_mfma_f32_16x16x32_f16 v[34:37], v[128:131], v[154:157], v[34:37]
	ds_read_b128 v[128:131], v16 offset:22528
	s_waitcnt lgkmcnt(1)
	v_mfma_f32_16x16x32_f16 v[120:123], v[78:81], v[108:111], v[120:123]
	v_mfma_f32_16x16x32_f16 v[124:127], v[78:81], v[132:135], v[124:127]
	s_waitcnt lgkmcnt(0)
	v_mfma_f32_16x16x32_f16 v[62:65], v[128:131], v[108:111], v[62:65]
	ds_read_b128 v[108:111], v32 offset:49152
	v_mfma_f32_16x16x32_f16 v[38:41], v[128:131], v[132:135], v[38:41]
	ds_read_b128 v[132:135], v32 offset:51200
	s_waitcnt vmcnt(7)
	ds_write_b128 v18, v[112:115]
	v_mfma_f32_16x16x32_f16 v[136:139], v[78:81], v[144:147], v[136:139]
	s_waitcnt vmcnt(6)
	ds_write_b128 v19, v[116:119]
	s_waitcnt vmcnt(5)
	ds_write_b128 v20, v[196:199]
	v_mfma_f32_16x16x32_f16 v[66:69], v[78:81], v[154:157], v[66:69]
	ds_read_b128 v[78:81], v29 offset:16384
	s_waitcnt vmcnt(4)
	ds_write_b128 v17, v[200:203]
	v_mfma_f32_16x16x32_f16 v[50:53], v[128:131], v[144:147], v[50:53]
	ds_read_b128 v[144:147], v32 offset:53248
	v_mfma_f32_16x16x32_f16 v[58:61], v[128:131], v[154:157], v[58:61]
	ds_read_b128 v[128:131], v29 offset:18432
	s_waitcnt lgkmcnt(3)
	v_mfma_f32_16x16x32_f16 v[42:45], v[78:81], v[108:111], v[42:45]
	ds_read_b128 v[154:157], v32 offset:55296
	v_mfma_f32_16x16x32_f16 v[46:49], v[78:81], v[132:135], v[46:49]
	s_waitcnt vmcnt(3)
	ds_write_b128 v18, v[140:143] offset:32768
	s_waitcnt lgkmcnt(2)
	v_mfma_f32_16x16x32_f16 v[54:57], v[128:131], v[108:111], v[54:57]
	s_waitcnt vmcnt(2)
	ds_write_b128 v19, v[204:207] offset:32768
	v_mfma_f32_16x16x32_f16 v[70:73], v[128:131], v[132:135], v[70:73]
	s_waitcnt vmcnt(1)
	ds_write_b128 v20, v[208:211] offset:32768
	v_mfma_f32_16x16x32_f16 v[104:107], v[78:81], v[144:147], v[104:107]
	s_waitcnt vmcnt(0)
	ds_write_b128 v17, v[212:215] offset:32768
	s_waitcnt lgkmcnt(4)
	v_mfma_f32_16x16x32_f16 v[22:25], v[78:81], v[154:157], v[22:25]
	ds_read_b128 v[78:81], v29 offset:20480
	v_mfma_f32_16x16x32_f16 v[74:77], v[128:131], v[144:147], v[74:77]
	v_mfma_f32_16x16x32_f16 v[34:37], v[128:131], v[154:157], v[34:37]
	ds_read_b128 v[128:131], v29 offset:22528
	s_waitcnt lgkmcnt(1)
	v_mfma_f32_16x16x32_f16 v[120:123], v[78:81], v[108:111], v[120:123]
	v_mfma_f32_16x16x32_f16 v[124:127], v[78:81], v[132:135], v[124:127]
	s_waitcnt lgkmcnt(0)
	v_mfma_f32_16x16x32_f16 v[62:65], v[128:131], v[108:111], v[62:65]
	v_mfma_f32_16x16x32_f16 v[38:41], v[128:131], v[132:135], v[38:41]
	v_mfma_f32_16x16x32_f16 v[136:139], v[78:81], v[144:147], v[136:139]
	v_mfma_f32_16x16x32_f16 v[66:69], v[78:81], v[154:157], v[66:69]
	global_load_dwordx4 v[78:81], v[0:1], off offset:1664
	global_load_dwordx4 v[108:111], v[2:3], off offset:1664
	global_load_dwordx4 v[158:161], v[4:5], off offset:1664
	global_load_dwordx4 v[162:165], v[8:9], off offset:1664
	global_load_dwordx4 v[132:135], v[6:7], off offset:1664
	global_load_dwordx4 v[166:169], v[10:11], off offset:1664
	global_load_dwordx4 v[188:191], v[12:13], off offset:1664
	global_load_dwordx4 v[192:195], v[14:15], off offset:1664
	s_waitcnt lgkmcnt(0)
	s_barrier
	v_mfma_f32_16x16x32_f16 v[50:53], v[128:131], v[144:147], v[50:53]
	ds_read_b128 v[112:115], v16
	v_mfma_f32_16x16x32_f16 v[58:61], v[128:131], v[154:157], v[58:61]
	ds_read_b128 v[116:119], v28 offset:32768
	s_waitcnt lgkmcnt(0)
	v_mfma_f32_16x16x32_f16 v[42:45], v[112:115], v[116:119], v[42:45]
	ds_read_b128 v[128:131], v16 offset:2048
	ds_read_b128 v[140:143], v28 offset:34816
	s_waitcnt lgkmcnt(0)
	v_mfma_f32_16x16x32_f16 v[46:49], v[112:115], v[140:143], v[46:49]
	ds_read_b128 v[144:147], v28 offset:36864
	v_mfma_f32_16x16x32_f16 v[54:57], v[128:131], v[116:119], v[54:57]
	ds_read_b128 v[154:157], v28 offset:38912
	v_mfma_f32_16x16x32_f16 v[70:73], v[128:131], v[140:143], v[70:73]
	s_waitcnt lgkmcnt(1)
	v_mfma_f32_16x16x32_f16 v[104:107], v[112:115], v[144:147], v[104:107]
	s_waitcnt lgkmcnt(0)
	v_mfma_f32_16x16x32_f16 v[22:25], v[112:115], v[154:157], v[22:25]
	ds_read_b128 v[112:115], v16 offset:4096
	v_mfma_f32_16x16x32_f16 v[74:77], v[128:131], v[144:147], v[74:77]
	v_mfma_f32_16x16x32_f16 v[34:37], v[128:131], v[154:157], v[34:37]
	ds_read_b128 v[128:131], v16 offset:6144
	s_waitcnt lgkmcnt(1)
	v_mfma_f32_16x16x32_f16 v[120:123], v[112:115], v[116:119], v[120:123]
	v_mfma_f32_16x16x32_f16 v[124:127], v[112:115], v[140:143], v[124:127]
	s_waitcnt lgkmcnt(0)
	v_mfma_f32_16x16x32_f16 v[62:65], v[128:131], v[116:119], v[62:65]
	ds_read_b128 v[116:119], v32 offset:32768
	v_mfma_f32_16x16x32_f16 v[38:41], v[128:131], v[140:143], v[38:41]
	ds_read_b128 v[140:143], v32 offset:34816
	s_waitcnt vmcnt(7)
; #define GL_LOAD(s_, kt_) if (VAR != 1) { a##s_##0 = GL_A(0, kt_); a##s_##1 = GL_A(1, kt_); a##s_##2 = GL_A(2, kt_); a##s_##3 = GL_A(3, kt_); b##s_##0 = GL_B(0, kt_); b##s_##1 = GL_B(1, kt_); b##s_##2 = GL_B(2, kt_); b##s_##3 = GL_B(3, kt_); }
; #define LDS_STORE(s_, buf_) if (VAR != 2) { LDS_ST1(sA, 0, buf_, a##s_##0) LDS_ST1(sA, 1, buf_, a##s_##1) LDS_ST1(sA, 2, buf_, a##s_##2) LDS_ST1(sA, 3, buf_, a##s_##3) LDS_ST1(sB, 0, buf_, b##s_##0) LDS_ST1(sB, 1, buf_, b##s_##1) LDS_ST1(sB, 2, buf_, b##s_##2) LDS_ST1(sB, 3, buf_, b##s_##3) }
;     ...
;   for (int kt = 0; kt < nk; kt += 2) {
;     if (kt + 2 < nk) { GL_LOAD(0, kt + 2) }
;     MMA_TILE(0)
;     LDS_STORE(1, 1)
;     if (VAR != 4) __syncthreads();
;     if (kt + 3 < nk) { GL_LOAD(1, kt + 3) }
;     MMA_TILE(1)
;     if (kt + 2 < nk) { LDS_STORE(0, 0) }
;     if (VAR != 4) __syncthreads();
	ds_write_b128 v18, v[78:81] offset:16384
	v_mfma_f32_16x16x32_f16 v[136:139], v[112:115], v[144:147], v[136:139]
	s_waitcnt vmcnt(6)
	ds_write_b128 v19, v[108:111] offset:16384
	s_waitcnt vmcnt(5)
	ds_write_b128 v20, v[158:161] offset:16384
	v_mfma_f32_16x16x32_f16 v[66:69], v[112:115], v[154:157], v[66:69]
	ds_read_b128 v[112:115], v29
	s_waitcnt vmcnt(4)
	ds_write_b128 v17, v[162:165] offset:16384
	v_mfma_f32_16x16x32_f16 v[50:53], v[128:131], v[144:147], v[50:53]
	ds_read_b128 v[144:147], v32 offset:36864
	v_mfma_f32_16x16x32_f16 v[58:61], v[128:131], v[154:157], v[58:61]
	ds_read_b128 v[128:131], v29 offset:2048
	s_waitcnt lgkmcnt(3)
	v_mfma_f32_16x16x32_f16 v[42:45], v[112:115], v[116:119], v[42:45]
	ds_read_b128 v[154:157], v32 offset:38912
	v_mfma_f32_16x16x32_f16 v[46:49], v[112:115], v[140:143], v[46:49]
	s_waitcnt vmcnt(3)
	ds_write_b128 v18, v[132:135] offset:49152
	s_waitcnt lgkmcnt(2)
	v_mfma_f32_16x16x32_f16 v[54:57], v[128:131], v[116:119], v[54:57]
	s_waitcnt vmcnt(2)
	ds_write_b128 v19, v[166:169] offset:49152
	v_mfma_f32_16x16x32_f16 v[70:73], v[128:131], v[140:143], v[70:73]
	s_waitcnt vmcnt(1)
	ds_write_b128 v20, v[188:191] offset:49152
	v_mfma_f32_16x16x32_f16 v[104:107], v[112:115], v[144:147], v[104:107]
	s_waitcnt vmcnt(0)
	ds_write_b128 v17, v[192:195] offset:49152
	s_waitcnt lgkmcnt(4)
	v_mfma_f32_16x16x32_f16 v[22:25], v[112:115], v[154:157], v[22:25]
	ds_read_b128 v[112:115], v29 offset:4096
	v_mfma_f32_16x16x32_f16 v[74:77], v[128:131], v[144:147], v[74:77]
	v_mfma_f32_16x16x32_f16 v[34:37], v[128:131], v[154:157], v[34:37]
	ds_read_b128 v[128:131], v29 offset:6144
	s_waitcnt lgkmcnt(1)
	v_mfma_f32_16x16x32_f16 v[120:123], v[112:115], v[116:119], v[120:123]
	v_mfma_f32_16x16x32_f16 v[124:127], v[112:115], v[140:143], v[124:127]
	s_waitcnt lgkmcnt(0)
	v_mfma_f32_16x16x32_f16 v[62:65], v[128:131], v[116:119], v[62:65]
	v_mfma_f32_16x16x32_f16 v[38:41], v[128:131], v[140:143], v[38:41]
	v_mfma_f32_16x16x32_f16 v[136:139], v[112:115], v[144:147], v[136:139]
	v_mfma_f32_16x16x32_f16 v[66:69], v[112:115], v[154:157], v[66:69]
	global_load_dwordx4 v[112:115], v[0:1], off offset:1792
	global_load_dwordx4 v[116:119], v[2:3], off offset:1792
	global_load_dwordx4 v[196:199], v[4:5], off offset:1792
	global_load_dwordx4 v[200:203], v[8:9], off offset:1792
	global_load_dwordx4 v[140:143], v[6:7], off offset:1792
	global_load_dwordx4 v[204:207], v[10:11], off offset:1792
	global_load_dwordx4 v[208:211], v[12:13], off offset:1792
	global_load_dwordx4 v[212:215], v[14:15], off offset:1792
	s_waitcnt lgkmcnt(0)
	s_barrier
	v_mfma_f32_16x16x32_f16 v[50:53], v[128:131], v[144:147], v[50:53]
	ds_read_b128 v[78:81], v16 offset:16384
	v_mfma_f32_16x16x32_f16 v[58:61], v[128:131], v[154:157], v[58:61]
	ds_read_b128 v[108:111], v28 offset:49152
	s_waitcnt lgkmcnt(0)
	v_mfma_f32_16x16x32_f16 v[42:45], v[78:81], v[108:111], v[42:45]
	ds_read_b128 v[128:131], v16 offset:18432
	ds_read_b128 v[132:135], v28 offset:51200
	s_waitcnt lgkmcnt(0)
	v_mfma_f32_16x16x32_f16 v[46:49], v[78:81], v[132:135], v[46:49]
	ds_read_b128 v[144:147], v28 offset:53248
	v_mfma_f32_16x16x32_f16 v[54:57], v[128:131], v[108:111], v[54:57]
	ds_read_b128 v[154:157], v28 offset:55296
	v_mfma_f32_16x16x32_f16 v[70:73], v[128:131], v[132:135], v[70:73]
	s_waitcnt lgkmcnt(1)
	v_mfma_f32_16x16x32_f16 v[104:107], v[78:81], v[144:147], v[104:107]
	s_waitcnt lgkmcnt(0)
	v_mfma_f32_16x16x32_f16 v[22:25], v[78:81], v[154:157], v[22:25]
	ds_read_b128 v[78:81], v16 offset:20480
	v_mfma_f32_16x16x32_f16 v[74:77], v[128:131], v[144:147], v[74:77]
	v_mfma_f32_16x16x32_f16 v[34:37], v[128:131], v[154:157], v[34:37]
	ds_read_b128 v[128:131], v16 offset:22528
	s_waitcnt lgkmcnt(1)
	v_mfma_f32_16x16x32_f16 v[120:123], v[78:81], v[108:111], v[120:123]
	v_mfma_f32_16x16x32_f16 v[124:127], v[78:81], v[132:135], v[124:127]
	s_waitcnt lgkmcnt(0)
	v_mfma_f32_16x16x32_f16 v[62:65], v[128:131], v[108:111], v[62:65]
	ds_read_b128 v[108:111], v32 offset:49152
	v_mfma_f32_16x16x32_f16 v[38:41], v[128:131], v[132:135], v[38:41]
	ds_read_b128 v[132:135], v32 offset:51200
	s_waitcnt vmcnt(7)
	ds_write_b128 v18, v[112:115]
	v_mfma_f32_16x16x32_f16 v[136:139], v[78:81], v[144:147], v[136:139]
	s_waitcnt vmcnt(6)
	ds_write_b128 v19, v[116:119]
	s_waitcnt vmcnt(5)
	ds_write_b128 v20, v[196:199]
	v_mfma_f32_16x16x32_f16 v[66:69], v[78:81], v[154:157], v[66:69]
	ds_read_b128 v[78:81], v29 offset:16384
	s_waitcnt vmcnt(4)
	ds_write_b128 v17, v[200:203]
	v_mfma_f32_16x16x32_f16 v[50:53], v[128:131], v[144:147], v[50:53]
	ds_read_b128 v[144:147], v32 offset:53248
	v_mfma_f32_16x16x32_f16 v[58:61], v[128:131], v[154:157], v[58:61]
	ds_read_b128 v[128:131], v29 offset:18432
	s_waitcnt lgkmcnt(3)
	v_mfma_f32_16x16x32_f16 v[42:45], v[78:81], v[108:111], v[42:45]
	ds_read_b128 v[154:157], v32 offset:55296
	v_mfma_f32_16x16x32_f16 v[46:49], v[78:81], v[132:135], v[46:49]
	s_waitcnt vmcnt(3)
	ds_write_b128 v18, v[140:143] offset:32768
	s_waitcnt lgkmcnt(2)
	v_mfma_f32_16x16x32_f16 v[54:57], v[128:131], v[108:111], v[54:57]
	s_waitcnt vmcnt(2)
	ds_write_b128 v19, v[204:207] offset:32768
	v_mfma_f32_16x16x32_f16 v[70:73], v[128:131], v[132:135], v[70:73]
	s_waitcnt vmcnt(1)
	ds_write_b128 v20, v[208:211] offset:32768
	v_mfma_f32_16x16x32_f16 v[104:107], v[78:81], v[144:147], v[104:107]
	s_waitcnt vmcnt(0)
	ds_write_b128 v17, v[212:215] offset:32768
	s_waitcnt lgkmcnt(4)
	v_mfma_f32_16x16x32_f16 v[22:25], v[78:81], v[154:157], v[22:25]
	ds_read_b128 v[78:81], v29 offset:20480
	v_mfma_f32_16x16x32_f16 v[74:77], v[128:131], v[144:147], v[74:77]
	v_mfma_f32_16x16x32_f16 v[34:37], v[128:131], v[154:157], v[34:37]
	ds_read_b128 v[128:131], v29 offset:22528
	s_waitcnt lgkmcnt(1)
	v_mfma_f32_16x16x32_f16 v[120:123], v[78:81], v[108:111], v[120:123]
	v_mfma_f32_16x16x32_f16 v[124:127], v[78:81], v[132:135], v[124:127]
	s_waitcnt lgkmcnt(0)
	v_mfma_f32_16x16x32_f16 v[62:65], v[128:131], v[108:111], v[62:65]
	v_mfma_f32_16x16x32_f16 v[38:41], v[128:131], v[132:135], v[38:41]
	v_mfma_f32_16x16x32_f16 v[136:139], v[78:81], v[144:147], v[136:139]
	v_mfma_f32_16x16x32_f16 v[66:69], v[78:81], v[154:157], v[66:69]
	global_load_dwordx4 v[80:83], v[0:1], off offset:1920
	global_load_dwordx4 v[108:111], v[2:3], off offset:1920
	global_load_dwordx4 v[158:161], v[4:5], off offset:1920
	global_load_dwordx4 v[162:165], v[8:9], off offset:1920
	global_load_dwordx4 v[132:135], v[6:7], off offset:1920
	global_load_dwordx4 v[166:169], v[10:11], off offset:1920
	global_load_dwordx4 v[188:191], v[12:13], off offset:1920
	global_load_dwordx4 v[12:15], v[14:15], off offset:1920
	s_waitcnt lgkmcnt(0)
	s_barrier
; DI unsigned pack2(float lo, float hi) { f2_t v = {lo, hi}; h2_t b = __builtin_convertvector(v, h2_t); return __builtin_bit_cast(unsigned, b); }
; #define GL_LOAD(s_, kt_) if (VAR != 1) { a##s_##0 = GL_A(0, kt_); a##s_##1 = GL_A(1, kt_); a##s_##2 = GL_A(2, kt_); a##s_##3 = GL_A(3, kt_); b##s_##0 = GL_B(0, kt_); b##s_##1 = GL_B(1, kt_); b##s_##2 = GL_B(2, kt_); b##s_##3 = GL_B(3, kt_); }
; #define LDS_STORE(s_, buf_) if (VAR != 2) { LDS_ST1(sA, 0, buf_, a##s_##0) LDS_ST1(sA, 1, buf_, a##s_##1) LDS_ST1(sA, 2, buf_, a##s_##2) LDS_ST1(sA, 3, buf_, a##s_##3) LDS_ST1(sB, 0, buf_, b##s_##0) LDS_ST1(sB, 1, buf_, b##s_##1) LDS_ST1(sB, 2, buf_, b##s_##2) LDS_ST1(sB, 3, buf_, b##s_##3) }
;     ...
;     MMA_TILE(0)
;     LDS_STORE(1, 1)
;     if (VAR != 4) __syncthreads();
;     if (kt + 3 < nk) { GL_LOAD(1, kt + 3) }
;     MMA_TILE(1)
;     if (kt + 2 < nk) { LDS_STORE(0, 0) }
;     if (VAR != 4) __syncthreads();
; DI void phase_proj(const Params& P, int l, char* smem) {
;     ...
;       const int cb = col0 - PW;
;       const int br = cb >> 9, c0 = cb & 511;
;       const int b = row0 >> 12, s0 = row0 & 4095;
; #pragma unroll
;       for (int mt = 0; mt < 4; ++mt) {
;         float r4[4];
; #pragma unroll
;         for (int j = 0; j < 4; ++j) r4[j] = __shfl(rs[mt], 4 * g + j);
; #pragma unroll
;         for (int nt = 0; nt < 4; ++nt) {
;           const int c = c0 + nt * 16 + lr;
;           bf16_t* dst = VT + ((size_t)(br * NB + b) * 512 + c) * SEQ + s0 + mt * 16 + 4 * g;
;           *(uint2*)dst = make_uint2(pack2(acc[mt][nt][0] * r4[0], acc[mt][nt][1] * r4[1]), pack2(acc[mt][nt][2] * r4[2], acc[mt][nt][3] * r4[3]));
;         }
;       }
	ds_read_b128 v[0:3], v16
	v_mfma_f32_16x16x32_f16 v[50:53], v[128:131], v[144:147], v[50:53]
	v_mfma_f32_16x16x32_f16 v[112:115], v[128:131], v[154:157], v[58:61]
	ds_read_b128 v[116:119], v28 offset:32768
	ds_read_b128 v[4:7], v16 offset:2048
	ds_read_b128 v[128:131], v28 offset:34816
	s_waitcnt lgkmcnt(2)
	v_mfma_f32_16x16x32_f16 v[140:143], v[0:3], v[116:119], v[42:45]
	s_waitcnt lgkmcnt(0)
	v_mfma_f32_16x16x32_f16 v[144:147], v[0:3], v[128:131], v[46:49]
	s_nop 0
	ds_read_b128 v[42:45], v28 offset:36864
	s_nop 0
	ds_read_b128 v[46:49], v28 offset:38912
	s_waitcnt lgkmcnt(0)
	v_mfma_f32_16x16x32_f16 v[154:157], v[0:3], v[46:49], v[22:25]
	v_mfma_f32_16x16x32_f16 v[204:207], v[4:7], v[46:49], v[34:37]
	s_nop 1
	ds_read_b128 v[22:25], v16 offset:4096
	ds_read_b128 v[34:37], v16 offset:6144
	ds_read_b128 v[208:211], v29
	ds_read_b128 v[212:215], v29 offset:2048
	v_mfma_f32_16x16x32_f16 v[104:107], v[0:3], v[42:45], v[104:107]
	v_mfma_f32_16x16x32_f16 v[192:195], v[4:7], v[116:119], v[54:57]
	v_mfma_f32_16x16x32_f16 v[200:203], v[4:7], v[42:45], v[74:77]
	s_nop 2
	ds_read_b128 v[76:79], v32 offset:32768
	ds_read_b128 v[56:59], v32 offset:34816
	ds_read_b128 v[220:223], v29 offset:4096
	ds_read_b128 v[0:3], v29 offset:6144
	v_mfma_f32_16x16x32_f16 v[196:199], v[4:7], v[128:131], v[70:73]
	ds_read_b128 v[8:11], v32 offset:36864
	ds_read_b128 v[4:7], v32 offset:38912
	s_waitcnt vmcnt(7)
	ds_write_b128 v18, v[80:83] offset:16384
	s_waitcnt lgkmcnt(10)
	v_mfma_f32_16x16x32_f16 v[120:123], v[22:25], v[116:119], v[120:123]
	s_waitcnt vmcnt(6)
	ds_write_b128 v19, v[108:111] offset:16384
	s_waitcnt vmcnt(5)
	ds_write_b128 v20, v[158:161] offset:16384
	s_waitcnt vmcnt(4)
	ds_write_b128 v17, v[162:165] offset:16384
	s_waitcnt vmcnt(3)
	ds_write_b128 v18, v[132:135] offset:49152
	s_waitcnt vmcnt(2)
	ds_write_b128 v19, v[166:169] offset:49152
	s_waitcnt vmcnt(1)
	ds_write_b128 v20, v[188:191] offset:49152
	v_mfma_f32_16x16x32_f16 v[136:139], v[22:25], v[42:45], v[136:139]
	s_waitcnt vmcnt(0)
	ds_write_b128 v17, v[12:15] offset:49152
	s_waitcnt lgkmcnt(0)
	s_barrier
	v_mfma_f32_16x16x32_f16 v[224:227], v[22:25], v[46:49], v[66:69]
	v_and_or_b32 v188, v94, s1, v97
	v_ashrrev_i32_e32 v94, 7, v94
	v_mfma_f32_16x16x32_f16 v[108:111], v[34:37], v[116:119], v[62:65]
	ds_read_b128 v[116:119], v16 offset:16384
	ds_read_b128 v[80:83], v16 offset:18432
	v_and_b32_e32 v94, -4, v94
	v_add_u32_e32 v94, v94, v95
	v_mfma_f32_16x16x32_f16 v[72:75], v[34:37], v[128:131], v[38:41]
	v_ashrrev_i32_e32 v95, 31, v94
	v_lshlrev_b64 v[170:171], 21, v[94:95]
	v_lshl_add_u64 v[94:95], v[92:93], 0, v[150:151]
	v_mfma_f32_16x16x32_f16 v[40:43], v[34:37], v[42:45], v[50:53]
	v_lshlrev_b32_e32 v150, 2, v103
	v_lshl_or_b32 v170, v188, 12, v170
	ds_bpermute_b32 v188, v150, v98
	v_mfma_f32_16x16x32_f16 v[44:47], v[34:37], v[46:49], v[112:115]
	ds_bpermute_b32 v189, v150, v98 offset:4
	ds_bpermute_b32 v190, v150, v98 offset:8
	v_mfma_f32_16x16x32_f16 v[112:115], v[208:211], v[76:79], v[140:143]
	v_mfma_f32_16x16x32_f16 v[124:127], v[22:25], v[128:131], v[124:127]
	ds_read_b128 v[36:39], v28 offset:49152
	ds_read_b128 v[24:27], v28 offset:51200
	ds_read_b128 v[64:67], v16 offset:20480
	ds_read_b128 v[12:15], v16 offset:22528
	ds_read_b128 v[20:23], v28 offset:53248
	ds_read_b128 v[16:19], v28 offset:55296
	ds_read_b128 v[128:131], v29 offset:16384
	ds_read_b128 v[132:135], v29 offset:18432
	ds_read_b128 v[60:63], v32 offset:49152
	ds_read_b128 v[52:55], v32 offset:51200
	ds_read_b128 v[68:71], v29 offset:20480
	ds_read_b128 v[28:31], v29 offset:22528
	s_waitcnt lgkmcnt(11)
	v_mfma_f32_16x16x32_f16 v[112:115], v[116:119], v[36:39], v[112:115]
	ds_read_b128 v[48:51], v32 offset:53248
	ds_read_b128 v[32:35], v32 offset:55296
	s_waitcnt lgkmcnt(0)
	s_barrier
	s_setprio 0
	v_mfma_f32_16x16x32_f16 v[140:143], v[208:211], v[56:59], v[144:147]
	v_mfma_f32_16x16x32_f16 v[144:147], v[208:211], v[4:7], v[154:157]
	v_mfma_f32_16x16x32_f16 v[154:157], v[212:215], v[76:79], v[192:195]
	s_nop 2
	v_or_b32_e32 v194, 12, v150
	ds_bpermute_b32 v191, v194, v98
	v_mfma_f32_16x16x32_f16 v[112:115], v[128:131], v[60:63], v[112:115]
	v_lshl_add_u64 v[98:99], v[170:171], 1, v[94:95]
	v_mfma_f32_16x16x32_f16 v[104:107], v[208:211], v[8:11], v[104:107]
	v_mfma_f32_16x16x32_f16 v[104:107], v[116:119], v[20:23], v[104:107]
	s_nop 4
	v_mul_f32_e64 v112, v112, v188
	v_mul_f32_e64 v113, v113, v189
	s_waitcnt lgkmcnt(0)
	v_pk_mul_f32 v[114:115], v[114:115], v[190:191]
	v_cvt_pk_f16_f32 v112, v112, v113
	v_cvt_pk_f16_f32 v113, v114, v115
	global_store_dwordx2 v[98:99], v[112:113], off
	v_mfma_f32_16x16x32_f16 v[112:115], v[116:119], v[24:27], v[140:143]
	v_mfma_f32_16x16x32_f16 v[112:115], v[128:131], v[52:55], v[112:115]
	s_nop 1
	v_or_b32_e32 v140, 0x10000, v170
	v_mov_b32_e32 v141, v171
	v_lshlrev_b64 v[140:141], 1, v[140:141]
	v_mfma_f32_16x16x32_f16 v[104:107], v[128:131], v[48:51], v[104:107]
	v_lshl_add_u64 v[142:143], v[94:95], 0, v[140:141]
	s_nop 0
	v_pk_mul_f32 v[112:113], v[112:113], v[188:189]
	v_pk_mul_f32 v[114:115], v[114:115], v[190:191]
	v_cvt_pk_f16_f32 v112, v112, v113
	v_cvt_pk_f16_f32 v113, v114, v115
	global_store_dwordx2 v[142:143], v[112:113], off
	v_or_b32_e32 v112, 0x20000, v170
	v_mov_b32_e32 v113, v171
	v_lshlrev_b64 v[142:143], 1, v[112:113]
	v_pk_mul_f32 v[104:105], v[104:105], v[188:189]
	v_pk_mul_f32 v[106:107], v[106:107], v[190:191]
	v_lshl_add_u64 v[192:193], v[94:95], 0, v[142:143]
	v_cvt_pk_f16_f32 v104, v104, v105
	v_cvt_pk_f16_f32 v105, v106, v107
	global_store_dwordx2 v[192:193], v[104:105], off
	v_mfma_f32_16x16x32_f16 v[104:107], v[116:119], v[16:19], v[144:147]
	v_or_b32_e32 v170, 0x30000, v170
	v_lshlrev_b64 v[116:117], 1, v[170:171]
	v_lshl_add_u64 v[118:119], v[94:95], 0, v[116:117]
	v_mfma_f32_16x16x32_f16 v[104:107], v[128:131], v[32:35], v[104:107]
	ds_bpermute_b32 v128, v150, v96 offset:8
	ds_bpermute_b32 v129, v194, v96
	v_lshl_add_u64 v[130:131], v[94:95], 0, 32
	v_mfma_f32_16x16x32_f16 v[158:161], v[212:215], v[56:59], v[196:199]
	v_lshl_add_u64 v[144:145], v[130:131], 0, v[140:141]
	s_nop 2
	v_pk_mul_f32 v[104:105], v[104:105], v[188:189]
	v_pk_mul_f32 v[106:107], v[106:107], v[190:191]
	v_cvt_pk_f16_f32 v104, v104, v105
	v_cvt_pk_f16_f32 v105, v106, v107
	global_store_dwordx2 v[118:119], v[104:105], off
	v_mfma_f32_16x16x32_f16 v[104:107], v[80:83], v[36:39], v[154:157]
	ds_bpermute_b32 v118, v150, v96
	ds_bpermute_b32 v119, v150, v96 offset:4
	v_mfma_f32_16x16x32_f16 v[104:107], v[132:135], v[60:63], v[104:107]
	v_mfma_f32_16x16x32_f16 v[120:123], v[220:223], v[76:79], v[120:123]
	v_mfma_f32_16x16x32_f16 v[76:79], v[0:3], v[76:79], v[108:111]
	s_waitcnt lgkmcnt(0)
; DI unsigned pack2(float lo, float hi) { f2_t v = {lo, hi}; h2_t b = __builtin_convertvector(v, h2_t); return __builtin_bit_cast(unsigned, b); }
; DI void phase_proj(const Params& P, int l, char* smem) {
;     ...
; #pragma unroll
;       for (int mt = 0; mt < 4; ++mt) {
;         float r4[4];
; #pragma unroll
;         for (int j = 0; j < 4; ++j) r4[j] = __shfl(rs[mt], 4 * g + j);
; #pragma unroll
;         for (int nt = 0; nt < 4; ++nt) {
;           const int c = c0 + nt * 16 + lr;
;           bf16_t* dst = VT + ((size_t)(br * NB + b) * 512 + c) * SEQ + s0 + mt * 16 + 4 * g;
;           *(uint2*)dst = make_uint2(pack2(acc[mt][nt][0] * r4[0], acc[mt][nt][1] * r4[1]), pack2(acc[mt][nt][2] * r4[2], acc[mt][nt][3] * r4[3]));
;         }
;       }
	s_nop 4
	v_pk_mul_f32 v[104:105], v[104:105], v[118:119]
	v_pk_mul_f32 v[106:107], v[106:107], v[128:129]
	v_cvt_pk_f16_f32 v104, v104, v105
	v_mfma_f32_16x16x32_f16 v[108:111], v[80:83], v[24:27], v[158:161]
	v_cvt_pk_f16_f32 v105, v106, v107
	global_store_dwordx2 v[98:99], v[104:105], off offset:32
	v_mfma_f32_16x16x32_f16 v[162:165], v[212:215], v[8:11], v[200:203]
	v_mfma_f32_16x16x32_f16 v[166:169], v[212:215], v[4:7], v[204:207]
	v_mfma_f32_16x16x32_f16 v[104:107], v[132:135], v[52:55], v[108:111]
	v_mfma_f32_16x16x32_f16 v[108:111], v[80:83], v[20:23], v[162:165]
	v_mfma_f32_16x16x32_f16 v[80:83], v[80:83], v[16:19], v[166:169]
	s_nop 5
	v_mul_f32_e64 v104, v104, v118
	v_mul_f32_e64 v105, v105, v119
	v_pk_mul_f32 v[106:107], v[106:107], v[128:129]
	v_cvt_pk_f16_f32 v104, v104, v105
	v_cvt_pk_f16_f32 v105, v106, v107
	v_mfma_f32_16x16x32_f16 v[80:83], v[132:135], v[32:35], v[80:83]
	global_store_dwordx2 v[144:145], v[104:105], off
	v_mfma_f32_16x16x32_f16 v[104:107], v[132:135], v[48:51], v[108:111]
	v_mfma_f32_16x16x32_f16 v[124:127], v[220:223], v[56:59], v[124:127]
	s_nop 4
	v_mul_f32_e64 v80, v80, v118
	v_mul_f32_e64 v81, v81, v119
	v_pk_mul_f32 v[104:105], v[104:105], v[118:119]
	v_pk_mul_f32 v[106:107], v[106:107], v[128:129]
	v_mfma_f32_16x16x32_f16 v[56:59], v[0:3], v[56:59], v[72:75]
	v_cvt_pk_f16_f32 v80, v80, v81
	v_lshl_add_u64 v[108:109], v[130:131], 0, v[142:143]
	v_cvt_pk_f16_f32 v104, v104, v105
	v_pk_mul_f32 v[72:73], v[82:83], v[128:129]
	v_cvt_pk_f16_f32 v105, v106, v107
	v_cvt_pk_f16_f32 v81, v72, v73
	v_mfma_f32_16x16x32_f16 v[72:75], v[64:67], v[36:39], v[120:123]
	global_store_dwordx2 v[108:109], v[104:105], off
	v_lshl_add_u64 v[104:105], v[130:131], 0, v[116:117]
	global_store_dwordx2 v[104:105], v[80:81], off
	ds_bpermute_b32 v104, v150, v102
	ds_bpermute_b32 v105, v150, v102 offset:4
	ds_bpermute_b32 v106, v150, v102 offset:8
	v_mfma_f32_16x16x32_f16 v[72:75], v[68:71], v[60:63], v[72:75]
	ds_bpermute_b32 v107, v194, v102
	v_lshl_add_u64 v[102:103], v[94:95], 0, 64
	v_mfma_f32_16x16x32_f16 v[80:83], v[64:67], v[24:27], v[124:127]
	v_mfma_f32_16x16x32_f16 v[136:139], v[220:223], v[8:11], v[136:139]
	s_waitcnt lgkmcnt(2)
	s_nop 2
	v_pk_mul_f32 v[72:73], v[72:73], v[104:105]
	s_nop 0
	v_cvt_pk_f16_f32 v108, v72, v73
	v_mfma_f32_16x16x32_f16 v[112:115], v[220:223], v[4:7], v[224:227]
	s_waitcnt lgkmcnt(0)
	v_pk_mul_f32 v[72:73], v[74:75], v[106:107]
	s_nop 0
	v_cvt_pk_f16_f32 v109, v72, v73
	v_mfma_f32_16x16x32_f16 v[72:75], v[68:71], v[52:55], v[80:83]
	global_store_dwordx2 v[98:99], v[108:109], off offset:64
	v_lshl_add_u64 v[108:109], v[102:103], 0, v[140:141]
	v_mfma_f32_16x16x32_f16 v[80:83], v[64:67], v[20:23], v[136:139]
	v_mfma_f32_16x16x32_f16 v[64:67], v[64:67], v[16:19], v[112:115]
	s_nop 3
	v_mul_f32_e64 v72, v72, v104
	v_mul_f32_e64 v73, v73, v105
	v_cvt_pk_f16_f32 v110, v72, v73
	v_pk_mul_f32 v[72:73], v[74:75], v[106:107]
	v_mfma_f32_16x16x32_f16 v[64:67], v[68:71], v[32:35], v[64:67]
	v_cvt_pk_f16_f32 v111, v72, v73
	global_store_dwordx2 v[108:109], v[110:111], off
	v_mfma_f32_16x16x32_f16 v[72:75], v[68:71], v[48:51], v[80:83]
	v_lshl_add_u64 v[68:69], v[102:103], 0, v[116:117]
	s_nop 3
	v_pk_mul_f32 v[64:65], v[64:65], v[104:105]
	v_mfma_f32_16x16x32_f16 v[8:11], v[0:3], v[8:11], v[40:43]
	v_lshl_add_u64 v[80:81], v[102:103], 0, v[142:143]
	v_pk_mul_f32 v[72:73], v[72:73], v[104:105]
	v_pk_mul_f32 v[74:75], v[74:75], v[106:107]
	v_mfma_f32_16x16x32_f16 v[0:3], v[0:3], v[4:7], v[44:47]
	v_mul_f32_e64 v42, v66, v106
	v_mul_f32_e64 v43, v67, v107
	v_cvt_pk_f16_f32 v72, v72, v73
	v_cvt_pk_f16_f32 v73, v74, v75
	v_mfma_f32_16x16x32_f16 v[4:7], v[12:15], v[36:39], v[76:79]
	v_cvt_pk_f16_f32 v40, v64, v65
	v_cvt_pk_f16_f32 v41, v42, v43
	global_store_dwordx2 v[80:81], v[72:73], off
	global_store_dwordx2 v[68:69], v[40:41], off
	ds_bpermute_b32 v40, v150, v100
	ds_bpermute_b32 v41, v150, v100 offset:4
	ds_bpermute_b32 v36, v150, v100 offset:8
	ds_bpermute_b32 v37, v194, v100
	v_mfma_f32_16x16x32_f16 v[4:7], v[28:31], v[60:63], v[4:7]
	v_lshl_add_u64 v[38:39], v[94:95], 0, s[4:5]
	v_mfma_f32_16x16x32_f16 v[0:3], v[12:15], v[16:19], v[0:3]
	v_mfma_f32_16x16x32_f16 v[0:3], v[28:31], v[32:35], v[0:3]
	s_waitcnt lgkmcnt(2)
	s_nop 3
	v_pk_mul_f32 v[4:5], v[4:5], v[40:41]
	s_waitcnt lgkmcnt(0)
	v_pk_mul_f32 v[44:45], v[6:7], v[36:37]
	v_cvt_pk_f16_f32 v42, v4, v5
	v_mfma_f32_16x16x32_f16 v[4:7], v[12:15], v[24:27], v[56:59]
	v_cvt_pk_f16_f32 v43, v44, v45
	global_store_dwordx2 v[98:99], v[42:43], off offset:96
	v_lshl_add_u64 v[24:25], v[38:39], 0, v[140:141]
	v_mfma_f32_16x16x32_f16 v[4:7], v[28:31], v[52:55], v[4:7]
	v_mul_f32_e64 v0, v0, v40
	v_mul_f32_e64 v1, v1, v41
	v_pk_mul_f32 v[2:3], v[2:3], v[36:37]
	v_cvt_pk_f16_f32 v0, v0, v1
	v_cvt_pk_f16_f32 v1, v2, v3
	s_nop 2
	v_pk_mul_f32 v[4:5], v[4:5], v[40:41]
	v_pk_mul_f32 v[42:43], v[6:7], v[36:37]
	v_cvt_pk_f16_f32 v26, v4, v5
	v_mfma_f32_16x16x32_f16 v[4:7], v[12:15], v[20:23], v[8:11]
	v_cvt_pk_f16_f32 v27, v42, v43
	global_store_dwordx2 v[24:25], v[26:27], off
	v_mfma_f32_16x16x32_f16 v[4:7], v[28:31], v[48:51], v[4:7]
	v_lshl_add_u64 v[8:9], v[38:39], 0, v[142:143]
	s_nop 6
	v_pk_mul_f32 v[4:5], v[4:5], v[40:41]
	v_pk_mul_f32 v[6:7], v[6:7], v[36:37]
	v_cvt_pk_f16_f32 v4, v4, v5
	v_cvt_pk_f16_f32 v5, v6, v7
	global_store_dwordx2 v[8:9], v[4:5], off
	v_lshl_add_u64 v[4:5], v[38:39], 0, v[116:117]
	global_store_dwordx2 v[4:5], v[0:1], off
	s_branch .LBB0_636

; #define GL_LOAD(s_, kt_) if (VAR != 1) { a##s_##0 = GL_A(0, kt_); a##s_##1 = GL_A(1, kt_); a##s_##2 = GL_A(2, kt_); a##s_##3 = GL_A(3, kt_); b##s_##0 = GL_B(0, kt_); b##s_##1 = GL_B(1, kt_); b##s_##2 = GL_B(2, kt_); b##s_##3 = GL_B(3, kt_); }
; #define LDS_STORE(s_, buf_) if (VAR != 2) { LDS_ST1(sA, 0, buf_, a##s_##0) LDS_ST1(sA, 1, buf_, a##s_##1) LDS_ST1(sA, 2, buf_, a##s_##2) LDS_ST1(sA, 3, buf_, a##s_##3) LDS_ST1(sB, 0, buf_, b##s_##0) LDS_ST1(sB, 1, buf_, b##s_##1) LDS_ST1(sB, 2, buf_, b##s_##2) LDS_ST1(sB, 3, buf_, b##s_##3) }
;     ...
;   GL_LOAD(0, 0)
;   GL_LOAD(1, 1)
;   LDS_STORE(0, 0)
;   if (VAR != 4) __syncthreads();
; #pragma unroll
;   for (int kt = 0; kt < nk; kt += 2) {
;     if (kt + 2 < nk) { GL_LOAD(0, kt + 2) }
;     MMA_TILE(0)
;     LDS_STORE(1, 1)
;     if (VAR != 4) __syncthreads();
;     if (kt + 3 < nk) { GL_LOAD(1, kt + 3) }
;     MMA_TILE(1)
; DI void phase_merge(const Params& P, int l, char* smem) {
;     ...
;     for (int br = 0; br < 3; ++br) {
;       f32x4 acc[4][4]; zero_acc(acc);
;       const int ycol = br == 0 ? C_AQ : (br == 1 ? C_BQ : C_CQ);
;       const bf16_t* Wb = W + (br == 0 ? WO_BRA : (br == 1 ? WO_BRB : WO_BRC));
;       gemm_kloop<false, true, 8>(acc, Pb + (size_t)m0 * PW + ycol, PW, Wb + (size_t)n0 * 512, 512, smem);
.LBB0_1161:
	s_cmp_lg_u32 s4, 0
	s_cselect_b64 s[6:7], -1, 0
	s_cmpk_eq_i32 s4, 0x800
	s_mov_b32 s8, 0x860000
	s_cselect_b32 s17, 0x400, s36
	s_cselect_b32 s20, s8, 0x8e0000
	s_cmp_eq_u32 s4, 0
	s_cselect_b64 s[8:9], -1, 0
	s_and_b64 s[18:19], s[8:9], exec
	s_cselect_b32 s17, 0, s17
	s_cselect_b32 s20, 0x7e0000, s20
	s_lshl_b32 s17, s17, 1
	s_add_u32 s18, s13, s17
	s_addc_u32 s19, s14, 0
	v_mov_b32_e32 v56, v148
	v_mov_b64_e32 v[6:7], s[18:19]
	v_ashrrev_i32_e32 v16, 3, v56
	v_lshlrev_b32_e32 v57, 4, v56
	v_mad_i64_i32 v[0:1], s[18:19], v16, s0, v[6:7]
	v_and_b32_e32 v150, 0x70, v57
	v_add_u32_e32 v18, 32, v16
	s_lshl_b32 s17, s20, 1
	v_lshl_add_u64 v[0:1], v[0:1], 0, v[150:151]
	v_mad_i64_i32 v[2:3], s[18:19], v18, s0, v[6:7]
	v_add_u32_e32 v52, 64, v16
	s_add_u32 s20, s15, s17
	v_ashrrev_i32_e32 v17, 31, v16
	global_load_dwordx4 v[20:23], v[0:1], off
	v_lshl_add_u64 v[2:3], v[2:3], 0, v[150:151]
	v_mad_i64_i32 v[4:5], s[18:19], v52, s0, v[6:7]
	v_add_u32_e32 v54, 0x60, v16
	s_addc_u32 s21, s16, 0
	v_ashrrev_i32_e32 v19, 31, v18
	global_load_dwordx4 v[24:27], v[2:3], off
	v_lshl_add_u64 v[4:5], v[4:5], 0, v[150:151]
	v_mad_i64_i32 v[6:7], s[18:19], v54, s0, v[6:7]
	v_lshlrev_b64 v[8:9], 10, v[16:17]
	v_ashrrev_i32_e32 v53, 31, v52
	global_load_dwordx4 v[28:31], v[4:5], off
	v_lshl_add_u64 v[6:7], v[6:7], 0, v[150:151]
	v_lshl_add_u64 v[8:9], s[20:21], 0, v[8:9]
	v_lshlrev_b64 v[10:11], 10, v[18:19]
	v_ashrrev_i32_e32 v55, 31, v54
	global_load_dwordx4 v[32:35], v[6:7], off
	v_lshl_add_u64 v[8:9], v[8:9], 0, v[150:151]
	v_lshl_add_u64 v[10:11], s[20:21], 0, v[10:11]
	v_lshlrev_b64 v[12:13], 10, v[52:53]
	global_load_dwordx4 v[36:39], v[8:9], off
	v_lshl_add_u64 v[10:11], v[10:11], 0, v[150:151]
	v_lshl_add_u64 v[12:13], s[20:21], 0, v[12:13]
	v_lshlrev_b64 v[14:15], 10, v[54:55]
	global_load_dwordx4 v[40:43], v[10:11], off
	v_lshl_add_u64 v[12:13], v[12:13], 0, v[150:151]
	v_lshl_add_u64 v[14:15], s[20:21], 0, v[14:15]
	global_load_dwordx4 v[44:47], v[12:13], off
	v_lshl_add_u64 v[14:15], v[14:15], 0, v[150:151]
	global_load_dwordx4 v[48:51], v[14:15], off
	v_lshlrev_b32_e32 v19, 3, v56
	v_and_b32_e32 v108, 48, v56
	v_and_b32_e32 v17, 15, v56
	v_lshrrev_b32_e32 v53, 1, v56
	v_lshlrev_b32_e32 v55, 7, v56
	v_and_b32_e32 v109, 0x70, v19
	v_bitop3_b32 v115, v19, v108, s23 bitop3:0x6c
	v_bitop3_b32 v19, v57, s23, v56 bitop3:0x48
	v_and_or_b32 v136, v53, s24, v17
	v_and_b32_e32 v150, 0x2780, v55
	v_lshl_or_b32 v16, v16, 7, v19
	v_lshl_or_b32 v17, v18, 7, v19
	v_lshl_or_b32 v18, v52, 7, v19
	v_lshl_or_b32 v19, v54, 7, v19
	global_load_dwordx4 v[52:55], v[0:1], off offset:128
	global_load_dwordx4 v[56:59], v[2:3], off offset:128
	global_load_dwordx4 v[104:107], v[4:5], off offset:128
	global_load_dwordx4 v[116:119], v[6:7], off offset:128
	global_load_dwordx4 v[120:123], v[8:9], off offset:128
	global_load_dwordx4 v[124:127], v[10:11], off offset:128
	global_load_dwordx4 v[128:131], v[12:13], off offset:128
	global_load_dwordx4 v[132:135], v[14:15], off offset:128
	s_and_b64 vcc, s[8:9], exec
	s_waitcnt vmcnt(15)
	ds_write_b128 v16, v[20:23]
	s_waitcnt vmcnt(14)
	ds_write_b128 v17, v[24:27]
	s_waitcnt vmcnt(13)
	ds_write_b128 v18, v[28:31]
	s_waitcnt vmcnt(12)
	ds_write_b128 v19, v[32:35]
	s_waitcnt vmcnt(11)
	ds_write_b128 v16, v[36:39] offset:32768
	s_waitcnt vmcnt(10)
	ds_write_b128 v17, v[40:43] offset:32768
	s_waitcnt vmcnt(9)
	ds_write_b128 v18, v[44:47] offset:32768
	s_waitcnt vmcnt(8)
	ds_write_b128 v19, v[48:51] offset:32768
	v_or_b32_e32 v20, v150, v115
	s_waitcnt lgkmcnt(0)
	s_barrier
	s_setprio 1
	ds_read_b128 v[22:25], v20 offset:32768
	v_lshlrev_b32_e32 v50, 7, v136
	v_bitop3_b32 v21, v50, v109, v108 bitop3:0xf6
	ds_read_b128 v[30:33], v21
	s_waitcnt lgkmcnt(0)
	v_mfma_f32_16x16x32_f16 v[38:41], v[22:25], v[30:33], 0
	ds_read_b128 v[26:29], v20 offset:34816
	ds_read_b128 v[34:37], v21 offset:2048
	s_waitcnt lgkmcnt(0)
	v_mfma_f32_16x16x32_f16 v[144:147], v[22:25], v[34:37], 0
	ds_read_b128 v[42:45], v20 offset:36864
	ds_read_b128 v[162:165], v21 offset:4096
	s_waitcnt lgkmcnt(0)
	v_mfma_f32_16x16x32_f16 v[190:193], v[22:25], v[162:165], 0
	ds_read_b128 v[136:139], v20 offset:38912
	ds_read_b128 v[166:169], v21 offset:6144
	s_waitcnt lgkmcnt(0)
	v_mfma_f32_16x16x32_f16 v[202:205], v[22:25], v[166:169], 0
	v_lshl_add_u64 v[108:109], v[80:81], 0, s[4:5]
	v_mfma_f32_16x16x32_f16 v[46:49], v[26:29], v[30:33], 0
	v_xor_b32_e32 v22, 64, v115
	v_mfma_f32_16x16x32_f16 v[140:143], v[42:45], v[30:33], 0
	v_or_b32_e32 v23, v150, v22
	v_mfma_f32_16x16x32_f16 v[30:33], v[136:139], v[30:33], 0
	ds_read_b128 v[206:209], v23 offset:32768
	v_mfma_f32_16x16x32_f16 v[154:157], v[26:29], v[34:37], 0
	ds_read_b128 v[224:227], v23 offset:36864
	v_mfma_f32_16x16x32_f16 v[158:161], v[42:45], v[34:37], 0
	ds_read_b128 v[228:231], v23 offset:38912
	v_mfma_f32_16x16x32_f16 v[34:37], v[136:139], v[34:37], 0
	v_bitop3_b32 v22, v50, v115, 64 bitop3:0xf6
	v_mfma_f32_16x16x32_f16 v[194:197], v[26:29], v[162:165], 0
	ds_read_b128 v[210:213], v22
	v_mfma_f32_16x16x32_f16 v[198:201], v[42:45], v[162:165], 0
	ds_read_b128 v[220:223], v22 offset:2048
	v_mfma_f32_16x16x32_f16 v[162:165], v[136:139], v[162:165], 0
	s_waitcnt vmcnt(7)
	ds_write_b128 v16, v[52:55] offset:16384
	v_mfma_f32_16x16x32_f16 v[24:27], v[26:29], v[166:169], 0
	s_waitcnt vmcnt(6)
	ds_write_b128 v17, v[56:59] offset:16384
	v_mfma_f32_16x16x32_f16 v[42:45], v[42:45], v[166:169], 0
	s_waitcnt vmcnt(5)
	ds_write_b128 v18, v[104:107] offset:16384
	v_mfma_f32_16x16x32_f16 v[136:139], v[136:139], v[166:169], 0
	ds_read_b128 v[166:169], v23 offset:34816
	s_waitcnt lgkmcnt(5)
; #define GL_LOAD(s_, kt_) if (VAR != 1) { a##s_##0 = GL_A(0, kt_); a##s_##1 = GL_A(1, kt_); a##s_##2 = GL_A(2, kt_); a##s_##3 = GL_A(3, kt_); b##s_##0 = GL_B(0, kt_); b##s_##1 = GL_B(1, kt_); b##s_##2 = GL_B(2, kt_); b##s_##3 = GL_B(3, kt_); }
; #define LDS_STORE(s_, buf_) if (VAR != 2) { LDS_ST1(sA, 0, buf_, a##s_##0) LDS_ST1(sA, 1, buf_, a##s_##1) LDS_ST1(sA, 2, buf_, a##s_##2) LDS_ST1(sA, 3, buf_, a##s_##3) LDS_ST1(sB, 0, buf_, b##s_##0) LDS_ST1(sB, 1, buf_, b##s_##1) LDS_ST1(sB, 2, buf_, b##s_##2) LDS_ST1(sB, 3, buf_, b##s_##3) }
;     ...
;   for (int kt = 0; kt < nk; kt += 2) {
;     if (kt + 2 < nk) { GL_LOAD(0, kt + 2) }
;     MMA_TILE(0)
;     LDS_STORE(1, 1)
;     if (VAR != 4) __syncthreads();
;     if (kt + 3 < nk) { GL_LOAD(1, kt + 3) }
;     MMA_TILE(1)
;     if (kt + 2 < nk) { LDS_STORE(0, 0) }
;     if (VAR != 4) __syncthreads();
	v_mfma_f32_16x16x32_f16 v[38:41], v[206:209], v[210:213], v[38:41]
	s_waitcnt vmcnt(4)
	ds_write_b128 v19, v[116:119] offset:16384
	v_mfma_f32_16x16x32_f16 v[140:143], v[224:227], v[210:213], v[140:143]
	s_waitcnt vmcnt(3)
	ds_write_b128 v16, v[120:123] offset:49152
	v_mfma_f32_16x16x32_f16 v[28:31], v[228:231], v[210:213], v[30:33]
	s_waitcnt vmcnt(2)
	ds_write_b128 v17, v[124:127] offset:49152
	s_waitcnt lgkmcnt(7)
	v_mfma_f32_16x16x32_f16 v[144:147], v[206:209], v[220:223], v[144:147]
	s_waitcnt vmcnt(1)
	ds_write_b128 v18, v[128:131] offset:49152
	v_mfma_f32_16x16x32_f16 v[158:161], v[224:227], v[220:223], v[158:161]
	s_waitcnt vmcnt(0)
	ds_write_b128 v19, v[132:135] offset:49152
	v_mfma_f32_16x16x32_f16 v[32:35], v[228:231], v[220:223], v[34:37]
	s_waitcnt lgkmcnt(5)
	v_mfma_f32_16x16x32_f16 v[46:49], v[166:169], v[210:213], v[46:49]
	ds_read_b128 v[210:213], v22 offset:4096
	v_mfma_f32_16x16x32_f16 v[154:157], v[166:169], v[220:223], v[154:157]
	ds_read_b128 v[220:223], v22 offset:6144
	s_waitcnt lgkmcnt(1)
	v_mfma_f32_16x16x32_f16 v[190:193], v[206:209], v[210:213], v[190:193]
	s_waitcnt lgkmcnt(0)
	v_mfma_f32_16x16x32_f16 v[202:205], v[206:209], v[220:223], v[202:205]
	global_load_dwordx4 v[206:209], v[0:1], off offset:256
	v_mfma_f32_16x16x32_f16 v[194:197], v[166:169], v[210:213], v[194:197]
	v_mfma_f32_16x16x32_f16 v[24:27], v[166:169], v[220:223], v[24:27]
	v_mfma_f32_16x16x32_f16 v[198:201], v[224:227], v[210:213], v[198:201]
	v_mfma_f32_16x16x32_f16 v[162:165], v[228:231], v[210:213], v[162:165]
	global_load_dwordx4 v[210:213], v[2:3], off offset:256
	global_load_dwordx4 v[232:235], v[4:5], off offset:256
	global_load_dwordx4 v[236:239], v[6:7], off offset:256
	global_load_dwordx4 v[166:169], v[8:9], off offset:256
	global_load_dwordx4 v[240:243], v[10:11], off offset:256
	global_load_dwordx4 v[244:247], v[12:13], off offset:256
	global_load_dwordx4 v[248:251], v[14:15], off offset:256
	s_waitcnt lgkmcnt(0)
	s_barrier
	v_mfma_f32_16x16x32_f16 v[54:57], v[228:231], v[220:223], v[136:139]
	ds_read_b128 v[50:53], v20 offset:49152
	v_mfma_f32_16x16x32_f16 v[42:45], v[224:227], v[220:223], v[42:45]
	ds_read_b128 v[104:107], v20 offset:51200
	ds_read_b128 v[116:119], v21 offset:16384
	s_waitcnt lgkmcnt(0)
	v_mfma_f32_16x16x32_f16 v[36:39], v[50:53], v[116:119], v[38:41]
	ds_read_b128 v[120:123], v21 offset:18432
	v_mfma_f32_16x16x32_f16 v[46:49], v[104:107], v[116:119], v[46:49]
	ds_read_b128 v[124:127], v20 offset:53248
	s_waitcnt lgkmcnt(0)
	v_mfma_f32_16x16x32_f16 v[132:135], v[124:127], v[116:119], v[140:143]
	ds_read_b128 v[128:131], v20 offset:55296
	s_waitcnt lgkmcnt(0)
	v_mfma_f32_16x16x32_f16 v[28:31], v[128:131], v[116:119], v[28:31]
	v_mfma_f32_16x16x32_f16 v[116:119], v[50:53], v[120:123], v[144:147]
	s_nop 2
	ds_read_b128 v[144:147], v21 offset:22528
	v_mfma_f32_16x16x32_f16 v[136:139], v[104:107], v[120:123], v[154:157]
	v_mfma_f32_16x16x32_f16 v[140:143], v[124:127], v[120:123], v[158:161]
	v_mfma_f32_16x16x32_f16 v[32:35], v[128:131], v[120:123], v[32:35]
	ds_read_b128 v[120:123], v21 offset:20480
	s_waitcnt lgkmcnt(0)
	v_mfma_f32_16x16x32_f16 v[154:157], v[50:53], v[120:123], v[190:193]
	v_mfma_f32_16x16x32_f16 v[50:53], v[50:53], v[144:147], v[202:205]
	v_mfma_f32_16x16x32_f16 v[158:161], v[104:107], v[120:123], v[194:197]
	s_nop 2
	ds_read_b128 v[194:197], v23 offset:55296
	v_mfma_f32_16x16x32_f16 v[24:27], v[104:107], v[144:147], v[24:27]
	ds_read_b128 v[104:107], v23 offset:49152
	s_waitcnt vmcnt(7)
	ds_write_b128 v16, v[206:209]
	v_mfma_f32_16x16x32_f16 v[190:193], v[124:127], v[120:123], v[198:201]
	s_waitcnt vmcnt(6)
	ds_write_b128 v17, v[210:213]
	s_waitcnt vmcnt(5)
	ds_write_b128 v18, v[232:235]
	v_mfma_f32_16x16x32_f16 v[40:43], v[124:127], v[144:147], v[42:45]
	ds_read_b128 v[124:127], v23 offset:51200
	v_mfma_f32_16x16x32_f16 v[120:123], v[128:131], v[120:123], v[162:165]
	s_nop 2
	ds_read_b128 v[162:165], v23 offset:53248
	v_mfma_f32_16x16x32_f16 v[54:57], v[128:131], v[144:147], v[54:57]
	ds_read_b128 v[128:131], v22 offset:16384
	s_waitcnt lgkmcnt(0)
	v_mfma_f32_16x16x32_f16 v[36:39], v[104:107], v[128:131], v[36:39]
	ds_read_b128 v[144:147], v22 offset:18432
	s_waitcnt lgkmcnt(0)
	v_mfma_f32_16x16x32_f16 v[116:119], v[104:107], v[144:147], v[116:119]
	s_waitcnt vmcnt(4)
	ds_write_b128 v19, v[236:239]
	v_mfma_f32_16x16x32_f16 v[44:47], v[124:127], v[128:131], v[46:49]
	s_waitcnt vmcnt(3)
	ds_write_b128 v16, v[166:169] offset:32768
	v_mfma_f32_16x16x32_f16 v[132:135], v[162:165], v[128:131], v[132:135]
	v_mfma_f32_16x16x32_f16 v[28:31], v[194:197], v[128:131], v[28:31]
	v_mfma_f32_16x16x32_f16 v[128:131], v[124:127], v[144:147], v[136:139]
	s_waitcnt vmcnt(2)
	ds_write_b128 v17, v[240:243] offset:32768
	s_waitcnt vmcnt(1)
	ds_write_b128 v18, v[244:247] offset:32768
	s_waitcnt vmcnt(0)
	ds_write_b128 v19, v[248:251] offset:32768
	v_mfma_f32_16x16x32_f16 v[136:139], v[162:165], v[144:147], v[140:143]
	s_nop 2
	ds_read_b128 v[140:143], v22 offset:20480
	v_mfma_f32_16x16x32_f16 v[32:35], v[194:197], v[144:147], v[32:35]
	ds_read_b128 v[144:147], v22 offset:22528
	s_waitcnt lgkmcnt(1)
	v_mfma_f32_16x16x32_f16 v[154:157], v[104:107], v[140:143], v[154:157]
	s_waitcnt lgkmcnt(0)
	v_mfma_f32_16x16x32_f16 v[48:51], v[104:107], v[144:147], v[50:53]
	global_load_dwordx4 v[104:107], v[0:1], off offset:384
	v_mfma_f32_16x16x32_f16 v[158:161], v[124:127], v[140:143], v[158:161]
	v_mfma_f32_16x16x32_f16 v[24:27], v[124:127], v[144:147], v[24:27]
	v_mfma_f32_16x16x32_f16 v[190:193], v[162:165], v[140:143], v[190:193]
	v_mfma_f32_16x16x32_f16 v[40:43], v[162:165], v[144:147], v[40:43]
	v_mfma_f32_16x16x32_f16 v[120:123], v[194:197], v[140:143], v[120:123]
	global_load_dwordx4 v[140:143], v[2:3], off offset:384
	global_load_dwordx4 v[198:201], v[4:5], off offset:384
	global_load_dwordx4 v[202:205], v[6:7], off offset:384
	global_load_dwordx4 v[124:127], v[8:9], off offset:384
	global_load_dwordx4 v[220:223], v[10:11], off offset:384
	global_load_dwordx4 v[224:227], v[12:13], off offset:384
	global_load_dwordx4 v[228:231], v[14:15], off offset:384
	s_waitcnt lgkmcnt(0)
	s_barrier
; #define GL_LOAD(s_, kt_) if (VAR != 1) { a##s_##0 = GL_A(0, kt_); a##s_##1 = GL_A(1, kt_); a##s_##2 = GL_A(2, kt_); a##s_##3 = GL_A(3, kt_); b##s_##0 = GL_B(0, kt_); b##s_##1 = GL_B(1, kt_); b##s_##2 = GL_B(2, kt_); b##s_##3 = GL_B(3, kt_); }
; #define LDS_STORE(s_, buf_) if (VAR != 2) { LDS_ST1(sA, 0, buf_, a##s_##0) LDS_ST1(sA, 1, buf_, a##s_##1) LDS_ST1(sA, 2, buf_, a##s_##2) LDS_ST1(sA, 3, buf_, a##s_##3) LDS_ST1(sB, 0, buf_, b##s_##0) LDS_ST1(sB, 1, buf_, b##s_##1) LDS_ST1(sB, 2, buf_, b##s_##2) LDS_ST1(sB, 3, buf_, b##s_##3) }
;     ...
;   for (int kt = 0; kt < nk; kt += 2) {
;     if (kt + 2 < nk) { GL_LOAD(0, kt + 2) }
;     MMA_TILE(0)
;     LDS_STORE(1, 1)
;     if (VAR != 4) __syncthreads();
;     if (kt + 3 < nk) { GL_LOAD(1, kt + 3) }
;     MMA_TILE(1)
;     if (kt + 2 < nk) { LDS_STORE(0, 0) }
;     if (VAR != 4) __syncthreads();
	v_mfma_f32_16x16x32_f16 v[52:55], v[194:197], v[144:147], v[54:57]
	ds_read_b128 v[162:165], v20 offset:32768
	ds_read_b128 v[144:147], v21
	s_waitcnt lgkmcnt(0)
	v_mfma_f32_16x16x32_f16 v[36:39], v[162:165], v[144:147], v[36:39]
	ds_read_b128 v[56:59], v20 offset:34816
	ds_read_b128 v[166:169], v21 offset:2048
	s_waitcnt lgkmcnt(0)
	v_mfma_f32_16x16x32_f16 v[116:119], v[162:165], v[166:169], v[116:119]
	ds_read_b128 v[194:197], v20 offset:36864
	v_mfma_f32_16x16x32_f16 v[44:47], v[56:59], v[144:147], v[44:47]
	ds_read_b128 v[206:209], v20 offset:38912
	v_mfma_f32_16x16x32_f16 v[128:131], v[56:59], v[166:169], v[128:131]
	s_waitcnt lgkmcnt(1)
	v_mfma_f32_16x16x32_f16 v[132:135], v[194:197], v[144:147], v[132:135]
	v_mfma_f32_16x16x32_f16 v[136:139], v[194:197], v[166:169], v[136:139]
	s_waitcnt lgkmcnt(0)
	v_mfma_f32_16x16x32_f16 v[28:31], v[206:209], v[144:147], v[28:31]
	ds_read_b128 v[144:147], v21 offset:4096
	v_mfma_f32_16x16x32_f16 v[32:35], v[206:209], v[166:169], v[32:35]
	ds_read_b128 v[166:169], v21 offset:6144
	s_waitcnt lgkmcnt(1)
	v_mfma_f32_16x16x32_f16 v[154:157], v[162:165], v[144:147], v[154:157]
	s_waitcnt lgkmcnt(0)
	v_mfma_f32_16x16x32_f16 v[48:51], v[162:165], v[166:169], v[48:51]
	ds_read_b128 v[162:165], v22
	v_mfma_f32_16x16x32_f16 v[158:161], v[56:59], v[144:147], v[158:161]
	v_mfma_f32_16x16x32_f16 v[24:27], v[56:59], v[166:169], v[24:27]
	ds_read_b128 v[56:59], v23 offset:32768
	v_mfma_f32_16x16x32_f16 v[190:193], v[194:197], v[144:147], v[190:193]
	s_waitcnt vmcnt(7)
	ds_write_b128 v16, v[104:107] offset:16384
	s_waitcnt vmcnt(6)
	ds_write_b128 v17, v[140:143] offset:16384
	v_mfma_f32_16x16x32_f16 v[40:43], v[194:197], v[166:169], v[40:43]
	ds_read_b128 v[194:197], v23 offset:36864
	s_waitcnt vmcnt(5)
	ds_write_b128 v18, v[198:201] offset:16384
	v_mfma_f32_16x16x32_f16 v[120:123], v[206:209], v[144:147], v[120:123]
	ds_read_b128 v[144:147], v23 offset:34816
	v_mfma_f32_16x16x32_f16 v[52:55], v[206:209], v[166:169], v[52:55]
	ds_read_b128 v[166:169], v22 offset:2048
	s_waitcnt lgkmcnt(6)
	v_mfma_f32_16x16x32_f16 v[36:39], v[56:59], v[162:165], v[36:39]
	ds_read_b128 v[206:209], v23 offset:38912
	s_waitcnt lgkmcnt(1)
	v_mfma_f32_16x16x32_f16 v[116:119], v[56:59], v[166:169], v[116:119]
	s_waitcnt vmcnt(4)
	ds_write_b128 v19, v[202:205] offset:16384
	v_mfma_f32_16x16x32_f16 v[44:47], v[144:147], v[162:165], v[44:47]
	s_waitcnt vmcnt(3)
	ds_write_b128 v16, v[124:127] offset:49152
	v_mfma_f32_16x16x32_f16 v[128:131], v[144:147], v[166:169], v[128:131]
	s_waitcnt vmcnt(2)
	ds_write_b128 v17, v[220:223] offset:49152
	v_mfma_f32_16x16x32_f16 v[132:135], v[194:197], v[162:165], v[132:135]
	s_waitcnt vmcnt(1)
	ds_write_b128 v18, v[224:227] offset:49152
	v_mfma_f32_16x16x32_f16 v[136:139], v[194:197], v[166:169], v[136:139]
	s_waitcnt vmcnt(0)
	ds_write_b128 v19, v[228:231] offset:49152
	s_waitcnt lgkmcnt(5)
	v_mfma_f32_16x16x32_f16 v[28:31], v[206:209], v[162:165], v[28:31]
	ds_read_b128 v[162:165], v22 offset:4096
	v_mfma_f32_16x16x32_f16 v[32:35], v[206:209], v[166:169], v[32:35]
	ds_read_b128 v[166:169], v22 offset:6144
	s_waitcnt lgkmcnt(1)
	v_mfma_f32_16x16x32_f16 v[154:157], v[56:59], v[162:165], v[154:157]
	s_waitcnt lgkmcnt(0)
	v_mfma_f32_16x16x32_f16 v[48:51], v[56:59], v[166:169], v[48:51]
	global_load_dwordx4 v[56:59], v[0:1], off offset:512
	v_mfma_f32_16x16x32_f16 v[158:161], v[144:147], v[162:165], v[158:161]
	v_mfma_f32_16x16x32_f16 v[24:27], v[144:147], v[166:169], v[24:27]
	v_mfma_f32_16x16x32_f16 v[190:193], v[194:197], v[162:165], v[190:193]
	v_mfma_f32_16x16x32_f16 v[40:43], v[194:197], v[166:169], v[40:43]
	v_mfma_f32_16x16x32_f16 v[120:123], v[206:209], v[162:165], v[120:123]
	global_load_dwordx4 v[162:165], v[2:3], off offset:512
	global_load_dwordx4 v[210:213], v[4:5], off offset:512
	global_load_dwordx4 v[232:235], v[6:7], off offset:512
	global_load_dwordx4 v[144:147], v[8:9], off offset:512
	global_load_dwordx4 v[236:239], v[10:11], off offset:512
	global_load_dwordx4 v[240:243], v[12:13], off offset:512
	global_load_dwordx4 v[244:247], v[14:15], off offset:512
	s_waitcnt lgkmcnt(0)
	s_barrier
	v_mfma_f32_16x16x32_f16 v[52:55], v[206:209], v[166:169], v[52:55]
	ds_read_b128 v[104:107], v20 offset:49152
	ds_read_b128 v[140:143], v21 offset:16384
	s_waitcnt lgkmcnt(0)
	v_mfma_f32_16x16x32_f16 v[36:39], v[104:107], v[140:143], v[36:39]
	ds_read_b128 v[124:127], v20 offset:51200
	ds_read_b128 v[166:169], v21 offset:18432
	s_waitcnt lgkmcnt(0)
	v_mfma_f32_16x16x32_f16 v[116:119], v[104:107], v[166:169], v[116:119]
	ds_read_b128 v[194:197], v20 offset:53248
	v_mfma_f32_16x16x32_f16 v[44:47], v[124:127], v[140:143], v[44:47]
	ds_read_b128 v[198:201], v20 offset:55296
	v_mfma_f32_16x16x32_f16 v[128:131], v[124:127], v[166:169], v[128:131]
	s_waitcnt lgkmcnt(1)
	v_mfma_f32_16x16x32_f16 v[132:135], v[194:197], v[140:143], v[132:135]
	v_mfma_f32_16x16x32_f16 v[136:139], v[194:197], v[166:169], v[136:139]
	s_waitcnt lgkmcnt(0)
	v_mfma_f32_16x16x32_f16 v[28:31], v[198:201], v[140:143], v[28:31]
	ds_read_b128 v[140:143], v21 offset:20480
	v_mfma_f32_16x16x32_f16 v[32:35], v[198:201], v[166:169], v[32:35]
	ds_read_b128 v[166:169], v21 offset:22528
	s_waitcnt lgkmcnt(1)
	v_mfma_f32_16x16x32_f16 v[154:157], v[104:107], v[140:143], v[154:157]
	s_waitcnt lgkmcnt(0)
	v_mfma_f32_16x16x32_f16 v[48:51], v[104:107], v[166:169], v[48:51]
	ds_read_b128 v[104:107], v23 offset:49152
	v_mfma_f32_16x16x32_f16 v[158:161], v[124:127], v[140:143], v[158:161]
	v_mfma_f32_16x16x32_f16 v[24:27], v[124:127], v[166:169], v[24:27]
	ds_read_b128 v[124:127], v23 offset:51200
	v_mfma_f32_16x16x32_f16 v[190:193], v[194:197], v[140:143], v[190:193]
	s_waitcnt vmcnt(7)
; #define GL_LOAD(s_, kt_) if (VAR != 1) { a##s_##0 = GL_A(0, kt_); a##s_##1 = GL_A(1, kt_); a##s_##2 = GL_A(2, kt_); a##s_##3 = GL_A(3, kt_); b##s_##0 = GL_B(0, kt_); b##s_##1 = GL_B(1, kt_); b##s_##2 = GL_B(2, kt_); b##s_##3 = GL_B(3, kt_); }
; #define LDS_STORE(s_, buf_) if (VAR != 2) { LDS_ST1(sA, 0, buf_, a##s_##0) LDS_ST1(sA, 1, buf_, a##s_##1) LDS_ST1(sA, 2, buf_, a##s_##2) LDS_ST1(sA, 3, buf_, a##s_##3) LDS_ST1(sB, 0, buf_, b##s_##0) LDS_ST1(sB, 1, buf_, b##s_##1) LDS_ST1(sB, 2, buf_, b##s_##2) LDS_ST1(sB, 3, buf_, b##s_##3) }
;     ...
;   for (int kt = 0; kt < nk; kt += 2) {
;     if (kt + 2 < nk) { GL_LOAD(0, kt + 2) }
;     MMA_TILE(0)
;     LDS_STORE(1, 1)
;     if (VAR != 4) __syncthreads();
;     if (kt + 3 < nk) { GL_LOAD(1, kt + 3) }
;     MMA_TILE(1)
;     if (kt + 2 < nk) { LDS_STORE(0, 0) }
;     if (VAR != 4) __syncthreads();
	ds_write_b128 v16, v[56:59]
	s_waitcnt vmcnt(6)
	ds_write_b128 v17, v[162:165]
	v_mfma_f32_16x16x32_f16 v[40:43], v[194:197], v[166:169], v[40:43]
	ds_read_b128 v[194:197], v23 offset:53248
	s_waitcnt vmcnt(5)
	ds_write_b128 v18, v[210:213]
	v_mfma_f32_16x16x32_f16 v[120:123], v[198:201], v[140:143], v[120:123]
	ds_read_b128 v[140:143], v22 offset:16384
	v_mfma_f32_16x16x32_f16 v[52:55], v[198:201], v[166:169], v[52:55]
	ds_read_b128 v[166:169], v22 offset:18432
	s_waitcnt lgkmcnt(1)
	v_mfma_f32_16x16x32_f16 v[36:39], v[104:107], v[140:143], v[36:39]
	ds_read_b128 v[198:201], v23 offset:55296
	s_waitcnt lgkmcnt(1)
	v_mfma_f32_16x16x32_f16 v[116:119], v[104:107], v[166:169], v[116:119]
	s_waitcnt vmcnt(4)
	ds_write_b128 v19, v[232:235]
	v_mfma_f32_16x16x32_f16 v[44:47], v[124:127], v[140:143], v[44:47]
	s_waitcnt vmcnt(3)
	ds_write_b128 v16, v[144:147] offset:32768
	v_mfma_f32_16x16x32_f16 v[128:131], v[124:127], v[166:169], v[128:131]
	s_waitcnt vmcnt(2)
	ds_write_b128 v17, v[236:239] offset:32768
	v_mfma_f32_16x16x32_f16 v[132:135], v[194:197], v[140:143], v[132:135]
	s_waitcnt vmcnt(1)
	ds_write_b128 v18, v[240:243] offset:32768
	v_mfma_f32_16x16x32_f16 v[136:139], v[194:197], v[166:169], v[136:139]
	s_waitcnt vmcnt(0)
	ds_write_b128 v19, v[244:247] offset:32768
	s_waitcnt lgkmcnt(5)
	v_mfma_f32_16x16x32_f16 v[28:31], v[198:201], v[140:143], v[28:31]
	ds_read_b128 v[140:143], v22 offset:20480
	v_mfma_f32_16x16x32_f16 v[32:35], v[198:201], v[166:169], v[32:35]
	ds_read_b128 v[166:169], v22 offset:22528
	s_waitcnt lgkmcnt(1)
	v_mfma_f32_16x16x32_f16 v[154:157], v[104:107], v[140:143], v[154:157]
	s_waitcnt lgkmcnt(0)
	v_mfma_f32_16x16x32_f16 v[48:51], v[104:107], v[166:169], v[48:51]
	global_load_dwordx4 v[104:107], v[0:1], off offset:640
	v_mfma_f32_16x16x32_f16 v[158:161], v[124:127], v[140:143], v[158:161]
	v_mfma_f32_16x16x32_f16 v[24:27], v[124:127], v[166:169], v[24:27]
	v_mfma_f32_16x16x32_f16 v[190:193], v[194:197], v[140:143], v[190:193]
	v_mfma_f32_16x16x32_f16 v[40:43], v[194:197], v[166:169], v[40:43]
	v_mfma_f32_16x16x32_f16 v[120:123], v[198:201], v[140:143], v[120:123]
	global_load_dwordx4 v[140:143], v[2:3], off offset:640
	global_load_dwordx4 v[202:205], v[4:5], off offset:640
	global_load_dwordx4 v[206:209], v[6:7], off offset:640
	global_load_dwordx4 v[124:127], v[8:9], off offset:640
	global_load_dwordx4 v[220:223], v[10:11], off offset:640
	global_load_dwordx4 v[224:227], v[12:13], off offset:640
	global_load_dwordx4 v[228:231], v[14:15], off offset:640
	s_waitcnt lgkmcnt(0)
	s_barrier
	v_mfma_f32_16x16x32_f16 v[52:55], v[198:201], v[166:169], v[52:55]
	ds_read_b128 v[56:59], v20 offset:32768
	ds_read_b128 v[162:165], v21
	s_waitcnt lgkmcnt(0)
	v_mfma_f32_16x16x32_f16 v[36:39], v[56:59], v[162:165], v[36:39]
	ds_read_b128 v[144:147], v20 offset:34816
	ds_read_b128 v[166:169], v21 offset:2048
	s_waitcnt lgkmcnt(0)
	v_mfma_f32_16x16x32_f16 v[116:119], v[56:59], v[166:169], v[116:119]
	ds_read_b128 v[194:197], v20 offset:36864
	v_mfma_f32_16x16x32_f16 v[44:47], v[144:147], v[162:165], v[44:47]
	ds_read_b128 v[198:201], v20 offset:38912
	v_mfma_f32_16x16x32_f16 v[128:131], v[144:147], v[166:169], v[128:131]
	s_waitcnt lgkmcnt(1)
	v_mfma_f32_16x16x32_f16 v[132:135], v[194:197], v[162:165], v[132:135]
	v_mfma_f32_16x16x32_f16 v[136:139], v[194:197], v[166:169], v[136:139]
	s_waitcnt lgkmcnt(0)
	v_mfma_f32_16x16x32_f16 v[28:31], v[198:201], v[162:165], v[28:31]
	ds_read_b128 v[162:165], v21 offset:4096
	v_mfma_f32_16x16x32_f16 v[32:35], v[198:201], v[166:169], v[32:35]
	ds_read_b128 v[166:169], v21 offset:6144
	s_waitcnt lgkmcnt(1)
	v_mfma_f32_16x16x32_f16 v[154:157], v[56:59], v[162:165], v[154:157]
	s_waitcnt lgkmcnt(0)
	v_mfma_f32_16x16x32_f16 v[48:51], v[56:59], v[166:169], v[48:51]
	ds_read_b128 v[56:59], v23 offset:32768
	v_mfma_f32_16x16x32_f16 v[158:161], v[144:147], v[162:165], v[158:161]
	v_mfma_f32_16x16x32_f16 v[24:27], v[144:147], v[166:169], v[24:27]
	ds_read_b128 v[144:147], v23 offset:34816
	v_mfma_f32_16x16x32_f16 v[190:193], v[194:197], v[162:165], v[190:193]
	s_waitcnt vmcnt(7)
	ds_write_b128 v16, v[104:107] offset:16384
	s_waitcnt vmcnt(6)
	ds_write_b128 v17, v[140:143] offset:16384
	v_mfma_f32_16x16x32_f16 v[40:43], v[194:197], v[166:169], v[40:43]
	ds_read_b128 v[194:197], v23 offset:36864
	s_waitcnt vmcnt(5)
	ds_write_b128 v18, v[202:205] offset:16384
	v_mfma_f32_16x16x32_f16 v[120:123], v[198:201], v[162:165], v[120:123]
	ds_read_b128 v[162:165], v22
	v_mfma_f32_16x16x32_f16 v[52:55], v[198:201], v[166:169], v[52:55]
	ds_read_b128 v[166:169], v22 offset:2048
	s_waitcnt lgkmcnt(1)
	v_mfma_f32_16x16x32_f16 v[36:39], v[56:59], v[162:165], v[36:39]
	ds_read_b128 v[198:201], v23 offset:38912
	s_waitcnt lgkmcnt(1)
	v_mfma_f32_16x16x32_f16 v[116:119], v[56:59], v[166:169], v[116:119]
	s_waitcnt vmcnt(4)
	ds_write_b128 v19, v[206:209] offset:16384
	v_mfma_f32_16x16x32_f16 v[44:47], v[144:147], v[162:165], v[44:47]
	s_waitcnt vmcnt(3)
	ds_write_b128 v16, v[124:127] offset:49152
	v_mfma_f32_16x16x32_f16 v[128:131], v[144:147], v[166:169], v[128:131]
	s_waitcnt vmcnt(2)
	ds_write_b128 v17, v[220:223] offset:49152
	v_mfma_f32_16x16x32_f16 v[132:135], v[194:197], v[162:165], v[132:135]
	s_waitcnt vmcnt(1)
	ds_write_b128 v18, v[224:227] offset:49152
	v_mfma_f32_16x16x32_f16 v[136:139], v[194:197], v[166:169], v[136:139]
	s_waitcnt vmcnt(0)
	ds_write_b128 v19, v[228:231] offset:49152
	s_waitcnt lgkmcnt(5)
	v_mfma_f32_16x16x32_f16 v[28:31], v[198:201], v[162:165], v[28:31]
	ds_read_b128 v[162:165], v22 offset:4096
	v_mfma_f32_16x16x32_f16 v[32:35], v[198:201], v[166:169], v[32:35]
	ds_read_b128 v[166:169], v22 offset:6144
	s_waitcnt lgkmcnt(1)
	v_mfma_f32_16x16x32_f16 v[154:157], v[56:59], v[162:165], v[154:157]
	s_waitcnt lgkmcnt(0)
	v_mfma_f32_16x16x32_f16 v[48:51], v[56:59], v[166:169], v[48:51]
	global_load_dwordx4 v[56:59], v[0:1], off offset:768
	v_mfma_f32_16x16x32_f16 v[158:161], v[144:147], v[162:165], v[158:161]
	v_mfma_f32_16x16x32_f16 v[24:27], v[144:147], v[166:169], v[24:27]
	v_mfma_f32_16x16x32_f16 v[190:193], v[194:197], v[162:165], v[190:193]
	v_mfma_f32_16x16x32_f16 v[40:43], v[194:197], v[166:169], v[40:43]
	v_mfma_f32_16x16x32_f16 v[120:123], v[198:201], v[162:165], v[120:123]
	global_load_dwordx4 v[162:165], v[2:3], off offset:768
	global_load_dwordx4 v[210:213], v[4:5], off offset:768
	global_load_dwordx4 v[232:235], v[6:7], off offset:768
	global_load_dwordx4 v[144:147], v[8:9], off offset:768
	global_load_dwordx4 v[236:239], v[10:11], off offset:768
	global_load_dwordx4 v[240:243], v[12:13], off offset:768
	global_load_dwordx4 v[244:247], v[14:15], off offset:768
	s_waitcnt lgkmcnt(0)
	s_barrier
; #define GL_LOAD(s_, kt_) if (VAR != 1) { a##s_##0 = GL_A(0, kt_); a##s_##1 = GL_A(1, kt_); a##s_##2 = GL_A(2, kt_); a##s_##3 = GL_A(3, kt_); b##s_##0 = GL_B(0, kt_); b##s_##1 = GL_B(1, kt_); b##s_##2 = GL_B(2, kt_); b##s_##3 = GL_B(3, kt_); }
; #define LDS_STORE(s_, buf_) if (VAR != 2) { LDS_ST1(sA, 0, buf_, a##s_##0) LDS_ST1(sA, 1, buf_, a##s_##1) LDS_ST1(sA, 2, buf_, a##s_##2) LDS_ST1(sA, 3, buf_, a##s_##3) LDS_ST1(sB, 0, buf_, b##s_##0) LDS_ST1(sB, 1, buf_, b##s_##1) LDS_ST1(sB, 2, buf_, b##s_##2) LDS_ST1(sB, 3, buf_, b##s_##3) }
;     ...
;   for (int kt = 0; kt < nk; kt += 2) {
;     if (kt + 2 < nk) { GL_LOAD(0, kt + 2) }
;     MMA_TILE(0)
;     LDS_STORE(1, 1)
;     if (VAR != 4) __syncthreads();
;     if (kt + 3 < nk) { GL_LOAD(1, kt + 3) }
;     MMA_TILE(1)
;     if (kt + 2 < nk) { LDS_STORE(0, 0) }
;     if (VAR != 4) __syncthreads();
	v_mfma_f32_16x16x32_f16 v[52:55], v[198:201], v[166:169], v[52:55]
	ds_read_b128 v[104:107], v20 offset:49152
	ds_read_b128 v[140:143], v21 offset:16384
	s_waitcnt lgkmcnt(0)
	v_mfma_f32_16x16x32_f16 v[36:39], v[104:107], v[140:143], v[36:39]
	ds_read_b128 v[124:127], v20 offset:51200
	ds_read_b128 v[166:169], v21 offset:18432
	s_waitcnt lgkmcnt(0)
	v_mfma_f32_16x16x32_f16 v[116:119], v[104:107], v[166:169], v[116:119]
	ds_read_b128 v[194:197], v20 offset:53248
	v_mfma_f32_16x16x32_f16 v[44:47], v[124:127], v[140:143], v[44:47]
	ds_read_b128 v[198:201], v20 offset:55296
	v_mfma_f32_16x16x32_f16 v[128:131], v[124:127], v[166:169], v[128:131]
	s_waitcnt lgkmcnt(1)
	v_mfma_f32_16x16x32_f16 v[132:135], v[194:197], v[140:143], v[132:135]
	v_mfma_f32_16x16x32_f16 v[136:139], v[194:197], v[166:169], v[136:139]
	s_waitcnt lgkmcnt(0)
	v_mfma_f32_16x16x32_f16 v[28:31], v[198:201], v[140:143], v[28:31]
	ds_read_b128 v[140:143], v21 offset:20480
	v_mfma_f32_16x16x32_f16 v[32:35], v[198:201], v[166:169], v[32:35]
	ds_read_b128 v[166:169], v21 offset:22528
	s_waitcnt lgkmcnt(1)
	v_mfma_f32_16x16x32_f16 v[154:157], v[104:107], v[140:143], v[154:157]
	s_waitcnt lgkmcnt(0)
	v_mfma_f32_16x16x32_f16 v[48:51], v[104:107], v[166:169], v[48:51]
	ds_read_b128 v[104:107], v23 offset:49152
	v_mfma_f32_16x16x32_f16 v[158:161], v[124:127], v[140:143], v[158:161]
	v_mfma_f32_16x16x32_f16 v[24:27], v[124:127], v[166:169], v[24:27]
	ds_read_b128 v[124:127], v23 offset:51200
	v_mfma_f32_16x16x32_f16 v[190:193], v[194:197], v[140:143], v[190:193]
	s_waitcnt vmcnt(7)
	ds_write_b128 v16, v[56:59]
	s_waitcnt vmcnt(6)
	ds_write_b128 v17, v[162:165]
	v_mfma_f32_16x16x32_f16 v[40:43], v[194:197], v[166:169], v[40:43]
	ds_read_b128 v[194:197], v23 offset:53248
	s_waitcnt vmcnt(5)
	ds_write_b128 v18, v[210:213]
	v_mfma_f32_16x16x32_f16 v[120:123], v[198:201], v[140:143], v[120:123]
	ds_read_b128 v[140:143], v22 offset:16384
	v_mfma_f32_16x16x32_f16 v[52:55], v[198:201], v[166:169], v[52:55]
	ds_read_b128 v[166:169], v22 offset:18432
	s_waitcnt lgkmcnt(1)
	v_mfma_f32_16x16x32_f16 v[36:39], v[104:107], v[140:143], v[36:39]
	ds_read_b128 v[198:201], v23 offset:55296
	s_waitcnt lgkmcnt(1)
	v_mfma_f32_16x16x32_f16 v[116:119], v[104:107], v[166:169], v[116:119]
	s_waitcnt vmcnt(4)
	ds_write_b128 v19, v[232:235]
	v_mfma_f32_16x16x32_f16 v[44:47], v[124:127], v[140:143], v[44:47]
	s_waitcnt vmcnt(3)
	ds_write_b128 v16, v[144:147] offset:32768
	v_mfma_f32_16x16x32_f16 v[128:131], v[124:127], v[166:169], v[128:131]
	s_waitcnt vmcnt(2)
	ds_write_b128 v17, v[236:239] offset:32768
	v_mfma_f32_16x16x32_f16 v[132:135], v[194:197], v[140:143], v[132:135]
	s_waitcnt vmcnt(1)
	ds_write_b128 v18, v[240:243] offset:32768
	v_mfma_f32_16x16x32_f16 v[136:139], v[194:197], v[166:169], v[136:139]
	s_waitcnt vmcnt(0)
	ds_write_b128 v19, v[244:247] offset:32768
	s_waitcnt lgkmcnt(5)
	v_mfma_f32_16x16x32_f16 v[28:31], v[198:201], v[140:143], v[28:31]
	ds_read_b128 v[140:143], v22 offset:20480
	v_mfma_f32_16x16x32_f16 v[32:35], v[198:201], v[166:169], v[32:35]
	ds_read_b128 v[166:169], v22 offset:22528
	s_waitcnt lgkmcnt(1)
	v_mfma_f32_16x16x32_f16 v[154:157], v[104:107], v[140:143], v[154:157]
	s_waitcnt lgkmcnt(0)
	v_mfma_f32_16x16x32_f16 v[48:51], v[104:107], v[166:169], v[48:51]
	global_load_dwordx4 v[104:107], v[0:1], off offset:896
	global_load_dwordx4 v[0:3], v[2:3], off offset:896
	v_mfma_f32_16x16x32_f16 v[158:161], v[124:127], v[140:143], v[158:161]
	v_mfma_f32_16x16x32_f16 v[24:27], v[124:127], v[166:169], v[24:27]
	v_mfma_f32_16x16x32_f16 v[190:193], v[194:197], v[140:143], v[190:193]
	v_mfma_f32_16x16x32_f16 v[40:43], v[194:197], v[166:169], v[40:43]
	v_mfma_f32_16x16x32_f16 v[120:123], v[198:201], v[140:143], v[120:123]
	global_load_dwordx4 v[140:143], v[4:5], off offset:896
	global_load_dwordx4 v[4:7], v[6:7], off offset:896
	global_load_dwordx4 v[124:127], v[8:9], off offset:896
	global_load_dwordx4 v[8:11], v[10:11], off offset:896
	global_load_dwordx4 v[202:205], v[12:13], off offset:896
	global_load_dwordx4 v[12:15], v[14:15], off offset:896
	s_waitcnt lgkmcnt(0)
	s_barrier
	ds_read_b128 v[56:59], v20 offset:32768
	v_mfma_f32_16x16x32_f16 v[52:55], v[198:201], v[166:169], v[52:55]
	ds_read_b128 v[144:147], v20 offset:34816
	ds_read_b128 v[162:165], v21
	ds_read_b128 v[166:169], v21 offset:2048
	ds_read_b128 v[194:197], v20 offset:36864
	ds_read_b128 v[198:201], v20 offset:38912
	s_waitcnt lgkmcnt(3)
	v_mfma_f32_16x16x32_f16 v[36:39], v[56:59], v[162:165], v[36:39]
	v_mfma_f32_16x16x32_f16 v[44:47], v[144:147], v[162:165], v[44:47]
	s_waitcnt lgkmcnt(1)
	v_mfma_f32_16x16x32_f16 v[132:135], v[194:197], v[162:165], v[132:135]
	s_waitcnt lgkmcnt(0)
	v_mfma_f32_16x16x32_f16 v[28:31], v[198:201], v[162:165], v[28:31]
	v_mfma_f32_16x16x32_f16 v[116:119], v[56:59], v[166:169], v[116:119]
	v_mfma_f32_16x16x32_f16 v[128:131], v[144:147], v[166:169], v[128:131]
	v_mfma_f32_16x16x32_f16 v[136:139], v[194:197], v[166:169], v[136:139]
	v_mfma_f32_16x16x32_f16 v[32:35], v[198:201], v[166:169], v[32:35]
	ds_read_b128 v[162:165], v21 offset:4096
	ds_read_b128 v[166:169], v21 offset:6144
	s_waitcnt lgkmcnt(1)
	v_mfma_f32_16x16x32_f16 v[154:157], v[56:59], v[162:165], v[154:157]
	v_mfma_f32_16x16x32_f16 v[158:161], v[144:147], v[162:165], v[158:161]
	v_mfma_f32_16x16x32_f16 v[190:193], v[194:197], v[162:165], v[190:193]
	v_mfma_f32_16x16x32_f16 v[120:123], v[198:201], v[162:165], v[120:123]
	s_waitcnt lgkmcnt(0)
; DI unsigned pack2(float lo, float hi) { f2_t v = {lo, hi}; h2_t b = __builtin_convertvector(v, h2_t); return __builtin_bit_cast(unsigned, b); }
; DI float lo_f(unsigned u) { return (float)(__builtin_bit_cast(h2_t, u)[0]); }
; DI float hi_f(unsigned u) { return (float)(__builtin_bit_cast(h2_t, u)[1]); }
; #define GL_LOAD(s_, kt_) if (VAR != 1) { a##s_##0 = GL_A(0, kt_); a##s_##1 = GL_A(1, kt_); a##s_##2 = GL_A(2, kt_); a##s_##3 = GL_A(3, kt_); b##s_##0 = GL_B(0, kt_); b##s_##1 = GL_B(1, kt_); b##s_##2 = GL_B(2, kt_); b##s_##3 = GL_B(3, kt_); }
; #define LDS_STORE(s_, buf_) if (VAR != 2) { LDS_ST1(sA, 0, buf_, a##s_##0) LDS_ST1(sA, 1, buf_, a##s_##1) LDS_ST1(sA, 2, buf_, a##s_##2) LDS_ST1(sA, 3, buf_, a##s_##3) LDS_ST1(sB, 0, buf_, b##s_##0) LDS_ST1(sB, 1, buf_, b##s_##1) LDS_ST1(sB, 2, buf_, b##s_##2) LDS_ST1(sB, 3, buf_, b##s_##3) }
;     ...
;   for (int kt = 0; kt < nk; kt += 2) {
;     if (kt + 2 < nk) { GL_LOAD(0, kt + 2) }
;     MMA_TILE(0)
;     LDS_STORE(1, 1)
;     if (VAR != 4) __syncthreads();
;     if (kt + 3 < nk) { GL_LOAD(1, kt + 3) }
;     MMA_TILE(1)
;     if (kt + 2 < nk) { LDS_STORE(0, 0) }
;     if (VAR != 4) __syncthreads();
;   }
; DI void phase_merge(const Params& P, int l, char* smem) {
;     ...
; #pragma unroll
;       for (int mt = 0; mt < 4; ++mt) {
;         const int row = row0 + mt * 16 + lr;
; #pragma unroll
;         for (int nt = 0; nt < 4; ++nt) {
;           const uint2 gu = *(const uint2*)(Pb + (size_t)row * PW + C_GL + br * 1024 + col0 + nt * 16 + 4 * g);
;           float t0 = lo_f(gu.x) * acc[mt][nt][0], t1 = hi_f(gu.x) * acc[mt][nt][1], t2 = lo_f(gu.y) * acc[mt][nt][2], t3 = hi_f(gu.y) * acc[mt][nt][3];
;           if (br > 0) { t0 += lo_f(tot[mt][nt][0]); t1 += hi_f(tot[mt][nt][0]); t2 += lo_f(tot[mt][nt][1]); t3 += hi_f(tot[mt][nt][1]); }
;           tot[mt][nt][0] = pack2(t0, t1); tot[mt][nt][1] = pack2(t2, t3);
	v_mfma_f32_16x16x32_f16 v[48:51], v[56:59], v[166:169], v[48:51]
	ds_read_b128 v[56:59], v23 offset:32768
	v_mfma_f32_16x16x32_f16 v[24:27], v[144:147], v[166:169], v[24:27]
	v_mfma_f32_16x16x32_f16 v[40:43], v[194:197], v[166:169], v[40:43]
	v_mfma_f32_16x16x32_f16 v[52:55], v[198:201], v[166:169], v[52:55]
	ds_read_b128 v[144:147], v23 offset:34816
	ds_read_b128 v[162:165], v22
	ds_read_b128 v[166:169], v22 offset:2048
	ds_read_b128 v[194:197], v23 offset:36864
	ds_read_b128 v[198:201], v23 offset:38912
	s_waitcnt lgkmcnt(3)
	v_mfma_f32_16x16x32_f16 v[36:39], v[56:59], v[162:165], v[36:39]
	v_mfma_f32_16x16x32_f16 v[44:47], v[144:147], v[162:165], v[44:47]
	s_waitcnt lgkmcnt(1)
	v_mfma_f32_16x16x32_f16 v[132:135], v[194:197], v[162:165], v[132:135]
	s_waitcnt lgkmcnt(0)
	v_mfma_f32_16x16x32_f16 v[28:31], v[198:201], v[162:165], v[28:31]
	v_mfma_f32_16x16x32_f16 v[116:119], v[56:59], v[166:169], v[116:119]
	v_mfma_f32_16x16x32_f16 v[128:131], v[144:147], v[166:169], v[128:131]
	v_mfma_f32_16x16x32_f16 v[136:139], v[194:197], v[166:169], v[136:139]
	v_mfma_f32_16x16x32_f16 v[32:35], v[198:201], v[166:169], v[32:35]
	ds_read_b128 v[162:165], v22 offset:4096
	ds_read_b128 v[166:169], v22 offset:6144
	s_waitcnt vmcnt(7)
	ds_write_b128 v16, v[104:107] offset:16384
	s_waitcnt vmcnt(6)
	ds_write_b128 v17, v[0:3] offset:16384
	s_waitcnt vmcnt(5)
	ds_write_b128 v18, v[140:143] offset:16384
	s_waitcnt vmcnt(4)
	ds_write_b128 v19, v[4:7] offset:16384
	s_waitcnt vmcnt(3)
	ds_write_b128 v16, v[124:127] offset:49152
	s_waitcnt vmcnt(2)
	ds_write_b128 v17, v[8:11] offset:49152
	s_waitcnt vmcnt(1)
	ds_write_b128 v18, v[202:205] offset:49152
	s_waitcnt vmcnt(0)
	ds_write_b128 v19, v[12:15] offset:49152
	s_waitcnt lgkmcnt(0)
	v_mfma_f32_16x16x32_f16 v[154:157], v[56:59], v[162:165], v[154:157]
	s_barrier
	ds_read_b128 v[0:3], v20 offset:49152
	v_mfma_f32_16x16x32_f16 v[48:51], v[56:59], v[166:169], v[48:51]
	ds_read_b128 v[8:11], v20 offset:51200
	ds_read_b128 v[12:15], v21 offset:16384
	ds_read_b128 v[16:19], v21 offset:18432
	ds_read_b128 v[56:59], v20 offset:55296
	v_mfma_f32_16x16x32_f16 v[4:7], v[198:201], v[166:169], v[52:55]
	s_nop 2
	ds_read_b128 v[52:55], v20 offset:53248
	s_waitcnt lgkmcnt(3)
	v_mfma_f32_16x16x32_f16 v[36:39], v[0:3], v[12:15], v[36:39]
	v_mfma_f32_16x16x32_f16 v[44:47], v[8:11], v[12:15], v[44:47]
	s_waitcnt lgkmcnt(0)
	v_mfma_f32_16x16x32_f16 v[104:107], v[52:55], v[12:15], v[132:135]
	v_mfma_f32_16x16x32_f16 v[12:15], v[56:59], v[12:15], v[28:31]
	v_mfma_f32_16x16x32_f16 v[28:31], v[0:3], v[16:19], v[116:119]
	v_mfma_f32_16x16x32_f16 v[116:119], v[8:11], v[16:19], v[128:131]
	v_mfma_f32_16x16x32_f16 v[124:127], v[52:55], v[16:19], v[136:139]
	v_mfma_f32_16x16x32_f16 v[16:19], v[56:59], v[16:19], v[32:35]
	s_nop 2
	ds_read_b128 v[32:35], v21 offset:20480
	ds_read_b128 v[128:131], v21 offset:22528
	v_mfma_f32_16x16x32_f16 v[158:161], v[144:147], v[162:165], v[158:161]
	v_mfma_f32_16x16x32_f16 v[190:193], v[194:197], v[162:165], v[190:193]
	v_mfma_f32_16x16x32_f16 v[120:123], v[198:201], v[162:165], v[120:123]
	v_mfma_f32_16x16x32_f16 v[24:27], v[144:147], v[166:169], v[24:27]
	v_mfma_f32_16x16x32_f16 v[40:43], v[194:197], v[166:169], v[40:43]
	s_waitcnt lgkmcnt(1)
	v_mfma_f32_16x16x32_f16 v[132:135], v[0:3], v[32:35], v[154:157]
	v_mfma_f32_16x16x32_f16 v[136:139], v[8:11], v[32:35], v[158:161]
	s_nop 1
	ds_read_b128 v[154:157], v23 offset:49152
	v_mfma_f32_16x16x32_f16 v[140:143], v[52:55], v[32:35], v[190:193]
	v_mfma_f32_16x16x32_f16 v[120:123], v[56:59], v[32:35], v[120:123]
	s_waitcnt lgkmcnt(1)
	v_mfma_f32_16x16x32_f16 v[0:3], v[0:3], v[128:131], v[48:51]
	v_mfma_f32_16x16x32_f16 v[8:11], v[8:11], v[128:131], v[24:27]
	v_mfma_f32_16x16x32_f16 v[144:147], v[52:55], v[128:131], v[40:43]
	v_mfma_f32_16x16x32_f16 v[128:131], v[56:59], v[128:131], v[4:7]
	s_nop 2
	ds_read_b128 v[4:7], v23 offset:51200
	ds_read_b128 v[24:27], v22 offset:16384
	ds_read_b128 v[32:35], v22 offset:18432
	ds_read_b128 v[162:165], v23 offset:53248
	ds_read_b128 v[166:169], v23 offset:55296
	s_waitcnt lgkmcnt(0)
	v_mfma_f32_16x16x32_f16 v[48:51], v[166:169], v[24:27], v[12:15]
	v_mfma_f32_16x16x32_f16 v[40:43], v[4:7], v[32:35], v[116:119]
	s_nop 1
	ds_read_b128 v[12:15], v22 offset:20480
	ds_read_b128 v[116:119], v22 offset:22528
	s_waitcnt lgkmcnt(0)
	s_barrier
	s_setprio 0
	v_mfma_f32_16x16x32_f16 v[158:161], v[154:157], v[24:27], v[36:39]
	v_mfma_f32_16x16x32_f16 v[56:59], v[4:7], v[24:27], v[44:47]
	v_mfma_f32_16x16x32_f16 v[52:55], v[162:165], v[24:27], v[104:107]
	v_mfma_f32_16x16x32_f16 v[44:47], v[154:157], v[32:35], v[28:31]
	v_mfma_f32_16x16x32_f16 v[36:39], v[162:165], v[32:35], v[124:127]
	v_mfma_f32_16x16x32_f16 v[32:35], v[166:169], v[32:35], v[16:19]
	v_mfma_f32_16x16x32_f16 v[28:31], v[154:157], v[12:15], v[132:135]
	v_mfma_f32_16x16x32_f16 v[24:27], v[4:7], v[12:15], v[136:139]
	v_mfma_f32_16x16x32_f16 v[20:23], v[162:165], v[12:15], v[140:143]
	v_mfma_f32_16x16x32_f16 v[16:19], v[166:169], v[12:15], v[120:123]
	v_mfma_f32_16x16x32_f16 v[12:15], v[154:157], v[116:119], v[0:3]
	s_nop 2
	global_load_dwordx2 v[0:1], v[108:109], off offset:-64
	v_mfma_f32_16x16x32_f16 v[8:11], v[4:7], v[116:119], v[8:11]
	s_waitcnt vmcnt(0)
	v_cvt_f32_f16_e32 v2, v0
	v_cvt_f32_f16_sdwa v3, v0 dst_sel:DWORD dst_unused:UNUSED_PAD src0_sel:WORD_1
	v_cvt_f32_f16_e32 v0, v1
	v_cvt_f32_f16_sdwa v1, v1 dst_sel:DWORD dst_unused:UNUSED_PAD src0_sel:WORD_1
	v_mfma_f32_16x16x32_f16 v[4:7], v[162:165], v[116:119], v[144:147]
	v_mul_f32_e64 v104, v158, v2
	v_mul_f32_e64 v105, v159, v3
	v_pk_mul_f32 v[106:107], v[160:161], v[0:1]
	v_mfma_f32_16x16x32_f16 v[0:3], v[166:169], v[116:119], v[128:131]
	s_cbranch_vccnz .LBB0_1163
	v_cvt_f32_f16_sdwa v117, v102 dst_sel:DWORD dst_unused:UNUSED_PAD src0_sel:WORD_1
	v_cvt_f32_f16_e32 v116, v102
	v_pk_add_f32 v[104:105], v[104:105], v[116:117]
	v_cvt_f32_f16_sdwa v117, v103 dst_sel:DWORD dst_unused:UNUSED_PAD src0_sel:WORD_1
	v_cvt_f32_f16_e32 v116, v103
	v_pk_add_f32 v[106:107], v[106:107], v[116:117]

; DI int BIDX() { int b = blockIdx.x; asm volatile("" : "+s"(b)); return b; }
; #define GL_LOAD(s_, kt_) if (VAR != 1) { a##s_##0 = GL_A(0, kt_); a##s_##1 = GL_A(1, kt_); a##s_##2 = GL_A(2, kt_); a##s_##3 = GL_A(3, kt_); b##s_##0 = GL_B(0, kt_); b##s_##1 = GL_B(1, kt_); b##s_##2 = GL_B(2, kt_); b##s_##3 = GL_B(3, kt_); }
; #define LDS_STORE(s_, buf_) if (VAR != 2) { LDS_ST1(sA, 0, buf_, a##s_##0) LDS_ST1(sA, 1, buf_, a##s_##1) LDS_ST1(sA, 2, buf_, a##s_##2) LDS_ST1(sA, 3, buf_, a##s_##3) LDS_ST1(sB, 0, buf_, b##s_##0) LDS_ST1(sB, 1, buf_, b##s_##1) LDS_ST1(sB, 2, buf_, b##s_##2) LDS_ST1(sB, 3, buf_, b##s_##3) }
; DI int tile_groups(int MT, int NT) { return (MT >> 6) * ((NT + 7) >> 3) * 512; }
;     ...
;   GL_LOAD(0, 0)
;   GL_LOAD(1, 1)
;   LDS_STORE(0, 0)
;   if (VAR != 4) __syncthreads();
; #pragma unroll
;   for (int kt = 0; kt < nk; kt += 2) {
;     if (kt + 2 < nk) { GL_LOAD(0, kt + 2) }
;     MMA_TILE(0)
;     LDS_STORE(1, 1)
;     if (VAR != 4) __syncthreads();
; DI void phase_resgemm(const Params& P, const bf16_t* A, int K, const bf16_t* Wt, float* ssq_out, const float* xsrc, char* smem) {
;     ...
;   for (int vb = BIDX(); vb < tile_groups(128, 8); vb += gridDim.x) {
;     int tm, tn; if (!tile_of(vb, 128, 8, tm, tn)) continue;
;     const int m0 = tm * 128, n0 = tn * 128;
;     f32x4 acc[4][4]; zero_acc(acc);
;     if (K == 1024) gemm_kloop<false, true, 16>(acc, A + (size_t)m0 * K, K, Wt + (size_t)n0 * K, K, smem);
.LBB0_1249:
	s_ashr_i32 s6, s1, 3
	s_andn2_b32 s6, s6, 63
	s_and_b32 s7, s10, 56
	s_or_b32 s6, s6, s7
	s_bfe_u32 s7, s1, 0x30003
	s_or_b32 s6, s6, s7
	s_cmpk_gt_i32 s6, 0x7f
	s_cbranch_scc1 .LBB0_1248
	s_lshl_b32 s6, s6, 7
	s_ashr_i32 s7, s6, 31
	v_mov_b32_e32 v20, v148
	s_and_b32 s11, s9, 0x380
	s_lshl_b64 s[12:13], s[6:7], 11
	v_readlane_b32 s14, v253, 19
	v_readlane_b32 s15, v253, 20
	v_ashrrev_i32_e32 v16, 3, v20
	s_add_u32 s12, s14, s12
	v_ashrrev_i32_e32 v17, 31, v16
	v_add_u32_e32 v18, 32, v16
	s_addc_u32 s13, s15, s13
	v_lshlrev_b64 v[8:9], 11, v[16:17]
	v_lshlrev_b32_e32 v17, 4, v20
	v_ashrrev_i32_e32 v19, 31, v18
	v_add_u32_e32 v54, 64, v16
	s_waitcnt lgkmcnt(0)
	v_lshl_add_u64 v[0:1], s[12:13], 0, v[8:9]
	v_and_b32_e32 v150, 0x70, v17
	v_lshlrev_b64 v[10:11], 11, v[18:19]
	v_ashrrev_i32_e32 v55, 31, v54
	v_add_u32_e32 v58, 0x60, v16
	s_lshl_b32 s7, s11, 11
	v_lshl_add_u64 v[0:1], v[0:1], 0, v[150:151]
	v_lshl_add_u64 v[2:3], s[12:13], 0, v[10:11]
	v_lshlrev_b64 v[12:13], 11, v[54:55]
	v_ashrrev_i32_e32 v59, 31, v58
	s_add_u32 s14, s2, s7
	global_load_dwordx4 v[22:25], v[0:1], off
	v_lshl_add_u64 v[2:3], v[2:3], 0, v[150:151]
	v_lshl_add_u64 v[4:5], s[12:13], 0, v[12:13]
	v_lshlrev_b64 v[14:15], 11, v[58:59]
	s_addc_u32 s15, s8, 0
	global_load_dwordx4 v[26:29], v[2:3], off
	v_lshl_add_u64 v[4:5], v[4:5], 0, v[150:151]
	v_lshl_add_u64 v[6:7], s[12:13], 0, v[14:15]
	global_load_dwordx4 v[30:33], v[4:5], off
	v_lshl_add_u64 v[6:7], v[6:7], 0, v[150:151]
	v_lshl_add_u64 v[8:9], s[14:15], 0, v[8:9]
	global_load_dwordx4 v[34:37], v[6:7], off
	v_lshl_add_u64 v[8:9], v[8:9], 0, v[150:151]
	v_lshl_add_u64 v[10:11], s[14:15], 0, v[10:11]
	global_load_dwordx4 v[38:41], v[8:9], off
	v_lshl_add_u64 v[10:11], v[10:11], 0, v[150:151]
	v_lshl_add_u64 v[12:13], s[14:15], 0, v[12:13]
	global_load_dwordx4 v[42:45], v[10:11], off
	v_lshl_add_u64 v[12:13], v[12:13], 0, v[150:151]
	v_lshl_add_u64 v[14:15], s[14:15], 0, v[14:15]
	global_load_dwordx4 v[46:49], v[12:13], off
	v_lshl_add_u64 v[14:15], v[14:15], 0, v[150:151]
	global_load_dwordx4 v[50:53], v[14:15], off
	v_lshlrev_b32_e32 v21, 3, v20
	v_and_b32_e32 v55, 48, v20
	v_and_b32_e32 v19, 15, v20
	v_lshrrev_b32_e32 v59, 1, v20
	s_waitcnt vmcnt(10)
	v_lshlrev_b32_e32 v60, 7, v20
	v_and_b32_e32 v90, 0x70, v21
	v_bitop3_b32 v134, v21, v55, s23 bitop3:0x6c
	v_bitop3_b32 v21, v17, s23, v20 bitop3:0x48
	v_and_or_b32 v91, v59, s24, v19
	v_and_b32_e32 v130, 0x2780, v60
	v_lshl_or_b32 v20, v18, 7, v21
	v_lshl_or_b32 v18, v58, 7, v21
	global_load_dwordx4 v[58:61], v[0:1], off offset:128
	global_load_dwordx4 v[62:65], v[2:3], off offset:128
	global_load_dwordx4 v[66:69], v[4:5], off offset:128
	global_load_dwordx4 v[70:73], v[6:7], off offset:128
	global_load_dwordx4 v[74:77], v[8:9], off offset:128
	global_load_dwordx4 v[78:81], v[10:11], off offset:128
	global_load_dwordx4 v[82:85], v[12:13], off offset:128
	global_load_dwordx4 v[86:89], v[14:15], off offset:128
	v_lshl_or_b32 v19, v16, 7, v21
	v_or_b32_e32 v16, v130, v134
	v_lshl_or_b32 v17, v54, 7, v21
	v_lshlrev_b32_e32 v54, 7, v91
	v_bitop3_b32 v21, v54, v90, v55 bitop3:0xf6
	v_readlane_b32 s12, v254, 55
	v_readlane_b32 s13, v254, 56
	v_readlane_b32 s14, v254, 57
	v_readlane_b32 s15, v254, 58
	s_waitcnt vmcnt(15)
	ds_write_b128 v19, v[22:25]
	s_waitcnt vmcnt(14)
	ds_write_b128 v20, v[26:29]
	s_waitcnt vmcnt(13)
	ds_write_b128 v17, v[30:33]
	s_waitcnt vmcnt(12)
	ds_write_b128 v18, v[34:37]
	s_waitcnt vmcnt(11)
	ds_write_b128 v19, v[38:41] offset:32768
	s_waitcnt vmcnt(10)
	ds_write_b128 v20, v[42:45] offset:32768
	s_waitcnt vmcnt(9)
	ds_write_b128 v17, v[46:49] offset:32768
	s_waitcnt vmcnt(8)
	ds_write_b128 v18, v[50:53] offset:32768
	s_waitcnt lgkmcnt(0)
	s_barrier
	s_setprio 1
	ds_read_b128 v[22:25], v16 offset:32768
	ds_read_b128 v[30:33], v21
	s_waitcnt lgkmcnt(0)
	v_mfma_f32_16x16x32_f16 v[38:41], v[22:25], v[30:33], 0
	ds_read_b128 v[26:29], v16 offset:34816
	ds_read_b128 v[34:37], v21 offset:2048
	s_waitcnt lgkmcnt(0)
	v_mfma_f32_16x16x32_f16 v[94:97], v[22:25], v[34:37], 0
	ds_read_b128 v[42:45], v16 offset:36864
	ds_read_b128 v[106:109], v21 offset:4096
	s_waitcnt lgkmcnt(0)
	v_mfma_f32_16x16x32_f16 v[114:117], v[22:25], v[106:109], 0
	ds_read_b128 v[50:53], v16 offset:38912
	ds_read_b128 v[110:113], v21 offset:6144
	s_waitcnt lgkmcnt(0)
	v_mfma_f32_16x16x32_f16 v[126:129], v[22:25], v[110:113], 0
	v_xor_b32_e32 v22, 64, v134
	v_mfma_f32_16x16x32_f16 v[46:49], v[26:29], v[30:33], 0
	v_or_b32_e32 v22, v130, v22
	v_mfma_f32_16x16x32_f16 v[90:93], v[42:45], v[30:33], 0
	ds_read_b128 v[130:133], v22 offset:32768
	v_mfma_f32_16x16x32_f16 v[30:33], v[50:53], v[30:33], 0
	ds_read_b128 v[142:145], v22 offset:36864
	v_mfma_f32_16x16x32_f16 v[98:101], v[26:29], v[34:37], 0
	ds_read_b128 v[154:157], v22 offset:38912
	v_mfma_f32_16x16x32_f16 v[102:105], v[42:45], v[34:37], 0
	v_bitop3_b32 v23, v54, v134, 64 bitop3:0xf6
	v_mfma_f32_16x16x32_f16 v[34:37], v[50:53], v[34:37], 0
	ds_read_b128 v[134:137], v23
	v_mfma_f32_16x16x32_f16 v[118:121], v[26:29], v[106:109], 0
	ds_read_b128 v[138:141], v23 offset:2048
	v_mfma_f32_16x16x32_f16 v[122:125], v[42:45], v[106:109], 0
	v_mfma_f32_16x16x32_f16 v[106:109], v[50:53], v[106:109], 0
	s_waitcnt vmcnt(7)
	ds_write_b128 v19, v[58:61] offset:16384
	v_mfma_f32_16x16x32_f16 v[24:27], v[26:29], v[110:113], 0
	s_waitcnt vmcnt(6)
	ds_write_b128 v20, v[62:65] offset:16384
	v_mfma_f32_16x16x32_f16 v[42:45], v[42:45], v[110:113], 0
	s_waitcnt vmcnt(5)
	ds_write_b128 v17, v[66:69] offset:16384
	v_mfma_f32_16x16x32_f16 v[50:53], v[50:53], v[110:113], 0
	ds_read_b128 v[110:113], v22 offset:34816
	s_waitcnt lgkmcnt(5)
; #define GL_LOAD(s_, kt_) if (VAR != 1) { a##s_##0 = GL_A(0, kt_); a##s_##1 = GL_A(1, kt_); a##s_##2 = GL_A(2, kt_); a##s_##3 = GL_A(3, kt_); b##s_##0 = GL_B(0, kt_); b##s_##1 = GL_B(1, kt_); b##s_##2 = GL_B(2, kt_); b##s_##3 = GL_B(3, kt_); }
; #define LDS_STORE(s_, buf_) if (VAR != 2) { LDS_ST1(sA, 0, buf_, a##s_##0) LDS_ST1(sA, 1, buf_, a##s_##1) LDS_ST1(sA, 2, buf_, a##s_##2) LDS_ST1(sA, 3, buf_, a##s_##3) LDS_ST1(sB, 0, buf_, b##s_##0) LDS_ST1(sB, 1, buf_, b##s_##1) LDS_ST1(sB, 2, buf_, b##s_##2) LDS_ST1(sB, 3, buf_, b##s_##3) }
;     ...
;   for (int kt = 0; kt < nk; kt += 2) {
;     if (kt + 2 < nk) { GL_LOAD(0, kt + 2) }
;     MMA_TILE(0)
;     LDS_STORE(1, 1)
;     if (VAR != 4) __syncthreads();
;     if (kt + 3 < nk) { GL_LOAD(1, kt + 3) }
;     MMA_TILE(1)
;     if (kt + 2 < nk) { LDS_STORE(0, 0) }
;     if (VAR != 4) __syncthreads();
	v_mfma_f32_16x16x32_f16 v[38:41], v[130:133], v[134:137], v[38:41]
	s_waitcnt vmcnt(4)
	ds_write_b128 v18, v[70:73] offset:16384
	v_mfma_f32_16x16x32_f16 v[90:93], v[142:145], v[134:137], v[90:93]
	s_waitcnt vmcnt(3)
	ds_write_b128 v19, v[74:77] offset:49152
	v_mfma_f32_16x16x32_f16 v[28:31], v[154:157], v[134:137], v[30:33]
	s_waitcnt vmcnt(2)
	ds_write_b128 v20, v[78:81] offset:49152
	s_waitcnt lgkmcnt(7)
	v_mfma_f32_16x16x32_f16 v[94:97], v[130:133], v[138:141], v[94:97]
	s_waitcnt vmcnt(1)
	ds_write_b128 v17, v[82:85] offset:49152
	v_mfma_f32_16x16x32_f16 v[102:105], v[142:145], v[138:141], v[102:105]
	s_waitcnt vmcnt(0)
	ds_write_b128 v18, v[86:89] offset:49152
	v_mfma_f32_16x16x32_f16 v[32:35], v[154:157], v[138:141], v[34:37]
	s_waitcnt lgkmcnt(5)
	v_mfma_f32_16x16x32_f16 v[46:49], v[110:113], v[134:137], v[46:49]
	ds_read_b128 v[134:137], v23 offset:4096
	v_mfma_f32_16x16x32_f16 v[98:101], v[110:113], v[138:141], v[98:101]
	ds_read_b128 v[138:141], v23 offset:6144
	s_waitcnt lgkmcnt(1)
	v_mfma_f32_16x16x32_f16 v[114:117], v[130:133], v[134:137], v[114:117]
	s_waitcnt lgkmcnt(0)
	v_mfma_f32_16x16x32_f16 v[126:129], v[130:133], v[138:141], v[126:129]
	global_load_dwordx4 v[130:133], v[0:1], off offset:256
	v_mfma_f32_16x16x32_f16 v[118:121], v[110:113], v[134:137], v[118:121]
	v_mfma_f32_16x16x32_f16 v[24:27], v[110:113], v[138:141], v[24:27]
	v_mfma_f32_16x16x32_f16 v[122:125], v[142:145], v[134:137], v[122:125]
	v_mfma_f32_16x16x32_f16 v[106:109], v[154:157], v[134:137], v[106:109]
	global_load_dwordx4 v[134:137], v[2:3], off offset:256
	global_load_dwordx4 v[158:161], v[4:5], off offset:256
	global_load_dwordx4 v[162:165], v[6:7], off offset:256
	global_load_dwordx4 v[110:113], v[8:9], off offset:256
	global_load_dwordx4 v[166:169], v[10:11], off offset:256
	global_load_dwordx4 v[190:193], v[12:13], off offset:256
	global_load_dwordx4 v[194:197], v[14:15], off offset:256
	s_waitcnt lgkmcnt(0)
	s_barrier
	v_mfma_f32_16x16x32_f16 v[42:45], v[142:145], v[138:141], v[42:45]
	ds_read_b128 v[58:61], v16 offset:49152
	v_mfma_f32_16x16x32_f16 v[50:53], v[154:157], v[138:141], v[50:53]
	ds_read_b128 v[62:65], v16 offset:51200
	ds_read_b128 v[66:69], v21 offset:16384
	s_waitcnt lgkmcnt(0)
	v_mfma_f32_16x16x32_f16 v[36:39], v[58:61], v[66:69], v[38:41]
	ds_read_b128 v[70:73], v21 offset:18432
	v_mfma_f32_16x16x32_f16 v[46:49], v[62:65], v[66:69], v[46:49]
	ds_read_b128 v[74:77], v16 offset:53248
	s_waitcnt lgkmcnt(0)
	v_mfma_f32_16x16x32_f16 v[82:85], v[74:77], v[66:69], v[90:93]
	ds_read_b128 v[78:81], v16 offset:55296
	s_waitcnt lgkmcnt(0)
	v_mfma_f32_16x16x32_f16 v[28:31], v[78:81], v[66:69], v[28:31]
	v_mfma_f32_16x16x32_f16 v[66:69], v[58:61], v[70:73], v[94:97]
	s_nop 2
	ds_read_b128 v[94:97], v21 offset:22528
	v_mfma_f32_16x16x32_f16 v[86:89], v[62:65], v[70:73], v[98:101]
	v_mfma_f32_16x16x32_f16 v[90:93], v[74:77], v[70:73], v[102:105]
	v_mfma_f32_16x16x32_f16 v[32:35], v[78:81], v[70:73], v[32:35]
	ds_read_b128 v[70:73], v21 offset:20480
	s_waitcnt lgkmcnt(0)
	v_mfma_f32_16x16x32_f16 v[98:101], v[58:61], v[70:73], v[114:117]
	v_mfma_f32_16x16x32_f16 v[58:61], v[58:61], v[94:97], v[126:129]
	v_mfma_f32_16x16x32_f16 v[102:105], v[62:65], v[70:73], v[118:121]
	s_nop 2
	ds_read_b128 v[118:121], v22 offset:55296
	v_mfma_f32_16x16x32_f16 v[24:27], v[62:65], v[94:97], v[24:27]
	ds_read_b128 v[62:65], v22 offset:49152
	s_waitcnt vmcnt(7)
	ds_write_b128 v19, v[130:133]
	v_mfma_f32_16x16x32_f16 v[114:117], v[74:77], v[70:73], v[122:125]
	s_waitcnt vmcnt(6)
	ds_write_b128 v20, v[134:137]
	s_waitcnt vmcnt(5)
	ds_write_b128 v17, v[158:161]
	v_mfma_f32_16x16x32_f16 v[40:43], v[74:77], v[94:97], v[42:45]
	ds_read_b128 v[74:77], v22 offset:51200
	v_mfma_f32_16x16x32_f16 v[70:73], v[78:81], v[70:73], v[106:109]
	s_nop 2
	ds_read_b128 v[106:109], v22 offset:53248
	v_mfma_f32_16x16x32_f16 v[50:53], v[78:81], v[94:97], v[50:53]
	ds_read_b128 v[78:81], v23 offset:16384
	s_waitcnt lgkmcnt(0)
	v_mfma_f32_16x16x32_f16 v[36:39], v[62:65], v[78:81], v[36:39]
	ds_read_b128 v[94:97], v23 offset:18432
	s_waitcnt lgkmcnt(0)
	v_mfma_f32_16x16x32_f16 v[66:69], v[62:65], v[94:97], v[66:69]
	s_waitcnt vmcnt(4)
	ds_write_b128 v18, v[162:165]
	v_mfma_f32_16x16x32_f16 v[44:47], v[74:77], v[78:81], v[46:49]
	s_waitcnt vmcnt(3)
	ds_write_b128 v19, v[110:113] offset:32768
	v_mfma_f32_16x16x32_f16 v[82:85], v[106:109], v[78:81], v[82:85]
	v_mfma_f32_16x16x32_f16 v[28:31], v[118:121], v[78:81], v[28:31]
	v_mfma_f32_16x16x32_f16 v[78:81], v[74:77], v[94:97], v[86:89]
	s_waitcnt vmcnt(2)
	ds_write_b128 v20, v[166:169] offset:32768
	s_waitcnt vmcnt(1)
	ds_write_b128 v17, v[190:193] offset:32768
	s_waitcnt vmcnt(0)
	ds_write_b128 v18, v[194:197] offset:32768
	v_mfma_f32_16x16x32_f16 v[86:89], v[106:109], v[94:97], v[90:93]
	s_nop 2
	ds_read_b128 v[90:93], v23 offset:20480
	v_mfma_f32_16x16x32_f16 v[32:35], v[118:121], v[94:97], v[32:35]
	ds_read_b128 v[94:97], v23 offset:22528
	s_waitcnt lgkmcnt(1)
	v_mfma_f32_16x16x32_f16 v[98:101], v[62:65], v[90:93], v[98:101]
	s_waitcnt lgkmcnt(0)
	v_mfma_f32_16x16x32_f16 v[58:61], v[62:65], v[94:97], v[58:61]
	global_load_dwordx4 v[62:65], v[0:1], off offset:384
	v_mfma_f32_16x16x32_f16 v[102:105], v[74:77], v[90:93], v[102:105]
	v_mfma_f32_16x16x32_f16 v[24:27], v[74:77], v[94:97], v[24:27]
	v_mfma_f32_16x16x32_f16 v[114:117], v[106:109], v[90:93], v[114:117]
	v_mfma_f32_16x16x32_f16 v[40:43], v[106:109], v[94:97], v[40:43]
	v_mfma_f32_16x16x32_f16 v[70:73], v[118:121], v[90:93], v[70:73]
	global_load_dwordx4 v[90:93], v[2:3], off offset:384
	global_load_dwordx4 v[122:125], v[4:5], off offset:384
	global_load_dwordx4 v[126:129], v[6:7], off offset:384
	global_load_dwordx4 v[74:77], v[8:9], off offset:384
	global_load_dwordx4 v[138:141], v[10:11], off offset:384
	global_load_dwordx4 v[142:145], v[12:13], off offset:384
	global_load_dwordx4 v[154:157], v[14:15], off offset:384
	s_waitcnt lgkmcnt(0)
	s_barrier
; #define GL_LOAD(s_, kt_) if (VAR != 1) { a##s_##0 = GL_A(0, kt_); a##s_##1 = GL_A(1, kt_); a##s_##2 = GL_A(2, kt_); a##s_##3 = GL_A(3, kt_); b##s_##0 = GL_B(0, kt_); b##s_##1 = GL_B(1, kt_); b##s_##2 = GL_B(2, kt_); b##s_##3 = GL_B(3, kt_); }
; #define LDS_STORE(s_, buf_) if (VAR != 2) { LDS_ST1(sA, 0, buf_, a##s_##0) LDS_ST1(sA, 1, buf_, a##s_##1) LDS_ST1(sA, 2, buf_, a##s_##2) LDS_ST1(sA, 3, buf_, a##s_##3) LDS_ST1(sB, 0, buf_, b##s_##0) LDS_ST1(sB, 1, buf_, b##s_##1) LDS_ST1(sB, 2, buf_, b##s_##2) LDS_ST1(sB, 3, buf_, b##s_##3) }
;     ...
;   for (int kt = 0; kt < nk; kt += 2) {
;     if (kt + 2 < nk) { GL_LOAD(0, kt + 2) }
;     MMA_TILE(0)
;     LDS_STORE(1, 1)
;     if (VAR != 4) __syncthreads();
;     if (kt + 3 < nk) { GL_LOAD(1, kt + 3) }
;     MMA_TILE(1)
;     if (kt + 2 < nk) { LDS_STORE(0, 0) }
;     if (VAR != 4) __syncthreads();
	v_mfma_f32_16x16x32_f16 v[48:51], v[118:121], v[94:97], v[50:53]
	ds_read_b128 v[106:109], v16 offset:32768
	ds_read_b128 v[94:97], v21
	s_waitcnt lgkmcnt(0)
	v_mfma_f32_16x16x32_f16 v[36:39], v[106:109], v[94:97], v[36:39]
	ds_read_b128 v[52:55], v16 offset:34816
	ds_read_b128 v[110:113], v21 offset:2048
	s_waitcnt lgkmcnt(0)
	v_mfma_f32_16x16x32_f16 v[66:69], v[106:109], v[110:113], v[66:69]
	ds_read_b128 v[118:121], v16 offset:36864
	v_mfma_f32_16x16x32_f16 v[44:47], v[52:55], v[94:97], v[44:47]
	ds_read_b128 v[130:133], v16 offset:38912
	v_mfma_f32_16x16x32_f16 v[78:81], v[52:55], v[110:113], v[78:81]
	s_waitcnt lgkmcnt(1)
	v_mfma_f32_16x16x32_f16 v[82:85], v[118:121], v[94:97], v[82:85]
	v_mfma_f32_16x16x32_f16 v[86:89], v[118:121], v[110:113], v[86:89]
	s_waitcnt lgkmcnt(0)
	v_mfma_f32_16x16x32_f16 v[28:31], v[130:133], v[94:97], v[28:31]
	ds_read_b128 v[94:97], v21 offset:4096
	v_mfma_f32_16x16x32_f16 v[32:35], v[130:133], v[110:113], v[32:35]
	ds_read_b128 v[110:113], v21 offset:6144
	s_waitcnt lgkmcnt(1)
	v_mfma_f32_16x16x32_f16 v[98:101], v[106:109], v[94:97], v[98:101]
	s_waitcnt lgkmcnt(0)
	v_mfma_f32_16x16x32_f16 v[58:61], v[106:109], v[110:113], v[58:61]
	ds_read_b128 v[106:109], v23
	v_mfma_f32_16x16x32_f16 v[102:105], v[52:55], v[94:97], v[102:105]
	v_mfma_f32_16x16x32_f16 v[24:27], v[52:55], v[110:113], v[24:27]
	ds_read_b128 v[52:55], v22 offset:32768
	v_mfma_f32_16x16x32_f16 v[114:117], v[118:121], v[94:97], v[114:117]
	s_waitcnt vmcnt(7)
	ds_write_b128 v19, v[62:65] offset:16384
	s_waitcnt vmcnt(6)
	ds_write_b128 v20, v[90:93] offset:16384
	v_mfma_f32_16x16x32_f16 v[40:43], v[118:121], v[110:113], v[40:43]
	ds_read_b128 v[118:121], v22 offset:36864
	s_waitcnt vmcnt(5)
	ds_write_b128 v17, v[122:125] offset:16384
	v_mfma_f32_16x16x32_f16 v[70:73], v[130:133], v[94:97], v[70:73]
	ds_read_b128 v[94:97], v22 offset:34816
	v_mfma_f32_16x16x32_f16 v[48:51], v[130:133], v[110:113], v[48:51]
	ds_read_b128 v[110:113], v23 offset:2048
	s_waitcnt lgkmcnt(6)
	v_mfma_f32_16x16x32_f16 v[36:39], v[52:55], v[106:109], v[36:39]
	ds_read_b128 v[130:133], v22 offset:38912
	s_waitcnt lgkmcnt(1)
	v_mfma_f32_16x16x32_f16 v[66:69], v[52:55], v[110:113], v[66:69]
	s_waitcnt vmcnt(4)
	ds_write_b128 v18, v[126:129] offset:16384
	v_mfma_f32_16x16x32_f16 v[44:47], v[94:97], v[106:109], v[44:47]
	s_waitcnt vmcnt(3)
	ds_write_b128 v19, v[74:77] offset:49152
	v_mfma_f32_16x16x32_f16 v[78:81], v[94:97], v[110:113], v[78:81]
	s_waitcnt vmcnt(2)
	ds_write_b128 v20, v[138:141] offset:49152
	v_mfma_f32_16x16x32_f16 v[82:85], v[118:121], v[106:109], v[82:85]
	s_waitcnt vmcnt(1)
	ds_write_b128 v17, v[142:145] offset:49152
	v_mfma_f32_16x16x32_f16 v[86:89], v[118:121], v[110:113], v[86:89]
	s_waitcnt vmcnt(0)
	ds_write_b128 v18, v[154:157] offset:49152
	s_waitcnt lgkmcnt(5)
	v_mfma_f32_16x16x32_f16 v[28:31], v[130:133], v[106:109], v[28:31]
	ds_read_b128 v[106:109], v23 offset:4096
	v_mfma_f32_16x16x32_f16 v[32:35], v[130:133], v[110:113], v[32:35]
	ds_read_b128 v[110:113], v23 offset:6144
	s_waitcnt lgkmcnt(1)
	v_mfma_f32_16x16x32_f16 v[98:101], v[52:55], v[106:109], v[98:101]
	s_waitcnt lgkmcnt(0)
	v_mfma_f32_16x16x32_f16 v[52:55], v[52:55], v[110:113], v[58:61]
	s_nop 2
	global_load_dwordx4 v[58:61], v[0:1], off offset:512
	v_mfma_f32_16x16x32_f16 v[102:105], v[94:97], v[106:109], v[102:105]
	v_mfma_f32_16x16x32_f16 v[24:27], v[94:97], v[110:113], v[24:27]
	v_mfma_f32_16x16x32_f16 v[114:117], v[118:121], v[106:109], v[114:117]
	v_mfma_f32_16x16x32_f16 v[40:43], v[118:121], v[110:113], v[40:43]
	v_mfma_f32_16x16x32_f16 v[70:73], v[130:133], v[106:109], v[70:73]
	global_load_dwordx4 v[106:109], v[2:3], off offset:512
	global_load_dwordx4 v[134:137], v[4:5], off offset:512
	global_load_dwordx4 v[158:161], v[6:7], off offset:512
	global_load_dwordx4 v[94:97], v[8:9], off offset:512
	global_load_dwordx4 v[162:165], v[10:11], off offset:512
	global_load_dwordx4 v[166:169], v[12:13], off offset:512
	global_load_dwordx4 v[190:193], v[14:15], off offset:512
	s_waitcnt lgkmcnt(0)
	s_barrier
	v_mfma_f32_16x16x32_f16 v[48:51], v[130:133], v[110:113], v[48:51]
	ds_read_b128 v[62:65], v16 offset:49152
	ds_read_b128 v[90:93], v21 offset:16384
	s_waitcnt lgkmcnt(0)
	v_mfma_f32_16x16x32_f16 v[36:39], v[62:65], v[90:93], v[36:39]
	ds_read_b128 v[74:77], v16 offset:51200
	ds_read_b128 v[110:113], v21 offset:18432
	s_waitcnt lgkmcnt(0)
	v_mfma_f32_16x16x32_f16 v[66:69], v[62:65], v[110:113], v[66:69]
	ds_read_b128 v[118:121], v16 offset:53248
	v_mfma_f32_16x16x32_f16 v[44:47], v[74:77], v[90:93], v[44:47]
	ds_read_b128 v[122:125], v16 offset:55296
	v_mfma_f32_16x16x32_f16 v[78:81], v[74:77], v[110:113], v[78:81]
	s_waitcnt lgkmcnt(1)
	v_mfma_f32_16x16x32_f16 v[82:85], v[118:121], v[90:93], v[82:85]
	v_mfma_f32_16x16x32_f16 v[86:89], v[118:121], v[110:113], v[86:89]
	s_waitcnt lgkmcnt(0)
	v_mfma_f32_16x16x32_f16 v[28:31], v[122:125], v[90:93], v[28:31]
	ds_read_b128 v[90:93], v21 offset:20480
	v_mfma_f32_16x16x32_f16 v[32:35], v[122:125], v[110:113], v[32:35]
	ds_read_b128 v[110:113], v21 offset:22528
	s_waitcnt lgkmcnt(1)
	v_mfma_f32_16x16x32_f16 v[98:101], v[62:65], v[90:93], v[98:101]
	s_waitcnt lgkmcnt(0)
	v_mfma_f32_16x16x32_f16 v[52:55], v[62:65], v[110:113], v[52:55]
	ds_read_b128 v[62:65], v22 offset:49152
	v_mfma_f32_16x16x32_f16 v[102:105], v[74:77], v[90:93], v[102:105]
	v_mfma_f32_16x16x32_f16 v[24:27], v[74:77], v[110:113], v[24:27]
	ds_read_b128 v[74:77], v22 offset:51200
	v_mfma_f32_16x16x32_f16 v[114:117], v[118:121], v[90:93], v[114:117]
	s_waitcnt vmcnt(7)
	ds_write_b128 v19, v[58:61]
	s_waitcnt vmcnt(6)
; #define GL_LOAD(s_, kt_) if (VAR != 1) { a##s_##0 = GL_A(0, kt_); a##s_##1 = GL_A(1, kt_); a##s_##2 = GL_A(2, kt_); a##s_##3 = GL_A(3, kt_); b##s_##0 = GL_B(0, kt_); b##s_##1 = GL_B(1, kt_); b##s_##2 = GL_B(2, kt_); b##s_##3 = GL_B(3, kt_); }
; #define LDS_STORE(s_, buf_) if (VAR != 2) { LDS_ST1(sA, 0, buf_, a##s_##0) LDS_ST1(sA, 1, buf_, a##s_##1) LDS_ST1(sA, 2, buf_, a##s_##2) LDS_ST1(sA, 3, buf_, a##s_##3) LDS_ST1(sB, 0, buf_, b##s_##0) LDS_ST1(sB, 1, buf_, b##s_##1) LDS_ST1(sB, 2, buf_, b##s_##2) LDS_ST1(sB, 3, buf_, b##s_##3) }
;     ...
;   for (int kt = 0; kt < nk; kt += 2) {
;     if (kt + 2 < nk) { GL_LOAD(0, kt + 2) }
;     MMA_TILE(0)
;     LDS_STORE(1, 1)
;     if (VAR != 4) __syncthreads();
;     if (kt + 3 < nk) { GL_LOAD(1, kt + 3) }
;     MMA_TILE(1)
;     if (kt + 2 < nk) { LDS_STORE(0, 0) }
;     if (VAR != 4) __syncthreads();
	ds_write_b128 v20, v[106:109]
	v_mfma_f32_16x16x32_f16 v[40:43], v[118:121], v[110:113], v[40:43]
	ds_read_b128 v[118:121], v22 offset:53248
	s_waitcnt vmcnt(5)
	ds_write_b128 v17, v[134:137]
	v_mfma_f32_16x16x32_f16 v[70:73], v[122:125], v[90:93], v[70:73]
	ds_read_b128 v[90:93], v23 offset:16384
	v_mfma_f32_16x16x32_f16 v[48:51], v[122:125], v[110:113], v[48:51]
	ds_read_b128 v[110:113], v23 offset:18432
	s_waitcnt lgkmcnt(1)
	v_mfma_f32_16x16x32_f16 v[36:39], v[62:65], v[90:93], v[36:39]
	ds_read_b128 v[122:125], v22 offset:55296
	s_waitcnt lgkmcnt(1)
	v_mfma_f32_16x16x32_f16 v[66:69], v[62:65], v[110:113], v[66:69]
	s_waitcnt vmcnt(4)
	ds_write_b128 v18, v[158:161]
	v_mfma_f32_16x16x32_f16 v[44:47], v[74:77], v[90:93], v[44:47]
	s_waitcnt vmcnt(3)
	ds_write_b128 v19, v[94:97] offset:32768
	v_mfma_f32_16x16x32_f16 v[78:81], v[74:77], v[110:113], v[78:81]
	s_waitcnt vmcnt(2)
	ds_write_b128 v20, v[162:165] offset:32768
	v_mfma_f32_16x16x32_f16 v[82:85], v[118:121], v[90:93], v[82:85]
	s_waitcnt vmcnt(1)
	ds_write_b128 v17, v[166:169] offset:32768
	v_mfma_f32_16x16x32_f16 v[86:89], v[118:121], v[110:113], v[86:89]
	s_waitcnt vmcnt(0)
	ds_write_b128 v18, v[190:193] offset:32768
	s_waitcnt lgkmcnt(5)
	v_mfma_f32_16x16x32_f16 v[28:31], v[122:125], v[90:93], v[28:31]
	ds_read_b128 v[90:93], v23 offset:20480
	v_mfma_f32_16x16x32_f16 v[32:35], v[122:125], v[110:113], v[32:35]
	ds_read_b128 v[110:113], v23 offset:22528
	s_waitcnt lgkmcnt(1)
	v_mfma_f32_16x16x32_f16 v[98:101], v[62:65], v[90:93], v[98:101]
	s_waitcnt lgkmcnt(0)
	v_mfma_f32_16x16x32_f16 v[52:55], v[62:65], v[110:113], v[52:55]
	global_load_dwordx4 v[62:65], v[0:1], off offset:640
	v_mfma_f32_16x16x32_f16 v[102:105], v[74:77], v[90:93], v[102:105]
	v_mfma_f32_16x16x32_f16 v[24:27], v[74:77], v[110:113], v[24:27]
	v_mfma_f32_16x16x32_f16 v[114:117], v[118:121], v[90:93], v[114:117]
	v_mfma_f32_16x16x32_f16 v[40:43], v[118:121], v[110:113], v[40:43]
	v_mfma_f32_16x16x32_f16 v[70:73], v[122:125], v[90:93], v[70:73]
	global_load_dwordx4 v[90:93], v[2:3], off offset:640
	global_load_dwordx4 v[126:129], v[4:5], off offset:640
	global_load_dwordx4 v[130:133], v[6:7], off offset:640
	global_load_dwordx4 v[74:77], v[8:9], off offset:640
	global_load_dwordx4 v[138:141], v[10:11], off offset:640
	global_load_dwordx4 v[142:145], v[12:13], off offset:640
	global_load_dwordx4 v[154:157], v[14:15], off offset:640
	s_waitcnt lgkmcnt(0)
	s_barrier
	v_mfma_f32_16x16x32_f16 v[48:51], v[122:125], v[110:113], v[48:51]
	ds_read_b128 v[58:61], v16 offset:32768
	ds_read_b128 v[106:109], v21
	s_waitcnt lgkmcnt(0)
	v_mfma_f32_16x16x32_f16 v[36:39], v[58:61], v[106:109], v[36:39]
	ds_read_b128 v[94:97], v16 offset:34816
	ds_read_b128 v[110:113], v21 offset:2048
	s_waitcnt lgkmcnt(0)
	v_mfma_f32_16x16x32_f16 v[66:69], v[58:61], v[110:113], v[66:69]
	ds_read_b128 v[118:121], v16 offset:36864
	v_mfma_f32_16x16x32_f16 v[44:47], v[94:97], v[106:109], v[44:47]
	ds_read_b128 v[122:125], v16 offset:38912
	v_mfma_f32_16x16x32_f16 v[78:81], v[94:97], v[110:113], v[78:81]
	s_waitcnt lgkmcnt(1)
	v_mfma_f32_16x16x32_f16 v[82:85], v[118:121], v[106:109], v[82:85]
	v_mfma_f32_16x16x32_f16 v[86:89], v[118:121], v[110:113], v[86:89]
	s_waitcnt lgkmcnt(0)
	v_mfma_f32_16x16x32_f16 v[28:31], v[122:125], v[106:109], v[28:31]
	ds_read_b128 v[106:109], v21 offset:4096
	v_mfma_f32_16x16x32_f16 v[32:35], v[122:125], v[110:113], v[32:35]
	ds_read_b128 v[110:113], v21 offset:6144
	s_waitcnt lgkmcnt(1)
	v_mfma_f32_16x16x32_f16 v[98:101], v[58:61], v[106:109], v[98:101]
	s_waitcnt lgkmcnt(0)
	v_mfma_f32_16x16x32_f16 v[52:55], v[58:61], v[110:113], v[52:55]
	ds_read_b128 v[58:61], v22 offset:32768
	v_mfma_f32_16x16x32_f16 v[102:105], v[94:97], v[106:109], v[102:105]
	v_mfma_f32_16x16x32_f16 v[24:27], v[94:97], v[110:113], v[24:27]
	ds_read_b128 v[94:97], v22 offset:34816
	v_mfma_f32_16x16x32_f16 v[114:117], v[118:121], v[106:109], v[114:117]
	s_waitcnt vmcnt(7)
	ds_write_b128 v19, v[62:65] offset:16384
	s_waitcnt vmcnt(6)
	ds_write_b128 v20, v[90:93] offset:16384
	v_mfma_f32_16x16x32_f16 v[40:43], v[118:121], v[110:113], v[40:43]
	ds_read_b128 v[118:121], v22 offset:36864
	s_waitcnt vmcnt(5)
	ds_write_b128 v17, v[126:129] offset:16384
	v_mfma_f32_16x16x32_f16 v[70:73], v[122:125], v[106:109], v[70:73]
	ds_read_b128 v[106:109], v23
	v_mfma_f32_16x16x32_f16 v[48:51], v[122:125], v[110:113], v[48:51]
	ds_read_b128 v[110:113], v23 offset:2048
	s_waitcnt lgkmcnt(1)
	v_mfma_f32_16x16x32_f16 v[36:39], v[58:61], v[106:109], v[36:39]
	ds_read_b128 v[122:125], v22 offset:38912
	s_waitcnt lgkmcnt(1)
	v_mfma_f32_16x16x32_f16 v[66:69], v[58:61], v[110:113], v[66:69]
	s_waitcnt vmcnt(4)
	ds_write_b128 v18, v[130:133] offset:16384
	v_mfma_f32_16x16x32_f16 v[44:47], v[94:97], v[106:109], v[44:47]
	s_waitcnt vmcnt(3)
	ds_write_b128 v19, v[74:77] offset:49152
	v_mfma_f32_16x16x32_f16 v[78:81], v[94:97], v[110:113], v[78:81]
	s_waitcnt vmcnt(2)
	ds_write_b128 v20, v[138:141] offset:49152
	v_mfma_f32_16x16x32_f16 v[82:85], v[118:121], v[106:109], v[82:85]
	s_waitcnt vmcnt(1)
	ds_write_b128 v17, v[142:145] offset:49152
	v_mfma_f32_16x16x32_f16 v[86:89], v[118:121], v[110:113], v[86:89]
	s_waitcnt vmcnt(0)
	ds_write_b128 v18, v[154:157] offset:49152
	s_waitcnt lgkmcnt(5)
	v_mfma_f32_16x16x32_f16 v[28:31], v[122:125], v[106:109], v[28:31]
	ds_read_b128 v[106:109], v23 offset:4096
	v_mfma_f32_16x16x32_f16 v[32:35], v[122:125], v[110:113], v[32:35]
	ds_read_b128 v[110:113], v23 offset:6144
	s_waitcnt lgkmcnt(1)
	v_mfma_f32_16x16x32_f16 v[98:101], v[58:61], v[106:109], v[98:101]
	s_waitcnt lgkmcnt(0)
	v_mfma_f32_16x16x32_f16 v[52:55], v[58:61], v[110:113], v[52:55]
	global_load_dwordx4 v[58:61], v[0:1], off offset:768
	v_mfma_f32_16x16x32_f16 v[102:105], v[94:97], v[106:109], v[102:105]
	v_mfma_f32_16x16x32_f16 v[24:27], v[94:97], v[110:113], v[24:27]
	v_mfma_f32_16x16x32_f16 v[114:117], v[118:121], v[106:109], v[114:117]
	v_mfma_f32_16x16x32_f16 v[40:43], v[118:121], v[110:113], v[40:43]
	v_mfma_f32_16x16x32_f16 v[70:73], v[122:125], v[106:109], v[70:73]
	global_load_dwordx4 v[106:109], v[2:3], off offset:768
	global_load_dwordx4 v[134:137], v[4:5], off offset:768
	global_load_dwordx4 v[158:161], v[6:7], off offset:768
	global_load_dwordx4 v[94:97], v[8:9], off offset:768
	global_load_dwordx4 v[162:165], v[10:11], off offset:768
	global_load_dwordx4 v[166:169], v[12:13], off offset:768
	global_load_dwordx4 v[190:193], v[14:15], off offset:768
	s_waitcnt lgkmcnt(0)
	s_barrier
; #define GL_LOAD(s_, kt_) if (VAR != 1) { a##s_##0 = GL_A(0, kt_); a##s_##1 = GL_A(1, kt_); a##s_##2 = GL_A(2, kt_); a##s_##3 = GL_A(3, kt_); b##s_##0 = GL_B(0, kt_); b##s_##1 = GL_B(1, kt_); b##s_##2 = GL_B(2, kt_); b##s_##3 = GL_B(3, kt_); }
; #define LDS_STORE(s_, buf_) if (VAR != 2) { LDS_ST1(sA, 0, buf_, a##s_##0) LDS_ST1(sA, 1, buf_, a##s_##1) LDS_ST1(sA, 2, buf_, a##s_##2) LDS_ST1(sA, 3, buf_, a##s_##3) LDS_ST1(sB, 0, buf_, b##s_##0) LDS_ST1(sB, 1, buf_, b##s_##1) LDS_ST1(sB, 2, buf_, b##s_##2) LDS_ST1(sB, 3, buf_, b##s_##3) }
;     ...
;   for (int kt = 0; kt < nk; kt += 2) {
;     if (kt + 2 < nk) { GL_LOAD(0, kt + 2) }
;     MMA_TILE(0)
;     LDS_STORE(1, 1)
;     if (VAR != 4) __syncthreads();
;     if (kt + 3 < nk) { GL_LOAD(1, kt + 3) }
;     MMA_TILE(1)
;     if (kt + 2 < nk) { LDS_STORE(0, 0) }
;     if (VAR != 4) __syncthreads();
	v_mfma_f32_16x16x32_f16 v[48:51], v[122:125], v[110:113], v[48:51]
	ds_read_b128 v[62:65], v16 offset:49152
	ds_read_b128 v[90:93], v21 offset:16384
	s_waitcnt lgkmcnt(0)
	v_mfma_f32_16x16x32_f16 v[36:39], v[62:65], v[90:93], v[36:39]
	ds_read_b128 v[74:77], v16 offset:51200
	ds_read_b128 v[110:113], v21 offset:18432
	s_waitcnt lgkmcnt(0)
	v_mfma_f32_16x16x32_f16 v[66:69], v[62:65], v[110:113], v[66:69]
	ds_read_b128 v[118:121], v16 offset:53248
	v_mfma_f32_16x16x32_f16 v[44:47], v[74:77], v[90:93], v[44:47]
	ds_read_b128 v[122:125], v16 offset:55296
	v_mfma_f32_16x16x32_f16 v[78:81], v[74:77], v[110:113], v[78:81]
	s_waitcnt lgkmcnt(1)
	v_mfma_f32_16x16x32_f16 v[82:85], v[118:121], v[90:93], v[82:85]
	v_mfma_f32_16x16x32_f16 v[86:89], v[118:121], v[110:113], v[86:89]
	s_waitcnt lgkmcnt(0)
	v_mfma_f32_16x16x32_f16 v[28:31], v[122:125], v[90:93], v[28:31]
	ds_read_b128 v[90:93], v21 offset:20480
	v_mfma_f32_16x16x32_f16 v[32:35], v[122:125], v[110:113], v[32:35]
	ds_read_b128 v[110:113], v21 offset:22528
	s_waitcnt lgkmcnt(1)
	v_mfma_f32_16x16x32_f16 v[98:101], v[62:65], v[90:93], v[98:101]
	s_waitcnt lgkmcnt(0)
	v_mfma_f32_16x16x32_f16 v[52:55], v[62:65], v[110:113], v[52:55]
	ds_read_b128 v[62:65], v22 offset:49152
	v_mfma_f32_16x16x32_f16 v[102:105], v[74:77], v[90:93], v[102:105]
	v_mfma_f32_16x16x32_f16 v[24:27], v[74:77], v[110:113], v[24:27]
	ds_read_b128 v[74:77], v22 offset:51200
	v_mfma_f32_16x16x32_f16 v[114:117], v[118:121], v[90:93], v[114:117]
	s_waitcnt vmcnt(7)
	ds_write_b128 v19, v[58:61]
	s_waitcnt vmcnt(6)
	ds_write_b128 v20, v[106:109]
	v_mfma_f32_16x16x32_f16 v[40:43], v[118:121], v[110:113], v[40:43]
	ds_read_b128 v[118:121], v22 offset:53248
	s_waitcnt vmcnt(5)
	ds_write_b128 v17, v[134:137]
	v_mfma_f32_16x16x32_f16 v[70:73], v[122:125], v[90:93], v[70:73]
	ds_read_b128 v[90:93], v23 offset:16384
	v_mfma_f32_16x16x32_f16 v[48:51], v[122:125], v[110:113], v[48:51]
	ds_read_b128 v[110:113], v23 offset:18432
	s_waitcnt lgkmcnt(1)
	v_mfma_f32_16x16x32_f16 v[36:39], v[62:65], v[90:93], v[36:39]
	ds_read_b128 v[122:125], v22 offset:55296
	s_waitcnt lgkmcnt(1)
	v_mfma_f32_16x16x32_f16 v[66:69], v[62:65], v[110:113], v[66:69]
	s_waitcnt vmcnt(4)
	ds_write_b128 v18, v[158:161]
	v_mfma_f32_16x16x32_f16 v[44:47], v[74:77], v[90:93], v[44:47]
	s_waitcnt vmcnt(3)
	ds_write_b128 v19, v[94:97] offset:32768
	v_mfma_f32_16x16x32_f16 v[78:81], v[74:77], v[110:113], v[78:81]
	s_waitcnt vmcnt(2)
	ds_write_b128 v20, v[162:165] offset:32768
	v_mfma_f32_16x16x32_f16 v[82:85], v[118:121], v[90:93], v[82:85]
	s_waitcnt vmcnt(1)
	ds_write_b128 v17, v[166:169] offset:32768
	v_mfma_f32_16x16x32_f16 v[86:89], v[118:121], v[110:113], v[86:89]
	s_waitcnt vmcnt(0)
	ds_write_b128 v18, v[190:193] offset:32768
	s_waitcnt lgkmcnt(5)
	v_mfma_f32_16x16x32_f16 v[28:31], v[122:125], v[90:93], v[28:31]
	ds_read_b128 v[90:93], v23 offset:20480
	v_mfma_f32_16x16x32_f16 v[32:35], v[122:125], v[110:113], v[32:35]
	ds_read_b128 v[110:113], v23 offset:22528
	s_waitcnt lgkmcnt(1)
	v_mfma_f32_16x16x32_f16 v[98:101], v[62:65], v[90:93], v[98:101]
	s_waitcnt lgkmcnt(0)
	v_mfma_f32_16x16x32_f16 v[52:55], v[62:65], v[110:113], v[52:55]
	global_load_dwordx4 v[62:65], v[0:1], off offset:896
	v_mfma_f32_16x16x32_f16 v[102:105], v[74:77], v[90:93], v[102:105]
	v_mfma_f32_16x16x32_f16 v[24:27], v[74:77], v[110:113], v[24:27]
	v_mfma_f32_16x16x32_f16 v[114:117], v[118:121], v[90:93], v[114:117]
	v_mfma_f32_16x16x32_f16 v[40:43], v[118:121], v[110:113], v[40:43]
	v_mfma_f32_16x16x32_f16 v[70:73], v[122:125], v[90:93], v[70:73]
	global_load_dwordx4 v[90:93], v[2:3], off offset:896
	global_load_dwordx4 v[126:129], v[4:5], off offset:896
	global_load_dwordx4 v[130:133], v[6:7], off offset:896
	global_load_dwordx4 v[74:77], v[8:9], off offset:896
	global_load_dwordx4 v[138:141], v[10:11], off offset:896
	global_load_dwordx4 v[142:145], v[12:13], off offset:896
	global_load_dwordx4 v[154:157], v[14:15], off offset:896
	s_waitcnt lgkmcnt(0)
	s_barrier
	v_mfma_f32_16x16x32_f16 v[48:51], v[122:125], v[110:113], v[48:51]
	ds_read_b128 v[58:61], v16 offset:32768
	ds_read_b128 v[106:109], v21
	s_waitcnt lgkmcnt(0)
	v_mfma_f32_16x16x32_f16 v[36:39], v[58:61], v[106:109], v[36:39]
	ds_read_b128 v[94:97], v16 offset:34816
	ds_read_b128 v[110:113], v21 offset:2048
	s_waitcnt lgkmcnt(0)
	v_mfma_f32_16x16x32_f16 v[66:69], v[58:61], v[110:113], v[66:69]
	ds_read_b128 v[118:121], v16 offset:36864
	v_mfma_f32_16x16x32_f16 v[44:47], v[94:97], v[106:109], v[44:47]
	ds_read_b128 v[122:125], v16 offset:38912
	v_mfma_f32_16x16x32_f16 v[78:81], v[94:97], v[110:113], v[78:81]
	s_waitcnt lgkmcnt(1)
	v_mfma_f32_16x16x32_f16 v[82:85], v[118:121], v[106:109], v[82:85]
	v_mfma_f32_16x16x32_f16 v[86:89], v[118:121], v[110:113], v[86:89]
	s_waitcnt lgkmcnt(0)
	v_mfma_f32_16x16x32_f16 v[28:31], v[122:125], v[106:109], v[28:31]
	ds_read_b128 v[106:109], v21 offset:4096
	v_mfma_f32_16x16x32_f16 v[32:35], v[122:125], v[110:113], v[32:35]
	ds_read_b128 v[110:113], v21 offset:6144
	s_waitcnt lgkmcnt(1)
	v_mfma_f32_16x16x32_f16 v[98:101], v[58:61], v[106:109], v[98:101]
	s_waitcnt lgkmcnt(0)
	v_mfma_f32_16x16x32_f16 v[52:55], v[58:61], v[110:113], v[52:55]
	ds_read_b128 v[58:61], v22 offset:32768
	v_mfma_f32_16x16x32_f16 v[102:105], v[94:97], v[106:109], v[102:105]
	v_mfma_f32_16x16x32_f16 v[24:27], v[94:97], v[110:113], v[24:27]
	ds_read_b128 v[94:97], v22 offset:34816
	v_mfma_f32_16x16x32_f16 v[114:117], v[118:121], v[106:109], v[114:117]
	s_waitcnt vmcnt(7)
	ds_write_b128 v19, v[62:65] offset:16384
	s_waitcnt vmcnt(6)
	ds_write_b128 v20, v[90:93] offset:16384
	v_mfma_f32_16x16x32_f16 v[40:43], v[118:121], v[110:113], v[40:43]
	ds_read_b128 v[118:121], v22 offset:36864
	s_waitcnt vmcnt(5)
; #define GL_LOAD(s_, kt_) if (VAR != 1) { a##s_##0 = GL_A(0, kt_); a##s_##1 = GL_A(1, kt_); a##s_##2 = GL_A(2, kt_); a##s_##3 = GL_A(3, kt_); b##s_##0 = GL_B(0, kt_); b##s_##1 = GL_B(1, kt_); b##s_##2 = GL_B(2, kt_); b##s_##3 = GL_B(3, kt_); }
; #define LDS_STORE(s_, buf_) if (VAR != 2) { LDS_ST1(sA, 0, buf_, a##s_##0) LDS_ST1(sA, 1, buf_, a##s_##1) LDS_ST1(sA, 2, buf_, a##s_##2) LDS_ST1(sA, 3, buf_, a##s_##3) LDS_ST1(sB, 0, buf_, b##s_##0) LDS_ST1(sB, 1, buf_, b##s_##1) LDS_ST1(sB, 2, buf_, b##s_##2) LDS_ST1(sB, 3, buf_, b##s_##3) }
;     ...
;   for (int kt = 0; kt < nk; kt += 2) {
;     if (kt + 2 < nk) { GL_LOAD(0, kt + 2) }
;     MMA_TILE(0)
;     LDS_STORE(1, 1)
;     if (VAR != 4) __syncthreads();
;     if (kt + 3 < nk) { GL_LOAD(1, kt + 3) }
;     MMA_TILE(1)
;     if (kt + 2 < nk) { LDS_STORE(0, 0) }
;     if (VAR != 4) __syncthreads();
	ds_write_b128 v17, v[126:129] offset:16384
	v_mfma_f32_16x16x32_f16 v[70:73], v[122:125], v[106:109], v[70:73]
	ds_read_b128 v[106:109], v23
	v_mfma_f32_16x16x32_f16 v[48:51], v[122:125], v[110:113], v[48:51]
	ds_read_b128 v[110:113], v23 offset:2048
	s_waitcnt lgkmcnt(1)
	v_mfma_f32_16x16x32_f16 v[36:39], v[58:61], v[106:109], v[36:39]
	ds_read_b128 v[122:125], v22 offset:38912
	s_waitcnt lgkmcnt(1)
	v_mfma_f32_16x16x32_f16 v[66:69], v[58:61], v[110:113], v[66:69]
	s_waitcnt vmcnt(4)
	ds_write_b128 v18, v[130:133] offset:16384
	v_mfma_f32_16x16x32_f16 v[44:47], v[94:97], v[106:109], v[44:47]
	s_waitcnt vmcnt(3)
	ds_write_b128 v19, v[74:77] offset:49152
	v_mfma_f32_16x16x32_f16 v[78:81], v[94:97], v[110:113], v[78:81]
	s_waitcnt vmcnt(2)
	ds_write_b128 v20, v[138:141] offset:49152
	v_mfma_f32_16x16x32_f16 v[82:85], v[118:121], v[106:109], v[82:85]
	s_waitcnt vmcnt(1)
	ds_write_b128 v17, v[142:145] offset:49152
	v_mfma_f32_16x16x32_f16 v[86:89], v[118:121], v[110:113], v[86:89]
	s_waitcnt vmcnt(0)
	ds_write_b128 v18, v[154:157] offset:49152
	s_waitcnt lgkmcnt(5)
	v_mfma_f32_16x16x32_f16 v[28:31], v[122:125], v[106:109], v[28:31]
	ds_read_b128 v[106:109], v23 offset:4096
	v_mfma_f32_16x16x32_f16 v[32:35], v[122:125], v[110:113], v[32:35]
	ds_read_b128 v[110:113], v23 offset:6144
	s_waitcnt lgkmcnt(1)
	v_mfma_f32_16x16x32_f16 v[98:101], v[58:61], v[106:109], v[98:101]
	s_waitcnt lgkmcnt(0)
	v_mfma_f32_16x16x32_f16 v[52:55], v[58:61], v[110:113], v[52:55]
	global_load_dwordx4 v[58:61], v[0:1], off offset:1024
	v_mfma_f32_16x16x32_f16 v[102:105], v[94:97], v[106:109], v[102:105]
	v_mfma_f32_16x16x32_f16 v[24:27], v[94:97], v[110:113], v[24:27]
	v_mfma_f32_16x16x32_f16 v[114:117], v[118:121], v[106:109], v[114:117]
	v_mfma_f32_16x16x32_f16 v[40:43], v[118:121], v[110:113], v[40:43]
	v_mfma_f32_16x16x32_f16 v[70:73], v[122:125], v[106:109], v[70:73]
	global_load_dwordx4 v[106:109], v[2:3], off offset:1024
	global_load_dwordx4 v[134:137], v[4:5], off offset:1024
	global_load_dwordx4 v[158:161], v[6:7], off offset:1024
	global_load_dwordx4 v[94:97], v[8:9], off offset:1024
	global_load_dwordx4 v[162:165], v[10:11], off offset:1024
	global_load_dwordx4 v[166:169], v[12:13], off offset:1024
	global_load_dwordx4 v[190:193], v[14:15], off offset:1024
	s_waitcnt lgkmcnt(0)
	s_barrier
	v_mfma_f32_16x16x32_f16 v[48:51], v[122:125], v[110:113], v[48:51]
	ds_read_b128 v[62:65], v16 offset:49152
	ds_read_b128 v[90:93], v21 offset:16384
	s_waitcnt lgkmcnt(0)
	v_mfma_f32_16x16x32_f16 v[36:39], v[62:65], v[90:93], v[36:39]
	ds_read_b128 v[74:77], v16 offset:51200
	ds_read_b128 v[110:113], v21 offset:18432
	s_waitcnt lgkmcnt(0)
	v_mfma_f32_16x16x32_f16 v[66:69], v[62:65], v[110:113], v[66:69]
	ds_read_b128 v[118:121], v16 offset:53248
	v_mfma_f32_16x16x32_f16 v[44:47], v[74:77], v[90:93], v[44:47]
	ds_read_b128 v[122:125], v16 offset:55296
	v_mfma_f32_16x16x32_f16 v[78:81], v[74:77], v[110:113], v[78:81]
	s_waitcnt lgkmcnt(1)
	v_mfma_f32_16x16x32_f16 v[82:85], v[118:121], v[90:93], v[82:85]
	v_mfma_f32_16x16x32_f16 v[86:89], v[118:121], v[110:113], v[86:89]
	s_waitcnt lgkmcnt(0)
	v_mfma_f32_16x16x32_f16 v[28:31], v[122:125], v[90:93], v[28:31]
	ds_read_b128 v[90:93], v21 offset:20480
	v_mfma_f32_16x16x32_f16 v[32:35], v[122:125], v[110:113], v[32:35]
	ds_read_b128 v[110:113], v21 offset:22528
	s_waitcnt lgkmcnt(1)
	v_mfma_f32_16x16x32_f16 v[98:101], v[62:65], v[90:93], v[98:101]
	s_waitcnt lgkmcnt(0)
	v_mfma_f32_16x16x32_f16 v[52:55], v[62:65], v[110:113], v[52:55]
	ds_read_b128 v[62:65], v22 offset:49152
	v_mfma_f32_16x16x32_f16 v[102:105], v[74:77], v[90:93], v[102:105]
	v_mfma_f32_16x16x32_f16 v[24:27], v[74:77], v[110:113], v[24:27]
	ds_read_b128 v[74:77], v22 offset:51200
	v_mfma_f32_16x16x32_f16 v[114:117], v[118:121], v[90:93], v[114:117]
	s_waitcnt vmcnt(7)
	ds_write_b128 v19, v[58:61]
	s_waitcnt vmcnt(6)
	ds_write_b128 v20, v[106:109]
	v_mfma_f32_16x16x32_f16 v[40:43], v[118:121], v[110:113], v[40:43]
	ds_read_b128 v[118:121], v22 offset:53248
	s_waitcnt vmcnt(5)
	ds_write_b128 v17, v[134:137]
	v_mfma_f32_16x16x32_f16 v[70:73], v[122:125], v[90:93], v[70:73]
	ds_read_b128 v[90:93], v23 offset:16384
	v_mfma_f32_16x16x32_f16 v[48:51], v[122:125], v[110:113], v[48:51]
	ds_read_b128 v[110:113], v23 offset:18432
	s_waitcnt lgkmcnt(1)
	v_mfma_f32_16x16x32_f16 v[36:39], v[62:65], v[90:93], v[36:39]
	ds_read_b128 v[122:125], v22 offset:55296
	s_waitcnt lgkmcnt(1)
	v_mfma_f32_16x16x32_f16 v[66:69], v[62:65], v[110:113], v[66:69]
	s_waitcnt vmcnt(4)
	ds_write_b128 v18, v[158:161]
	v_mfma_f32_16x16x32_f16 v[44:47], v[74:77], v[90:93], v[44:47]
	s_waitcnt vmcnt(3)
	ds_write_b128 v19, v[94:97] offset:32768
	v_mfma_f32_16x16x32_f16 v[78:81], v[74:77], v[110:113], v[78:81]
	s_waitcnt vmcnt(2)
	ds_write_b128 v20, v[162:165] offset:32768
	v_mfma_f32_16x16x32_f16 v[82:85], v[118:121], v[90:93], v[82:85]
	s_waitcnt vmcnt(1)
	ds_write_b128 v17, v[166:169] offset:32768
	v_mfma_f32_16x16x32_f16 v[86:89], v[118:121], v[110:113], v[86:89]
	s_waitcnt vmcnt(0)
	ds_write_b128 v18, v[190:193] offset:32768
	s_waitcnt lgkmcnt(5)
	v_mfma_f32_16x16x32_f16 v[28:31], v[122:125], v[90:93], v[28:31]
	ds_read_b128 v[90:93], v23 offset:20480
	v_mfma_f32_16x16x32_f16 v[32:35], v[122:125], v[110:113], v[32:35]
	ds_read_b128 v[110:113], v23 offset:22528
	s_waitcnt lgkmcnt(1)
	v_mfma_f32_16x16x32_f16 v[98:101], v[62:65], v[90:93], v[98:101]
	s_waitcnt lgkmcnt(0)
	v_mfma_f32_16x16x32_f16 v[52:55], v[62:65], v[110:113], v[52:55]
	global_load_dwordx4 v[62:65], v[0:1], off offset:1152
	v_mfma_f32_16x16x32_f16 v[102:105], v[74:77], v[90:93], v[102:105]
	v_mfma_f32_16x16x32_f16 v[24:27], v[74:77], v[110:113], v[24:27]
	v_mfma_f32_16x16x32_f16 v[114:117], v[118:121], v[90:93], v[114:117]
	v_mfma_f32_16x16x32_f16 v[40:43], v[118:121], v[110:113], v[40:43]
	v_mfma_f32_16x16x32_f16 v[70:73], v[122:125], v[90:93], v[70:73]
	global_load_dwordx4 v[90:93], v[2:3], off offset:1152
	global_load_dwordx4 v[126:129], v[4:5], off offset:1152
	global_load_dwordx4 v[130:133], v[6:7], off offset:1152
	global_load_dwordx4 v[74:77], v[8:9], off offset:1152
	global_load_dwordx4 v[138:141], v[10:11], off offset:1152
	global_load_dwordx4 v[142:145], v[12:13], off offset:1152
	global_load_dwordx4 v[154:157], v[14:15], off offset:1152
	s_waitcnt lgkmcnt(0)
	s_barrier
; #define GL_LOAD(s_, kt_) if (VAR != 1) { a##s_##0 = GL_A(0, kt_); a##s_##1 = GL_A(1, kt_); a##s_##2 = GL_A(2, kt_); a##s_##3 = GL_A(3, kt_); b##s_##0 = GL_B(0, kt_); b##s_##1 = GL_B(1, kt_); b##s_##2 = GL_B(2, kt_); b##s_##3 = GL_B(3, kt_); }
; #define LDS_STORE(s_, buf_) if (VAR != 2) { LDS_ST1(sA, 0, buf_, a##s_##0) LDS_ST1(sA, 1, buf_, a##s_##1) LDS_ST1(sA, 2, buf_, a##s_##2) LDS_ST1(sA, 3, buf_, a##s_##3) LDS_ST1(sB, 0, buf_, b##s_##0) LDS_ST1(sB, 1, buf_, b##s_##1) LDS_ST1(sB, 2, buf_, b##s_##2) LDS_ST1(sB, 3, buf_, b##s_##3) }
;     ...
;   for (int kt = 0; kt < nk; kt += 2) {
;     if (kt + 2 < nk) { GL_LOAD(0, kt + 2) }
;     MMA_TILE(0)
;     LDS_STORE(1, 1)
;     if (VAR != 4) __syncthreads();
;     if (kt + 3 < nk) { GL_LOAD(1, kt + 3) }
;     MMA_TILE(1)
;     if (kt + 2 < nk) { LDS_STORE(0, 0) }
;     if (VAR != 4) __syncthreads();
	v_mfma_f32_16x16x32_f16 v[48:51], v[122:125], v[110:113], v[48:51]
	ds_read_b128 v[58:61], v16 offset:32768
	ds_read_b128 v[106:109], v21
	s_waitcnt lgkmcnt(0)
	v_mfma_f32_16x16x32_f16 v[36:39], v[58:61], v[106:109], v[36:39]
	ds_read_b128 v[94:97], v16 offset:34816
	ds_read_b128 v[110:113], v21 offset:2048
	s_waitcnt lgkmcnt(0)
	v_mfma_f32_16x16x32_f16 v[66:69], v[58:61], v[110:113], v[66:69]
	ds_read_b128 v[118:121], v16 offset:36864
	v_mfma_f32_16x16x32_f16 v[44:47], v[94:97], v[106:109], v[44:47]
	ds_read_b128 v[122:125], v16 offset:38912
	v_mfma_f32_16x16x32_f16 v[78:81], v[94:97], v[110:113], v[78:81]
	s_waitcnt lgkmcnt(1)
	v_mfma_f32_16x16x32_f16 v[82:85], v[118:121], v[106:109], v[82:85]
	v_mfma_f32_16x16x32_f16 v[86:89], v[118:121], v[110:113], v[86:89]
	s_waitcnt lgkmcnt(0)
	v_mfma_f32_16x16x32_f16 v[28:31], v[122:125], v[106:109], v[28:31]
	ds_read_b128 v[106:109], v21 offset:4096
	v_mfma_f32_16x16x32_f16 v[32:35], v[122:125], v[110:113], v[32:35]
	ds_read_b128 v[110:113], v21 offset:6144
	s_waitcnt lgkmcnt(1)
	v_mfma_f32_16x16x32_f16 v[98:101], v[58:61], v[106:109], v[98:101]
	s_waitcnt lgkmcnt(0)
	v_mfma_f32_16x16x32_f16 v[52:55], v[58:61], v[110:113], v[52:55]
	ds_read_b128 v[58:61], v22 offset:32768
	v_mfma_f32_16x16x32_f16 v[102:105], v[94:97], v[106:109], v[102:105]
	v_mfma_f32_16x16x32_f16 v[24:27], v[94:97], v[110:113], v[24:27]
	ds_read_b128 v[94:97], v22 offset:34816
	v_mfma_f32_16x16x32_f16 v[114:117], v[118:121], v[106:109], v[114:117]
	s_waitcnt vmcnt(7)
	ds_write_b128 v19, v[62:65] offset:16384
	s_waitcnt vmcnt(6)
	ds_write_b128 v20, v[90:93] offset:16384
	v_mfma_f32_16x16x32_f16 v[40:43], v[118:121], v[110:113], v[40:43]
	ds_read_b128 v[118:121], v22 offset:36864
	s_waitcnt vmcnt(5)
	ds_write_b128 v17, v[126:129] offset:16384
	v_mfma_f32_16x16x32_f16 v[70:73], v[122:125], v[106:109], v[70:73]
	ds_read_b128 v[106:109], v23
	v_mfma_f32_16x16x32_f16 v[48:51], v[122:125], v[110:113], v[48:51]
	ds_read_b128 v[110:113], v23 offset:2048
	s_waitcnt lgkmcnt(1)
	v_mfma_f32_16x16x32_f16 v[36:39], v[58:61], v[106:109], v[36:39]
	ds_read_b128 v[122:125], v22 offset:38912
	s_waitcnt lgkmcnt(1)
	v_mfma_f32_16x16x32_f16 v[66:69], v[58:61], v[110:113], v[66:69]
	s_waitcnt vmcnt(4)
	ds_write_b128 v18, v[130:133] offset:16384
	v_mfma_f32_16x16x32_f16 v[44:47], v[94:97], v[106:109], v[44:47]
	s_waitcnt vmcnt(3)
	ds_write_b128 v19, v[74:77] offset:49152
	v_mfma_f32_16x16x32_f16 v[78:81], v[94:97], v[110:113], v[78:81]
	s_waitcnt vmcnt(2)
	ds_write_b128 v20, v[138:141] offset:49152
	v_mfma_f32_16x16x32_f16 v[82:85], v[118:121], v[106:109], v[82:85]
	s_waitcnt vmcnt(1)
	ds_write_b128 v17, v[142:145] offset:49152
	v_mfma_f32_16x16x32_f16 v[86:89], v[118:121], v[110:113], v[86:89]
	s_waitcnt vmcnt(0)
	ds_write_b128 v18, v[154:157] offset:49152
	s_waitcnt lgkmcnt(5)
	v_mfma_f32_16x16x32_f16 v[28:31], v[122:125], v[106:109], v[28:31]
	ds_read_b128 v[106:109], v23 offset:4096
	v_mfma_f32_16x16x32_f16 v[32:35], v[122:125], v[110:113], v[32:35]
	ds_read_b128 v[110:113], v23 offset:6144
	s_waitcnt lgkmcnt(1)
	v_mfma_f32_16x16x32_f16 v[98:101], v[58:61], v[106:109], v[98:101]
	s_waitcnt lgkmcnt(0)
	v_mfma_f32_16x16x32_f16 v[52:55], v[58:61], v[110:113], v[52:55]
	global_load_dwordx4 v[58:61], v[0:1], off offset:1280
	v_mfma_f32_16x16x32_f16 v[102:105], v[94:97], v[106:109], v[102:105]
	v_mfma_f32_16x16x32_f16 v[24:27], v[94:97], v[110:113], v[24:27]
	v_mfma_f32_16x16x32_f16 v[114:117], v[118:121], v[106:109], v[114:117]
	v_mfma_f32_16x16x32_f16 v[40:43], v[118:121], v[110:113], v[40:43]
	v_mfma_f32_16x16x32_f16 v[70:73], v[122:125], v[106:109], v[70:73]
	global_load_dwordx4 v[106:109], v[2:3], off offset:1280
	global_load_dwordx4 v[134:137], v[4:5], off offset:1280
	global_load_dwordx4 v[158:161], v[6:7], off offset:1280
	global_load_dwordx4 v[94:97], v[8:9], off offset:1280
	global_load_dwordx4 v[162:165], v[10:11], off offset:1280
	global_load_dwordx4 v[166:169], v[12:13], off offset:1280
	global_load_dwordx4 v[190:193], v[14:15], off offset:1280
	s_waitcnt lgkmcnt(0)
	s_barrier
	v_mfma_f32_16x16x32_f16 v[48:51], v[122:125], v[110:113], v[48:51]
	ds_read_b128 v[62:65], v16 offset:49152
	ds_read_b128 v[90:93], v21 offset:16384
	s_waitcnt lgkmcnt(0)
	v_mfma_f32_16x16x32_f16 v[36:39], v[62:65], v[90:93], v[36:39]
	ds_read_b128 v[74:77], v16 offset:51200
	ds_read_b128 v[110:113], v21 offset:18432
	s_waitcnt lgkmcnt(0)
	v_mfma_f32_16x16x32_f16 v[66:69], v[62:65], v[110:113], v[66:69]
	ds_read_b128 v[118:121], v16 offset:53248
	v_mfma_f32_16x16x32_f16 v[44:47], v[74:77], v[90:93], v[44:47]
	ds_read_b128 v[122:125], v16 offset:55296
	v_mfma_f32_16x16x32_f16 v[78:81], v[74:77], v[110:113], v[78:81]
	s_waitcnt lgkmcnt(1)
	v_mfma_f32_16x16x32_f16 v[82:85], v[118:121], v[90:93], v[82:85]
	v_mfma_f32_16x16x32_f16 v[86:89], v[118:121], v[110:113], v[86:89]
	s_waitcnt lgkmcnt(0)
	v_mfma_f32_16x16x32_f16 v[28:31], v[122:125], v[90:93], v[28:31]
	ds_read_b128 v[90:93], v21 offset:20480
	v_mfma_f32_16x16x32_f16 v[32:35], v[122:125], v[110:113], v[32:35]
	ds_read_b128 v[110:113], v21 offset:22528
	s_waitcnt lgkmcnt(1)
	v_mfma_f32_16x16x32_f16 v[98:101], v[62:65], v[90:93], v[98:101]
	s_waitcnt lgkmcnt(0)
	v_mfma_f32_16x16x32_f16 v[52:55], v[62:65], v[110:113], v[52:55]
	ds_read_b128 v[62:65], v22 offset:49152
	v_mfma_f32_16x16x32_f16 v[102:105], v[74:77], v[90:93], v[102:105]
	v_mfma_f32_16x16x32_f16 v[24:27], v[74:77], v[110:113], v[24:27]
	ds_read_b128 v[74:77], v22 offset:51200
	v_mfma_f32_16x16x32_f16 v[114:117], v[118:121], v[90:93], v[114:117]
	s_waitcnt vmcnt(7)
	ds_write_b128 v19, v[58:61]
	s_waitcnt vmcnt(6)
; #define GL_LOAD(s_, kt_) if (VAR != 1) { a##s_##0 = GL_A(0, kt_); a##s_##1 = GL_A(1, kt_); a##s_##2 = GL_A(2, kt_); a##s_##3 = GL_A(3, kt_); b##s_##0 = GL_B(0, kt_); b##s_##1 = GL_B(1, kt_); b##s_##2 = GL_B(2, kt_); b##s_##3 = GL_B(3, kt_); }
; #define LDS_STORE(s_, buf_) if (VAR != 2) { LDS_ST1(sA, 0, buf_, a##s_##0) LDS_ST1(sA, 1, buf_, a##s_##1) LDS_ST1(sA, 2, buf_, a##s_##2) LDS_ST1(sA, 3, buf_, a##s_##3) LDS_ST1(sB, 0, buf_, b##s_##0) LDS_ST1(sB, 1, buf_, b##s_##1) LDS_ST1(sB, 2, buf_, b##s_##2) LDS_ST1(sB, 3, buf_, b##s_##3) }
;     ...
;   for (int kt = 0; kt < nk; kt += 2) {
;     if (kt + 2 < nk) { GL_LOAD(0, kt + 2) }
;     MMA_TILE(0)
;     LDS_STORE(1, 1)
;     if (VAR != 4) __syncthreads();
;     if (kt + 3 < nk) { GL_LOAD(1, kt + 3) }
;     MMA_TILE(1)
;     if (kt + 2 < nk) { LDS_STORE(0, 0) }
;     if (VAR != 4) __syncthreads();
	ds_write_b128 v20, v[106:109]
	v_mfma_f32_16x16x32_f16 v[40:43], v[118:121], v[110:113], v[40:43]
	ds_read_b128 v[118:121], v22 offset:53248
	s_waitcnt vmcnt(5)
	ds_write_b128 v17, v[134:137]
	v_mfma_f32_16x16x32_f16 v[70:73], v[122:125], v[90:93], v[70:73]
	ds_read_b128 v[90:93], v23 offset:16384
	v_mfma_f32_16x16x32_f16 v[48:51], v[122:125], v[110:113], v[48:51]
	ds_read_b128 v[110:113], v23 offset:18432
	s_waitcnt lgkmcnt(1)
	v_mfma_f32_16x16x32_f16 v[36:39], v[62:65], v[90:93], v[36:39]
	ds_read_b128 v[122:125], v22 offset:55296
	s_waitcnt lgkmcnt(1)
	v_mfma_f32_16x16x32_f16 v[66:69], v[62:65], v[110:113], v[66:69]
	s_waitcnt vmcnt(4)
	ds_write_b128 v18, v[158:161]
	v_mfma_f32_16x16x32_f16 v[44:47], v[74:77], v[90:93], v[44:47]
	s_waitcnt vmcnt(3)
	ds_write_b128 v19, v[94:97] offset:32768
	v_mfma_f32_16x16x32_f16 v[78:81], v[74:77], v[110:113], v[78:81]
	s_waitcnt vmcnt(2)
	ds_write_b128 v20, v[162:165] offset:32768
	v_mfma_f32_16x16x32_f16 v[82:85], v[118:121], v[90:93], v[82:85]
	s_waitcnt vmcnt(1)
	ds_write_b128 v17, v[166:169] offset:32768
	v_mfma_f32_16x16x32_f16 v[86:89], v[118:121], v[110:113], v[86:89]
	s_waitcnt vmcnt(0)
	ds_write_b128 v18, v[190:193] offset:32768
	s_waitcnt lgkmcnt(5)
	v_mfma_f32_16x16x32_f16 v[28:31], v[122:125], v[90:93], v[28:31]
	ds_read_b128 v[90:93], v23 offset:20480
	v_mfma_f32_16x16x32_f16 v[32:35], v[122:125], v[110:113], v[32:35]
	ds_read_b128 v[110:113], v23 offset:22528
	s_waitcnt lgkmcnt(1)
	v_mfma_f32_16x16x32_f16 v[98:101], v[62:65], v[90:93], v[98:101]
	s_waitcnt lgkmcnt(0)
	v_mfma_f32_16x16x32_f16 v[52:55], v[62:65], v[110:113], v[52:55]
	global_load_dwordx4 v[62:65], v[0:1], off offset:1408
	v_mfma_f32_16x16x32_f16 v[102:105], v[74:77], v[90:93], v[102:105]
	v_mfma_f32_16x16x32_f16 v[24:27], v[74:77], v[110:113], v[24:27]
	v_mfma_f32_16x16x32_f16 v[114:117], v[118:121], v[90:93], v[114:117]
	v_mfma_f32_16x16x32_f16 v[40:43], v[118:121], v[110:113], v[40:43]
	v_mfma_f32_16x16x32_f16 v[70:73], v[122:125], v[90:93], v[70:73]
	global_load_dwordx4 v[90:93], v[2:3], off offset:1408
	global_load_dwordx4 v[126:129], v[4:5], off offset:1408
	global_load_dwordx4 v[130:133], v[6:7], off offset:1408
	global_load_dwordx4 v[74:77], v[8:9], off offset:1408
	global_load_dwordx4 v[138:141], v[10:11], off offset:1408
	global_load_dwordx4 v[142:145], v[12:13], off offset:1408
	global_load_dwordx4 v[154:157], v[14:15], off offset:1408
	s_waitcnt lgkmcnt(0)
	s_barrier
	v_mfma_f32_16x16x32_f16 v[48:51], v[122:125], v[110:113], v[48:51]
	ds_read_b128 v[58:61], v16 offset:32768
	ds_read_b128 v[106:109], v21
	s_waitcnt lgkmcnt(0)
	v_mfma_f32_16x16x32_f16 v[36:39], v[58:61], v[106:109], v[36:39]
	ds_read_b128 v[94:97], v16 offset:34816
	ds_read_b128 v[110:113], v21 offset:2048
	s_waitcnt lgkmcnt(0)
	v_mfma_f32_16x16x32_f16 v[66:69], v[58:61], v[110:113], v[66:69]
	ds_read_b128 v[118:121], v16 offset:36864
	v_mfma_f32_16x16x32_f16 v[44:47], v[94:97], v[106:109], v[44:47]
	ds_read_b128 v[122:125], v16 offset:38912
	v_mfma_f32_16x16x32_f16 v[78:81], v[94:97], v[110:113], v[78:81]
	s_waitcnt lgkmcnt(1)
	v_mfma_f32_16x16x32_f16 v[82:85], v[118:121], v[106:109], v[82:85]
	v_mfma_f32_16x16x32_f16 v[86:89], v[118:121], v[110:113], v[86:89]
	s_waitcnt lgkmcnt(0)
	v_mfma_f32_16x16x32_f16 v[28:31], v[122:125], v[106:109], v[28:31]
	ds_read_b128 v[106:109], v21 offset:4096
	v_mfma_f32_16x16x32_f16 v[32:35], v[122:125], v[110:113], v[32:35]
	ds_read_b128 v[110:113], v21 offset:6144
	s_waitcnt lgkmcnt(1)
	v_mfma_f32_16x16x32_f16 v[98:101], v[58:61], v[106:109], v[98:101]
	s_waitcnt lgkmcnt(0)
	v_mfma_f32_16x16x32_f16 v[52:55], v[58:61], v[110:113], v[52:55]
	ds_read_b128 v[58:61], v22 offset:32768
	v_mfma_f32_16x16x32_f16 v[102:105], v[94:97], v[106:109], v[102:105]
	v_mfma_f32_16x16x32_f16 v[24:27], v[94:97], v[110:113], v[24:27]
	ds_read_b128 v[94:97], v22 offset:34816
	v_mfma_f32_16x16x32_f16 v[114:117], v[118:121], v[106:109], v[114:117]
	s_waitcnt vmcnt(7)
	ds_write_b128 v19, v[62:65] offset:16384
	s_waitcnt vmcnt(6)
	ds_write_b128 v20, v[90:93] offset:16384
	v_mfma_f32_16x16x32_f16 v[40:43], v[118:121], v[110:113], v[40:43]
	ds_read_b128 v[118:121], v22 offset:36864
	s_waitcnt vmcnt(5)
	ds_write_b128 v17, v[126:129] offset:16384
	v_mfma_f32_16x16x32_f16 v[70:73], v[122:125], v[106:109], v[70:73]
	ds_read_b128 v[106:109], v23
	v_mfma_f32_16x16x32_f16 v[48:51], v[122:125], v[110:113], v[48:51]
	ds_read_b128 v[110:113], v23 offset:2048
	s_waitcnt lgkmcnt(1)
	v_mfma_f32_16x16x32_f16 v[36:39], v[58:61], v[106:109], v[36:39]
	ds_read_b128 v[122:125], v22 offset:38912
	s_waitcnt lgkmcnt(1)
	v_mfma_f32_16x16x32_f16 v[66:69], v[58:61], v[110:113], v[66:69]
	s_waitcnt vmcnt(4)
	ds_write_b128 v18, v[130:133] offset:16384
	v_mfma_f32_16x16x32_f16 v[44:47], v[94:97], v[106:109], v[44:47]
	s_waitcnt vmcnt(3)
	ds_write_b128 v19, v[74:77] offset:49152
	v_mfma_f32_16x16x32_f16 v[78:81], v[94:97], v[110:113], v[78:81]
	s_waitcnt vmcnt(2)
	ds_write_b128 v20, v[138:141] offset:49152
	v_mfma_f32_16x16x32_f16 v[82:85], v[118:121], v[106:109], v[82:85]
	s_waitcnt vmcnt(1)
	ds_write_b128 v17, v[142:145] offset:49152
	v_mfma_f32_16x16x32_f16 v[86:89], v[118:121], v[110:113], v[86:89]
	s_waitcnt vmcnt(0)
	ds_write_b128 v18, v[154:157] offset:49152
	s_waitcnt lgkmcnt(5)
	v_mfma_f32_16x16x32_f16 v[28:31], v[122:125], v[106:109], v[28:31]
	ds_read_b128 v[106:109], v23 offset:4096
	v_mfma_f32_16x16x32_f16 v[32:35], v[122:125], v[110:113], v[32:35]
	ds_read_b128 v[110:113], v23 offset:6144
	s_waitcnt lgkmcnt(1)
	v_mfma_f32_16x16x32_f16 v[98:101], v[58:61], v[106:109], v[98:101]
	s_waitcnt lgkmcnt(0)
	v_mfma_f32_16x16x32_f16 v[52:55], v[58:61], v[110:113], v[52:55]
	global_load_dwordx4 v[58:61], v[0:1], off offset:1536
	v_mfma_f32_16x16x32_f16 v[102:105], v[94:97], v[106:109], v[102:105]
	v_mfma_f32_16x16x32_f16 v[24:27], v[94:97], v[110:113], v[24:27]
	v_mfma_f32_16x16x32_f16 v[114:117], v[118:121], v[106:109], v[114:117]
	v_mfma_f32_16x16x32_f16 v[40:43], v[118:121], v[110:113], v[40:43]
	v_mfma_f32_16x16x32_f16 v[70:73], v[122:125], v[106:109], v[70:73]
	global_load_dwordx4 v[106:109], v[2:3], off offset:1536
	global_load_dwordx4 v[134:137], v[4:5], off offset:1536
	global_load_dwordx4 v[158:161], v[6:7], off offset:1536
	global_load_dwordx4 v[94:97], v[8:9], off offset:1536
	global_load_dwordx4 v[162:165], v[10:11], off offset:1536
	global_load_dwordx4 v[166:169], v[12:13], off offset:1536
	global_load_dwordx4 v[190:193], v[14:15], off offset:1536
	s_waitcnt lgkmcnt(0)
	s_barrier
; #define GL_LOAD(s_, kt_) if (VAR != 1) { a##s_##0 = GL_A(0, kt_); a##s_##1 = GL_A(1, kt_); a##s_##2 = GL_A(2, kt_); a##s_##3 = GL_A(3, kt_); b##s_##0 = GL_B(0, kt_); b##s_##1 = GL_B(1, kt_); b##s_##2 = GL_B(2, kt_); b##s_##3 = GL_B(3, kt_); }
; #define LDS_STORE(s_, buf_) if (VAR != 2) { LDS_ST1(sA, 0, buf_, a##s_##0) LDS_ST1(sA, 1, buf_, a##s_##1) LDS_ST1(sA, 2, buf_, a##s_##2) LDS_ST1(sA, 3, buf_, a##s_##3) LDS_ST1(sB, 0, buf_, b##s_##0) LDS_ST1(sB, 1, buf_, b##s_##1) LDS_ST1(sB, 2, buf_, b##s_##2) LDS_ST1(sB, 3, buf_, b##s_##3) }
;     ...
;   for (int kt = 0; kt < nk; kt += 2) {
;     if (kt + 2 < nk) { GL_LOAD(0, kt + 2) }
;     MMA_TILE(0)
;     LDS_STORE(1, 1)
;     if (VAR != 4) __syncthreads();
;     if (kt + 3 < nk) { GL_LOAD(1, kt + 3) }
;     MMA_TILE(1)
;     if (kt + 2 < nk) { LDS_STORE(0, 0) }
;     if (VAR != 4) __syncthreads();
	v_mfma_f32_16x16x32_f16 v[48:51], v[122:125], v[110:113], v[48:51]
	ds_read_b128 v[62:65], v16 offset:49152
	ds_read_b128 v[90:93], v21 offset:16384
	s_waitcnt lgkmcnt(0)
	v_mfma_f32_16x16x32_f16 v[36:39], v[62:65], v[90:93], v[36:39]
	ds_read_b128 v[74:77], v16 offset:51200
	ds_read_b128 v[110:113], v21 offset:18432
	s_waitcnt lgkmcnt(0)
	v_mfma_f32_16x16x32_f16 v[66:69], v[62:65], v[110:113], v[66:69]
	ds_read_b128 v[118:121], v16 offset:53248
	v_mfma_f32_16x16x32_f16 v[44:47], v[74:77], v[90:93], v[44:47]
	ds_read_b128 v[122:125], v16 offset:55296
	v_mfma_f32_16x16x32_f16 v[78:81], v[74:77], v[110:113], v[78:81]
	s_waitcnt lgkmcnt(1)
	v_mfma_f32_16x16x32_f16 v[82:85], v[118:121], v[90:93], v[82:85]
	v_mfma_f32_16x16x32_f16 v[86:89], v[118:121], v[110:113], v[86:89]
	s_waitcnt lgkmcnt(0)
	v_mfma_f32_16x16x32_f16 v[28:31], v[122:125], v[90:93], v[28:31]
	ds_read_b128 v[90:93], v21 offset:20480
	v_mfma_f32_16x16x32_f16 v[32:35], v[122:125], v[110:113], v[32:35]
	ds_read_b128 v[110:113], v21 offset:22528
	s_waitcnt lgkmcnt(1)
	v_mfma_f32_16x16x32_f16 v[98:101], v[62:65], v[90:93], v[98:101]
	s_waitcnt lgkmcnt(0)
	v_mfma_f32_16x16x32_f16 v[52:55], v[62:65], v[110:113], v[52:55]
	ds_read_b128 v[62:65], v22 offset:49152
	v_mfma_f32_16x16x32_f16 v[102:105], v[74:77], v[90:93], v[102:105]
	v_mfma_f32_16x16x32_f16 v[24:27], v[74:77], v[110:113], v[24:27]
	ds_read_b128 v[74:77], v22 offset:51200
	v_mfma_f32_16x16x32_f16 v[114:117], v[118:121], v[90:93], v[114:117]
	s_waitcnt vmcnt(7)
	ds_write_b128 v19, v[58:61]
	s_waitcnt vmcnt(6)
	ds_write_b128 v20, v[106:109]
	v_mfma_f32_16x16x32_f16 v[40:43], v[118:121], v[110:113], v[40:43]
	ds_read_b128 v[118:121], v22 offset:53248
	s_waitcnt vmcnt(5)
	ds_write_b128 v17, v[134:137]
	v_mfma_f32_16x16x32_f16 v[70:73], v[122:125], v[90:93], v[70:73]
	ds_read_b128 v[90:93], v23 offset:16384
	v_mfma_f32_16x16x32_f16 v[48:51], v[122:125], v[110:113], v[48:51]
	ds_read_b128 v[110:113], v23 offset:18432
	s_waitcnt lgkmcnt(1)
	v_mfma_f32_16x16x32_f16 v[36:39], v[62:65], v[90:93], v[36:39]
	ds_read_b128 v[122:125], v22 offset:55296
	s_waitcnt lgkmcnt(1)
	v_mfma_f32_16x16x32_f16 v[66:69], v[62:65], v[110:113], v[66:69]
	s_waitcnt vmcnt(4)
	ds_write_b128 v18, v[158:161]
	v_mfma_f32_16x16x32_f16 v[44:47], v[74:77], v[90:93], v[44:47]
	s_waitcnt vmcnt(3)
	ds_write_b128 v19, v[94:97] offset:32768
	v_mfma_f32_16x16x32_f16 v[78:81], v[74:77], v[110:113], v[78:81]
	s_waitcnt vmcnt(2)
	ds_write_b128 v20, v[162:165] offset:32768
	v_mfma_f32_16x16x32_f16 v[82:85], v[118:121], v[90:93], v[82:85]
	s_waitcnt vmcnt(1)
	ds_write_b128 v17, v[166:169] offset:32768
	v_mfma_f32_16x16x32_f16 v[86:89], v[118:121], v[110:113], v[86:89]
	s_waitcnt vmcnt(0)
	ds_write_b128 v18, v[190:193] offset:32768
	s_waitcnt lgkmcnt(5)
	v_mfma_f32_16x16x32_f16 v[28:31], v[122:125], v[90:93], v[28:31]
	ds_read_b128 v[90:93], v23 offset:20480
	v_mfma_f32_16x16x32_f16 v[32:35], v[122:125], v[110:113], v[32:35]
	ds_read_b128 v[110:113], v23 offset:22528
	s_waitcnt lgkmcnt(1)
	v_mfma_f32_16x16x32_f16 v[98:101], v[62:65], v[90:93], v[98:101]
	s_waitcnt lgkmcnt(0)
	v_mfma_f32_16x16x32_f16 v[52:55], v[62:65], v[110:113], v[52:55]
	global_load_dwordx4 v[62:65], v[0:1], off offset:1664
	v_mfma_f32_16x16x32_f16 v[102:105], v[74:77], v[90:93], v[102:105]
	v_mfma_f32_16x16x32_f16 v[24:27], v[74:77], v[110:113], v[24:27]
	v_mfma_f32_16x16x32_f16 v[114:117], v[118:121], v[90:93], v[114:117]
	v_mfma_f32_16x16x32_f16 v[40:43], v[118:121], v[110:113], v[40:43]
	v_mfma_f32_16x16x32_f16 v[70:73], v[122:125], v[90:93], v[70:73]
	global_load_dwordx4 v[90:93], v[2:3], off offset:1664
	global_load_dwordx4 v[126:129], v[4:5], off offset:1664
	global_load_dwordx4 v[130:133], v[6:7], off offset:1664
	global_load_dwordx4 v[74:77], v[8:9], off offset:1664
	global_load_dwordx4 v[138:141], v[10:11], off offset:1664
	global_load_dwordx4 v[142:145], v[12:13], off offset:1664
	global_load_dwordx4 v[154:157], v[14:15], off offset:1664
	s_waitcnt lgkmcnt(0)
	s_barrier
	v_mfma_f32_16x16x32_f16 v[48:51], v[122:125], v[110:113], v[48:51]
	ds_read_b128 v[58:61], v16 offset:32768
	ds_read_b128 v[106:109], v21
	s_waitcnt lgkmcnt(0)
	v_mfma_f32_16x16x32_f16 v[36:39], v[58:61], v[106:109], v[36:39]
	ds_read_b128 v[94:97], v16 offset:34816
	ds_read_b128 v[110:113], v21 offset:2048
	s_waitcnt lgkmcnt(0)
	v_mfma_f32_16x16x32_f16 v[66:69], v[58:61], v[110:113], v[66:69]
	ds_read_b128 v[118:121], v16 offset:36864
	v_mfma_f32_16x16x32_f16 v[44:47], v[94:97], v[106:109], v[44:47]
	ds_read_b128 v[122:125], v16 offset:38912
	v_mfma_f32_16x16x32_f16 v[78:81], v[94:97], v[110:113], v[78:81]
	s_waitcnt lgkmcnt(1)
	v_mfma_f32_16x16x32_f16 v[82:85], v[118:121], v[106:109], v[82:85]
	v_mfma_f32_16x16x32_f16 v[86:89], v[118:121], v[110:113], v[86:89]
	s_waitcnt lgkmcnt(0)
	v_mfma_f32_16x16x32_f16 v[28:31], v[122:125], v[106:109], v[28:31]
	ds_read_b128 v[106:109], v21 offset:4096
	v_mfma_f32_16x16x32_f16 v[32:35], v[122:125], v[110:113], v[32:35]
	ds_read_b128 v[110:113], v21 offset:6144
	s_waitcnt lgkmcnt(1)
	v_mfma_f32_16x16x32_f16 v[98:101], v[58:61], v[106:109], v[98:101]
	s_waitcnt lgkmcnt(0)
	v_mfma_f32_16x16x32_f16 v[52:55], v[58:61], v[110:113], v[52:55]
	ds_read_b128 v[58:61], v22 offset:32768
	v_mfma_f32_16x16x32_f16 v[102:105], v[94:97], v[106:109], v[102:105]
	v_mfma_f32_16x16x32_f16 v[24:27], v[94:97], v[110:113], v[24:27]
	ds_read_b128 v[94:97], v22 offset:34816
	v_mfma_f32_16x16x32_f16 v[114:117], v[118:121], v[106:109], v[114:117]
	s_waitcnt vmcnt(7)
	ds_write_b128 v19, v[62:65] offset:16384
	s_waitcnt vmcnt(6)
; #define GL_LOAD(s_, kt_) if (VAR != 1) { a##s_##0 = GL_A(0, kt_); a##s_##1 = GL_A(1, kt_); a##s_##2 = GL_A(2, kt_); a##s_##3 = GL_A(3, kt_); b##s_##0 = GL_B(0, kt_); b##s_##1 = GL_B(1, kt_); b##s_##2 = GL_B(2, kt_); b##s_##3 = GL_B(3, kt_); }
; #define LDS_STORE(s_, buf_) if (VAR != 2) { LDS_ST1(sA, 0, buf_, a##s_##0) LDS_ST1(sA, 1, buf_, a##s_##1) LDS_ST1(sA, 2, buf_, a##s_##2) LDS_ST1(sA, 3, buf_, a##s_##3) LDS_ST1(sB, 0, buf_, b##s_##0) LDS_ST1(sB, 1, buf_, b##s_##1) LDS_ST1(sB, 2, buf_, b##s_##2) LDS_ST1(sB, 3, buf_, b##s_##3) }
;     ...
;   for (int kt = 0; kt < nk; kt += 2) {
;     if (kt + 2 < nk) { GL_LOAD(0, kt + 2) }
;     MMA_TILE(0)
;     LDS_STORE(1, 1)
;     if (VAR != 4) __syncthreads();
;     if (kt + 3 < nk) { GL_LOAD(1, kt + 3) }
;     MMA_TILE(1)
;     if (kt + 2 < nk) { LDS_STORE(0, 0) }
;     if (VAR != 4) __syncthreads();
	ds_write_b128 v20, v[90:93] offset:16384
	v_mfma_f32_16x16x32_f16 v[40:43], v[118:121], v[110:113], v[40:43]
	ds_read_b128 v[118:121], v22 offset:36864
	s_waitcnt vmcnt(5)
	ds_write_b128 v17, v[126:129] offset:16384
	v_mfma_f32_16x16x32_f16 v[70:73], v[122:125], v[106:109], v[70:73]
	ds_read_b128 v[106:109], v23
	v_mfma_f32_16x16x32_f16 v[48:51], v[122:125], v[110:113], v[48:51]
	ds_read_b128 v[110:113], v23 offset:2048
	s_waitcnt lgkmcnt(1)
	v_mfma_f32_16x16x32_f16 v[36:39], v[58:61], v[106:109], v[36:39]
	ds_read_b128 v[122:125], v22 offset:38912
	s_waitcnt lgkmcnt(1)
	v_mfma_f32_16x16x32_f16 v[66:69], v[58:61], v[110:113], v[66:69]
	s_waitcnt vmcnt(4)
	ds_write_b128 v18, v[130:133] offset:16384
	v_mfma_f32_16x16x32_f16 v[44:47], v[94:97], v[106:109], v[44:47]
	s_waitcnt vmcnt(3)
	ds_write_b128 v19, v[74:77] offset:49152
	v_mfma_f32_16x16x32_f16 v[78:81], v[94:97], v[110:113], v[78:81]
	s_waitcnt vmcnt(2)
	ds_write_b128 v20, v[138:141] offset:49152
	v_mfma_f32_16x16x32_f16 v[82:85], v[118:121], v[106:109], v[82:85]
	s_waitcnt vmcnt(1)
	ds_write_b128 v17, v[142:145] offset:49152
	v_mfma_f32_16x16x32_f16 v[86:89], v[118:121], v[110:113], v[86:89]
	s_waitcnt vmcnt(0)
	ds_write_b128 v18, v[154:157] offset:49152
	s_waitcnt lgkmcnt(5)
	v_mfma_f32_16x16x32_f16 v[28:31], v[122:125], v[106:109], v[28:31]
	ds_read_b128 v[106:109], v23 offset:4096
	v_mfma_f32_16x16x32_f16 v[32:35], v[122:125], v[110:113], v[32:35]
	ds_read_b128 v[110:113], v23 offset:6144
	s_waitcnt lgkmcnt(1)
	v_mfma_f32_16x16x32_f16 v[98:101], v[58:61], v[106:109], v[98:101]
	s_waitcnt lgkmcnt(0)
	v_mfma_f32_16x16x32_f16 v[52:55], v[58:61], v[110:113], v[52:55]
	global_load_dwordx4 v[58:61], v[0:1], off offset:1792
	v_mfma_f32_16x16x32_f16 v[102:105], v[94:97], v[106:109], v[102:105]
	v_mfma_f32_16x16x32_f16 v[24:27], v[94:97], v[110:113], v[24:27]
	v_mfma_f32_16x16x32_f16 v[114:117], v[118:121], v[106:109], v[114:117]
	v_mfma_f32_16x16x32_f16 v[40:43], v[118:121], v[110:113], v[40:43]
	v_mfma_f32_16x16x32_f16 v[70:73], v[122:125], v[106:109], v[70:73]
	global_load_dwordx4 v[106:109], v[2:3], off offset:1792
	global_load_dwordx4 v[134:137], v[4:5], off offset:1792
	global_load_dwordx4 v[158:161], v[6:7], off offset:1792
	global_load_dwordx4 v[94:97], v[8:9], off offset:1792
	global_load_dwordx4 v[162:165], v[10:11], off offset:1792
	global_load_dwordx4 v[166:169], v[12:13], off offset:1792
	global_load_dwordx4 v[190:193], v[14:15], off offset:1792
	s_waitcnt lgkmcnt(0)
	s_barrier
	v_mfma_f32_16x16x32_f16 v[48:51], v[122:125], v[110:113], v[48:51]
	ds_read_b128 v[62:65], v16 offset:49152
	ds_read_b128 v[90:93], v21 offset:16384
	s_waitcnt lgkmcnt(0)
	v_mfma_f32_16x16x32_f16 v[36:39], v[62:65], v[90:93], v[36:39]
	ds_read_b128 v[74:77], v16 offset:51200
	ds_read_b128 v[110:113], v21 offset:18432
	s_waitcnt lgkmcnt(0)
	v_mfma_f32_16x16x32_f16 v[66:69], v[62:65], v[110:113], v[66:69]
	ds_read_b128 v[118:121], v16 offset:53248
	v_mfma_f32_16x16x32_f16 v[44:47], v[74:77], v[90:93], v[44:47]
	ds_read_b128 v[122:125], v16 offset:55296
	v_mfma_f32_16x16x32_f16 v[78:81], v[74:77], v[110:113], v[78:81]
	v_or_b32_e32 v130, s11, v56
	s_waitcnt lgkmcnt(1)
	v_mfma_f32_16x16x32_f16 v[82:85], v[118:121], v[90:93], v[82:85]
	v_lshrrev_b32_e32 v150, 4, v130
	v_mfma_f32_16x16x32_f16 v[86:89], v[118:121], v[110:113], v[86:89]
	s_waitcnt lgkmcnt(0)
	v_mfma_f32_16x16x32_f16 v[28:31], v[122:125], v[90:93], v[28:31]
	ds_read_b128 v[90:93], v21 offset:20480
	v_mfma_f32_16x16x32_f16 v[32:35], v[122:125], v[110:113], v[32:35]
	ds_read_b128 v[110:113], v21 offset:22528
	s_waitcnt lgkmcnt(1)
	v_mfma_f32_16x16x32_f16 v[98:101], v[62:65], v[90:93], v[98:101]
	s_waitcnt lgkmcnt(0)
	v_mfma_f32_16x16x32_f16 v[52:55], v[62:65], v[110:113], v[52:55]
	ds_read_b128 v[62:65], v22 offset:49152
	v_mfma_f32_16x16x32_f16 v[102:105], v[74:77], v[90:93], v[102:105]
	v_mfma_f32_16x16x32_f16 v[24:27], v[74:77], v[110:113], v[24:27]
	ds_read_b128 v[74:77], v22 offset:51200
	v_mfma_f32_16x16x32_f16 v[114:117], v[118:121], v[90:93], v[114:117]
	s_waitcnt vmcnt(7)
	ds_write_b128 v19, v[58:61]
	s_waitcnt vmcnt(6)
	ds_write_b128 v20, v[106:109]
	v_mfma_f32_16x16x32_f16 v[40:43], v[118:121], v[110:113], v[40:43]
	ds_read_b128 v[118:121], v22 offset:53248
	s_waitcnt vmcnt(5)
	ds_write_b128 v17, v[134:137]
	v_mfma_f32_16x16x32_f16 v[70:73], v[122:125], v[90:93], v[70:73]
	ds_read_b128 v[90:93], v23 offset:16384
	v_mfma_f32_16x16x32_f16 v[48:51], v[122:125], v[110:113], v[48:51]
	ds_read_b128 v[110:113], v23 offset:18432
	s_waitcnt lgkmcnt(1)
	v_mfma_f32_16x16x32_f16 v[36:39], v[62:65], v[90:93], v[36:39]
	ds_read_b128 v[122:125], v22 offset:55296
	s_waitcnt lgkmcnt(1)
	v_mfma_f32_16x16x32_f16 v[66:69], v[62:65], v[110:113], v[66:69]
	s_waitcnt vmcnt(4)
	ds_write_b128 v18, v[158:161]
	v_mfma_f32_16x16x32_f16 v[44:47], v[74:77], v[90:93], v[44:47]
	s_waitcnt vmcnt(3)
	ds_write_b128 v19, v[94:97] offset:32768
	v_mfma_f32_16x16x32_f16 v[78:81], v[74:77], v[110:113], v[78:81]
	s_waitcnt vmcnt(2)
	ds_write_b128 v20, v[162:165] offset:32768
	v_mfma_f32_16x16x32_f16 v[82:85], v[118:121], v[90:93], v[82:85]
	s_waitcnt vmcnt(1)
	ds_write_b128 v17, v[166:169] offset:32768
	v_mfma_f32_16x16x32_f16 v[86:89], v[118:121], v[110:113], v[86:89]
	s_waitcnt vmcnt(0)
	ds_write_b128 v18, v[190:193] offset:32768
	s_waitcnt lgkmcnt(5)
	v_mfma_f32_16x16x32_f16 v[28:31], v[122:125], v[90:93], v[28:31]
	ds_read_b128 v[90:93], v23 offset:20480
	v_mfma_f32_16x16x32_f16 v[32:35], v[122:125], v[110:113], v[32:35]
	ds_read_b128 v[110:113], v23 offset:22528
	s_waitcnt lgkmcnt(1)
	v_mfma_f32_16x16x32_f16 v[98:101], v[62:65], v[90:93], v[98:101]
	s_waitcnt lgkmcnt(0)
	v_mfma_f32_16x16x32_f16 v[52:55], v[62:65], v[110:113], v[52:55]
	global_load_dwordx4 v[62:65], v[0:1], off offset:1920
	global_load_dwordx4 v[0:3], v[2:3], off offset:1920
	v_mfma_f32_16x16x32_f16 v[102:105], v[74:77], v[90:93], v[102:105]
	v_mfma_f32_16x16x32_f16 v[24:27], v[74:77], v[110:113], v[24:27]
	v_mfma_f32_16x16x32_f16 v[114:117], v[118:121], v[90:93], v[114:117]
	v_mfma_f32_16x16x32_f16 v[40:43], v[118:121], v[110:113], v[40:43]
	v_mfma_f32_16x16x32_f16 v[70:73], v[122:125], v[90:93], v[70:73]
	global_load_dwordx4 v[90:93], v[4:5], off offset:1920
	global_load_dwordx4 v[4:7], v[6:7], off offset:1920
	global_load_dwordx4 v[74:77], v[8:9], off offset:1920
	global_load_dwordx4 v[8:11], v[10:11], off offset:1920
	global_load_dwordx4 v[126:129], v[12:13], off offset:1920
	global_load_dwordx4 v[12:15], v[14:15], off offset:1920
	s_waitcnt lgkmcnt(0)
	s_barrier
; #define GL_LOAD(s_, kt_) if (VAR != 1) { a##s_##0 = GL_A(0, kt_); a##s_##1 = GL_A(1, kt_); a##s_##2 = GL_A(2, kt_); a##s_##3 = GL_A(3, kt_); b##s_##0 = GL_B(0, kt_); b##s_##1 = GL_B(1, kt_); b##s_##2 = GL_B(2, kt_); b##s_##3 = GL_B(3, kt_); }
; #define LDS_STORE(s_, buf_) if (VAR != 2) { LDS_ST1(sA, 0, buf_, a##s_##0) LDS_ST1(sA, 1, buf_, a##s_##1) LDS_ST1(sA, 2, buf_, a##s_##2) LDS_ST1(sA, 3, buf_, a##s_##3) LDS_ST1(sB, 0, buf_, b##s_##0) LDS_ST1(sB, 1, buf_, b##s_##1) LDS_ST1(sB, 2, buf_, b##s_##2) LDS_ST1(sB, 3, buf_, b##s_##3) }
;     ...
;   for (int kt = 0; kt < nk; kt += 2) {
;     if (kt + 2 < nk) { GL_LOAD(0, kt + 2) }
;     MMA_TILE(0)
;     LDS_STORE(1, 1)
;     if (VAR != 4) __syncthreads();
;     if (kt + 3 < nk) { GL_LOAD(1, kt + 3) }
;     MMA_TILE(1)
;     if (kt + 2 < nk) { LDS_STORE(0, 0) }
;     if (VAR != 4) __syncthreads();
;   }
	ds_read_b128 v[58:61], v16 offset:32768
	v_mfma_f32_16x16x32_f16 v[48:51], v[122:125], v[110:113], v[48:51]
	ds_read_b128 v[94:97], v16 offset:34816
	ds_read_b128 v[106:109], v21
	ds_read_b128 v[110:113], v21 offset:2048
	ds_read_b128 v[118:121], v16 offset:36864
	ds_read_b128 v[122:125], v16 offset:38912
	s_waitcnt lgkmcnt(3)
	v_mfma_f32_16x16x32_f16 v[36:39], v[58:61], v[106:109], v[36:39]
	v_mfma_f32_16x16x32_f16 v[44:47], v[94:97], v[106:109], v[44:47]
	s_waitcnt lgkmcnt(1)
	v_mfma_f32_16x16x32_f16 v[82:85], v[118:121], v[106:109], v[82:85]
	s_waitcnt lgkmcnt(0)
	v_mfma_f32_16x16x32_f16 v[28:31], v[122:125], v[106:109], v[28:31]
	v_mfma_f32_16x16x32_f16 v[66:69], v[58:61], v[110:113], v[66:69]
	v_mfma_f32_16x16x32_f16 v[78:81], v[94:97], v[110:113], v[78:81]
	v_mfma_f32_16x16x32_f16 v[86:89], v[118:121], v[110:113], v[86:89]
	v_mfma_f32_16x16x32_f16 v[32:35], v[122:125], v[110:113], v[32:35]
	ds_read_b128 v[106:109], v21 offset:4096
	ds_read_b128 v[110:113], v21 offset:6144
	s_waitcnt lgkmcnt(1)
	v_mfma_f32_16x16x32_f16 v[98:101], v[58:61], v[106:109], v[98:101]
	v_mfma_f32_16x16x32_f16 v[102:105], v[94:97], v[106:109], v[102:105]
	v_mfma_f32_16x16x32_f16 v[114:117], v[118:121], v[106:109], v[114:117]
	v_mfma_f32_16x16x32_f16 v[70:73], v[122:125], v[106:109], v[70:73]
	s_waitcnt lgkmcnt(0)
	v_mfma_f32_16x16x32_f16 v[52:55], v[58:61], v[110:113], v[52:55]
	ds_read_b128 v[58:61], v22 offset:32768
	v_mfma_f32_16x16x32_f16 v[24:27], v[94:97], v[110:113], v[24:27]
	v_mfma_f32_16x16x32_f16 v[40:43], v[118:121], v[110:113], v[40:43]
	v_mfma_f32_16x16x32_f16 v[48:51], v[122:125], v[110:113], v[48:51]
	ds_read_b128 v[94:97], v22 offset:34816
	ds_read_b128 v[106:109], v23
	ds_read_b128 v[110:113], v23 offset:2048
	ds_read_b128 v[118:121], v22 offset:36864
	ds_read_b128 v[122:125], v22 offset:38912
	s_waitcnt lgkmcnt(3)
	v_mfma_f32_16x16x32_f16 v[36:39], v[58:61], v[106:109], v[36:39]
	v_mfma_f32_16x16x32_f16 v[44:47], v[94:97], v[106:109], v[44:47]
	s_waitcnt lgkmcnt(1)
	v_mfma_f32_16x16x32_f16 v[82:85], v[118:121], v[106:109], v[82:85]
	s_waitcnt lgkmcnt(0)
	v_mfma_f32_16x16x32_f16 v[28:31], v[122:125], v[106:109], v[28:31]
	v_mfma_f32_16x16x32_f16 v[66:69], v[58:61], v[110:113], v[66:69]
	v_mfma_f32_16x16x32_f16 v[78:81], v[94:97], v[110:113], v[78:81]
	v_mfma_f32_16x16x32_f16 v[86:89], v[118:121], v[110:113], v[86:89]
	v_mfma_f32_16x16x32_f16 v[32:35], v[122:125], v[110:113], v[32:35]
	ds_read_b128 v[106:109], v23 offset:4096
	ds_read_b128 v[110:113], v23 offset:6144
	s_waitcnt vmcnt(7)
	ds_write_b128 v19, v[62:65] offset:16384
	s_waitcnt vmcnt(6)
	ds_write_b128 v20, v[0:3] offset:16384
	s_waitcnt vmcnt(5)
	ds_write_b128 v17, v[90:93] offset:16384
	s_waitcnt vmcnt(4)
	ds_write_b128 v18, v[4:7] offset:16384
	s_waitcnt vmcnt(3)
	ds_write_b128 v19, v[74:77] offset:49152
	s_waitcnt vmcnt(2)
	ds_write_b128 v20, v[8:11] offset:49152
	s_waitcnt lgkmcnt(7)
	v_mfma_f32_16x16x32_f16 v[98:101], v[58:61], v[106:109], v[98:101]
	s_waitcnt vmcnt(1)
	ds_write_b128 v17, v[126:129] offset:49152
	s_waitcnt vmcnt(0)
	ds_write_b128 v18, v[12:15] offset:49152
	s_waitcnt lgkmcnt(0)
	s_barrier
	v_mfma_f32_16x16x32_f16 v[52:55], v[58:61], v[110:113], v[52:55]
	ds_read_b128 v[8:11], v16 offset:49152
	v_mfma_f32_16x16x32_f16 v[0:3], v[94:97], v[110:113], v[24:27]
	v_mfma_f32_16x16x32_f16 v[4:7], v[118:121], v[110:113], v[40:43]
	v_mfma_f32_16x16x32_f16 v[12:15], v[122:125], v[110:113], v[48:51]
	s_nop 0
	ds_read_b128 v[24:27], v16 offset:51200
	ds_read_b128 v[40:43], v21 offset:16384
	ds_read_b128 v[48:51], v21 offset:18432
	ds_read_b128 v[58:61], v16 offset:53248
	ds_read_b128 v[16:19], v16 offset:55296
	v_mfma_f32_16x16x32_f16 v[102:105], v[94:97], v[106:109], v[102:105]
	v_mfma_f32_16x16x32_f16 v[114:117], v[118:121], v[106:109], v[114:117]
	v_mfma_f32_16x16x32_f16 v[70:73], v[122:125], v[106:109], v[70:73]
	s_waitcnt lgkmcnt(3)
	v_mfma_f32_16x16x32_f16 v[36:39], v[8:11], v[40:43], v[36:39]
	v_mfma_f32_16x16x32_f16 v[44:47], v[24:27], v[40:43], v[44:47]
	s_waitcnt lgkmcnt(1)
	v_mfma_f32_16x16x32_f16 v[62:65], v[58:61], v[40:43], v[82:85]
	ds_read_b128 v[74:77], v21 offset:20480
	s_nop 1
	ds_read_b128 v[82:85], v21 offset:22528
	s_waitcnt lgkmcnt(2)
	v_mfma_f32_16x16x32_f16 v[28:31], v[16:19], v[40:43], v[28:31]
	ds_read_b128 v[40:43], v23 offset:16384
	ds_read_b128 v[90:93], v23 offset:18432
	ds_read_b128 v[94:97], v22 offset:49152
	ds_read_b128 v[106:109], v22 offset:51200
	ds_read_b128 v[110:113], v23 offset:20480
	ds_read_b128 v[118:121], v23 offset:22528
	ds_read_b128 v[122:125], v22 offset:53248
	ds_read_b128 v[126:129], v22 offset:55296
	s_waitcnt lgkmcnt(0)
	v_mfma_f32_16x16x32_f16 v[20:23], v[24:27], v[48:51], v[78:81]
	s_barrier
; DI int TIDX() { int t = threadIdx.x; asm volatile("" : "+v"(t)); return t; }
; DI unsigned pack2(float lo, float hi) { f2_t v = {lo, hi}; h2_t b = __builtin_convertvector(v, h2_t); return __builtin_bit_cast(unsigned, b); }
; DI void epi_residual(const f32x4 (&v)[4][4], int row0, int col0, const float* xsrc, float* x, bf16_t* xb, float* ssq_out, bool write_xb, bool write_ssq) {
;   const int lane = TIDX() & 63, lr = lane & 15, g = lane >> 4;
; #pragma unroll
;   for (int mt = 0; mt < 4; ++mt) {
;     const int row = row0 + mt * 16 + lr;
;     float ss = 0.f;
; #pragma unroll
;     for (int nt = 0; nt < 4; ++nt) {
;       const int col = col0 + nt * 16 + 4 * g;
;       float4* px = (float4*)(x + (size_t)row * DM + col);
;       float4 o = *(const float4*)(xsrc + (size_t)row * DM + col);
;       o.x += v[mt][nt][0]; o.y += v[mt][nt][1]; o.z += v[mt][nt][2]; o.w += v[mt][nt][3];
;       *px = o;
;       ss += (o.x * o.x + o.y * o.y) + (o.z * o.z + o.w * o.w);
;       if (write_xb) *(uint2*)(xb + (size_t)row * DM + col) = make_uint2(pack2(o.x, o.y), pack2(o.z, o.w));
;     }
;     if (write_ssq) {
;       ss += __shfl_xor(ss, 16); ss += __shfl_xor(ss, 32);
;       if (g == 0) ssq_out[(size_t)row * 16 + (col0 >> 6)] = ss;
;     }
;   }
	s_setprio 0
	v_mfma_f32_16x16x32_f16 v[78:81], v[58:61], v[48:51], v[86:89]
	s_nop 2
	v_add_u32_e32 v86, s6, v57
	v_mov_b32_e32 v87, v148
	v_mfma_f32_16x16x32_f16 v[66:69], v[8:11], v[48:51], v[66:69]
	v_readlane_b32 s6, v254, 41
	v_bfe_u32 v134, v87, 4, 2
	v_mfma_f32_16x16x32_f16 v[32:35], v[16:19], v[48:51], v[32:35]
	v_and_or_b32 v50, v87, 15, v86
	v_ashrrev_i32_e32 v51, 31, v50
	v_lshl_or_b32 v135, v134, 2, v130
	v_readlane_b32 s7, v254, 42
	v_lshlrev_b64 v[130:131], 12, v[50:51]
	v_lshl_add_u64 v[132:133], s[4:5], 0, v[130:131]
	v_lshl_add_u64 v[48:49], s[6:7], 0, v[150:151]
	v_lshlrev_b32_e32 v150, 2, v135
	v_lshl_add_u64 v[132:133], v[132:133], 0, v[150:151]
	v_mfma_f32_16x16x32_f16 v[86:89], v[8:11], v[74:77], v[98:101]
	v_readlane_b32 s6, v254, 43
	v_readlane_b32 s7, v254, 44
	v_cmp_eq_u32_e32 vcc, 0, v134
	v_mfma_f32_16x16x32_f16 v[98:101], v[24:27], v[74:77], v[102:105]
	v_mfma_f32_16x16x32_f16 v[102:105], v[58:61], v[74:77], v[114:117]
	s_nop 2
	global_load_dwordx4 v[114:117], v[132:133], off
	v_mfma_f32_16x16x32_f16 v[36:39], v[94:97], v[40:43], v[36:39]
	v_mfma_f32_16x16x32_f16 v[70:73], v[16:19], v[74:77], v[70:73]
	v_lshlrev_b64 v[76:77], 11, v[50:51]
	v_lshl_add_u64 v[74:75], s[12:13], 0, v[130:131]
	v_lshl_add_u64 v[76:77], s[6:7], 0, v[76:77]
	v_mfma_f32_16x16x32_f16 v[8:11], v[8:11], v[82:85], v[52:55]
	v_lshl_add_u64 v[74:75], v[74:75], 0, v[150:151]
	s_waitcnt vmcnt(0)
	s_nop 0
	v_pk_add_f32 v[36:37], v[36:37], v[114:115]
	v_pk_add_f32 v[38:39], v[38:39], v[116:117]
	v_lshlrev_b32_e32 v52, 1, v135
	v_mov_b32_e32 v53, v151
	v_cvt_pk_f16_f32 v54, v36, v37
	v_cvt_pk_f16_f32 v55, v38, v39
	v_lshl_add_u64 v[76:77], v[76:77], 0, v[52:53]
	global_store_dwordx4 v[74:75], v[36:39], off
	global_store_dwordx2 v[76:77], v[54:55], off
	v_mfma_f32_16x16x32_f16 v[0:3], v[24:27], v[82:85], v[0:3]
	v_mul_f32_e64 v54, v36, v36
	v_mul_f32_e64 v55, v37, v37
	v_mfma_f32_16x16x32_f16 v[24:27], v[106:109], v[40:43], v[44:47]
	s_nop 2
	global_load_dwordx4 v[44:47], v[132:133], off offset:64
	v_mfma_f32_16x16x32_f16 v[4:7], v[58:61], v[82:85], v[4:7]
	s_waitcnt vmcnt(0)
	s_nop 1
	v_pk_add_f32 v[24:25], v[24:25], v[44:45]
	v_pk_add_f32 v[26:27], v[26:27], v[46:47]
	v_cvt_pk_f16_f32 v44, v24, v25
	v_cvt_pk_f16_f32 v45, v26, v27
	global_store_dwordx4 v[74:75], v[24:27], off offset:64
	global_store_dwordx2 v[76:77], v[44:45], off offset:32
	v_mfma_f32_16x16x32_f16 v[58:61], v[16:19], v[82:85], v[12:15]
	s_nop 2
	global_load_dwordx4 v[12:15], v[132:133], off offset:128
	v_mfma_f32_16x16x32_f16 v[16:19], v[122:125], v[40:43], v[62:65]
	v_mfma_f32_16x16x32_f16 v[44:47], v[94:97], v[90:93], v[66:69]
	s_nop 2
	v_mul_f32_e64 v66, v26, v26
	v_mul_f32_e64 v67, v27, v27
	v_mfma_f32_16x16x32_f16 v[32:35], v[126:129], v[90:93], v[32:35]
	s_waitcnt vmcnt(0)
	v_pk_add_f32 v[12:13], v[16:17], v[12:13]
	v_pk_add_f32 v[14:15], v[18:19], v[14:15]
	v_mfma_f32_16x16x32_f16 v[16:19], v[126:129], v[40:43], v[28:31]
	global_store_dwordx4 v[74:75], v[12:15], off offset:128
	s_nop 1
	v_cvt_pk_f16_f32 v28, v12, v13
	v_cvt_pk_f16_f32 v29, v14, v15
	global_store_dwordx2 v[76:77], v[28:29], off offset:64
	global_load_dwordx4 v[28:31], v[132:133], off offset:192
	v_mfma_f32_16x16x32_f16 v[40:43], v[106:109], v[90:93], v[20:23]
	v_mul_f32_e64 v12, v12, v12
	v_mul_f32_e64 v13, v13, v13
	v_pk_mul_f32 v[14:15], v[14:15], v[14:15]
	v_add_f32_e32 v12, v12, v13
	v_pk_mul_f32 v[20:21], v[38:39], v[38:39]
	v_pk_mul_f32 v[22:23], v[24:25], v[24:25]
	v_add_f32_e32 v14, v14, v15
	v_add_f32_e32 v12, v12, v14
	v_mfma_f32_16x16x32_f16 v[36:39], v[122:125], v[90:93], v[78:81]
	s_waitcnt vmcnt(0)
	v_pk_add_f32 v[62:63], v[16:17], v[28:29]
	v_add_f32_e32 v16, v20, v21
	v_add_f32_e32 v17, v54, v55
	v_pk_add_f32 v[64:65], v[18:19], v[30:31]
	v_add_f32_e32 v16, v17, v16
	v_add_f32_e32 v17, v66, v67
	v_add_f32_e32 v18, v22, v23
	v_add_f32_e32 v17, v18, v17
	global_store_dwordx4 v[74:75], v[62:65], off offset:192
	v_pk_mul_f32 v[68:69], v[62:63], v[62:63]
	v_pk_mul_f32 v[74:75], v[64:65], v[64:65]
	v_add_f32_e32 v54, v16, v17
	v_add_f32_e32 v54, v54, v12
	v_mfma_f32_16x16x32_f16 v[12:15], v[94:97], v[118:121], v[8:11]
	s_nop 2
	v_add_f32_e32 v8, v74, v75
	v_add_f32_e32 v9, v68, v69
	v_add_f32_e32 v55, v9, v8
	v_mfma_f32_16x16x32_f16 v[8:11], v[106:109], v[118:121], v[0:3]
	s_nop 2
	v_add_f32_e32 v2, v54, v55
	ds_bpermute_b32 v3, v189, v2
	v_cvt_pk_f16_f32 v0, v62, v63
	v_cvt_pk_f16_f32 v1, v64, v65
	v_mfma_f32_16x16x32_f16 v[28:31], v[94:97], v[110:113], v[86:89]
	global_store_dwordx2 v[76:77], v[0:1], off offset:96
	s_waitcnt lgkmcnt(0)
	v_add_f32_e32 v54, v2, v3
	ds_bpermute_b32 v55, v188, v54
	v_mfma_f32_16x16x32_f16 v[24:27], v[106:109], v[110:113], v[98:101]
	v_mfma_f32_16x16x32_f16 v[20:23], v[122:125], v[110:113], v[102:105]
	v_mfma_f32_16x16x32_f16 v[16:19], v[126:129], v[110:113], v[70:73]
	v_mfma_f32_16x16x32_f16 v[4:7], v[122:125], v[118:121], v[4:7]
	v_mfma_f32_16x16x32_f16 v[0:3], v[126:129], v[118:121], v[58:61]
	s_and_saveexec_b64 s[6:7], vcc
	s_cbranch_execz .LBB0_1252
	s_waitcnt lgkmcnt(0)
	v_add_f32_e32 v58, v54, v55
	v_lshlrev_b64 v[54:55], 6, v[50:51]
	v_lshl_add_u64 v[54:55], v[48:49], 0, v[54:55]
	global_store_dword v[54:55], v58, off

; DI int BIDX() { int b = blockIdx.x; asm volatile("" : "+s"(b)); return b; }
; DI int tile_groups(int MT, int NT) { return (MT >> 6) * ((NT + 7) >> 3) * 512; }
; DI void load_rstd(float (&rs)[4], const float* ssq, int row0, int lr) {
; #pragma unroll
;   for (int mt = 0; mt < 4; ++mt) {
;     const float4* q = (const float4*)(ssq + (size_t)(row0 + mt * 16 + lr) * 16);
;     const float4 a = q[0], b = q[1], c = q[2], d = q[3];
;     const float s = ((a.x + a.y) + (a.z + a.w)) + ((b.x + b.y) + (b.z + b.w)) + ((c.x + c.y) + (c.z + c.w)) + ((d.x + d.y) + (d.z + d.w));
;     rs[mt] = rsqrtf(s * (1.0f / 1024.0f) + EPS);
;   }
; template <int VAR> DI void phase_up(const Params& P, int l, char* smem) {
;     ...
;   for (int vb = BIDX(); vb < tile_groups(128, 32); vb += gridDim.x) {
;     int tm, tn; if (!tile_of(vb, 128, 32, tm, tn)) continue;
;     const int m0 = tm * 128, n0 = tn * 128;
;     const int row0 = m0 + wm * 64, col0 = n0 + wn * 64;
;     f32x4 acc[4][4]; zero_acc(acc);
;     float rs[4]; load_rstd(rs, ssq, row0, lr);
.LBB0_1313:
	s_ashr_i32 s4, s2, 9
	s_lshr_b32 s1, s4, 30
	s_add_i32 s1, s4, s1
	s_ashr_i32 s5, s1, 2
	s_lshl_b32 s1, s5, 6
	s_and_b32 s6, s12, 56
	s_lshl_b32 s5, s5, 5
	s_lshl_b32 s4, s4, 3
	s_or_b32 s1, s1, s6
	s_bfe_u32 s6, s2, 0x30003
	s_sub_i32 s4, s4, s5
	s_bfe_u32 s5, s2, 0x30006
	s_or_b32 s1, s1, s6
	s_or_b32 s4, s4, s5
	s_cmpk_lt_i32 s1, 0x80
	s_cselect_b64 s[6:7], -1, 0
	s_cmp_lt_i32 s4, 32
	s_cselect_b64 s[8:9], -1, 0
	s_and_b64 s[6:7], s[6:7], s[8:9]
	s_andn2_b64 vcc, exec, s[6:7]
	s_cbranch_vccnz .LBB0_1312
	s_lshl_b32 s8, s1, 7
	v_add_u32_e32 v102, s8, v125
	v_ashrrev_i32_e32 v103, 31, v102
	v_readlane_b32 s14, v254, 41
	v_lshlrev_b64 v[0:1], 6, v[102:103]
	v_readlane_b32 s15, v254, 42
	v_or_b32_e32 v98, 16, v102
	v_ashrrev_i32_e32 v99, 31, v98
	v_lshl_add_u64 v[12:13], s[14:15], 0, v[0:1]
	global_load_dwordx4 v[0:3], v[12:13], off offset:32
	global_load_dwordx4 v[4:7], v[12:13], off offset:16
	global_load_dwordx4 v[8:11], v[12:13], off
	s_nop 0
	global_load_dwordx4 v[12:15], v[12:13], off offset:48
	s_lshl_b32 s6, s4, 7
	s_mov_b32 s4, 0x358637bd
	s_mov_b32 s16, 0x3a800000
	s_mov_b32 s1, 0x800000
	v_or_b32_e32 v106, 32, v102
	v_ashrrev_i32_e32 v107, 31, v106
	v_or_b32_e32 v104, 48, v102
	v_ashrrev_i32_e32 v105, 31, v104
	s_ashr_i32 s9, s8, 31
	s_waitcnt vmcnt(7)
	v_mov_b32_e32 v72, v148
	v_or_b32_e32 v100, s6, v124
	s_waitcnt vmcnt(2)
	v_mov_b32_e32 v18, v5
	s_waitcnt vmcnt(1)
	v_mov_b32_e32 v16, v9
	v_mov_b32_e32 v17, v10
	v_mov_b32_e32 v19, v6
	v_mov_b32_e32 v9, v11
	v_mov_b32_e32 v5, v7
	v_mov_b32_e32 v6, v1
	v_pk_add_f32 v[8:9], v[16:17], v[8:9]
	v_pk_add_f32 v[4:5], v[18:19], v[4:5]
	v_pk_add_f32 v[0:1], v[0:1], v[6:7]
	v_mov_b32_e32 v6, v3
	v_pk_add_f32 v[8:9], v[8:9], v[8:9] op_sel:[0,1] op_sel_hi:[1,0]
	v_pk_add_f32 v[4:5], v[4:5], v[4:5] op_sel:[0,1] op_sel_hi:[1,0]
	v_pk_add_f32 v[2:3], v[2:3], v[6:7]
	s_waitcnt vmcnt(0)
	v_mov_b32_e32 v9, v12
	v_mov_b32_e32 v5, v13
	v_mov_b32_e32 v1, v14
	v_mov_b32_e32 v3, v15
	v_pk_add_f32 v[4:5], v[8:9], v[4:5]
	v_pk_add_f32 v[0:1], v[0:1], v[2:3]
	s_nop 0
	v_pk_add_f32 v[16:17], v[4:5], v[0:1]
	v_lshlrev_b64 v[0:1], 6, v[98:99]
	v_lshl_add_u64 v[12:13], s[14:15], 0, v[0:1]
	global_load_dwordx4 v[0:3], v[12:13], off offset:32
	global_load_dwordx4 v[4:7], v[12:13], off offset:16
	global_load_dwordx4 v[8:11], v[12:13], off
	s_nop 0
	global_load_dwordx4 v[12:15], v[12:13], off offset:48
	s_waitcnt vmcnt(2)
	v_mov_b32_e32 v20, v5
	s_waitcnt vmcnt(1)
	v_mov_b32_e32 v18, v9
	v_mov_b32_e32 v19, v10
	v_mov_b32_e32 v21, v6
	v_mov_b32_e32 v9, v11
	v_mov_b32_e32 v5, v7
	v_mov_b32_e32 v6, v1
	v_pk_add_f32 v[8:9], v[18:19], v[8:9]
	v_pk_add_f32 v[4:5], v[20:21], v[4:5]
	v_pk_add_f32 v[0:1], v[0:1], v[6:7]
	v_mov_b32_e32 v6, v3
	v_pk_add_f32 v[8:9], v[8:9], v[8:9] op_sel:[0,1] op_sel_hi:[1,0]
	v_pk_add_f32 v[4:5], v[4:5], v[4:5] op_sel:[0,1] op_sel_hi:[1,0]
	v_pk_add_f32 v[2:3], v[2:3], v[6:7]
	s_waitcnt vmcnt(0)
	v_mov_b32_e32 v9, v12
	v_mov_b32_e32 v5, v13
	v_mov_b32_e32 v1, v14
	v_mov_b32_e32 v3, v15
	v_pk_add_f32 v[4:5], v[8:9], v[4:5]
	v_pk_add_f32 v[0:1], v[0:1], v[2:3]
	v_mov_b32_e32 v3, v16
	v_pk_add_f32 v[0:1], v[4:5], v[0:1]
	s_nop 0
	v_mov_b32_e32 v2, v0
	v_mov_b32_e32 v16, v1
	v_pk_add_f32 v[2:3], v[2:3], v[16:17]
	v_mov_b64_e32 v[0:1], s[4:5]
	v_pk_fma_f32 v[2:3], v[2:3], s[16:17], v[0:1] op_sel_hi:[1,0,0]
	s_nop 0
	v_mul_f32_e32 v4, 0x4b800000, v3
	v_cmp_gt_f32_e64 s[4:5], s1, v3
	v_cmp_gt_f32_e32 vcc, s1, v2
	s_nop 0
	v_cndmask_b32_e64 v3, v3, v4, s[4:5]
	v_rsq_f32_e32 v3, v3
	s_nop 0
	v_mul_f32_e32 v4, 0x45800000, v3
	v_cndmask_b32_e64 v128, v3, v4, s[4:5]
	v_mul_f32_e32 v3, 0x4b800000, v2
	v_cndmask_b32_e32 v2, v2, v3, vcc
	v_rsq_f32_e32 v2, v2
	s_nop 0
	v_mul_f32_e32 v3, 0x45800000, v2
	v_cndmask_b32_e32 v126, v2, v3, vcc
	v_lshlrev_b64 v[2:3], 6, v[106:107]
	v_lshl_add_u64 v[14:15], s[14:15], 0, v[2:3]
	global_load_dwordx4 v[2:5], v[14:15], off offset:32
	global_load_dwordx4 v[6:9], v[14:15], off offset:16
	global_load_dwordx4 v[10:13], v[14:15], off
	s_nop 0
	global_load_dwordx4 v[14:17], v[14:15], off offset:48
	s_waitcnt vmcnt(2)
	v_mov_b32_e32 v20, v7
	s_waitcnt vmcnt(1)
	v_mov_b32_e32 v18, v11
	v_mov_b32_e32 v19, v12
	v_mov_b32_e32 v21, v8
	v_mov_b32_e32 v11, v13
	v_mov_b32_e32 v7, v9
	v_mov_b32_e32 v8, v3
	v_pk_add_f32 v[10:11], v[18:19], v[10:11]
	v_pk_add_f32 v[6:7], v[20:21], v[6:7]
	v_pk_add_f32 v[2:3], v[2:3], v[8:9]
	v_mov_b32_e32 v8, v5
	v_pk_add_f32 v[10:11], v[10:11], v[10:11] op_sel:[0,1] op_sel_hi:[1,0]
	v_pk_add_f32 v[6:7], v[6:7], v[6:7] op_sel:[0,1] op_sel_hi:[1,0]
	v_pk_add_f32 v[4:5], v[4:5], v[8:9]
	s_waitcnt vmcnt(0)
	v_mov_b32_e32 v11, v14
	v_mov_b32_e32 v7, v15
	v_mov_b32_e32 v3, v16
	v_mov_b32_e32 v5, v17
	v_pk_add_f32 v[6:7], v[10:11], v[6:7]
	v_pk_add_f32 v[2:3], v[2:3], v[4:5]
	s_nop 0
	v_pk_add_f32 v[18:19], v[6:7], v[2:3]
	v_lshlrev_b64 v[2:3], 6, v[104:105]
	v_lshl_add_u64 v[14:15], s[14:15], 0, v[2:3]
	global_load_dwordx4 v[2:5], v[14:15], off offset:32
	global_load_dwordx4 v[6:9], v[14:15], off offset:16
	global_load_dwordx4 v[10:13], v[14:15], off
	s_nop 0
	global_load_dwordx4 v[14:17], v[14:15], off offset:48
	s_waitcnt vmcnt(2)
	v_mov_b32_e32 v22, v7
	s_waitcnt vmcnt(1)
	v_mov_b32_e32 v20, v11
	v_mov_b32_e32 v21, v12
	v_mov_b32_e32 v23, v8
	v_mov_b32_e32 v11, v13
	v_mov_b32_e32 v7, v9
	v_mov_b32_e32 v8, v3
	v_pk_add_f32 v[10:11], v[20:21], v[10:11]
	v_pk_add_f32 v[6:7], v[22:23], v[6:7]
	v_pk_add_f32 v[2:3], v[2:3], v[8:9]
	v_mov_b32_e32 v8, v5
	v_pk_add_f32 v[10:11], v[10:11], v[10:11] op_sel:[0,1] op_sel_hi:[1,0]
	v_pk_add_f32 v[6:7], v[6:7], v[6:7] op_sel:[0,1] op_sel_hi:[1,0]
	v_pk_add_f32 v[4:5], v[4:5], v[8:9]
	s_waitcnt vmcnt(0)
; #define GL_LOAD(s_, kt_) if (VAR != 1) { a##s_##0 = GL_A(0, kt_); a##s_##1 = GL_A(1, kt_); a##s_##2 = GL_A(2, kt_); a##s_##3 = GL_A(3, kt_); b##s_##0 = GL_B(0, kt_); b##s_##1 = GL_B(1, kt_); b##s_##2 = GL_B(2, kt_); b##s_##3 = GL_B(3, kt_); }
; #define LDS_STORE(s_, buf_) if (VAR != 2) { LDS_ST1(sA, 0, buf_, a##s_##0) LDS_ST1(sA, 1, buf_, a##s_##1) LDS_ST1(sA, 2, buf_, a##s_##2) LDS_ST1(sA, 3, buf_, a##s_##3) LDS_ST1(sB, 0, buf_, b##s_##0) LDS_ST1(sB, 1, buf_, b##s_##1) LDS_ST1(sB, 2, buf_, b##s_##2) LDS_ST1(sB, 3, buf_, b##s_##3) }
;     ...
;   GL_LOAD(0, 0)
;   GL_LOAD(1, 1)
;   LDS_STORE(0, 0)
;   if (VAR != 4) __syncthreads();
; DI void load_rstd(float (&rs)[4], const float* ssq, int row0, int lr) {
; #pragma unroll
;   for (int mt = 0; mt < 4; ++mt) {
;     const float4* q = (const float4*)(ssq + (size_t)(row0 + mt * 16 + lr) * 16);
;     const float4 a = q[0], b = q[1], c = q[2], d = q[3];
;     const float s = ((a.x + a.y) + (a.z + a.w)) + ((b.x + b.y) + (b.z + b.w)) + ((c.x + c.y) + (c.z + c.w)) + ((d.x + d.y) + (d.z + d.w));
;     rs[mt] = rsqrtf(s * (1.0f / 1024.0f) + EPS);
;   }
	v_mov_b32_e32 v11, v14
	v_mov_b32_e32 v7, v15
	v_mov_b32_e32 v3, v16
	v_mov_b32_e32 v5, v17
	v_pk_add_f32 v[6:7], v[10:11], v[6:7]
	v_pk_add_f32 v[2:3], v[2:3], v[4:5]
	v_mov_b32_e32 v5, v18
	v_pk_add_f32 v[2:3], v[6:7], v[2:3]
	v_ashrrev_i32_e32 v64, 3, v72
	v_mov_b32_e32 v4, v2
	v_mov_b32_e32 v18, v3
	v_pk_add_f32 v[2:3], v[4:5], v[18:19]
	v_ashrrev_i32_e32 v65, 31, v64
	v_pk_fma_f32 v[0:1], v[2:3], s[16:17], v[0:1] op_sel_hi:[1,0,0]
	v_and_b32_e32 v75, 48, v72
	v_mul_f32_e32 v2, 0x4b800000, v1
	v_cmp_gt_f32_e64 s[4:5], s1, v1
	v_cmp_gt_f32_e32 vcc, s1, v0
	v_lshlrev_b64 v[16:17], 11, v[64:65]
	v_cndmask_b32_e64 v1, v1, v2, s[4:5]
	v_rsq_f32_e32 v1, v1
	v_lshlrev_b32_e32 v65, 4, v72
	v_and_b32_e32 v150, 0x70, v65
	v_add_u32_e32 v66, 32, v64
	v_mul_f32_e32 v2, 0x45800000, v1
	v_cndmask_b32_e64 v129, v1, v2, s[4:5]
	v_mul_f32_e32 v1, 0x4b800000, v0
	v_cndmask_b32_e32 v0, v0, v1, vcc
	v_rsq_f32_e32 v0, v0
	s_lshl_b64 s[4:5], s[8:9], 11
	v_readlane_b32 s8, v254, 43
	v_readlane_b32 s9, v254, 44
	v_mul_f32_e32 v1, 0x45800000, v0
	s_add_u32 s4, s8, s4
	v_cndmask_b32_e32 v127, v0, v1, vcc
	s_addc_u32 s5, s9, s5
	v_lshlrev_b32_e32 v0, 3, v72
	s_ashr_i32 s7, s6, 31
	v_and_b32_e32 v74, 0x70, v0
	v_bitop3_b32 v134, v0, v75, s23 bitop3:0x6c
	v_lshl_add_u64 v[0:1], s[4:5], 0, v[16:17]
	v_add_u32_e32 v68, 64, v64
	v_add_u32_e32 v70, 0x60, v64
	s_lshl_b64 s[6:7], s[6:7], 11
	v_lshl_add_u64 v[108:109], v[0:1], 0, v[150:151]
	v_ashrrev_i32_e32 v67, 31, v66
	v_ashrrev_i32_e32 v69, 31, v68
	v_ashrrev_i32_e32 v71, 31, v70
	s_add_u32 s6, s10, s6
	v_lshlrev_b64 v[20:21], 11, v[66:67]
	v_lshlrev_b64 v[24:25], 11, v[68:69]
	v_lshlrev_b64 v[28:29], 11, v[70:71]
	s_addc_u32 s7, s11, s7
	v_lshl_add_u64 v[4:5], s[4:5], 0, v[20:21]
	v_lshl_add_u64 v[8:9], s[4:5], 0, v[24:25]
	v_lshl_add_u64 v[12:13], s[4:5], 0, v[28:29]
	v_lshl_add_u64 v[110:111], v[4:5], 0, v[150:151]
	v_lshl_add_u64 v[112:113], v[8:9], 0, v[150:151]
	v_lshl_add_u64 v[114:115], v[12:13], 0, v[150:151]
	v_lshl_add_u64 v[16:17], s[6:7], 0, v[16:17]
	v_lshl_add_u64 v[116:117], v[16:17], 0, v[150:151]
	v_lshl_add_u64 v[20:21], s[6:7], 0, v[20:21]
	v_lshl_add_u64 v[118:119], v[20:21], 0, v[150:151]
	v_lshl_add_u64 v[24:25], s[6:7], 0, v[24:25]
	v_lshl_add_u64 v[120:121], v[24:25], 0, v[150:151]
	v_lshl_add_u64 v[28:29], s[6:7], 0, v[28:29]
	v_lshl_add_u64 v[122:123], v[28:29], 0, v[150:151]
	v_bitop3_b32 v65, v65, s23, v72 bitop3:0x48
	v_lshl_or_b32 v101, v64, 7, v65
	v_and_b32_e32 v73, 15, v72
	v_lshl_or_b32 v131, v66, 7, v65
	v_lshl_or_b32 v132, v68, 7, v65
	v_lshl_or_b32 v130, v70, 7, v65
	v_xor_b32_e32 v135, 64, v134
	v_and_b32_e32 v30, 7, v148
	v_bfe_u32 v31, v148, 4, 3
	v_xor_b32_e32 v31, v31, v30
	v_sub_u32_e32 v31, v31, v30
	v_lshlrev_b32_e32 v30, 4, v31
	v_ashrrev_i32_e32 v31, 31, v30
	v_mov_b32_e32 v0, v101
	v_and_b32_e32 v0, 0xffffff80, v0
	s_nop 0
	v_readfirstlane_b32 s101, v0
	v_lshl_add_u64 v[0:1], v[108:109], 0, v[30:31]
	s_mov_b32 m0, s101
	s_nop 0
	global_load_lds_dwordx4 v[0:1], off
	v_lshrrev_b32_e32 v0, 1, v72
	v_and_or_b32 v0, v0, s24, v73
	v_lshlrev_b32_e32 v137, 7, v0
	v_lshlrev_b32_e32 v0, 7, v72
	v_and_b32_e32 v146, 0x2780, v0
	v_bitop3_b32 v133, v137, v74, v75 bitop3:0xf6
	v_or_b32_e32 v136, v146, v134
	v_bitop3_b32 v134, v137, v134, 64 bitop3:0xf6
	v_or_b32_e32 v135, v146, v135
	v_mov_b32_e32 v4, v131
	v_and_b32_e32 v4, 0xffffff80, v4
	s_nop 0
	v_readfirstlane_b32 s101, v4
	v_lshl_add_u64 v[4:5], v[110:111], 0, v[30:31]
	s_mov_b32 m0, s101
	s_nop 0
	global_load_lds_dwordx4 v[4:5], off
	v_mov_b32_e32 v8, v132
	v_and_b32_e32 v8, 0xffffff80, v8
	s_nop 0
	v_readfirstlane_b32 s101, v8
	v_lshl_add_u64 v[8:9], v[112:113], 0, v[30:31]
	s_mov_b32 m0, s101
	s_nop 0
	global_load_lds_dwordx4 v[8:9], off
	v_mov_b32_e32 v12, v130
	v_and_b32_e32 v12, 0xffffff80, v12
	s_nop 0
	v_readfirstlane_b32 s101, v12
	v_lshl_add_u64 v[12:13], v[114:115], 0, v[30:31]
	s_mov_b32 m0, s101
	s_nop 0
	global_load_lds_dwordx4 v[12:13], off
	v_add_u32_e32 v16, 0x8000, v101
	v_and_b32_e32 v16, 0xffffff80, v16
	s_nop 0
	v_readfirstlane_b32 s101, v16
	v_lshl_add_u64 v[16:17], v[116:117], 0, v[30:31]
	s_mov_b32 m0, s101
	s_nop 0
	global_load_lds_dwordx4 v[16:17], off
	v_add_u32_e32 v20, 0x8000, v131
	v_and_b32_e32 v20, 0xffffff80, v20
	s_nop 0
	v_readfirstlane_b32 s101, v20
	v_lshl_add_u64 v[20:21], v[118:119], 0, v[30:31]
	s_mov_b32 m0, s101
	s_nop 0
	global_load_lds_dwordx4 v[20:21], off
	v_add_u32_e32 v24, 0x8000, v132
	v_and_b32_e32 v24, 0xffffff80, v24
	s_nop 0
	v_readfirstlane_b32 s101, v24
	v_lshl_add_u64 v[24:25], v[120:121], 0, v[30:31]
	s_mov_b32 m0, s101
	s_nop 0
	global_load_lds_dwordx4 v[24:25], off
	v_add_u32_e32 v28, 0x8000, v130
	v_and_b32_e32 v28, 0xffffff80, v28
	s_nop 0
	v_readfirstlane_b32 s101, v28
	v_lshl_add_u64 v[28:29], v[122:123], 0, v[30:31]
	s_mov_b32 m0, s101
	s_nop 0
	global_load_lds_dwordx4 v[28:29], off
	s_waitcnt lgkmcnt(0)
	s_waitcnt vmcnt(0)
	s_barrier
; #define GL_LOAD(s_, kt_) if (VAR != 1) { a##s_##0 = GL_A(0, kt_); a##s_##1 = GL_A(1, kt_); a##s_##2 = GL_A(2, kt_); a##s_##3 = GL_A(3, kt_); b##s_##0 = GL_B(0, kt_); b##s_##1 = GL_B(1, kt_); b##s_##2 = GL_B(2, kt_); b##s_##3 = GL_B(3, kt_); }
; #define LDS_STORE(s_, buf_) if (VAR != 2) { LDS_ST1(sA, 0, buf_, a##s_##0) LDS_ST1(sA, 1, buf_, a##s_##1) LDS_ST1(sA, 2, buf_, a##s_##2) LDS_ST1(sA, 3, buf_, a##s_##3) LDS_ST1(sB, 0, buf_, b##s_##0) LDS_ST1(sB, 1, buf_, b##s_##1) LDS_ST1(sB, 2, buf_, b##s_##2) LDS_ST1(sB, 3, buf_, b##s_##3) }
;     ...
;   for (int kt = 0; kt < nk; kt += 2) {
;     if (kt + 2 < nk) { GL_LOAD(0, kt + 2) }
;     MMA_TILE(0)
;     LDS_STORE(1, 1)
;     if (VAR != 4) __syncthreads();
;     if (kt + 3 < nk) { GL_LOAD(1, kt + 3) }
;     MMA_TILE(1)
	s_setprio 1
	ds_read_b128 v[64:67], v133
	ds_read_b128 v[68:71], v136 offset:32768
	s_waitcnt lgkmcnt(0)
	v_mfma_f32_16x16x32_f16 v[138:141], v[68:71], v[64:67], 0
	ds_read_b128 v[72:75], v133 offset:2048
	ds_read_b128 v[76:79], v136 offset:34816
	s_waitcnt lgkmcnt(1)
	v_mfma_f32_16x16x32_f16 v[158:161], v[68:71], v[72:75], 0
	ds_read_b128 v[80:83], v133 offset:4096
	ds_read_b128 v[84:87], v136 offset:36864
	s_waitcnt lgkmcnt(2)
	v_mfma_f32_16x16x32_f16 v[142:145], v[76:79], v[64:67], 0
	ds_read_b128 v[88:91], v133 offset:6144
	ds_read_b128 v[92:95], v136 offset:38912
	v_mfma_f32_16x16x32_f16 v[162:165], v[76:79], v[72:75], 0
	ds_read_b128 v[202:205], v135 offset:32768
	ds_read_b128 v[206:209], v134 offset:2048
	s_waitcnt lgkmcnt(5)
	v_mfma_f32_16x16x32_f16 v[190:193], v[68:71], v[80:83], 0
	ds_read_b128 v[210:213], v135 offset:34816
	ds_read_b128 v[220:223], v134 offset:4096
	s_waitcnt lgkmcnt(5)
	v_mfma_f32_16x16x32_f16 v[68:71], v[68:71], v[88:91], 0
	ds_read_b128 v[224:227], v135 offset:36864
	v_mfma_f32_16x16x32_f16 v[194:197], v[76:79], v[80:83], 0
	ds_read_b128 v[228:231], v134 offset:6144
	v_mfma_f32_16x16x32_f16 v[76:79], v[76:79], v[88:91], 0
	ds_read_b128 v[232:235], v135 offset:38912
	v_mfma_f32_16x16x32_f16 v[154:157], v[84:87], v[64:67], 0
	v_mfma_f32_16x16x32_f16 v[166:169], v[84:87], v[72:75], 0
	s_waitcnt lgkmcnt(7)
	v_mfma_f32_16x16x32_f16 v[64:67], v[92:95], v[64:67], 0
	v_mfma_f32_16x16x32_f16 v[72:75], v[92:95], v[72:75], 0
	v_mfma_f32_16x16x32_f16 v[198:201], v[84:87], v[80:83], 0
	v_and_b32_e32 v62, 7, v148
	v_bfe_u32 v63, v148, 4, 3
	v_xor_b32_e32 v63, v63, v62
	v_sub_u32_e32 v63, v63, v62
	v_lshlrev_b32_e32 v62, 4, v63
	v_add_u32_e32 v62, 0x80, v62
	v_ashrrev_i32_e32 v63, 31, v62
	v_mfma_f32_16x16x32_f16 v[84:87], v[84:87], v[88:91], 0
	v_add_u32_e32 v32, 0x4000, v101
	v_and_b32_e32 v32, 0xffffff80, v32
	s_nop 0
	v_readfirstlane_b32 s101, v32
	v_lshl_add_u64 v[32:33], v[108:109], 0, v[62:63]
	s_mov_b32 m0, s101
	s_nop 0
	global_load_lds_dwordx4 v[32:33], off
	v_add_u32_e32 v36, 0x4000, v131
	v_and_b32_e32 v36, 0xffffff80, v36
	s_nop 0
	v_readfirstlane_b32 s101, v36
	v_lshl_add_u64 v[36:37], v[110:111], 0, v[62:63]
	s_mov_b32 m0, s101
	s_nop 0
	global_load_lds_dwordx4 v[36:37], off
	v_mfma_f32_16x16x32_f16 v[80:83], v[92:95], v[80:83], 0
	v_add_u32_e32 v40, 0x4000, v132
	v_and_b32_e32 v40, 0xffffff80, v40
	s_nop 0
	v_readfirstlane_b32 s101, v40
	v_lshl_add_u64 v[40:41], v[112:113], 0, v[62:63]
	s_mov_b32 m0, s101
	s_nop 0
	global_load_lds_dwordx4 v[40:41], off
	v_add_u32_e32 v44, 0x4000, v130
	v_and_b32_e32 v44, 0xffffff80, v44
	s_nop 0
	v_readfirstlane_b32 s101, v44
	v_lshl_add_u64 v[44:45], v[114:115], 0, v[62:63]
	s_mov_b32 m0, s101
	s_nop 0
	global_load_lds_dwordx4 v[44:45], off
	v_mfma_f32_16x16x32_f16 v[88:91], v[92:95], v[88:91], 0
	ds_read_b128 v[92:95], v134
	v_add_u32_e32 v48, 0xc000, v101
	v_and_b32_e32 v48, 0xffffff80, v48
	s_nop 0
	v_readfirstlane_b32 s101, v48
	v_lshl_add_u64 v[48:49], v[116:117], 0, v[62:63]
	s_mov_b32 m0, s101
	s_nop 0
	global_load_lds_dwordx4 v[48:49], off
	v_add_u32_e32 v52, 0xc000, v131
	v_and_b32_e32 v52, 0xffffff80, v52
	s_nop 0
	v_readfirstlane_b32 s101, v52
	v_lshl_add_u64 v[52:53], v[118:119], 0, v[62:63]
	s_mov_b32 m0, s101
	s_nop 0
	global_load_lds_dwordx4 v[52:53], off
	v_add_u32_e32 v56, 0xc000, v132
	v_and_b32_e32 v56, 0xffffff80, v56
	s_nop 0
	v_readfirstlane_b32 s101, v56
	v_lshl_add_u64 v[56:57], v[120:121], 0, v[62:63]
	s_mov_b32 m0, s101
	s_nop 0
	global_load_lds_dwordx4 v[56:57], off
	v_add_u32_e32 v60, 0xc000, v130
	v_and_b32_e32 v60, 0xffffff80, v60
	s_nop 0
	v_readfirstlane_b32 s101, v60
	v_lshl_add_u64 v[60:61], v[122:123], 0, v[62:63]
	s_mov_b32 m0, s101
	s_nop 0
	global_load_lds_dwordx4 v[60:61], off
	s_waitcnt vmcnt(0) lgkmcnt(0)
	s_barrier
	v_mfma_f32_16x16x32_f16 v[138:141], v[202:205], v[92:95], v[138:141]
	v_mfma_f32_16x16x32_f16 v[142:145], v[210:213], v[92:95], v[142:145]
	v_mfma_f32_16x16x32_f16 v[154:157], v[224:227], v[92:95], v[154:157]
	v_mfma_f32_16x16x32_f16 v[64:67], v[232:235], v[92:95], v[64:67]
	v_mfma_f32_16x16x32_f16 v[92:95], v[202:205], v[206:209], v[158:161]
	v_mfma_f32_16x16x32_f16 v[158:161], v[210:213], v[206:209], v[162:165]
	v_mfma_f32_16x16x32_f16 v[162:165], v[224:227], v[206:209], v[166:169]
	v_mfma_f32_16x16x32_f16 v[166:169], v[202:205], v[220:223], v[190:193]
	v_mfma_f32_16x16x32_f16 v[68:71], v[202:205], v[228:231], v[68:71]
	ds_read_b128 v[202:205], v136 offset:49152
	v_mfma_f32_16x16x32_f16 v[190:193], v[210:213], v[220:223], v[194:197]
	v_mfma_f32_16x16x32_f16 v[76:79], v[210:213], v[228:231], v[76:79]
	ds_read_b128 v[210:213], v136 offset:51200
	v_and_b32_e32 v30, 7, v148
	v_bfe_u32 v31, v148, 4, 3
	v_xor_b32_e32 v31, v31, v30
	v_sub_u32_e32 v31, v31, v30
	v_lshlrev_b32_e32 v30, 4, v31
	v_add_u32_e32 v30, 0x100, v30
	v_ashrrev_i32_e32 v31, 31, v30
	v_mfma_f32_16x16x32_f16 v[72:75], v[232:235], v[206:209], v[72:75]
	ds_read_b128 v[206:209], v133 offset:18432
	v_mfma_f32_16x16x32_f16 v[194:197], v[224:227], v[220:223], v[198:201]
	s_nop 2
	ds_read_b128 v[198:201], v133 offset:16384
	v_mfma_f32_16x16x32_f16 v[84:87], v[224:227], v[228:231], v[84:87]
	ds_read_b128 v[224:227], v136 offset:53248
	v_mfma_f32_16x16x32_f16 v[80:83], v[232:235], v[220:223], v[80:83]
	ds_read_b128 v[220:223], v133 offset:20480
	v_mfma_f32_16x16x32_f16 v[88:91], v[232:235], v[228:231], v[88:91]
	ds_read_b128 v[228:231], v133 offset:22528
	s_waitcnt lgkmcnt(3)
; #define GL_LOAD(s_, kt_) if (VAR != 1) { a##s_##0 = GL_A(0, kt_); a##s_##1 = GL_A(1, kt_); a##s_##2 = GL_A(2, kt_); a##s_##3 = GL_A(3, kt_); b##s_##0 = GL_B(0, kt_); b##s_##1 = GL_B(1, kt_); b##s_##2 = GL_B(2, kt_); b##s_##3 = GL_B(3, kt_); }
; #define LDS_STORE(s_, buf_) if (VAR != 2) { LDS_ST1(sA, 0, buf_, a##s_##0) LDS_ST1(sA, 1, buf_, a##s_##1) LDS_ST1(sA, 2, buf_, a##s_##2) LDS_ST1(sA, 3, buf_, a##s_##3) LDS_ST1(sB, 0, buf_, b##s_##0) LDS_ST1(sB, 1, buf_, b##s_##1) LDS_ST1(sB, 2, buf_, b##s_##2) LDS_ST1(sB, 3, buf_, b##s_##3) }
;     ...
;   GL_LOAD(0, 0)
;   GL_LOAD(1, 1)
;   LDS_STORE(0, 0)
;   if (VAR != 4) __syncthreads();
; #pragma unroll
;   for (int kt = 0; kt < nk; kt += 2) {
;     if (kt + 2 < nk) { GL_LOAD(0, kt + 2) }
;     MMA_TILE(0)
;     LDS_STORE(1, 1)
;     if (VAR != 4) __syncthreads();
;     if (kt + 3 < nk) { GL_LOAD(1, kt + 3) }
;     MMA_TILE(1)
;     if (kt + 2 < nk) { LDS_STORE(0, 0) }
;     if (VAR != 4) __syncthreads();
	v_mfma_f32_16x16x32_f16 v[138:141], v[202:205], v[198:201], v[138:141]
	ds_read_b128 v[232:235], v136 offset:55296
	v_mfma_f32_16x16x32_f16 v[92:95], v[202:205], v[206:209], v[92:95]
	v_mov_b32_e32 v0, v101
	v_and_b32_e32 v0, 0xffffff80, v0
	s_nop 0
	v_readfirstlane_b32 s101, v0
	v_lshl_add_u64 v[0:1], v[108:109], 0, v[30:31]
	s_mov_b32 m0, s101
	s_nop 0
	global_load_lds_dwordx4 v[0:1], off
	v_mfma_f32_16x16x32_f16 v[142:145], v[210:213], v[198:201], v[142:145]
	v_mov_b32_e32 v4, v131
	v_and_b32_e32 v4, 0xffffff80, v4
	s_nop 0
	v_readfirstlane_b32 s101, v4
	v_lshl_add_u64 v[4:5], v[110:111], 0, v[30:31]
	s_mov_b32 m0, s101
	s_nop 0
	global_load_lds_dwordx4 v[4:5], off
	v_mfma_f32_16x16x32_f16 v[158:161], v[210:213], v[206:209], v[158:161]
	v_mov_b32_e32 v8, v132
	v_and_b32_e32 v8, 0xffffff80, v8
	s_nop 0
	v_readfirstlane_b32 s101, v8
	v_lshl_add_u64 v[8:9], v[112:113], 0, v[30:31]
	s_mov_b32 m0, s101
	s_nop 0
	global_load_lds_dwordx4 v[8:9], off
	s_waitcnt lgkmcnt(2)
	v_mfma_f32_16x16x32_f16 v[166:169], v[202:205], v[220:223], v[166:169]
	v_mov_b32_e32 v12, v130
	v_and_b32_e32 v12, 0xffffff80, v12
	s_nop 0
	v_readfirstlane_b32 s101, v12
	v_lshl_add_u64 v[12:13], v[114:115], 0, v[30:31]
	s_mov_b32 m0, s101
	s_nop 0
	global_load_lds_dwordx4 v[12:13], off
	s_waitcnt lgkmcnt(1)
	v_mfma_f32_16x16x32_f16 v[68:71], v[202:205], v[228:231], v[68:71]
	ds_read_b128 v[202:205], v135 offset:49152
	v_mfma_f32_16x16x32_f16 v[190:193], v[210:213], v[220:223], v[190:193]
	v_add_u32_e32 v16, 0x8000, v101
	v_and_b32_e32 v16, 0xffffff80, v16
	s_nop 0
	v_readfirstlane_b32 s101, v16
	v_lshl_add_u64 v[16:17], v[116:117], 0, v[30:31]
	s_mov_b32 m0, s101
	s_nop 0
	global_load_lds_dwordx4 v[16:17], off
	v_mfma_f32_16x16x32_f16 v[76:79], v[210:213], v[228:231], v[76:79]
	ds_read_b128 v[210:213], v135 offset:51200
	v_mfma_f32_16x16x32_f16 v[154:157], v[224:227], v[198:201], v[154:157]
	v_add_u32_e32 v20, 0x8000, v131
	v_and_b32_e32 v20, 0xffffff80, v20
	s_nop 0
	v_readfirstlane_b32 s101, v20
	v_lshl_add_u64 v[20:21], v[118:119], 0, v[30:31]
	s_mov_b32 m0, s101
	s_nop 0
	global_load_lds_dwordx4 v[20:21], off
	v_mfma_f32_16x16x32_f16 v[162:165], v[224:227], v[206:209], v[162:165]
	v_add_u32_e32 v24, 0x8000, v132
	v_and_b32_e32 v24, 0xffffff80, v24
	s_nop 0
	v_readfirstlane_b32 s101, v24
	v_lshl_add_u64 v[24:25], v[120:121], 0, v[30:31]
	s_mov_b32 m0, s101
	s_nop 0
	global_load_lds_dwordx4 v[24:25], off
	s_waitcnt lgkmcnt(2)
	v_mfma_f32_16x16x32_f16 v[64:67], v[232:235], v[198:201], v[64:67]
	ds_read_b128 v[198:201], v134 offset:16384
	v_mfma_f32_16x16x32_f16 v[72:75], v[232:235], v[206:209], v[72:75]
	ds_read_b128 v[206:209], v134 offset:18432
	v_mfma_f32_16x16x32_f16 v[194:197], v[224:227], v[220:223], v[194:197]
	v_add_u32_e32 v28, 0x8000, v130
	v_and_b32_e32 v28, 0xffffff80, v28
	s_nop 0
	v_readfirstlane_b32 s101, v28
	v_lshl_add_u64 v[28:29], v[122:123], 0, v[30:31]
	s_mov_b32 m0, s101
	s_nop 0
	global_load_lds_dwordx4 v[28:29], off
	v_mfma_f32_16x16x32_f16 v[84:87], v[224:227], v[228:231], v[84:87]
	ds_read_b128 v[224:227], v135 offset:53248
	v_mfma_f32_16x16x32_f16 v[80:83], v[232:235], v[220:223], v[80:83]
	ds_read_b128 v[220:223], v134 offset:20480
	v_mfma_f32_16x16x32_f16 v[88:91], v[232:235], v[228:231], v[88:91]
	ds_read_b128 v[228:231], v134 offset:22528
	ds_read_b128 v[232:235], v135 offset:55296
	s_waitcnt vmcnt(0) lgkmcnt(0)
	s_barrier
	v_mfma_f32_16x16x32_f16 v[138:141], v[202:205], v[198:201], v[138:141]
	v_mfma_f32_16x16x32_f16 v[92:95], v[202:205], v[206:209], v[92:95]
	v_mfma_f32_16x16x32_f16 v[142:145], v[210:213], v[198:201], v[142:145]
	v_mfma_f32_16x16x32_f16 v[158:161], v[210:213], v[206:209], v[158:161]
	v_mfma_f32_16x16x32_f16 v[166:169], v[202:205], v[220:223], v[166:169]
	v_mfma_f32_16x16x32_f16 v[68:71], v[202:205], v[228:231], v[68:71]
	ds_read_b128 v[202:205], v136 offset:32768
	v_mfma_f32_16x16x32_f16 v[190:193], v[210:213], v[220:223], v[190:193]
	v_mfma_f32_16x16x32_f16 v[76:79], v[210:213], v[228:231], v[76:79]
	ds_read_b128 v[210:213], v136 offset:34816
	v_mfma_f32_16x16x32_f16 v[154:157], v[224:227], v[198:201], v[154:157]
	v_mfma_f32_16x16x32_f16 v[162:165], v[224:227], v[206:209], v[162:165]
	v_mfma_f32_16x16x32_f16 v[64:67], v[232:235], v[198:201], v[64:67]
	ds_read_b128 v[198:201], v133
	v_mfma_f32_16x16x32_f16 v[72:75], v[232:235], v[206:209], v[72:75]
	ds_read_b128 v[206:209], v133 offset:2048
	v_mfma_f32_16x16x32_f16 v[194:197], v[224:227], v[220:223], v[194:197]
	v_and_b32_e32 v62, 7, v148
	v_bfe_u32 v63, v148, 4, 3
	v_xor_b32_e32 v63, v63, v62
	v_sub_u32_e32 v63, v63, v62
	v_lshlrev_b32_e32 v62, 4, v63
	v_add_u32_e32 v62, 0x180, v62
	v_ashrrev_i32_e32 v63, 31, v62
	v_mfma_f32_16x16x32_f16 v[84:87], v[224:227], v[228:231], v[84:87]
	ds_read_b128 v[224:227], v136 offset:36864
	v_mfma_f32_16x16x32_f16 v[80:83], v[232:235], v[220:223], v[80:83]
	ds_read_b128 v[220:223], v133 offset:4096
	v_mfma_f32_16x16x32_f16 v[88:91], v[232:235], v[228:231], v[88:91]
	ds_read_b128 v[228:231], v133 offset:6144
	s_waitcnt lgkmcnt(4)
	v_mfma_f32_16x16x32_f16 v[138:141], v[202:205], v[198:201], v[138:141]
	ds_read_b128 v[232:235], v136 offset:38912
	s_waitcnt lgkmcnt(4)
	v_mfma_f32_16x16x32_f16 v[92:95], v[202:205], v[206:209], v[92:95]
	v_add_u32_e32 v32, 0x4000, v101
	v_and_b32_e32 v32, 0xffffff80, v32
	s_nop 0
	v_readfirstlane_b32 s101, v32
	v_lshl_add_u64 v[32:33], v[108:109], 0, v[62:63]
	s_mov_b32 m0, s101
	s_nop 0
	global_load_lds_dwordx4 v[32:33], off
	v_mfma_f32_16x16x32_f16 v[142:145], v[210:213], v[198:201], v[142:145]
	v_add_u32_e32 v36, 0x4000, v131
	v_and_b32_e32 v36, 0xffffff80, v36
	s_nop 0
	v_readfirstlane_b32 s101, v36
	v_lshl_add_u64 v[36:37], v[110:111], 0, v[62:63]
	s_mov_b32 m0, s101
	s_nop 0
	global_load_lds_dwordx4 v[36:37], off
	v_mfma_f32_16x16x32_f16 v[158:161], v[210:213], v[206:209], v[158:161]
	v_add_u32_e32 v40, 0x4000, v132
	v_and_b32_e32 v40, 0xffffff80, v40
	s_nop 0
	v_readfirstlane_b32 s101, v40
	v_lshl_add_u64 v[40:41], v[112:113], 0, v[62:63]
	s_mov_b32 m0, s101
	s_nop 0
	global_load_lds_dwordx4 v[40:41], off
	s_waitcnt lgkmcnt(2)
; #define GL_LOAD(s_, kt_) if (VAR != 1) { a##s_##0 = GL_A(0, kt_); a##s_##1 = GL_A(1, kt_); a##s_##2 = GL_A(2, kt_); a##s_##3 = GL_A(3, kt_); b##s_##0 = GL_B(0, kt_); b##s_##1 = GL_B(1, kt_); b##s_##2 = GL_B(2, kt_); b##s_##3 = GL_B(3, kt_); }
; #define LDS_STORE(s_, buf_) if (VAR != 2) { LDS_ST1(sA, 0, buf_, a##s_##0) LDS_ST1(sA, 1, buf_, a##s_##1) LDS_ST1(sA, 2, buf_, a##s_##2) LDS_ST1(sA, 3, buf_, a##s_##3) LDS_ST1(sB, 0, buf_, b##s_##0) LDS_ST1(sB, 1, buf_, b##s_##1) LDS_ST1(sB, 2, buf_, b##s_##2) LDS_ST1(sB, 3, buf_, b##s_##3) }
;     ...
;   GL_LOAD(0, 0)
;   GL_LOAD(1, 1)
;   LDS_STORE(0, 0)
;   if (VAR != 4) __syncthreads();
; #pragma unroll
;   for (int kt = 0; kt < nk; kt += 2) {
;     if (kt + 2 < nk) { GL_LOAD(0, kt + 2) }
;     MMA_TILE(0)
;     LDS_STORE(1, 1)
;     if (VAR != 4) __syncthreads();
;     if (kt + 3 < nk) { GL_LOAD(1, kt + 3) }
;     MMA_TILE(1)
;     if (kt + 2 < nk) { LDS_STORE(0, 0) }
;     if (VAR != 4) __syncthreads();
	v_mfma_f32_16x16x32_f16 v[166:169], v[202:205], v[220:223], v[166:169]
	v_add_u32_e32 v44, 0x4000, v130
	v_and_b32_e32 v44, 0xffffff80, v44
	s_nop 0
	v_readfirstlane_b32 s101, v44
	v_lshl_add_u64 v[44:45], v[114:115], 0, v[62:63]
	s_mov_b32 m0, s101
	s_nop 0
	global_load_lds_dwordx4 v[44:45], off
	s_waitcnt lgkmcnt(1)
	v_mfma_f32_16x16x32_f16 v[68:71], v[202:205], v[228:231], v[68:71]
	ds_read_b128 v[202:205], v135 offset:32768
	v_mfma_f32_16x16x32_f16 v[190:193], v[210:213], v[220:223], v[190:193]
	v_add_u32_e32 v48, 0xc000, v101
	v_and_b32_e32 v48, 0xffffff80, v48
	s_nop 0
	v_readfirstlane_b32 s101, v48
	v_lshl_add_u64 v[48:49], v[116:117], 0, v[62:63]
	s_mov_b32 m0, s101
	s_nop 0
	global_load_lds_dwordx4 v[48:49], off
	v_mfma_f32_16x16x32_f16 v[76:79], v[210:213], v[228:231], v[76:79]
	ds_read_b128 v[210:213], v135 offset:34816
	v_mfma_f32_16x16x32_f16 v[154:157], v[224:227], v[198:201], v[154:157]
	v_add_u32_e32 v52, 0xc000, v131
	v_and_b32_e32 v52, 0xffffff80, v52
	s_nop 0
	v_readfirstlane_b32 s101, v52
	v_lshl_add_u64 v[52:53], v[118:119], 0, v[62:63]
	s_mov_b32 m0, s101
	s_nop 0
	global_load_lds_dwordx4 v[52:53], off
	v_mfma_f32_16x16x32_f16 v[162:165], v[224:227], v[206:209], v[162:165]
	v_add_u32_e32 v56, 0xc000, v132
	v_and_b32_e32 v56, 0xffffff80, v56
	s_nop 0
	v_readfirstlane_b32 s101, v56
	v_lshl_add_u64 v[56:57], v[120:121], 0, v[62:63]
	s_mov_b32 m0, s101
	s_nop 0
	global_load_lds_dwordx4 v[56:57], off
	s_waitcnt lgkmcnt(2)
	v_mfma_f32_16x16x32_f16 v[64:67], v[232:235], v[198:201], v[64:67]
	ds_read_b128 v[198:201], v134
	v_mfma_f32_16x16x32_f16 v[72:75], v[232:235], v[206:209], v[72:75]
	ds_read_b128 v[206:209], v134 offset:2048
	v_mfma_f32_16x16x32_f16 v[194:197], v[224:227], v[220:223], v[194:197]
	v_add_u32_e32 v60, 0xc000, v130
	v_and_b32_e32 v60, 0xffffff80, v60
	s_nop 0
	v_readfirstlane_b32 s101, v60
	v_lshl_add_u64 v[60:61], v[122:123], 0, v[62:63]
	s_mov_b32 m0, s101
	s_nop 0
	global_load_lds_dwordx4 v[60:61], off
	v_mfma_f32_16x16x32_f16 v[84:87], v[224:227], v[228:231], v[84:87]
	ds_read_b128 v[224:227], v135 offset:36864
	v_mfma_f32_16x16x32_f16 v[80:83], v[232:235], v[220:223], v[80:83]
	ds_read_b128 v[220:223], v134 offset:4096
	v_mfma_f32_16x16x32_f16 v[88:91], v[232:235], v[228:231], v[88:91]
	ds_read_b128 v[228:231], v134 offset:6144
	ds_read_b128 v[232:235], v135 offset:38912
	s_waitcnt vmcnt(0) lgkmcnt(0)
	s_barrier
	v_mfma_f32_16x16x32_f16 v[138:141], v[202:205], v[198:201], v[138:141]
	v_mfma_f32_16x16x32_f16 v[92:95], v[202:205], v[206:209], v[92:95]
	v_mfma_f32_16x16x32_f16 v[142:145], v[210:213], v[198:201], v[142:145]
	v_mfma_f32_16x16x32_f16 v[158:161], v[210:213], v[206:209], v[158:161]
	v_mfma_f32_16x16x32_f16 v[166:169], v[202:205], v[220:223], v[166:169]
	v_mfma_f32_16x16x32_f16 v[68:71], v[202:205], v[228:231], v[68:71]
	ds_read_b128 v[202:205], v136 offset:49152
	v_mfma_f32_16x16x32_f16 v[190:193], v[210:213], v[220:223], v[190:193]
	v_mfma_f32_16x16x32_f16 v[76:79], v[210:213], v[228:231], v[76:79]
	ds_read_b128 v[210:213], v136 offset:51200
	v_mfma_f32_16x16x32_f16 v[154:157], v[224:227], v[198:201], v[154:157]
	v_mfma_f32_16x16x32_f16 v[162:165], v[224:227], v[206:209], v[162:165]
	v_mfma_f32_16x16x32_f16 v[64:67], v[232:235], v[198:201], v[64:67]
	ds_read_b128 v[198:201], v133 offset:16384
	v_mfma_f32_16x16x32_f16 v[72:75], v[232:235], v[206:209], v[72:75]
	ds_read_b128 v[206:209], v133 offset:18432
	v_mfma_f32_16x16x32_f16 v[194:197], v[224:227], v[220:223], v[194:197]
	v_and_b32_e32 v30, 7, v148
	v_bfe_u32 v31, v148, 4, 3
	v_xor_b32_e32 v31, v31, v30
	v_sub_u32_e32 v31, v31, v30
	v_lshlrev_b32_e32 v30, 4, v31
	v_add_u32_e32 v30, 0x200, v30
	v_ashrrev_i32_e32 v31, 31, v30
	v_mfma_f32_16x16x32_f16 v[84:87], v[224:227], v[228:231], v[84:87]
	ds_read_b128 v[224:227], v136 offset:53248
	v_mfma_f32_16x16x32_f16 v[80:83], v[232:235], v[220:223], v[80:83]
	ds_read_b128 v[220:223], v133 offset:20480
	v_mfma_f32_16x16x32_f16 v[88:91], v[232:235], v[228:231], v[88:91]
	ds_read_b128 v[228:231], v133 offset:22528
	s_waitcnt lgkmcnt(4)
	v_mfma_f32_16x16x32_f16 v[138:141], v[202:205], v[198:201], v[138:141]
	ds_read_b128 v[232:235], v136 offset:55296
	s_waitcnt lgkmcnt(4)
	v_mfma_f32_16x16x32_f16 v[92:95], v[202:205], v[206:209], v[92:95]
	v_mov_b32_e32 v0, v101
	v_and_b32_e32 v0, 0xffffff80, v0
	s_nop 0
	v_readfirstlane_b32 s101, v0
	v_lshl_add_u64 v[0:1], v[108:109], 0, v[30:31]
	s_mov_b32 m0, s101
	s_nop 0
	global_load_lds_dwordx4 v[0:1], off
	v_mfma_f32_16x16x32_f16 v[142:145], v[210:213], v[198:201], v[142:145]
	v_mov_b32_e32 v4, v131
	v_and_b32_e32 v4, 0xffffff80, v4
	s_nop 0
	v_readfirstlane_b32 s101, v4
	v_lshl_add_u64 v[4:5], v[110:111], 0, v[30:31]
	s_mov_b32 m0, s101
	s_nop 0
	global_load_lds_dwordx4 v[4:5], off
	v_mfma_f32_16x16x32_f16 v[158:161], v[210:213], v[206:209], v[158:161]
	v_mov_b32_e32 v8, v132
	v_and_b32_e32 v8, 0xffffff80, v8
	s_nop 0
	v_readfirstlane_b32 s101, v8
	v_lshl_add_u64 v[8:9], v[112:113], 0, v[30:31]
	s_mov_b32 m0, s101
	s_nop 0
	global_load_lds_dwordx4 v[8:9], off
	s_waitcnt lgkmcnt(2)
	v_mfma_f32_16x16x32_f16 v[166:169], v[202:205], v[220:223], v[166:169]
	v_mov_b32_e32 v12, v130
	v_and_b32_e32 v12, 0xffffff80, v12
	s_nop 0
	v_readfirstlane_b32 s101, v12
	v_lshl_add_u64 v[12:13], v[114:115], 0, v[30:31]
	s_mov_b32 m0, s101
	s_nop 0
	global_load_lds_dwordx4 v[12:13], off
	s_waitcnt lgkmcnt(1)
; #define GL_LOAD(s_, kt_) if (VAR != 1) { a##s_##0 = GL_A(0, kt_); a##s_##1 = GL_A(1, kt_); a##s_##2 = GL_A(2, kt_); a##s_##3 = GL_A(3, kt_); b##s_##0 = GL_B(0, kt_); b##s_##1 = GL_B(1, kt_); b##s_##2 = GL_B(2, kt_); b##s_##3 = GL_B(3, kt_); }
; #define LDS_STORE(s_, buf_) if (VAR != 2) { LDS_ST1(sA, 0, buf_, a##s_##0) LDS_ST1(sA, 1, buf_, a##s_##1) LDS_ST1(sA, 2, buf_, a##s_##2) LDS_ST1(sA, 3, buf_, a##s_##3) LDS_ST1(sB, 0, buf_, b##s_##0) LDS_ST1(sB, 1, buf_, b##s_##1) LDS_ST1(sB, 2, buf_, b##s_##2) LDS_ST1(sB, 3, buf_, b##s_##3) }
;     ...
;   GL_LOAD(0, 0)
;   GL_LOAD(1, 1)
;   LDS_STORE(0, 0)
;   if (VAR != 4) __syncthreads();
; #pragma unroll
;   for (int kt = 0; kt < nk; kt += 2) {
;     if (kt + 2 < nk) { GL_LOAD(0, kt + 2) }
;     MMA_TILE(0)
;     LDS_STORE(1, 1)
;     if (VAR != 4) __syncthreads();
;     if (kt + 3 < nk) { GL_LOAD(1, kt + 3) }
;     MMA_TILE(1)
;     if (kt + 2 < nk) { LDS_STORE(0, 0) }
;     if (VAR != 4) __syncthreads();
	v_mfma_f32_16x16x32_f16 v[68:71], v[202:205], v[228:231], v[68:71]
	ds_read_b128 v[202:205], v135 offset:49152
	v_mfma_f32_16x16x32_f16 v[190:193], v[210:213], v[220:223], v[190:193]
	v_add_u32_e32 v16, 0x8000, v101
	v_and_b32_e32 v16, 0xffffff80, v16
	s_nop 0
	v_readfirstlane_b32 s101, v16
	v_lshl_add_u64 v[16:17], v[116:117], 0, v[30:31]
	s_mov_b32 m0, s101
	s_nop 0
	global_load_lds_dwordx4 v[16:17], off
	v_mfma_f32_16x16x32_f16 v[76:79], v[210:213], v[228:231], v[76:79]
	ds_read_b128 v[210:213], v135 offset:51200
	v_mfma_f32_16x16x32_f16 v[154:157], v[224:227], v[198:201], v[154:157]
	v_add_u32_e32 v20, 0x8000, v131
	v_and_b32_e32 v20, 0xffffff80, v20
	s_nop 0
	v_readfirstlane_b32 s101, v20
	v_lshl_add_u64 v[20:21], v[118:119], 0, v[30:31]
	s_mov_b32 m0, s101
	s_nop 0
	global_load_lds_dwordx4 v[20:21], off
	v_mfma_f32_16x16x32_f16 v[162:165], v[224:227], v[206:209], v[162:165]
	v_add_u32_e32 v24, 0x8000, v132
	v_and_b32_e32 v24, 0xffffff80, v24
	s_nop 0
	v_readfirstlane_b32 s101, v24
	v_lshl_add_u64 v[24:25], v[120:121], 0, v[30:31]
	s_mov_b32 m0, s101
	s_nop 0
	global_load_lds_dwordx4 v[24:25], off
	s_waitcnt lgkmcnt(2)
	v_mfma_f32_16x16x32_f16 v[64:67], v[232:235], v[198:201], v[64:67]
	ds_read_b128 v[198:201], v134 offset:16384
	v_mfma_f32_16x16x32_f16 v[72:75], v[232:235], v[206:209], v[72:75]
	ds_read_b128 v[206:209], v134 offset:18432
	v_mfma_f32_16x16x32_f16 v[194:197], v[224:227], v[220:223], v[194:197]
	v_add_u32_e32 v28, 0x8000, v130
	v_and_b32_e32 v28, 0xffffff80, v28
	s_nop 0
	v_readfirstlane_b32 s101, v28
	v_lshl_add_u64 v[28:29], v[122:123], 0, v[30:31]
	s_mov_b32 m0, s101
	s_nop 0
	global_load_lds_dwordx4 v[28:29], off
	v_mfma_f32_16x16x32_f16 v[84:87], v[224:227], v[228:231], v[84:87]
	ds_read_b128 v[224:227], v135 offset:53248
	v_mfma_f32_16x16x32_f16 v[80:83], v[232:235], v[220:223], v[80:83]
	ds_read_b128 v[220:223], v134 offset:20480
	v_mfma_f32_16x16x32_f16 v[88:91], v[232:235], v[228:231], v[88:91]
	ds_read_b128 v[228:231], v134 offset:22528
	ds_read_b128 v[232:235], v135 offset:55296
	s_waitcnt vmcnt(0) lgkmcnt(0)
	s_barrier
	v_mfma_f32_16x16x32_f16 v[138:141], v[202:205], v[198:201], v[138:141]
	v_mfma_f32_16x16x32_f16 v[92:95], v[202:205], v[206:209], v[92:95]
	v_mfma_f32_16x16x32_f16 v[142:145], v[210:213], v[198:201], v[142:145]
	v_mfma_f32_16x16x32_f16 v[158:161], v[210:213], v[206:209], v[158:161]
	v_mfma_f32_16x16x32_f16 v[166:169], v[202:205], v[220:223], v[166:169]
	v_mfma_f32_16x16x32_f16 v[68:71], v[202:205], v[228:231], v[68:71]
	ds_read_b128 v[202:205], v136 offset:32768
	v_mfma_f32_16x16x32_f16 v[190:193], v[210:213], v[220:223], v[190:193]
	v_mfma_f32_16x16x32_f16 v[76:79], v[210:213], v[228:231], v[76:79]
	ds_read_b128 v[210:213], v136 offset:34816
	v_mfma_f32_16x16x32_f16 v[154:157], v[224:227], v[198:201], v[154:157]
	v_mfma_f32_16x16x32_f16 v[162:165], v[224:227], v[206:209], v[162:165]
	v_mfma_f32_16x16x32_f16 v[64:67], v[232:235], v[198:201], v[64:67]
	ds_read_b128 v[198:201], v133
	v_mfma_f32_16x16x32_f16 v[72:75], v[232:235], v[206:209], v[72:75]
	ds_read_b128 v[206:209], v133 offset:2048
	v_mfma_f32_16x16x32_f16 v[194:197], v[224:227], v[220:223], v[194:197]
	v_and_b32_e32 v62, 7, v148
	v_bfe_u32 v63, v148, 4, 3
	v_xor_b32_e32 v63, v63, v62
	v_sub_u32_e32 v63, v63, v62
	v_lshlrev_b32_e32 v62, 4, v63
	v_add_u32_e32 v62, 0x280, v62
	v_ashrrev_i32_e32 v63, 31, v62
	v_mfma_f32_16x16x32_f16 v[84:87], v[224:227], v[228:231], v[84:87]
	ds_read_b128 v[224:227], v136 offset:36864
	v_mfma_f32_16x16x32_f16 v[80:83], v[232:235], v[220:223], v[80:83]
	ds_read_b128 v[220:223], v133 offset:4096
	v_mfma_f32_16x16x32_f16 v[88:91], v[232:235], v[228:231], v[88:91]
	ds_read_b128 v[228:231], v133 offset:6144
	s_waitcnt lgkmcnt(4)
	v_mfma_f32_16x16x32_f16 v[138:141], v[202:205], v[198:201], v[138:141]
	ds_read_b128 v[232:235], v136 offset:38912
	s_waitcnt lgkmcnt(4)
	v_mfma_f32_16x16x32_f16 v[92:95], v[202:205], v[206:209], v[92:95]
	v_add_u32_e32 v32, 0x4000, v101
	v_and_b32_e32 v32, 0xffffff80, v32
	s_nop 0
	v_readfirstlane_b32 s101, v32
	v_lshl_add_u64 v[32:33], v[108:109], 0, v[62:63]
	s_mov_b32 m0, s101
	s_nop 0
	global_load_lds_dwordx4 v[32:33], off
	v_mfma_f32_16x16x32_f16 v[142:145], v[210:213], v[198:201], v[142:145]
	v_add_u32_e32 v36, 0x4000, v131
	v_and_b32_e32 v36, 0xffffff80, v36
	s_nop 0
	v_readfirstlane_b32 s101, v36
	v_lshl_add_u64 v[36:37], v[110:111], 0, v[62:63]
	s_mov_b32 m0, s101
	s_nop 0
	global_load_lds_dwordx4 v[36:37], off
	v_mfma_f32_16x16x32_f16 v[158:161], v[210:213], v[206:209], v[158:161]
	v_add_u32_e32 v40, 0x4000, v132
	v_and_b32_e32 v40, 0xffffff80, v40
	s_nop 0
	v_readfirstlane_b32 s101, v40
	v_lshl_add_u64 v[40:41], v[112:113], 0, v[62:63]
	s_mov_b32 m0, s101
	s_nop 0
	global_load_lds_dwordx4 v[40:41], off
	s_waitcnt lgkmcnt(2)
	v_mfma_f32_16x16x32_f16 v[166:169], v[202:205], v[220:223], v[166:169]
	v_add_u32_e32 v44, 0x4000, v130
	v_and_b32_e32 v44, 0xffffff80, v44
	s_nop 0
	v_readfirstlane_b32 s101, v44
	v_lshl_add_u64 v[44:45], v[114:115], 0, v[62:63]
	s_mov_b32 m0, s101
	s_nop 0
	global_load_lds_dwordx4 v[44:45], off
	s_waitcnt lgkmcnt(1)
; #define GL_LOAD(s_, kt_) if (VAR != 1) { a##s_##0 = GL_A(0, kt_); a##s_##1 = GL_A(1, kt_); a##s_##2 = GL_A(2, kt_); a##s_##3 = GL_A(3, kt_); b##s_##0 = GL_B(0, kt_); b##s_##1 = GL_B(1, kt_); b##s_##2 = GL_B(2, kt_); b##s_##3 = GL_B(3, kt_); }
; #define LDS_STORE(s_, buf_) if (VAR != 2) { LDS_ST1(sA, 0, buf_, a##s_##0) LDS_ST1(sA, 1, buf_, a##s_##1) LDS_ST1(sA, 2, buf_, a##s_##2) LDS_ST1(sA, 3, buf_, a##s_##3) LDS_ST1(sB, 0, buf_, b##s_##0) LDS_ST1(sB, 1, buf_, b##s_##1) LDS_ST1(sB, 2, buf_, b##s_##2) LDS_ST1(sB, 3, buf_, b##s_##3) }
;     ...
;   GL_LOAD(0, 0)
;   GL_LOAD(1, 1)
;   LDS_STORE(0, 0)
;   if (VAR != 4) __syncthreads();
; #pragma unroll
;   for (int kt = 0; kt < nk; kt += 2) {
;     if (kt + 2 < nk) { GL_LOAD(0, kt + 2) }
;     MMA_TILE(0)
;     LDS_STORE(1, 1)
;     if (VAR != 4) __syncthreads();
;     if (kt + 3 < nk) { GL_LOAD(1, kt + 3) }
;     MMA_TILE(1)
;     if (kt + 2 < nk) { LDS_STORE(0, 0) }
;     if (VAR != 4) __syncthreads();
	v_mfma_f32_16x16x32_f16 v[68:71], v[202:205], v[228:231], v[68:71]
	ds_read_b128 v[202:205], v135 offset:32768
	v_mfma_f32_16x16x32_f16 v[190:193], v[210:213], v[220:223], v[190:193]
	v_add_u32_e32 v48, 0xc000, v101
	v_and_b32_e32 v48, 0xffffff80, v48
	s_nop 0
	v_readfirstlane_b32 s101, v48
	v_lshl_add_u64 v[48:49], v[116:117], 0, v[62:63]
	s_mov_b32 m0, s101
	s_nop 0
	global_load_lds_dwordx4 v[48:49], off
	v_mfma_f32_16x16x32_f16 v[76:79], v[210:213], v[228:231], v[76:79]
	ds_read_b128 v[210:213], v135 offset:34816
	v_mfma_f32_16x16x32_f16 v[154:157], v[224:227], v[198:201], v[154:157]
	v_add_u32_e32 v52, 0xc000, v131
	v_and_b32_e32 v52, 0xffffff80, v52
	s_nop 0
	v_readfirstlane_b32 s101, v52
	v_lshl_add_u64 v[52:53], v[118:119], 0, v[62:63]
	s_mov_b32 m0, s101
	s_nop 0
	global_load_lds_dwordx4 v[52:53], off
	v_mfma_f32_16x16x32_f16 v[162:165], v[224:227], v[206:209], v[162:165]
	v_add_u32_e32 v56, 0xc000, v132
	v_and_b32_e32 v56, 0xffffff80, v56
	s_nop 0
	v_readfirstlane_b32 s101, v56
	v_lshl_add_u64 v[56:57], v[120:121], 0, v[62:63]
	s_mov_b32 m0, s101
	s_nop 0
	global_load_lds_dwordx4 v[56:57], off
	s_waitcnt lgkmcnt(2)
	v_mfma_f32_16x16x32_f16 v[64:67], v[232:235], v[198:201], v[64:67]
	ds_read_b128 v[198:201], v134
	v_mfma_f32_16x16x32_f16 v[72:75], v[232:235], v[206:209], v[72:75]
	ds_read_b128 v[206:209], v134 offset:2048
	v_mfma_f32_16x16x32_f16 v[194:197], v[224:227], v[220:223], v[194:197]
	v_add_u32_e32 v60, 0xc000, v130
	v_and_b32_e32 v60, 0xffffff80, v60
	s_nop 0
	v_readfirstlane_b32 s101, v60
	v_lshl_add_u64 v[60:61], v[122:123], 0, v[62:63]
	s_mov_b32 m0, s101
	s_nop 0
	global_load_lds_dwordx4 v[60:61], off
	v_mfma_f32_16x16x32_f16 v[84:87], v[224:227], v[228:231], v[84:87]
	ds_read_b128 v[224:227], v135 offset:36864
	v_mfma_f32_16x16x32_f16 v[80:83], v[232:235], v[220:223], v[80:83]
	ds_read_b128 v[220:223], v134 offset:4096
	v_mfma_f32_16x16x32_f16 v[88:91], v[232:235], v[228:231], v[88:91]
	ds_read_b128 v[228:231], v134 offset:6144
	ds_read_b128 v[232:235], v135 offset:38912
	s_waitcnt vmcnt(0) lgkmcnt(0)
	s_barrier
	v_mfma_f32_16x16x32_f16 v[138:141], v[202:205], v[198:201], v[138:141]
	v_mfma_f32_16x16x32_f16 v[92:95], v[202:205], v[206:209], v[92:95]
	v_mfma_f32_16x16x32_f16 v[142:145], v[210:213], v[198:201], v[142:145]
	v_mfma_f32_16x16x32_f16 v[158:161], v[210:213], v[206:209], v[158:161]
	v_mfma_f32_16x16x32_f16 v[166:169], v[202:205], v[220:223], v[166:169]
	v_mfma_f32_16x16x32_f16 v[68:71], v[202:205], v[228:231], v[68:71]
	ds_read_b128 v[202:205], v136 offset:49152
	v_mfma_f32_16x16x32_f16 v[190:193], v[210:213], v[220:223], v[190:193]
	v_mfma_f32_16x16x32_f16 v[76:79], v[210:213], v[228:231], v[76:79]
	ds_read_b128 v[210:213], v136 offset:51200
	v_mfma_f32_16x16x32_f16 v[154:157], v[224:227], v[198:201], v[154:157]
	v_mfma_f32_16x16x32_f16 v[162:165], v[224:227], v[206:209], v[162:165]
	v_mfma_f32_16x16x32_f16 v[64:67], v[232:235], v[198:201], v[64:67]
	ds_read_b128 v[198:201], v133 offset:16384
	v_mfma_f32_16x16x32_f16 v[72:75], v[232:235], v[206:209], v[72:75]
	ds_read_b128 v[206:209], v133 offset:18432
	v_mfma_f32_16x16x32_f16 v[194:197], v[224:227], v[220:223], v[194:197]
	v_and_b32_e32 v30, 7, v148
	v_bfe_u32 v31, v148, 4, 3
	v_xor_b32_e32 v31, v31, v30
	v_sub_u32_e32 v31, v31, v30
	v_lshlrev_b32_e32 v30, 4, v31
	v_add_u32_e32 v30, 0x300, v30
	v_ashrrev_i32_e32 v31, 31, v30
	v_mfma_f32_16x16x32_f16 v[84:87], v[224:227], v[228:231], v[84:87]
	ds_read_b128 v[224:227], v136 offset:53248
	v_mfma_f32_16x16x32_f16 v[80:83], v[232:235], v[220:223], v[80:83]
	ds_read_b128 v[220:223], v133 offset:20480
	v_mfma_f32_16x16x32_f16 v[88:91], v[232:235], v[228:231], v[88:91]
	ds_read_b128 v[228:231], v133 offset:22528
	s_waitcnt lgkmcnt(4)
	v_mfma_f32_16x16x32_f16 v[138:141], v[202:205], v[198:201], v[138:141]
	ds_read_b128 v[232:235], v136 offset:55296
	s_waitcnt lgkmcnt(4)
	v_mfma_f32_16x16x32_f16 v[92:95], v[202:205], v[206:209], v[92:95]
	v_mov_b32_e32 v0, v101
	v_and_b32_e32 v0, 0xffffff80, v0
	s_nop 0
	v_readfirstlane_b32 s101, v0
	v_lshl_add_u64 v[0:1], v[108:109], 0, v[30:31]
	s_mov_b32 m0, s101
	s_nop 0
	global_load_lds_dwordx4 v[0:1], off
	v_mfma_f32_16x16x32_f16 v[142:145], v[210:213], v[198:201], v[142:145]
	v_mov_b32_e32 v4, v131
	v_and_b32_e32 v4, 0xffffff80, v4
	s_nop 0
	v_readfirstlane_b32 s101, v4
	v_lshl_add_u64 v[4:5], v[110:111], 0, v[30:31]
	s_mov_b32 m0, s101
	s_nop 0
	global_load_lds_dwordx4 v[4:5], off
	v_mfma_f32_16x16x32_f16 v[158:161], v[210:213], v[206:209], v[158:161]
	v_mov_b32_e32 v8, v132
	v_and_b32_e32 v8, 0xffffff80, v8
	s_nop 0
	v_readfirstlane_b32 s101, v8
	v_lshl_add_u64 v[8:9], v[112:113], 0, v[30:31]
	s_mov_b32 m0, s101
	s_nop 0
	global_load_lds_dwordx4 v[8:9], off
	s_waitcnt lgkmcnt(2)
	v_mfma_f32_16x16x32_f16 v[166:169], v[202:205], v[220:223], v[166:169]
	v_mov_b32_e32 v12, v130
	v_and_b32_e32 v12, 0xffffff80, v12
	s_nop 0
	v_readfirstlane_b32 s101, v12
	v_lshl_add_u64 v[12:13], v[114:115], 0, v[30:31]
	s_mov_b32 m0, s101
	s_nop 0
	global_load_lds_dwordx4 v[12:13], off
	s_waitcnt lgkmcnt(1)
	v_mfma_f32_16x16x32_f16 v[68:71], v[202:205], v[228:231], v[68:71]
	ds_read_b128 v[202:205], v135 offset:49152
	v_mfma_f32_16x16x32_f16 v[190:193], v[210:213], v[220:223], v[190:193]
	v_add_u32_e32 v16, 0x8000, v101
	v_and_b32_e32 v16, 0xffffff80, v16
	s_nop 0
	v_readfirstlane_b32 s101, v16
	v_lshl_add_u64 v[16:17], v[116:117], 0, v[30:31]
	s_mov_b32 m0, s101
	s_nop 0
	global_load_lds_dwordx4 v[16:17], off
	v_mfma_f32_16x16x32_f16 v[76:79], v[210:213], v[228:231], v[76:79]
	ds_read_b128 v[210:213], v135 offset:51200
	v_mfma_f32_16x16x32_f16 v[154:157], v[224:227], v[198:201], v[154:157]
	v_add_u32_e32 v20, 0x8000, v131
	v_and_b32_e32 v20, 0xffffff80, v20
	s_nop 0
	v_readfirstlane_b32 s101, v20
	v_lshl_add_u64 v[20:21], v[118:119], 0, v[30:31]
	s_mov_b32 m0, s101
	s_nop 0
	global_load_lds_dwordx4 v[20:21], off
	v_mfma_f32_16x16x32_f16 v[162:165], v[224:227], v[206:209], v[162:165]
	v_add_u32_e32 v24, 0x8000, v132
	v_and_b32_e32 v24, 0xffffff80, v24
	s_nop 0
	v_readfirstlane_b32 s101, v24
	v_lshl_add_u64 v[24:25], v[120:121], 0, v[30:31]
	s_mov_b32 m0, s101
	s_nop 0
	global_load_lds_dwordx4 v[24:25], off
	s_waitcnt lgkmcnt(2)
; #define GL_LOAD(s_, kt_) if (VAR != 1) { a##s_##0 = GL_A(0, kt_); a##s_##1 = GL_A(1, kt_); a##s_##2 = GL_A(2, kt_); a##s_##3 = GL_A(3, kt_); b##s_##0 = GL_B(0, kt_); b##s_##1 = GL_B(1, kt_); b##s_##2 = GL_B(2, kt_); b##s_##3 = GL_B(3, kt_); }
; #define LDS_STORE(s_, buf_) if (VAR != 2) { LDS_ST1(sA, 0, buf_, a##s_##0) LDS_ST1(sA, 1, buf_, a##s_##1) LDS_ST1(sA, 2, buf_, a##s_##2) LDS_ST1(sA, 3, buf_, a##s_##3) LDS_ST1(sB, 0, buf_, b##s_##0) LDS_ST1(sB, 1, buf_, b##s_##1) LDS_ST1(sB, 2, buf_, b##s_##2) LDS_ST1(sB, 3, buf_, b##s_##3) }
;     ...
;   GL_LOAD(0, 0)
;   GL_LOAD(1, 1)
;   LDS_STORE(0, 0)
;   if (VAR != 4) __syncthreads();
; #pragma unroll
;   for (int kt = 0; kt < nk; kt += 2) {
;     if (kt + 2 < nk) { GL_LOAD(0, kt + 2) }
;     MMA_TILE(0)
;     LDS_STORE(1, 1)
;     if (VAR != 4) __syncthreads();
;     if (kt + 3 < nk) { GL_LOAD(1, kt + 3) }
;     MMA_TILE(1)
;     if (kt + 2 < nk) { LDS_STORE(0, 0) }
;     if (VAR != 4) __syncthreads();
	v_mfma_f32_16x16x32_f16 v[64:67], v[232:235], v[198:201], v[64:67]
	ds_read_b128 v[198:201], v134 offset:16384
	v_mfma_f32_16x16x32_f16 v[72:75], v[232:235], v[206:209], v[72:75]
	ds_read_b128 v[206:209], v134 offset:18432
	v_mfma_f32_16x16x32_f16 v[194:197], v[224:227], v[220:223], v[194:197]
	v_add_u32_e32 v28, 0x8000, v130
	v_and_b32_e32 v28, 0xffffff80, v28
	s_nop 0
	v_readfirstlane_b32 s101, v28
	v_lshl_add_u64 v[28:29], v[122:123], 0, v[30:31]
	s_mov_b32 m0, s101
	s_nop 0
	global_load_lds_dwordx4 v[28:29], off
	v_mfma_f32_16x16x32_f16 v[84:87], v[224:227], v[228:231], v[84:87]
	ds_read_b128 v[224:227], v135 offset:53248
	v_mfma_f32_16x16x32_f16 v[80:83], v[232:235], v[220:223], v[80:83]
	ds_read_b128 v[220:223], v134 offset:20480
	v_mfma_f32_16x16x32_f16 v[88:91], v[232:235], v[228:231], v[88:91]
	ds_read_b128 v[228:231], v134 offset:22528
	ds_read_b128 v[232:235], v135 offset:55296
	s_waitcnt vmcnt(0) lgkmcnt(0)
	s_barrier
	v_mfma_f32_16x16x32_f16 v[138:141], v[202:205], v[198:201], v[138:141]
	v_mfma_f32_16x16x32_f16 v[92:95], v[202:205], v[206:209], v[92:95]
	v_mfma_f32_16x16x32_f16 v[142:145], v[210:213], v[198:201], v[142:145]
	v_mfma_f32_16x16x32_f16 v[158:161], v[210:213], v[206:209], v[158:161]
	v_mfma_f32_16x16x32_f16 v[166:169], v[202:205], v[220:223], v[166:169]
	v_mfma_f32_16x16x32_f16 v[68:71], v[202:205], v[228:231], v[68:71]
	ds_read_b128 v[202:205], v136 offset:32768
	v_mfma_f32_16x16x32_f16 v[190:193], v[210:213], v[220:223], v[190:193]
	v_mfma_f32_16x16x32_f16 v[76:79], v[210:213], v[228:231], v[76:79]
	ds_read_b128 v[210:213], v136 offset:34816
	v_mfma_f32_16x16x32_f16 v[154:157], v[224:227], v[198:201], v[154:157]
	v_mfma_f32_16x16x32_f16 v[162:165], v[224:227], v[206:209], v[162:165]
	v_mfma_f32_16x16x32_f16 v[64:67], v[232:235], v[198:201], v[64:67]
	ds_read_b128 v[198:201], v133
	v_mfma_f32_16x16x32_f16 v[72:75], v[232:235], v[206:209], v[72:75]
	ds_read_b128 v[206:209], v133 offset:2048
	v_mfma_f32_16x16x32_f16 v[194:197], v[224:227], v[220:223], v[194:197]
	v_and_b32_e32 v62, 7, v148
	v_bfe_u32 v63, v148, 4, 3
	v_xor_b32_e32 v63, v63, v62
	v_sub_u32_e32 v63, v63, v62
	v_lshlrev_b32_e32 v62, 4, v63
	v_add_u32_e32 v62, 0x380, v62
	v_ashrrev_i32_e32 v63, 31, v62
	v_mfma_f32_16x16x32_f16 v[84:87], v[224:227], v[228:231], v[84:87]
	ds_read_b128 v[224:227], v136 offset:36864
	v_mfma_f32_16x16x32_f16 v[80:83], v[232:235], v[220:223], v[80:83]
	ds_read_b128 v[220:223], v133 offset:4096
	v_mfma_f32_16x16x32_f16 v[88:91], v[232:235], v[228:231], v[88:91]
	ds_read_b128 v[228:231], v133 offset:6144
	s_waitcnt lgkmcnt(4)
	v_mfma_f32_16x16x32_f16 v[138:141], v[202:205], v[198:201], v[138:141]
	ds_read_b128 v[232:235], v136 offset:38912
	s_waitcnt lgkmcnt(4)
	v_mfma_f32_16x16x32_f16 v[92:95], v[202:205], v[206:209], v[92:95]
	v_add_u32_e32 v32, 0x4000, v101
	v_and_b32_e32 v32, 0xffffff80, v32
	s_nop 0
	v_readfirstlane_b32 s101, v32
	v_lshl_add_u64 v[32:33], v[108:109], 0, v[62:63]
	s_mov_b32 m0, s101
	s_nop 0
	global_load_lds_dwordx4 v[32:33], off
	v_mfma_f32_16x16x32_f16 v[142:145], v[210:213], v[198:201], v[142:145]
	v_add_u32_e32 v36, 0x4000, v131
	v_and_b32_e32 v36, 0xffffff80, v36
	s_nop 0
	v_readfirstlane_b32 s101, v36
	v_lshl_add_u64 v[36:37], v[110:111], 0, v[62:63]
	s_mov_b32 m0, s101
	s_nop 0
	global_load_lds_dwordx4 v[36:37], off
	v_mfma_f32_16x16x32_f16 v[158:161], v[210:213], v[206:209], v[158:161]
	v_add_u32_e32 v40, 0x4000, v132
	v_and_b32_e32 v40, 0xffffff80, v40
	s_nop 0
	v_readfirstlane_b32 s101, v40
	v_lshl_add_u64 v[40:41], v[112:113], 0, v[62:63]
	s_mov_b32 m0, s101
	s_nop 0
	global_load_lds_dwordx4 v[40:41], off
	s_waitcnt lgkmcnt(2)
	v_mfma_f32_16x16x32_f16 v[166:169], v[202:205], v[220:223], v[166:169]
	v_add_u32_e32 v44, 0x4000, v130
	v_and_b32_e32 v44, 0xffffff80, v44
	s_nop 0
	v_readfirstlane_b32 s101, v44
	v_lshl_add_u64 v[44:45], v[114:115], 0, v[62:63]
	s_mov_b32 m0, s101
	s_nop 0
	global_load_lds_dwordx4 v[44:45], off
	s_waitcnt lgkmcnt(1)
	v_mfma_f32_16x16x32_f16 v[68:71], v[202:205], v[228:231], v[68:71]
	ds_read_b128 v[202:205], v135 offset:32768
	v_mfma_f32_16x16x32_f16 v[190:193], v[210:213], v[220:223], v[190:193]
	v_add_u32_e32 v48, 0xc000, v101
	v_and_b32_e32 v48, 0xffffff80, v48
	s_nop 0
	v_readfirstlane_b32 s101, v48
	v_lshl_add_u64 v[48:49], v[116:117], 0, v[62:63]
	s_mov_b32 m0, s101
	s_nop 0
	global_load_lds_dwordx4 v[48:49], off
	v_mfma_f32_16x16x32_f16 v[76:79], v[210:213], v[228:231], v[76:79]
	ds_read_b128 v[210:213], v135 offset:34816
	v_mfma_f32_16x16x32_f16 v[154:157], v[224:227], v[198:201], v[154:157]
	v_add_u32_e32 v52, 0xc000, v131
	v_and_b32_e32 v52, 0xffffff80, v52
	s_nop 0
	v_readfirstlane_b32 s101, v52
	v_lshl_add_u64 v[52:53], v[118:119], 0, v[62:63]
	s_mov_b32 m0, s101
	s_nop 0
	global_load_lds_dwordx4 v[52:53], off
	v_mfma_f32_16x16x32_f16 v[162:165], v[224:227], v[206:209], v[162:165]
	v_add_u32_e32 v56, 0xc000, v132
	v_and_b32_e32 v56, 0xffffff80, v56
	s_nop 0
	v_readfirstlane_b32 s101, v56
	v_lshl_add_u64 v[56:57], v[120:121], 0, v[62:63]
	s_mov_b32 m0, s101
	s_nop 0
	global_load_lds_dwordx4 v[56:57], off
	s_waitcnt lgkmcnt(2)
	v_mfma_f32_16x16x32_f16 v[64:67], v[232:235], v[198:201], v[64:67]
	ds_read_b128 v[198:201], v134
	v_mfma_f32_16x16x32_f16 v[72:75], v[232:235], v[206:209], v[72:75]
	ds_read_b128 v[206:209], v134 offset:2048
	v_mfma_f32_16x16x32_f16 v[194:197], v[224:227], v[220:223], v[194:197]
	v_add_u32_e32 v60, 0xc000, v130
	v_and_b32_e32 v60, 0xffffff80, v60
	s_nop 0
	v_readfirstlane_b32 s101, v60
	v_lshl_add_u64 v[60:61], v[122:123], 0, v[62:63]
	s_mov_b32 m0, s101
	s_nop 0
	global_load_lds_dwordx4 v[60:61], off
	v_mfma_f32_16x16x32_f16 v[84:87], v[224:227], v[228:231], v[84:87]
	ds_read_b128 v[224:227], v135 offset:36864
	v_mfma_f32_16x16x32_f16 v[80:83], v[232:235], v[220:223], v[80:83]
	ds_read_b128 v[220:223], v134 offset:4096
	v_mfma_f32_16x16x32_f16 v[88:91], v[232:235], v[228:231], v[88:91]
	ds_read_b128 v[228:231], v134 offset:6144
	ds_read_b128 v[232:235], v135 offset:38912
	s_waitcnt vmcnt(0) lgkmcnt(0)
	s_barrier
; #define GL_LOAD(s_, kt_) if (VAR != 1) { a##s_##0 = GL_A(0, kt_); a##s_##1 = GL_A(1, kt_); a##s_##2 = GL_A(2, kt_); a##s_##3 = GL_A(3, kt_); b##s_##0 = GL_B(0, kt_); b##s_##1 = GL_B(1, kt_); b##s_##2 = GL_B(2, kt_); b##s_##3 = GL_B(3, kt_); }
; #define LDS_STORE(s_, buf_) if (VAR != 2) { LDS_ST1(sA, 0, buf_, a##s_##0) LDS_ST1(sA, 1, buf_, a##s_##1) LDS_ST1(sA, 2, buf_, a##s_##2) LDS_ST1(sA, 3, buf_, a##s_##3) LDS_ST1(sB, 0, buf_, b##s_##0) LDS_ST1(sB, 1, buf_, b##s_##1) LDS_ST1(sB, 2, buf_, b##s_##2) LDS_ST1(sB, 3, buf_, b##s_##3) }
;     ...
;   GL_LOAD(0, 0)
;   GL_LOAD(1, 1)
;   LDS_STORE(0, 0)
;   if (VAR != 4) __syncthreads();
; #pragma unroll
;   for (int kt = 0; kt < nk; kt += 2) {
;     if (kt + 2 < nk) { GL_LOAD(0, kt + 2) }
;     MMA_TILE(0)
;     LDS_STORE(1, 1)
;     if (VAR != 4) __syncthreads();
;     if (kt + 3 < nk) { GL_LOAD(1, kt + 3) }
;     MMA_TILE(1)
;     if (kt + 2 < nk) { LDS_STORE(0, 0) }
;     if (VAR != 4) __syncthreads();
	v_mfma_f32_16x16x32_f16 v[138:141], v[202:205], v[198:201], v[138:141]
	v_mfma_f32_16x16x32_f16 v[92:95], v[202:205], v[206:209], v[92:95]
	v_mfma_f32_16x16x32_f16 v[142:145], v[210:213], v[198:201], v[142:145]
	v_mfma_f32_16x16x32_f16 v[158:161], v[210:213], v[206:209], v[158:161]
	v_mfma_f32_16x16x32_f16 v[166:169], v[202:205], v[220:223], v[166:169]
	v_mfma_f32_16x16x32_f16 v[68:71], v[202:205], v[228:231], v[68:71]
	ds_read_b128 v[202:205], v136 offset:49152
	v_mfma_f32_16x16x32_f16 v[190:193], v[210:213], v[220:223], v[190:193]
	v_mfma_f32_16x16x32_f16 v[76:79], v[210:213], v[228:231], v[76:79]
	ds_read_b128 v[210:213], v136 offset:51200
	v_mfma_f32_16x16x32_f16 v[154:157], v[224:227], v[198:201], v[154:157]
	v_mfma_f32_16x16x32_f16 v[162:165], v[224:227], v[206:209], v[162:165]
	v_mfma_f32_16x16x32_f16 v[64:67], v[232:235], v[198:201], v[64:67]
	ds_read_b128 v[198:201], v133 offset:16384
	v_mfma_f32_16x16x32_f16 v[72:75], v[232:235], v[206:209], v[72:75]
	ds_read_b128 v[206:209], v133 offset:18432
	v_mfma_f32_16x16x32_f16 v[194:197], v[224:227], v[220:223], v[194:197]
	v_and_b32_e32 v30, 7, v148
	v_bfe_u32 v31, v148, 4, 3
	v_xor_b32_e32 v31, v31, v30
	v_sub_u32_e32 v31, v31, v30
	v_lshlrev_b32_e32 v30, 4, v31
	v_add_u32_e32 v30, 0x400, v30
	v_ashrrev_i32_e32 v31, 31, v30
	v_mfma_f32_16x16x32_f16 v[84:87], v[224:227], v[228:231], v[84:87]
	ds_read_b128 v[224:227], v136 offset:53248
	v_mfma_f32_16x16x32_f16 v[80:83], v[232:235], v[220:223], v[80:83]
	ds_read_b128 v[220:223], v133 offset:20480
	v_mfma_f32_16x16x32_f16 v[88:91], v[232:235], v[228:231], v[88:91]
	ds_read_b128 v[228:231], v133 offset:22528
	s_waitcnt lgkmcnt(4)
	v_mfma_f32_16x16x32_f16 v[138:141], v[202:205], v[198:201], v[138:141]
	ds_read_b128 v[232:235], v136 offset:55296
	s_waitcnt lgkmcnt(4)
	v_mfma_f32_16x16x32_f16 v[92:95], v[202:205], v[206:209], v[92:95]
	v_mov_b32_e32 v0, v101
	v_and_b32_e32 v0, 0xffffff80, v0
	s_nop 0
	v_readfirstlane_b32 s101, v0
	v_lshl_add_u64 v[0:1], v[108:109], 0, v[30:31]
	s_mov_b32 m0, s101
	s_nop 0
	global_load_lds_dwordx4 v[0:1], off
	v_mfma_f32_16x16x32_f16 v[142:145], v[210:213], v[198:201], v[142:145]
	v_mov_b32_e32 v4, v131
	v_and_b32_e32 v4, 0xffffff80, v4
	s_nop 0
	v_readfirstlane_b32 s101, v4
	v_lshl_add_u64 v[4:5], v[110:111], 0, v[30:31]
	s_mov_b32 m0, s101
	s_nop 0
	global_load_lds_dwordx4 v[4:5], off
	v_mfma_f32_16x16x32_f16 v[158:161], v[210:213], v[206:209], v[158:161]
	v_mov_b32_e32 v8, v132
	v_and_b32_e32 v8, 0xffffff80, v8
	s_nop 0
	v_readfirstlane_b32 s101, v8
	v_lshl_add_u64 v[8:9], v[112:113], 0, v[30:31]
	s_mov_b32 m0, s101
	s_nop 0
	global_load_lds_dwordx4 v[8:9], off
	s_waitcnt lgkmcnt(2)
	v_mfma_f32_16x16x32_f16 v[166:169], v[202:205], v[220:223], v[166:169]
	v_mov_b32_e32 v12, v130
	v_and_b32_e32 v12, 0xffffff80, v12
	s_nop 0
	v_readfirstlane_b32 s101, v12
	v_lshl_add_u64 v[12:13], v[114:115], 0, v[30:31]
	s_mov_b32 m0, s101
	s_nop 0
	global_load_lds_dwordx4 v[12:13], off
	s_waitcnt lgkmcnt(1)
	v_mfma_f32_16x16x32_f16 v[68:71], v[202:205], v[228:231], v[68:71]
	ds_read_b128 v[202:205], v135 offset:49152
	v_mfma_f32_16x16x32_f16 v[190:193], v[210:213], v[220:223], v[190:193]
	v_add_u32_e32 v16, 0x8000, v101
	v_and_b32_e32 v16, 0xffffff80, v16
	s_nop 0
	v_readfirstlane_b32 s101, v16
	v_lshl_add_u64 v[16:17], v[116:117], 0, v[30:31]
	s_mov_b32 m0, s101
	s_nop 0
	global_load_lds_dwordx4 v[16:17], off
	v_mfma_f32_16x16x32_f16 v[76:79], v[210:213], v[228:231], v[76:79]
	ds_read_b128 v[210:213], v135 offset:51200
	v_mfma_f32_16x16x32_f16 v[154:157], v[224:227], v[198:201], v[154:157]
	v_add_u32_e32 v20, 0x8000, v131
	v_and_b32_e32 v20, 0xffffff80, v20
	s_nop 0
	v_readfirstlane_b32 s101, v20
	v_lshl_add_u64 v[20:21], v[118:119], 0, v[30:31]
	s_mov_b32 m0, s101
	s_nop 0
	global_load_lds_dwordx4 v[20:21], off
	v_mfma_f32_16x16x32_f16 v[162:165], v[224:227], v[206:209], v[162:165]
	v_add_u32_e32 v24, 0x8000, v132
	v_and_b32_e32 v24, 0xffffff80, v24
	s_nop 0
	v_readfirstlane_b32 s101, v24
	v_lshl_add_u64 v[24:25], v[120:121], 0, v[30:31]
	s_mov_b32 m0, s101
	s_nop 0
	global_load_lds_dwordx4 v[24:25], off
	s_waitcnt lgkmcnt(2)
	v_mfma_f32_16x16x32_f16 v[64:67], v[232:235], v[198:201], v[64:67]
	ds_read_b128 v[198:201], v134 offset:16384
	v_mfma_f32_16x16x32_f16 v[72:75], v[232:235], v[206:209], v[72:75]
	ds_read_b128 v[206:209], v134 offset:18432
	v_mfma_f32_16x16x32_f16 v[194:197], v[224:227], v[220:223], v[194:197]
	v_add_u32_e32 v28, 0x8000, v130
	v_and_b32_e32 v28, 0xffffff80, v28
	s_nop 0
	v_readfirstlane_b32 s101, v28
	v_lshl_add_u64 v[28:29], v[122:123], 0, v[30:31]
	s_mov_b32 m0, s101
	s_nop 0
	global_load_lds_dwordx4 v[28:29], off
	v_mfma_f32_16x16x32_f16 v[84:87], v[224:227], v[228:231], v[84:87]
	ds_read_b128 v[224:227], v135 offset:53248
	v_mfma_f32_16x16x32_f16 v[80:83], v[232:235], v[220:223], v[80:83]
	ds_read_b128 v[220:223], v134 offset:20480
	v_mfma_f32_16x16x32_f16 v[88:91], v[232:235], v[228:231], v[88:91]
	ds_read_b128 v[228:231], v134 offset:22528
	s_waitcnt lgkmcnt(4)
	v_mfma_f32_16x16x32_f16 v[138:141], v[202:205], v[198:201], v[138:141]
	ds_read_b128 v[232:235], v135 offset:55296
	s_waitcnt vmcnt(0) lgkmcnt(0)
	s_barrier
; #define GL_LOAD(s_, kt_) if (VAR != 1) { a##s_##0 = GL_A(0, kt_); a##s_##1 = GL_A(1, kt_); a##s_##2 = GL_A(2, kt_); a##s_##3 = GL_A(3, kt_); b##s_##0 = GL_B(0, kt_); b##s_##1 = GL_B(1, kt_); b##s_##2 = GL_B(2, kt_); b##s_##3 = GL_B(3, kt_); }
; #define LDS_STORE(s_, buf_) if (VAR != 2) { LDS_ST1(sA, 0, buf_, a##s_##0) LDS_ST1(sA, 1, buf_, a##s_##1) LDS_ST1(sA, 2, buf_, a##s_##2) LDS_ST1(sA, 3, buf_, a##s_##3) LDS_ST1(sB, 0, buf_, b##s_##0) LDS_ST1(sB, 1, buf_, b##s_##1) LDS_ST1(sB, 2, buf_, b##s_##2) LDS_ST1(sB, 3, buf_, b##s_##3) }
;     ...
;   GL_LOAD(0, 0)
;   GL_LOAD(1, 1)
;   LDS_STORE(0, 0)
;   if (VAR != 4) __syncthreads();
; #pragma unroll
;   for (int kt = 0; kt < nk; kt += 2) {
;     if (kt + 2 < nk) { GL_LOAD(0, kt + 2) }
;     MMA_TILE(0)
;     LDS_STORE(1, 1)
;     if (VAR != 4) __syncthreads();
;     if (kt + 3 < nk) { GL_LOAD(1, kt + 3) }
;     MMA_TILE(1)
;     if (kt + 2 < nk) { LDS_STORE(0, 0) }
;     if (VAR != 4) __syncthreads();
	v_mfma_f32_16x16x32_f16 v[142:145], v[210:213], v[198:201], v[142:145]
	ds_read_b128 v[0:3], v133
	v_mfma_f32_16x16x32_f16 v[158:161], v[210:213], v[206:209], v[158:161]
	ds_read_b128 v[4:7], v136 offset:32768
	v_mfma_f32_16x16x32_f16 v[154:157], v[224:227], v[198:201], v[154:157]
	ds_read_b128 v[8:11], v133 offset:2048
	v_mfma_f32_16x16x32_f16 v[162:165], v[224:227], v[206:209], v[162:165]
	ds_read_b128 v[12:15], v136 offset:34816
	v_mfma_f32_16x16x32_f16 v[190:193], v[210:213], v[220:223], v[190:193]
	ds_read_b128 v[16:19], v133 offset:4096
	v_mfma_f32_16x16x32_f16 v[210:213], v[210:213], v[228:231], v[76:79]
	ds_read_b128 v[20:23], v136 offset:36864
	v_mfma_f32_16x16x32_f16 v[194:197], v[224:227], v[220:223], v[194:197]
	ds_read_b128 v[24:27], v133 offset:6144
	v_mfma_f32_16x16x32_f16 v[224:227], v[224:227], v[228:231], v[84:87]
	ds_read_b128 v[28:31], v136 offset:38912
	v_mfma_f32_16x16x32_f16 v[198:201], v[232:235], v[198:201], v[64:67]
	s_nop 2
	v_mfma_f32_16x16x32_f16 v[236:239], v[202:205], v[206:209], v[92:95]
	v_mfma_f32_16x16x32_f16 v[206:209], v[232:235], v[206:209], v[72:75]
	v_mfma_f32_16x16x32_f16 v[166:169], v[202:205], v[220:223], v[166:169]
	v_mfma_f32_16x16x32_f16 v[220:223], v[232:235], v[220:223], v[80:83]
	v_mfma_f32_16x16x32_f16 v[202:205], v[202:205], v[228:231], v[68:71]
	v_mfma_f32_16x16x32_f16 v[228:231], v[232:235], v[228:231], v[88:91]
	ds_read_b128 v[232:235], v135 offset:38912
	s_nop 0
	s_waitcnt lgkmcnt(7)
	v_mfma_f32_16x16x32_f16 v[138:141], v[4:7], v[0:3], v[138:141]
	s_waitcnt lgkmcnt(5)
	v_mfma_f32_16x16x32_f16 v[142:145], v[12:15], v[0:3], v[142:145]
	s_waitcnt lgkmcnt(3)
	v_mfma_f32_16x16x32_f16 v[154:157], v[20:23], v[0:3], v[154:157]
	s_waitcnt lgkmcnt(1)
	v_mfma_f32_16x16x32_f16 v[0:3], v[28:31], v[0:3], v[198:201]
	v_mfma_f32_16x16x32_f16 v[198:201], v[4:7], v[8:11], v[236:239]
	v_mfma_f32_16x16x32_f16 v[158:161], v[12:15], v[8:11], v[158:161]
	v_and_b32_e32 v62, 7, v148
	v_bfe_u32 v63, v148, 4, 3
	v_xor_b32_e32 v63, v63, v62
	v_sub_u32_e32 v63, v63, v62
	v_lshlrev_b32_e32 v62, 4, v63
	v_add_u32_e32 v62, 0x480, v62
	v_ashrrev_i32_e32 v63, 31, v62
	v_add_u32_e32 v32, 0x4000, v101
	v_and_b32_e32 v32, 0xffffff80, v32
	s_nop 0
	v_readfirstlane_b32 s101, v32
	v_lshl_add_u64 v[32:33], v[108:109], 0, v[62:63]
	s_mov_b32 m0, s101
	s_nop 0
	global_load_lds_dwordx4 v[32:33], off
	v_mfma_f32_16x16x32_f16 v[166:169], v[4:7], v[16:19], v[166:169]
	v_add_u32_e32 v36, 0x4000, v131
	v_and_b32_e32 v36, 0xffffff80, v36
	s_nop 0
	v_readfirstlane_b32 s101, v36
	v_lshl_add_u64 v[36:37], v[110:111], 0, v[62:63]
	s_mov_b32 m0, s101
	s_nop 0
	global_load_lds_dwordx4 v[36:37], off
	v_add_u32_e32 v40, 0x4000, v132
	v_and_b32_e32 v40, 0xffffff80, v40
	s_nop 0
	v_readfirstlane_b32 s101, v40
	v_lshl_add_u64 v[40:41], v[112:113], 0, v[62:63]
	s_mov_b32 m0, s101
	s_nop 0
	global_load_lds_dwordx4 v[40:41], off
	v_mfma_f32_16x16x32_f16 v[4:7], v[4:7], v[24:27], v[202:205]
	s_nop 2
	ds_read_b128 v[202:205], v135 offset:32768
	v_add_u32_e32 v44, 0x4000, v130
	v_and_b32_e32 v44, 0xffffff80, v44
	s_nop 0
	v_readfirstlane_b32 s101, v44
	v_lshl_add_u64 v[44:45], v[114:115], 0, v[62:63]
	s_mov_b32 m0, s101
	s_nop 0
	global_load_lds_dwordx4 v[44:45], off
	v_mfma_f32_16x16x32_f16 v[190:193], v[12:15], v[16:19], v[190:193]
	v_add_u32_e32 v48, 0xc000, v101
	v_and_b32_e32 v48, 0xffffff80, v48
	s_nop 0
	v_readfirstlane_b32 s101, v48
	v_lshl_add_u64 v[48:49], v[116:117], 0, v[62:63]
	s_mov_b32 m0, s101
	s_nop 0
	global_load_lds_dwordx4 v[48:49], off
	v_mfma_f32_16x16x32_f16 v[12:15], v[12:15], v[24:27], v[210:213]
	s_nop 2
	ds_read_b128 v[210:213], v135 offset:34816
	v_add_u32_e32 v52, 0xc000, v131
	v_and_b32_e32 v52, 0xffffff80, v52
	s_nop 0
	v_readfirstlane_b32 s101, v52
	v_lshl_add_u64 v[52:53], v[118:119], 0, v[62:63]
	s_mov_b32 m0, s101
	s_nop 0
	global_load_lds_dwordx4 v[52:53], off
	v_mfma_f32_16x16x32_f16 v[162:165], v[20:23], v[8:11], v[162:165]
	v_add_u32_e32 v56, 0xc000, v132
	v_and_b32_e32 v56, 0xffffff80, v56
	s_nop 0
	v_readfirstlane_b32 s101, v56
	v_lshl_add_u64 v[56:57], v[120:121], 0, v[62:63]
	s_mov_b32 m0, s101
	s_nop 0
	global_load_lds_dwordx4 v[56:57], off
	v_add_u32_e32 v60, 0xc000, v130
	v_and_b32_e32 v60, 0xffffff80, v60
	s_nop 0
	v_readfirstlane_b32 s101, v60
	v_lshl_add_u64 v[60:61], v[122:123], 0, v[62:63]
	s_mov_b32 m0, s101
	s_nop 0
	global_load_lds_dwordx4 v[60:61], off
	v_mfma_f32_16x16x32_f16 v[8:11], v[28:31], v[8:11], v[206:209]
	s_nop 2
	ds_read_b128 v[206:209], v134 offset:2048
	v_mfma_f32_16x16x32_f16 v[194:197], v[20:23], v[16:19], v[194:197]
	v_mfma_f32_16x16x32_f16 v[20:23], v[20:23], v[24:27], v[224:227]
	s_nop 2
	ds_read_b128 v[224:227], v135 offset:36864
	v_mfma_f32_16x16x32_f16 v[16:19], v[28:31], v[16:19], v[220:223]
	s_nop 2
	ds_read_b128 v[220:223], v134 offset:4096
	v_mfma_f32_16x16x32_f16 v[24:27], v[28:31], v[24:27], v[228:231]
	ds_read_b128 v[28:31], v134
	s_waitcnt lgkmcnt(0)
	v_mfma_f32_16x16x32_f16 v[138:141], v[202:205], v[28:31], v[138:141]
	ds_read_b128 v[228:231], v134 offset:6144
	s_waitcnt vmcnt(0) lgkmcnt(0)
	s_barrier
; #define GL_LOAD(s_, kt_) if (VAR != 1) { a##s_##0 = GL_A(0, kt_); a##s_##1 = GL_A(1, kt_); a##s_##2 = GL_A(2, kt_); a##s_##3 = GL_A(3, kt_); b##s_##0 = GL_B(0, kt_); b##s_##1 = GL_B(1, kt_); b##s_##2 = GL_B(2, kt_); b##s_##3 = GL_B(3, kt_); }
; #define LDS_STORE(s_, buf_) if (VAR != 2) { LDS_ST1(sA, 0, buf_, a##s_##0) LDS_ST1(sA, 1, buf_, a##s_##1) LDS_ST1(sA, 2, buf_, a##s_##2) LDS_ST1(sA, 3, buf_, a##s_##3) LDS_ST1(sB, 0, buf_, b##s_##0) LDS_ST1(sB, 1, buf_, b##s_##1) LDS_ST1(sB, 2, buf_, b##s_##2) LDS_ST1(sB, 3, buf_, b##s_##3) }
;     ...
;   GL_LOAD(0, 0)
;   GL_LOAD(1, 1)
;   LDS_STORE(0, 0)
;   if (VAR != 4) __syncthreads();
; #pragma unroll
;   for (int kt = 0; kt < nk; kt += 2) {
;     if (kt + 2 < nk) { GL_LOAD(0, kt + 2) }
;     MMA_TILE(0)
;     LDS_STORE(1, 1)
;     if (VAR != 4) __syncthreads();
;     if (kt + 3 < nk) { GL_LOAD(1, kt + 3) }
;     MMA_TILE(1)
;     if (kt + 2 < nk) { LDS_STORE(0, 0) }
;     if (VAR != 4) __syncthreads();
	v_mfma_f32_16x16x32_f16 v[142:145], v[210:213], v[28:31], v[142:145]
	ds_read_b128 v[32:35], v133 offset:16384
	v_mfma_f32_16x16x32_f16 v[158:161], v[210:213], v[206:209], v[158:161]
	ds_read_b128 v[36:39], v136 offset:49152
	v_mfma_f32_16x16x32_f16 v[154:157], v[224:227], v[28:31], v[154:157]
	ds_read_b128 v[40:43], v133 offset:18432
	v_mfma_f32_16x16x32_f16 v[162:165], v[224:227], v[206:209], v[162:165]
	ds_read_b128 v[44:47], v136 offset:51200
	v_mfma_f32_16x16x32_f16 v[190:193], v[210:213], v[220:223], v[190:193]
	ds_read_b128 v[48:51], v133 offset:20480
	v_mfma_f32_16x16x32_f16 v[210:213], v[210:213], v[228:231], v[12:15]
	ds_read_b128 v[52:55], v136 offset:53248
	v_mfma_f32_16x16x32_f16 v[194:197], v[224:227], v[220:223], v[194:197]
	ds_read_b128 v[56:59], v133 offset:22528
	v_mfma_f32_16x16x32_f16 v[224:227], v[224:227], v[228:231], v[20:23]
	ds_read_b128 v[60:63], v136 offset:55296
	v_mfma_f32_16x16x32_f16 v[236:239], v[232:235], v[28:31], v[0:3]
	v_mfma_f32_16x16x32_f16 v[198:201], v[202:205], v[206:209], v[198:201]
	v_mfma_f32_16x16x32_f16 v[206:209], v[232:235], v[206:209], v[8:11]
	v_mfma_f32_16x16x32_f16 v[166:169], v[202:205], v[220:223], v[166:169]
	v_mfma_f32_16x16x32_f16 v[220:223], v[232:235], v[220:223], v[16:19]
	v_mfma_f32_16x16x32_f16 v[202:205], v[202:205], v[228:231], v[4:7]
	v_mfma_f32_16x16x32_f16 v[228:231], v[232:235], v[228:231], v[24:27]
	ds_read_b128 v[232:235], v135 offset:55296
	s_nop 1
	s_waitcnt lgkmcnt(7)
	v_mfma_f32_16x16x32_f16 v[138:141], v[36:39], v[32:35], v[138:141]
	s_waitcnt lgkmcnt(6)
	v_mfma_f32_16x16x32_f16 v[198:201], v[36:39], v[40:43], v[198:201]
	s_waitcnt lgkmcnt(5)
	v_mfma_f32_16x16x32_f16 v[142:145], v[44:47], v[32:35], v[142:145]
	v_mfma_f32_16x16x32_f16 v[158:161], v[44:47], v[40:43], v[158:161]
	s_waitcnt lgkmcnt(4)
	v_mfma_f32_16x16x32_f16 v[166:169], v[36:39], v[48:51], v[166:169]
	v_and_b32_e32 v94, 7, v148
	v_bfe_u32 v95, v148, 4, 3
	v_xor_b32_e32 v95, v95, v94
	v_sub_u32_e32 v95, v95, v94
	v_lshlrev_b32_e32 v94, 4, v95
	v_add_u32_e32 v94, 0x500, v94
	v_ashrrev_i32_e32 v95, 31, v94
	s_waitcnt lgkmcnt(2)
	v_mfma_f32_16x16x32_f16 v[36:39], v[36:39], v[56:59], v[202:205]
	s_nop 2
	ds_read_b128 v[202:205], v135 offset:49152
	v_mov_b32_e32 v64, v101
	v_and_b32_e32 v64, 0xffffff80, v64
	s_nop 0
	v_readfirstlane_b32 s101, v64
	v_lshl_add_u64 v[64:65], v[108:109], 0, v[94:95]
	s_mov_b32 m0, s101
	s_nop 0
	global_load_lds_dwordx4 v[64:65], off
	v_mfma_f32_16x16x32_f16 v[190:193], v[44:47], v[48:51], v[190:193]
	v_mov_b32_e32 v68, v131
	v_and_b32_e32 v68, 0xffffff80, v68
	s_nop 0
	v_readfirstlane_b32 s101, v68
	v_lshl_add_u64 v[68:69], v[110:111], 0, v[94:95]
	s_mov_b32 m0, s101
	s_nop 0
	global_load_lds_dwordx4 v[68:69], off
	v_mov_b32_e32 v72, v132
	v_and_b32_e32 v72, 0xffffff80, v72
	s_nop 0
	v_readfirstlane_b32 s101, v72
	v_lshl_add_u64 v[72:73], v[112:113], 0, v[94:95]
	s_mov_b32 m0, s101
	s_nop 0
	global_load_lds_dwordx4 v[72:73], off
	v_mfma_f32_16x16x32_f16 v[44:47], v[44:47], v[56:59], v[210:213]
	s_nop 2
	ds_read_b128 v[210:213], v135 offset:51200
	v_mfma_f32_16x16x32_f16 v[154:157], v[52:55], v[32:35], v[154:157]
	v_mov_b32_e32 v76, v130
	v_and_b32_e32 v76, 0xffffff80, v76
	s_nop 0
	v_readfirstlane_b32 s101, v76
	v_lshl_add_u64 v[76:77], v[114:115], 0, v[94:95]
	s_mov_b32 m0, s101
	s_nop 0
	global_load_lds_dwordx4 v[76:77], off
	v_mfma_f32_16x16x32_f16 v[162:165], v[52:55], v[40:43], v[162:165]
	v_add_u32_e32 v80, 0x8000, v101
	v_and_b32_e32 v80, 0xffffff80, v80
	s_nop 0
	v_readfirstlane_b32 s101, v80
	v_lshl_add_u64 v[80:81], v[116:117], 0, v[94:95]
	s_mov_b32 m0, s101
	s_nop 0
	global_load_lds_dwordx4 v[80:81], off
	s_waitcnt lgkmcnt(3)
	v_mfma_f32_16x16x32_f16 v[32:35], v[60:63], v[32:35], v[236:239]
	v_add_u32_e32 v84, 0x8000, v131
	v_and_b32_e32 v84, 0xffffff80, v84
	s_nop 0
	v_readfirstlane_b32 s101, v84
	v_lshl_add_u64 v[84:85], v[118:119], 0, v[94:95]
	s_mov_b32 m0, s101
	s_nop 0
	global_load_lds_dwordx4 v[84:85], off
	v_mfma_f32_16x16x32_f16 v[40:43], v[60:63], v[40:43], v[206:209]
	s_nop 2
	ds_read_b128 v[206:209], v134 offset:18432
	v_mfma_f32_16x16x32_f16 v[194:197], v[52:55], v[48:51], v[194:197]
	v_add_u32_e32 v88, 0x8000, v132
	v_and_b32_e32 v88, 0xffffff80, v88
	s_nop 0
	v_readfirstlane_b32 s101, v88
	v_lshl_add_u64 v[88:89], v[120:121], 0, v[94:95]
	s_mov_b32 m0, s101
	s_nop 0
	global_load_lds_dwordx4 v[88:89], off
	v_mfma_f32_16x16x32_f16 v[52:55], v[52:55], v[56:59], v[224:227]
	s_nop 2
	ds_read_b128 v[224:227], v135 offset:53248
	v_mfma_f32_16x16x32_f16 v[48:51], v[60:63], v[48:51], v[220:223]
	s_nop 2
	ds_read_b128 v[220:223], v134 offset:20480
	v_mfma_f32_16x16x32_f16 v[56:59], v[60:63], v[56:59], v[228:231]
	ds_read_b128 v[60:63], v134 offset:16384
	s_waitcnt lgkmcnt(0)
	v_mfma_f32_16x16x32_f16 v[138:141], v[202:205], v[60:63], v[138:141]
	ds_read_b128 v[228:231], v134 offset:22528
	v_add_u32_e32 v92, 0x8000, v130
	v_and_b32_e32 v92, 0xffffff80, v92
	s_nop 0
	v_readfirstlane_b32 s101, v92
	v_lshl_add_u64 v[92:93], v[122:123], 0, v[94:95]
	s_mov_b32 m0, s101
	s_nop 0
	global_load_lds_dwordx4 v[92:93], off
	s_waitcnt vmcnt(0) lgkmcnt(0)
	s_barrier
; #define GL_LOAD(s_, kt_) if (VAR != 1) { a##s_##0 = GL_A(0, kt_); a##s_##1 = GL_A(1, kt_); a##s_##2 = GL_A(2, kt_); a##s_##3 = GL_A(3, kt_); b##s_##0 = GL_B(0, kt_); b##s_##1 = GL_B(1, kt_); b##s_##2 = GL_B(2, kt_); b##s_##3 = GL_B(3, kt_); }
; #define LDS_STORE(s_, buf_) if (VAR != 2) { LDS_ST1(sA, 0, buf_, a##s_##0) LDS_ST1(sA, 1, buf_, a##s_##1) LDS_ST1(sA, 2, buf_, a##s_##2) LDS_ST1(sA, 3, buf_, a##s_##3) LDS_ST1(sB, 0, buf_, b##s_##0) LDS_ST1(sB, 1, buf_, b##s_##1) LDS_ST1(sB, 2, buf_, b##s_##2) LDS_ST1(sB, 3, buf_, b##s_##3) }
;     ...
;   GL_LOAD(0, 0)
;   GL_LOAD(1, 1)
;   LDS_STORE(0, 0)
;   if (VAR != 4) __syncthreads();
; #pragma unroll
;   for (int kt = 0; kt < nk; kt += 2) {
;     if (kt + 2 < nk) { GL_LOAD(0, kt + 2) }
;     MMA_TILE(0)
;     LDS_STORE(1, 1)
;     if (VAR != 4) __syncthreads();
;     if (kt + 3 < nk) { GL_LOAD(1, kt + 3) }
;     MMA_TILE(1)
;     if (kt + 2 < nk) { LDS_STORE(0, 0) }
;     if (VAR != 4) __syncthreads();
	v_mfma_f32_16x16x32_f16 v[142:145], v[210:213], v[60:63], v[142:145]
	ds_read_b128 v[64:67], v133
	v_mfma_f32_16x16x32_f16 v[158:161], v[210:213], v[206:209], v[158:161]
	ds_read_b128 v[68:71], v136 offset:32768
	v_mfma_f32_16x16x32_f16 v[154:157], v[224:227], v[60:63], v[154:157]
	ds_read_b128 v[72:75], v133 offset:2048
	v_mfma_f32_16x16x32_f16 v[162:165], v[224:227], v[206:209], v[162:165]
	ds_read_b128 v[76:79], v136 offset:34816
	v_mfma_f32_16x16x32_f16 v[190:193], v[210:213], v[220:223], v[190:193]
	ds_read_b128 v[80:83], v133 offset:4096
	v_mfma_f32_16x16x32_f16 v[210:213], v[210:213], v[228:231], v[44:47]
	ds_read_b128 v[84:87], v136 offset:36864
	v_mfma_f32_16x16x32_f16 v[194:197], v[224:227], v[220:223], v[194:197]
	ds_read_b128 v[88:91], v133 offset:6144
	v_mfma_f32_16x16x32_f16 v[224:227], v[224:227], v[228:231], v[52:55]
	ds_read_b128 v[92:95], v136 offset:38912
	v_mfma_f32_16x16x32_f16 v[236:239], v[232:235], v[60:63], v[32:35]
	s_nop 0
	v_mfma_f32_16x16x32_f16 v[198:201], v[202:205], v[206:209], v[198:201]
	v_mfma_f32_16x16x32_f16 v[206:209], v[232:235], v[206:209], v[40:43]
	v_mfma_f32_16x16x32_f16 v[166:169], v[202:205], v[220:223], v[166:169]
	v_mfma_f32_16x16x32_f16 v[220:223], v[232:235], v[220:223], v[48:51]
	v_mfma_f32_16x16x32_f16 v[202:205], v[202:205], v[228:231], v[36:39]
	v_mfma_f32_16x16x32_f16 v[228:231], v[232:235], v[228:231], v[56:59]
	ds_read_b128 v[232:235], v135 offset:38912
	s_nop 1
	s_waitcnt lgkmcnt(7)
	v_mfma_f32_16x16x32_f16 v[138:141], v[68:71], v[64:67], v[138:141]
	s_waitcnt lgkmcnt(6)
	v_mfma_f32_16x16x32_f16 v[198:201], v[68:71], v[72:75], v[198:201]
	s_waitcnt lgkmcnt(5)
	v_mfma_f32_16x16x32_f16 v[142:145], v[76:79], v[64:67], v[142:145]
	v_mfma_f32_16x16x32_f16 v[158:161], v[76:79], v[72:75], v[158:161]
	s_waitcnt lgkmcnt(4)
	v_mfma_f32_16x16x32_f16 v[166:169], v[68:71], v[80:83], v[166:169]
	v_and_b32_e32 v10, 7, v148
	v_bfe_u32 v11, v148, 4, 3
	v_xor_b32_e32 v11, v11, v10
	v_sub_u32_e32 v11, v11, v10
	v_lshlrev_b32_e32 v10, 4, v11
	v_add_u32_e32 v10, 0x580, v10
	v_ashrrev_i32_e32 v11, 31, v10
	v_add_u32_e32 v28, 0x4000, v101
	v_and_b32_e32 v28, 0xffffff80, v28
	s_nop 0
	v_readfirstlane_b32 s101, v28
	v_lshl_add_u64 v[28:29], v[108:109], 0, v[10:11]
	s_mov_b32 m0, s101
	s_nop 0
	global_load_lds_dwordx4 v[28:29], off
	s_waitcnt lgkmcnt(2)
	v_mfma_f32_16x16x32_f16 v[68:71], v[68:71], v[88:91], v[202:205]
	s_nop 2
	ds_read_b128 v[202:205], v135 offset:32768
	v_add_u32_e32 v24, 0x4000, v131
	v_and_b32_e32 v24, 0xffffff80, v24
	s_nop 0
	v_readfirstlane_b32 s101, v24
	v_lshl_add_u64 v[24:25], v[110:111], 0, v[10:11]
	s_mov_b32 m0, s101
	s_nop 0
	global_load_lds_dwordx4 v[24:25], off
	v_mfma_f32_16x16x32_f16 v[190:193], v[76:79], v[80:83], v[190:193]
	v_add_u32_e32 v12, 0x4000, v132
	v_and_b32_e32 v12, 0xffffff80, v12
	s_nop 0
	v_readfirstlane_b32 s101, v12
	v_lshl_add_u64 v[12:13], v[112:113], 0, v[10:11]
	s_mov_b32 m0, s101
	s_nop 0
	global_load_lds_dwordx4 v[12:13], off
	v_add_u32_e32 v16, 0x4000, v130
	v_and_b32_e32 v16, 0xffffff80, v16
	s_nop 0
	v_readfirstlane_b32 s101, v16
	v_lshl_add_u64 v[16:17], v[114:115], 0, v[10:11]
	s_mov_b32 m0, s101
	s_nop 0
	global_load_lds_dwordx4 v[16:17], off
	v_mfma_f32_16x16x32_f16 v[76:79], v[76:79], v[88:91], v[210:213]
	s_nop 2
	ds_read_b128 v[210:213], v135 offset:34816
	v_mfma_f32_16x16x32_f16 v[154:157], v[84:87], v[64:67], v[154:157]
	v_add_u32_e32 v20, 0xc000, v101
	v_and_b32_e32 v20, 0xffffff80, v20
	s_nop 0
	v_readfirstlane_b32 s101, v20
	v_lshl_add_u64 v[20:21], v[116:117], 0, v[10:11]
	s_mov_b32 m0, s101
	s_nop 0
	global_load_lds_dwordx4 v[20:21], off
	v_mfma_f32_16x16x32_f16 v[162:165], v[84:87], v[72:75], v[162:165]
	v_add_u32_e32 v0, 0xc000, v131
	v_and_b32_e32 v0, 0xffffff80, v0
	s_nop 0
	v_readfirstlane_b32 s101, v0
	v_lshl_add_u64 v[0:1], v[118:119], 0, v[10:11]
	s_mov_b32 m0, s101
	s_nop 0
	global_load_lds_dwordx4 v[0:1], off
	s_waitcnt lgkmcnt(3)
	v_mfma_f32_16x16x32_f16 v[64:67], v[92:95], v[64:67], v[236:239]
	v_add_u32_e32 v4, 0xc000, v132
	v_and_b32_e32 v4, 0xffffff80, v4
	s_nop 0
	v_readfirstlane_b32 s101, v4
	v_lshl_add_u64 v[4:5], v[120:121], 0, v[10:11]
	s_mov_b32 m0, s101
	s_nop 0
	global_load_lds_dwordx4 v[4:5], off
	v_mfma_f32_16x16x32_f16 v[72:75], v[92:95], v[72:75], v[206:209]
	s_nop 2
	ds_read_b128 v[206:209], v134 offset:2048
	v_mfma_f32_16x16x32_f16 v[194:197], v[84:87], v[80:83], v[194:197]
	v_add_u32_e32 v8, 0xc000, v130
	v_and_b32_e32 v8, 0xffffff80, v8
	s_nop 0
	v_readfirstlane_b32 s101, v8
	v_lshl_add_u64 v[8:9], v[122:123], 0, v[10:11]
	s_mov_b32 m0, s101
	s_nop 0
	global_load_lds_dwordx4 v[8:9], off
	v_mfma_f32_16x16x32_f16 v[84:87], v[84:87], v[88:91], v[224:227]
	s_nop 2
	ds_read_b128 v[224:227], v135 offset:36864
	v_mfma_f32_16x16x32_f16 v[80:83], v[92:95], v[80:83], v[220:223]
	s_nop 2
	ds_read_b128 v[220:223], v134 offset:4096
	v_mfma_f32_16x16x32_f16 v[88:91], v[92:95], v[88:91], v[228:231]
	ds_read_b128 v[92:95], v134
	s_nop 1
	ds_read_b128 v[228:231], v134 offset:6144
	s_waitcnt vmcnt(0) lgkmcnt(0)
	s_barrier
; #define GL_LOAD(s_, kt_) if (VAR != 1) { a##s_##0 = GL_A(0, kt_); a##s_##1 = GL_A(1, kt_); a##s_##2 = GL_A(2, kt_); a##s_##3 = GL_A(3, kt_); b##s_##0 = GL_B(0, kt_); b##s_##1 = GL_B(1, kt_); b##s_##2 = GL_B(2, kt_); b##s_##3 = GL_B(3, kt_); }
; #define LDS_STORE(s_, buf_) if (VAR != 2) { LDS_ST1(sA, 0, buf_, a##s_##0) LDS_ST1(sA, 1, buf_, a##s_##1) LDS_ST1(sA, 2, buf_, a##s_##2) LDS_ST1(sA, 3, buf_, a##s_##3) LDS_ST1(sB, 0, buf_, b##s_##0) LDS_ST1(sB, 1, buf_, b##s_##1) LDS_ST1(sB, 2, buf_, b##s_##2) LDS_ST1(sB, 3, buf_, b##s_##3) }
;     ...
;   GL_LOAD(0, 0)
;   GL_LOAD(1, 1)
;   LDS_STORE(0, 0)
;   if (VAR != 4) __syncthreads();
; #pragma unroll
;   for (int kt = 0; kt < nk; kt += 2) {
;     if (kt + 2 < nk) { GL_LOAD(0, kt + 2) }
;     MMA_TILE(0)
;     LDS_STORE(1, 1)
;     if (VAR != 4) __syncthreads();
;     if (kt + 3 < nk) { GL_LOAD(1, kt + 3) }
;     MMA_TILE(1)
;     if (kt + 2 < nk) { LDS_STORE(0, 0) }
;     if (VAR != 4) __syncthreads();
	v_mfma_f32_16x16x32_f16 v[138:141], v[202:205], v[92:95], v[138:141]
	v_mfma_f32_16x16x32_f16 v[142:145], v[210:213], v[92:95], v[142:145]
	v_mfma_f32_16x16x32_f16 v[154:157], v[224:227], v[92:95], v[154:157]
	v_mfma_f32_16x16x32_f16 v[64:67], v[232:235], v[92:95], v[64:67]
	v_mfma_f32_16x16x32_f16 v[92:95], v[202:205], v[206:209], v[198:201]
	s_nop 2
	ds_read_b128 v[198:201], v133 offset:16384
	v_mfma_f32_16x16x32_f16 v[158:161], v[210:213], v[206:209], v[158:161]
	v_mfma_f32_16x16x32_f16 v[166:169], v[202:205], v[220:223], v[166:169]
	v_mfma_f32_16x16x32_f16 v[68:71], v[202:205], v[228:231], v[68:71]
	ds_read_b128 v[202:205], v136 offset:49152
	v_mfma_f32_16x16x32_f16 v[190:193], v[210:213], v[220:223], v[190:193]
	v_mfma_f32_16x16x32_f16 v[76:79], v[210:213], v[228:231], v[76:79]
	ds_read_b128 v[210:213], v136 offset:51200
	v_mfma_f32_16x16x32_f16 v[162:165], v[224:227], v[206:209], v[162:165]
	v_mfma_f32_16x16x32_f16 v[72:75], v[232:235], v[206:209], v[72:75]
	ds_read_b128 v[206:209], v133 offset:18432
	v_mfma_f32_16x16x32_f16 v[194:197], v[224:227], v[220:223], v[194:197]
	v_and_b32_e32 v38, 7, v148
	v_bfe_u32 v39, v148, 4, 3
	v_xor_b32_e32 v39, v39, v38
	v_sub_u32_e32 v39, v39, v38
	v_lshlrev_b32_e32 v38, 4, v39
	v_add_u32_e32 v38, 0x600, v38
	v_ashrrev_i32_e32 v39, 31, v38
	v_mfma_f32_16x16x32_f16 v[84:87], v[224:227], v[228:231], v[84:87]
	ds_read_b128 v[224:227], v136 offset:53248
	v_mfma_f32_16x16x32_f16 v[80:83], v[232:235], v[220:223], v[80:83]
	ds_read_b128 v[220:223], v133 offset:20480
	v_mfma_f32_16x16x32_f16 v[88:91], v[232:235], v[228:231], v[88:91]
	ds_read_b128 v[228:231], v133 offset:22528
	s_waitcnt lgkmcnt(5)
	v_mfma_f32_16x16x32_f16 v[138:141], v[202:205], v[198:201], v[138:141]
	ds_read_b128 v[232:235], v136 offset:55296
	s_waitcnt lgkmcnt(4)
	v_mfma_f32_16x16x32_f16 v[92:95], v[202:205], v[206:209], v[92:95]
	v_mov_b32_e32 v52, v101
	v_and_b32_e32 v52, 0xffffff80, v52
	s_nop 0
	v_readfirstlane_b32 s101, v52
	v_lshl_add_u64 v[52:53], v[108:109], 0, v[38:39]
	s_mov_b32 m0, s101
	s_nop 0
	global_load_lds_dwordx4 v[52:53], off
	v_mfma_f32_16x16x32_f16 v[142:145], v[210:213], v[198:201], v[142:145]
	v_mov_b32_e32 v56, v131
	v_and_b32_e32 v56, 0xffffff80, v56
	s_nop 0
	v_readfirstlane_b32 s101, v56
	v_lshl_add_u64 v[56:57], v[110:111], 0, v[38:39]
	s_mov_b32 m0, s101
	s_nop 0
	global_load_lds_dwordx4 v[56:57], off
	v_mfma_f32_16x16x32_f16 v[158:161], v[210:213], v[206:209], v[158:161]
	v_mov_b32_e32 v60, v132
	v_and_b32_e32 v60, 0xffffff80, v60
	s_nop 0
	v_readfirstlane_b32 s101, v60
	v_lshl_add_u64 v[60:61], v[112:113], 0, v[38:39]
	s_mov_b32 m0, s101
	s_nop 0
	global_load_lds_dwordx4 v[60:61], off
	s_waitcnt lgkmcnt(2)
	v_mfma_f32_16x16x32_f16 v[166:169], v[202:205], v[220:223], v[166:169]
	v_mov_b32_e32 v40, v130
	v_and_b32_e32 v40, 0xffffff80, v40
	s_nop 0
	v_readfirstlane_b32 s101, v40
	v_lshl_add_u64 v[40:41], v[114:115], 0, v[38:39]
	s_mov_b32 m0, s101
	s_nop 0
	global_load_lds_dwordx4 v[40:41], off
	s_waitcnt lgkmcnt(1)
	v_mfma_f32_16x16x32_f16 v[68:71], v[202:205], v[228:231], v[68:71]
	ds_read_b128 v[202:205], v135 offset:49152
	v_mfma_f32_16x16x32_f16 v[190:193], v[210:213], v[220:223], v[190:193]
	v_add_u32_e32 v44, 0x8000, v101
	v_and_b32_e32 v44, 0xffffff80, v44
	s_nop 0
	v_readfirstlane_b32 s101, v44
	v_lshl_add_u64 v[44:45], v[116:117], 0, v[38:39]
	s_mov_b32 m0, s101
	s_nop 0
	global_load_lds_dwordx4 v[44:45], off
	v_mfma_f32_16x16x32_f16 v[76:79], v[210:213], v[228:231], v[76:79]
	ds_read_b128 v[210:213], v135 offset:51200
	v_mfma_f32_16x16x32_f16 v[154:157], v[224:227], v[198:201], v[154:157]
	v_add_u32_e32 v48, 0x8000, v131
	v_and_b32_e32 v48, 0xffffff80, v48
	s_nop 0
	v_readfirstlane_b32 s101, v48
	v_lshl_add_u64 v[48:49], v[118:119], 0, v[38:39]
	s_mov_b32 m0, s101
	s_nop 0
	global_load_lds_dwordx4 v[48:49], off
	v_mfma_f32_16x16x32_f16 v[162:165], v[224:227], v[206:209], v[162:165]
	v_add_u32_e32 v32, 0x8000, v132
	v_and_b32_e32 v32, 0xffffff80, v32
	s_nop 0
	v_readfirstlane_b32 s101, v32
	v_lshl_add_u64 v[32:33], v[120:121], 0, v[38:39]
	s_mov_b32 m0, s101
	s_nop 0
	global_load_lds_dwordx4 v[32:33], off
	s_waitcnt lgkmcnt(2)
	v_mfma_f32_16x16x32_f16 v[64:67], v[232:235], v[198:201], v[64:67]
	ds_read_b128 v[198:201], v134 offset:16384
	v_mfma_f32_16x16x32_f16 v[72:75], v[232:235], v[206:209], v[72:75]
	ds_read_b128 v[206:209], v134 offset:18432
	v_mfma_f32_16x16x32_f16 v[194:197], v[224:227], v[220:223], v[194:197]
	v_add_u32_e32 v36, 0x8000, v130
	v_and_b32_e32 v36, 0xffffff80, v36
	s_nop 0
	v_readfirstlane_b32 s101, v36
	v_lshl_add_u64 v[36:37], v[122:123], 0, v[38:39]
	s_mov_b32 m0, s101
	s_nop 0
	global_load_lds_dwordx4 v[36:37], off
	v_mfma_f32_16x16x32_f16 v[84:87], v[224:227], v[228:231], v[84:87]
	ds_read_b128 v[224:227], v135 offset:53248
	v_mfma_f32_16x16x32_f16 v[80:83], v[232:235], v[220:223], v[80:83]
	ds_read_b128 v[220:223], v134 offset:20480
	v_mfma_f32_16x16x32_f16 v[88:91], v[232:235], v[228:231], v[88:91]
	ds_read_b128 v[228:231], v134 offset:22528
	ds_read_b128 v[232:235], v135 offset:55296
	s_waitcnt vmcnt(0) lgkmcnt(0)
	s_barrier
; #define GL_LOAD(s_, kt_) if (VAR != 1) { a##s_##0 = GL_A(0, kt_); a##s_##1 = GL_A(1, kt_); a##s_##2 = GL_A(2, kt_); a##s_##3 = GL_A(3, kt_); b##s_##0 = GL_B(0, kt_); b##s_##1 = GL_B(1, kt_); b##s_##2 = GL_B(2, kt_); b##s_##3 = GL_B(3, kt_); }
; #define LDS_STORE(s_, buf_) if (VAR != 2) { LDS_ST1(sA, 0, buf_, a##s_##0) LDS_ST1(sA, 1, buf_, a##s_##1) LDS_ST1(sA, 2, buf_, a##s_##2) LDS_ST1(sA, 3, buf_, a##s_##3) LDS_ST1(sB, 0, buf_, b##s_##0) LDS_ST1(sB, 1, buf_, b##s_##1) LDS_ST1(sB, 2, buf_, b##s_##2) LDS_ST1(sB, 3, buf_, b##s_##3) }
;     ...
;   GL_LOAD(0, 0)
;   GL_LOAD(1, 1)
;   LDS_STORE(0, 0)
;   if (VAR != 4) __syncthreads();
; #pragma unroll
;   for (int kt = 0; kt < nk; kt += 2) {
;     if (kt + 2 < nk) { GL_LOAD(0, kt + 2) }
;     MMA_TILE(0)
;     LDS_STORE(1, 1)
;     if (VAR != 4) __syncthreads();
;     if (kt + 3 < nk) { GL_LOAD(1, kt + 3) }
;     MMA_TILE(1)
;     if (kt + 2 < nk) { LDS_STORE(0, 0) }
;     if (VAR != 4) __syncthreads();
	v_mfma_f32_16x16x32_f16 v[138:141], v[202:205], v[198:201], v[138:141]
	v_and_b32_e32 v6, 7, v148
	v_bfe_u32 v7, v148, 4, 3
	v_xor_b32_e32 v7, v7, v6
	v_sub_u32_e32 v7, v7, v6
	v_lshlrev_b32_e32 v6, 4, v7
	v_add_u32_e32 v6, 0x680, v6
	v_ashrrev_i32_e32 v7, 31, v6
	v_mfma_f32_16x16x32_f16 v[92:95], v[202:205], v[206:209], v[92:95]
	global_load_dwordx4 v[60:63], v[108:109], off offset:1792
	v_mfma_f32_16x16x32_f16 v[142:145], v[210:213], v[198:201], v[142:145]
	global_load_dwordx4 v[48:51], v[110:111], off offset:1792
	v_mfma_f32_16x16x32_f16 v[158:161], v[210:213], v[206:209], v[158:161]
	global_load_dwordx4 v[52:55], v[112:113], off offset:1792
	v_mfma_f32_16x16x32_f16 v[166:169], v[202:205], v[220:223], v[166:169]
	global_load_dwordx4 v[56:59], v[114:115], off offset:1792
	v_mfma_f32_16x16x32_f16 v[68:71], v[202:205], v[228:231], v[68:71]
	ds_read_b128 v[202:205], v136 offset:32768
	v_mfma_f32_16x16x32_f16 v[190:193], v[210:213], v[220:223], v[190:193]
	global_load_dwordx4 v[36:39], v[116:117], off offset:1792
	v_mfma_f32_16x16x32_f16 v[76:79], v[210:213], v[228:231], v[76:79]
	ds_read_b128 v[210:213], v136 offset:34816
	v_mfma_f32_16x16x32_f16 v[154:157], v[224:227], v[198:201], v[154:157]
	global_load_dwordx4 v[40:43], v[118:119], off offset:1792
	v_mfma_f32_16x16x32_f16 v[162:165], v[224:227], v[206:209], v[162:165]
	global_load_dwordx4 v[44:47], v[120:121], off offset:1792
	v_mfma_f32_16x16x32_f16 v[64:67], v[232:235], v[198:201], v[64:67]
	ds_read_b128 v[198:201], v133
	v_mfma_f32_16x16x32_f16 v[72:75], v[232:235], v[206:209], v[72:75]
	ds_read_b128 v[206:209], v133 offset:2048
	v_mfma_f32_16x16x32_f16 v[194:197], v[224:227], v[220:223], v[194:197]
	global_load_dwordx4 v[32:35], v[122:123], off offset:1792
	v_mfma_f32_16x16x32_f16 v[84:87], v[224:227], v[228:231], v[84:87]
	ds_read_b128 v[224:227], v136 offset:36864
	v_mfma_f32_16x16x32_f16 v[80:83], v[232:235], v[220:223], v[80:83]
	ds_read_b128 v[220:223], v133 offset:4096
	v_mfma_f32_16x16x32_f16 v[88:91], v[232:235], v[228:231], v[88:91]
	ds_read_b128 v[228:231], v133 offset:6144
	s_waitcnt lgkmcnt(4)
	v_mfma_f32_16x16x32_f16 v[138:141], v[202:205], v[198:201], v[138:141]
	ds_read_b128 v[232:235], v136 offset:38912
	s_waitcnt lgkmcnt(4)
	v_mfma_f32_16x16x32_f16 v[92:95], v[202:205], v[206:209], v[92:95]
	v_add_u32_e32 v20, 0x4000, v101
	v_and_b32_e32 v20, 0xffffff80, v20
	s_nop 0
	v_readfirstlane_b32 s101, v20
	v_lshl_add_u64 v[20:21], v[108:109], 0, v[6:7]
	s_mov_b32 m0, s101
	s_nop 0
	global_load_lds_dwordx4 v[20:21], off
	v_mfma_f32_16x16x32_f16 v[142:145], v[210:213], v[198:201], v[142:145]
	v_add_u32_e32 v24, 0x4000, v131
	v_and_b32_e32 v24, 0xffffff80, v24
	s_nop 0
	v_readfirstlane_b32 s101, v24
	v_lshl_add_u64 v[24:25], v[110:111], 0, v[6:7]
	s_mov_b32 m0, s101
	s_nop 0
	global_load_lds_dwordx4 v[24:25], off
	v_mfma_f32_16x16x32_f16 v[158:161], v[210:213], v[206:209], v[158:161]
	v_add_u32_e32 v28, 0x4000, v132
	v_and_b32_e32 v28, 0xffffff80, v28
	s_nop 0
	v_readfirstlane_b32 s101, v28
	v_lshl_add_u64 v[28:29], v[112:113], 0, v[6:7]
	s_mov_b32 m0, s101
	s_nop 0
	global_load_lds_dwordx4 v[28:29], off
	s_waitcnt lgkmcnt(2)
	v_mfma_f32_16x16x32_f16 v[166:169], v[202:205], v[220:223], v[166:169]
	v_add_u32_e32 v8, 0x4000, v130
	v_and_b32_e32 v8, 0xffffff80, v8
	s_nop 0
	v_readfirstlane_b32 s101, v8
	v_lshl_add_u64 v[8:9], v[114:115], 0, v[6:7]
	s_mov_b32 m0, s101
	s_nop 0
	global_load_lds_dwordx4 v[8:9], off
	s_waitcnt lgkmcnt(1)
	v_mfma_f32_16x16x32_f16 v[68:71], v[202:205], v[228:231], v[68:71]
	ds_read_b128 v[202:205], v135 offset:32768
	v_mfma_f32_16x16x32_f16 v[190:193], v[210:213], v[220:223], v[190:193]
	v_add_u32_e32 v12, 0xc000, v101
	v_and_b32_e32 v12, 0xffffff80, v12
	s_nop 0
	v_readfirstlane_b32 s101, v12
	v_lshl_add_u64 v[12:13], v[116:117], 0, v[6:7]
	s_mov_b32 m0, s101
	s_nop 0
	global_load_lds_dwordx4 v[12:13], off
	v_mfma_f32_16x16x32_f16 v[76:79], v[210:213], v[228:231], v[76:79]
	ds_read_b128 v[210:213], v135 offset:34816
	v_mfma_f32_16x16x32_f16 v[154:157], v[224:227], v[198:201], v[154:157]
	v_add_u32_e32 v16, 0xc000, v131
	v_and_b32_e32 v16, 0xffffff80, v16
	s_nop 0
	v_readfirstlane_b32 s101, v16
	v_lshl_add_u64 v[16:17], v[118:119], 0, v[6:7]
	s_mov_b32 m0, s101
	s_nop 0
	global_load_lds_dwordx4 v[16:17], off
	v_mfma_f32_16x16x32_f16 v[162:165], v[224:227], v[206:209], v[162:165]
	v_add_u32_e32 v0, 0xc000, v132
	v_and_b32_e32 v0, 0xffffff80, v0
	s_nop 0
	v_readfirstlane_b32 s101, v0
	v_lshl_add_u64 v[0:1], v[120:121], 0, v[6:7]
	s_mov_b32 m0, s101
	s_nop 0
	global_load_lds_dwordx4 v[0:1], off
	s_waitcnt lgkmcnt(2)
	v_mfma_f32_16x16x32_f16 v[64:67], v[232:235], v[198:201], v[64:67]
	ds_read_b128 v[198:201], v134
	v_mfma_f32_16x16x32_f16 v[72:75], v[232:235], v[206:209], v[72:75]
	ds_read_b128 v[206:209], v134 offset:2048
	v_mfma_f32_16x16x32_f16 v[194:197], v[224:227], v[220:223], v[194:197]
	v_add_u32_e32 v4, 0xc000, v130
	v_and_b32_e32 v4, 0xffffff80, v4
	s_nop 0
	v_readfirstlane_b32 s101, v4
	v_lshl_add_u64 v[4:5], v[122:123], 0, v[6:7]
	s_mov_b32 m0, s101
	s_nop 0
	global_load_lds_dwordx4 v[4:5], off
	v_mfma_f32_16x16x32_f16 v[84:87], v[224:227], v[228:231], v[84:87]
	ds_read_b128 v[224:227], v135 offset:36864
	v_mfma_f32_16x16x32_f16 v[80:83], v[232:235], v[220:223], v[80:83]
	ds_read_b128 v[220:223], v134 offset:4096
	v_mfma_f32_16x16x32_f16 v[88:91], v[232:235], v[228:231], v[88:91]
	ds_read_b128 v[228:231], v134 offset:6144
	ds_read_b128 v[232:235], v135 offset:38912
	s_waitcnt vmcnt(0) lgkmcnt(0)
	s_barrier
; #define GL_LOAD(s_, kt_) if (VAR != 1) { a##s_##0 = GL_A(0, kt_); a##s_##1 = GL_A(1, kt_); a##s_##2 = GL_A(2, kt_); a##s_##3 = GL_A(3, kt_); b##s_##0 = GL_B(0, kt_); b##s_##1 = GL_B(1, kt_); b##s_##2 = GL_B(2, kt_); b##s_##3 = GL_B(3, kt_); }
; #define LDS_STORE(s_, buf_) if (VAR != 2) { LDS_ST1(sA, 0, buf_, a##s_##0) LDS_ST1(sA, 1, buf_, a##s_##1) LDS_ST1(sA, 2, buf_, a##s_##2) LDS_ST1(sA, 3, buf_, a##s_##3) LDS_ST1(sB, 0, buf_, b##s_##0) LDS_ST1(sB, 1, buf_, b##s_##1) LDS_ST1(sB, 2, buf_, b##s_##2) LDS_ST1(sB, 3, buf_, b##s_##3) }
;     ...
;   GL_LOAD(0, 0)
;   GL_LOAD(1, 1)
;   LDS_STORE(0, 0)
;   if (VAR != 4) __syncthreads();
; #pragma unroll
;   for (int kt = 0; kt < nk; kt += 2) {
;     if (kt + 2 < nk) { GL_LOAD(0, kt + 2) }
;     MMA_TILE(0)
;     LDS_STORE(1, 1)
;     if (VAR != 4) __syncthreads();
;     if (kt + 3 < nk) { GL_LOAD(1, kt + 3) }
;     MMA_TILE(1)
;     if (kt + 2 < nk) { LDS_STORE(0, 0) }
;     if (VAR != 4) __syncthreads();
	v_mfma_f32_16x16x32_f16 v[138:141], v[202:205], v[198:201], v[138:141]
	global_load_dwordx4 v[28:31], v[108:109], off offset:1920
	v_mfma_f32_16x16x32_f16 v[92:95], v[202:205], v[206:209], v[92:95]
	global_load_dwordx4 v[16:19], v[110:111], off offset:1920
	v_mfma_f32_16x16x32_f16 v[142:145], v[210:213], v[198:201], v[142:145]
	ds_read_b128 v[108:111], v133 offset:16384
	v_mfma_f32_16x16x32_f16 v[158:161], v[210:213], v[206:209], v[158:161]
	global_load_dwordx4 v[20:23], v[112:113], off offset:1920
	v_mfma_f32_16x16x32_f16 v[166:169], v[202:205], v[220:223], v[166:169]
	global_load_dwordx4 v[24:27], v[114:115], off offset:1920
	v_mfma_f32_16x16x32_f16 v[68:71], v[202:205], v[228:231], v[68:71]
	ds_read_b128 v[112:115], v136 offset:49152
	v_mfma_f32_16x16x32_f16 v[190:193], v[210:213], v[220:223], v[190:193]
	ds_read_b128 v[202:205], v136 offset:53248
	v_mfma_f32_16x16x32_f16 v[76:79], v[210:213], v[228:231], v[76:79]
	ds_read_b128 v[210:213], v136 offset:55296
	v_mfma_f32_16x16x32_f16 v[154:157], v[224:227], v[198:201], v[154:157]
	global_load_dwordx4 v[4:7], v[116:117], off offset:1920
	v_mfma_f32_16x16x32_f16 v[162:165], v[224:227], v[206:209], v[162:165]
	global_load_dwordx4 v[8:11], v[118:119], off offset:1920
	v_mfma_f32_16x16x32_f16 v[64:67], v[232:235], v[198:201], v[64:67]
	ds_read_b128 v[116:119], v133 offset:18432
	v_mfma_f32_16x16x32_f16 v[72:75], v[232:235], v[206:209], v[72:75]
	ds_read_b128 v[198:201], v133 offset:20480
	v_mfma_f32_16x16x32_f16 v[194:197], v[224:227], v[220:223], v[194:197]
	ds_read_b128 v[206:209], v133 offset:22528
	v_mfma_f32_16x16x32_f16 v[84:87], v[224:227], v[228:231], v[84:87]
	global_load_dwordx4 v[12:15], v[120:121], off offset:1920
	v_mfma_f32_16x16x32_f16 v[80:83], v[232:235], v[220:223], v[80:83]
	global_load_dwordx4 v[0:3], v[122:123], off offset:1920
	v_mfma_f32_16x16x32_f16 v[88:91], v[232:235], v[228:231], v[88:91]
	ds_read_b128 v[120:123], v136 offset:51200
	s_waitcnt lgkmcnt(6)
	v_mfma_f32_16x16x32_f16 v[138:141], v[112:115], v[108:111], v[138:141]
	ds_write_b128 v101, v[60:63]
	s_waitcnt lgkmcnt(4)
	v_mfma_f32_16x16x32_f16 v[92:95], v[112:115], v[116:119], v[92:95]
	ds_write_b128 v131, v[48:51]
	s_waitcnt lgkmcnt(2)
	v_mfma_f32_16x16x32_f16 v[142:145], v[120:123], v[108:111], v[142:145]
	ds_write_b128 v132, v[52:55]
	v_mfma_f32_16x16x32_f16 v[154:157], v[202:205], v[108:111], v[154:157]
	v_mfma_f32_16x16x32_f16 v[64:67], v[210:213], v[108:111], v[64:67]
	v_mfma_f32_16x16x32_f16 v[108:111], v[120:123], v[116:119], v[158:161]
	ds_write_b128 v130, v[56:59]
	v_mfma_f32_16x16x32_f16 v[158:161], v[202:205], v[116:119], v[162:165]
	v_mfma_f32_16x16x32_f16 v[72:75], v[210:213], v[116:119], v[72:75]
	v_mfma_f32_16x16x32_f16 v[116:119], v[112:115], v[198:201], v[166:169]
	ds_write_b128 v101, v[36:39] offset:32768
	ds_write_b128 v131, v[40:43] offset:32768
	v_mfma_f32_16x16x32_f16 v[68:71], v[112:115], v[206:209], v[68:71]
	ds_read_b128 v[112:115], v134 offset:16384
	ds_write_b128 v132, v[44:47] offset:32768
	v_mfma_f32_16x16x32_f16 v[162:165], v[120:123], v[198:201], v[190:193]
	s_nop 2
	ds_read_b128 v[190:193], v134 offset:18432
	v_mfma_f32_16x16x32_f16 v[76:79], v[120:123], v[206:209], v[76:79]
	ds_read_b128 v[120:123], v135 offset:49152
	ds_write_b128 v130, v[32:35] offset:32768
	v_mfma_f32_16x16x32_f16 v[166:169], v[202:205], v[198:201], v[194:197]
	s_nop 2
	ds_read_b128 v[194:197], v135 offset:51200
	v_mfma_f32_16x16x32_f16 v[84:87], v[202:205], v[206:209], v[84:87]
	ds_read_b128 v[202:205], v135 offset:53248
	v_mfma_f32_16x16x32_f16 v[80:83], v[210:213], v[198:201], v[80:83]
	ds_read_b128 v[198:201], v134 offset:20480
	v_mfma_f32_16x16x32_f16 v[88:91], v[210:213], v[206:209], v[88:91]
	ds_read_b128 v[206:209], v134 offset:22528
	s_waitcnt lgkmcnt(5)
	v_mfma_f32_16x16x32_f16 v[138:141], v[120:123], v[112:115], v[138:141]
	ds_read_b128 v[210:213], v135 offset:55296
	s_waitcnt lgkmcnt(0)
	s_barrier
	v_mfma_f32_16x16x32_f16 v[142:145], v[194:197], v[112:115], v[142:145]
	ds_read_b128 v[32:35], v133
	v_mfma_f32_16x16x32_f16 v[108:111], v[194:197], v[190:193], v[108:111]
	ds_read_b128 v[36:39], v136 offset:32768
	v_mfma_f32_16x16x32_f16 v[154:157], v[202:205], v[112:115], v[154:157]
	ds_read_b128 v[40:43], v133 offset:2048
	v_mfma_f32_16x16x32_f16 v[64:67], v[210:213], v[112:115], v[64:67]
	v_mfma_f32_16x16x32_f16 v[112:115], v[202:205], v[190:193], v[158:161]
	ds_read_b128 v[44:47], v136 offset:34816
	v_mfma_f32_16x16x32_f16 v[158:161], v[194:197], v[198:201], v[162:165]
	ds_read_b128 v[48:51], v133 offset:4096
	v_mfma_f32_16x16x32_f16 v[76:79], v[194:197], v[206:209], v[76:79]
	ds_read_b128 v[52:55], v136 offset:36864
	v_mfma_f32_16x16x32_f16 v[162:165], v[202:205], v[198:201], v[166:169]
	ds_read_b128 v[56:59], v133 offset:6144
	v_mfma_f32_16x16x32_f16 v[84:87], v[202:205], v[206:209], v[84:87]
	ds_read_b128 v[60:63], v136 offset:38912
	v_mfma_f32_16x16x32_f16 v[72:75], v[210:213], v[190:193], v[72:75]
	v_mfma_f32_16x16x32_f16 v[92:95], v[120:123], v[190:193], v[92:95]
	v_mfma_f32_16x16x32_f16 v[80:83], v[210:213], v[198:201], v[80:83]
	v_mfma_f32_16x16x32_f16 v[88:91], v[210:213], v[206:209], v[88:91]
	v_mfma_f32_16x16x32_f16 v[116:119], v[120:123], v[198:201], v[116:119]
	s_waitcnt vmcnt(7)
	ds_write_b128 v101, v[28:31] offset:16384
	v_mfma_f32_16x16x32_f16 v[68:71], v[120:123], v[206:209], v[68:71]
	s_waitcnt vmcnt(6)
	ds_write_b128 v131, v[16:19] offset:16384
	s_waitcnt lgkmcnt(8)
	v_mfma_f32_16x16x32_f16 v[120:123], v[36:39], v[32:35], v[138:141]
	s_waitcnt vmcnt(5)
	ds_write_b128 v132, v[20:23] offset:16384
	s_waitcnt lgkmcnt(7)
	v_mfma_f32_16x16x32_f16 v[138:141], v[44:47], v[32:35], v[142:145]
	s_waitcnt lgkmcnt(5)
; #define GL_LOAD(s_, kt_) if (VAR != 1) { a##s_##0 = GL_A(0, kt_); a##s_##1 = GL_A(1, kt_); a##s_##2 = GL_A(2, kt_); a##s_##3 = GL_A(3, kt_); b##s_##0 = GL_B(0, kt_); b##s_##1 = GL_B(1, kt_); b##s_##2 = GL_B(2, kt_); b##s_##3 = GL_B(3, kt_); }
; #define LDS_STORE(s_, buf_) if (VAR != 2) { LDS_ST1(sA, 0, buf_, a##s_##0) LDS_ST1(sA, 1, buf_, a##s_##1) LDS_ST1(sA, 2, buf_, a##s_##2) LDS_ST1(sA, 3, buf_, a##s_##3) LDS_ST1(sB, 0, buf_, b##s_##0) LDS_ST1(sB, 1, buf_, b##s_##1) LDS_ST1(sB, 2, buf_, b##s_##2) LDS_ST1(sB, 3, buf_, b##s_##3) }
;     ...
;   GL_LOAD(0, 0)
;   GL_LOAD(1, 1)
;   LDS_STORE(0, 0)
;   if (VAR != 4) __syncthreads();
; #pragma unroll
;   for (int kt = 0; kt < nk; kt += 2) {
;     if (kt + 2 < nk) { GL_LOAD(0, kt + 2) }
;     MMA_TILE(0)
;     LDS_STORE(1, 1)
;     if (VAR != 4) __syncthreads();
;     if (kt + 3 < nk) { GL_LOAD(1, kt + 3) }
;     MMA_TILE(1)
;     if (kt + 2 < nk) { LDS_STORE(0, 0) }
;     if (VAR != 4) __syncthreads();
	v_mfma_f32_16x16x32_f16 v[142:145], v[52:55], v[32:35], v[154:157]
	s_waitcnt lgkmcnt(3)
	v_mfma_f32_16x16x32_f16 v[32:35], v[60:63], v[32:35], v[64:67]
	v_mfma_f32_16x16x32_f16 v[64:67], v[36:39], v[40:43], v[92:95]
	ds_read_b128 v[154:157], v134 offset:6144
	s_waitcnt vmcnt(4)
	ds_write_b128 v130, v[24:27] offset:16384
	v_mfma_f32_16x16x32_f16 v[92:95], v[44:47], v[40:43], v[108:111]
	s_waitcnt vmcnt(3)
	ds_write_b128 v101, v[4:7] offset:49152
	v_mfma_f32_16x16x32_f16 v[108:111], v[52:55], v[40:43], v[112:115]
	v_mfma_f32_16x16x32_f16 v[40:43], v[60:63], v[40:43], v[72:75]
	v_mfma_f32_16x16x32_f16 v[72:75], v[36:39], v[48:51], v[116:119]
	s_waitcnt vmcnt(2)
	ds_write_b128 v131, v[8:11] offset:49152
	v_mfma_f32_16x16x32_f16 v[36:39], v[36:39], v[56:59], v[68:71]
	s_nop 2
	ds_read_b128 v[68:71], v135 offset:32768
	v_mfma_f32_16x16x32_f16 v[112:115], v[44:47], v[48:51], v[158:161]
	s_nop 2
	ds_read_b128 v[158:161], v135 offset:38912
	v_mfma_f32_16x16x32_f16 v[44:47], v[44:47], v[56:59], v[76:79]
	s_nop 2
	ds_read_b128 v[76:79], v134 offset:2048
	s_waitcnt vmcnt(1)
	ds_write_b128 v132, v[12:15] offset:49152
	s_waitcnt vmcnt(0)
	ds_write_b128 v130, v[0:3] offset:49152
	v_mfma_f32_16x16x32_f16 v[116:119], v[52:55], v[48:51], v[162:165]
	v_mfma_f32_16x16x32_f16 v[52:55], v[52:55], v[56:59], v[84:87]
	s_nop 2
	ds_read_b128 v[84:87], v134 offset:4096
	v_mfma_f32_16x16x32_f16 v[48:51], v[60:63], v[48:51], v[80:83]
	s_nop 2
	ds_read_b128 v[80:83], v135 offset:34816
	v_mfma_f32_16x16x32_f16 v[56:59], v[60:63], v[56:59], v[88:91]
	ds_read_b128 v[60:63], v134
	s_waitcnt lgkmcnt(0)
	v_mfma_f32_16x16x32_f16 v[120:123], v[68:71], v[60:63], v[120:123]
	ds_read_b128 v[88:91], v135 offset:36864
	s_waitcnt lgkmcnt(0)
	s_barrier
	v_mfma_f32_16x16x32_f16 v[138:141], v[80:83], v[60:63], v[138:141]
	ds_read_b128 v[0:3], v133 offset:16384
	v_mfma_f32_16x16x32_f16 v[142:145], v[88:91], v[60:63], v[142:145]
	v_mfma_f32_16x16x32_f16 v[32:35], v[158:161], v[60:63], v[32:35]
	v_mfma_f32_16x16x32_f16 v[60:63], v[68:71], v[76:79], v[64:67]
	v_mfma_f32_16x16x32_f16 v[64:67], v[80:83], v[76:79], v[92:95]
	ds_read_b128 v[4:7], v136 offset:49152
	ds_read_b128 v[8:11], v133 offset:18432
	v_mfma_f32_16x16x32_f16 v[92:95], v[88:91], v[76:79], v[108:111]
	ds_read_b128 v[12:15], v136 offset:51200
	v_mfma_f32_16x16x32_f16 v[40:43], v[158:161], v[76:79], v[40:43]
	v_mfma_f32_16x16x32_f16 v[76:79], v[80:83], v[84:87], v[112:115]
	ds_read_b128 v[16:19], v133 offset:20480
	v_mfma_f32_16x16x32_f16 v[44:47], v[80:83], v[154:157], v[44:47]
	ds_read_b128 v[20:23], v136 offset:53248
	v_mfma_f32_16x16x32_f16 v[108:111], v[88:91], v[84:87], v[116:119]
	ds_read_b128 v[24:27], v133 offset:22528
	v_mfma_f32_16x16x32_f16 v[52:55], v[88:91], v[154:157], v[52:55]
	ds_read_b128 v[28:31], v136 offset:55296
	ds_read_b128 v[112:115], v135 offset:53248
	ds_read_b128 v[116:119], v134 offset:22528
	v_ashrrev_i32_e32 v101, 31, v100
	v_mfma_f32_16x16x32_f16 v[48:51], v[158:161], v[84:87], v[48:51]
	v_mfma_f32_16x16x32_f16 v[56:59], v[158:161], v[154:157], v[56:59]
	v_mfma_f32_16x16x32_f16 v[72:75], v[68:71], v[84:87], v[72:75]
	v_mfma_f32_16x16x32_f16 v[36:39], v[68:71], v[154:157], v[36:39]
	s_waitcnt lgkmcnt(8)
	v_mfma_f32_16x16x32_f16 v[68:71], v[4:7], v[0:3], v[120:123]
	s_nop 2
	ds_read_b128 v[120:123], v135 offset:55296
	s_waitcnt lgkmcnt(7)
	v_mfma_f32_16x16x32_f16 v[80:83], v[12:15], v[0:3], v[138:141]
	s_waitcnt lgkmcnt(5)
	v_mfma_f32_16x16x32_f16 v[84:87], v[20:23], v[0:3], v[142:145]
	s_waitcnt lgkmcnt(3)
	v_mfma_f32_16x16x32_f16 v[0:3], v[28:31], v[0:3], v[32:35]
	v_mfma_f32_16x16x32_f16 v[32:35], v[4:7], v[8:11], v[60:63]
	v_mfma_f32_16x16x32_f16 v[60:63], v[12:15], v[8:11], v[64:67]
	v_mfma_f32_16x16x32_f16 v[72:75], v[4:7], v[16:19], v[72:75]
	v_mfma_f32_16x16x32_f16 v[76:79], v[12:15], v[16:19], v[76:79]
	v_mfma_f32_16x16x32_f16 v[44:47], v[12:15], v[24:27], v[44:47]
	ds_read_b128 v[12:15], v134 offset:16384
	v_mfma_f32_16x16x32_f16 v[64:67], v[20:23], v[8:11], v[92:95]
	s_nop 2
	ds_read_b128 v[92:95], v135 offset:51200
	v_mfma_f32_16x16x32_f16 v[88:91], v[20:23], v[16:19], v[108:111]
	s_nop 2
	ds_read_b128 v[108:111], v134 offset:20480
	v_mfma_f32_16x16x32_f16 v[16:19], v[28:31], v[16:19], v[48:51]
	v_mfma_f32_16x16x32_f16 v[48:51], v[20:23], v[24:27], v[52:55]
	ds_read_b128 v[20:23], v134 offset:18432
	v_mfma_f32_16x16x32_f16 v[52:55], v[28:31], v[24:27], v[56:59]
	s_nop 2
	ds_read_b128 v[56:59], v135 offset:49152
	s_waitcnt lgkmcnt(0)
	s_barrier
; DI unsigned pack2(float lo, float hi) { f2_t v = {lo, hi}; h2_t b = __builtin_convertvector(v, h2_t); return __builtin_bit_cast(unsigned, b); }
; template <int VAR> DI void phase_up(const Params& P, int l, char* smem) {
;     ...
;     gemm_kloop<false, true, 16, VAR>(acc, xb + (size_t)m0 * DM, DM, Wt + (size_t)n0 * DM, DM, smem);
; #pragma unroll
;     for (int mt = 0; mt < 4; ++mt) {
;       const int row = row0 + mt * 16 + lr;
; #pragma unroll
;       for (int nt = 0; nt < 4; ++nt) {
;         float v[4];
; #pragma unroll
;         for (int j = 0; j < 4; ++j) { const float a = fmaxf(acc[mt][nt][j] * rs[mt], 0.f); v[j] = a * a; }
;         *(uint2*)(U + (size_t)row * DFF + col0 + nt * 16 + 4 * g) = make_uint2(pack2(v[0], v[1]), pack2(v[2], v[3]));
;       }
	s_setprio 0
	v_mfma_f32_16x16x32_f16 v[4:7], v[4:7], v[24:27], v[36:39]
	v_mfma_f32_16x16x32_f16 v[68:71], v[56:59], v[12:15], v[68:71]
	v_mfma_f32_16x16x32_f16 v[8:11], v[28:31], v[8:11], v[40:43]
	v_mfma_f32_16x16x32_f16 v[80:83], v[92:95], v[12:15], v[80:83]
	v_mfma_f32_16x16x32_f16 v[84:87], v[112:115], v[12:15], v[84:87]
	v_mfma_f32_16x16x32_f16 v[130:133], v[120:123], v[12:15], v[0:3]
	v_mfma_f32_16x16x32_f16 v[12:15], v[56:59], v[116:119], v[4:7]
	v_mfma_f32_16x16x32_f16 v[4:7], v[112:115], v[116:119], v[48:51]
	s_nop 2
	v_mul_f32_e32 v48, v128, v68
	v_mul_f32_e32 v49, v128, v69
	v_mul_f32_e32 v50, v128, v70
	v_mul_f32_e32 v51, v128, v71
	v_max_f32_e32 v48, 0, v48
	v_max_f32_e32 v49, 0, v49
	v_max_f32_e32 v50, 0, v50
	v_max_f32_e32 v51, 0, v51
	v_mfma_f32_16x16x32_f16 v[134:137], v[56:59], v[20:23], v[32:35]
	v_mul_f32_e64 v48, v48, v48
	v_mul_f32_e64 v49, v49, v49
	v_pk_mul_f32 v[50:51], v[50:51], v[50:51]
	v_cvt_pk_f16_f32 v48, v48, v49
	v_mfma_f32_16x16x32_f16 v[32:35], v[120:123], v[20:23], v[8:11]
	v_cvt_pk_f16_f32 v49, v50, v51
	v_mul_f32_e32 v50, v128, v82
	v_mul_f32_e32 v51, v128, v83
	v_mfma_f32_16x16x32_f16 v[8:11], v[92:95], v[116:119], v[44:47]
	v_max_f32_e32 v50, 0, v50
	v_max_f32_e32 v51, 0, v51
	v_pk_mul_f32 v[50:51], v[50:51], v[50:51]
	v_lshl_add_u64 v[44:45], v[100:101], 1, v[96:97]
	v_lshlrev_b64 v[46:47], 13, v[102:103]
	v_lshl_add_u64 v[46:47], v[44:45], 0, v[46:47]
	global_store_dwordx2 v[46:47], v[48:49], off
	v_mul_f32_e32 v48, v128, v80
	v_mul_f32_e32 v49, v128, v81
	v_max_f32_e32 v48, 0, v48
	v_max_f32_e32 v49, 0, v49
	v_pk_mul_f32 v[48:49], v[48:49], v[48:49]
	v_mfma_f32_16x16x32_f16 v[16:19], v[120:123], v[108:111], v[16:19]
	v_cvt_pk_f16_f32 v48, v48, v49
	v_cvt_pk_f16_f32 v49, v50, v51
	global_store_dwordx2 v[46:47], v[48:49], off offset:32
	v_mul_f32_e32 v48, v128, v84
	v_mul_f32_e32 v49, v128, v85
	v_mul_f32_e32 v50, v128, v86
	v_mul_f32_e32 v51, v128, v87
	v_max_f32_e32 v48, 0, v48
	v_max_f32_e32 v49, 0, v49
	v_max_f32_e32 v50, 0, v50
	v_max_f32_e32 v51, 0, v51
	v_pk_mul_f32 v[48:49], v[48:49], v[48:49]
	v_pk_mul_f32 v[50:51], v[50:51], v[50:51]
	v_cvt_pk_f16_f32 v48, v48, v49
	v_cvt_pk_f16_f32 v49, v50, v51
	global_store_dwordx2 v[46:47], v[48:49], off offset:64
	v_mul_f32_e32 v48, v128, v130
	v_mul_f32_e32 v49, v128, v131
	v_mul_f32_e32 v50, v128, v132
	v_mul_f32_e32 v51, v128, v133
	v_max_f32_e32 v48, 0, v48
	v_max_f32_e32 v49, 0, v49
	v_max_f32_e32 v50, 0, v50
	v_max_f32_e32 v51, 0, v51
	v_mfma_f32_16x16x32_f16 v[40:43], v[92:95], v[20:23], v[60:63]
	v_mul_f32_e64 v48, v48, v48
	v_mul_f32_e64 v49, v49, v49
	v_pk_mul_f32 v[50:51], v[50:51], v[50:51]
	v_mul_f32_e32 v32, v126, v32
	v_mfma_f32_16x16x32_f16 v[36:39], v[112:115], v[20:23], v[64:67]
	v_mul_f32_e32 v33, v126, v33
	v_mul_f32_e32 v34, v126, v34
	v_mul_f32_e32 v35, v126, v35
	v_mfma_f32_16x16x32_f16 v[28:31], v[56:59], v[108:111], v[72:75]
	v_cvt_pk_f16_f32 v48, v48, v49
	v_cvt_pk_f16_f32 v49, v50, v51
	v_max_f32_e32 v32, 0, v32
	v_mfma_f32_16x16x32_f16 v[24:27], v[92:95], v[108:111], v[76:79]
	v_max_f32_e32 v33, 0, v33
	v_max_f32_e32 v34, 0, v34
	v_max_f32_e32 v35, 0, v35
	v_mfma_f32_16x16x32_f16 v[20:23], v[112:115], v[108:111], v[88:91]
	global_store_dwordx2 v[46:47], v[48:49], off offset:96
	v_lshlrev_b64 v[46:47], 13, v[98:99]
	v_pk_mul_f32 v[32:33], v[32:33], v[32:33]
	v_mfma_f32_16x16x32_f16 v[0:3], v[120:123], v[116:119], v[52:55]
	v_mul_f32_e64 v34, v34, v34
	v_mul_f32_e64 v35, v35, v35
	v_mul_f32_e32 v16, v129, v16
	v_mul_f32_e32 v17, v129, v17
	v_mul_f32_e32 v18, v129, v18
	v_mul_f32_e32 v19, v129, v19
	v_lshl_add_u64 v[46:47], v[44:45], 0, v[46:47]
	v_cvt_pk_f16_f32 v32, v32, v33
	v_cvt_pk_f16_f32 v33, v34, v35
	v_max_f32_e32 v16, 0, v16
	v_max_f32_e32 v17, 0, v17
	v_max_f32_e32 v18, 0, v18
	v_max_f32_e32 v19, 0, v19
	v_mul_f32_e32 v48, v126, v134
	v_mul_f32_e32 v49, v126, v135
	v_mul_f32_e32 v50, v126, v136
	v_mul_f32_e32 v51, v126, v137
	v_mul_f32_e32 v40, v126, v40
	v_mul_f32_e32 v41, v126, v41
	v_mul_f32_e32 v42, v126, v42
	v_mul_f32_e32 v43, v126, v43
	v_mul_f32_e32 v36, v126, v36
	v_mul_f32_e32 v37, v126, v37
	v_mul_f32_e32 v38, v126, v38
	v_mul_f32_e32 v39, v126, v39
	global_store_dwordx2 v[46:47], v[32:33], off offset:96
	v_lshlrev_b64 v[32:33], 13, v[106:107]
; DI unsigned pack2(float lo, float hi) { f2_t v = {lo, hi}; h2_t b = __builtin_convertvector(v, h2_t); return __builtin_bit_cast(unsigned, b); }
; template <int VAR> DI void phase_up(const Params& P, int l, char* smem) {
;     ...
; #pragma unroll
;     for (int mt = 0; mt < 4; ++mt) {
;       const int row = row0 + mt * 16 + lr;
; #pragma unroll
;       for (int nt = 0; nt < 4; ++nt) {
;         float v[4];
; #pragma unroll
;         for (int j = 0; j < 4; ++j) { const float a = fmaxf(acc[mt][nt][j] * rs[mt], 0.f); v[j] = a * a; }
;         *(uint2*)(U + (size_t)row * DFF + col0 + nt * 16 + 4 * g) = make_uint2(pack2(v[0], v[1]), pack2(v[2], v[3]));
;       }
	v_mul_f32_e32 v28, v129, v28
	v_mul_f32_e32 v29, v129, v29
	v_mul_f32_e32 v30, v129, v30
	v_mul_f32_e32 v31, v129, v31
	v_mul_f32_e32 v24, v129, v24
	v_mul_f32_e32 v25, v129, v25
	v_mul_f32_e32 v26, v129, v26
	v_mul_f32_e32 v27, v129, v27
	v_mul_f32_e32 v20, v129, v20
	v_mul_f32_e32 v21, v129, v21
	v_mul_f32_e32 v22, v129, v22
	v_mul_f32_e32 v23, v129, v23
	v_pk_mul_f32 v[16:17], v[16:17], v[16:17]
	v_pk_mul_f32 v[18:19], v[18:19], v[18:19]
	v_mul_f32_e32 v12, v127, v12
	v_mul_f32_e32 v13, v127, v13
	v_mul_f32_e32 v14, v127, v14
	v_mul_f32_e32 v15, v127, v15
	v_mul_f32_e32 v8, v127, v8
	v_mul_f32_e32 v9, v127, v9
	v_mul_f32_e32 v10, v127, v10
	v_mul_f32_e32 v11, v127, v11
	v_mul_f32_e32 v4, v127, v4
	v_mul_f32_e32 v5, v127, v5
	v_mul_f32_e32 v6, v127, v6
	v_mul_f32_e32 v7, v127, v7
	v_mul_f32_e32 v0, v127, v0
	v_mul_f32_e32 v1, v127, v1
	v_mul_f32_e32 v2, v127, v2
	v_mul_f32_e32 v3, v127, v3
	v_max_f32_e32 v48, 0, v48
	v_max_f32_e32 v49, 0, v49
	v_max_f32_e32 v50, 0, v50
	v_max_f32_e32 v51, 0, v51
	v_max_f32_e32 v40, 0, v40
	v_max_f32_e32 v41, 0, v41
	v_max_f32_e32 v42, 0, v42
	v_max_f32_e32 v43, 0, v43
	v_max_f32_e32 v36, 0, v36
	v_max_f32_e32 v37, 0, v37
	v_max_f32_e32 v38, 0, v38
	v_max_f32_e32 v39, 0, v39
	v_lshl_add_u64 v[32:33], v[44:45], 0, v[32:33]
	v_max_f32_e32 v28, 0, v28
	v_max_f32_e32 v29, 0, v29
	v_max_f32_e32 v30, 0, v30
	v_max_f32_e32 v31, 0, v31
	v_max_f32_e32 v24, 0, v24
	v_max_f32_e32 v25, 0, v25
	v_max_f32_e32 v26, 0, v26
	v_max_f32_e32 v27, 0, v27
	v_max_f32_e32 v20, 0, v20
	v_max_f32_e32 v21, 0, v21
	v_max_f32_e32 v22, 0, v22
	v_max_f32_e32 v23, 0, v23
	v_cvt_pk_f16_f32 v16, v16, v17
	v_cvt_pk_f16_f32 v17, v18, v19
	v_max_f32_e32 v12, 0, v12
	v_max_f32_e32 v13, 0, v13
	v_max_f32_e32 v14, 0, v14
	v_max_f32_e32 v15, 0, v15
	v_max_f32_e32 v8, 0, v8
	v_max_f32_e32 v9, 0, v9
	v_max_f32_e32 v10, 0, v10
	v_max_f32_e32 v11, 0, v11
	v_max_f32_e32 v4, 0, v4
	v_max_f32_e32 v5, 0, v5
	v_max_f32_e32 v6, 0, v6
	v_max_f32_e32 v7, 0, v7
	v_max_f32_e32 v0, 0, v0
	v_max_f32_e32 v1, 0, v1
	v_max_f32_e32 v2, 0, v2
	v_max_f32_e32 v3, 0, v3
	v_pk_mul_f32 v[48:49], v[48:49], v[48:49]
	v_pk_mul_f32 v[50:51], v[50:51], v[50:51]
	v_pk_mul_f32 v[40:41], v[40:41], v[40:41]
	v_pk_mul_f32 v[42:43], v[42:43], v[42:43]
	v_pk_mul_f32 v[36:37], v[36:37], v[36:37]
	v_pk_mul_f32 v[38:39], v[38:39], v[38:39]
	v_pk_mul_f32 v[28:29], v[28:29], v[28:29]
	v_pk_mul_f32 v[30:31], v[30:31], v[30:31]
	v_pk_mul_f32 v[24:25], v[24:25], v[24:25]
	v_pk_mul_f32 v[26:27], v[26:27], v[26:27]
	v_pk_mul_f32 v[20:21], v[20:21], v[20:21]
	v_pk_mul_f32 v[22:23], v[22:23], v[22:23]
	global_store_dwordx2 v[32:33], v[16:17], off offset:96
	v_lshlrev_b64 v[16:17], 13, v[104:105]
	v_pk_mul_f32 v[12:13], v[12:13], v[12:13]
	v_pk_mul_f32 v[14:15], v[14:15], v[14:15]
	v_pk_mul_f32 v[8:9], v[8:9], v[8:9]
	v_pk_mul_f32 v[10:11], v[10:11], v[10:11]
	v_pk_mul_f32 v[4:5], v[4:5], v[4:5]
	v_pk_mul_f32 v[6:7], v[6:7], v[6:7]
	v_pk_mul_f32 v[0:1], v[0:1], v[0:1]
	v_pk_mul_f32 v[2:3], v[2:3], v[2:3]
	v_cvt_pk_f16_f32 v48, v48, v49
	v_cvt_pk_f16_f32 v49, v50, v51
	v_cvt_pk_f16_f32 v40, v40, v41
	v_cvt_pk_f16_f32 v41, v42, v43
	v_cvt_pk_f16_f32 v36, v36, v37
	v_cvt_pk_f16_f32 v37, v38, v39
	v_cvt_pk_f16_f32 v28, v28, v29
	v_cvt_pk_f16_f32 v29, v30, v31
	v_cvt_pk_f16_f32 v24, v24, v25
	v_cvt_pk_f16_f32 v25, v26, v27
	v_cvt_pk_f16_f32 v20, v20, v21
	v_cvt_pk_f16_f32 v21, v22, v23
	v_lshl_add_u64 v[16:17], v[44:45], 0, v[16:17]
	v_cvt_pk_f16_f32 v12, v12, v13
	v_cvt_pk_f16_f32 v13, v14, v15
	v_cvt_pk_f16_f32 v8, v8, v9
	v_cvt_pk_f16_f32 v9, v10, v11
	v_cvt_pk_f16_f32 v4, v4, v5
	v_cvt_pk_f16_f32 v5, v6, v7
	v_cvt_pk_f16_f32 v0, v0, v1
	v_cvt_pk_f16_f32 v1, v2, v3
	global_store_dwordx2 v[46:47], v[48:49], off
	global_store_dwordx2 v[46:47], v[40:41], off offset:32
	global_store_dwordx2 v[46:47], v[36:37], off offset:64
	global_store_dwordx2 v[32:33], v[28:29], off
	global_store_dwordx2 v[32:33], v[24:25], off offset:32
	global_store_dwordx2 v[32:33], v[20:21], off offset:64
	global_store_dwordx2 v[16:17], v[12:13], off
	global_store_dwordx2 v[16:17], v[8:9], off offset:32
	global_store_dwordx2 v[16:17], v[4:5], off offset:64
	global_store_dwordx2 v[16:17], v[0:1], off offset:96
	s_branch .LBB0_1312

; DI int TIDX() { int t = threadIdx.x; asm volatile("" : "+v"(t)); return t; }
; DI int BIDX() { int b = blockIdx.x; asm volatile("" : "+s"(b)); return b; }
; #define GL_LOAD(s_, kt_) if (VAR != 1) { a##s_##0 = GL_A(0, kt_); a##s_##1 = GL_A(1, kt_); a##s_##2 = GL_A(2, kt_); a##s_##3 = GL_A(3, kt_); b##s_##0 = GL_B(0, kt_); b##s_##1 = GL_B(1, kt_); b##s_##2 = GL_B(2, kt_); b##s_##3 = GL_B(3, kt_); }
; #define LDS_STORE(s_, buf_) if (VAR != 2) { LDS_ST1(sA, 0, buf_, a##s_##0) LDS_ST1(sA, 1, buf_, a##s_##1) LDS_ST1(sA, 2, buf_, a##s_##2) LDS_ST1(sA, 3, buf_, a##s_##3) LDS_ST1(sB, 0, buf_, b##s_##0) LDS_ST1(sB, 1, buf_, b##s_##1) LDS_ST1(sB, 2, buf_, b##s_##2) LDS_ST1(sB, 3, buf_, b##s_##3) }
; DI int tile_groups(int MT, int NT) { return (MT >> 6) * ((NT + 7) >> 3) * 512; }
;   const int tid = TIDX(), lane = tid & 63, wid = tid >> 6, wm = wid >> 1, wn = wid & 1, lr = lane & 15, g = lane >> 4;
;   char* sA = smem; char* sB = smem + 2 * LTILE;
;   uint4 a00 = {}, a01 = {}, a02 = {}, a03 = {}, b00 = {}, b01 = {}, b02 = {}, b03 = {}, a10 = {}, a11 = {}, a12 = {}, a13 = {}, b10 = {}, b11 = {}, b12 = {}, b13 = {};
;   constexpr int nk = NK;
;   const int sw0 = (g ^ ((lr >> 1) & 7)) << 4, sw1 = sw0 ^ 64;
;   const int r0 = tid >> 3, kc = tid & 7, kcs = kc ^ ((r0 >> 1) & 7);
;     ...
;   GL_LOAD(0, 0)
;   GL_LOAD(1, 1)
;   LDS_STORE(0, 0)
;   if (VAR != 4) __syncthreads();
; #pragma unroll
;   for (int kt = 0; kt < nk; kt += 2) {
;     if (kt + 2 < nk) { GL_LOAD(0, kt + 2) }
;     MMA_TILE(0)
; DI void phase_resgemm(const Params& P, const bf16_t* A, int K, const bf16_t* Wt, float* ssq_out, const float* xsrc, char* smem) {
;     ...
;   for (int vb = BIDX(); vb < tile_groups(128, 8); vb += gridDim.x) {
;     int tm, tn; if (!tile_of(vb, 128, 8, tm, tn)) continue;
;     const int m0 = tm * 128, n0 = tn * 128;
;     f32x4 acc[4][4]; zero_acc(acc);
;     if (K == 1024) gemm_kloop<false, true, 16>(acc, A + (size_t)m0 * K, K, Wt + (size_t)n0 * K, K, smem);
;     else gemm_kloop<false, true, 64>(acc, A + (size_t)m0 * K, K, Wt + (size_t)n0 * K, K, smem);
.LBB0_1371:
	s_ashr_i32 s1, s2, 3
	s_andn2_b32 s1, s1, 63
	s_and_b32 s4, s9, 56
	s_or_b32 s1, s1, s4
	s_bfe_u32 s4, s2, 0x30003
	s_or_b32 s1, s1, s4
	s_cmpk_gt_i32 s1, 0x7f
	s_cbranch_scc1 .LBB0_1370
	s_lshl_b32 s4, s1, 7
	s_ashr_i32 s5, s4, 31
	v_mov_b32_e32 v58, v148
	s_and_b32 s10, s8, 0x380
	s_lshl_b64 s[12:13], s[4:5], 13
	s_add_u32 s12, s34, s12
	v_ashrrev_i32_e32 v16, 3, v58
	v_ashrrev_i32_e32 v17, 31, v16
	v_add_u32_e32 v18, 32, v16
	s_addc_u32 s13, s35, s13
	v_lshlrev_b64 v[6:7], 13, v[16:17]
	v_lshlrev_b32_e32 v17, 4, v58
	v_ashrrev_i32_e32 v19, 31, v18
	v_add_u32_e32 v20, 64, v16
	s_waitcnt lgkmcnt(0)
	v_lshl_add_u64 v[0:1], s[12:13], 0, v[6:7]
	v_and_b32_e32 v150, 0x70, v17
	v_lshlrev_b64 v[8:9], 13, v[18:19]
	v_ashrrev_i32_e32 v21, 31, v20
	v_add_u32_e32 v54, 0x60, v16
	s_lshl_b32 s1, s10, 13
	v_lshl_add_u64 v[0:1], v[0:1], 0, v[150:151]
	v_lshl_add_u64 v[2:3], s[12:13], 0, v[8:9]
	v_lshlrev_b64 v[46:47], 13, v[20:21]
	v_ashrrev_i32_e32 v55, 31, v54
	s_add_u32 s14, s6, s1
	global_load_dwordx4 v[22:25], v[0:1], off
	v_lshl_add_u64 v[2:3], v[2:3], 0, v[150:151]
	v_lshl_add_u64 v[4:5], s[12:13], 0, v[46:47]
	v_lshlrev_b64 v[50:51], 13, v[54:55]
	s_addc_u32 s15, s7, 0
	global_load_dwordx4 v[26:29], v[2:3], off
	v_lshl_add_u64 v[4:5], v[4:5], 0, v[150:151]
	v_lshl_add_u64 v[10:11], s[12:13], 0, v[50:51]
	global_load_dwordx4 v[30:33], v[4:5], off
	v_lshl_add_u64 v[14:15], v[10:11], 0, v[150:151]
	v_lshl_add_u64 v[6:7], s[14:15], 0, v[6:7]
	global_load_dwordx4 v[34:37], v[14:15], off
	v_lshl_add_u64 v[10:11], v[6:7], 0, v[150:151]
	v_lshl_add_u64 v[6:7], s[14:15], 0, v[8:9]
	global_load_dwordx4 v[38:41], v[10:11], off
	v_lshl_add_u64 v[12:13], v[6:7], 0, v[150:151]
	v_lshl_add_u64 v[6:7], s[14:15], 0, v[46:47]
	global_load_dwordx4 v[42:45], v[12:13], off
	v_lshl_add_u64 v[8:9], v[6:7], 0, v[150:151]
	v_lshl_add_u64 v[6:7], s[14:15], 0, v[50:51]
	global_load_dwordx4 v[46:49], v[8:9], off
	v_lshl_add_u64 v[6:7], v[6:7], 0, v[150:151]
	global_load_dwordx4 v[50:53], v[6:7], off
	v_and_b32_e32 v19, 15, v58
	v_lshlrev_b32_e32 v21, 3, v58
	v_and_b32_e32 v55, 48, v58
	v_lshrrev_b32_e32 v59, 1, v58
	s_waitcnt vmcnt(10)
	v_lshlrev_b32_e32 v60, 7, v58
	v_and_b32_e32 v90, 0x70, v21
	v_bitop3_b32 v134, v21, v55, s23 bitop3:0x6c
	v_bitop3_b32 v21, v17, s23, v58 bitop3:0x48
	v_and_or_b32 v91, v59, s24, v19
	v_and_b32_e32 v130, 0x2780, v60
	global_load_dwordx4 v[58:61], v[0:1], off offset:128
	global_load_dwordx4 v[62:65], v[2:3], off offset:128
	global_load_dwordx4 v[66:69], v[4:5], off offset:128
	global_load_dwordx4 v[70:73], v[14:15], off offset:128
	global_load_dwordx4 v[74:77], v[10:11], off offset:128
	global_load_dwordx4 v[78:81], v[12:13], off offset:128
	global_load_dwordx4 v[82:85], v[8:9], off offset:128
	global_load_dwordx4 v[86:89], v[6:7], off offset:128
	v_lshl_or_b32 v17, v16, 7, v21
	v_or_b32_e32 v16, v130, v134
	v_lshl_or_b32 v18, v18, 7, v21
	v_lshl_or_b32 v19, v20, 7, v21
	v_lshl_or_b32 v20, v54, 7, v21
	v_lshlrev_b32_e32 v54, 7, v91
	v_bitop3_b32 v21, v54, v90, v55 bitop3:0xf6
	s_movk_i32 s1, 0x1000
	v_readlane_b32 s12, v254, 55
	v_readlane_b32 s13, v254, 56
	v_readlane_b32 s14, v254, 57
	v_readlane_b32 s15, v254, 58
	s_waitcnt vmcnt(15)
	ds_write_b128 v17, v[22:25]
	s_waitcnt vmcnt(14)
	ds_write_b128 v18, v[26:29]
	s_waitcnt vmcnt(13)
	ds_write_b128 v19, v[30:33]
	s_waitcnt vmcnt(12)
	ds_write_b128 v20, v[34:37]
	s_waitcnt vmcnt(11)
	ds_write_b128 v17, v[38:41] offset:32768
	s_waitcnt vmcnt(10)
	ds_write_b128 v18, v[42:45] offset:32768
	s_waitcnt vmcnt(9)
	ds_write_b128 v19, v[46:49] offset:32768
	s_waitcnt vmcnt(8)
	ds_write_b128 v20, v[50:53] offset:32768
	s_waitcnt lgkmcnt(0)
	s_barrier
	s_setprio 1
	ds_read_b128 v[22:25], v16 offset:32768
	ds_read_b128 v[30:33], v21
	s_waitcnt lgkmcnt(0)
	v_mfma_f32_16x16x32_f16 v[38:41], v[22:25], v[30:33], 0
	ds_read_b128 v[26:29], v16 offset:34816
	ds_read_b128 v[34:37], v21 offset:2048
	s_waitcnt lgkmcnt(0)
	v_mfma_f32_16x16x32_f16 v[94:97], v[22:25], v[34:37], 0
	ds_read_b128 v[42:45], v16 offset:36864
	ds_read_b128 v[106:109], v21 offset:4096
	s_waitcnt lgkmcnt(0)
	v_mfma_f32_16x16x32_f16 v[114:117], v[22:25], v[106:109], 0
	ds_read_b128 v[50:53], v16 offset:38912
	ds_read_b128 v[110:113], v21 offset:6144
	s_waitcnt lgkmcnt(0)
	v_mfma_f32_16x16x32_f16 v[126:129], v[22:25], v[110:113], 0
	v_xor_b32_e32 v22, 64, v134
	v_mfma_f32_16x16x32_f16 v[46:49], v[26:29], v[30:33], 0
	v_or_b32_e32 v22, v130, v22
	v_mfma_f32_16x16x32_f16 v[90:93], v[42:45], v[30:33], 0
	ds_read_b128 v[130:133], v22 offset:32768
	v_mfma_f32_16x16x32_f16 v[30:33], v[50:53], v[30:33], 0
	ds_read_b128 v[142:145], v22 offset:36864
	v_mfma_f32_16x16x32_f16 v[98:101], v[26:29], v[34:37], 0
	ds_read_b128 v[154:157], v22 offset:38912
	v_mfma_f32_16x16x32_f16 v[102:105], v[42:45], v[34:37], 0
	v_bitop3_b32 v23, v54, v134, 64 bitop3:0xf6
	v_mfma_f32_16x16x32_f16 v[34:37], v[50:53], v[34:37], 0
	ds_read_b128 v[134:137], v23
	v_mfma_f32_16x16x32_f16 v[118:121], v[26:29], v[106:109], 0
	ds_read_b128 v[138:141], v23 offset:2048
	v_mfma_f32_16x16x32_f16 v[122:125], v[42:45], v[106:109], 0
	v_mfma_f32_16x16x32_f16 v[106:109], v[50:53], v[106:109], 0
	s_waitcnt vmcnt(7)
	ds_write_b128 v17, v[58:61] offset:16384
	v_mfma_f32_16x16x32_f16 v[24:27], v[26:29], v[110:113], 0
	s_waitcnt vmcnt(6)
	ds_write_b128 v18, v[62:65] offset:16384
	v_mfma_f32_16x16x32_f16 v[42:45], v[42:45], v[110:113], 0
	s_waitcnt vmcnt(5)
	ds_write_b128 v19, v[66:69] offset:16384
	v_mfma_f32_16x16x32_f16 v[50:53], v[50:53], v[110:113], 0
	ds_read_b128 v[110:113], v22 offset:34816
	s_waitcnt lgkmcnt(5)
	v_mfma_f32_16x16x32_f16 v[38:41], v[130:133], v[134:137], v[38:41]
	s_waitcnt vmcnt(4)
; #define GL_LOAD(s_, kt_) if (VAR != 1) { a##s_##0 = GL_A(0, kt_); a##s_##1 = GL_A(1, kt_); a##s_##2 = GL_A(2, kt_); a##s_##3 = GL_A(3, kt_); b##s_##0 = GL_B(0, kt_); b##s_##1 = GL_B(1, kt_); b##s_##2 = GL_B(2, kt_); b##s_##3 = GL_B(3, kt_); }
; #define LDS_STORE(s_, buf_) if (VAR != 2) { LDS_ST1(sA, 0, buf_, a##s_##0) LDS_ST1(sA, 1, buf_, a##s_##1) LDS_ST1(sA, 2, buf_, a##s_##2) LDS_ST1(sA, 3, buf_, a##s_##3) LDS_ST1(sB, 0, buf_, b##s_##0) LDS_ST1(sB, 1, buf_, b##s_##1) LDS_ST1(sB, 2, buf_, b##s_##2) LDS_ST1(sB, 3, buf_, b##s_##3) }
;     ...
;   GL_LOAD(0, 0)
;   GL_LOAD(1, 1)
;   LDS_STORE(0, 0)
;   if (VAR != 4) __syncthreads();
; #pragma unroll
;   for (int kt = 0; kt < nk; kt += 2) {
;     if (kt + 2 < nk) { GL_LOAD(0, kt + 2) }
;     MMA_TILE(0)
;     LDS_STORE(1, 1)
;     if (VAR != 4) __syncthreads();
;     if (kt + 3 < nk) { GL_LOAD(1, kt + 3) }
;     MMA_TILE(1)
;     if (kt + 2 < nk) { LDS_STORE(0, 0) }
;     if (VAR != 4) __syncthreads();
	ds_write_b128 v20, v[70:73] offset:16384
	v_mfma_f32_16x16x32_f16 v[90:93], v[142:145], v[134:137], v[90:93]
	s_waitcnt vmcnt(3)
	ds_write_b128 v17, v[74:77] offset:49152
	v_mfma_f32_16x16x32_f16 v[28:31], v[154:157], v[134:137], v[30:33]
	s_waitcnt vmcnt(2)
	ds_write_b128 v18, v[78:81] offset:49152
	s_waitcnt lgkmcnt(7)
	v_mfma_f32_16x16x32_f16 v[94:97], v[130:133], v[138:141], v[94:97]
	s_waitcnt vmcnt(1)
	ds_write_b128 v19, v[82:85] offset:49152
	v_mfma_f32_16x16x32_f16 v[102:105], v[142:145], v[138:141], v[102:105]
	s_waitcnt vmcnt(0)
	ds_write_b128 v20, v[86:89] offset:49152
	v_mfma_f32_16x16x32_f16 v[32:35], v[154:157], v[138:141], v[34:37]
	s_waitcnt lgkmcnt(5)
	v_mfma_f32_16x16x32_f16 v[46:49], v[110:113], v[134:137], v[46:49]
	ds_read_b128 v[134:137], v23 offset:4096
	v_mfma_f32_16x16x32_f16 v[98:101], v[110:113], v[138:141], v[98:101]
	ds_read_b128 v[138:141], v23 offset:6144
	s_waitcnt lgkmcnt(1)
	v_mfma_f32_16x16x32_f16 v[114:117], v[130:133], v[134:137], v[114:117]
	s_waitcnt lgkmcnt(0)
	v_mfma_f32_16x16x32_f16 v[126:129], v[130:133], v[138:141], v[126:129]
	global_load_dwordx4 v[130:133], v[0:1], off offset:256
	v_mfma_f32_16x16x32_f16 v[118:121], v[110:113], v[134:137], v[118:121]
	v_mfma_f32_16x16x32_f16 v[24:27], v[110:113], v[138:141], v[24:27]
	v_mfma_f32_16x16x32_f16 v[122:125], v[142:145], v[134:137], v[122:125]
	v_mfma_f32_16x16x32_f16 v[106:109], v[154:157], v[134:137], v[106:109]
	global_load_dwordx4 v[134:137], v[2:3], off offset:256
	global_load_dwordx4 v[158:161], v[4:5], off offset:256
	global_load_dwordx4 v[162:165], v[14:15], off offset:256
	global_load_dwordx4 v[110:113], v[10:11], off offset:256
	global_load_dwordx4 v[166:169], v[12:13], off offset:256
	global_load_dwordx4 v[190:193], v[8:9], off offset:256
	global_load_dwordx4 v[194:197], v[6:7], off offset:256
	s_waitcnt lgkmcnt(0)
	s_barrier
	v_mfma_f32_16x16x32_f16 v[42:45], v[142:145], v[138:141], v[42:45]
	ds_read_b128 v[58:61], v16 offset:49152
	v_mfma_f32_16x16x32_f16 v[50:53], v[154:157], v[138:141], v[50:53]
	ds_read_b128 v[62:65], v16 offset:51200
	ds_read_b128 v[66:69], v21 offset:16384
	s_waitcnt lgkmcnt(0)
	v_mfma_f32_16x16x32_f16 v[36:39], v[58:61], v[66:69], v[38:41]
	ds_read_b128 v[70:73], v21 offset:18432
	v_mfma_f32_16x16x32_f16 v[46:49], v[62:65], v[66:69], v[46:49]
	ds_read_b128 v[74:77], v16 offset:53248
	s_waitcnt lgkmcnt(0)
	v_mfma_f32_16x16x32_f16 v[82:85], v[74:77], v[66:69], v[90:93]
	ds_read_b128 v[78:81], v16 offset:55296
	s_waitcnt lgkmcnt(0)
	v_mfma_f32_16x16x32_f16 v[28:31], v[78:81], v[66:69], v[28:31]
	v_mfma_f32_16x16x32_f16 v[66:69], v[58:61], v[70:73], v[94:97]
	s_nop 2
	ds_read_b128 v[94:97], v21 offset:22528
	v_mfma_f32_16x16x32_f16 v[86:89], v[62:65], v[70:73], v[98:101]
	v_mfma_f32_16x16x32_f16 v[90:93], v[74:77], v[70:73], v[102:105]
	v_mfma_f32_16x16x32_f16 v[32:35], v[78:81], v[70:73], v[32:35]
	ds_read_b128 v[70:73], v21 offset:20480
	s_waitcnt lgkmcnt(0)
	v_mfma_f32_16x16x32_f16 v[98:101], v[58:61], v[70:73], v[114:117]
	v_mfma_f32_16x16x32_f16 v[58:61], v[58:61], v[94:97], v[126:129]
	v_mfma_f32_16x16x32_f16 v[102:105], v[62:65], v[70:73], v[118:121]
	s_nop 2
	ds_read_b128 v[118:121], v22 offset:55296
	v_mfma_f32_16x16x32_f16 v[24:27], v[62:65], v[94:97], v[24:27]
	ds_read_b128 v[62:65], v22 offset:49152
	s_waitcnt vmcnt(7)
	ds_write_b128 v17, v[130:133]
	v_mfma_f32_16x16x32_f16 v[114:117], v[74:77], v[70:73], v[122:125]
	s_waitcnt vmcnt(6)
	ds_write_b128 v18, v[134:137]
	s_waitcnt vmcnt(5)
	ds_write_b128 v19, v[158:161]
	v_mfma_f32_16x16x32_f16 v[40:43], v[74:77], v[94:97], v[42:45]
	ds_read_b128 v[74:77], v22 offset:51200
	v_mfma_f32_16x16x32_f16 v[70:73], v[78:81], v[70:73], v[106:109]
	s_nop 2
	ds_read_b128 v[106:109], v22 offset:53248
	v_mfma_f32_16x16x32_f16 v[50:53], v[78:81], v[94:97], v[50:53]
	ds_read_b128 v[78:81], v23 offset:16384
	s_waitcnt lgkmcnt(0)
	v_mfma_f32_16x16x32_f16 v[36:39], v[62:65], v[78:81], v[36:39]
	ds_read_b128 v[94:97], v23 offset:18432
	s_waitcnt lgkmcnt(0)
	v_mfma_f32_16x16x32_f16 v[66:69], v[62:65], v[94:97], v[66:69]
	s_waitcnt vmcnt(4)
	ds_write_b128 v20, v[162:165]
	v_mfma_f32_16x16x32_f16 v[44:47], v[74:77], v[78:81], v[46:49]
	s_waitcnt vmcnt(3)
	ds_write_b128 v17, v[110:113] offset:32768
	v_mfma_f32_16x16x32_f16 v[82:85], v[106:109], v[78:81], v[82:85]
	v_mfma_f32_16x16x32_f16 v[28:31], v[118:121], v[78:81], v[28:31]
	v_mfma_f32_16x16x32_f16 v[78:81], v[74:77], v[94:97], v[86:89]
	s_waitcnt vmcnt(2)
	ds_write_b128 v18, v[166:169] offset:32768
	s_waitcnt vmcnt(1)
	ds_write_b128 v19, v[190:193] offset:32768
	s_waitcnt vmcnt(0)
	ds_write_b128 v20, v[194:197] offset:32768
	v_mfma_f32_16x16x32_f16 v[86:89], v[106:109], v[94:97], v[90:93]
	s_nop 2
	ds_read_b128 v[90:93], v23 offset:20480
	v_mfma_f32_16x16x32_f16 v[32:35], v[118:121], v[94:97], v[32:35]
	ds_read_b128 v[94:97], v23 offset:22528
	s_waitcnt lgkmcnt(1)
	v_mfma_f32_16x16x32_f16 v[98:101], v[62:65], v[90:93], v[98:101]
	s_waitcnt lgkmcnt(0)
	v_mfma_f32_16x16x32_f16 v[58:61], v[62:65], v[94:97], v[58:61]
	global_load_dwordx4 v[62:65], v[0:1], off offset:384
	v_mfma_f32_16x16x32_f16 v[102:105], v[74:77], v[90:93], v[102:105]
	v_mfma_f32_16x16x32_f16 v[24:27], v[74:77], v[94:97], v[24:27]
	v_mfma_f32_16x16x32_f16 v[114:117], v[106:109], v[90:93], v[114:117]
	v_mfma_f32_16x16x32_f16 v[40:43], v[106:109], v[94:97], v[40:43]
	v_mfma_f32_16x16x32_f16 v[70:73], v[118:121], v[90:93], v[70:73]
	global_load_dwordx4 v[90:93], v[2:3], off offset:384
	global_load_dwordx4 v[122:125], v[4:5], off offset:384
	global_load_dwordx4 v[126:129], v[14:15], off offset:384
	global_load_dwordx4 v[74:77], v[10:11], off offset:384
	global_load_dwordx4 v[138:141], v[12:13], off offset:384
	global_load_dwordx4 v[142:145], v[8:9], off offset:384
	global_load_dwordx4 v[154:157], v[6:7], off offset:384
	s_waitcnt lgkmcnt(0)
	s_barrier
; #define GL_LOAD(s_, kt_) if (VAR != 1) { a##s_##0 = GL_A(0, kt_); a##s_##1 = GL_A(1, kt_); a##s_##2 = GL_A(2, kt_); a##s_##3 = GL_A(3, kt_); b##s_##0 = GL_B(0, kt_); b##s_##1 = GL_B(1, kt_); b##s_##2 = GL_B(2, kt_); b##s_##3 = GL_B(3, kt_); }
; #define LDS_STORE(s_, buf_) if (VAR != 2) { LDS_ST1(sA, 0, buf_, a##s_##0) LDS_ST1(sA, 1, buf_, a##s_##1) LDS_ST1(sA, 2, buf_, a##s_##2) LDS_ST1(sA, 3, buf_, a##s_##3) LDS_ST1(sB, 0, buf_, b##s_##0) LDS_ST1(sB, 1, buf_, b##s_##1) LDS_ST1(sB, 2, buf_, b##s_##2) LDS_ST1(sB, 3, buf_, b##s_##3) }
;     ...
;   GL_LOAD(0, 0)
;   GL_LOAD(1, 1)
;   LDS_STORE(0, 0)
;   if (VAR != 4) __syncthreads();
; #pragma unroll
;   for (int kt = 0; kt < nk; kt += 2) {
;     if (kt + 2 < nk) { GL_LOAD(0, kt + 2) }
;     MMA_TILE(0)
;     LDS_STORE(1, 1)
;     if (VAR != 4) __syncthreads();
;     if (kt + 3 < nk) { GL_LOAD(1, kt + 3) }
;     MMA_TILE(1)
;     if (kt + 2 < nk) { LDS_STORE(0, 0) }
;     if (VAR != 4) __syncthreads();
	v_mfma_f32_16x16x32_f16 v[48:51], v[118:121], v[94:97], v[50:53]
	ds_read_b128 v[106:109], v16 offset:32768
	ds_read_b128 v[94:97], v21
	s_waitcnt lgkmcnt(0)
	v_mfma_f32_16x16x32_f16 v[36:39], v[106:109], v[94:97], v[36:39]
	ds_read_b128 v[52:55], v16 offset:34816
	ds_read_b128 v[110:113], v21 offset:2048
	s_waitcnt lgkmcnt(0)
	v_mfma_f32_16x16x32_f16 v[66:69], v[106:109], v[110:113], v[66:69]
	ds_read_b128 v[118:121], v16 offset:36864
	v_mfma_f32_16x16x32_f16 v[44:47], v[52:55], v[94:97], v[44:47]
	ds_read_b128 v[130:133], v16 offset:38912
	v_mfma_f32_16x16x32_f16 v[78:81], v[52:55], v[110:113], v[78:81]
	s_waitcnt lgkmcnt(1)
	v_mfma_f32_16x16x32_f16 v[82:85], v[118:121], v[94:97], v[82:85]
	v_mfma_f32_16x16x32_f16 v[86:89], v[118:121], v[110:113], v[86:89]
	s_waitcnt lgkmcnt(0)
	v_mfma_f32_16x16x32_f16 v[28:31], v[130:133], v[94:97], v[28:31]
	ds_read_b128 v[94:97], v21 offset:4096
	v_mfma_f32_16x16x32_f16 v[32:35], v[130:133], v[110:113], v[32:35]
	ds_read_b128 v[110:113], v21 offset:6144
	s_waitcnt lgkmcnt(1)
	v_mfma_f32_16x16x32_f16 v[98:101], v[106:109], v[94:97], v[98:101]
	s_waitcnt lgkmcnt(0)
	v_mfma_f32_16x16x32_f16 v[58:61], v[106:109], v[110:113], v[58:61]
	ds_read_b128 v[106:109], v23
	v_mfma_f32_16x16x32_f16 v[102:105], v[52:55], v[94:97], v[102:105]
	v_mfma_f32_16x16x32_f16 v[24:27], v[52:55], v[110:113], v[24:27]
	ds_read_b128 v[52:55], v22 offset:32768
	v_mfma_f32_16x16x32_f16 v[114:117], v[118:121], v[94:97], v[114:117]
	s_waitcnt vmcnt(7)
	ds_write_b128 v17, v[62:65] offset:16384
	s_waitcnt vmcnt(6)
	ds_write_b128 v18, v[90:93] offset:16384
	v_mfma_f32_16x16x32_f16 v[40:43], v[118:121], v[110:113], v[40:43]
	ds_read_b128 v[118:121], v22 offset:36864
	s_waitcnt vmcnt(5)
	ds_write_b128 v19, v[122:125] offset:16384
	v_mfma_f32_16x16x32_f16 v[70:73], v[130:133], v[94:97], v[70:73]
	ds_read_b128 v[94:97], v22 offset:34816
	v_mfma_f32_16x16x32_f16 v[48:51], v[130:133], v[110:113], v[48:51]
	ds_read_b128 v[110:113], v23 offset:2048
	s_waitcnt lgkmcnt(6)
	v_mfma_f32_16x16x32_f16 v[36:39], v[52:55], v[106:109], v[36:39]
	ds_read_b128 v[130:133], v22 offset:38912
	s_waitcnt lgkmcnt(1)
	v_mfma_f32_16x16x32_f16 v[66:69], v[52:55], v[110:113], v[66:69]
	s_waitcnt vmcnt(4)
	ds_write_b128 v20, v[126:129] offset:16384
	v_mfma_f32_16x16x32_f16 v[44:47], v[94:97], v[106:109], v[44:47]
	s_waitcnt vmcnt(3)
	ds_write_b128 v17, v[74:77] offset:49152
	v_mfma_f32_16x16x32_f16 v[78:81], v[94:97], v[110:113], v[78:81]
	s_waitcnt vmcnt(2)
	ds_write_b128 v18, v[138:141] offset:49152
	v_mfma_f32_16x16x32_f16 v[82:85], v[118:121], v[106:109], v[82:85]
	s_waitcnt vmcnt(1)
	ds_write_b128 v19, v[142:145] offset:49152
	v_mfma_f32_16x16x32_f16 v[86:89], v[118:121], v[110:113], v[86:89]
	s_waitcnt vmcnt(0)
	ds_write_b128 v20, v[154:157] offset:49152
	s_waitcnt lgkmcnt(5)
	v_mfma_f32_16x16x32_f16 v[28:31], v[130:133], v[106:109], v[28:31]
	ds_read_b128 v[106:109], v23 offset:4096
	v_mfma_f32_16x16x32_f16 v[32:35], v[130:133], v[110:113], v[32:35]
	ds_read_b128 v[110:113], v23 offset:6144
	s_waitcnt lgkmcnt(1)
	v_mfma_f32_16x16x32_f16 v[98:101], v[52:55], v[106:109], v[98:101]
	s_waitcnt lgkmcnt(0)
	v_mfma_f32_16x16x32_f16 v[52:55], v[52:55], v[110:113], v[58:61]
	s_nop 2
	global_load_dwordx4 v[58:61], v[0:1], off offset:512
	v_mfma_f32_16x16x32_f16 v[102:105], v[94:97], v[106:109], v[102:105]
	v_mfma_f32_16x16x32_f16 v[24:27], v[94:97], v[110:113], v[24:27]
	v_mfma_f32_16x16x32_f16 v[114:117], v[118:121], v[106:109], v[114:117]
	v_mfma_f32_16x16x32_f16 v[40:43], v[118:121], v[110:113], v[40:43]
	v_mfma_f32_16x16x32_f16 v[70:73], v[130:133], v[106:109], v[70:73]
	global_load_dwordx4 v[106:109], v[2:3], off offset:512
	global_load_dwordx4 v[134:137], v[4:5], off offset:512
	global_load_dwordx4 v[158:161], v[14:15], off offset:512
	global_load_dwordx4 v[94:97], v[10:11], off offset:512
	global_load_dwordx4 v[162:165], v[12:13], off offset:512
	global_load_dwordx4 v[166:169], v[8:9], off offset:512
	global_load_dwordx4 v[190:193], v[6:7], off offset:512
	s_waitcnt lgkmcnt(0)
	s_barrier
	v_mfma_f32_16x16x32_f16 v[48:51], v[130:133], v[110:113], v[48:51]
	ds_read_b128 v[62:65], v16 offset:49152
	ds_read_b128 v[90:93], v21 offset:16384
	s_waitcnt lgkmcnt(0)
	v_mfma_f32_16x16x32_f16 v[36:39], v[62:65], v[90:93], v[36:39]
	ds_read_b128 v[74:77], v16 offset:51200
	ds_read_b128 v[110:113], v21 offset:18432
	s_waitcnt lgkmcnt(0)
	v_mfma_f32_16x16x32_f16 v[66:69], v[62:65], v[110:113], v[66:69]
	ds_read_b128 v[118:121], v16 offset:53248
	v_mfma_f32_16x16x32_f16 v[44:47], v[74:77], v[90:93], v[44:47]
	ds_read_b128 v[122:125], v16 offset:55296
	v_mfma_f32_16x16x32_f16 v[78:81], v[74:77], v[110:113], v[78:81]
	s_waitcnt lgkmcnt(1)
	v_mfma_f32_16x16x32_f16 v[82:85], v[118:121], v[90:93], v[82:85]
	v_mfma_f32_16x16x32_f16 v[86:89], v[118:121], v[110:113], v[86:89]
	s_waitcnt lgkmcnt(0)
	v_mfma_f32_16x16x32_f16 v[28:31], v[122:125], v[90:93], v[28:31]
	ds_read_b128 v[90:93], v21 offset:20480
	v_mfma_f32_16x16x32_f16 v[32:35], v[122:125], v[110:113], v[32:35]
	ds_read_b128 v[110:113], v21 offset:22528
	s_waitcnt lgkmcnt(1)
	v_mfma_f32_16x16x32_f16 v[98:101], v[62:65], v[90:93], v[98:101]
	s_waitcnt lgkmcnt(0)
	v_mfma_f32_16x16x32_f16 v[52:55], v[62:65], v[110:113], v[52:55]
	ds_read_b128 v[62:65], v22 offset:49152
	v_mfma_f32_16x16x32_f16 v[102:105], v[74:77], v[90:93], v[102:105]
	v_mfma_f32_16x16x32_f16 v[24:27], v[74:77], v[110:113], v[24:27]
	ds_read_b128 v[74:77], v22 offset:51200
	v_mfma_f32_16x16x32_f16 v[114:117], v[118:121], v[90:93], v[114:117]
	s_waitcnt vmcnt(7)
	ds_write_b128 v17, v[58:61]
	s_waitcnt vmcnt(6)
; #define GL_LOAD(s_, kt_) if (VAR != 1) { a##s_##0 = GL_A(0, kt_); a##s_##1 = GL_A(1, kt_); a##s_##2 = GL_A(2, kt_); a##s_##3 = GL_A(3, kt_); b##s_##0 = GL_B(0, kt_); b##s_##1 = GL_B(1, kt_); b##s_##2 = GL_B(2, kt_); b##s_##3 = GL_B(3, kt_); }
; #define LDS_STORE(s_, buf_) if (VAR != 2) { LDS_ST1(sA, 0, buf_, a##s_##0) LDS_ST1(sA, 1, buf_, a##s_##1) LDS_ST1(sA, 2, buf_, a##s_##2) LDS_ST1(sA, 3, buf_, a##s_##3) LDS_ST1(sB, 0, buf_, b##s_##0) LDS_ST1(sB, 1, buf_, b##s_##1) LDS_ST1(sB, 2, buf_, b##s_##2) LDS_ST1(sB, 3, buf_, b##s_##3) }
;     ...
;   GL_LOAD(0, 0)
;   GL_LOAD(1, 1)
;   LDS_STORE(0, 0)
;   if (VAR != 4) __syncthreads();
; #pragma unroll
;   for (int kt = 0; kt < nk; kt += 2) {
;     if (kt + 2 < nk) { GL_LOAD(0, kt + 2) }
;     MMA_TILE(0)
;     LDS_STORE(1, 1)
;     if (VAR != 4) __syncthreads();
;     if (kt + 3 < nk) { GL_LOAD(1, kt + 3) }
;     MMA_TILE(1)
;     if (kt + 2 < nk) { LDS_STORE(0, 0) }
;     if (VAR != 4) __syncthreads();
	ds_write_b128 v18, v[106:109]
	v_mfma_f32_16x16x32_f16 v[40:43], v[118:121], v[110:113], v[40:43]
	ds_read_b128 v[118:121], v22 offset:53248
	s_waitcnt vmcnt(5)
	ds_write_b128 v19, v[134:137]
	v_mfma_f32_16x16x32_f16 v[70:73], v[122:125], v[90:93], v[70:73]
	ds_read_b128 v[90:93], v23 offset:16384
	v_mfma_f32_16x16x32_f16 v[48:51], v[122:125], v[110:113], v[48:51]
	ds_read_b128 v[110:113], v23 offset:18432
	s_waitcnt lgkmcnt(1)
	v_mfma_f32_16x16x32_f16 v[36:39], v[62:65], v[90:93], v[36:39]
	ds_read_b128 v[122:125], v22 offset:55296
	s_waitcnt lgkmcnt(1)
	v_mfma_f32_16x16x32_f16 v[66:69], v[62:65], v[110:113], v[66:69]
	s_waitcnt vmcnt(4)
	ds_write_b128 v20, v[158:161]
	v_mfma_f32_16x16x32_f16 v[44:47], v[74:77], v[90:93], v[44:47]
	s_waitcnt vmcnt(3)
	ds_write_b128 v17, v[94:97] offset:32768
	v_mfma_f32_16x16x32_f16 v[78:81], v[74:77], v[110:113], v[78:81]
	s_waitcnt vmcnt(2)
	ds_write_b128 v18, v[162:165] offset:32768
	v_mfma_f32_16x16x32_f16 v[82:85], v[118:121], v[90:93], v[82:85]
	s_waitcnt vmcnt(1)
	ds_write_b128 v19, v[166:169] offset:32768
	v_mfma_f32_16x16x32_f16 v[86:89], v[118:121], v[110:113], v[86:89]
	s_waitcnt vmcnt(0)
	ds_write_b128 v20, v[190:193] offset:32768
	s_waitcnt lgkmcnt(5)
	v_mfma_f32_16x16x32_f16 v[28:31], v[122:125], v[90:93], v[28:31]
	ds_read_b128 v[90:93], v23 offset:20480
	v_mfma_f32_16x16x32_f16 v[32:35], v[122:125], v[110:113], v[32:35]
	ds_read_b128 v[110:113], v23 offset:22528
	s_waitcnt lgkmcnt(1)
	v_mfma_f32_16x16x32_f16 v[98:101], v[62:65], v[90:93], v[98:101]
	s_waitcnt lgkmcnt(0)
	v_mfma_f32_16x16x32_f16 v[52:55], v[62:65], v[110:113], v[52:55]
	global_load_dwordx4 v[62:65], v[0:1], off offset:640
	v_mfma_f32_16x16x32_f16 v[102:105], v[74:77], v[90:93], v[102:105]
	v_mfma_f32_16x16x32_f16 v[24:27], v[74:77], v[110:113], v[24:27]
	v_mfma_f32_16x16x32_f16 v[114:117], v[118:121], v[90:93], v[114:117]
	v_mfma_f32_16x16x32_f16 v[40:43], v[118:121], v[110:113], v[40:43]
	v_mfma_f32_16x16x32_f16 v[70:73], v[122:125], v[90:93], v[70:73]
	global_load_dwordx4 v[90:93], v[2:3], off offset:640
	global_load_dwordx4 v[126:129], v[4:5], off offset:640
	global_load_dwordx4 v[130:133], v[14:15], off offset:640
	global_load_dwordx4 v[74:77], v[10:11], off offset:640
	global_load_dwordx4 v[138:141], v[12:13], off offset:640
	global_load_dwordx4 v[142:145], v[8:9], off offset:640
	global_load_dwordx4 v[154:157], v[6:7], off offset:640
	s_waitcnt lgkmcnt(0)
	s_barrier
	v_mfma_f32_16x16x32_f16 v[48:51], v[122:125], v[110:113], v[48:51]
	ds_read_b128 v[58:61], v16 offset:32768
	ds_read_b128 v[106:109], v21
	s_waitcnt lgkmcnt(0)
	v_mfma_f32_16x16x32_f16 v[36:39], v[58:61], v[106:109], v[36:39]
	ds_read_b128 v[94:97], v16 offset:34816
	ds_read_b128 v[110:113], v21 offset:2048
	s_waitcnt lgkmcnt(0)
	v_mfma_f32_16x16x32_f16 v[66:69], v[58:61], v[110:113], v[66:69]
	ds_read_b128 v[118:121], v16 offset:36864
	v_mfma_f32_16x16x32_f16 v[44:47], v[94:97], v[106:109], v[44:47]
	ds_read_b128 v[122:125], v16 offset:38912
	v_mfma_f32_16x16x32_f16 v[78:81], v[94:97], v[110:113], v[78:81]
	s_waitcnt lgkmcnt(1)
	v_mfma_f32_16x16x32_f16 v[82:85], v[118:121], v[106:109], v[82:85]
	v_mfma_f32_16x16x32_f16 v[86:89], v[118:121], v[110:113], v[86:89]
	s_waitcnt lgkmcnt(0)
	v_mfma_f32_16x16x32_f16 v[28:31], v[122:125], v[106:109], v[28:31]
	ds_read_b128 v[106:109], v21 offset:4096
	v_mfma_f32_16x16x32_f16 v[32:35], v[122:125], v[110:113], v[32:35]
	ds_read_b128 v[110:113], v21 offset:6144
	s_waitcnt lgkmcnt(1)
	v_mfma_f32_16x16x32_f16 v[98:101], v[58:61], v[106:109], v[98:101]
	s_waitcnt lgkmcnt(0)
	v_mfma_f32_16x16x32_f16 v[52:55], v[58:61], v[110:113], v[52:55]
	ds_read_b128 v[58:61], v22 offset:32768
	v_mfma_f32_16x16x32_f16 v[102:105], v[94:97], v[106:109], v[102:105]
	v_mfma_f32_16x16x32_f16 v[24:27], v[94:97], v[110:113], v[24:27]
	ds_read_b128 v[94:97], v22 offset:34816
	v_mfma_f32_16x16x32_f16 v[114:117], v[118:121], v[106:109], v[114:117]
	s_waitcnt vmcnt(7)
	ds_write_b128 v17, v[62:65] offset:16384
	s_waitcnt vmcnt(6)
	ds_write_b128 v18, v[90:93] offset:16384
	v_mfma_f32_16x16x32_f16 v[40:43], v[118:121], v[110:113], v[40:43]
	ds_read_b128 v[118:121], v22 offset:36864
	s_waitcnt vmcnt(5)
	ds_write_b128 v19, v[126:129] offset:16384
	v_mfma_f32_16x16x32_f16 v[70:73], v[122:125], v[106:109], v[70:73]
	ds_read_b128 v[106:109], v23
	v_mfma_f32_16x16x32_f16 v[48:51], v[122:125], v[110:113], v[48:51]
	ds_read_b128 v[110:113], v23 offset:2048
	s_waitcnt lgkmcnt(1)
	v_mfma_f32_16x16x32_f16 v[36:39], v[58:61], v[106:109], v[36:39]
	ds_read_b128 v[122:125], v22 offset:38912
	s_waitcnt lgkmcnt(1)
	v_mfma_f32_16x16x32_f16 v[66:69], v[58:61], v[110:113], v[66:69]
	s_waitcnt vmcnt(4)
	ds_write_b128 v20, v[130:133] offset:16384
	v_mfma_f32_16x16x32_f16 v[44:47], v[94:97], v[106:109], v[44:47]
	s_waitcnt vmcnt(3)
	ds_write_b128 v17, v[74:77] offset:49152
	v_mfma_f32_16x16x32_f16 v[78:81], v[94:97], v[110:113], v[78:81]
	s_waitcnt vmcnt(2)
	ds_write_b128 v18, v[138:141] offset:49152
	v_mfma_f32_16x16x32_f16 v[82:85], v[118:121], v[106:109], v[82:85]
	s_waitcnt vmcnt(1)
	ds_write_b128 v19, v[142:145] offset:49152
	v_mfma_f32_16x16x32_f16 v[86:89], v[118:121], v[110:113], v[86:89]
	s_waitcnt vmcnt(0)
	ds_write_b128 v20, v[154:157] offset:49152
	s_waitcnt lgkmcnt(5)
	v_mfma_f32_16x16x32_f16 v[28:31], v[122:125], v[106:109], v[28:31]
	ds_read_b128 v[106:109], v23 offset:4096
	v_mfma_f32_16x16x32_f16 v[32:35], v[122:125], v[110:113], v[32:35]
	ds_read_b128 v[110:113], v23 offset:6144
	s_waitcnt lgkmcnt(1)
	v_mfma_f32_16x16x32_f16 v[98:101], v[58:61], v[106:109], v[98:101]
	s_waitcnt lgkmcnt(0)
	v_mfma_f32_16x16x32_f16 v[52:55], v[58:61], v[110:113], v[52:55]
	global_load_dwordx4 v[58:61], v[0:1], off offset:768
	v_mfma_f32_16x16x32_f16 v[102:105], v[94:97], v[106:109], v[102:105]
	v_mfma_f32_16x16x32_f16 v[24:27], v[94:97], v[110:113], v[24:27]
	v_mfma_f32_16x16x32_f16 v[114:117], v[118:121], v[106:109], v[114:117]
	v_mfma_f32_16x16x32_f16 v[40:43], v[118:121], v[110:113], v[40:43]
	v_mfma_f32_16x16x32_f16 v[70:73], v[122:125], v[106:109], v[70:73]
	global_load_dwordx4 v[106:109], v[2:3], off offset:768
	global_load_dwordx4 v[134:137], v[4:5], off offset:768
	global_load_dwordx4 v[158:161], v[14:15], off offset:768
	global_load_dwordx4 v[94:97], v[10:11], off offset:768
	global_load_dwordx4 v[162:165], v[12:13], off offset:768
	global_load_dwordx4 v[166:169], v[8:9], off offset:768
	global_load_dwordx4 v[190:193], v[6:7], off offset:768
	s_waitcnt lgkmcnt(0)
	s_barrier
; #define GL_LOAD(s_, kt_) if (VAR != 1) { a##s_##0 = GL_A(0, kt_); a##s_##1 = GL_A(1, kt_); a##s_##2 = GL_A(2, kt_); a##s_##3 = GL_A(3, kt_); b##s_##0 = GL_B(0, kt_); b##s_##1 = GL_B(1, kt_); b##s_##2 = GL_B(2, kt_); b##s_##3 = GL_B(3, kt_); }
; #define LDS_STORE(s_, buf_) if (VAR != 2) { LDS_ST1(sA, 0, buf_, a##s_##0) LDS_ST1(sA, 1, buf_, a##s_##1) LDS_ST1(sA, 2, buf_, a##s_##2) LDS_ST1(sA, 3, buf_, a##s_##3) LDS_ST1(sB, 0, buf_, b##s_##0) LDS_ST1(sB, 1, buf_, b##s_##1) LDS_ST1(sB, 2, buf_, b##s_##2) LDS_ST1(sB, 3, buf_, b##s_##3) }
;     ...
;   GL_LOAD(0, 0)
;   GL_LOAD(1, 1)
;   LDS_STORE(0, 0)
;   if (VAR != 4) __syncthreads();
; #pragma unroll
;   for (int kt = 0; kt < nk; kt += 2) {
;     if (kt + 2 < nk) { GL_LOAD(0, kt + 2) }
;     MMA_TILE(0)
;     LDS_STORE(1, 1)
;     if (VAR != 4) __syncthreads();
;     if (kt + 3 < nk) { GL_LOAD(1, kt + 3) }
;     MMA_TILE(1)
;     if (kt + 2 < nk) { LDS_STORE(0, 0) }
;     if (VAR != 4) __syncthreads();
	v_mfma_f32_16x16x32_f16 v[48:51], v[122:125], v[110:113], v[48:51]
	ds_read_b128 v[62:65], v16 offset:49152
	ds_read_b128 v[90:93], v21 offset:16384
	s_waitcnt lgkmcnt(0)
	v_mfma_f32_16x16x32_f16 v[36:39], v[62:65], v[90:93], v[36:39]
	ds_read_b128 v[74:77], v16 offset:51200
	ds_read_b128 v[110:113], v21 offset:18432
	s_waitcnt lgkmcnt(0)
	v_mfma_f32_16x16x32_f16 v[66:69], v[62:65], v[110:113], v[66:69]
	ds_read_b128 v[118:121], v16 offset:53248
	v_mfma_f32_16x16x32_f16 v[44:47], v[74:77], v[90:93], v[44:47]
	ds_read_b128 v[122:125], v16 offset:55296
	v_mfma_f32_16x16x32_f16 v[78:81], v[74:77], v[110:113], v[78:81]
	s_waitcnt lgkmcnt(1)
	v_mfma_f32_16x16x32_f16 v[82:85], v[118:121], v[90:93], v[82:85]
	v_mfma_f32_16x16x32_f16 v[86:89], v[118:121], v[110:113], v[86:89]
	s_waitcnt lgkmcnt(0)
	v_mfma_f32_16x16x32_f16 v[28:31], v[122:125], v[90:93], v[28:31]
	ds_read_b128 v[90:93], v21 offset:20480
	v_mfma_f32_16x16x32_f16 v[32:35], v[122:125], v[110:113], v[32:35]
	ds_read_b128 v[110:113], v21 offset:22528
	s_waitcnt lgkmcnt(1)
	v_mfma_f32_16x16x32_f16 v[98:101], v[62:65], v[90:93], v[98:101]
	s_waitcnt lgkmcnt(0)
	v_mfma_f32_16x16x32_f16 v[52:55], v[62:65], v[110:113], v[52:55]
	ds_read_b128 v[62:65], v22 offset:49152
	v_mfma_f32_16x16x32_f16 v[102:105], v[74:77], v[90:93], v[102:105]
	v_mfma_f32_16x16x32_f16 v[24:27], v[74:77], v[110:113], v[24:27]
	ds_read_b128 v[74:77], v22 offset:51200
	v_mfma_f32_16x16x32_f16 v[114:117], v[118:121], v[90:93], v[114:117]
	s_waitcnt vmcnt(7)
	ds_write_b128 v17, v[58:61]
	s_waitcnt vmcnt(6)
	ds_write_b128 v18, v[106:109]
	v_mfma_f32_16x16x32_f16 v[40:43], v[118:121], v[110:113], v[40:43]
	ds_read_b128 v[118:121], v22 offset:53248
	s_waitcnt vmcnt(5)
	ds_write_b128 v19, v[134:137]
	v_mfma_f32_16x16x32_f16 v[70:73], v[122:125], v[90:93], v[70:73]
	ds_read_b128 v[90:93], v23 offset:16384
	v_mfma_f32_16x16x32_f16 v[48:51], v[122:125], v[110:113], v[48:51]
	ds_read_b128 v[110:113], v23 offset:18432
	s_waitcnt lgkmcnt(1)
	v_mfma_f32_16x16x32_f16 v[36:39], v[62:65], v[90:93], v[36:39]
	ds_read_b128 v[122:125], v22 offset:55296
	s_waitcnt lgkmcnt(1)
	v_mfma_f32_16x16x32_f16 v[66:69], v[62:65], v[110:113], v[66:69]
	s_waitcnt vmcnt(4)
	ds_write_b128 v20, v[158:161]
	v_mfma_f32_16x16x32_f16 v[44:47], v[74:77], v[90:93], v[44:47]
	s_waitcnt vmcnt(3)
	ds_write_b128 v17, v[94:97] offset:32768
	v_mfma_f32_16x16x32_f16 v[78:81], v[74:77], v[110:113], v[78:81]
	s_waitcnt vmcnt(2)
	ds_write_b128 v18, v[162:165] offset:32768
	v_mfma_f32_16x16x32_f16 v[82:85], v[118:121], v[90:93], v[82:85]
	s_waitcnt vmcnt(1)
	ds_write_b128 v19, v[166:169] offset:32768
	v_mfma_f32_16x16x32_f16 v[86:89], v[118:121], v[110:113], v[86:89]
	s_waitcnt vmcnt(0)
	ds_write_b128 v20, v[190:193] offset:32768
	s_waitcnt lgkmcnt(5)
	v_mfma_f32_16x16x32_f16 v[28:31], v[122:125], v[90:93], v[28:31]
	ds_read_b128 v[90:93], v23 offset:20480
	v_mfma_f32_16x16x32_f16 v[32:35], v[122:125], v[110:113], v[32:35]
	ds_read_b128 v[110:113], v23 offset:22528
	s_waitcnt lgkmcnt(1)
	v_mfma_f32_16x16x32_f16 v[98:101], v[62:65], v[90:93], v[98:101]
	s_waitcnt lgkmcnt(0)
	v_mfma_f32_16x16x32_f16 v[52:55], v[62:65], v[110:113], v[52:55]
	global_load_dwordx4 v[62:65], v[0:1], off offset:896
	v_mfma_f32_16x16x32_f16 v[102:105], v[74:77], v[90:93], v[102:105]
	v_mfma_f32_16x16x32_f16 v[24:27], v[74:77], v[110:113], v[24:27]
	v_mfma_f32_16x16x32_f16 v[114:117], v[118:121], v[90:93], v[114:117]
	v_mfma_f32_16x16x32_f16 v[40:43], v[118:121], v[110:113], v[40:43]
	v_mfma_f32_16x16x32_f16 v[70:73], v[122:125], v[90:93], v[70:73]
	global_load_dwordx4 v[90:93], v[2:3], off offset:896
	global_load_dwordx4 v[126:129], v[4:5], off offset:896
	global_load_dwordx4 v[130:133], v[14:15], off offset:896
	global_load_dwordx4 v[74:77], v[10:11], off offset:896
	global_load_dwordx4 v[138:141], v[12:13], off offset:896
	global_load_dwordx4 v[142:145], v[8:9], off offset:896
	global_load_dwordx4 v[154:157], v[6:7], off offset:896
	s_waitcnt lgkmcnt(0)
	s_barrier
	v_mfma_f32_16x16x32_f16 v[48:51], v[122:125], v[110:113], v[48:51]
	ds_read_b128 v[58:61], v16 offset:32768
	ds_read_b128 v[106:109], v21
	s_waitcnt lgkmcnt(0)
	v_mfma_f32_16x16x32_f16 v[36:39], v[58:61], v[106:109], v[36:39]
	ds_read_b128 v[94:97], v16 offset:34816
	ds_read_b128 v[110:113], v21 offset:2048
	s_waitcnt lgkmcnt(0)
	v_mfma_f32_16x16x32_f16 v[66:69], v[58:61], v[110:113], v[66:69]
	ds_read_b128 v[118:121], v16 offset:36864
	v_mfma_f32_16x16x32_f16 v[44:47], v[94:97], v[106:109], v[44:47]
	ds_read_b128 v[122:125], v16 offset:38912
	v_mfma_f32_16x16x32_f16 v[78:81], v[94:97], v[110:113], v[78:81]
	s_waitcnt lgkmcnt(1)
	v_mfma_f32_16x16x32_f16 v[82:85], v[118:121], v[106:109], v[82:85]
	v_mfma_f32_16x16x32_f16 v[86:89], v[118:121], v[110:113], v[86:89]
	s_waitcnt lgkmcnt(0)
	v_mfma_f32_16x16x32_f16 v[28:31], v[122:125], v[106:109], v[28:31]
	ds_read_b128 v[106:109], v21 offset:4096
	v_mfma_f32_16x16x32_f16 v[32:35], v[122:125], v[110:113], v[32:35]
	ds_read_b128 v[110:113], v21 offset:6144
	s_waitcnt lgkmcnt(1)
	v_mfma_f32_16x16x32_f16 v[98:101], v[58:61], v[106:109], v[98:101]
	s_waitcnt lgkmcnt(0)
	v_mfma_f32_16x16x32_f16 v[52:55], v[58:61], v[110:113], v[52:55]
	ds_read_b128 v[58:61], v22 offset:32768
	v_mfma_f32_16x16x32_f16 v[102:105], v[94:97], v[106:109], v[102:105]
	v_mfma_f32_16x16x32_f16 v[24:27], v[94:97], v[110:113], v[24:27]
	ds_read_b128 v[94:97], v22 offset:34816
	v_mfma_f32_16x16x32_f16 v[114:117], v[118:121], v[106:109], v[114:117]
	s_waitcnt vmcnt(7)
	ds_write_b128 v17, v[62:65] offset:16384
	s_waitcnt vmcnt(6)
	ds_write_b128 v18, v[90:93] offset:16384
	v_mfma_f32_16x16x32_f16 v[40:43], v[118:121], v[110:113], v[40:43]
	ds_read_b128 v[118:121], v22 offset:36864
	s_waitcnt vmcnt(5)
; #define GL_LOAD(s_, kt_) if (VAR != 1) { a##s_##0 = GL_A(0, kt_); a##s_##1 = GL_A(1, kt_); a##s_##2 = GL_A(2, kt_); a##s_##3 = GL_A(3, kt_); b##s_##0 = GL_B(0, kt_); b##s_##1 = GL_B(1, kt_); b##s_##2 = GL_B(2, kt_); b##s_##3 = GL_B(3, kt_); }
; #define LDS_STORE(s_, buf_) if (VAR != 2) { LDS_ST1(sA, 0, buf_, a##s_##0) LDS_ST1(sA, 1, buf_, a##s_##1) LDS_ST1(sA, 2, buf_, a##s_##2) LDS_ST1(sA, 3, buf_, a##s_##3) LDS_ST1(sB, 0, buf_, b##s_##0) LDS_ST1(sB, 1, buf_, b##s_##1) LDS_ST1(sB, 2, buf_, b##s_##2) LDS_ST1(sB, 3, buf_, b##s_##3) }
;     ...
;   GL_LOAD(0, 0)
;   GL_LOAD(1, 1)
;   LDS_STORE(0, 0)
;   if (VAR != 4) __syncthreads();
; #pragma unroll
;   for (int kt = 0; kt < nk; kt += 2) {
;     if (kt + 2 < nk) { GL_LOAD(0, kt + 2) }
;     MMA_TILE(0)
;     LDS_STORE(1, 1)
;     if (VAR != 4) __syncthreads();
;     if (kt + 3 < nk) { GL_LOAD(1, kt + 3) }
;     MMA_TILE(1)
;     if (kt + 2 < nk) { LDS_STORE(0, 0) }
;     if (VAR != 4) __syncthreads();
	ds_write_b128 v19, v[126:129] offset:16384
	v_mfma_f32_16x16x32_f16 v[70:73], v[122:125], v[106:109], v[70:73]
	ds_read_b128 v[106:109], v23
	v_mfma_f32_16x16x32_f16 v[48:51], v[122:125], v[110:113], v[48:51]
	ds_read_b128 v[110:113], v23 offset:2048
	s_waitcnt lgkmcnt(1)
	v_mfma_f32_16x16x32_f16 v[36:39], v[58:61], v[106:109], v[36:39]
	ds_read_b128 v[122:125], v22 offset:38912
	s_waitcnt lgkmcnt(1)
	v_mfma_f32_16x16x32_f16 v[66:69], v[58:61], v[110:113], v[66:69]
	s_waitcnt vmcnt(4)
	ds_write_b128 v20, v[130:133] offset:16384
	v_mfma_f32_16x16x32_f16 v[44:47], v[94:97], v[106:109], v[44:47]
	s_waitcnt vmcnt(3)
	ds_write_b128 v17, v[74:77] offset:49152
	v_mfma_f32_16x16x32_f16 v[78:81], v[94:97], v[110:113], v[78:81]
	s_waitcnt vmcnt(2)
	ds_write_b128 v18, v[138:141] offset:49152
	v_mfma_f32_16x16x32_f16 v[82:85], v[118:121], v[106:109], v[82:85]
	s_waitcnt vmcnt(1)
	ds_write_b128 v19, v[142:145] offset:49152
	v_mfma_f32_16x16x32_f16 v[86:89], v[118:121], v[110:113], v[86:89]
	s_waitcnt vmcnt(0)
	ds_write_b128 v20, v[154:157] offset:49152
	s_waitcnt lgkmcnt(5)
	v_mfma_f32_16x16x32_f16 v[28:31], v[122:125], v[106:109], v[28:31]
	ds_read_b128 v[106:109], v23 offset:4096
	v_mfma_f32_16x16x32_f16 v[32:35], v[122:125], v[110:113], v[32:35]
	ds_read_b128 v[110:113], v23 offset:6144
	s_waitcnt lgkmcnt(1)
	v_mfma_f32_16x16x32_f16 v[98:101], v[58:61], v[106:109], v[98:101]
	s_waitcnt lgkmcnt(0)
	v_mfma_f32_16x16x32_f16 v[52:55], v[58:61], v[110:113], v[52:55]
	global_load_dwordx4 v[58:61], v[0:1], off offset:1024
	v_mfma_f32_16x16x32_f16 v[102:105], v[94:97], v[106:109], v[102:105]
	v_mfma_f32_16x16x32_f16 v[24:27], v[94:97], v[110:113], v[24:27]
	v_mfma_f32_16x16x32_f16 v[114:117], v[118:121], v[106:109], v[114:117]
	v_mfma_f32_16x16x32_f16 v[40:43], v[118:121], v[110:113], v[40:43]
	v_mfma_f32_16x16x32_f16 v[70:73], v[122:125], v[106:109], v[70:73]
	global_load_dwordx4 v[106:109], v[2:3], off offset:1024
	global_load_dwordx4 v[134:137], v[4:5], off offset:1024
	global_load_dwordx4 v[158:161], v[14:15], off offset:1024
	global_load_dwordx4 v[94:97], v[10:11], off offset:1024
	global_load_dwordx4 v[162:165], v[12:13], off offset:1024
	global_load_dwordx4 v[166:169], v[8:9], off offset:1024
	global_load_dwordx4 v[190:193], v[6:7], off offset:1024
	s_waitcnt lgkmcnt(0)
	s_barrier
	v_mfma_f32_16x16x32_f16 v[48:51], v[122:125], v[110:113], v[48:51]
	ds_read_b128 v[62:65], v16 offset:49152
	ds_read_b128 v[90:93], v21 offset:16384
	s_waitcnt lgkmcnt(0)
	v_mfma_f32_16x16x32_f16 v[36:39], v[62:65], v[90:93], v[36:39]
	ds_read_b128 v[74:77], v16 offset:51200
	ds_read_b128 v[110:113], v21 offset:18432
	s_waitcnt lgkmcnt(0)
	v_mfma_f32_16x16x32_f16 v[66:69], v[62:65], v[110:113], v[66:69]
	ds_read_b128 v[118:121], v16 offset:53248
	v_mfma_f32_16x16x32_f16 v[44:47], v[74:77], v[90:93], v[44:47]
	ds_read_b128 v[122:125], v16 offset:55296
	v_mfma_f32_16x16x32_f16 v[78:81], v[74:77], v[110:113], v[78:81]
	s_waitcnt lgkmcnt(1)
	v_mfma_f32_16x16x32_f16 v[82:85], v[118:121], v[90:93], v[82:85]
	v_mfma_f32_16x16x32_f16 v[86:89], v[118:121], v[110:113], v[86:89]
	s_waitcnt lgkmcnt(0)
	v_mfma_f32_16x16x32_f16 v[28:31], v[122:125], v[90:93], v[28:31]
	ds_read_b128 v[90:93], v21 offset:20480
	v_mfma_f32_16x16x32_f16 v[32:35], v[122:125], v[110:113], v[32:35]
	ds_read_b128 v[110:113], v21 offset:22528
	s_waitcnt lgkmcnt(1)
	v_mfma_f32_16x16x32_f16 v[98:101], v[62:65], v[90:93], v[98:101]
	s_waitcnt lgkmcnt(0)
	v_mfma_f32_16x16x32_f16 v[52:55], v[62:65], v[110:113], v[52:55]
	ds_read_b128 v[62:65], v22 offset:49152
	v_mfma_f32_16x16x32_f16 v[102:105], v[74:77], v[90:93], v[102:105]
	v_mfma_f32_16x16x32_f16 v[24:27], v[74:77], v[110:113], v[24:27]
	ds_read_b128 v[74:77], v22 offset:51200
	v_mfma_f32_16x16x32_f16 v[114:117], v[118:121], v[90:93], v[114:117]
	s_waitcnt vmcnt(7)
	ds_write_b128 v17, v[58:61]
	s_waitcnt vmcnt(6)
	ds_write_b128 v18, v[106:109]
	v_mfma_f32_16x16x32_f16 v[40:43], v[118:121], v[110:113], v[40:43]
	ds_read_b128 v[118:121], v22 offset:53248
	s_waitcnt vmcnt(5)
	ds_write_b128 v19, v[134:137]
	v_mfma_f32_16x16x32_f16 v[70:73], v[122:125], v[90:93], v[70:73]
	ds_read_b128 v[90:93], v23 offset:16384
	v_mfma_f32_16x16x32_f16 v[48:51], v[122:125], v[110:113], v[48:51]
	ds_read_b128 v[110:113], v23 offset:18432
	s_waitcnt lgkmcnt(1)
	v_mfma_f32_16x16x32_f16 v[36:39], v[62:65], v[90:93], v[36:39]
	ds_read_b128 v[122:125], v22 offset:55296
	s_waitcnt lgkmcnt(1)
	v_mfma_f32_16x16x32_f16 v[66:69], v[62:65], v[110:113], v[66:69]
	s_waitcnt vmcnt(4)
	ds_write_b128 v20, v[158:161]
	v_mfma_f32_16x16x32_f16 v[44:47], v[74:77], v[90:93], v[44:47]
	s_waitcnt vmcnt(3)
	ds_write_b128 v17, v[94:97] offset:32768
	v_mfma_f32_16x16x32_f16 v[78:81], v[74:77], v[110:113], v[78:81]
	s_waitcnt vmcnt(2)
	ds_write_b128 v18, v[162:165] offset:32768
	v_mfma_f32_16x16x32_f16 v[82:85], v[118:121], v[90:93], v[82:85]
	s_waitcnt vmcnt(1)
	ds_write_b128 v19, v[166:169] offset:32768
	v_mfma_f32_16x16x32_f16 v[86:89], v[118:121], v[110:113], v[86:89]
	s_waitcnt vmcnt(0)
	ds_write_b128 v20, v[190:193] offset:32768
	s_waitcnt lgkmcnt(5)
	v_mfma_f32_16x16x32_f16 v[28:31], v[122:125], v[90:93], v[28:31]
	ds_read_b128 v[90:93], v23 offset:20480
	v_mfma_f32_16x16x32_f16 v[32:35], v[122:125], v[110:113], v[32:35]
	ds_read_b128 v[110:113], v23 offset:22528
	s_waitcnt lgkmcnt(1)
	v_mfma_f32_16x16x32_f16 v[98:101], v[62:65], v[90:93], v[98:101]
	s_waitcnt lgkmcnt(0)
	v_mfma_f32_16x16x32_f16 v[52:55], v[62:65], v[110:113], v[52:55]
	global_load_dwordx4 v[62:65], v[0:1], off offset:1152
	v_mfma_f32_16x16x32_f16 v[102:105], v[74:77], v[90:93], v[102:105]
	v_mfma_f32_16x16x32_f16 v[24:27], v[74:77], v[110:113], v[24:27]
	v_mfma_f32_16x16x32_f16 v[114:117], v[118:121], v[90:93], v[114:117]
	v_mfma_f32_16x16x32_f16 v[40:43], v[118:121], v[110:113], v[40:43]
	v_mfma_f32_16x16x32_f16 v[70:73], v[122:125], v[90:93], v[70:73]
	global_load_dwordx4 v[90:93], v[2:3], off offset:1152
	global_load_dwordx4 v[126:129], v[4:5], off offset:1152
	global_load_dwordx4 v[130:133], v[14:15], off offset:1152
	global_load_dwordx4 v[74:77], v[10:11], off offset:1152
	global_load_dwordx4 v[138:141], v[12:13], off offset:1152
	global_load_dwordx4 v[142:145], v[8:9], off offset:1152
	global_load_dwordx4 v[154:157], v[6:7], off offset:1152
	s_waitcnt lgkmcnt(0)
	s_barrier
; #define GL_LOAD(s_, kt_) if (VAR != 1) { a##s_##0 = GL_A(0, kt_); a##s_##1 = GL_A(1, kt_); a##s_##2 = GL_A(2, kt_); a##s_##3 = GL_A(3, kt_); b##s_##0 = GL_B(0, kt_); b##s_##1 = GL_B(1, kt_); b##s_##2 = GL_B(2, kt_); b##s_##3 = GL_B(3, kt_); }
; #define LDS_STORE(s_, buf_) if (VAR != 2) { LDS_ST1(sA, 0, buf_, a##s_##0) LDS_ST1(sA, 1, buf_, a##s_##1) LDS_ST1(sA, 2, buf_, a##s_##2) LDS_ST1(sA, 3, buf_, a##s_##3) LDS_ST1(sB, 0, buf_, b##s_##0) LDS_ST1(sB, 1, buf_, b##s_##1) LDS_ST1(sB, 2, buf_, b##s_##2) LDS_ST1(sB, 3, buf_, b##s_##3) }
;     ...
;   GL_LOAD(0, 0)
;   GL_LOAD(1, 1)
;   LDS_STORE(0, 0)
;   if (VAR != 4) __syncthreads();
; #pragma unroll
;   for (int kt = 0; kt < nk; kt += 2) {
;     if (kt + 2 < nk) { GL_LOAD(0, kt + 2) }
;     MMA_TILE(0)
;     LDS_STORE(1, 1)
;     if (VAR != 4) __syncthreads();
;     if (kt + 3 < nk) { GL_LOAD(1, kt + 3) }
;     MMA_TILE(1)
;     if (kt + 2 < nk) { LDS_STORE(0, 0) }
;     if (VAR != 4) __syncthreads();
	v_mfma_f32_16x16x32_f16 v[48:51], v[122:125], v[110:113], v[48:51]
	ds_read_b128 v[58:61], v16 offset:32768
	ds_read_b128 v[106:109], v21
	s_waitcnt lgkmcnt(0)
	v_mfma_f32_16x16x32_f16 v[36:39], v[58:61], v[106:109], v[36:39]
	ds_read_b128 v[94:97], v16 offset:34816
	ds_read_b128 v[110:113], v21 offset:2048
	s_waitcnt lgkmcnt(0)
	v_mfma_f32_16x16x32_f16 v[66:69], v[58:61], v[110:113], v[66:69]
	ds_read_b128 v[118:121], v16 offset:36864
	v_mfma_f32_16x16x32_f16 v[44:47], v[94:97], v[106:109], v[44:47]
	ds_read_b128 v[122:125], v16 offset:38912
	v_mfma_f32_16x16x32_f16 v[78:81], v[94:97], v[110:113], v[78:81]
	s_waitcnt lgkmcnt(1)
	v_mfma_f32_16x16x32_f16 v[82:85], v[118:121], v[106:109], v[82:85]
	v_mfma_f32_16x16x32_f16 v[86:89], v[118:121], v[110:113], v[86:89]
	s_waitcnt lgkmcnt(0)
	v_mfma_f32_16x16x32_f16 v[28:31], v[122:125], v[106:109], v[28:31]
	ds_read_b128 v[106:109], v21 offset:4096
	v_mfma_f32_16x16x32_f16 v[32:35], v[122:125], v[110:113], v[32:35]
	ds_read_b128 v[110:113], v21 offset:6144
	s_waitcnt lgkmcnt(1)
	v_mfma_f32_16x16x32_f16 v[98:101], v[58:61], v[106:109], v[98:101]
	s_waitcnt lgkmcnt(0)
	v_mfma_f32_16x16x32_f16 v[52:55], v[58:61], v[110:113], v[52:55]
	ds_read_b128 v[58:61], v22 offset:32768
	v_mfma_f32_16x16x32_f16 v[102:105], v[94:97], v[106:109], v[102:105]
	v_mfma_f32_16x16x32_f16 v[24:27], v[94:97], v[110:113], v[24:27]
	ds_read_b128 v[94:97], v22 offset:34816
	v_mfma_f32_16x16x32_f16 v[114:117], v[118:121], v[106:109], v[114:117]
	s_waitcnt vmcnt(7)
	ds_write_b128 v17, v[62:65] offset:16384
	s_waitcnt vmcnt(6)
	ds_write_b128 v18, v[90:93] offset:16384
	v_mfma_f32_16x16x32_f16 v[40:43], v[118:121], v[110:113], v[40:43]
	ds_read_b128 v[118:121], v22 offset:36864
	s_waitcnt vmcnt(5)
	ds_write_b128 v19, v[126:129] offset:16384
	v_mfma_f32_16x16x32_f16 v[70:73], v[122:125], v[106:109], v[70:73]
	ds_read_b128 v[106:109], v23
	v_mfma_f32_16x16x32_f16 v[48:51], v[122:125], v[110:113], v[48:51]
	ds_read_b128 v[110:113], v23 offset:2048
	s_waitcnt lgkmcnt(1)
	v_mfma_f32_16x16x32_f16 v[36:39], v[58:61], v[106:109], v[36:39]
	ds_read_b128 v[122:125], v22 offset:38912
	s_waitcnt lgkmcnt(1)
	v_mfma_f32_16x16x32_f16 v[66:69], v[58:61], v[110:113], v[66:69]
	s_waitcnt vmcnt(4)
	ds_write_b128 v20, v[130:133] offset:16384
	v_mfma_f32_16x16x32_f16 v[44:47], v[94:97], v[106:109], v[44:47]
	s_waitcnt vmcnt(3)
	ds_write_b128 v17, v[74:77] offset:49152
	v_mfma_f32_16x16x32_f16 v[78:81], v[94:97], v[110:113], v[78:81]
	s_waitcnt vmcnt(2)
	ds_write_b128 v18, v[138:141] offset:49152
	v_mfma_f32_16x16x32_f16 v[82:85], v[118:121], v[106:109], v[82:85]
	s_waitcnt vmcnt(1)
	ds_write_b128 v19, v[142:145] offset:49152
	v_mfma_f32_16x16x32_f16 v[86:89], v[118:121], v[110:113], v[86:89]
	s_waitcnt vmcnt(0)
	ds_write_b128 v20, v[154:157] offset:49152
	s_waitcnt lgkmcnt(5)
	v_mfma_f32_16x16x32_f16 v[28:31], v[122:125], v[106:109], v[28:31]
	ds_read_b128 v[106:109], v23 offset:4096
	v_mfma_f32_16x16x32_f16 v[32:35], v[122:125], v[110:113], v[32:35]
	ds_read_b128 v[110:113], v23 offset:6144
	s_waitcnt lgkmcnt(1)
	v_mfma_f32_16x16x32_f16 v[98:101], v[58:61], v[106:109], v[98:101]
	s_waitcnt lgkmcnt(0)
	v_mfma_f32_16x16x32_f16 v[52:55], v[58:61], v[110:113], v[52:55]
	global_load_dwordx4 v[58:61], v[0:1], off offset:1280
	v_mfma_f32_16x16x32_f16 v[102:105], v[94:97], v[106:109], v[102:105]
	v_mfma_f32_16x16x32_f16 v[24:27], v[94:97], v[110:113], v[24:27]
	v_mfma_f32_16x16x32_f16 v[114:117], v[118:121], v[106:109], v[114:117]
	v_mfma_f32_16x16x32_f16 v[40:43], v[118:121], v[110:113], v[40:43]
	v_mfma_f32_16x16x32_f16 v[70:73], v[122:125], v[106:109], v[70:73]
	global_load_dwordx4 v[106:109], v[2:3], off offset:1280
	global_load_dwordx4 v[134:137], v[4:5], off offset:1280
	global_load_dwordx4 v[158:161], v[14:15], off offset:1280
	global_load_dwordx4 v[94:97], v[10:11], off offset:1280
	global_load_dwordx4 v[162:165], v[12:13], off offset:1280
	global_load_dwordx4 v[166:169], v[8:9], off offset:1280
	global_load_dwordx4 v[190:193], v[6:7], off offset:1280
	s_waitcnt lgkmcnt(0)
	s_barrier
	v_mfma_f32_16x16x32_f16 v[48:51], v[122:125], v[110:113], v[48:51]
	ds_read_b128 v[62:65], v16 offset:49152
	ds_read_b128 v[90:93], v21 offset:16384
	s_waitcnt lgkmcnt(0)
	v_mfma_f32_16x16x32_f16 v[36:39], v[62:65], v[90:93], v[36:39]
	ds_read_b128 v[74:77], v16 offset:51200
	ds_read_b128 v[110:113], v21 offset:18432
	s_waitcnt lgkmcnt(0)
	v_mfma_f32_16x16x32_f16 v[66:69], v[62:65], v[110:113], v[66:69]
	ds_read_b128 v[118:121], v16 offset:53248
	v_mfma_f32_16x16x32_f16 v[44:47], v[74:77], v[90:93], v[44:47]
	ds_read_b128 v[122:125], v16 offset:55296
	v_mfma_f32_16x16x32_f16 v[78:81], v[74:77], v[110:113], v[78:81]
	s_waitcnt lgkmcnt(1)
	v_mfma_f32_16x16x32_f16 v[82:85], v[118:121], v[90:93], v[82:85]
	v_mfma_f32_16x16x32_f16 v[86:89], v[118:121], v[110:113], v[86:89]
	s_waitcnt lgkmcnt(0)
	v_mfma_f32_16x16x32_f16 v[28:31], v[122:125], v[90:93], v[28:31]
	ds_read_b128 v[90:93], v21 offset:20480
	v_mfma_f32_16x16x32_f16 v[32:35], v[122:125], v[110:113], v[32:35]
	ds_read_b128 v[110:113], v21 offset:22528
	s_waitcnt lgkmcnt(1)
	v_mfma_f32_16x16x32_f16 v[98:101], v[62:65], v[90:93], v[98:101]
	s_waitcnt lgkmcnt(0)
	v_mfma_f32_16x16x32_f16 v[52:55], v[62:65], v[110:113], v[52:55]
	ds_read_b128 v[62:65], v22 offset:49152
	v_mfma_f32_16x16x32_f16 v[102:105], v[74:77], v[90:93], v[102:105]
	v_mfma_f32_16x16x32_f16 v[24:27], v[74:77], v[110:113], v[24:27]
	ds_read_b128 v[74:77], v22 offset:51200
	v_mfma_f32_16x16x32_f16 v[114:117], v[118:121], v[90:93], v[114:117]
	s_waitcnt vmcnt(7)
	ds_write_b128 v17, v[58:61]
	s_waitcnt vmcnt(6)
; #define GL_LOAD(s_, kt_) if (VAR != 1) { a##s_##0 = GL_A(0, kt_); a##s_##1 = GL_A(1, kt_); a##s_##2 = GL_A(2, kt_); a##s_##3 = GL_A(3, kt_); b##s_##0 = GL_B(0, kt_); b##s_##1 = GL_B(1, kt_); b##s_##2 = GL_B(2, kt_); b##s_##3 = GL_B(3, kt_); }
; #define LDS_STORE(s_, buf_) if (VAR != 2) { LDS_ST1(sA, 0, buf_, a##s_##0) LDS_ST1(sA, 1, buf_, a##s_##1) LDS_ST1(sA, 2, buf_, a##s_##2) LDS_ST1(sA, 3, buf_, a##s_##3) LDS_ST1(sB, 0, buf_, b##s_##0) LDS_ST1(sB, 1, buf_, b##s_##1) LDS_ST1(sB, 2, buf_, b##s_##2) LDS_ST1(sB, 3, buf_, b##s_##3) }
;     ...
;   GL_LOAD(0, 0)
;   GL_LOAD(1, 1)
;   LDS_STORE(0, 0)
;   if (VAR != 4) __syncthreads();
; #pragma unroll
;   for (int kt = 0; kt < nk; kt += 2) {
;     if (kt + 2 < nk) { GL_LOAD(0, kt + 2) }
;     MMA_TILE(0)
;     LDS_STORE(1, 1)
;     if (VAR != 4) __syncthreads();
;     if (kt + 3 < nk) { GL_LOAD(1, kt + 3) }
;     MMA_TILE(1)
;     if (kt + 2 < nk) { LDS_STORE(0, 0) }
;     if (VAR != 4) __syncthreads();
	ds_write_b128 v18, v[106:109]
	v_mfma_f32_16x16x32_f16 v[40:43], v[118:121], v[110:113], v[40:43]
	ds_read_b128 v[118:121], v22 offset:53248
	s_waitcnt vmcnt(5)
	ds_write_b128 v19, v[134:137]
	v_mfma_f32_16x16x32_f16 v[70:73], v[122:125], v[90:93], v[70:73]
	ds_read_b128 v[90:93], v23 offset:16384
	v_mfma_f32_16x16x32_f16 v[48:51], v[122:125], v[110:113], v[48:51]
	ds_read_b128 v[110:113], v23 offset:18432
	s_waitcnt lgkmcnt(1)
	v_mfma_f32_16x16x32_f16 v[36:39], v[62:65], v[90:93], v[36:39]
	ds_read_b128 v[122:125], v22 offset:55296
	s_waitcnt lgkmcnt(1)
	v_mfma_f32_16x16x32_f16 v[66:69], v[62:65], v[110:113], v[66:69]
	s_waitcnt vmcnt(4)
	ds_write_b128 v20, v[158:161]
	v_mfma_f32_16x16x32_f16 v[44:47], v[74:77], v[90:93], v[44:47]
	s_waitcnt vmcnt(3)
	ds_write_b128 v17, v[94:97] offset:32768
	v_mfma_f32_16x16x32_f16 v[78:81], v[74:77], v[110:113], v[78:81]
	s_waitcnt vmcnt(2)
	ds_write_b128 v18, v[162:165] offset:32768
	v_mfma_f32_16x16x32_f16 v[82:85], v[118:121], v[90:93], v[82:85]
	s_waitcnt vmcnt(1)
	ds_write_b128 v19, v[166:169] offset:32768
	v_mfma_f32_16x16x32_f16 v[86:89], v[118:121], v[110:113], v[86:89]
	s_waitcnt vmcnt(0)
	ds_write_b128 v20, v[190:193] offset:32768
	s_waitcnt lgkmcnt(5)
	v_mfma_f32_16x16x32_f16 v[28:31], v[122:125], v[90:93], v[28:31]
	ds_read_b128 v[90:93], v23 offset:20480
	v_mfma_f32_16x16x32_f16 v[32:35], v[122:125], v[110:113], v[32:35]
	ds_read_b128 v[110:113], v23 offset:22528
	s_waitcnt lgkmcnt(1)
	v_mfma_f32_16x16x32_f16 v[98:101], v[62:65], v[90:93], v[98:101]
	s_waitcnt lgkmcnt(0)
	v_mfma_f32_16x16x32_f16 v[52:55], v[62:65], v[110:113], v[52:55]
	global_load_dwordx4 v[62:65], v[0:1], off offset:1408
	v_mfma_f32_16x16x32_f16 v[102:105], v[74:77], v[90:93], v[102:105]
	v_mfma_f32_16x16x32_f16 v[24:27], v[74:77], v[110:113], v[24:27]
	v_mfma_f32_16x16x32_f16 v[114:117], v[118:121], v[90:93], v[114:117]
	v_mfma_f32_16x16x32_f16 v[40:43], v[118:121], v[110:113], v[40:43]
	v_mfma_f32_16x16x32_f16 v[70:73], v[122:125], v[90:93], v[70:73]
	global_load_dwordx4 v[90:93], v[2:3], off offset:1408
	global_load_dwordx4 v[126:129], v[4:5], off offset:1408
	global_load_dwordx4 v[130:133], v[14:15], off offset:1408
	global_load_dwordx4 v[74:77], v[10:11], off offset:1408
	global_load_dwordx4 v[138:141], v[12:13], off offset:1408
	global_load_dwordx4 v[142:145], v[8:9], off offset:1408
	global_load_dwordx4 v[154:157], v[6:7], off offset:1408
	s_waitcnt lgkmcnt(0)
	s_barrier
	v_mfma_f32_16x16x32_f16 v[48:51], v[122:125], v[110:113], v[48:51]
	ds_read_b128 v[58:61], v16 offset:32768
	ds_read_b128 v[106:109], v21
	s_waitcnt lgkmcnt(0)
	v_mfma_f32_16x16x32_f16 v[36:39], v[58:61], v[106:109], v[36:39]
	ds_read_b128 v[94:97], v16 offset:34816
	ds_read_b128 v[110:113], v21 offset:2048
	s_waitcnt lgkmcnt(0)
	v_mfma_f32_16x16x32_f16 v[66:69], v[58:61], v[110:113], v[66:69]
	ds_read_b128 v[118:121], v16 offset:36864
	v_mfma_f32_16x16x32_f16 v[44:47], v[94:97], v[106:109], v[44:47]
	ds_read_b128 v[122:125], v16 offset:38912
	v_mfma_f32_16x16x32_f16 v[78:81], v[94:97], v[110:113], v[78:81]
	s_waitcnt lgkmcnt(1)
	v_mfma_f32_16x16x32_f16 v[82:85], v[118:121], v[106:109], v[82:85]
	v_mfma_f32_16x16x32_f16 v[86:89], v[118:121], v[110:113], v[86:89]
	s_waitcnt lgkmcnt(0)
	v_mfma_f32_16x16x32_f16 v[28:31], v[122:125], v[106:109], v[28:31]
	ds_read_b128 v[106:109], v21 offset:4096
	v_mfma_f32_16x16x32_f16 v[32:35], v[122:125], v[110:113], v[32:35]
	ds_read_b128 v[110:113], v21 offset:6144
	s_waitcnt lgkmcnt(1)
	v_mfma_f32_16x16x32_f16 v[98:101], v[58:61], v[106:109], v[98:101]
	s_waitcnt lgkmcnt(0)
	v_mfma_f32_16x16x32_f16 v[52:55], v[58:61], v[110:113], v[52:55]
	ds_read_b128 v[58:61], v22 offset:32768
	v_mfma_f32_16x16x32_f16 v[102:105], v[94:97], v[106:109], v[102:105]
	v_mfma_f32_16x16x32_f16 v[24:27], v[94:97], v[110:113], v[24:27]
	ds_read_b128 v[94:97], v22 offset:34816
	v_mfma_f32_16x16x32_f16 v[114:117], v[118:121], v[106:109], v[114:117]
	s_waitcnt vmcnt(7)
	ds_write_b128 v17, v[62:65] offset:16384
	s_waitcnt vmcnt(6)
	ds_write_b128 v18, v[90:93] offset:16384
	v_mfma_f32_16x16x32_f16 v[40:43], v[118:121], v[110:113], v[40:43]
	ds_read_b128 v[118:121], v22 offset:36864
	s_waitcnt vmcnt(5)
	ds_write_b128 v19, v[126:129] offset:16384
	v_mfma_f32_16x16x32_f16 v[70:73], v[122:125], v[106:109], v[70:73]
	ds_read_b128 v[106:109], v23
	v_mfma_f32_16x16x32_f16 v[48:51], v[122:125], v[110:113], v[48:51]
	ds_read_b128 v[110:113], v23 offset:2048
	s_waitcnt lgkmcnt(1)
	v_mfma_f32_16x16x32_f16 v[36:39], v[58:61], v[106:109], v[36:39]
	ds_read_b128 v[122:125], v22 offset:38912
	s_waitcnt lgkmcnt(1)
	v_mfma_f32_16x16x32_f16 v[66:69], v[58:61], v[110:113], v[66:69]
	s_waitcnt vmcnt(4)
	ds_write_b128 v20, v[130:133] offset:16384
	v_mfma_f32_16x16x32_f16 v[44:47], v[94:97], v[106:109], v[44:47]
	s_waitcnt vmcnt(3)
	ds_write_b128 v17, v[74:77] offset:49152
	v_mfma_f32_16x16x32_f16 v[78:81], v[94:97], v[110:113], v[78:81]
	s_waitcnt vmcnt(2)
	ds_write_b128 v18, v[138:141] offset:49152
	v_mfma_f32_16x16x32_f16 v[82:85], v[118:121], v[106:109], v[82:85]
	s_waitcnt vmcnt(1)
	ds_write_b128 v19, v[142:145] offset:49152
	v_mfma_f32_16x16x32_f16 v[86:89], v[118:121], v[110:113], v[86:89]
	s_waitcnt vmcnt(0)
	ds_write_b128 v20, v[154:157] offset:49152
	s_waitcnt lgkmcnt(5)
	v_mfma_f32_16x16x32_f16 v[28:31], v[122:125], v[106:109], v[28:31]
	ds_read_b128 v[106:109], v23 offset:4096
	v_mfma_f32_16x16x32_f16 v[32:35], v[122:125], v[110:113], v[32:35]
	ds_read_b128 v[110:113], v23 offset:6144
	s_waitcnt lgkmcnt(1)
	v_mfma_f32_16x16x32_f16 v[98:101], v[58:61], v[106:109], v[98:101]
	s_waitcnt lgkmcnt(0)
	v_mfma_f32_16x16x32_f16 v[52:55], v[58:61], v[110:113], v[52:55]
	global_load_dwordx4 v[58:61], v[0:1], off offset:1536
	v_mfma_f32_16x16x32_f16 v[102:105], v[94:97], v[106:109], v[102:105]
	v_mfma_f32_16x16x32_f16 v[24:27], v[94:97], v[110:113], v[24:27]
	v_mfma_f32_16x16x32_f16 v[114:117], v[118:121], v[106:109], v[114:117]
	v_mfma_f32_16x16x32_f16 v[40:43], v[118:121], v[110:113], v[40:43]
	v_mfma_f32_16x16x32_f16 v[70:73], v[122:125], v[106:109], v[70:73]
	global_load_dwordx4 v[106:109], v[2:3], off offset:1536
	global_load_dwordx4 v[134:137], v[4:5], off offset:1536
	global_load_dwordx4 v[158:161], v[14:15], off offset:1536
	global_load_dwordx4 v[94:97], v[10:11], off offset:1536
	global_load_dwordx4 v[162:165], v[12:13], off offset:1536
	global_load_dwordx4 v[166:169], v[8:9], off offset:1536
	global_load_dwordx4 v[190:193], v[6:7], off offset:1536
	s_waitcnt lgkmcnt(0)
	s_barrier
; #define GL_LOAD(s_, kt_) if (VAR != 1) { a##s_##0 = GL_A(0, kt_); a##s_##1 = GL_A(1, kt_); a##s_##2 = GL_A(2, kt_); a##s_##3 = GL_A(3, kt_); b##s_##0 = GL_B(0, kt_); b##s_##1 = GL_B(1, kt_); b##s_##2 = GL_B(2, kt_); b##s_##3 = GL_B(3, kt_); }
; #define LDS_STORE(s_, buf_) if (VAR != 2) { LDS_ST1(sA, 0, buf_, a##s_##0) LDS_ST1(sA, 1, buf_, a##s_##1) LDS_ST1(sA, 2, buf_, a##s_##2) LDS_ST1(sA, 3, buf_, a##s_##3) LDS_ST1(sB, 0, buf_, b##s_##0) LDS_ST1(sB, 1, buf_, b##s_##1) LDS_ST1(sB, 2, buf_, b##s_##2) LDS_ST1(sB, 3, buf_, b##s_##3) }
;     ...
;   GL_LOAD(0, 0)
;   GL_LOAD(1, 1)
;   LDS_STORE(0, 0)
;   if (VAR != 4) __syncthreads();
; #pragma unroll
;   for (int kt = 0; kt < nk; kt += 2) {
;     if (kt + 2 < nk) { GL_LOAD(0, kt + 2) }
;     MMA_TILE(0)
;     LDS_STORE(1, 1)
;     if (VAR != 4) __syncthreads();
;     if (kt + 3 < nk) { GL_LOAD(1, kt + 3) }
;     MMA_TILE(1)
;     if (kt + 2 < nk) { LDS_STORE(0, 0) }
;     if (VAR != 4) __syncthreads();
	v_mfma_f32_16x16x32_f16 v[48:51], v[122:125], v[110:113], v[48:51]
	ds_read_b128 v[62:65], v16 offset:49152
	ds_read_b128 v[90:93], v21 offset:16384
	s_waitcnt lgkmcnt(0)
	v_mfma_f32_16x16x32_f16 v[36:39], v[62:65], v[90:93], v[36:39]
	ds_read_b128 v[74:77], v16 offset:51200
	ds_read_b128 v[110:113], v21 offset:18432
	s_waitcnt lgkmcnt(0)
	v_mfma_f32_16x16x32_f16 v[66:69], v[62:65], v[110:113], v[66:69]
	ds_read_b128 v[118:121], v16 offset:53248
	v_mfma_f32_16x16x32_f16 v[44:47], v[74:77], v[90:93], v[44:47]
	ds_read_b128 v[122:125], v16 offset:55296
	v_mfma_f32_16x16x32_f16 v[78:81], v[74:77], v[110:113], v[78:81]
	s_waitcnt lgkmcnt(1)
	v_mfma_f32_16x16x32_f16 v[82:85], v[118:121], v[90:93], v[82:85]
	v_mfma_f32_16x16x32_f16 v[86:89], v[118:121], v[110:113], v[86:89]
	s_waitcnt lgkmcnt(0)
	v_mfma_f32_16x16x32_f16 v[28:31], v[122:125], v[90:93], v[28:31]
	ds_read_b128 v[90:93], v21 offset:20480
	v_mfma_f32_16x16x32_f16 v[32:35], v[122:125], v[110:113], v[32:35]
	ds_read_b128 v[110:113], v21 offset:22528
	s_waitcnt lgkmcnt(1)
	v_mfma_f32_16x16x32_f16 v[98:101], v[62:65], v[90:93], v[98:101]
	s_waitcnt lgkmcnt(0)
	v_mfma_f32_16x16x32_f16 v[52:55], v[62:65], v[110:113], v[52:55]
	ds_read_b128 v[62:65], v22 offset:49152
	v_mfma_f32_16x16x32_f16 v[102:105], v[74:77], v[90:93], v[102:105]
	v_mfma_f32_16x16x32_f16 v[24:27], v[74:77], v[110:113], v[24:27]
	ds_read_b128 v[74:77], v22 offset:51200
	v_mfma_f32_16x16x32_f16 v[114:117], v[118:121], v[90:93], v[114:117]
	s_waitcnt vmcnt(7)
	ds_write_b128 v17, v[58:61]
	s_waitcnt vmcnt(6)
	ds_write_b128 v18, v[106:109]
	v_mfma_f32_16x16x32_f16 v[40:43], v[118:121], v[110:113], v[40:43]
	ds_read_b128 v[118:121], v22 offset:53248
	s_waitcnt vmcnt(5)
	ds_write_b128 v19, v[134:137]
	v_mfma_f32_16x16x32_f16 v[70:73], v[122:125], v[90:93], v[70:73]
	ds_read_b128 v[90:93], v23 offset:16384
	v_mfma_f32_16x16x32_f16 v[48:51], v[122:125], v[110:113], v[48:51]
	ds_read_b128 v[110:113], v23 offset:18432
	s_waitcnt lgkmcnt(1)
	v_mfma_f32_16x16x32_f16 v[36:39], v[62:65], v[90:93], v[36:39]
	ds_read_b128 v[122:125], v22 offset:55296
	s_waitcnt lgkmcnt(1)
	v_mfma_f32_16x16x32_f16 v[66:69], v[62:65], v[110:113], v[66:69]
	s_waitcnt vmcnt(4)
	ds_write_b128 v20, v[158:161]
	v_mfma_f32_16x16x32_f16 v[44:47], v[74:77], v[90:93], v[44:47]
	s_waitcnt vmcnt(3)
	ds_write_b128 v17, v[94:97] offset:32768
	v_mfma_f32_16x16x32_f16 v[78:81], v[74:77], v[110:113], v[78:81]
	s_waitcnt vmcnt(2)
	ds_write_b128 v18, v[162:165] offset:32768
	v_mfma_f32_16x16x32_f16 v[82:85], v[118:121], v[90:93], v[82:85]
	s_waitcnt vmcnt(1)
	ds_write_b128 v19, v[166:169] offset:32768
	v_mfma_f32_16x16x32_f16 v[86:89], v[118:121], v[110:113], v[86:89]
	s_waitcnt vmcnt(0)
	ds_write_b128 v20, v[190:193] offset:32768
	s_waitcnt lgkmcnt(5)
	v_mfma_f32_16x16x32_f16 v[28:31], v[122:125], v[90:93], v[28:31]
	ds_read_b128 v[90:93], v23 offset:20480
	v_mfma_f32_16x16x32_f16 v[32:35], v[122:125], v[110:113], v[32:35]
	ds_read_b128 v[110:113], v23 offset:22528
	s_waitcnt lgkmcnt(1)
	v_mfma_f32_16x16x32_f16 v[98:101], v[62:65], v[90:93], v[98:101]
	s_waitcnt lgkmcnt(0)
	v_mfma_f32_16x16x32_f16 v[52:55], v[62:65], v[110:113], v[52:55]
	global_load_dwordx4 v[62:65], v[0:1], off offset:1664
	v_mfma_f32_16x16x32_f16 v[102:105], v[74:77], v[90:93], v[102:105]
	v_mfma_f32_16x16x32_f16 v[24:27], v[74:77], v[110:113], v[24:27]
	v_mfma_f32_16x16x32_f16 v[114:117], v[118:121], v[90:93], v[114:117]
	v_mfma_f32_16x16x32_f16 v[40:43], v[118:121], v[110:113], v[40:43]
	v_mfma_f32_16x16x32_f16 v[70:73], v[122:125], v[90:93], v[70:73]
	global_load_dwordx4 v[90:93], v[2:3], off offset:1664
	global_load_dwordx4 v[126:129], v[4:5], off offset:1664
	global_load_dwordx4 v[130:133], v[14:15], off offset:1664
	global_load_dwordx4 v[74:77], v[10:11], off offset:1664
	global_load_dwordx4 v[138:141], v[12:13], off offset:1664
	global_load_dwordx4 v[142:145], v[8:9], off offset:1664
	global_load_dwordx4 v[154:157], v[6:7], off offset:1664
	s_waitcnt lgkmcnt(0)
	s_barrier
	v_mfma_f32_16x16x32_f16 v[48:51], v[122:125], v[110:113], v[48:51]
	ds_read_b128 v[58:61], v16 offset:32768
	ds_read_b128 v[106:109], v21
	s_waitcnt lgkmcnt(0)
	v_mfma_f32_16x16x32_f16 v[36:39], v[58:61], v[106:109], v[36:39]
	ds_read_b128 v[94:97], v16 offset:34816
	ds_read_b128 v[110:113], v21 offset:2048
	s_waitcnt lgkmcnt(0)
	v_mfma_f32_16x16x32_f16 v[66:69], v[58:61], v[110:113], v[66:69]
	ds_read_b128 v[118:121], v16 offset:36864
	v_mfma_f32_16x16x32_f16 v[44:47], v[94:97], v[106:109], v[44:47]
	ds_read_b128 v[122:125], v16 offset:38912
	v_mfma_f32_16x16x32_f16 v[78:81], v[94:97], v[110:113], v[78:81]
	s_waitcnt lgkmcnt(1)
	v_mfma_f32_16x16x32_f16 v[82:85], v[118:121], v[106:109], v[82:85]
	v_mfma_f32_16x16x32_f16 v[86:89], v[118:121], v[110:113], v[86:89]
	s_waitcnt lgkmcnt(0)
	v_mfma_f32_16x16x32_f16 v[28:31], v[122:125], v[106:109], v[28:31]
	ds_read_b128 v[106:109], v21 offset:4096
	v_mfma_f32_16x16x32_f16 v[32:35], v[122:125], v[110:113], v[32:35]
	ds_read_b128 v[110:113], v21 offset:6144
	s_waitcnt lgkmcnt(1)
	v_mfma_f32_16x16x32_f16 v[98:101], v[58:61], v[106:109], v[98:101]
	s_waitcnt lgkmcnt(0)
	v_mfma_f32_16x16x32_f16 v[52:55], v[58:61], v[110:113], v[52:55]
	ds_read_b128 v[58:61], v22 offset:32768
	v_mfma_f32_16x16x32_f16 v[102:105], v[94:97], v[106:109], v[102:105]
	v_mfma_f32_16x16x32_f16 v[24:27], v[94:97], v[110:113], v[24:27]
	ds_read_b128 v[94:97], v22 offset:34816
	v_mfma_f32_16x16x32_f16 v[114:117], v[118:121], v[106:109], v[114:117]
	s_waitcnt vmcnt(7)
	ds_write_b128 v17, v[62:65] offset:16384
	s_waitcnt vmcnt(6)
; #define GL_LOAD(s_, kt_) if (VAR != 1) { a##s_##0 = GL_A(0, kt_); a##s_##1 = GL_A(1, kt_); a##s_##2 = GL_A(2, kt_); a##s_##3 = GL_A(3, kt_); b##s_##0 = GL_B(0, kt_); b##s_##1 = GL_B(1, kt_); b##s_##2 = GL_B(2, kt_); b##s_##3 = GL_B(3, kt_); }
; #define LDS_STORE(s_, buf_) if (VAR != 2) { LDS_ST1(sA, 0, buf_, a##s_##0) LDS_ST1(sA, 1, buf_, a##s_##1) LDS_ST1(sA, 2, buf_, a##s_##2) LDS_ST1(sA, 3, buf_, a##s_##3) LDS_ST1(sB, 0, buf_, b##s_##0) LDS_ST1(sB, 1, buf_, b##s_##1) LDS_ST1(sB, 2, buf_, b##s_##2) LDS_ST1(sB, 3, buf_, b##s_##3) }
;     ...
;   GL_LOAD(0, 0)
;   GL_LOAD(1, 1)
;   LDS_STORE(0, 0)
;   if (VAR != 4) __syncthreads();
; #pragma unroll
;   for (int kt = 0; kt < nk; kt += 2) {
;     if (kt + 2 < nk) { GL_LOAD(0, kt + 2) }
;     MMA_TILE(0)
;     LDS_STORE(1, 1)
;     if (VAR != 4) __syncthreads();
;     if (kt + 3 < nk) { GL_LOAD(1, kt + 3) }
;     MMA_TILE(1)
;     if (kt + 2 < nk) { LDS_STORE(0, 0) }
;     if (VAR != 4) __syncthreads();
	ds_write_b128 v18, v[90:93] offset:16384
	v_mfma_f32_16x16x32_f16 v[40:43], v[118:121], v[110:113], v[40:43]
	ds_read_b128 v[118:121], v22 offset:36864
	s_waitcnt vmcnt(5)
	ds_write_b128 v19, v[126:129] offset:16384
	v_mfma_f32_16x16x32_f16 v[70:73], v[122:125], v[106:109], v[70:73]
	ds_read_b128 v[106:109], v23
	v_mfma_f32_16x16x32_f16 v[48:51], v[122:125], v[110:113], v[48:51]
	ds_read_b128 v[110:113], v23 offset:2048
	s_waitcnt lgkmcnt(1)
	v_mfma_f32_16x16x32_f16 v[36:39], v[58:61], v[106:109], v[36:39]
	ds_read_b128 v[122:125], v22 offset:38912
	s_waitcnt lgkmcnt(1)
	v_mfma_f32_16x16x32_f16 v[66:69], v[58:61], v[110:113], v[66:69]
	s_waitcnt vmcnt(4)
	ds_write_b128 v20, v[130:133] offset:16384
	v_mfma_f32_16x16x32_f16 v[44:47], v[94:97], v[106:109], v[44:47]
	s_waitcnt vmcnt(3)
	ds_write_b128 v17, v[74:77] offset:49152
	v_mfma_f32_16x16x32_f16 v[78:81], v[94:97], v[110:113], v[78:81]
	s_waitcnt vmcnt(2)
	ds_write_b128 v18, v[138:141] offset:49152
	v_mfma_f32_16x16x32_f16 v[82:85], v[118:121], v[106:109], v[82:85]
	s_waitcnt vmcnt(1)
	ds_write_b128 v19, v[142:145] offset:49152
	v_mfma_f32_16x16x32_f16 v[86:89], v[118:121], v[110:113], v[86:89]
	s_waitcnt vmcnt(0)
	ds_write_b128 v20, v[154:157] offset:49152
	s_waitcnt lgkmcnt(5)
	v_mfma_f32_16x16x32_f16 v[28:31], v[122:125], v[106:109], v[28:31]
	ds_read_b128 v[106:109], v23 offset:4096
	v_mfma_f32_16x16x32_f16 v[32:35], v[122:125], v[110:113], v[32:35]
	ds_read_b128 v[110:113], v23 offset:6144
	s_waitcnt lgkmcnt(1)
	v_mfma_f32_16x16x32_f16 v[98:101], v[58:61], v[106:109], v[98:101]
	s_waitcnt lgkmcnt(0)
	v_mfma_f32_16x16x32_f16 v[52:55], v[58:61], v[110:113], v[52:55]
	global_load_dwordx4 v[58:61], v[0:1], off offset:1792
	v_mfma_f32_16x16x32_f16 v[102:105], v[94:97], v[106:109], v[102:105]
	v_mfma_f32_16x16x32_f16 v[24:27], v[94:97], v[110:113], v[24:27]
	v_mfma_f32_16x16x32_f16 v[114:117], v[118:121], v[106:109], v[114:117]
	v_mfma_f32_16x16x32_f16 v[40:43], v[118:121], v[110:113], v[40:43]
	v_mfma_f32_16x16x32_f16 v[70:73], v[122:125], v[106:109], v[70:73]
	global_load_dwordx4 v[106:109], v[2:3], off offset:1792
	global_load_dwordx4 v[134:137], v[4:5], off offset:1792
	global_load_dwordx4 v[158:161], v[14:15], off offset:1792
	global_load_dwordx4 v[94:97], v[10:11], off offset:1792
	global_load_dwordx4 v[162:165], v[12:13], off offset:1792
	global_load_dwordx4 v[166:169], v[8:9], off offset:1792
	global_load_dwordx4 v[190:193], v[6:7], off offset:1792
	s_waitcnt lgkmcnt(0)
	s_barrier
	v_mfma_f32_16x16x32_f16 v[48:51], v[122:125], v[110:113], v[48:51]
	ds_read_b128 v[62:65], v16 offset:49152
	ds_read_b128 v[90:93], v21 offset:16384
	s_waitcnt lgkmcnt(0)
	v_mfma_f32_16x16x32_f16 v[36:39], v[62:65], v[90:93], v[36:39]
	ds_read_b128 v[74:77], v16 offset:51200
	ds_read_b128 v[110:113], v21 offset:18432
	s_waitcnt lgkmcnt(0)
	v_mfma_f32_16x16x32_f16 v[66:69], v[62:65], v[110:113], v[66:69]
	ds_read_b128 v[118:121], v16 offset:53248
	v_mfma_f32_16x16x32_f16 v[44:47], v[74:77], v[90:93], v[44:47]
	ds_read_b128 v[122:125], v16 offset:55296
	v_mfma_f32_16x16x32_f16 v[78:81], v[74:77], v[110:113], v[78:81]
	s_waitcnt lgkmcnt(1)
	v_mfma_f32_16x16x32_f16 v[82:85], v[118:121], v[90:93], v[82:85]
	v_mfma_f32_16x16x32_f16 v[86:89], v[118:121], v[110:113], v[86:89]
	s_waitcnt lgkmcnt(0)
	v_mfma_f32_16x16x32_f16 v[28:31], v[122:125], v[90:93], v[28:31]
	ds_read_b128 v[90:93], v21 offset:20480
	v_mfma_f32_16x16x32_f16 v[32:35], v[122:125], v[110:113], v[32:35]
	ds_read_b128 v[110:113], v21 offset:22528
	s_waitcnt lgkmcnt(1)
	v_mfma_f32_16x16x32_f16 v[98:101], v[62:65], v[90:93], v[98:101]
	s_waitcnt lgkmcnt(0)
	v_mfma_f32_16x16x32_f16 v[52:55], v[62:65], v[110:113], v[52:55]
	ds_read_b128 v[62:65], v22 offset:49152
	v_mfma_f32_16x16x32_f16 v[102:105], v[74:77], v[90:93], v[102:105]
	v_mfma_f32_16x16x32_f16 v[24:27], v[74:77], v[110:113], v[24:27]
	ds_read_b128 v[74:77], v22 offset:51200
	v_mfma_f32_16x16x32_f16 v[114:117], v[118:121], v[90:93], v[114:117]
	s_waitcnt vmcnt(7)
	ds_write_b128 v17, v[58:61]
	s_waitcnt vmcnt(6)
	ds_write_b128 v18, v[106:109]
	v_mfma_f32_16x16x32_f16 v[40:43], v[118:121], v[110:113], v[40:43]
	ds_read_b128 v[118:121], v22 offset:53248
	s_waitcnt vmcnt(5)
	ds_write_b128 v19, v[134:137]
	v_mfma_f32_16x16x32_f16 v[70:73], v[122:125], v[90:93], v[70:73]
	ds_read_b128 v[90:93], v23 offset:16384
	v_mfma_f32_16x16x32_f16 v[48:51], v[122:125], v[110:113], v[48:51]
	ds_read_b128 v[110:113], v23 offset:18432
	s_waitcnt lgkmcnt(1)
	v_mfma_f32_16x16x32_f16 v[36:39], v[62:65], v[90:93], v[36:39]
	ds_read_b128 v[122:125], v22 offset:55296
	s_waitcnt lgkmcnt(1)
	v_mfma_f32_16x16x32_f16 v[66:69], v[62:65], v[110:113], v[66:69]
	s_waitcnt vmcnt(4)
	ds_write_b128 v20, v[158:161]
	v_mfma_f32_16x16x32_f16 v[44:47], v[74:77], v[90:93], v[44:47]
	s_waitcnt vmcnt(3)
	ds_write_b128 v17, v[94:97] offset:32768
	v_mfma_f32_16x16x32_f16 v[78:81], v[74:77], v[110:113], v[78:81]
	s_waitcnt vmcnt(2)
	ds_write_b128 v18, v[162:165] offset:32768
	v_mfma_f32_16x16x32_f16 v[82:85], v[118:121], v[90:93], v[82:85]
	s_waitcnt vmcnt(1)
	ds_write_b128 v19, v[166:169] offset:32768
	v_mfma_f32_16x16x32_f16 v[86:89], v[118:121], v[110:113], v[86:89]
	s_waitcnt vmcnt(0)
	ds_write_b128 v20, v[190:193] offset:32768
	s_waitcnt lgkmcnt(5)
	v_mfma_f32_16x16x32_f16 v[28:31], v[122:125], v[90:93], v[28:31]
	ds_read_b128 v[90:93], v23 offset:20480
	v_mfma_f32_16x16x32_f16 v[32:35], v[122:125], v[110:113], v[32:35]
	ds_read_b128 v[110:113], v23 offset:22528
	s_waitcnt lgkmcnt(1)
	v_mfma_f32_16x16x32_f16 v[98:101], v[62:65], v[90:93], v[98:101]
	s_waitcnt lgkmcnt(0)
	v_mfma_f32_16x16x32_f16 v[52:55], v[62:65], v[110:113], v[52:55]
	global_load_dwordx4 v[62:65], v[0:1], off offset:1920
	v_mfma_f32_16x16x32_f16 v[102:105], v[74:77], v[90:93], v[102:105]
	v_mfma_f32_16x16x32_f16 v[24:27], v[74:77], v[110:113], v[24:27]
	v_mfma_f32_16x16x32_f16 v[114:117], v[118:121], v[90:93], v[114:117]
	v_mfma_f32_16x16x32_f16 v[40:43], v[118:121], v[110:113], v[40:43]
	v_mfma_f32_16x16x32_f16 v[70:73], v[122:125], v[90:93], v[70:73]
	global_load_dwordx4 v[90:93], v[2:3], off offset:1920
	global_load_dwordx4 v[126:129], v[4:5], off offset:1920
	global_load_dwordx4 v[130:133], v[14:15], off offset:1920
	global_load_dwordx4 v[74:77], v[10:11], off offset:1920
	global_load_dwordx4 v[138:141], v[12:13], off offset:1920
	global_load_dwordx4 v[142:145], v[8:9], off offset:1920
	global_load_dwordx4 v[154:157], v[6:7], off offset:1920
	s_waitcnt lgkmcnt(0)
	s_barrier
; #define GL_LOAD(s_, kt_) if (VAR != 1) { a##s_##0 = GL_A(0, kt_); a##s_##1 = GL_A(1, kt_); a##s_##2 = GL_A(2, kt_); a##s_##3 = GL_A(3, kt_); b##s_##0 = GL_B(0, kt_); b##s_##1 = GL_B(1, kt_); b##s_##2 = GL_B(2, kt_); b##s_##3 = GL_B(3, kt_); }
; #define LDS_STORE(s_, buf_) if (VAR != 2) { LDS_ST1(sA, 0, buf_, a##s_##0) LDS_ST1(sA, 1, buf_, a##s_##1) LDS_ST1(sA, 2, buf_, a##s_##2) LDS_ST1(sA, 3, buf_, a##s_##3) LDS_ST1(sB, 0, buf_, b##s_##0) LDS_ST1(sB, 1, buf_, b##s_##1) LDS_ST1(sB, 2, buf_, b##s_##2) LDS_ST1(sB, 3, buf_, b##s_##3) }
;     ...
;   GL_LOAD(0, 0)
;   GL_LOAD(1, 1)
;   LDS_STORE(0, 0)
;   if (VAR != 4) __syncthreads();
; #pragma unroll
;   for (int kt = 0; kt < nk; kt += 2) {
;     if (kt + 2 < nk) { GL_LOAD(0, kt + 2) }
;     MMA_TILE(0)
;     LDS_STORE(1, 1)
;     if (VAR != 4) __syncthreads();
;     if (kt + 3 < nk) { GL_LOAD(1, kt + 3) }
;     MMA_TILE(1)
;     if (kt + 2 < nk) { LDS_STORE(0, 0) }
;     if (VAR != 4) __syncthreads();
	v_mfma_f32_16x16x32_f16 v[48:51], v[122:125], v[110:113], v[48:51]
	ds_read_b128 v[58:61], v16 offset:32768
	ds_read_b128 v[106:109], v21
	s_waitcnt lgkmcnt(0)
	v_mfma_f32_16x16x32_f16 v[36:39], v[58:61], v[106:109], v[36:39]
	ds_read_b128 v[94:97], v16 offset:34816
	ds_read_b128 v[110:113], v21 offset:2048
	s_waitcnt lgkmcnt(0)
	v_mfma_f32_16x16x32_f16 v[66:69], v[58:61], v[110:113], v[66:69]
	ds_read_b128 v[118:121], v16 offset:36864
	v_mfma_f32_16x16x32_f16 v[44:47], v[94:97], v[106:109], v[44:47]
	ds_read_b128 v[122:125], v16 offset:38912
	v_mfma_f32_16x16x32_f16 v[78:81], v[94:97], v[110:113], v[78:81]
	s_waitcnt lgkmcnt(1)
	v_mfma_f32_16x16x32_f16 v[82:85], v[118:121], v[106:109], v[82:85]
	v_mfma_f32_16x16x32_f16 v[86:89], v[118:121], v[110:113], v[86:89]
	s_waitcnt lgkmcnt(0)
	v_mfma_f32_16x16x32_f16 v[28:31], v[122:125], v[106:109], v[28:31]
	ds_read_b128 v[106:109], v21 offset:4096
	v_mfma_f32_16x16x32_f16 v[32:35], v[122:125], v[110:113], v[32:35]
	ds_read_b128 v[110:113], v21 offset:6144
	s_waitcnt lgkmcnt(1)
	v_mfma_f32_16x16x32_f16 v[98:101], v[58:61], v[106:109], v[98:101]
	s_waitcnt lgkmcnt(0)
	v_mfma_f32_16x16x32_f16 v[52:55], v[58:61], v[110:113], v[52:55]
	ds_read_b128 v[58:61], v22 offset:32768
	v_mfma_f32_16x16x32_f16 v[102:105], v[94:97], v[106:109], v[102:105]
	v_mfma_f32_16x16x32_f16 v[24:27], v[94:97], v[110:113], v[24:27]
	ds_read_b128 v[94:97], v22 offset:34816
	v_mfma_f32_16x16x32_f16 v[114:117], v[118:121], v[106:109], v[114:117]
	s_waitcnt vmcnt(7)
	ds_write_b128 v17, v[62:65] offset:16384
	s_waitcnt vmcnt(6)
	ds_write_b128 v18, v[90:93] offset:16384
	v_mfma_f32_16x16x32_f16 v[40:43], v[118:121], v[110:113], v[40:43]
	ds_read_b128 v[118:121], v22 offset:36864
	s_waitcnt vmcnt(5)
	ds_write_b128 v19, v[126:129] offset:16384
	v_mfma_f32_16x16x32_f16 v[70:73], v[122:125], v[106:109], v[70:73]
	ds_read_b128 v[106:109], v23
	v_mfma_f32_16x16x32_f16 v[48:51], v[122:125], v[110:113], v[48:51]
	ds_read_b128 v[110:113], v23 offset:2048
	s_waitcnt lgkmcnt(1)
	v_mfma_f32_16x16x32_f16 v[36:39], v[58:61], v[106:109], v[36:39]
	ds_read_b128 v[122:125], v22 offset:38912
	s_waitcnt lgkmcnt(1)
	v_mfma_f32_16x16x32_f16 v[66:69], v[58:61], v[110:113], v[66:69]
	s_waitcnt vmcnt(4)
	ds_write_b128 v20, v[130:133] offset:16384
	v_mfma_f32_16x16x32_f16 v[44:47], v[94:97], v[106:109], v[44:47]
	s_waitcnt vmcnt(3)
	ds_write_b128 v17, v[74:77] offset:49152
	v_mfma_f32_16x16x32_f16 v[78:81], v[94:97], v[110:113], v[78:81]
	s_waitcnt vmcnt(2)
	ds_write_b128 v18, v[138:141] offset:49152
	v_mfma_f32_16x16x32_f16 v[82:85], v[118:121], v[106:109], v[82:85]
	s_waitcnt vmcnt(1)
	ds_write_b128 v19, v[142:145] offset:49152
	v_mfma_f32_16x16x32_f16 v[86:89], v[118:121], v[110:113], v[86:89]
	s_waitcnt vmcnt(0)
	ds_write_b128 v20, v[154:157] offset:49152
	s_waitcnt lgkmcnt(5)
	v_mfma_f32_16x16x32_f16 v[28:31], v[122:125], v[106:109], v[28:31]
	ds_read_b128 v[106:109], v23 offset:4096
	v_mfma_f32_16x16x32_f16 v[32:35], v[122:125], v[110:113], v[32:35]
	ds_read_b128 v[110:113], v23 offset:6144
	s_waitcnt lgkmcnt(1)
	v_mfma_f32_16x16x32_f16 v[98:101], v[58:61], v[106:109], v[98:101]
	s_waitcnt lgkmcnt(0)
	v_mfma_f32_16x16x32_f16 v[52:55], v[58:61], v[110:113], v[52:55]
	global_load_dwordx4 v[58:61], v[0:1], off offset:2048
	v_mfma_f32_16x16x32_f16 v[102:105], v[94:97], v[106:109], v[102:105]
	v_mfma_f32_16x16x32_f16 v[24:27], v[94:97], v[110:113], v[24:27]
	v_mfma_f32_16x16x32_f16 v[114:117], v[118:121], v[106:109], v[114:117]
	v_mfma_f32_16x16x32_f16 v[40:43], v[118:121], v[110:113], v[40:43]
	v_mfma_f32_16x16x32_f16 v[70:73], v[122:125], v[106:109], v[70:73]
	global_load_dwordx4 v[106:109], v[2:3], off offset:2048
	global_load_dwordx4 v[134:137], v[4:5], off offset:2048
	global_load_dwordx4 v[158:161], v[14:15], off offset:2048
	global_load_dwordx4 v[94:97], v[10:11], off offset:2048
	global_load_dwordx4 v[162:165], v[12:13], off offset:2048
	global_load_dwordx4 v[166:169], v[8:9], off offset:2048
	global_load_dwordx4 v[190:193], v[6:7], off offset:2048
	s_waitcnt lgkmcnt(0)
	s_barrier
	v_mfma_f32_16x16x32_f16 v[48:51], v[122:125], v[110:113], v[48:51]
	ds_read_b128 v[62:65], v16 offset:49152
	ds_read_b128 v[90:93], v21 offset:16384
	s_waitcnt lgkmcnt(0)
	v_mfma_f32_16x16x32_f16 v[36:39], v[62:65], v[90:93], v[36:39]
	ds_read_b128 v[74:77], v16 offset:51200
	ds_read_b128 v[110:113], v21 offset:18432
	s_waitcnt lgkmcnt(0)
	v_mfma_f32_16x16x32_f16 v[66:69], v[62:65], v[110:113], v[66:69]
	ds_read_b128 v[118:121], v16 offset:53248
	v_mfma_f32_16x16x32_f16 v[44:47], v[74:77], v[90:93], v[44:47]
	ds_read_b128 v[122:125], v16 offset:55296
	v_mfma_f32_16x16x32_f16 v[78:81], v[74:77], v[110:113], v[78:81]
	s_waitcnt lgkmcnt(1)
	v_mfma_f32_16x16x32_f16 v[82:85], v[118:121], v[90:93], v[82:85]
	v_mfma_f32_16x16x32_f16 v[86:89], v[118:121], v[110:113], v[86:89]
	s_waitcnt lgkmcnt(0)
	v_mfma_f32_16x16x32_f16 v[28:31], v[122:125], v[90:93], v[28:31]
	ds_read_b128 v[90:93], v21 offset:20480
	v_mfma_f32_16x16x32_f16 v[32:35], v[122:125], v[110:113], v[32:35]
	ds_read_b128 v[110:113], v21 offset:22528
	s_waitcnt lgkmcnt(1)
	v_mfma_f32_16x16x32_f16 v[98:101], v[62:65], v[90:93], v[98:101]
	s_waitcnt lgkmcnt(0)
	v_mfma_f32_16x16x32_f16 v[52:55], v[62:65], v[110:113], v[52:55]
	ds_read_b128 v[62:65], v22 offset:49152
	v_mfma_f32_16x16x32_f16 v[102:105], v[74:77], v[90:93], v[102:105]
	v_mfma_f32_16x16x32_f16 v[24:27], v[74:77], v[110:113], v[24:27]
	ds_read_b128 v[74:77], v22 offset:51200
	v_mfma_f32_16x16x32_f16 v[114:117], v[118:121], v[90:93], v[114:117]
	s_waitcnt vmcnt(7)
	ds_write_b128 v17, v[58:61]
	s_waitcnt vmcnt(6)
; #define GL_LOAD(s_, kt_) if (VAR != 1) { a##s_##0 = GL_A(0, kt_); a##s_##1 = GL_A(1, kt_); a##s_##2 = GL_A(2, kt_); a##s_##3 = GL_A(3, kt_); b##s_##0 = GL_B(0, kt_); b##s_##1 = GL_B(1, kt_); b##s_##2 = GL_B(2, kt_); b##s_##3 = GL_B(3, kt_); }
; #define LDS_STORE(s_, buf_) if (VAR != 2) { LDS_ST1(sA, 0, buf_, a##s_##0) LDS_ST1(sA, 1, buf_, a##s_##1) LDS_ST1(sA, 2, buf_, a##s_##2) LDS_ST1(sA, 3, buf_, a##s_##3) LDS_ST1(sB, 0, buf_, b##s_##0) LDS_ST1(sB, 1, buf_, b##s_##1) LDS_ST1(sB, 2, buf_, b##s_##2) LDS_ST1(sB, 3, buf_, b##s_##3) }
;     ...
;   GL_LOAD(0, 0)
;   GL_LOAD(1, 1)
;   LDS_STORE(0, 0)
;   if (VAR != 4) __syncthreads();
; #pragma unroll
;   for (int kt = 0; kt < nk; kt += 2) {
;     if (kt + 2 < nk) { GL_LOAD(0, kt + 2) }
;     MMA_TILE(0)
;     LDS_STORE(1, 1)
;     if (VAR != 4) __syncthreads();
;     if (kt + 3 < nk) { GL_LOAD(1, kt + 3) }
;     MMA_TILE(1)
;     if (kt + 2 < nk) { LDS_STORE(0, 0) }
;     if (VAR != 4) __syncthreads();
	ds_write_b128 v18, v[106:109]
	v_mfma_f32_16x16x32_f16 v[40:43], v[118:121], v[110:113], v[40:43]
	ds_read_b128 v[118:121], v22 offset:53248
	s_waitcnt vmcnt(5)
	ds_write_b128 v19, v[134:137]
	v_mfma_f32_16x16x32_f16 v[70:73], v[122:125], v[90:93], v[70:73]
	ds_read_b128 v[90:93], v23 offset:16384
	v_mfma_f32_16x16x32_f16 v[48:51], v[122:125], v[110:113], v[48:51]
	ds_read_b128 v[110:113], v23 offset:18432
	s_waitcnt lgkmcnt(1)
	v_mfma_f32_16x16x32_f16 v[36:39], v[62:65], v[90:93], v[36:39]
	ds_read_b128 v[122:125], v22 offset:55296
	s_waitcnt lgkmcnt(1)
	v_mfma_f32_16x16x32_f16 v[66:69], v[62:65], v[110:113], v[66:69]
	s_waitcnt vmcnt(4)
	ds_write_b128 v20, v[158:161]
	v_mfma_f32_16x16x32_f16 v[44:47], v[74:77], v[90:93], v[44:47]
	s_waitcnt vmcnt(3)
	ds_write_b128 v17, v[94:97] offset:32768
	v_mfma_f32_16x16x32_f16 v[78:81], v[74:77], v[110:113], v[78:81]
	s_waitcnt vmcnt(2)
	ds_write_b128 v18, v[162:165] offset:32768
	v_mfma_f32_16x16x32_f16 v[82:85], v[118:121], v[90:93], v[82:85]
	s_waitcnt vmcnt(1)
	ds_write_b128 v19, v[166:169] offset:32768
	v_mfma_f32_16x16x32_f16 v[86:89], v[118:121], v[110:113], v[86:89]
	s_waitcnt vmcnt(0)
	ds_write_b128 v20, v[190:193] offset:32768
	s_waitcnt lgkmcnt(5)
	v_mfma_f32_16x16x32_f16 v[28:31], v[122:125], v[90:93], v[28:31]
	ds_read_b128 v[90:93], v23 offset:20480
	v_mfma_f32_16x16x32_f16 v[32:35], v[122:125], v[110:113], v[32:35]
	ds_read_b128 v[110:113], v23 offset:22528
	s_waitcnt lgkmcnt(1)
	v_mfma_f32_16x16x32_f16 v[98:101], v[62:65], v[90:93], v[98:101]
	s_waitcnt lgkmcnt(0)
	v_mfma_f32_16x16x32_f16 v[52:55], v[62:65], v[110:113], v[52:55]
	global_load_dwordx4 v[62:65], v[0:1], off offset:2176
	v_mfma_f32_16x16x32_f16 v[102:105], v[74:77], v[90:93], v[102:105]
	v_mfma_f32_16x16x32_f16 v[24:27], v[74:77], v[110:113], v[24:27]
	v_mfma_f32_16x16x32_f16 v[114:117], v[118:121], v[90:93], v[114:117]
	v_mfma_f32_16x16x32_f16 v[40:43], v[118:121], v[110:113], v[40:43]
	v_mfma_f32_16x16x32_f16 v[70:73], v[122:125], v[90:93], v[70:73]
	global_load_dwordx4 v[90:93], v[2:3], off offset:2176
	global_load_dwordx4 v[126:129], v[4:5], off offset:2176
	global_load_dwordx4 v[130:133], v[14:15], off offset:2176
	global_load_dwordx4 v[74:77], v[10:11], off offset:2176
	global_load_dwordx4 v[138:141], v[12:13], off offset:2176
	global_load_dwordx4 v[142:145], v[8:9], off offset:2176
	global_load_dwordx4 v[154:157], v[6:7], off offset:2176
	s_waitcnt lgkmcnt(0)
	s_barrier
	v_mfma_f32_16x16x32_f16 v[48:51], v[122:125], v[110:113], v[48:51]
	ds_read_b128 v[58:61], v16 offset:32768
	ds_read_b128 v[106:109], v21
	s_waitcnt lgkmcnt(0)
	v_mfma_f32_16x16x32_f16 v[36:39], v[58:61], v[106:109], v[36:39]
	ds_read_b128 v[94:97], v16 offset:34816
	ds_read_b128 v[110:113], v21 offset:2048
	s_waitcnt lgkmcnt(0)
	v_mfma_f32_16x16x32_f16 v[66:69], v[58:61], v[110:113], v[66:69]
	ds_read_b128 v[118:121], v16 offset:36864
	v_mfma_f32_16x16x32_f16 v[44:47], v[94:97], v[106:109], v[44:47]
	ds_read_b128 v[122:125], v16 offset:38912
	v_mfma_f32_16x16x32_f16 v[78:81], v[94:97], v[110:113], v[78:81]
	s_waitcnt lgkmcnt(1)
	v_mfma_f32_16x16x32_f16 v[82:85], v[118:121], v[106:109], v[82:85]
	v_mfma_f32_16x16x32_f16 v[86:89], v[118:121], v[110:113], v[86:89]
	s_waitcnt lgkmcnt(0)
	v_mfma_f32_16x16x32_f16 v[28:31], v[122:125], v[106:109], v[28:31]
	ds_read_b128 v[106:109], v21 offset:4096
	v_mfma_f32_16x16x32_f16 v[32:35], v[122:125], v[110:113], v[32:35]
	ds_read_b128 v[110:113], v21 offset:6144
	s_waitcnt lgkmcnt(1)
	v_mfma_f32_16x16x32_f16 v[98:101], v[58:61], v[106:109], v[98:101]
	s_waitcnt lgkmcnt(0)
	v_mfma_f32_16x16x32_f16 v[52:55], v[58:61], v[110:113], v[52:55]
	ds_read_b128 v[58:61], v22 offset:32768
	v_mfma_f32_16x16x32_f16 v[102:105], v[94:97], v[106:109], v[102:105]
	v_mfma_f32_16x16x32_f16 v[24:27], v[94:97], v[110:113], v[24:27]
	ds_read_b128 v[94:97], v22 offset:34816
	v_mfma_f32_16x16x32_f16 v[114:117], v[118:121], v[106:109], v[114:117]
	s_waitcnt vmcnt(7)
	ds_write_b128 v17, v[62:65] offset:16384
	s_waitcnt vmcnt(6)
	ds_write_b128 v18, v[90:93] offset:16384
	v_mfma_f32_16x16x32_f16 v[40:43], v[118:121], v[110:113], v[40:43]
	ds_read_b128 v[118:121], v22 offset:36864
	s_waitcnt vmcnt(5)
	ds_write_b128 v19, v[126:129] offset:16384
	v_mfma_f32_16x16x32_f16 v[70:73], v[122:125], v[106:109], v[70:73]
	ds_read_b128 v[106:109], v23
	v_mfma_f32_16x16x32_f16 v[48:51], v[122:125], v[110:113], v[48:51]
	ds_read_b128 v[110:113], v23 offset:2048
	s_waitcnt lgkmcnt(1)
	v_mfma_f32_16x16x32_f16 v[36:39], v[58:61], v[106:109], v[36:39]
	ds_read_b128 v[122:125], v22 offset:38912
	s_waitcnt lgkmcnt(1)
	v_mfma_f32_16x16x32_f16 v[66:69], v[58:61], v[110:113], v[66:69]
	s_waitcnt vmcnt(4)
	ds_write_b128 v20, v[130:133] offset:16384
	v_mfma_f32_16x16x32_f16 v[44:47], v[94:97], v[106:109], v[44:47]
	s_waitcnt vmcnt(3)
	ds_write_b128 v17, v[74:77] offset:49152
	v_mfma_f32_16x16x32_f16 v[78:81], v[94:97], v[110:113], v[78:81]
	s_waitcnt vmcnt(2)
	ds_write_b128 v18, v[138:141] offset:49152
	v_mfma_f32_16x16x32_f16 v[82:85], v[118:121], v[106:109], v[82:85]
	s_waitcnt vmcnt(1)
	ds_write_b128 v19, v[142:145] offset:49152
	v_mfma_f32_16x16x32_f16 v[86:89], v[118:121], v[110:113], v[86:89]
	s_waitcnt vmcnt(0)
	ds_write_b128 v20, v[154:157] offset:49152
	s_waitcnt lgkmcnt(5)
	v_mfma_f32_16x16x32_f16 v[28:31], v[122:125], v[106:109], v[28:31]
	ds_read_b128 v[106:109], v23 offset:4096
	v_mfma_f32_16x16x32_f16 v[32:35], v[122:125], v[110:113], v[32:35]
	ds_read_b128 v[110:113], v23 offset:6144
	s_waitcnt lgkmcnt(1)
	v_mfma_f32_16x16x32_f16 v[98:101], v[58:61], v[106:109], v[98:101]
	s_waitcnt lgkmcnt(0)
	v_mfma_f32_16x16x32_f16 v[52:55], v[58:61], v[110:113], v[52:55]
	global_load_dwordx4 v[58:61], v[0:1], off offset:2304
	v_mfma_f32_16x16x32_f16 v[102:105], v[94:97], v[106:109], v[102:105]
	v_mfma_f32_16x16x32_f16 v[24:27], v[94:97], v[110:113], v[24:27]
	v_mfma_f32_16x16x32_f16 v[114:117], v[118:121], v[106:109], v[114:117]
	v_mfma_f32_16x16x32_f16 v[40:43], v[118:121], v[110:113], v[40:43]
	v_mfma_f32_16x16x32_f16 v[70:73], v[122:125], v[106:109], v[70:73]
	global_load_dwordx4 v[106:109], v[2:3], off offset:2304
	global_load_dwordx4 v[134:137], v[4:5], off offset:2304
	global_load_dwordx4 v[158:161], v[14:15], off offset:2304
	global_load_dwordx4 v[94:97], v[10:11], off offset:2304
	global_load_dwordx4 v[162:165], v[12:13], off offset:2304
	global_load_dwordx4 v[166:169], v[8:9], off offset:2304
	global_load_dwordx4 v[190:193], v[6:7], off offset:2304
	s_waitcnt lgkmcnt(0)
	s_barrier
; #define GL_LOAD(s_, kt_) if (VAR != 1) { a##s_##0 = GL_A(0, kt_); a##s_##1 = GL_A(1, kt_); a##s_##2 = GL_A(2, kt_); a##s_##3 = GL_A(3, kt_); b##s_##0 = GL_B(0, kt_); b##s_##1 = GL_B(1, kt_); b##s_##2 = GL_B(2, kt_); b##s_##3 = GL_B(3, kt_); }
; #define LDS_STORE(s_, buf_) if (VAR != 2) { LDS_ST1(sA, 0, buf_, a##s_##0) LDS_ST1(sA, 1, buf_, a##s_##1) LDS_ST1(sA, 2, buf_, a##s_##2) LDS_ST1(sA, 3, buf_, a##s_##3) LDS_ST1(sB, 0, buf_, b##s_##0) LDS_ST1(sB, 1, buf_, b##s_##1) LDS_ST1(sB, 2, buf_, b##s_##2) LDS_ST1(sB, 3, buf_, b##s_##3) }
;     ...
;   GL_LOAD(0, 0)
;   GL_LOAD(1, 1)
;   LDS_STORE(0, 0)
;   if (VAR != 4) __syncthreads();
; #pragma unroll
;   for (int kt = 0; kt < nk; kt += 2) {
;     if (kt + 2 < nk) { GL_LOAD(0, kt + 2) }
;     MMA_TILE(0)
;     LDS_STORE(1, 1)
;     if (VAR != 4) __syncthreads();
;     if (kt + 3 < nk) { GL_LOAD(1, kt + 3) }
;     MMA_TILE(1)
;     if (kt + 2 < nk) { LDS_STORE(0, 0) }
;     if (VAR != 4) __syncthreads();
	v_mfma_f32_16x16x32_f16 v[48:51], v[122:125], v[110:113], v[48:51]
	ds_read_b128 v[62:65], v16 offset:49152
	ds_read_b128 v[90:93], v21 offset:16384
	s_waitcnt lgkmcnt(0)
	v_mfma_f32_16x16x32_f16 v[36:39], v[62:65], v[90:93], v[36:39]
	ds_read_b128 v[74:77], v16 offset:51200
	ds_read_b128 v[110:113], v21 offset:18432
	s_waitcnt lgkmcnt(0)
	v_mfma_f32_16x16x32_f16 v[66:69], v[62:65], v[110:113], v[66:69]
	ds_read_b128 v[118:121], v16 offset:53248
	v_mfma_f32_16x16x32_f16 v[44:47], v[74:77], v[90:93], v[44:47]
	ds_read_b128 v[122:125], v16 offset:55296
	v_mfma_f32_16x16x32_f16 v[78:81], v[74:77], v[110:113], v[78:81]
	s_waitcnt lgkmcnt(1)
	v_mfma_f32_16x16x32_f16 v[82:85], v[118:121], v[90:93], v[82:85]
	v_mfma_f32_16x16x32_f16 v[86:89], v[118:121], v[110:113], v[86:89]
	s_waitcnt lgkmcnt(0)
	v_mfma_f32_16x16x32_f16 v[28:31], v[122:125], v[90:93], v[28:31]
	ds_read_b128 v[90:93], v21 offset:20480
	v_mfma_f32_16x16x32_f16 v[32:35], v[122:125], v[110:113], v[32:35]
	ds_read_b128 v[110:113], v21 offset:22528
	s_waitcnt lgkmcnt(1)
	v_mfma_f32_16x16x32_f16 v[98:101], v[62:65], v[90:93], v[98:101]
	s_waitcnt lgkmcnt(0)
	v_mfma_f32_16x16x32_f16 v[52:55], v[62:65], v[110:113], v[52:55]
	ds_read_b128 v[62:65], v22 offset:49152
	v_mfma_f32_16x16x32_f16 v[102:105], v[74:77], v[90:93], v[102:105]
	v_mfma_f32_16x16x32_f16 v[24:27], v[74:77], v[110:113], v[24:27]
	ds_read_b128 v[74:77], v22 offset:51200
	v_mfma_f32_16x16x32_f16 v[114:117], v[118:121], v[90:93], v[114:117]
	s_waitcnt vmcnt(7)
	ds_write_b128 v17, v[58:61]
	s_waitcnt vmcnt(6)
	ds_write_b128 v18, v[106:109]
	v_mfma_f32_16x16x32_f16 v[40:43], v[118:121], v[110:113], v[40:43]
	ds_read_b128 v[118:121], v22 offset:53248
	s_waitcnt vmcnt(5)
	ds_write_b128 v19, v[134:137]
	v_mfma_f32_16x16x32_f16 v[70:73], v[122:125], v[90:93], v[70:73]
	ds_read_b128 v[90:93], v23 offset:16384
	v_mfma_f32_16x16x32_f16 v[48:51], v[122:125], v[110:113], v[48:51]
	ds_read_b128 v[110:113], v23 offset:18432
	s_waitcnt lgkmcnt(1)
	v_mfma_f32_16x16x32_f16 v[36:39], v[62:65], v[90:93], v[36:39]
	ds_read_b128 v[122:125], v22 offset:55296
	s_waitcnt lgkmcnt(1)
	v_mfma_f32_16x16x32_f16 v[66:69], v[62:65], v[110:113], v[66:69]
	s_waitcnt vmcnt(4)
	ds_write_b128 v20, v[158:161]
	v_mfma_f32_16x16x32_f16 v[44:47], v[74:77], v[90:93], v[44:47]
	s_waitcnt vmcnt(3)
	ds_write_b128 v17, v[94:97] offset:32768
	v_mfma_f32_16x16x32_f16 v[78:81], v[74:77], v[110:113], v[78:81]
	s_waitcnt vmcnt(2)
	ds_write_b128 v18, v[162:165] offset:32768
	v_mfma_f32_16x16x32_f16 v[82:85], v[118:121], v[90:93], v[82:85]
	s_waitcnt vmcnt(1)
	ds_write_b128 v19, v[166:169] offset:32768
	v_mfma_f32_16x16x32_f16 v[86:89], v[118:121], v[110:113], v[86:89]
	s_waitcnt vmcnt(0)
	ds_write_b128 v20, v[190:193] offset:32768
	s_waitcnt lgkmcnt(5)
	v_mfma_f32_16x16x32_f16 v[28:31], v[122:125], v[90:93], v[28:31]
	ds_read_b128 v[90:93], v23 offset:20480
	v_mfma_f32_16x16x32_f16 v[32:35], v[122:125], v[110:113], v[32:35]
	ds_read_b128 v[110:113], v23 offset:22528
	s_waitcnt lgkmcnt(1)
	v_mfma_f32_16x16x32_f16 v[98:101], v[62:65], v[90:93], v[98:101]
	s_waitcnt lgkmcnt(0)
	v_mfma_f32_16x16x32_f16 v[52:55], v[62:65], v[110:113], v[52:55]
	global_load_dwordx4 v[62:65], v[0:1], off offset:2432
	v_mfma_f32_16x16x32_f16 v[102:105], v[74:77], v[90:93], v[102:105]
	v_mfma_f32_16x16x32_f16 v[24:27], v[74:77], v[110:113], v[24:27]
	v_mfma_f32_16x16x32_f16 v[114:117], v[118:121], v[90:93], v[114:117]
	v_mfma_f32_16x16x32_f16 v[40:43], v[118:121], v[110:113], v[40:43]
	v_mfma_f32_16x16x32_f16 v[70:73], v[122:125], v[90:93], v[70:73]
	global_load_dwordx4 v[90:93], v[2:3], off offset:2432
	global_load_dwordx4 v[126:129], v[4:5], off offset:2432
	global_load_dwordx4 v[130:133], v[14:15], off offset:2432
	global_load_dwordx4 v[74:77], v[10:11], off offset:2432
	global_load_dwordx4 v[138:141], v[12:13], off offset:2432
	global_load_dwordx4 v[142:145], v[8:9], off offset:2432
	global_load_dwordx4 v[154:157], v[6:7], off offset:2432
	s_waitcnt lgkmcnt(0)
	s_barrier
	v_mfma_f32_16x16x32_f16 v[48:51], v[122:125], v[110:113], v[48:51]
	ds_read_b128 v[58:61], v16 offset:32768
	ds_read_b128 v[106:109], v21
	s_waitcnt lgkmcnt(0)
	v_mfma_f32_16x16x32_f16 v[36:39], v[58:61], v[106:109], v[36:39]
	ds_read_b128 v[94:97], v16 offset:34816
	ds_read_b128 v[110:113], v21 offset:2048
	s_waitcnt lgkmcnt(0)
	v_mfma_f32_16x16x32_f16 v[66:69], v[58:61], v[110:113], v[66:69]
	ds_read_b128 v[118:121], v16 offset:36864
	v_mfma_f32_16x16x32_f16 v[44:47], v[94:97], v[106:109], v[44:47]
	ds_read_b128 v[122:125], v16 offset:38912
	v_mfma_f32_16x16x32_f16 v[78:81], v[94:97], v[110:113], v[78:81]
	s_waitcnt lgkmcnt(1)
	v_mfma_f32_16x16x32_f16 v[82:85], v[118:121], v[106:109], v[82:85]
	v_mfma_f32_16x16x32_f16 v[86:89], v[118:121], v[110:113], v[86:89]
	s_waitcnt lgkmcnt(0)
	v_mfma_f32_16x16x32_f16 v[28:31], v[122:125], v[106:109], v[28:31]
	ds_read_b128 v[106:109], v21 offset:4096
	v_mfma_f32_16x16x32_f16 v[32:35], v[122:125], v[110:113], v[32:35]
	ds_read_b128 v[110:113], v21 offset:6144
	s_waitcnt lgkmcnt(1)
	v_mfma_f32_16x16x32_f16 v[98:101], v[58:61], v[106:109], v[98:101]
	s_waitcnt lgkmcnt(0)
	v_mfma_f32_16x16x32_f16 v[52:55], v[58:61], v[110:113], v[52:55]
	ds_read_b128 v[58:61], v22 offset:32768
	v_mfma_f32_16x16x32_f16 v[102:105], v[94:97], v[106:109], v[102:105]
	v_mfma_f32_16x16x32_f16 v[24:27], v[94:97], v[110:113], v[24:27]
	ds_read_b128 v[94:97], v22 offset:34816
	v_mfma_f32_16x16x32_f16 v[114:117], v[118:121], v[106:109], v[114:117]
	s_waitcnt vmcnt(7)
	ds_write_b128 v17, v[62:65] offset:16384
	s_waitcnt vmcnt(6)
; #define GL_LOAD(s_, kt_) if (VAR != 1) { a##s_##0 = GL_A(0, kt_); a##s_##1 = GL_A(1, kt_); a##s_##2 = GL_A(2, kt_); a##s_##3 = GL_A(3, kt_); b##s_##0 = GL_B(0, kt_); b##s_##1 = GL_B(1, kt_); b##s_##2 = GL_B(2, kt_); b##s_##3 = GL_B(3, kt_); }
; #define LDS_STORE(s_, buf_) if (VAR != 2) { LDS_ST1(sA, 0, buf_, a##s_##0) LDS_ST1(sA, 1, buf_, a##s_##1) LDS_ST1(sA, 2, buf_, a##s_##2) LDS_ST1(sA, 3, buf_, a##s_##3) LDS_ST1(sB, 0, buf_, b##s_##0) LDS_ST1(sB, 1, buf_, b##s_##1) LDS_ST1(sB, 2, buf_, b##s_##2) LDS_ST1(sB, 3, buf_, b##s_##3) }
;     ...
;   GL_LOAD(0, 0)
;   GL_LOAD(1, 1)
;   LDS_STORE(0, 0)
;   if (VAR != 4) __syncthreads();
; #pragma unroll
;   for (int kt = 0; kt < nk; kt += 2) {
;     if (kt + 2 < nk) { GL_LOAD(0, kt + 2) }
;     MMA_TILE(0)
;     LDS_STORE(1, 1)
;     if (VAR != 4) __syncthreads();
;     if (kt + 3 < nk) { GL_LOAD(1, kt + 3) }
;     MMA_TILE(1)
;     if (kt + 2 < nk) { LDS_STORE(0, 0) }
;     if (VAR != 4) __syncthreads();
	ds_write_b128 v18, v[90:93] offset:16384
	v_mfma_f32_16x16x32_f16 v[40:43], v[118:121], v[110:113], v[40:43]
	ds_read_b128 v[118:121], v22 offset:36864
	s_waitcnt vmcnt(5)
	ds_write_b128 v19, v[126:129] offset:16384
	v_mfma_f32_16x16x32_f16 v[70:73], v[122:125], v[106:109], v[70:73]
	ds_read_b128 v[106:109], v23
	v_mfma_f32_16x16x32_f16 v[48:51], v[122:125], v[110:113], v[48:51]
	ds_read_b128 v[110:113], v23 offset:2048
	s_waitcnt lgkmcnt(1)
	v_mfma_f32_16x16x32_f16 v[36:39], v[58:61], v[106:109], v[36:39]
	ds_read_b128 v[122:125], v22 offset:38912
	s_waitcnt lgkmcnt(1)
	v_mfma_f32_16x16x32_f16 v[66:69], v[58:61], v[110:113], v[66:69]
	s_waitcnt vmcnt(4)
	ds_write_b128 v20, v[130:133] offset:16384
	v_mfma_f32_16x16x32_f16 v[44:47], v[94:97], v[106:109], v[44:47]
	s_waitcnt vmcnt(3)
	ds_write_b128 v17, v[74:77] offset:49152
	v_mfma_f32_16x16x32_f16 v[78:81], v[94:97], v[110:113], v[78:81]
	s_waitcnt vmcnt(2)
	ds_write_b128 v18, v[138:141] offset:49152
	v_mfma_f32_16x16x32_f16 v[82:85], v[118:121], v[106:109], v[82:85]
	s_waitcnt vmcnt(1)
	ds_write_b128 v19, v[142:145] offset:49152
	v_mfma_f32_16x16x32_f16 v[86:89], v[118:121], v[110:113], v[86:89]
	s_waitcnt vmcnt(0)
	ds_write_b128 v20, v[154:157] offset:49152
	s_waitcnt lgkmcnt(5)
	v_mfma_f32_16x16x32_f16 v[28:31], v[122:125], v[106:109], v[28:31]
	ds_read_b128 v[106:109], v23 offset:4096
	v_mfma_f32_16x16x32_f16 v[32:35], v[122:125], v[110:113], v[32:35]
	ds_read_b128 v[110:113], v23 offset:6144
	s_waitcnt lgkmcnt(1)
	v_mfma_f32_16x16x32_f16 v[98:101], v[58:61], v[106:109], v[98:101]
	s_waitcnt lgkmcnt(0)
	v_mfma_f32_16x16x32_f16 v[52:55], v[58:61], v[110:113], v[52:55]
	global_load_dwordx4 v[58:61], v[0:1], off offset:2560
	v_mfma_f32_16x16x32_f16 v[102:105], v[94:97], v[106:109], v[102:105]
	v_mfma_f32_16x16x32_f16 v[24:27], v[94:97], v[110:113], v[24:27]
	v_mfma_f32_16x16x32_f16 v[114:117], v[118:121], v[106:109], v[114:117]
	v_mfma_f32_16x16x32_f16 v[40:43], v[118:121], v[110:113], v[40:43]
	v_mfma_f32_16x16x32_f16 v[70:73], v[122:125], v[106:109], v[70:73]
	global_load_dwordx4 v[106:109], v[2:3], off offset:2560
	global_load_dwordx4 v[134:137], v[4:5], off offset:2560
	global_load_dwordx4 v[158:161], v[14:15], off offset:2560
	global_load_dwordx4 v[94:97], v[10:11], off offset:2560
	global_load_dwordx4 v[162:165], v[12:13], off offset:2560
	global_load_dwordx4 v[166:169], v[8:9], off offset:2560
	global_load_dwordx4 v[190:193], v[6:7], off offset:2560
	s_waitcnt lgkmcnt(0)
	s_barrier
	v_mfma_f32_16x16x32_f16 v[48:51], v[122:125], v[110:113], v[48:51]
	ds_read_b128 v[62:65], v16 offset:49152
	ds_read_b128 v[90:93], v21 offset:16384
	s_waitcnt lgkmcnt(0)
	v_mfma_f32_16x16x32_f16 v[36:39], v[62:65], v[90:93], v[36:39]
	ds_read_b128 v[74:77], v16 offset:51200
	ds_read_b128 v[110:113], v21 offset:18432
	s_waitcnt lgkmcnt(0)
	v_mfma_f32_16x16x32_f16 v[66:69], v[62:65], v[110:113], v[66:69]
	ds_read_b128 v[118:121], v16 offset:53248
	v_mfma_f32_16x16x32_f16 v[44:47], v[74:77], v[90:93], v[44:47]
	ds_read_b128 v[122:125], v16 offset:55296
	v_mfma_f32_16x16x32_f16 v[78:81], v[74:77], v[110:113], v[78:81]
	s_waitcnt lgkmcnt(1)
	v_mfma_f32_16x16x32_f16 v[82:85], v[118:121], v[90:93], v[82:85]
	v_mfma_f32_16x16x32_f16 v[86:89], v[118:121], v[110:113], v[86:89]
	s_waitcnt lgkmcnt(0)
	v_mfma_f32_16x16x32_f16 v[28:31], v[122:125], v[90:93], v[28:31]
	ds_read_b128 v[90:93], v21 offset:20480
	v_mfma_f32_16x16x32_f16 v[32:35], v[122:125], v[110:113], v[32:35]
	ds_read_b128 v[110:113], v21 offset:22528
	s_waitcnt lgkmcnt(1)
	v_mfma_f32_16x16x32_f16 v[98:101], v[62:65], v[90:93], v[98:101]
	s_waitcnt lgkmcnt(0)
	v_mfma_f32_16x16x32_f16 v[52:55], v[62:65], v[110:113], v[52:55]
	ds_read_b128 v[62:65], v22 offset:49152
	v_mfma_f32_16x16x32_f16 v[102:105], v[74:77], v[90:93], v[102:105]
	v_mfma_f32_16x16x32_f16 v[24:27], v[74:77], v[110:113], v[24:27]
	ds_read_b128 v[74:77], v22 offset:51200
	v_mfma_f32_16x16x32_f16 v[114:117], v[118:121], v[90:93], v[114:117]
	s_waitcnt vmcnt(7)
	ds_write_b128 v17, v[58:61]
	s_waitcnt vmcnt(6)
	ds_write_b128 v18, v[106:109]
	v_mfma_f32_16x16x32_f16 v[40:43], v[118:121], v[110:113], v[40:43]
	ds_read_b128 v[118:121], v22 offset:53248
	s_waitcnt vmcnt(5)
	ds_write_b128 v19, v[134:137]
	v_mfma_f32_16x16x32_f16 v[70:73], v[122:125], v[90:93], v[70:73]
	ds_read_b128 v[90:93], v23 offset:16384
	v_mfma_f32_16x16x32_f16 v[48:51], v[122:125], v[110:113], v[48:51]
	ds_read_b128 v[110:113], v23 offset:18432
	s_waitcnt lgkmcnt(1)
	v_mfma_f32_16x16x32_f16 v[36:39], v[62:65], v[90:93], v[36:39]
	ds_read_b128 v[122:125], v22 offset:55296
	s_waitcnt lgkmcnt(1)
	v_mfma_f32_16x16x32_f16 v[66:69], v[62:65], v[110:113], v[66:69]
	s_waitcnt vmcnt(4)
	ds_write_b128 v20, v[158:161]
	v_mfma_f32_16x16x32_f16 v[44:47], v[74:77], v[90:93], v[44:47]
	s_waitcnt vmcnt(3)
	ds_write_b128 v17, v[94:97] offset:32768
	v_mfma_f32_16x16x32_f16 v[78:81], v[74:77], v[110:113], v[78:81]
	s_waitcnt vmcnt(2)
	ds_write_b128 v18, v[162:165] offset:32768
	v_mfma_f32_16x16x32_f16 v[82:85], v[118:121], v[90:93], v[82:85]
	s_waitcnt vmcnt(1)
	ds_write_b128 v19, v[166:169] offset:32768
	v_mfma_f32_16x16x32_f16 v[86:89], v[118:121], v[110:113], v[86:89]
	s_waitcnt vmcnt(0)
	ds_write_b128 v20, v[190:193] offset:32768
	s_waitcnt lgkmcnt(5)
	v_mfma_f32_16x16x32_f16 v[28:31], v[122:125], v[90:93], v[28:31]
	ds_read_b128 v[90:93], v23 offset:20480
	v_mfma_f32_16x16x32_f16 v[32:35], v[122:125], v[110:113], v[32:35]
	ds_read_b128 v[110:113], v23 offset:22528
	s_waitcnt lgkmcnt(1)
	v_mfma_f32_16x16x32_f16 v[98:101], v[62:65], v[90:93], v[98:101]
	s_waitcnt lgkmcnt(0)
	v_mfma_f32_16x16x32_f16 v[52:55], v[62:65], v[110:113], v[52:55]
	global_load_dwordx4 v[62:65], v[0:1], off offset:2688
	v_mfma_f32_16x16x32_f16 v[102:105], v[74:77], v[90:93], v[102:105]
	v_mfma_f32_16x16x32_f16 v[24:27], v[74:77], v[110:113], v[24:27]
	v_mfma_f32_16x16x32_f16 v[114:117], v[118:121], v[90:93], v[114:117]
	v_mfma_f32_16x16x32_f16 v[40:43], v[118:121], v[110:113], v[40:43]
	v_mfma_f32_16x16x32_f16 v[70:73], v[122:125], v[90:93], v[70:73]
	global_load_dwordx4 v[90:93], v[2:3], off offset:2688
	global_load_dwordx4 v[126:129], v[4:5], off offset:2688
	global_load_dwordx4 v[130:133], v[14:15], off offset:2688
	global_load_dwordx4 v[74:77], v[10:11], off offset:2688
	global_load_dwordx4 v[138:141], v[12:13], off offset:2688
	global_load_dwordx4 v[142:145], v[8:9], off offset:2688
	global_load_dwordx4 v[154:157], v[6:7], off offset:2688
	s_waitcnt lgkmcnt(0)
	s_barrier
; #define GL_LOAD(s_, kt_) if (VAR != 1) { a##s_##0 = GL_A(0, kt_); a##s_##1 = GL_A(1, kt_); a##s_##2 = GL_A(2, kt_); a##s_##3 = GL_A(3, kt_); b##s_##0 = GL_B(0, kt_); b##s_##1 = GL_B(1, kt_); b##s_##2 = GL_B(2, kt_); b##s_##3 = GL_B(3, kt_); }
; #define LDS_STORE(s_, buf_) if (VAR != 2) { LDS_ST1(sA, 0, buf_, a##s_##0) LDS_ST1(sA, 1, buf_, a##s_##1) LDS_ST1(sA, 2, buf_, a##s_##2) LDS_ST1(sA, 3, buf_, a##s_##3) LDS_ST1(sB, 0, buf_, b##s_##0) LDS_ST1(sB, 1, buf_, b##s_##1) LDS_ST1(sB, 2, buf_, b##s_##2) LDS_ST1(sB, 3, buf_, b##s_##3) }
;     ...
;   GL_LOAD(0, 0)
;   GL_LOAD(1, 1)
;   LDS_STORE(0, 0)
;   if (VAR != 4) __syncthreads();
; #pragma unroll
;   for (int kt = 0; kt < nk; kt += 2) {
;     if (kt + 2 < nk) { GL_LOAD(0, kt + 2) }
;     MMA_TILE(0)
;     LDS_STORE(1, 1)
;     if (VAR != 4) __syncthreads();
;     if (kt + 3 < nk) { GL_LOAD(1, kt + 3) }
;     MMA_TILE(1)
;     if (kt + 2 < nk) { LDS_STORE(0, 0) }
;     if (VAR != 4) __syncthreads();
	v_mfma_f32_16x16x32_f16 v[48:51], v[122:125], v[110:113], v[48:51]
	ds_read_b128 v[58:61], v16 offset:32768
	ds_read_b128 v[106:109], v21
	s_waitcnt lgkmcnt(0)
	v_mfma_f32_16x16x32_f16 v[36:39], v[58:61], v[106:109], v[36:39]
	ds_read_b128 v[94:97], v16 offset:34816
	ds_read_b128 v[110:113], v21 offset:2048
	s_waitcnt lgkmcnt(0)
	v_mfma_f32_16x16x32_f16 v[66:69], v[58:61], v[110:113], v[66:69]
	ds_read_b128 v[118:121], v16 offset:36864
	v_mfma_f32_16x16x32_f16 v[44:47], v[94:97], v[106:109], v[44:47]
	ds_read_b128 v[122:125], v16 offset:38912
	v_mfma_f32_16x16x32_f16 v[78:81], v[94:97], v[110:113], v[78:81]
	s_waitcnt lgkmcnt(1)
	v_mfma_f32_16x16x32_f16 v[82:85], v[118:121], v[106:109], v[82:85]
	v_mfma_f32_16x16x32_f16 v[86:89], v[118:121], v[110:113], v[86:89]
	s_waitcnt lgkmcnt(0)
	v_mfma_f32_16x16x32_f16 v[28:31], v[122:125], v[106:109], v[28:31]
	ds_read_b128 v[106:109], v21 offset:4096
	v_mfma_f32_16x16x32_f16 v[32:35], v[122:125], v[110:113], v[32:35]
	ds_read_b128 v[110:113], v21 offset:6144
	s_waitcnt lgkmcnt(1)
	v_mfma_f32_16x16x32_f16 v[98:101], v[58:61], v[106:109], v[98:101]
	s_waitcnt lgkmcnt(0)
	v_mfma_f32_16x16x32_f16 v[52:55], v[58:61], v[110:113], v[52:55]
	ds_read_b128 v[58:61], v22 offset:32768
	v_mfma_f32_16x16x32_f16 v[102:105], v[94:97], v[106:109], v[102:105]
	v_mfma_f32_16x16x32_f16 v[24:27], v[94:97], v[110:113], v[24:27]
	ds_read_b128 v[94:97], v22 offset:34816
	v_mfma_f32_16x16x32_f16 v[114:117], v[118:121], v[106:109], v[114:117]
	s_waitcnt vmcnt(7)
	ds_write_b128 v17, v[62:65] offset:16384
	s_waitcnt vmcnt(6)
	ds_write_b128 v18, v[90:93] offset:16384
	v_mfma_f32_16x16x32_f16 v[40:43], v[118:121], v[110:113], v[40:43]
	ds_read_b128 v[118:121], v22 offset:36864
	s_waitcnt vmcnt(5)
	ds_write_b128 v19, v[126:129] offset:16384
	v_mfma_f32_16x16x32_f16 v[70:73], v[122:125], v[106:109], v[70:73]
	ds_read_b128 v[106:109], v23
	v_mfma_f32_16x16x32_f16 v[48:51], v[122:125], v[110:113], v[48:51]
	ds_read_b128 v[110:113], v23 offset:2048
	s_waitcnt lgkmcnt(1)
	v_mfma_f32_16x16x32_f16 v[36:39], v[58:61], v[106:109], v[36:39]
	ds_read_b128 v[122:125], v22 offset:38912
	s_waitcnt lgkmcnt(1)
	v_mfma_f32_16x16x32_f16 v[66:69], v[58:61], v[110:113], v[66:69]
	s_waitcnt vmcnt(4)
	ds_write_b128 v20, v[130:133] offset:16384
	v_mfma_f32_16x16x32_f16 v[44:47], v[94:97], v[106:109], v[44:47]
	s_waitcnt vmcnt(3)
	ds_write_b128 v17, v[74:77] offset:49152
	v_mfma_f32_16x16x32_f16 v[78:81], v[94:97], v[110:113], v[78:81]
	s_waitcnt vmcnt(2)
	ds_write_b128 v18, v[138:141] offset:49152
	v_mfma_f32_16x16x32_f16 v[82:85], v[118:121], v[106:109], v[82:85]
	s_waitcnt vmcnt(1)
	ds_write_b128 v19, v[142:145] offset:49152
	v_mfma_f32_16x16x32_f16 v[86:89], v[118:121], v[110:113], v[86:89]
	s_waitcnt vmcnt(0)
	ds_write_b128 v20, v[154:157] offset:49152
	s_waitcnt lgkmcnt(5)
	v_mfma_f32_16x16x32_f16 v[28:31], v[122:125], v[106:109], v[28:31]
	ds_read_b128 v[106:109], v23 offset:4096
	v_mfma_f32_16x16x32_f16 v[32:35], v[122:125], v[110:113], v[32:35]
	ds_read_b128 v[110:113], v23 offset:6144
	s_waitcnt lgkmcnt(1)
	v_mfma_f32_16x16x32_f16 v[98:101], v[58:61], v[106:109], v[98:101]
	s_waitcnt lgkmcnt(0)
	v_mfma_f32_16x16x32_f16 v[52:55], v[58:61], v[110:113], v[52:55]
	global_load_dwordx4 v[58:61], v[0:1], off offset:2816
	v_mfma_f32_16x16x32_f16 v[102:105], v[94:97], v[106:109], v[102:105]
	v_mfma_f32_16x16x32_f16 v[24:27], v[94:97], v[110:113], v[24:27]
	v_mfma_f32_16x16x32_f16 v[114:117], v[118:121], v[106:109], v[114:117]
	v_mfma_f32_16x16x32_f16 v[40:43], v[118:121], v[110:113], v[40:43]
	v_mfma_f32_16x16x32_f16 v[70:73], v[122:125], v[106:109], v[70:73]
	global_load_dwordx4 v[106:109], v[2:3], off offset:2816
	global_load_dwordx4 v[134:137], v[4:5], off offset:2816
	global_load_dwordx4 v[158:161], v[14:15], off offset:2816
	global_load_dwordx4 v[94:97], v[10:11], off offset:2816
	global_load_dwordx4 v[162:165], v[12:13], off offset:2816
	global_load_dwordx4 v[166:169], v[8:9], off offset:2816
	global_load_dwordx4 v[190:193], v[6:7], off offset:2816
	s_waitcnt lgkmcnt(0)
	s_barrier
	v_mfma_f32_16x16x32_f16 v[48:51], v[122:125], v[110:113], v[48:51]
	ds_read_b128 v[62:65], v16 offset:49152
	ds_read_b128 v[90:93], v21 offset:16384
	s_waitcnt lgkmcnt(0)
	v_mfma_f32_16x16x32_f16 v[36:39], v[62:65], v[90:93], v[36:39]
	ds_read_b128 v[74:77], v16 offset:51200
	ds_read_b128 v[110:113], v21 offset:18432
	s_waitcnt lgkmcnt(0)
	v_mfma_f32_16x16x32_f16 v[66:69], v[62:65], v[110:113], v[66:69]
	ds_read_b128 v[118:121], v16 offset:53248
	v_mfma_f32_16x16x32_f16 v[44:47], v[74:77], v[90:93], v[44:47]
	ds_read_b128 v[122:125], v16 offset:55296
	v_mfma_f32_16x16x32_f16 v[78:81], v[74:77], v[110:113], v[78:81]
	s_waitcnt lgkmcnt(1)
	v_mfma_f32_16x16x32_f16 v[82:85], v[118:121], v[90:93], v[82:85]
	v_mfma_f32_16x16x32_f16 v[86:89], v[118:121], v[110:113], v[86:89]
	s_waitcnt lgkmcnt(0)
	v_mfma_f32_16x16x32_f16 v[28:31], v[122:125], v[90:93], v[28:31]
	ds_read_b128 v[90:93], v21 offset:20480
	v_mfma_f32_16x16x32_f16 v[32:35], v[122:125], v[110:113], v[32:35]
	ds_read_b128 v[110:113], v21 offset:22528
	s_waitcnt lgkmcnt(1)
	v_mfma_f32_16x16x32_f16 v[98:101], v[62:65], v[90:93], v[98:101]
	s_waitcnt lgkmcnt(0)
	v_mfma_f32_16x16x32_f16 v[52:55], v[62:65], v[110:113], v[52:55]
	ds_read_b128 v[62:65], v22 offset:49152
	v_mfma_f32_16x16x32_f16 v[102:105], v[74:77], v[90:93], v[102:105]
	v_mfma_f32_16x16x32_f16 v[24:27], v[74:77], v[110:113], v[24:27]
	ds_read_b128 v[74:77], v22 offset:51200
	v_mfma_f32_16x16x32_f16 v[114:117], v[118:121], v[90:93], v[114:117]
	s_waitcnt vmcnt(7)
	ds_write_b128 v17, v[58:61]
	s_waitcnt vmcnt(6)
; #define GL_LOAD(s_, kt_) if (VAR != 1) { a##s_##0 = GL_A(0, kt_); a##s_##1 = GL_A(1, kt_); a##s_##2 = GL_A(2, kt_); a##s_##3 = GL_A(3, kt_); b##s_##0 = GL_B(0, kt_); b##s_##1 = GL_B(1, kt_); b##s_##2 = GL_B(2, kt_); b##s_##3 = GL_B(3, kt_); }
; #define LDS_STORE(s_, buf_) if (VAR != 2) { LDS_ST1(sA, 0, buf_, a##s_##0) LDS_ST1(sA, 1, buf_, a##s_##1) LDS_ST1(sA, 2, buf_, a##s_##2) LDS_ST1(sA, 3, buf_, a##s_##3) LDS_ST1(sB, 0, buf_, b##s_##0) LDS_ST1(sB, 1, buf_, b##s_##1) LDS_ST1(sB, 2, buf_, b##s_##2) LDS_ST1(sB, 3, buf_, b##s_##3) }
;     ...
;   GL_LOAD(0, 0)
;   GL_LOAD(1, 1)
;   LDS_STORE(0, 0)
;   if (VAR != 4) __syncthreads();
; #pragma unroll
;   for (int kt = 0; kt < nk; kt += 2) {
;     if (kt + 2 < nk) { GL_LOAD(0, kt + 2) }
;     MMA_TILE(0)
;     LDS_STORE(1, 1)
;     if (VAR != 4) __syncthreads();
;     if (kt + 3 < nk) { GL_LOAD(1, kt + 3) }
;     MMA_TILE(1)
;     if (kt + 2 < nk) { LDS_STORE(0, 0) }
;     if (VAR != 4) __syncthreads();
	ds_write_b128 v18, v[106:109]
	v_mfma_f32_16x16x32_f16 v[40:43], v[118:121], v[110:113], v[40:43]
	ds_read_b128 v[118:121], v22 offset:53248
	s_waitcnt vmcnt(5)
	ds_write_b128 v19, v[134:137]
	v_mfma_f32_16x16x32_f16 v[70:73], v[122:125], v[90:93], v[70:73]
	ds_read_b128 v[90:93], v23 offset:16384
	v_mfma_f32_16x16x32_f16 v[48:51], v[122:125], v[110:113], v[48:51]
	ds_read_b128 v[110:113], v23 offset:18432
	s_waitcnt lgkmcnt(1)
	v_mfma_f32_16x16x32_f16 v[36:39], v[62:65], v[90:93], v[36:39]
	ds_read_b128 v[122:125], v22 offset:55296
	s_waitcnt lgkmcnt(1)
	v_mfma_f32_16x16x32_f16 v[66:69], v[62:65], v[110:113], v[66:69]
	s_waitcnt vmcnt(4)
	ds_write_b128 v20, v[158:161]
	v_mfma_f32_16x16x32_f16 v[44:47], v[74:77], v[90:93], v[44:47]
	s_waitcnt vmcnt(3)
	ds_write_b128 v17, v[94:97] offset:32768
	v_mfma_f32_16x16x32_f16 v[78:81], v[74:77], v[110:113], v[78:81]
	s_waitcnt vmcnt(2)
	ds_write_b128 v18, v[162:165] offset:32768
	v_mfma_f32_16x16x32_f16 v[82:85], v[118:121], v[90:93], v[82:85]
	s_waitcnt vmcnt(1)
	ds_write_b128 v19, v[166:169] offset:32768
	v_mfma_f32_16x16x32_f16 v[86:89], v[118:121], v[110:113], v[86:89]
	s_waitcnt vmcnt(0)
	ds_write_b128 v20, v[190:193] offset:32768
	s_waitcnt lgkmcnt(5)
	v_mfma_f32_16x16x32_f16 v[28:31], v[122:125], v[90:93], v[28:31]
	ds_read_b128 v[90:93], v23 offset:20480
	v_mfma_f32_16x16x32_f16 v[32:35], v[122:125], v[110:113], v[32:35]
	ds_read_b128 v[110:113], v23 offset:22528
	s_waitcnt lgkmcnt(1)
	v_mfma_f32_16x16x32_f16 v[98:101], v[62:65], v[90:93], v[98:101]
	s_waitcnt lgkmcnt(0)
	v_mfma_f32_16x16x32_f16 v[52:55], v[62:65], v[110:113], v[52:55]
	global_load_dwordx4 v[62:65], v[0:1], off offset:2944
	v_mfma_f32_16x16x32_f16 v[102:105], v[74:77], v[90:93], v[102:105]
	v_mfma_f32_16x16x32_f16 v[24:27], v[74:77], v[110:113], v[24:27]
	v_mfma_f32_16x16x32_f16 v[114:117], v[118:121], v[90:93], v[114:117]
	v_mfma_f32_16x16x32_f16 v[40:43], v[118:121], v[110:113], v[40:43]
	v_mfma_f32_16x16x32_f16 v[70:73], v[122:125], v[90:93], v[70:73]
	global_load_dwordx4 v[90:93], v[2:3], off offset:2944
	global_load_dwordx4 v[126:129], v[4:5], off offset:2944
	global_load_dwordx4 v[130:133], v[14:15], off offset:2944
	global_load_dwordx4 v[74:77], v[10:11], off offset:2944
	global_load_dwordx4 v[138:141], v[12:13], off offset:2944
	global_load_dwordx4 v[142:145], v[8:9], off offset:2944
	global_load_dwordx4 v[154:157], v[6:7], off offset:2944
	s_waitcnt lgkmcnt(0)
	s_barrier
	v_mfma_f32_16x16x32_f16 v[48:51], v[122:125], v[110:113], v[48:51]
	ds_read_b128 v[58:61], v16 offset:32768
	ds_read_b128 v[106:109], v21
	s_waitcnt lgkmcnt(0)
	v_mfma_f32_16x16x32_f16 v[36:39], v[58:61], v[106:109], v[36:39]
	ds_read_b128 v[94:97], v16 offset:34816
	ds_read_b128 v[110:113], v21 offset:2048
	s_waitcnt lgkmcnt(0)
	v_mfma_f32_16x16x32_f16 v[66:69], v[58:61], v[110:113], v[66:69]
	ds_read_b128 v[118:121], v16 offset:36864
	v_mfma_f32_16x16x32_f16 v[44:47], v[94:97], v[106:109], v[44:47]
	ds_read_b128 v[122:125], v16 offset:38912
	v_mfma_f32_16x16x32_f16 v[78:81], v[94:97], v[110:113], v[78:81]
	s_waitcnt lgkmcnt(1)
	v_mfma_f32_16x16x32_f16 v[82:85], v[118:121], v[106:109], v[82:85]
	v_mfma_f32_16x16x32_f16 v[86:89], v[118:121], v[110:113], v[86:89]
	s_waitcnt lgkmcnt(0)
	v_mfma_f32_16x16x32_f16 v[28:31], v[122:125], v[106:109], v[28:31]
	ds_read_b128 v[106:109], v21 offset:4096
	v_mfma_f32_16x16x32_f16 v[32:35], v[122:125], v[110:113], v[32:35]
	ds_read_b128 v[110:113], v21 offset:6144
	s_waitcnt lgkmcnt(1)
	v_mfma_f32_16x16x32_f16 v[98:101], v[58:61], v[106:109], v[98:101]
	s_waitcnt lgkmcnt(0)
	v_mfma_f32_16x16x32_f16 v[52:55], v[58:61], v[110:113], v[52:55]
	ds_read_b128 v[58:61], v22 offset:32768
	v_mfma_f32_16x16x32_f16 v[102:105], v[94:97], v[106:109], v[102:105]
	v_mfma_f32_16x16x32_f16 v[24:27], v[94:97], v[110:113], v[24:27]
	ds_read_b128 v[94:97], v22 offset:34816
	v_mfma_f32_16x16x32_f16 v[114:117], v[118:121], v[106:109], v[114:117]
	s_waitcnt vmcnt(7)
	ds_write_b128 v17, v[62:65] offset:16384
	s_waitcnt vmcnt(6)
	ds_write_b128 v18, v[90:93] offset:16384
	v_mfma_f32_16x16x32_f16 v[40:43], v[118:121], v[110:113], v[40:43]
	ds_read_b128 v[118:121], v22 offset:36864
	s_waitcnt vmcnt(5)
	ds_write_b128 v19, v[126:129] offset:16384
	v_mfma_f32_16x16x32_f16 v[70:73], v[122:125], v[106:109], v[70:73]
	ds_read_b128 v[106:109], v23
	v_mfma_f32_16x16x32_f16 v[48:51], v[122:125], v[110:113], v[48:51]
	ds_read_b128 v[110:113], v23 offset:2048
	s_waitcnt lgkmcnt(1)
	v_mfma_f32_16x16x32_f16 v[36:39], v[58:61], v[106:109], v[36:39]
	ds_read_b128 v[122:125], v22 offset:38912
	s_waitcnt lgkmcnt(1)
	v_mfma_f32_16x16x32_f16 v[66:69], v[58:61], v[110:113], v[66:69]
	s_waitcnt vmcnt(4)
	ds_write_b128 v20, v[130:133] offset:16384
	v_mfma_f32_16x16x32_f16 v[44:47], v[94:97], v[106:109], v[44:47]
	s_waitcnt vmcnt(3)
	ds_write_b128 v17, v[74:77] offset:49152
	v_mfma_f32_16x16x32_f16 v[78:81], v[94:97], v[110:113], v[78:81]
	s_waitcnt vmcnt(2)
	ds_write_b128 v18, v[138:141] offset:49152
	v_mfma_f32_16x16x32_f16 v[82:85], v[118:121], v[106:109], v[82:85]
	s_waitcnt vmcnt(1)
	ds_write_b128 v19, v[142:145] offset:49152
	v_mfma_f32_16x16x32_f16 v[86:89], v[118:121], v[110:113], v[86:89]
	s_waitcnt vmcnt(0)
	ds_write_b128 v20, v[154:157] offset:49152
	s_waitcnt lgkmcnt(5)
	v_mfma_f32_16x16x32_f16 v[28:31], v[122:125], v[106:109], v[28:31]
	ds_read_b128 v[106:109], v23 offset:4096
	v_mfma_f32_16x16x32_f16 v[32:35], v[122:125], v[110:113], v[32:35]
	ds_read_b128 v[110:113], v23 offset:6144
	s_waitcnt lgkmcnt(1)
	v_mfma_f32_16x16x32_f16 v[98:101], v[58:61], v[106:109], v[98:101]
	s_waitcnt lgkmcnt(0)
	v_mfma_f32_16x16x32_f16 v[52:55], v[58:61], v[110:113], v[52:55]
	global_load_dwordx4 v[58:61], v[0:1], off offset:3072
	v_mfma_f32_16x16x32_f16 v[102:105], v[94:97], v[106:109], v[102:105]
	v_mfma_f32_16x16x32_f16 v[24:27], v[94:97], v[110:113], v[24:27]
	v_mfma_f32_16x16x32_f16 v[114:117], v[118:121], v[106:109], v[114:117]
	v_mfma_f32_16x16x32_f16 v[40:43], v[118:121], v[110:113], v[40:43]
	v_mfma_f32_16x16x32_f16 v[70:73], v[122:125], v[106:109], v[70:73]
	global_load_dwordx4 v[106:109], v[2:3], off offset:3072
	global_load_dwordx4 v[134:137], v[4:5], off offset:3072
	global_load_dwordx4 v[158:161], v[14:15], off offset:3072
	global_load_dwordx4 v[94:97], v[10:11], off offset:3072
	global_load_dwordx4 v[162:165], v[12:13], off offset:3072
	global_load_dwordx4 v[166:169], v[8:9], off offset:3072
	global_load_dwordx4 v[190:193], v[6:7], off offset:3072
	s_waitcnt lgkmcnt(0)
	s_barrier
; #define GL_LOAD(s_, kt_) if (VAR != 1) { a##s_##0 = GL_A(0, kt_); a##s_##1 = GL_A(1, kt_); a##s_##2 = GL_A(2, kt_); a##s_##3 = GL_A(3, kt_); b##s_##0 = GL_B(0, kt_); b##s_##1 = GL_B(1, kt_); b##s_##2 = GL_B(2, kt_); b##s_##3 = GL_B(3, kt_); }
; #define LDS_STORE(s_, buf_) if (VAR != 2) { LDS_ST1(sA, 0, buf_, a##s_##0) LDS_ST1(sA, 1, buf_, a##s_##1) LDS_ST1(sA, 2, buf_, a##s_##2) LDS_ST1(sA, 3, buf_, a##s_##3) LDS_ST1(sB, 0, buf_, b##s_##0) LDS_ST1(sB, 1, buf_, b##s_##1) LDS_ST1(sB, 2, buf_, b##s_##2) LDS_ST1(sB, 3, buf_, b##s_##3) }
;     ...
;   GL_LOAD(0, 0)
;   GL_LOAD(1, 1)
;   LDS_STORE(0, 0)
;   if (VAR != 4) __syncthreads();
; #pragma unroll
;   for (int kt = 0; kt < nk; kt += 2) {
;     if (kt + 2 < nk) { GL_LOAD(0, kt + 2) }
;     MMA_TILE(0)
;     LDS_STORE(1, 1)
;     if (VAR != 4) __syncthreads();
;     if (kt + 3 < nk) { GL_LOAD(1, kt + 3) }
;     MMA_TILE(1)
;     if (kt + 2 < nk) { LDS_STORE(0, 0) }
;     if (VAR != 4) __syncthreads();
	v_mfma_f32_16x16x32_f16 v[48:51], v[122:125], v[110:113], v[48:51]
	ds_read_b128 v[62:65], v16 offset:49152
	ds_read_b128 v[90:93], v21 offset:16384
	s_waitcnt lgkmcnt(0)
	v_mfma_f32_16x16x32_f16 v[36:39], v[62:65], v[90:93], v[36:39]
	ds_read_b128 v[74:77], v16 offset:51200
	ds_read_b128 v[110:113], v21 offset:18432
	s_waitcnt lgkmcnt(0)
	v_mfma_f32_16x16x32_f16 v[66:69], v[62:65], v[110:113], v[66:69]
	ds_read_b128 v[118:121], v16 offset:53248
	v_mfma_f32_16x16x32_f16 v[44:47], v[74:77], v[90:93], v[44:47]
	ds_read_b128 v[122:125], v16 offset:55296
	v_mfma_f32_16x16x32_f16 v[78:81], v[74:77], v[110:113], v[78:81]
	s_waitcnt lgkmcnt(1)
	v_mfma_f32_16x16x32_f16 v[82:85], v[118:121], v[90:93], v[82:85]
	v_mfma_f32_16x16x32_f16 v[86:89], v[118:121], v[110:113], v[86:89]
	s_waitcnt lgkmcnt(0)
	v_mfma_f32_16x16x32_f16 v[28:31], v[122:125], v[90:93], v[28:31]
	ds_read_b128 v[90:93], v21 offset:20480
	v_mfma_f32_16x16x32_f16 v[32:35], v[122:125], v[110:113], v[32:35]
	ds_read_b128 v[110:113], v21 offset:22528
	s_waitcnt lgkmcnt(1)
	v_mfma_f32_16x16x32_f16 v[98:101], v[62:65], v[90:93], v[98:101]
	s_waitcnt lgkmcnt(0)
	v_mfma_f32_16x16x32_f16 v[52:55], v[62:65], v[110:113], v[52:55]
	ds_read_b128 v[62:65], v22 offset:49152
	v_mfma_f32_16x16x32_f16 v[102:105], v[74:77], v[90:93], v[102:105]
	v_mfma_f32_16x16x32_f16 v[24:27], v[74:77], v[110:113], v[24:27]
	ds_read_b128 v[74:77], v22 offset:51200
	v_mfma_f32_16x16x32_f16 v[114:117], v[118:121], v[90:93], v[114:117]
	s_waitcnt vmcnt(7)
	ds_write_b128 v17, v[58:61]
	s_waitcnt vmcnt(6)
	ds_write_b128 v18, v[106:109]
	v_mfma_f32_16x16x32_f16 v[40:43], v[118:121], v[110:113], v[40:43]
	ds_read_b128 v[118:121], v22 offset:53248
	s_waitcnt vmcnt(5)
	ds_write_b128 v19, v[134:137]
	v_mfma_f32_16x16x32_f16 v[70:73], v[122:125], v[90:93], v[70:73]
	ds_read_b128 v[90:93], v23 offset:16384
	v_mfma_f32_16x16x32_f16 v[48:51], v[122:125], v[110:113], v[48:51]
	ds_read_b128 v[110:113], v23 offset:18432
	s_waitcnt lgkmcnt(1)
	v_mfma_f32_16x16x32_f16 v[36:39], v[62:65], v[90:93], v[36:39]
	ds_read_b128 v[122:125], v22 offset:55296
	s_waitcnt lgkmcnt(1)
	v_mfma_f32_16x16x32_f16 v[66:69], v[62:65], v[110:113], v[66:69]
	s_waitcnt vmcnt(4)
	ds_write_b128 v20, v[158:161]
	v_mfma_f32_16x16x32_f16 v[44:47], v[74:77], v[90:93], v[44:47]
	s_waitcnt vmcnt(3)
	ds_write_b128 v17, v[94:97] offset:32768
	v_mfma_f32_16x16x32_f16 v[78:81], v[74:77], v[110:113], v[78:81]
	s_waitcnt vmcnt(2)
	ds_write_b128 v18, v[162:165] offset:32768
	v_mfma_f32_16x16x32_f16 v[82:85], v[118:121], v[90:93], v[82:85]
	s_waitcnt vmcnt(1)
	ds_write_b128 v19, v[166:169] offset:32768
	v_mfma_f32_16x16x32_f16 v[86:89], v[118:121], v[110:113], v[86:89]
	s_waitcnt vmcnt(0)
	ds_write_b128 v20, v[190:193] offset:32768
	s_waitcnt lgkmcnt(5)
	v_mfma_f32_16x16x32_f16 v[28:31], v[122:125], v[90:93], v[28:31]
	ds_read_b128 v[90:93], v23 offset:20480
	v_mfma_f32_16x16x32_f16 v[32:35], v[122:125], v[110:113], v[32:35]
	ds_read_b128 v[110:113], v23 offset:22528
	s_waitcnt lgkmcnt(1)
	v_mfma_f32_16x16x32_f16 v[98:101], v[62:65], v[90:93], v[98:101]
	s_waitcnt lgkmcnt(0)
	v_mfma_f32_16x16x32_f16 v[52:55], v[62:65], v[110:113], v[52:55]
	global_load_dwordx4 v[62:65], v[0:1], off offset:3200
	v_mfma_f32_16x16x32_f16 v[102:105], v[74:77], v[90:93], v[102:105]
	v_mfma_f32_16x16x32_f16 v[24:27], v[74:77], v[110:113], v[24:27]
	v_mfma_f32_16x16x32_f16 v[114:117], v[118:121], v[90:93], v[114:117]
	v_mfma_f32_16x16x32_f16 v[40:43], v[118:121], v[110:113], v[40:43]
	v_mfma_f32_16x16x32_f16 v[70:73], v[122:125], v[90:93], v[70:73]
	global_load_dwordx4 v[90:93], v[2:3], off offset:3200
	global_load_dwordx4 v[126:129], v[4:5], off offset:3200
	global_load_dwordx4 v[130:133], v[14:15], off offset:3200
	global_load_dwordx4 v[74:77], v[10:11], off offset:3200
	global_load_dwordx4 v[138:141], v[12:13], off offset:3200
	global_load_dwordx4 v[142:145], v[8:9], off offset:3200
	global_load_dwordx4 v[154:157], v[6:7], off offset:3200
	s_waitcnt lgkmcnt(0)
	s_barrier
	v_mfma_f32_16x16x32_f16 v[48:51], v[122:125], v[110:113], v[48:51]
	ds_read_b128 v[58:61], v16 offset:32768
	ds_read_b128 v[106:109], v21
	s_waitcnt lgkmcnt(0)
	v_mfma_f32_16x16x32_f16 v[36:39], v[58:61], v[106:109], v[36:39]
	ds_read_b128 v[94:97], v16 offset:34816
	ds_read_b128 v[110:113], v21 offset:2048
	s_waitcnt lgkmcnt(0)
	v_mfma_f32_16x16x32_f16 v[66:69], v[58:61], v[110:113], v[66:69]
	ds_read_b128 v[118:121], v16 offset:36864
	v_mfma_f32_16x16x32_f16 v[44:47], v[94:97], v[106:109], v[44:47]
	ds_read_b128 v[122:125], v16 offset:38912
	v_mfma_f32_16x16x32_f16 v[78:81], v[94:97], v[110:113], v[78:81]
	s_waitcnt lgkmcnt(1)
	v_mfma_f32_16x16x32_f16 v[82:85], v[118:121], v[106:109], v[82:85]
	v_mfma_f32_16x16x32_f16 v[86:89], v[118:121], v[110:113], v[86:89]
	s_waitcnt lgkmcnt(0)
	v_mfma_f32_16x16x32_f16 v[28:31], v[122:125], v[106:109], v[28:31]
	ds_read_b128 v[106:109], v21 offset:4096
	v_mfma_f32_16x16x32_f16 v[32:35], v[122:125], v[110:113], v[32:35]
	ds_read_b128 v[110:113], v21 offset:6144
	s_waitcnt lgkmcnt(1)
	v_mfma_f32_16x16x32_f16 v[98:101], v[58:61], v[106:109], v[98:101]
	s_waitcnt lgkmcnt(0)
	v_mfma_f32_16x16x32_f16 v[52:55], v[58:61], v[110:113], v[52:55]
	ds_read_b128 v[58:61], v22 offset:32768
	v_mfma_f32_16x16x32_f16 v[102:105], v[94:97], v[106:109], v[102:105]
	v_mfma_f32_16x16x32_f16 v[24:27], v[94:97], v[110:113], v[24:27]
	ds_read_b128 v[94:97], v22 offset:34816
	v_mfma_f32_16x16x32_f16 v[114:117], v[118:121], v[106:109], v[114:117]
	s_waitcnt vmcnt(7)
	ds_write_b128 v17, v[62:65] offset:16384
	s_waitcnt vmcnt(6)
; #define GL_LOAD(s_, kt_) if (VAR != 1) { a##s_##0 = GL_A(0, kt_); a##s_##1 = GL_A(1, kt_); a##s_##2 = GL_A(2, kt_); a##s_##3 = GL_A(3, kt_); b##s_##0 = GL_B(0, kt_); b##s_##1 = GL_B(1, kt_); b##s_##2 = GL_B(2, kt_); b##s_##3 = GL_B(3, kt_); }
; #define LDS_STORE(s_, buf_) if (VAR != 2) { LDS_ST1(sA, 0, buf_, a##s_##0) LDS_ST1(sA, 1, buf_, a##s_##1) LDS_ST1(sA, 2, buf_, a##s_##2) LDS_ST1(sA, 3, buf_, a##s_##3) LDS_ST1(sB, 0, buf_, b##s_##0) LDS_ST1(sB, 1, buf_, b##s_##1) LDS_ST1(sB, 2, buf_, b##s_##2) LDS_ST1(sB, 3, buf_, b##s_##3) }
;     ...
;   GL_LOAD(0, 0)
;   GL_LOAD(1, 1)
;   LDS_STORE(0, 0)
;   if (VAR != 4) __syncthreads();
; #pragma unroll
;   for (int kt = 0; kt < nk; kt += 2) {
;     if (kt + 2 < nk) { GL_LOAD(0, kt + 2) }
;     MMA_TILE(0)
;     LDS_STORE(1, 1)
;     if (VAR != 4) __syncthreads();
;     if (kt + 3 < nk) { GL_LOAD(1, kt + 3) }
;     MMA_TILE(1)
;     if (kt + 2 < nk) { LDS_STORE(0, 0) }
;     if (VAR != 4) __syncthreads();
	ds_write_b128 v18, v[90:93] offset:16384
	v_mfma_f32_16x16x32_f16 v[40:43], v[118:121], v[110:113], v[40:43]
	ds_read_b128 v[118:121], v22 offset:36864
	s_waitcnt vmcnt(5)
	ds_write_b128 v19, v[126:129] offset:16384
	v_mfma_f32_16x16x32_f16 v[70:73], v[122:125], v[106:109], v[70:73]
	ds_read_b128 v[106:109], v23
	v_mfma_f32_16x16x32_f16 v[48:51], v[122:125], v[110:113], v[48:51]
	ds_read_b128 v[110:113], v23 offset:2048
	s_waitcnt lgkmcnt(1)
	v_mfma_f32_16x16x32_f16 v[36:39], v[58:61], v[106:109], v[36:39]
	ds_read_b128 v[122:125], v22 offset:38912
	s_waitcnt lgkmcnt(1)
	v_mfma_f32_16x16x32_f16 v[66:69], v[58:61], v[110:113], v[66:69]
	s_waitcnt vmcnt(4)
	ds_write_b128 v20, v[130:133] offset:16384
	v_mfma_f32_16x16x32_f16 v[44:47], v[94:97], v[106:109], v[44:47]
	s_waitcnt vmcnt(3)
	ds_write_b128 v17, v[74:77] offset:49152
	v_mfma_f32_16x16x32_f16 v[78:81], v[94:97], v[110:113], v[78:81]
	s_waitcnt vmcnt(2)
	ds_write_b128 v18, v[138:141] offset:49152
	v_mfma_f32_16x16x32_f16 v[82:85], v[118:121], v[106:109], v[82:85]
	s_waitcnt vmcnt(1)
	ds_write_b128 v19, v[142:145] offset:49152
	v_mfma_f32_16x16x32_f16 v[86:89], v[118:121], v[110:113], v[86:89]
	s_waitcnt vmcnt(0)
	ds_write_b128 v20, v[154:157] offset:49152
	s_waitcnt lgkmcnt(5)
	v_mfma_f32_16x16x32_f16 v[28:31], v[122:125], v[106:109], v[28:31]
	ds_read_b128 v[106:109], v23 offset:4096
	v_mfma_f32_16x16x32_f16 v[32:35], v[122:125], v[110:113], v[32:35]
	ds_read_b128 v[110:113], v23 offset:6144
	s_waitcnt lgkmcnt(1)
	v_mfma_f32_16x16x32_f16 v[98:101], v[58:61], v[106:109], v[98:101]
	s_waitcnt lgkmcnt(0)
	v_mfma_f32_16x16x32_f16 v[52:55], v[58:61], v[110:113], v[52:55]
	global_load_dwordx4 v[58:61], v[0:1], off offset:3328
	v_mfma_f32_16x16x32_f16 v[102:105], v[94:97], v[106:109], v[102:105]
	v_mfma_f32_16x16x32_f16 v[24:27], v[94:97], v[110:113], v[24:27]
	v_mfma_f32_16x16x32_f16 v[114:117], v[118:121], v[106:109], v[114:117]
	v_mfma_f32_16x16x32_f16 v[40:43], v[118:121], v[110:113], v[40:43]
	v_mfma_f32_16x16x32_f16 v[70:73], v[122:125], v[106:109], v[70:73]
	global_load_dwordx4 v[106:109], v[2:3], off offset:3328
	global_load_dwordx4 v[134:137], v[4:5], off offset:3328
	global_load_dwordx4 v[158:161], v[14:15], off offset:3328
	global_load_dwordx4 v[94:97], v[10:11], off offset:3328
	global_load_dwordx4 v[162:165], v[12:13], off offset:3328
	global_load_dwordx4 v[166:169], v[8:9], off offset:3328
	global_load_dwordx4 v[190:193], v[6:7], off offset:3328
	s_waitcnt lgkmcnt(0)
	s_barrier
	v_mfma_f32_16x16x32_f16 v[48:51], v[122:125], v[110:113], v[48:51]
	ds_read_b128 v[62:65], v16 offset:49152
	ds_read_b128 v[90:93], v21 offset:16384
	s_waitcnt lgkmcnt(0)
	v_mfma_f32_16x16x32_f16 v[36:39], v[62:65], v[90:93], v[36:39]
	ds_read_b128 v[74:77], v16 offset:51200
	ds_read_b128 v[110:113], v21 offset:18432
	s_waitcnt lgkmcnt(0)
	v_mfma_f32_16x16x32_f16 v[66:69], v[62:65], v[110:113], v[66:69]
	ds_read_b128 v[118:121], v16 offset:53248
	v_mfma_f32_16x16x32_f16 v[44:47], v[74:77], v[90:93], v[44:47]
	ds_read_b128 v[122:125], v16 offset:55296
	v_mfma_f32_16x16x32_f16 v[78:81], v[74:77], v[110:113], v[78:81]
	s_waitcnt lgkmcnt(1)
	v_mfma_f32_16x16x32_f16 v[82:85], v[118:121], v[90:93], v[82:85]
	v_mfma_f32_16x16x32_f16 v[86:89], v[118:121], v[110:113], v[86:89]
	s_waitcnt lgkmcnt(0)
	v_mfma_f32_16x16x32_f16 v[28:31], v[122:125], v[90:93], v[28:31]
	ds_read_b128 v[90:93], v21 offset:20480
	v_mfma_f32_16x16x32_f16 v[32:35], v[122:125], v[110:113], v[32:35]
	ds_read_b128 v[110:113], v21 offset:22528
	s_waitcnt lgkmcnt(1)
	v_mfma_f32_16x16x32_f16 v[98:101], v[62:65], v[90:93], v[98:101]
	s_waitcnt lgkmcnt(0)
	v_mfma_f32_16x16x32_f16 v[52:55], v[62:65], v[110:113], v[52:55]
	ds_read_b128 v[62:65], v22 offset:49152
	v_mfma_f32_16x16x32_f16 v[102:105], v[74:77], v[90:93], v[102:105]
	v_mfma_f32_16x16x32_f16 v[24:27], v[74:77], v[110:113], v[24:27]
	ds_read_b128 v[74:77], v22 offset:51200
	v_mfma_f32_16x16x32_f16 v[114:117], v[118:121], v[90:93], v[114:117]
	s_waitcnt vmcnt(7)
	ds_write_b128 v17, v[58:61]
	s_waitcnt vmcnt(6)
	ds_write_b128 v18, v[106:109]
	v_mfma_f32_16x16x32_f16 v[40:43], v[118:121], v[110:113], v[40:43]
	ds_read_b128 v[118:121], v22 offset:53248
	s_waitcnt vmcnt(5)
	ds_write_b128 v19, v[134:137]
	v_mfma_f32_16x16x32_f16 v[70:73], v[122:125], v[90:93], v[70:73]
	ds_read_b128 v[90:93], v23 offset:16384
	v_mfma_f32_16x16x32_f16 v[48:51], v[122:125], v[110:113], v[48:51]
	ds_read_b128 v[110:113], v23 offset:18432
	s_waitcnt lgkmcnt(1)
	v_mfma_f32_16x16x32_f16 v[36:39], v[62:65], v[90:93], v[36:39]
	ds_read_b128 v[122:125], v22 offset:55296
	s_waitcnt lgkmcnt(1)
	v_mfma_f32_16x16x32_f16 v[66:69], v[62:65], v[110:113], v[66:69]
	s_waitcnt vmcnt(4)
	ds_write_b128 v20, v[158:161]
	v_mfma_f32_16x16x32_f16 v[44:47], v[74:77], v[90:93], v[44:47]
	s_waitcnt vmcnt(3)
	ds_write_b128 v17, v[94:97] offset:32768
	v_mfma_f32_16x16x32_f16 v[78:81], v[74:77], v[110:113], v[78:81]
	s_waitcnt vmcnt(2)
	ds_write_b128 v18, v[162:165] offset:32768
	v_mfma_f32_16x16x32_f16 v[82:85], v[118:121], v[90:93], v[82:85]
	s_waitcnt vmcnt(1)
	ds_write_b128 v19, v[166:169] offset:32768
	v_mfma_f32_16x16x32_f16 v[86:89], v[118:121], v[110:113], v[86:89]
	s_waitcnt vmcnt(0)
	ds_write_b128 v20, v[190:193] offset:32768
	s_waitcnt lgkmcnt(5)
	v_mfma_f32_16x16x32_f16 v[28:31], v[122:125], v[90:93], v[28:31]
	ds_read_b128 v[90:93], v23 offset:20480
	v_mfma_f32_16x16x32_f16 v[32:35], v[122:125], v[110:113], v[32:35]
	ds_read_b128 v[110:113], v23 offset:22528
	s_waitcnt lgkmcnt(1)
	v_mfma_f32_16x16x32_f16 v[98:101], v[62:65], v[90:93], v[98:101]
	s_waitcnt lgkmcnt(0)
	v_mfma_f32_16x16x32_f16 v[52:55], v[62:65], v[110:113], v[52:55]
	global_load_dwordx4 v[62:65], v[0:1], off offset:3456
	v_mfma_f32_16x16x32_f16 v[102:105], v[74:77], v[90:93], v[102:105]
	v_mfma_f32_16x16x32_f16 v[24:27], v[74:77], v[110:113], v[24:27]
	v_mfma_f32_16x16x32_f16 v[114:117], v[118:121], v[90:93], v[114:117]
	v_mfma_f32_16x16x32_f16 v[40:43], v[118:121], v[110:113], v[40:43]
	v_mfma_f32_16x16x32_f16 v[70:73], v[122:125], v[90:93], v[70:73]
	global_load_dwordx4 v[90:93], v[2:3], off offset:3456
	global_load_dwordx4 v[126:129], v[4:5], off offset:3456
	global_load_dwordx4 v[130:133], v[14:15], off offset:3456
	global_load_dwordx4 v[74:77], v[10:11], off offset:3456
	global_load_dwordx4 v[138:141], v[12:13], off offset:3456
	global_load_dwordx4 v[142:145], v[8:9], off offset:3456
	global_load_dwordx4 v[154:157], v[6:7], off offset:3456
	s_waitcnt lgkmcnt(0)
	s_barrier
; #define GL_LOAD(s_, kt_) if (VAR != 1) { a##s_##0 = GL_A(0, kt_); a##s_##1 = GL_A(1, kt_); a##s_##2 = GL_A(2, kt_); a##s_##3 = GL_A(3, kt_); b##s_##0 = GL_B(0, kt_); b##s_##1 = GL_B(1, kt_); b##s_##2 = GL_B(2, kt_); b##s_##3 = GL_B(3, kt_); }
; #define LDS_STORE(s_, buf_) if (VAR != 2) { LDS_ST1(sA, 0, buf_, a##s_##0) LDS_ST1(sA, 1, buf_, a##s_##1) LDS_ST1(sA, 2, buf_, a##s_##2) LDS_ST1(sA, 3, buf_, a##s_##3) LDS_ST1(sB, 0, buf_, b##s_##0) LDS_ST1(sB, 1, buf_, b##s_##1) LDS_ST1(sB, 2, buf_, b##s_##2) LDS_ST1(sB, 3, buf_, b##s_##3) }
;     ...
;   GL_LOAD(0, 0)
;   GL_LOAD(1, 1)
;   LDS_STORE(0, 0)
;   if (VAR != 4) __syncthreads();
; #pragma unroll
;   for (int kt = 0; kt < nk; kt += 2) {
;     if (kt + 2 < nk) { GL_LOAD(0, kt + 2) }
;     MMA_TILE(0)
;     LDS_STORE(1, 1)
;     if (VAR != 4) __syncthreads();
;     if (kt + 3 < nk) { GL_LOAD(1, kt + 3) }
;     MMA_TILE(1)
;     if (kt + 2 < nk) { LDS_STORE(0, 0) }
;     if (VAR != 4) __syncthreads();
	v_mfma_f32_16x16x32_f16 v[48:51], v[122:125], v[110:113], v[48:51]
	ds_read_b128 v[58:61], v16 offset:32768
	ds_read_b128 v[106:109], v21
	s_waitcnt lgkmcnt(0)
	v_mfma_f32_16x16x32_f16 v[36:39], v[58:61], v[106:109], v[36:39]
	ds_read_b128 v[94:97], v16 offset:34816
	ds_read_b128 v[110:113], v21 offset:2048
	s_waitcnt lgkmcnt(0)
	v_mfma_f32_16x16x32_f16 v[66:69], v[58:61], v[110:113], v[66:69]
	ds_read_b128 v[118:121], v16 offset:36864
	v_mfma_f32_16x16x32_f16 v[44:47], v[94:97], v[106:109], v[44:47]
	ds_read_b128 v[122:125], v16 offset:38912
	v_mfma_f32_16x16x32_f16 v[78:81], v[94:97], v[110:113], v[78:81]
	s_waitcnt lgkmcnt(1)
	v_mfma_f32_16x16x32_f16 v[82:85], v[118:121], v[106:109], v[82:85]
	v_mfma_f32_16x16x32_f16 v[86:89], v[118:121], v[110:113], v[86:89]
	s_waitcnt lgkmcnt(0)
	v_mfma_f32_16x16x32_f16 v[28:31], v[122:125], v[106:109], v[28:31]
	ds_read_b128 v[106:109], v21 offset:4096
	v_mfma_f32_16x16x32_f16 v[32:35], v[122:125], v[110:113], v[32:35]
	ds_read_b128 v[110:113], v21 offset:6144
	s_waitcnt lgkmcnt(1)
	v_mfma_f32_16x16x32_f16 v[98:101], v[58:61], v[106:109], v[98:101]
	s_waitcnt lgkmcnt(0)
	v_mfma_f32_16x16x32_f16 v[52:55], v[58:61], v[110:113], v[52:55]
	ds_read_b128 v[58:61], v22 offset:32768
	v_mfma_f32_16x16x32_f16 v[102:105], v[94:97], v[106:109], v[102:105]
	v_mfma_f32_16x16x32_f16 v[24:27], v[94:97], v[110:113], v[24:27]
	ds_read_b128 v[94:97], v22 offset:34816
	v_mfma_f32_16x16x32_f16 v[114:117], v[118:121], v[106:109], v[114:117]
	s_waitcnt vmcnt(7)
	ds_write_b128 v17, v[62:65] offset:16384
	s_waitcnt vmcnt(6)
	ds_write_b128 v18, v[90:93] offset:16384
	v_mfma_f32_16x16x32_f16 v[40:43], v[118:121], v[110:113], v[40:43]
	ds_read_b128 v[118:121], v22 offset:36864
	s_waitcnt vmcnt(5)
	ds_write_b128 v19, v[126:129] offset:16384
	v_mfma_f32_16x16x32_f16 v[70:73], v[122:125], v[106:109], v[70:73]
	ds_read_b128 v[106:109], v23
	v_mfma_f32_16x16x32_f16 v[48:51], v[122:125], v[110:113], v[48:51]
	ds_read_b128 v[110:113], v23 offset:2048
	s_waitcnt lgkmcnt(1)
	v_mfma_f32_16x16x32_f16 v[36:39], v[58:61], v[106:109], v[36:39]
	ds_read_b128 v[122:125], v22 offset:38912
	s_waitcnt lgkmcnt(1)
	v_mfma_f32_16x16x32_f16 v[66:69], v[58:61], v[110:113], v[66:69]
	s_waitcnt vmcnt(4)
	ds_write_b128 v20, v[130:133] offset:16384
	v_mfma_f32_16x16x32_f16 v[44:47], v[94:97], v[106:109], v[44:47]
	s_waitcnt vmcnt(3)
	ds_write_b128 v17, v[74:77] offset:49152
	v_mfma_f32_16x16x32_f16 v[78:81], v[94:97], v[110:113], v[78:81]
	s_waitcnt vmcnt(2)
	ds_write_b128 v18, v[138:141] offset:49152
	v_mfma_f32_16x16x32_f16 v[82:85], v[118:121], v[106:109], v[82:85]
	s_waitcnt vmcnt(1)
	ds_write_b128 v19, v[142:145] offset:49152
	v_mfma_f32_16x16x32_f16 v[86:89], v[118:121], v[110:113], v[86:89]
	s_waitcnt vmcnt(0)
	ds_write_b128 v20, v[154:157] offset:49152
	s_waitcnt lgkmcnt(5)
	v_mfma_f32_16x16x32_f16 v[28:31], v[122:125], v[106:109], v[28:31]
	ds_read_b128 v[106:109], v23 offset:4096
	v_mfma_f32_16x16x32_f16 v[32:35], v[122:125], v[110:113], v[32:35]
	ds_read_b128 v[110:113], v23 offset:6144
	s_waitcnt lgkmcnt(1)
	v_mfma_f32_16x16x32_f16 v[98:101], v[58:61], v[106:109], v[98:101]
	s_waitcnt lgkmcnt(0)
	v_mfma_f32_16x16x32_f16 v[52:55], v[58:61], v[110:113], v[52:55]
	global_load_dwordx4 v[58:61], v[0:1], off offset:3584
	v_mfma_f32_16x16x32_f16 v[102:105], v[94:97], v[106:109], v[102:105]
	v_mfma_f32_16x16x32_f16 v[24:27], v[94:97], v[110:113], v[24:27]
	v_mfma_f32_16x16x32_f16 v[114:117], v[118:121], v[106:109], v[114:117]
	v_mfma_f32_16x16x32_f16 v[40:43], v[118:121], v[110:113], v[40:43]
	v_mfma_f32_16x16x32_f16 v[70:73], v[122:125], v[106:109], v[70:73]
	global_load_dwordx4 v[106:109], v[2:3], off offset:3584
	global_load_dwordx4 v[134:137], v[4:5], off offset:3584
	global_load_dwordx4 v[158:161], v[14:15], off offset:3584
	global_load_dwordx4 v[94:97], v[10:11], off offset:3584
	global_load_dwordx4 v[162:165], v[12:13], off offset:3584
	global_load_dwordx4 v[166:169], v[8:9], off offset:3584
	global_load_dwordx4 v[190:193], v[6:7], off offset:3584
	s_waitcnt lgkmcnt(0)
	s_barrier
	v_mfma_f32_16x16x32_f16 v[48:51], v[122:125], v[110:113], v[48:51]
	ds_read_b128 v[62:65], v16 offset:49152
	ds_read_b128 v[90:93], v21 offset:16384
	s_waitcnt lgkmcnt(0)
	v_mfma_f32_16x16x32_f16 v[36:39], v[62:65], v[90:93], v[36:39]
	ds_read_b128 v[74:77], v16 offset:51200
	ds_read_b128 v[110:113], v21 offset:18432
	s_waitcnt lgkmcnt(0)
	v_mfma_f32_16x16x32_f16 v[66:69], v[62:65], v[110:113], v[66:69]
	ds_read_b128 v[118:121], v16 offset:53248
	v_mfma_f32_16x16x32_f16 v[44:47], v[74:77], v[90:93], v[44:47]
	ds_read_b128 v[122:125], v16 offset:55296
	v_mfma_f32_16x16x32_f16 v[78:81], v[74:77], v[110:113], v[78:81]
	s_waitcnt lgkmcnt(1)
	v_mfma_f32_16x16x32_f16 v[82:85], v[118:121], v[90:93], v[82:85]
	v_mfma_f32_16x16x32_f16 v[86:89], v[118:121], v[110:113], v[86:89]
	s_waitcnt lgkmcnt(0)
	v_mfma_f32_16x16x32_f16 v[28:31], v[122:125], v[90:93], v[28:31]
	ds_read_b128 v[90:93], v21 offset:20480
	v_mfma_f32_16x16x32_f16 v[32:35], v[122:125], v[110:113], v[32:35]
	ds_read_b128 v[110:113], v21 offset:22528
	s_waitcnt lgkmcnt(1)
	v_mfma_f32_16x16x32_f16 v[98:101], v[62:65], v[90:93], v[98:101]
	s_waitcnt lgkmcnt(0)
	v_mfma_f32_16x16x32_f16 v[52:55], v[62:65], v[110:113], v[52:55]
	ds_read_b128 v[62:65], v22 offset:49152
	v_mfma_f32_16x16x32_f16 v[102:105], v[74:77], v[90:93], v[102:105]
	v_mfma_f32_16x16x32_f16 v[24:27], v[74:77], v[110:113], v[24:27]
	ds_read_b128 v[74:77], v22 offset:51200
	v_mfma_f32_16x16x32_f16 v[114:117], v[118:121], v[90:93], v[114:117]
	s_waitcnt vmcnt(7)
	ds_write_b128 v17, v[58:61]
	s_waitcnt vmcnt(6)
; #define GL_LOAD(s_, kt_) if (VAR != 1) { a##s_##0 = GL_A(0, kt_); a##s_##1 = GL_A(1, kt_); a##s_##2 = GL_A(2, kt_); a##s_##3 = GL_A(3, kt_); b##s_##0 = GL_B(0, kt_); b##s_##1 = GL_B(1, kt_); b##s_##2 = GL_B(2, kt_); b##s_##3 = GL_B(3, kt_); }
; #define LDS_STORE(s_, buf_) if (VAR != 2) { LDS_ST1(sA, 0, buf_, a##s_##0) LDS_ST1(sA, 1, buf_, a##s_##1) LDS_ST1(sA, 2, buf_, a##s_##2) LDS_ST1(sA, 3, buf_, a##s_##3) LDS_ST1(sB, 0, buf_, b##s_##0) LDS_ST1(sB, 1, buf_, b##s_##1) LDS_ST1(sB, 2, buf_, b##s_##2) LDS_ST1(sB, 3, buf_, b##s_##3) }
;     ...
;   GL_LOAD(0, 0)
;   GL_LOAD(1, 1)
;   LDS_STORE(0, 0)
;   if (VAR != 4) __syncthreads();
; #pragma unroll
;   for (int kt = 0; kt < nk; kt += 2) {
;     if (kt + 2 < nk) { GL_LOAD(0, kt + 2) }
;     MMA_TILE(0)
;     LDS_STORE(1, 1)
;     if (VAR != 4) __syncthreads();
;     if (kt + 3 < nk) { GL_LOAD(1, kt + 3) }
;     MMA_TILE(1)
;     if (kt + 2 < nk) { LDS_STORE(0, 0) }
;     if (VAR != 4) __syncthreads();
	ds_write_b128 v18, v[106:109]
	v_mfma_f32_16x16x32_f16 v[40:43], v[118:121], v[110:113], v[40:43]
	ds_read_b128 v[118:121], v22 offset:53248
	s_waitcnt vmcnt(5)
	ds_write_b128 v19, v[134:137]
	v_mfma_f32_16x16x32_f16 v[70:73], v[122:125], v[90:93], v[70:73]
	ds_read_b128 v[90:93], v23 offset:16384
	v_mfma_f32_16x16x32_f16 v[48:51], v[122:125], v[110:113], v[48:51]
	ds_read_b128 v[110:113], v23 offset:18432
	s_waitcnt lgkmcnt(1)
	v_mfma_f32_16x16x32_f16 v[36:39], v[62:65], v[90:93], v[36:39]
	ds_read_b128 v[122:125], v22 offset:55296
	s_waitcnt lgkmcnt(1)
	v_mfma_f32_16x16x32_f16 v[66:69], v[62:65], v[110:113], v[66:69]
	s_waitcnt vmcnt(4)
	ds_write_b128 v20, v[158:161]
	v_mfma_f32_16x16x32_f16 v[44:47], v[74:77], v[90:93], v[44:47]
	s_waitcnt vmcnt(3)
	ds_write_b128 v17, v[94:97] offset:32768
	v_mfma_f32_16x16x32_f16 v[78:81], v[74:77], v[110:113], v[78:81]
	s_waitcnt vmcnt(2)
	ds_write_b128 v18, v[162:165] offset:32768
	v_mfma_f32_16x16x32_f16 v[82:85], v[118:121], v[90:93], v[82:85]
	s_waitcnt vmcnt(1)
	ds_write_b128 v19, v[166:169] offset:32768
	v_mfma_f32_16x16x32_f16 v[86:89], v[118:121], v[110:113], v[86:89]
	s_waitcnt vmcnt(0)
	ds_write_b128 v20, v[190:193] offset:32768
	s_waitcnt lgkmcnt(5)
	v_mfma_f32_16x16x32_f16 v[28:31], v[122:125], v[90:93], v[28:31]
	ds_read_b128 v[90:93], v23 offset:20480
	v_mfma_f32_16x16x32_f16 v[32:35], v[122:125], v[110:113], v[32:35]
	ds_read_b128 v[110:113], v23 offset:22528
	s_waitcnt lgkmcnt(1)
	v_mfma_f32_16x16x32_f16 v[98:101], v[62:65], v[90:93], v[98:101]
	s_waitcnt lgkmcnt(0)
	v_mfma_f32_16x16x32_f16 v[52:55], v[62:65], v[110:113], v[52:55]
	global_load_dwordx4 v[62:65], v[0:1], off offset:3712
	v_mfma_f32_16x16x32_f16 v[102:105], v[74:77], v[90:93], v[102:105]
	v_mfma_f32_16x16x32_f16 v[24:27], v[74:77], v[110:113], v[24:27]
	v_mfma_f32_16x16x32_f16 v[114:117], v[118:121], v[90:93], v[114:117]
	v_mfma_f32_16x16x32_f16 v[40:43], v[118:121], v[110:113], v[40:43]
	v_mfma_f32_16x16x32_f16 v[70:73], v[122:125], v[90:93], v[70:73]
	global_load_dwordx4 v[90:93], v[2:3], off offset:3712
	global_load_dwordx4 v[126:129], v[4:5], off offset:3712
	global_load_dwordx4 v[130:133], v[14:15], off offset:3712
	global_load_dwordx4 v[74:77], v[10:11], off offset:3712
	global_load_dwordx4 v[138:141], v[12:13], off offset:3712
	global_load_dwordx4 v[142:145], v[8:9], off offset:3712
	global_load_dwordx4 v[154:157], v[6:7], off offset:3712
	s_waitcnt lgkmcnt(0)
	s_barrier
	v_mfma_f32_16x16x32_f16 v[48:51], v[122:125], v[110:113], v[48:51]
	ds_read_b128 v[58:61], v16 offset:32768
	ds_read_b128 v[106:109], v21
	s_waitcnt lgkmcnt(0)
	v_mfma_f32_16x16x32_f16 v[36:39], v[58:61], v[106:109], v[36:39]
	ds_read_b128 v[94:97], v16 offset:34816
	ds_read_b128 v[110:113], v21 offset:2048
	s_waitcnt lgkmcnt(0)
	v_mfma_f32_16x16x32_f16 v[66:69], v[58:61], v[110:113], v[66:69]
	ds_read_b128 v[118:121], v16 offset:36864
	v_mfma_f32_16x16x32_f16 v[44:47], v[94:97], v[106:109], v[44:47]
	ds_read_b128 v[122:125], v16 offset:38912
	v_mfma_f32_16x16x32_f16 v[78:81], v[94:97], v[110:113], v[78:81]
	s_waitcnt lgkmcnt(1)
	v_mfma_f32_16x16x32_f16 v[82:85], v[118:121], v[106:109], v[82:85]
	v_mfma_f32_16x16x32_f16 v[86:89], v[118:121], v[110:113], v[86:89]
	s_waitcnt lgkmcnt(0)
	v_mfma_f32_16x16x32_f16 v[28:31], v[122:125], v[106:109], v[28:31]
	ds_read_b128 v[106:109], v21 offset:4096
	v_mfma_f32_16x16x32_f16 v[32:35], v[122:125], v[110:113], v[32:35]
	ds_read_b128 v[110:113], v21 offset:6144
	s_waitcnt lgkmcnt(1)
	v_mfma_f32_16x16x32_f16 v[98:101], v[58:61], v[106:109], v[98:101]
	s_waitcnt lgkmcnt(0)
	v_mfma_f32_16x16x32_f16 v[52:55], v[58:61], v[110:113], v[52:55]
	ds_read_b128 v[58:61], v22 offset:32768
	v_mfma_f32_16x16x32_f16 v[102:105], v[94:97], v[106:109], v[102:105]
	v_mfma_f32_16x16x32_f16 v[24:27], v[94:97], v[110:113], v[24:27]
	ds_read_b128 v[94:97], v22 offset:34816
	v_mfma_f32_16x16x32_f16 v[114:117], v[118:121], v[106:109], v[114:117]
	s_waitcnt vmcnt(7)
	ds_write_b128 v17, v[62:65] offset:16384
	s_waitcnt vmcnt(6)
	ds_write_b128 v18, v[90:93] offset:16384
	v_mfma_f32_16x16x32_f16 v[40:43], v[118:121], v[110:113], v[40:43]
	ds_read_b128 v[118:121], v22 offset:36864
	s_waitcnt vmcnt(5)
	ds_write_b128 v19, v[126:129] offset:16384
	v_mfma_f32_16x16x32_f16 v[70:73], v[122:125], v[106:109], v[70:73]
	ds_read_b128 v[106:109], v23
	v_mfma_f32_16x16x32_f16 v[48:51], v[122:125], v[110:113], v[48:51]
	ds_read_b128 v[110:113], v23 offset:2048
	s_waitcnt lgkmcnt(1)
	v_mfma_f32_16x16x32_f16 v[36:39], v[58:61], v[106:109], v[36:39]
	ds_read_b128 v[122:125], v22 offset:38912
	s_waitcnt lgkmcnt(1)
	v_mfma_f32_16x16x32_f16 v[66:69], v[58:61], v[110:113], v[66:69]
	s_waitcnt vmcnt(4)
	ds_write_b128 v20, v[130:133] offset:16384
	v_mfma_f32_16x16x32_f16 v[44:47], v[94:97], v[106:109], v[44:47]
	s_waitcnt vmcnt(3)
	ds_write_b128 v17, v[74:77] offset:49152
	v_mfma_f32_16x16x32_f16 v[78:81], v[94:97], v[110:113], v[78:81]
	s_waitcnt vmcnt(2)
	ds_write_b128 v18, v[138:141] offset:49152
	v_mfma_f32_16x16x32_f16 v[82:85], v[118:121], v[106:109], v[82:85]
	s_waitcnt vmcnt(1)
	ds_write_b128 v19, v[142:145] offset:49152
	v_mfma_f32_16x16x32_f16 v[86:89], v[118:121], v[110:113], v[86:89]
	s_waitcnt vmcnt(0)
	ds_write_b128 v20, v[154:157] offset:49152
	s_waitcnt lgkmcnt(5)
	v_mfma_f32_16x16x32_f16 v[28:31], v[122:125], v[106:109], v[28:31]
	ds_read_b128 v[106:109], v23 offset:4096
	v_mfma_f32_16x16x32_f16 v[32:35], v[122:125], v[110:113], v[32:35]
	ds_read_b128 v[110:113], v23 offset:6144
	s_waitcnt lgkmcnt(1)
	v_mfma_f32_16x16x32_f16 v[98:101], v[58:61], v[106:109], v[98:101]
	s_waitcnt lgkmcnt(0)
	v_mfma_f32_16x16x32_f16 v[52:55], v[58:61], v[110:113], v[52:55]
	global_load_dwordx4 v[58:61], v[0:1], off offset:3840
	v_mfma_f32_16x16x32_f16 v[102:105], v[94:97], v[106:109], v[102:105]
	v_mfma_f32_16x16x32_f16 v[24:27], v[94:97], v[110:113], v[24:27]
	v_mfma_f32_16x16x32_f16 v[114:117], v[118:121], v[106:109], v[114:117]
	v_mfma_f32_16x16x32_f16 v[40:43], v[118:121], v[110:113], v[40:43]
	v_mfma_f32_16x16x32_f16 v[70:73], v[122:125], v[106:109], v[70:73]
	global_load_dwordx4 v[106:109], v[2:3], off offset:3840
	global_load_dwordx4 v[134:137], v[4:5], off offset:3840
	global_load_dwordx4 v[158:161], v[14:15], off offset:3840
	global_load_dwordx4 v[94:97], v[10:11], off offset:3840
	global_load_dwordx4 v[162:165], v[12:13], off offset:3840
	global_load_dwordx4 v[166:169], v[8:9], off offset:3840
	global_load_dwordx4 v[190:193], v[6:7], off offset:3840
	s_waitcnt lgkmcnt(0)
	s_barrier
; #define GL_LOAD(s_, kt_) if (VAR != 1) { a##s_##0 = GL_A(0, kt_); a##s_##1 = GL_A(1, kt_); a##s_##2 = GL_A(2, kt_); a##s_##3 = GL_A(3, kt_); b##s_##0 = GL_B(0, kt_); b##s_##1 = GL_B(1, kt_); b##s_##2 = GL_B(2, kt_); b##s_##3 = GL_B(3, kt_); }
; #define LDS_STORE(s_, buf_) if (VAR != 2) { LDS_ST1(sA, 0, buf_, a##s_##0) LDS_ST1(sA, 1, buf_, a##s_##1) LDS_ST1(sA, 2, buf_, a##s_##2) LDS_ST1(sA, 3, buf_, a##s_##3) LDS_ST1(sB, 0, buf_, b##s_##0) LDS_ST1(sB, 1, buf_, b##s_##1) LDS_ST1(sB, 2, buf_, b##s_##2) LDS_ST1(sB, 3, buf_, b##s_##3) }
;     ...
;   GL_LOAD(0, 0)
;   GL_LOAD(1, 1)
;   LDS_STORE(0, 0)
;   if (VAR != 4) __syncthreads();
; #pragma unroll
;   for (int kt = 0; kt < nk; kt += 2) {
;     if (kt + 2 < nk) { GL_LOAD(0, kt + 2) }
;     MMA_TILE(0)
;     LDS_STORE(1, 1)
;     if (VAR != 4) __syncthreads();
;     if (kt + 3 < nk) { GL_LOAD(1, kt + 3) }
;     MMA_TILE(1)
;     if (kt + 2 < nk) { LDS_STORE(0, 0) }
;     if (VAR != 4) __syncthreads();
	v_mfma_f32_16x16x32_f16 v[48:51], v[122:125], v[110:113], v[48:51]
	ds_read_b128 v[62:65], v16 offset:49152
	ds_read_b128 v[90:93], v21 offset:16384
	s_waitcnt lgkmcnt(0)
	v_mfma_f32_16x16x32_f16 v[36:39], v[62:65], v[90:93], v[36:39]
	ds_read_b128 v[74:77], v16 offset:51200
	ds_read_b128 v[110:113], v21 offset:18432
	s_waitcnt lgkmcnt(0)
	v_mfma_f32_16x16x32_f16 v[66:69], v[62:65], v[110:113], v[66:69]
	ds_read_b128 v[118:121], v16 offset:53248
	v_mfma_f32_16x16x32_f16 v[44:47], v[74:77], v[90:93], v[44:47]
	ds_read_b128 v[122:125], v16 offset:55296
	v_mfma_f32_16x16x32_f16 v[78:81], v[74:77], v[110:113], v[78:81]
	s_waitcnt lgkmcnt(1)
	v_mfma_f32_16x16x32_f16 v[82:85], v[118:121], v[90:93], v[82:85]
	v_mfma_f32_16x16x32_f16 v[86:89], v[118:121], v[110:113], v[86:89]
	s_waitcnt lgkmcnt(0)
	v_mfma_f32_16x16x32_f16 v[28:31], v[122:125], v[90:93], v[28:31]
	ds_read_b128 v[90:93], v21 offset:20480
	v_mfma_f32_16x16x32_f16 v[32:35], v[122:125], v[110:113], v[32:35]
	ds_read_b128 v[110:113], v21 offset:22528
	s_waitcnt lgkmcnt(1)
	v_mfma_f32_16x16x32_f16 v[98:101], v[62:65], v[90:93], v[98:101]
	s_waitcnt lgkmcnt(0)
	v_mfma_f32_16x16x32_f16 v[52:55], v[62:65], v[110:113], v[52:55]
	ds_read_b128 v[62:65], v22 offset:49152
	v_mfma_f32_16x16x32_f16 v[102:105], v[74:77], v[90:93], v[102:105]
	v_mfma_f32_16x16x32_f16 v[24:27], v[74:77], v[110:113], v[24:27]
	ds_read_b128 v[74:77], v22 offset:51200
	v_mfma_f32_16x16x32_f16 v[114:117], v[118:121], v[90:93], v[114:117]
	s_waitcnt vmcnt(7)
	ds_write_b128 v17, v[58:61]
	s_waitcnt vmcnt(6)
	ds_write_b128 v18, v[106:109]
	v_mfma_f32_16x16x32_f16 v[40:43], v[118:121], v[110:113], v[40:43]
	ds_read_b128 v[118:121], v22 offset:53248
	s_waitcnt vmcnt(5)
	ds_write_b128 v19, v[134:137]
	v_mfma_f32_16x16x32_f16 v[70:73], v[122:125], v[90:93], v[70:73]
	ds_read_b128 v[90:93], v23 offset:16384
	v_mfma_f32_16x16x32_f16 v[48:51], v[122:125], v[110:113], v[48:51]
	ds_read_b128 v[110:113], v23 offset:18432
	s_waitcnt lgkmcnt(1)
	v_mfma_f32_16x16x32_f16 v[36:39], v[62:65], v[90:93], v[36:39]
	ds_read_b128 v[122:125], v22 offset:55296
	s_waitcnt lgkmcnt(1)
	v_mfma_f32_16x16x32_f16 v[66:69], v[62:65], v[110:113], v[66:69]
	s_waitcnt vmcnt(4)
	ds_write_b128 v20, v[158:161]
	v_mfma_f32_16x16x32_f16 v[44:47], v[74:77], v[90:93], v[44:47]
	s_waitcnt vmcnt(3)
	ds_write_b128 v17, v[94:97] offset:32768
	v_mfma_f32_16x16x32_f16 v[78:81], v[74:77], v[110:113], v[78:81]
	s_waitcnt vmcnt(2)
	ds_write_b128 v18, v[162:165] offset:32768
	v_mfma_f32_16x16x32_f16 v[82:85], v[118:121], v[90:93], v[82:85]
	s_waitcnt vmcnt(1)
	ds_write_b128 v19, v[166:169] offset:32768
	v_mfma_f32_16x16x32_f16 v[86:89], v[118:121], v[110:113], v[86:89]
	s_waitcnt vmcnt(0)
	ds_write_b128 v20, v[190:193] offset:32768
	s_waitcnt lgkmcnt(5)
	v_mfma_f32_16x16x32_f16 v[28:31], v[122:125], v[90:93], v[28:31]
	ds_read_b128 v[90:93], v23 offset:20480
	v_mfma_f32_16x16x32_f16 v[32:35], v[122:125], v[110:113], v[32:35]
	ds_read_b128 v[110:113], v23 offset:22528
	s_waitcnt lgkmcnt(1)
	v_mfma_f32_16x16x32_f16 v[98:101], v[62:65], v[90:93], v[98:101]
	s_waitcnt lgkmcnt(0)
	v_mfma_f32_16x16x32_f16 v[52:55], v[62:65], v[110:113], v[52:55]
	global_load_dwordx4 v[62:65], v[0:1], off offset:3968
	v_add_co_u32_e32 v0, vcc, s1, v0
	v_mfma_f32_16x16x32_f16 v[102:105], v[74:77], v[90:93], v[102:105]
	v_mfma_f32_16x16x32_f16 v[24:27], v[74:77], v[110:113], v[24:27]
	v_mfma_f32_16x16x32_f16 v[114:117], v[118:121], v[90:93], v[114:117]
	v_mfma_f32_16x16x32_f16 v[40:43], v[118:121], v[110:113], v[40:43]
	v_mfma_f32_16x16x32_f16 v[70:73], v[122:125], v[90:93], v[70:73]
	global_load_dwordx4 v[90:93], v[2:3], off offset:3968
	global_load_dwordx4 v[126:129], v[4:5], off offset:3968
	global_load_dwordx4 v[130:133], v[14:15], off offset:3968
	global_load_dwordx4 v[74:77], v[10:11], off offset:3968
	global_load_dwordx4 v[138:141], v[12:13], off offset:3968
	global_load_dwordx4 v[142:145], v[8:9], off offset:3968
	global_load_dwordx4 v[154:157], v[6:7], off offset:3968
	s_waitcnt lgkmcnt(0)
	s_barrier
	v_mfma_f32_16x16x32_f16 v[48:51], v[122:125], v[110:113], v[48:51]
	ds_read_b128 v[58:61], v16 offset:32768
	ds_read_b128 v[106:109], v21
	s_waitcnt lgkmcnt(0)
	v_mfma_f32_16x16x32_f16 v[36:39], v[58:61], v[106:109], v[36:39]
	ds_read_b128 v[94:97], v16 offset:34816
	ds_read_b128 v[110:113], v21 offset:2048
	s_waitcnt lgkmcnt(0)
	v_mfma_f32_16x16x32_f16 v[66:69], v[58:61], v[110:113], v[66:69]
	ds_read_b128 v[118:121], v16 offset:36864
	v_mfma_f32_16x16x32_f16 v[44:47], v[94:97], v[106:109], v[44:47]
	ds_read_b128 v[122:125], v16 offset:38912
	v_mfma_f32_16x16x32_f16 v[78:81], v[94:97], v[110:113], v[78:81]
	ds_read_b128 v[158:161], v23 offset:6144
	s_waitcnt lgkmcnt(2)
	v_mfma_f32_16x16x32_f16 v[82:85], v[118:121], v[106:109], v[82:85]
	v_addc_co_u32_e32 v1, vcc, 0, v1, vcc
	v_mfma_f32_16x16x32_f16 v[86:89], v[118:121], v[110:113], v[86:89]
	v_add_co_u32_e32 v2, vcc, s1, v2
	s_waitcnt lgkmcnt(1)
	v_mfma_f32_16x16x32_f16 v[28:31], v[122:125], v[106:109], v[28:31]
	ds_read_b128 v[106:109], v21 offset:4096
	v_mfma_f32_16x16x32_f16 v[32:35], v[122:125], v[110:113], v[32:35]
	ds_read_b128 v[110:113], v21 offset:6144
	s_waitcnt lgkmcnt(1)
	v_mfma_f32_16x16x32_f16 v[98:101], v[58:61], v[106:109], v[98:101]
	v_addc_co_u32_e32 v3, vcc, 0, v3, vcc
	s_waitcnt lgkmcnt(0)
; #define GL_LOAD(s_, kt_) if (VAR != 1) { a##s_##0 = GL_A(0, kt_); a##s_##1 = GL_A(1, kt_); a##s_##2 = GL_A(2, kt_); a##s_##3 = GL_A(3, kt_); b##s_##0 = GL_B(0, kt_); b##s_##1 = GL_B(1, kt_); b##s_##2 = GL_B(2, kt_); b##s_##3 = GL_B(3, kt_); }
; #define LDS_STORE(s_, buf_) if (VAR != 2) { LDS_ST1(sA, 0, buf_, a##s_##0) LDS_ST1(sA, 1, buf_, a##s_##1) LDS_ST1(sA, 2, buf_, a##s_##2) LDS_ST1(sA, 3, buf_, a##s_##3) LDS_ST1(sB, 0, buf_, b##s_##0) LDS_ST1(sB, 1, buf_, b##s_##1) LDS_ST1(sB, 2, buf_, b##s_##2) LDS_ST1(sB, 3, buf_, b##s_##3) }
;     ...
;   GL_LOAD(0, 0)
;   GL_LOAD(1, 1)
;   LDS_STORE(0, 0)
;   if (VAR != 4) __syncthreads();
; #pragma unroll
;   for (int kt = 0; kt < nk; kt += 2) {
;     if (kt + 2 < nk) { GL_LOAD(0, kt + 2) }
;     MMA_TILE(0)
;     LDS_STORE(1, 1)
;     if (VAR != 4) __syncthreads();
;     if (kt + 3 < nk) { GL_LOAD(1, kt + 3) }
;     MMA_TILE(1)
;     if (kt + 2 < nk) { LDS_STORE(0, 0) }
;     if (VAR != 4) __syncthreads();
	v_mfma_f32_16x16x32_f16 v[52:55], v[58:61], v[110:113], v[52:55]
	ds_read_b128 v[58:61], v22 offset:32768
	v_mfma_f32_16x16x32_f16 v[102:105], v[94:97], v[106:109], v[102:105]
	v_add_co_u32_e32 v4, vcc, s1, v4
	v_mfma_f32_16x16x32_f16 v[24:27], v[94:97], v[110:113], v[24:27]
	ds_read_b128 v[94:97], v22 offset:34816
	v_addc_co_u32_e32 v5, vcc, 0, v5, vcc
	v_mfma_f32_16x16x32_f16 v[114:117], v[118:121], v[106:109], v[114:117]
	v_add_co_u32_e32 v14, vcc, s1, v14
	v_addc_co_u32_e32 v15, vcc, 0, v15, vcc
	v_mfma_f32_16x16x32_f16 v[40:43], v[118:121], v[110:113], v[40:43]
	ds_read_b128 v[118:121], v22 offset:36864
	v_add_co_u32_e32 v10, vcc, s1, v10
	v_mfma_f32_16x16x32_f16 v[70:73], v[122:125], v[106:109], v[70:73]
	ds_read_b128 v[106:109], v23
	v_addc_co_u32_e32 v11, vcc, 0, v11, vcc
	v_mfma_f32_16x16x32_f16 v[48:51], v[122:125], v[110:113], v[48:51]
	ds_read_b128 v[110:113], v23 offset:2048
	ds_read_b128 v[122:125], v22 offset:38912
	s_waitcnt lgkmcnt(2)
	v_mfma_f32_16x16x32_f16 v[36:39], v[58:61], v[106:109], v[36:39]
	v_add_co_u32_e32 v12, vcc, s1, v12
	v_addc_co_u32_e32 v13, vcc, 0, v13, vcc
	s_waitcnt lgkmcnt(1)
	v_mfma_f32_16x16x32_f16 v[66:69], v[58:61], v[110:113], v[66:69]
	v_add_co_u32_e32 v8, vcc, s1, v8
	v_addc_co_u32_e32 v9, vcc, 0, v9, vcc
	v_mfma_f32_16x16x32_f16 v[44:47], v[94:97], v[106:109], v[44:47]
	v_add_co_u32_e32 v6, vcc, s1, v6
	v_addc_co_u32_e32 v7, vcc, 0, v7, vcc
	v_mfma_f32_16x16x32_f16 v[78:81], v[94:97], v[110:113], v[78:81]
	s_waitcnt vmcnt(7)
	ds_write_b128 v17, v[62:65] offset:16384
	s_waitcnt vmcnt(6)
	ds_write_b128 v18, v[90:93] offset:16384
	v_mfma_f32_16x16x32_f16 v[52:55], v[58:61], v[158:161], v[52:55]
	s_waitcnt vmcnt(5)
	ds_write_b128 v19, v[126:129] offset:16384
	s_waitcnt vmcnt(4)
	ds_write_b128 v20, v[130:133] offset:16384
	v_mfma_f32_16x16x32_f16 v[24:27], v[94:97], v[158:161], v[24:27]
	s_waitcnt vmcnt(3)
	ds_write_b128 v17, v[74:77] offset:49152
	s_waitcnt vmcnt(2)
	ds_write_b128 v18, v[138:141] offset:49152
	v_mfma_f32_16x16x32_f16 v[82:85], v[118:121], v[106:109], v[82:85]
	s_waitcnt vmcnt(1)
	ds_write_b128 v19, v[142:145] offset:49152
	s_waitcnt vmcnt(0)
	ds_write_b128 v20, v[154:157] offset:49152
	v_mfma_f32_16x16x32_f16 v[86:89], v[118:121], v[110:113], v[86:89]
	s_waitcnt lgkmcnt(8)
	v_mfma_f32_16x16x32_f16 v[28:31], v[122:125], v[106:109], v[28:31]
	ds_read_b128 v[106:109], v23 offset:4096
	v_mfma_f32_16x16x32_f16 v[32:35], v[122:125], v[110:113], v[32:35]
	global_load_dwordx4 v[110:113], v[0:1], off
	global_load_dwordx4 v[134:137], v[2:3], off
	v_mfma_f32_16x16x32_f16 v[40:43], v[118:121], v[158:161], v[40:43]
	global_load_dwordx4 v[162:165], v[4:5], off
	s_waitcnt lgkmcnt(0)
	v_mfma_f32_16x16x32_f16 v[98:101], v[58:61], v[106:109], v[98:101]
	global_load_dwordx4 v[166:169], v[14:15], off
	v_mfma_f32_16x16x32_f16 v[102:105], v[94:97], v[106:109], v[102:105]
	v_mfma_f32_16x16x32_f16 v[114:117], v[118:121], v[106:109], v[114:117]
	v_mfma_f32_16x16x32_f16 v[70:73], v[122:125], v[106:109], v[70:73]
	global_load_dwordx4 v[106:109], v[10:11], off
	global_load_dwordx4 v[190:193], v[12:13], off
	global_load_dwordx4 v[58:61], v[8:9], off
	global_load_dwordx4 v[94:97], v[6:7], off
	s_waitcnt lgkmcnt(0)
	s_barrier
	v_mfma_f32_16x16x32_f16 v[48:51], v[122:125], v[158:161], v[48:51]
	ds_read_b128 v[62:65], v16 offset:49152
	ds_read_b128 v[90:93], v21 offset:16384
	s_waitcnt lgkmcnt(0)
	v_mfma_f32_16x16x32_f16 v[36:39], v[62:65], v[90:93], v[36:39]
	ds_read_b128 v[74:77], v16 offset:51200
	ds_read_b128 v[118:121], v21 offset:18432
	s_waitcnt lgkmcnt(0)
	v_mfma_f32_16x16x32_f16 v[66:69], v[62:65], v[118:121], v[66:69]
	ds_read_b128 v[122:125], v16 offset:53248
	v_mfma_f32_16x16x32_f16 v[44:47], v[74:77], v[90:93], v[44:47]
	ds_read_b128 v[126:129], v16 offset:55296
	v_mfma_f32_16x16x32_f16 v[78:81], v[74:77], v[118:121], v[78:81]
	s_waitcnt lgkmcnt(1)
	v_mfma_f32_16x16x32_f16 v[82:85], v[122:125], v[90:93], v[82:85]
	v_mfma_f32_16x16x32_f16 v[86:89], v[122:125], v[118:121], v[86:89]
	s_waitcnt lgkmcnt(0)
	v_mfma_f32_16x16x32_f16 v[28:31], v[126:129], v[90:93], v[28:31]
	ds_read_b128 v[90:93], v21 offset:20480
	v_mfma_f32_16x16x32_f16 v[32:35], v[126:129], v[118:121], v[32:35]
	ds_read_b128 v[118:121], v21 offset:22528
	s_waitcnt lgkmcnt(1)
	v_mfma_f32_16x16x32_f16 v[98:101], v[62:65], v[90:93], v[98:101]
	s_waitcnt lgkmcnt(0)
	v_mfma_f32_16x16x32_f16 v[52:55], v[62:65], v[118:121], v[52:55]
	ds_read_b128 v[62:65], v22 offset:49152
	v_mfma_f32_16x16x32_f16 v[102:105], v[74:77], v[90:93], v[102:105]
	v_mfma_f32_16x16x32_f16 v[24:27], v[74:77], v[118:121], v[24:27]
	ds_read_b128 v[74:77], v22 offset:51200
	v_mfma_f32_16x16x32_f16 v[114:117], v[122:125], v[90:93], v[114:117]
	s_waitcnt vmcnt(7)
	ds_write_b128 v17, v[110:113]
	s_waitcnt vmcnt(6)
	ds_write_b128 v18, v[134:137]
	v_mfma_f32_16x16x32_f16 v[40:43], v[122:125], v[118:121], v[40:43]
	ds_read_b128 v[122:125], v22 offset:53248
	s_waitcnt vmcnt(5)
	ds_write_b128 v19, v[162:165]
	v_mfma_f32_16x16x32_f16 v[70:73], v[126:129], v[90:93], v[70:73]
	ds_read_b128 v[90:93], v23 offset:16384
	v_mfma_f32_16x16x32_f16 v[48:51], v[126:129], v[118:121], v[48:51]
	ds_read_b128 v[118:121], v23 offset:18432
	s_waitcnt lgkmcnt(1)
	v_mfma_f32_16x16x32_f16 v[36:39], v[62:65], v[90:93], v[36:39]
	ds_read_b128 v[126:129], v22 offset:55296
	s_waitcnt lgkmcnt(1)
	v_mfma_f32_16x16x32_f16 v[66:69], v[62:65], v[118:121], v[66:69]
	s_waitcnt vmcnt(4)
	ds_write_b128 v20, v[166:169]
	v_mfma_f32_16x16x32_f16 v[44:47], v[74:77], v[90:93], v[44:47]
	s_waitcnt vmcnt(3)
	ds_write_b128 v17, v[106:109] offset:32768
	v_mfma_f32_16x16x32_f16 v[78:81], v[74:77], v[118:121], v[78:81]
	s_waitcnt vmcnt(2)
; #define GL_LOAD(s_, kt_) if (VAR != 1) { a##s_##0 = GL_A(0, kt_); a##s_##1 = GL_A(1, kt_); a##s_##2 = GL_A(2, kt_); a##s_##3 = GL_A(3, kt_); b##s_##0 = GL_B(0, kt_); b##s_##1 = GL_B(1, kt_); b##s_##2 = GL_B(2, kt_); b##s_##3 = GL_B(3, kt_); }
; #define LDS_STORE(s_, buf_) if (VAR != 2) { LDS_ST1(sA, 0, buf_, a##s_##0) LDS_ST1(sA, 1, buf_, a##s_##1) LDS_ST1(sA, 2, buf_, a##s_##2) LDS_ST1(sA, 3, buf_, a##s_##3) LDS_ST1(sB, 0, buf_, b##s_##0) LDS_ST1(sB, 1, buf_, b##s_##1) LDS_ST1(sB, 2, buf_, b##s_##2) LDS_ST1(sB, 3, buf_, b##s_##3) }
;     ...
;   GL_LOAD(0, 0)
;   GL_LOAD(1, 1)
;   LDS_STORE(0, 0)
;   if (VAR != 4) __syncthreads();
; #pragma unroll
;   for (int kt = 0; kt < nk; kt += 2) {
;     if (kt + 2 < nk) { GL_LOAD(0, kt + 2) }
;     MMA_TILE(0)
;     LDS_STORE(1, 1)
;     if (VAR != 4) __syncthreads();
;     if (kt + 3 < nk) { GL_LOAD(1, kt + 3) }
;     MMA_TILE(1)
;     if (kt + 2 < nk) { LDS_STORE(0, 0) }
;     if (VAR != 4) __syncthreads();
	ds_write_b128 v18, v[190:193] offset:32768
	v_mfma_f32_16x16x32_f16 v[82:85], v[122:125], v[90:93], v[82:85]
	s_waitcnt vmcnt(1)
	ds_write_b128 v19, v[58:61] offset:32768
	v_mfma_f32_16x16x32_f16 v[86:89], v[122:125], v[118:121], v[86:89]
	s_waitcnt vmcnt(0)
	ds_write_b128 v20, v[94:97] offset:32768
	s_waitcnt lgkmcnt(5)
	v_mfma_f32_16x16x32_f16 v[28:31], v[126:129], v[90:93], v[28:31]
	ds_read_b128 v[90:93], v23 offset:20480
	v_mfma_f32_16x16x32_f16 v[32:35], v[126:129], v[118:121], v[32:35]
	ds_read_b128 v[118:121], v23 offset:22528
	s_waitcnt lgkmcnt(1)
	v_mfma_f32_16x16x32_f16 v[98:101], v[62:65], v[90:93], v[98:101]
	s_waitcnt lgkmcnt(0)
	v_mfma_f32_16x16x32_f16 v[52:55], v[62:65], v[118:121], v[52:55]
	global_load_dwordx4 v[62:65], v[0:1], off offset:128
	v_mfma_f32_16x16x32_f16 v[102:105], v[74:77], v[90:93], v[102:105]
	v_mfma_f32_16x16x32_f16 v[24:27], v[74:77], v[118:121], v[24:27]
	v_mfma_f32_16x16x32_f16 v[114:117], v[122:125], v[90:93], v[114:117]
	v_mfma_f32_16x16x32_f16 v[40:43], v[122:125], v[118:121], v[40:43]
	v_mfma_f32_16x16x32_f16 v[70:73], v[126:129], v[90:93], v[70:73]
	global_load_dwordx4 v[90:93], v[2:3], off offset:128
	global_load_dwordx4 v[130:133], v[4:5], off offset:128
	global_load_dwordx4 v[138:141], v[14:15], off offset:128
	global_load_dwordx4 v[74:77], v[10:11], off offset:128
	global_load_dwordx4 v[142:145], v[12:13], off offset:128
	global_load_dwordx4 v[154:157], v[8:9], off offset:128
	global_load_dwordx4 v[158:161], v[6:7], off offset:128
	s_waitcnt lgkmcnt(0)
	s_barrier
	v_mfma_f32_16x16x32_f16 v[48:51], v[126:129], v[118:121], v[48:51]
	ds_read_b128 v[58:61], v16 offset:32768
	ds_read_b128 v[106:109], v21
	s_waitcnt lgkmcnt(0)
	v_mfma_f32_16x16x32_f16 v[36:39], v[58:61], v[106:109], v[36:39]
	ds_read_b128 v[94:97], v16 offset:34816
	ds_read_b128 v[110:113], v21 offset:2048
	s_waitcnt lgkmcnt(0)
	v_mfma_f32_16x16x32_f16 v[66:69], v[58:61], v[110:113], v[66:69]
	ds_read_b128 v[118:121], v16 offset:36864
	v_mfma_f32_16x16x32_f16 v[44:47], v[94:97], v[106:109], v[44:47]
	ds_read_b128 v[122:125], v16 offset:38912
	v_mfma_f32_16x16x32_f16 v[78:81], v[94:97], v[110:113], v[78:81]
	s_waitcnt lgkmcnt(1)
	v_mfma_f32_16x16x32_f16 v[82:85], v[118:121], v[106:109], v[82:85]
	v_mfma_f32_16x16x32_f16 v[86:89], v[118:121], v[110:113], v[86:89]
	s_waitcnt lgkmcnt(0)
	v_mfma_f32_16x16x32_f16 v[28:31], v[122:125], v[106:109], v[28:31]
	ds_read_b128 v[106:109], v21 offset:4096
	v_mfma_f32_16x16x32_f16 v[32:35], v[122:125], v[110:113], v[32:35]
	ds_read_b128 v[110:113], v21 offset:6144
	s_waitcnt lgkmcnt(1)
	v_mfma_f32_16x16x32_f16 v[98:101], v[58:61], v[106:109], v[98:101]
	s_waitcnt lgkmcnt(0)
	v_mfma_f32_16x16x32_f16 v[52:55], v[58:61], v[110:113], v[52:55]
	ds_read_b128 v[58:61], v22 offset:32768
	v_mfma_f32_16x16x32_f16 v[102:105], v[94:97], v[106:109], v[102:105]
	v_mfma_f32_16x16x32_f16 v[24:27], v[94:97], v[110:113], v[24:27]
	ds_read_b128 v[94:97], v22 offset:34816
	v_mfma_f32_16x16x32_f16 v[114:117], v[118:121], v[106:109], v[114:117]
	s_waitcnt vmcnt(7)
	ds_write_b128 v17, v[62:65] offset:16384
	s_waitcnt vmcnt(6)
	ds_write_b128 v18, v[90:93] offset:16384
	v_mfma_f32_16x16x32_f16 v[40:43], v[118:121], v[110:113], v[40:43]
	ds_read_b128 v[118:121], v22 offset:36864
	s_waitcnt vmcnt(5)
	ds_write_b128 v19, v[130:133] offset:16384
	v_mfma_f32_16x16x32_f16 v[70:73], v[122:125], v[106:109], v[70:73]
	ds_read_b128 v[106:109], v23
	v_mfma_f32_16x16x32_f16 v[48:51], v[122:125], v[110:113], v[48:51]
	ds_read_b128 v[110:113], v23 offset:2048
	s_waitcnt lgkmcnt(1)
	v_mfma_f32_16x16x32_f16 v[36:39], v[58:61], v[106:109], v[36:39]
	ds_read_b128 v[122:125], v22 offset:38912
	s_waitcnt lgkmcnt(1)
	v_mfma_f32_16x16x32_f16 v[66:69], v[58:61], v[110:113], v[66:69]
	s_waitcnt vmcnt(4)
	ds_write_b128 v20, v[138:141] offset:16384
	v_mfma_f32_16x16x32_f16 v[44:47], v[94:97], v[106:109], v[44:47]
	s_waitcnt vmcnt(3)
	ds_write_b128 v17, v[74:77] offset:49152
	v_mfma_f32_16x16x32_f16 v[78:81], v[94:97], v[110:113], v[78:81]
	s_waitcnt vmcnt(2)
	ds_write_b128 v18, v[142:145] offset:49152
	v_mfma_f32_16x16x32_f16 v[82:85], v[118:121], v[106:109], v[82:85]
	s_waitcnt vmcnt(1)
	ds_write_b128 v19, v[154:157] offset:49152
	v_mfma_f32_16x16x32_f16 v[86:89], v[118:121], v[110:113], v[86:89]
	s_waitcnt vmcnt(0)
	ds_write_b128 v20, v[158:161] offset:49152
	s_waitcnt lgkmcnt(5)
	v_mfma_f32_16x16x32_f16 v[28:31], v[122:125], v[106:109], v[28:31]
	ds_read_b128 v[106:109], v23 offset:4096
	v_mfma_f32_16x16x32_f16 v[32:35], v[122:125], v[110:113], v[32:35]
	ds_read_b128 v[110:113], v23 offset:6144
	s_waitcnt lgkmcnt(1)
	v_mfma_f32_16x16x32_f16 v[98:101], v[58:61], v[106:109], v[98:101]
	s_waitcnt lgkmcnt(0)
	v_mfma_f32_16x16x32_f16 v[52:55], v[58:61], v[110:113], v[52:55]
	global_load_dwordx4 v[58:61], v[0:1], off offset:256
	v_mfma_f32_16x16x32_f16 v[102:105], v[94:97], v[106:109], v[102:105]
	v_mfma_f32_16x16x32_f16 v[24:27], v[94:97], v[110:113], v[24:27]
	v_mfma_f32_16x16x32_f16 v[114:117], v[118:121], v[106:109], v[114:117]
	v_mfma_f32_16x16x32_f16 v[40:43], v[118:121], v[110:113], v[40:43]
	v_mfma_f32_16x16x32_f16 v[70:73], v[122:125], v[106:109], v[70:73]
	global_load_dwordx4 v[106:109], v[2:3], off offset:256
	global_load_dwordx4 v[126:129], v[4:5], off offset:256
	global_load_dwordx4 v[134:137], v[14:15], off offset:256
	global_load_dwordx4 v[94:97], v[10:11], off offset:256
	global_load_dwordx4 v[162:165], v[12:13], off offset:256
	global_load_dwordx4 v[166:169], v[8:9], off offset:256
	global_load_dwordx4 v[190:193], v[6:7], off offset:256
	s_waitcnt lgkmcnt(0)
	s_barrier
; #define GL_LOAD(s_, kt_) if (VAR != 1) { a##s_##0 = GL_A(0, kt_); a##s_##1 = GL_A(1, kt_); a##s_##2 = GL_A(2, kt_); a##s_##3 = GL_A(3, kt_); b##s_##0 = GL_B(0, kt_); b##s_##1 = GL_B(1, kt_); b##s_##2 = GL_B(2, kt_); b##s_##3 = GL_B(3, kt_); }
; #define LDS_STORE(s_, buf_) if (VAR != 2) { LDS_ST1(sA, 0, buf_, a##s_##0) LDS_ST1(sA, 1, buf_, a##s_##1) LDS_ST1(sA, 2, buf_, a##s_##2) LDS_ST1(sA, 3, buf_, a##s_##3) LDS_ST1(sB, 0, buf_, b##s_##0) LDS_ST1(sB, 1, buf_, b##s_##1) LDS_ST1(sB, 2, buf_, b##s_##2) LDS_ST1(sB, 3, buf_, b##s_##3) }
;     ...
;   GL_LOAD(0, 0)
;   GL_LOAD(1, 1)
;   LDS_STORE(0, 0)
;   if (VAR != 4) __syncthreads();
; #pragma unroll
;   for (int kt = 0; kt < nk; kt += 2) {
;     if (kt + 2 < nk) { GL_LOAD(0, kt + 2) }
;     MMA_TILE(0)
;     LDS_STORE(1, 1)
;     if (VAR != 4) __syncthreads();
;     if (kt + 3 < nk) { GL_LOAD(1, kt + 3) }
;     MMA_TILE(1)
;     if (kt + 2 < nk) { LDS_STORE(0, 0) }
;     if (VAR != 4) __syncthreads();
	v_mfma_f32_16x16x32_f16 v[48:51], v[122:125], v[110:113], v[48:51]
	ds_read_b128 v[62:65], v16 offset:49152
	ds_read_b128 v[90:93], v21 offset:16384
	s_waitcnt lgkmcnt(0)
	v_mfma_f32_16x16x32_f16 v[36:39], v[62:65], v[90:93], v[36:39]
	ds_read_b128 v[74:77], v16 offset:51200
	ds_read_b128 v[110:113], v21 offset:18432
	s_waitcnt lgkmcnt(0)
	v_mfma_f32_16x16x32_f16 v[66:69], v[62:65], v[110:113], v[66:69]
	ds_read_b128 v[118:121], v16 offset:53248
	v_mfma_f32_16x16x32_f16 v[44:47], v[74:77], v[90:93], v[44:47]
	ds_read_b128 v[122:125], v16 offset:55296
	v_mfma_f32_16x16x32_f16 v[78:81], v[74:77], v[110:113], v[78:81]
	s_waitcnt lgkmcnt(1)
	v_mfma_f32_16x16x32_f16 v[82:85], v[118:121], v[90:93], v[82:85]
	v_mfma_f32_16x16x32_f16 v[86:89], v[118:121], v[110:113], v[86:89]
	s_waitcnt lgkmcnt(0)
	v_mfma_f32_16x16x32_f16 v[28:31], v[122:125], v[90:93], v[28:31]
	ds_read_b128 v[90:93], v21 offset:20480
	v_mfma_f32_16x16x32_f16 v[32:35], v[122:125], v[110:113], v[32:35]
	ds_read_b128 v[110:113], v21 offset:22528
	s_waitcnt lgkmcnt(1)
	v_mfma_f32_16x16x32_f16 v[98:101], v[62:65], v[90:93], v[98:101]
	s_waitcnt lgkmcnt(0)
	v_mfma_f32_16x16x32_f16 v[52:55], v[62:65], v[110:113], v[52:55]
	ds_read_b128 v[62:65], v22 offset:49152
	v_mfma_f32_16x16x32_f16 v[102:105], v[74:77], v[90:93], v[102:105]
	v_mfma_f32_16x16x32_f16 v[24:27], v[74:77], v[110:113], v[24:27]
	ds_read_b128 v[74:77], v22 offset:51200
	v_mfma_f32_16x16x32_f16 v[114:117], v[118:121], v[90:93], v[114:117]
	s_waitcnt vmcnt(7)
	ds_write_b128 v17, v[58:61]
	s_waitcnt vmcnt(6)
	ds_write_b128 v18, v[106:109]
	v_mfma_f32_16x16x32_f16 v[40:43], v[118:121], v[110:113], v[40:43]
	ds_read_b128 v[118:121], v22 offset:53248
	s_waitcnt vmcnt(5)
	ds_write_b128 v19, v[126:129]
	v_mfma_f32_16x16x32_f16 v[70:73], v[122:125], v[90:93], v[70:73]
	ds_read_b128 v[90:93], v23 offset:16384
	v_mfma_f32_16x16x32_f16 v[48:51], v[122:125], v[110:113], v[48:51]
	ds_read_b128 v[110:113], v23 offset:18432
	s_waitcnt lgkmcnt(1)
	v_mfma_f32_16x16x32_f16 v[36:39], v[62:65], v[90:93], v[36:39]
	ds_read_b128 v[122:125], v22 offset:55296
	s_waitcnt lgkmcnt(1)
	v_mfma_f32_16x16x32_f16 v[66:69], v[62:65], v[110:113], v[66:69]
	s_waitcnt vmcnt(4)
	ds_write_b128 v20, v[134:137]
	v_mfma_f32_16x16x32_f16 v[44:47], v[74:77], v[90:93], v[44:47]
	s_waitcnt vmcnt(3)
	ds_write_b128 v17, v[94:97] offset:32768
	v_mfma_f32_16x16x32_f16 v[78:81], v[74:77], v[110:113], v[78:81]
	s_waitcnt vmcnt(2)
	ds_write_b128 v18, v[162:165] offset:32768
	v_mfma_f32_16x16x32_f16 v[82:85], v[118:121], v[90:93], v[82:85]
	s_waitcnt vmcnt(1)
	ds_write_b128 v19, v[166:169] offset:32768
	v_mfma_f32_16x16x32_f16 v[86:89], v[118:121], v[110:113], v[86:89]
	s_waitcnt vmcnt(0)
	ds_write_b128 v20, v[190:193] offset:32768
	s_waitcnt lgkmcnt(5)
	v_mfma_f32_16x16x32_f16 v[28:31], v[122:125], v[90:93], v[28:31]
	ds_read_b128 v[90:93], v23 offset:20480
	v_mfma_f32_16x16x32_f16 v[32:35], v[122:125], v[110:113], v[32:35]
	ds_read_b128 v[110:113], v23 offset:22528
	s_waitcnt lgkmcnt(1)
	v_mfma_f32_16x16x32_f16 v[98:101], v[62:65], v[90:93], v[98:101]
	s_waitcnt lgkmcnt(0)
	v_mfma_f32_16x16x32_f16 v[52:55], v[62:65], v[110:113], v[52:55]
	global_load_dwordx4 v[62:65], v[0:1], off offset:384
	v_mfma_f32_16x16x32_f16 v[102:105], v[74:77], v[90:93], v[102:105]
	v_mfma_f32_16x16x32_f16 v[24:27], v[74:77], v[110:113], v[24:27]
	v_mfma_f32_16x16x32_f16 v[114:117], v[118:121], v[90:93], v[114:117]
	v_mfma_f32_16x16x32_f16 v[40:43], v[118:121], v[110:113], v[40:43]
	v_mfma_f32_16x16x32_f16 v[70:73], v[122:125], v[90:93], v[70:73]
	global_load_dwordx4 v[90:93], v[2:3], off offset:384
	global_load_dwordx4 v[130:133], v[4:5], off offset:384
	global_load_dwordx4 v[138:141], v[14:15], off offset:384
	global_load_dwordx4 v[74:77], v[10:11], off offset:384
	global_load_dwordx4 v[142:145], v[12:13], off offset:384
	global_load_dwordx4 v[154:157], v[8:9], off offset:384
	global_load_dwordx4 v[158:161], v[6:7], off offset:384
	s_waitcnt lgkmcnt(0)
	s_barrier
	v_mfma_f32_16x16x32_f16 v[48:51], v[122:125], v[110:113], v[48:51]
	ds_read_b128 v[58:61], v16 offset:32768
	ds_read_b128 v[106:109], v21
	s_waitcnt lgkmcnt(0)
	v_mfma_f32_16x16x32_f16 v[36:39], v[58:61], v[106:109], v[36:39]
	ds_read_b128 v[94:97], v16 offset:34816
	ds_read_b128 v[110:113], v21 offset:2048
	s_waitcnt lgkmcnt(0)
	v_mfma_f32_16x16x32_f16 v[66:69], v[58:61], v[110:113], v[66:69]
	ds_read_b128 v[118:121], v16 offset:36864
	v_mfma_f32_16x16x32_f16 v[44:47], v[94:97], v[106:109], v[44:47]
	ds_read_b128 v[122:125], v16 offset:38912
	v_mfma_f32_16x16x32_f16 v[78:81], v[94:97], v[110:113], v[78:81]
	s_waitcnt lgkmcnt(1)
	v_mfma_f32_16x16x32_f16 v[82:85], v[118:121], v[106:109], v[82:85]
	v_mfma_f32_16x16x32_f16 v[86:89], v[118:121], v[110:113], v[86:89]
	s_waitcnt lgkmcnt(0)
	v_mfma_f32_16x16x32_f16 v[28:31], v[122:125], v[106:109], v[28:31]
	ds_read_b128 v[106:109], v21 offset:4096
	v_mfma_f32_16x16x32_f16 v[32:35], v[122:125], v[110:113], v[32:35]
	ds_read_b128 v[110:113], v21 offset:6144
	s_waitcnt lgkmcnt(1)
	v_mfma_f32_16x16x32_f16 v[98:101], v[58:61], v[106:109], v[98:101]
	s_waitcnt lgkmcnt(0)
	v_mfma_f32_16x16x32_f16 v[52:55], v[58:61], v[110:113], v[52:55]
	ds_read_b128 v[58:61], v22 offset:32768
	v_mfma_f32_16x16x32_f16 v[102:105], v[94:97], v[106:109], v[102:105]
	v_mfma_f32_16x16x32_f16 v[24:27], v[94:97], v[110:113], v[24:27]
	ds_read_b128 v[94:97], v22 offset:34816
	v_mfma_f32_16x16x32_f16 v[114:117], v[118:121], v[106:109], v[114:117]
	s_waitcnt vmcnt(7)
	ds_write_b128 v17, v[62:65] offset:16384
	s_waitcnt vmcnt(6)
	ds_write_b128 v18, v[90:93] offset:16384
	v_mfma_f32_16x16x32_f16 v[40:43], v[118:121], v[110:113], v[40:43]
	ds_read_b128 v[118:121], v22 offset:36864
	s_waitcnt vmcnt(5)
; #define GL_LOAD(s_, kt_) if (VAR != 1) { a##s_##0 = GL_A(0, kt_); a##s_##1 = GL_A(1, kt_); a##s_##2 = GL_A(2, kt_); a##s_##3 = GL_A(3, kt_); b##s_##0 = GL_B(0, kt_); b##s_##1 = GL_B(1, kt_); b##s_##2 = GL_B(2, kt_); b##s_##3 = GL_B(3, kt_); }
; #define LDS_STORE(s_, buf_) if (VAR != 2) { LDS_ST1(sA, 0, buf_, a##s_##0) LDS_ST1(sA, 1, buf_, a##s_##1) LDS_ST1(sA, 2, buf_, a##s_##2) LDS_ST1(sA, 3, buf_, a##s_##3) LDS_ST1(sB, 0, buf_, b##s_##0) LDS_ST1(sB, 1, buf_, b##s_##1) LDS_ST1(sB, 2, buf_, b##s_##2) LDS_ST1(sB, 3, buf_, b##s_##3) }
;     ...
;   GL_LOAD(0, 0)
;   GL_LOAD(1, 1)
;   LDS_STORE(0, 0)
;   if (VAR != 4) __syncthreads();
; #pragma unroll
;   for (int kt = 0; kt < nk; kt += 2) {
;     if (kt + 2 < nk) { GL_LOAD(0, kt + 2) }
;     MMA_TILE(0)
;     LDS_STORE(1, 1)
;     if (VAR != 4) __syncthreads();
;     if (kt + 3 < nk) { GL_LOAD(1, kt + 3) }
;     MMA_TILE(1)
;     if (kt + 2 < nk) { LDS_STORE(0, 0) }
;     if (VAR != 4) __syncthreads();
	ds_write_b128 v19, v[130:133] offset:16384
	v_mfma_f32_16x16x32_f16 v[70:73], v[122:125], v[106:109], v[70:73]
	ds_read_b128 v[106:109], v23
	v_mfma_f32_16x16x32_f16 v[48:51], v[122:125], v[110:113], v[48:51]
	ds_read_b128 v[110:113], v23 offset:2048
	s_waitcnt lgkmcnt(1)
	v_mfma_f32_16x16x32_f16 v[36:39], v[58:61], v[106:109], v[36:39]
	ds_read_b128 v[122:125], v22 offset:38912
	s_waitcnt lgkmcnt(1)
	v_mfma_f32_16x16x32_f16 v[66:69], v[58:61], v[110:113], v[66:69]
	s_waitcnt vmcnt(4)
	ds_write_b128 v20, v[138:141] offset:16384
	v_mfma_f32_16x16x32_f16 v[44:47], v[94:97], v[106:109], v[44:47]
	s_waitcnt vmcnt(3)
	ds_write_b128 v17, v[74:77] offset:49152
	v_mfma_f32_16x16x32_f16 v[78:81], v[94:97], v[110:113], v[78:81]
	s_waitcnt vmcnt(2)
	ds_write_b128 v18, v[142:145] offset:49152
	v_mfma_f32_16x16x32_f16 v[82:85], v[118:121], v[106:109], v[82:85]
	s_waitcnt vmcnt(1)
	ds_write_b128 v19, v[154:157] offset:49152
	v_mfma_f32_16x16x32_f16 v[86:89], v[118:121], v[110:113], v[86:89]
	s_waitcnt vmcnt(0)
	ds_write_b128 v20, v[158:161] offset:49152
	s_waitcnt lgkmcnt(5)
	v_mfma_f32_16x16x32_f16 v[28:31], v[122:125], v[106:109], v[28:31]
	ds_read_b128 v[106:109], v23 offset:4096
	v_mfma_f32_16x16x32_f16 v[32:35], v[122:125], v[110:113], v[32:35]
	ds_read_b128 v[110:113], v23 offset:6144
	s_waitcnt lgkmcnt(1)
	v_mfma_f32_16x16x32_f16 v[98:101], v[58:61], v[106:109], v[98:101]
	s_waitcnt lgkmcnt(0)
	v_mfma_f32_16x16x32_f16 v[52:55], v[58:61], v[110:113], v[52:55]
	global_load_dwordx4 v[58:61], v[0:1], off offset:512
	v_mfma_f32_16x16x32_f16 v[102:105], v[94:97], v[106:109], v[102:105]
	v_mfma_f32_16x16x32_f16 v[24:27], v[94:97], v[110:113], v[24:27]
	v_mfma_f32_16x16x32_f16 v[114:117], v[118:121], v[106:109], v[114:117]
	v_mfma_f32_16x16x32_f16 v[40:43], v[118:121], v[110:113], v[40:43]
	v_mfma_f32_16x16x32_f16 v[70:73], v[122:125], v[106:109], v[70:73]
	global_load_dwordx4 v[106:109], v[2:3], off offset:512
	global_load_dwordx4 v[126:129], v[4:5], off offset:512
	global_load_dwordx4 v[134:137], v[14:15], off offset:512
	global_load_dwordx4 v[94:97], v[10:11], off offset:512
	global_load_dwordx4 v[162:165], v[12:13], off offset:512
	global_load_dwordx4 v[166:169], v[8:9], off offset:512
	global_load_dwordx4 v[190:193], v[6:7], off offset:512
	s_waitcnt lgkmcnt(0)
	s_barrier
	v_mfma_f32_16x16x32_f16 v[48:51], v[122:125], v[110:113], v[48:51]
	ds_read_b128 v[62:65], v16 offset:49152
	ds_read_b128 v[90:93], v21 offset:16384
	s_waitcnt lgkmcnt(0)
	v_mfma_f32_16x16x32_f16 v[36:39], v[62:65], v[90:93], v[36:39]
	ds_read_b128 v[74:77], v16 offset:51200
	ds_read_b128 v[110:113], v21 offset:18432
	s_waitcnt lgkmcnt(0)
	v_mfma_f32_16x16x32_f16 v[66:69], v[62:65], v[110:113], v[66:69]
	ds_read_b128 v[118:121], v16 offset:53248
	v_mfma_f32_16x16x32_f16 v[44:47], v[74:77], v[90:93], v[44:47]
	ds_read_b128 v[122:125], v16 offset:55296
	v_mfma_f32_16x16x32_f16 v[78:81], v[74:77], v[110:113], v[78:81]
	s_waitcnt lgkmcnt(1)
	v_mfma_f32_16x16x32_f16 v[82:85], v[118:121], v[90:93], v[82:85]
	v_mfma_f32_16x16x32_f16 v[86:89], v[118:121], v[110:113], v[86:89]
	s_waitcnt lgkmcnt(0)
	v_mfma_f32_16x16x32_f16 v[28:31], v[122:125], v[90:93], v[28:31]
	ds_read_b128 v[90:93], v21 offset:20480
	v_mfma_f32_16x16x32_f16 v[32:35], v[122:125], v[110:113], v[32:35]
	ds_read_b128 v[110:113], v21 offset:22528
	s_waitcnt lgkmcnt(1)
	v_mfma_f32_16x16x32_f16 v[98:101], v[62:65], v[90:93], v[98:101]
	s_waitcnt lgkmcnt(0)
	v_mfma_f32_16x16x32_f16 v[52:55], v[62:65], v[110:113], v[52:55]
	ds_read_b128 v[62:65], v22 offset:49152
	v_mfma_f32_16x16x32_f16 v[102:105], v[74:77], v[90:93], v[102:105]
	v_mfma_f32_16x16x32_f16 v[24:27], v[74:77], v[110:113], v[24:27]
	ds_read_b128 v[74:77], v22 offset:51200
	v_mfma_f32_16x16x32_f16 v[114:117], v[118:121], v[90:93], v[114:117]
	s_waitcnt vmcnt(7)
	ds_write_b128 v17, v[58:61]
	s_waitcnt vmcnt(6)
	ds_write_b128 v18, v[106:109]
	v_mfma_f32_16x16x32_f16 v[40:43], v[118:121], v[110:113], v[40:43]
	ds_read_b128 v[118:121], v22 offset:53248
	s_waitcnt vmcnt(5)
	ds_write_b128 v19, v[126:129]
	v_mfma_f32_16x16x32_f16 v[70:73], v[122:125], v[90:93], v[70:73]
	ds_read_b128 v[90:93], v23 offset:16384
	v_mfma_f32_16x16x32_f16 v[48:51], v[122:125], v[110:113], v[48:51]
	ds_read_b128 v[110:113], v23 offset:18432
	s_waitcnt lgkmcnt(1)
	v_mfma_f32_16x16x32_f16 v[36:39], v[62:65], v[90:93], v[36:39]
	ds_read_b128 v[122:125], v22 offset:55296
	s_waitcnt lgkmcnt(1)
	v_mfma_f32_16x16x32_f16 v[66:69], v[62:65], v[110:113], v[66:69]
	s_waitcnt vmcnt(4)
	ds_write_b128 v20, v[134:137]
	v_mfma_f32_16x16x32_f16 v[44:47], v[74:77], v[90:93], v[44:47]
	s_waitcnt vmcnt(3)
	ds_write_b128 v17, v[94:97] offset:32768
	v_mfma_f32_16x16x32_f16 v[78:81], v[74:77], v[110:113], v[78:81]
	s_waitcnt vmcnt(2)
	ds_write_b128 v18, v[162:165] offset:32768
	v_mfma_f32_16x16x32_f16 v[82:85], v[118:121], v[90:93], v[82:85]
	s_waitcnt vmcnt(1)
	ds_write_b128 v19, v[166:169] offset:32768
	v_mfma_f32_16x16x32_f16 v[86:89], v[118:121], v[110:113], v[86:89]
	s_waitcnt vmcnt(0)
	ds_write_b128 v20, v[190:193] offset:32768
	s_waitcnt lgkmcnt(5)
	v_mfma_f32_16x16x32_f16 v[28:31], v[122:125], v[90:93], v[28:31]
	ds_read_b128 v[90:93], v23 offset:20480
	v_mfma_f32_16x16x32_f16 v[32:35], v[122:125], v[110:113], v[32:35]
	ds_read_b128 v[110:113], v23 offset:22528
	s_waitcnt lgkmcnt(1)
	v_mfma_f32_16x16x32_f16 v[98:101], v[62:65], v[90:93], v[98:101]
	s_waitcnt lgkmcnt(0)
	v_mfma_f32_16x16x32_f16 v[52:55], v[62:65], v[110:113], v[52:55]
	global_load_dwordx4 v[62:65], v[0:1], off offset:640
	v_mfma_f32_16x16x32_f16 v[102:105], v[74:77], v[90:93], v[102:105]
	v_mfma_f32_16x16x32_f16 v[24:27], v[74:77], v[110:113], v[24:27]
	v_mfma_f32_16x16x32_f16 v[114:117], v[118:121], v[90:93], v[114:117]
	v_mfma_f32_16x16x32_f16 v[40:43], v[118:121], v[110:113], v[40:43]
	v_mfma_f32_16x16x32_f16 v[70:73], v[122:125], v[90:93], v[70:73]
	global_load_dwordx4 v[90:93], v[2:3], off offset:640
	global_load_dwordx4 v[130:133], v[4:5], off offset:640
	global_load_dwordx4 v[138:141], v[14:15], off offset:640
	global_load_dwordx4 v[74:77], v[10:11], off offset:640
	global_load_dwordx4 v[142:145], v[12:13], off offset:640
	global_load_dwordx4 v[154:157], v[8:9], off offset:640
	global_load_dwordx4 v[158:161], v[6:7], off offset:640
	s_waitcnt lgkmcnt(0)
	s_barrier
; #define GL_LOAD(s_, kt_) if (VAR != 1) { a##s_##0 = GL_A(0, kt_); a##s_##1 = GL_A(1, kt_); a##s_##2 = GL_A(2, kt_); a##s_##3 = GL_A(3, kt_); b##s_##0 = GL_B(0, kt_); b##s_##1 = GL_B(1, kt_); b##s_##2 = GL_B(2, kt_); b##s_##3 = GL_B(3, kt_); }
; #define LDS_STORE(s_, buf_) if (VAR != 2) { LDS_ST1(sA, 0, buf_, a##s_##0) LDS_ST1(sA, 1, buf_, a##s_##1) LDS_ST1(sA, 2, buf_, a##s_##2) LDS_ST1(sA, 3, buf_, a##s_##3) LDS_ST1(sB, 0, buf_, b##s_##0) LDS_ST1(sB, 1, buf_, b##s_##1) LDS_ST1(sB, 2, buf_, b##s_##2) LDS_ST1(sB, 3, buf_, b##s_##3) }
;     ...
;   GL_LOAD(0, 0)
;   GL_LOAD(1, 1)
;   LDS_STORE(0, 0)
;   if (VAR != 4) __syncthreads();
; #pragma unroll
;   for (int kt = 0; kt < nk; kt += 2) {
;     if (kt + 2 < nk) { GL_LOAD(0, kt + 2) }
;     MMA_TILE(0)
;     LDS_STORE(1, 1)
;     if (VAR != 4) __syncthreads();
;     if (kt + 3 < nk) { GL_LOAD(1, kt + 3) }
;     MMA_TILE(1)
;     if (kt + 2 < nk) { LDS_STORE(0, 0) }
;     if (VAR != 4) __syncthreads();
	v_mfma_f32_16x16x32_f16 v[48:51], v[122:125], v[110:113], v[48:51]
	ds_read_b128 v[58:61], v16 offset:32768
	ds_read_b128 v[106:109], v21
	s_waitcnt lgkmcnt(0)
	v_mfma_f32_16x16x32_f16 v[36:39], v[58:61], v[106:109], v[36:39]
	ds_read_b128 v[94:97], v16 offset:34816
	ds_read_b128 v[110:113], v21 offset:2048
	s_waitcnt lgkmcnt(0)
	v_mfma_f32_16x16x32_f16 v[66:69], v[58:61], v[110:113], v[66:69]
	ds_read_b128 v[118:121], v16 offset:36864
	v_mfma_f32_16x16x32_f16 v[44:47], v[94:97], v[106:109], v[44:47]
	ds_read_b128 v[122:125], v16 offset:38912
	v_mfma_f32_16x16x32_f16 v[78:81], v[94:97], v[110:113], v[78:81]
	s_waitcnt lgkmcnt(1)
	v_mfma_f32_16x16x32_f16 v[82:85], v[118:121], v[106:109], v[82:85]
	v_mfma_f32_16x16x32_f16 v[86:89], v[118:121], v[110:113], v[86:89]
	s_waitcnt lgkmcnt(0)
	v_mfma_f32_16x16x32_f16 v[28:31], v[122:125], v[106:109], v[28:31]
	ds_read_b128 v[106:109], v21 offset:4096
	v_mfma_f32_16x16x32_f16 v[32:35], v[122:125], v[110:113], v[32:35]
	ds_read_b128 v[110:113], v21 offset:6144
	s_waitcnt lgkmcnt(1)
	v_mfma_f32_16x16x32_f16 v[98:101], v[58:61], v[106:109], v[98:101]
	s_waitcnt lgkmcnt(0)
	v_mfma_f32_16x16x32_f16 v[52:55], v[58:61], v[110:113], v[52:55]
	ds_read_b128 v[58:61], v22 offset:32768
	v_mfma_f32_16x16x32_f16 v[102:105], v[94:97], v[106:109], v[102:105]
	v_mfma_f32_16x16x32_f16 v[24:27], v[94:97], v[110:113], v[24:27]
	ds_read_b128 v[94:97], v22 offset:34816
	v_mfma_f32_16x16x32_f16 v[114:117], v[118:121], v[106:109], v[114:117]
	s_waitcnt vmcnt(7)
	ds_write_b128 v17, v[62:65] offset:16384
	s_waitcnt vmcnt(6)
	ds_write_b128 v18, v[90:93] offset:16384
	v_mfma_f32_16x16x32_f16 v[40:43], v[118:121], v[110:113], v[40:43]
	ds_read_b128 v[118:121], v22 offset:36864
	s_waitcnt vmcnt(5)
	ds_write_b128 v19, v[130:133] offset:16384
	v_mfma_f32_16x16x32_f16 v[70:73], v[122:125], v[106:109], v[70:73]
	ds_read_b128 v[106:109], v23
	v_mfma_f32_16x16x32_f16 v[48:51], v[122:125], v[110:113], v[48:51]
	ds_read_b128 v[110:113], v23 offset:2048
	s_waitcnt lgkmcnt(1)
	v_mfma_f32_16x16x32_f16 v[36:39], v[58:61], v[106:109], v[36:39]
	ds_read_b128 v[122:125], v22 offset:38912
	s_waitcnt lgkmcnt(1)
	v_mfma_f32_16x16x32_f16 v[66:69], v[58:61], v[110:113], v[66:69]
	s_waitcnt vmcnt(4)
	ds_write_b128 v20, v[138:141] offset:16384
	v_mfma_f32_16x16x32_f16 v[44:47], v[94:97], v[106:109], v[44:47]
	s_waitcnt vmcnt(3)
	ds_write_b128 v17, v[74:77] offset:49152
	v_mfma_f32_16x16x32_f16 v[78:81], v[94:97], v[110:113], v[78:81]
	s_waitcnt vmcnt(2)
	ds_write_b128 v18, v[142:145] offset:49152
	v_mfma_f32_16x16x32_f16 v[82:85], v[118:121], v[106:109], v[82:85]
	s_waitcnt vmcnt(1)
	ds_write_b128 v19, v[154:157] offset:49152
	v_mfma_f32_16x16x32_f16 v[86:89], v[118:121], v[110:113], v[86:89]
	s_waitcnt vmcnt(0)
	ds_write_b128 v20, v[158:161] offset:49152
	s_waitcnt lgkmcnt(5)
	v_mfma_f32_16x16x32_f16 v[28:31], v[122:125], v[106:109], v[28:31]
	ds_read_b128 v[106:109], v23 offset:4096
	v_mfma_f32_16x16x32_f16 v[32:35], v[122:125], v[110:113], v[32:35]
	ds_read_b128 v[110:113], v23 offset:6144
	s_waitcnt lgkmcnt(1)
	v_mfma_f32_16x16x32_f16 v[98:101], v[58:61], v[106:109], v[98:101]
	s_waitcnt lgkmcnt(0)
	v_mfma_f32_16x16x32_f16 v[52:55], v[58:61], v[110:113], v[52:55]
	global_load_dwordx4 v[58:61], v[0:1], off offset:768
	v_mfma_f32_16x16x32_f16 v[102:105], v[94:97], v[106:109], v[102:105]
	v_mfma_f32_16x16x32_f16 v[24:27], v[94:97], v[110:113], v[24:27]
	v_mfma_f32_16x16x32_f16 v[114:117], v[118:121], v[106:109], v[114:117]
	v_mfma_f32_16x16x32_f16 v[40:43], v[118:121], v[110:113], v[40:43]
	v_mfma_f32_16x16x32_f16 v[70:73], v[122:125], v[106:109], v[70:73]
	global_load_dwordx4 v[106:109], v[2:3], off offset:768
	global_load_dwordx4 v[126:129], v[4:5], off offset:768
	global_load_dwordx4 v[134:137], v[14:15], off offset:768
	global_load_dwordx4 v[94:97], v[10:11], off offset:768
	global_load_dwordx4 v[162:165], v[12:13], off offset:768
	global_load_dwordx4 v[166:169], v[8:9], off offset:768
	global_load_dwordx4 v[190:193], v[6:7], off offset:768
	s_waitcnt lgkmcnt(0)
	s_barrier
	v_mfma_f32_16x16x32_f16 v[48:51], v[122:125], v[110:113], v[48:51]
	ds_read_b128 v[62:65], v16 offset:49152
	ds_read_b128 v[90:93], v21 offset:16384
	s_waitcnt lgkmcnt(0)
	v_mfma_f32_16x16x32_f16 v[36:39], v[62:65], v[90:93], v[36:39]
	ds_read_b128 v[74:77], v16 offset:51200
	ds_read_b128 v[110:113], v21 offset:18432
	s_waitcnt lgkmcnt(0)
	v_mfma_f32_16x16x32_f16 v[66:69], v[62:65], v[110:113], v[66:69]
	ds_read_b128 v[118:121], v16 offset:53248
	v_mfma_f32_16x16x32_f16 v[44:47], v[74:77], v[90:93], v[44:47]
	ds_read_b128 v[122:125], v16 offset:55296
	v_mfma_f32_16x16x32_f16 v[78:81], v[74:77], v[110:113], v[78:81]
	s_waitcnt lgkmcnt(1)
	v_mfma_f32_16x16x32_f16 v[82:85], v[118:121], v[90:93], v[82:85]
	v_mfma_f32_16x16x32_f16 v[86:89], v[118:121], v[110:113], v[86:89]
	s_waitcnt lgkmcnt(0)
	v_mfma_f32_16x16x32_f16 v[28:31], v[122:125], v[90:93], v[28:31]
	ds_read_b128 v[90:93], v21 offset:20480
	v_mfma_f32_16x16x32_f16 v[32:35], v[122:125], v[110:113], v[32:35]
	ds_read_b128 v[110:113], v21 offset:22528
	s_waitcnt lgkmcnt(1)
	v_mfma_f32_16x16x32_f16 v[98:101], v[62:65], v[90:93], v[98:101]
	s_waitcnt lgkmcnt(0)
	v_mfma_f32_16x16x32_f16 v[52:55], v[62:65], v[110:113], v[52:55]
	ds_read_b128 v[62:65], v22 offset:49152
	v_mfma_f32_16x16x32_f16 v[102:105], v[74:77], v[90:93], v[102:105]
	v_mfma_f32_16x16x32_f16 v[24:27], v[74:77], v[110:113], v[24:27]
	ds_read_b128 v[74:77], v22 offset:51200
	v_mfma_f32_16x16x32_f16 v[114:117], v[118:121], v[90:93], v[114:117]
	s_waitcnt vmcnt(7)
	ds_write_b128 v17, v[58:61]
	s_waitcnt vmcnt(6)
; #define GL_LOAD(s_, kt_) if (VAR != 1) { a##s_##0 = GL_A(0, kt_); a##s_##1 = GL_A(1, kt_); a##s_##2 = GL_A(2, kt_); a##s_##3 = GL_A(3, kt_); b##s_##0 = GL_B(0, kt_); b##s_##1 = GL_B(1, kt_); b##s_##2 = GL_B(2, kt_); b##s_##3 = GL_B(3, kt_); }
; #define LDS_STORE(s_, buf_) if (VAR != 2) { LDS_ST1(sA, 0, buf_, a##s_##0) LDS_ST1(sA, 1, buf_, a##s_##1) LDS_ST1(sA, 2, buf_, a##s_##2) LDS_ST1(sA, 3, buf_, a##s_##3) LDS_ST1(sB, 0, buf_, b##s_##0) LDS_ST1(sB, 1, buf_, b##s_##1) LDS_ST1(sB, 2, buf_, b##s_##2) LDS_ST1(sB, 3, buf_, b##s_##3) }
;     ...
;   GL_LOAD(0, 0)
;   GL_LOAD(1, 1)
;   LDS_STORE(0, 0)
;   if (VAR != 4) __syncthreads();
; #pragma unroll
;   for (int kt = 0; kt < nk; kt += 2) {
;     if (kt + 2 < nk) { GL_LOAD(0, kt + 2) }
;     MMA_TILE(0)
;     LDS_STORE(1, 1)
;     if (VAR != 4) __syncthreads();
;     if (kt + 3 < nk) { GL_LOAD(1, kt + 3) }
;     MMA_TILE(1)
;     if (kt + 2 < nk) { LDS_STORE(0, 0) }
;     if (VAR != 4) __syncthreads();
	ds_write_b128 v18, v[106:109]
	v_mfma_f32_16x16x32_f16 v[40:43], v[118:121], v[110:113], v[40:43]
	ds_read_b128 v[118:121], v22 offset:53248
	s_waitcnt vmcnt(5)
	ds_write_b128 v19, v[126:129]
	v_mfma_f32_16x16x32_f16 v[70:73], v[122:125], v[90:93], v[70:73]
	ds_read_b128 v[90:93], v23 offset:16384
	v_mfma_f32_16x16x32_f16 v[48:51], v[122:125], v[110:113], v[48:51]
	ds_read_b128 v[110:113], v23 offset:18432
	s_waitcnt lgkmcnt(1)
	v_mfma_f32_16x16x32_f16 v[36:39], v[62:65], v[90:93], v[36:39]
	ds_read_b128 v[122:125], v22 offset:55296
	s_waitcnt lgkmcnt(1)
	v_mfma_f32_16x16x32_f16 v[66:69], v[62:65], v[110:113], v[66:69]
	s_waitcnt vmcnt(4)
	ds_write_b128 v20, v[134:137]
	v_mfma_f32_16x16x32_f16 v[44:47], v[74:77], v[90:93], v[44:47]
	s_waitcnt vmcnt(3)
	ds_write_b128 v17, v[94:97] offset:32768
	v_mfma_f32_16x16x32_f16 v[78:81], v[74:77], v[110:113], v[78:81]
	s_waitcnt vmcnt(2)
	ds_write_b128 v18, v[162:165] offset:32768
	v_mfma_f32_16x16x32_f16 v[82:85], v[118:121], v[90:93], v[82:85]
	s_waitcnt vmcnt(1)
	ds_write_b128 v19, v[166:169] offset:32768
	v_mfma_f32_16x16x32_f16 v[86:89], v[118:121], v[110:113], v[86:89]
	s_waitcnt vmcnt(0)
	ds_write_b128 v20, v[190:193] offset:32768
	s_waitcnt lgkmcnt(5)
	v_mfma_f32_16x16x32_f16 v[28:31], v[122:125], v[90:93], v[28:31]
	ds_read_b128 v[90:93], v23 offset:20480
	v_mfma_f32_16x16x32_f16 v[32:35], v[122:125], v[110:113], v[32:35]
	ds_read_b128 v[110:113], v23 offset:22528
	s_waitcnt lgkmcnt(1)
	v_mfma_f32_16x16x32_f16 v[98:101], v[62:65], v[90:93], v[98:101]
	s_waitcnt lgkmcnt(0)
	v_mfma_f32_16x16x32_f16 v[52:55], v[62:65], v[110:113], v[52:55]
	global_load_dwordx4 v[62:65], v[0:1], off offset:896
	v_mfma_f32_16x16x32_f16 v[102:105], v[74:77], v[90:93], v[102:105]
	v_mfma_f32_16x16x32_f16 v[24:27], v[74:77], v[110:113], v[24:27]
	v_mfma_f32_16x16x32_f16 v[114:117], v[118:121], v[90:93], v[114:117]
	v_mfma_f32_16x16x32_f16 v[40:43], v[118:121], v[110:113], v[40:43]
	v_mfma_f32_16x16x32_f16 v[70:73], v[122:125], v[90:93], v[70:73]
	global_load_dwordx4 v[90:93], v[2:3], off offset:896
	global_load_dwordx4 v[130:133], v[4:5], off offset:896
	global_load_dwordx4 v[138:141], v[14:15], off offset:896
	global_load_dwordx4 v[74:77], v[10:11], off offset:896
	global_load_dwordx4 v[142:145], v[12:13], off offset:896
	global_load_dwordx4 v[154:157], v[8:9], off offset:896
	global_load_dwordx4 v[158:161], v[6:7], off offset:896
	s_waitcnt lgkmcnt(0)
	s_barrier
	v_mfma_f32_16x16x32_f16 v[48:51], v[122:125], v[110:113], v[48:51]
	ds_read_b128 v[58:61], v16 offset:32768
	ds_read_b128 v[106:109], v21
	s_waitcnt lgkmcnt(0)
	v_mfma_f32_16x16x32_f16 v[36:39], v[58:61], v[106:109], v[36:39]
	ds_read_b128 v[94:97], v16 offset:34816
	ds_read_b128 v[110:113], v21 offset:2048
	s_waitcnt lgkmcnt(0)
	v_mfma_f32_16x16x32_f16 v[66:69], v[58:61], v[110:113], v[66:69]
	ds_read_b128 v[118:121], v16 offset:36864
	v_mfma_f32_16x16x32_f16 v[44:47], v[94:97], v[106:109], v[44:47]
	ds_read_b128 v[122:125], v16 offset:38912
	v_mfma_f32_16x16x32_f16 v[78:81], v[94:97], v[110:113], v[78:81]
	s_waitcnt lgkmcnt(1)
	v_mfma_f32_16x16x32_f16 v[82:85], v[118:121], v[106:109], v[82:85]
	v_mfma_f32_16x16x32_f16 v[86:89], v[118:121], v[110:113], v[86:89]
	s_waitcnt lgkmcnt(0)
	v_mfma_f32_16x16x32_f16 v[28:31], v[122:125], v[106:109], v[28:31]
	ds_read_b128 v[106:109], v21 offset:4096
	v_mfma_f32_16x16x32_f16 v[32:35], v[122:125], v[110:113], v[32:35]
	ds_read_b128 v[110:113], v21 offset:6144
	s_waitcnt lgkmcnt(1)
	v_mfma_f32_16x16x32_f16 v[98:101], v[58:61], v[106:109], v[98:101]
	s_waitcnt lgkmcnt(0)
	v_mfma_f32_16x16x32_f16 v[52:55], v[58:61], v[110:113], v[52:55]
	ds_read_b128 v[58:61], v22 offset:32768
	v_mfma_f32_16x16x32_f16 v[102:105], v[94:97], v[106:109], v[102:105]
	v_mfma_f32_16x16x32_f16 v[24:27], v[94:97], v[110:113], v[24:27]
	ds_read_b128 v[94:97], v22 offset:34816
	v_mfma_f32_16x16x32_f16 v[114:117], v[118:121], v[106:109], v[114:117]
	s_waitcnt vmcnt(7)
	ds_write_b128 v17, v[62:65] offset:16384
	s_waitcnt vmcnt(6)
	ds_write_b128 v18, v[90:93] offset:16384
	v_mfma_f32_16x16x32_f16 v[40:43], v[118:121], v[110:113], v[40:43]
	ds_read_b128 v[118:121], v22 offset:36864
	s_waitcnt vmcnt(5)
	ds_write_b128 v19, v[130:133] offset:16384
	v_mfma_f32_16x16x32_f16 v[70:73], v[122:125], v[106:109], v[70:73]
	ds_read_b128 v[106:109], v23
	v_mfma_f32_16x16x32_f16 v[48:51], v[122:125], v[110:113], v[48:51]
	ds_read_b128 v[110:113], v23 offset:2048
	s_waitcnt lgkmcnt(1)
	v_mfma_f32_16x16x32_f16 v[36:39], v[58:61], v[106:109], v[36:39]
	ds_read_b128 v[122:125], v22 offset:38912
	s_waitcnt lgkmcnt(1)
	v_mfma_f32_16x16x32_f16 v[66:69], v[58:61], v[110:113], v[66:69]
	s_waitcnt vmcnt(4)
	ds_write_b128 v20, v[138:141] offset:16384
	v_mfma_f32_16x16x32_f16 v[44:47], v[94:97], v[106:109], v[44:47]
	s_waitcnt vmcnt(3)
	ds_write_b128 v17, v[74:77] offset:49152
	v_mfma_f32_16x16x32_f16 v[78:81], v[94:97], v[110:113], v[78:81]
	s_waitcnt vmcnt(2)
	ds_write_b128 v18, v[142:145] offset:49152
	v_mfma_f32_16x16x32_f16 v[82:85], v[118:121], v[106:109], v[82:85]
	s_waitcnt vmcnt(1)
	ds_write_b128 v19, v[154:157] offset:49152
	v_mfma_f32_16x16x32_f16 v[86:89], v[118:121], v[110:113], v[86:89]
	s_waitcnt vmcnt(0)
	ds_write_b128 v20, v[158:161] offset:49152
	s_waitcnt lgkmcnt(5)
	v_mfma_f32_16x16x32_f16 v[28:31], v[122:125], v[106:109], v[28:31]
	ds_read_b128 v[106:109], v23 offset:4096
	v_mfma_f32_16x16x32_f16 v[32:35], v[122:125], v[110:113], v[32:35]
	ds_read_b128 v[110:113], v23 offset:6144
	s_waitcnt lgkmcnt(1)
	v_mfma_f32_16x16x32_f16 v[98:101], v[58:61], v[106:109], v[98:101]
	s_waitcnt lgkmcnt(0)
	v_mfma_f32_16x16x32_f16 v[52:55], v[58:61], v[110:113], v[52:55]
	global_load_dwordx4 v[58:61], v[0:1], off offset:1024
	v_mfma_f32_16x16x32_f16 v[102:105], v[94:97], v[106:109], v[102:105]
	v_mfma_f32_16x16x32_f16 v[24:27], v[94:97], v[110:113], v[24:27]
	v_mfma_f32_16x16x32_f16 v[114:117], v[118:121], v[106:109], v[114:117]
	v_mfma_f32_16x16x32_f16 v[40:43], v[118:121], v[110:113], v[40:43]
	v_mfma_f32_16x16x32_f16 v[70:73], v[122:125], v[106:109], v[70:73]
	global_load_dwordx4 v[106:109], v[2:3], off offset:1024
	global_load_dwordx4 v[126:129], v[4:5], off offset:1024
	global_load_dwordx4 v[134:137], v[14:15], off offset:1024
	global_load_dwordx4 v[94:97], v[10:11], off offset:1024
	global_load_dwordx4 v[162:165], v[12:13], off offset:1024
	global_load_dwordx4 v[166:169], v[8:9], off offset:1024
	global_load_dwordx4 v[190:193], v[6:7], off offset:1024
	s_waitcnt lgkmcnt(0)
	s_barrier
; #define GL_LOAD(s_, kt_) if (VAR != 1) { a##s_##0 = GL_A(0, kt_); a##s_##1 = GL_A(1, kt_); a##s_##2 = GL_A(2, kt_); a##s_##3 = GL_A(3, kt_); b##s_##0 = GL_B(0, kt_); b##s_##1 = GL_B(1, kt_); b##s_##2 = GL_B(2, kt_); b##s_##3 = GL_B(3, kt_); }
; #define LDS_STORE(s_, buf_) if (VAR != 2) { LDS_ST1(sA, 0, buf_, a##s_##0) LDS_ST1(sA, 1, buf_, a##s_##1) LDS_ST1(sA, 2, buf_, a##s_##2) LDS_ST1(sA, 3, buf_, a##s_##3) LDS_ST1(sB, 0, buf_, b##s_##0) LDS_ST1(sB, 1, buf_, b##s_##1) LDS_ST1(sB, 2, buf_, b##s_##2) LDS_ST1(sB, 3, buf_, b##s_##3) }
;     ...
;   GL_LOAD(0, 0)
;   GL_LOAD(1, 1)
;   LDS_STORE(0, 0)
;   if (VAR != 4) __syncthreads();
; #pragma unroll
;   for (int kt = 0; kt < nk; kt += 2) {
;     if (kt + 2 < nk) { GL_LOAD(0, kt + 2) }
;     MMA_TILE(0)
;     LDS_STORE(1, 1)
;     if (VAR != 4) __syncthreads();
;     if (kt + 3 < nk) { GL_LOAD(1, kt + 3) }
;     MMA_TILE(1)
;     if (kt + 2 < nk) { LDS_STORE(0, 0) }
;     if (VAR != 4) __syncthreads();
	v_mfma_f32_16x16x32_f16 v[48:51], v[122:125], v[110:113], v[48:51]
	ds_read_b128 v[62:65], v16 offset:49152
	ds_read_b128 v[90:93], v21 offset:16384
	s_waitcnt lgkmcnt(0)
	v_mfma_f32_16x16x32_f16 v[36:39], v[62:65], v[90:93], v[36:39]
	ds_read_b128 v[74:77], v16 offset:51200
	ds_read_b128 v[110:113], v21 offset:18432
	s_waitcnt lgkmcnt(0)
	v_mfma_f32_16x16x32_f16 v[66:69], v[62:65], v[110:113], v[66:69]
	ds_read_b128 v[118:121], v16 offset:53248
	v_mfma_f32_16x16x32_f16 v[44:47], v[74:77], v[90:93], v[44:47]
	ds_read_b128 v[122:125], v16 offset:55296
	v_mfma_f32_16x16x32_f16 v[78:81], v[74:77], v[110:113], v[78:81]
	s_waitcnt lgkmcnt(1)
	v_mfma_f32_16x16x32_f16 v[82:85], v[118:121], v[90:93], v[82:85]
	v_mfma_f32_16x16x32_f16 v[86:89], v[118:121], v[110:113], v[86:89]
	s_waitcnt lgkmcnt(0)
	v_mfma_f32_16x16x32_f16 v[28:31], v[122:125], v[90:93], v[28:31]
	ds_read_b128 v[90:93], v21 offset:20480
	v_mfma_f32_16x16x32_f16 v[32:35], v[122:125], v[110:113], v[32:35]
	ds_read_b128 v[110:113], v21 offset:22528
	s_waitcnt lgkmcnt(1)
	v_mfma_f32_16x16x32_f16 v[98:101], v[62:65], v[90:93], v[98:101]
	s_waitcnt lgkmcnt(0)
	v_mfma_f32_16x16x32_f16 v[52:55], v[62:65], v[110:113], v[52:55]
	ds_read_b128 v[62:65], v22 offset:49152
	v_mfma_f32_16x16x32_f16 v[102:105], v[74:77], v[90:93], v[102:105]
	v_mfma_f32_16x16x32_f16 v[24:27], v[74:77], v[110:113], v[24:27]
	ds_read_b128 v[74:77], v22 offset:51200
	v_mfma_f32_16x16x32_f16 v[114:117], v[118:121], v[90:93], v[114:117]
	s_waitcnt vmcnt(7)
	ds_write_b128 v17, v[58:61]
	s_waitcnt vmcnt(6)
	ds_write_b128 v18, v[106:109]
	v_mfma_f32_16x16x32_f16 v[40:43], v[118:121], v[110:113], v[40:43]
	ds_read_b128 v[118:121], v22 offset:53248
	s_waitcnt vmcnt(5)
	ds_write_b128 v19, v[126:129]
	v_mfma_f32_16x16x32_f16 v[70:73], v[122:125], v[90:93], v[70:73]
	ds_read_b128 v[90:93], v23 offset:16384
	v_mfma_f32_16x16x32_f16 v[48:51], v[122:125], v[110:113], v[48:51]
	ds_read_b128 v[110:113], v23 offset:18432
	s_waitcnt lgkmcnt(1)
	v_mfma_f32_16x16x32_f16 v[36:39], v[62:65], v[90:93], v[36:39]
	ds_read_b128 v[122:125], v22 offset:55296
	s_waitcnt lgkmcnt(1)
	v_mfma_f32_16x16x32_f16 v[66:69], v[62:65], v[110:113], v[66:69]
	s_waitcnt vmcnt(4)
	ds_write_b128 v20, v[134:137]
	v_mfma_f32_16x16x32_f16 v[44:47], v[74:77], v[90:93], v[44:47]
	s_waitcnt vmcnt(3)
	ds_write_b128 v17, v[94:97] offset:32768
	v_mfma_f32_16x16x32_f16 v[78:81], v[74:77], v[110:113], v[78:81]
	s_waitcnt vmcnt(2)
	ds_write_b128 v18, v[162:165] offset:32768
	v_mfma_f32_16x16x32_f16 v[82:85], v[118:121], v[90:93], v[82:85]
	s_waitcnt vmcnt(1)
	ds_write_b128 v19, v[166:169] offset:32768
	v_mfma_f32_16x16x32_f16 v[86:89], v[118:121], v[110:113], v[86:89]
	s_waitcnt vmcnt(0)
	ds_write_b128 v20, v[190:193] offset:32768
	s_waitcnt lgkmcnt(5)
	v_mfma_f32_16x16x32_f16 v[28:31], v[122:125], v[90:93], v[28:31]
	ds_read_b128 v[90:93], v23 offset:20480
	v_mfma_f32_16x16x32_f16 v[32:35], v[122:125], v[110:113], v[32:35]
	ds_read_b128 v[110:113], v23 offset:22528
	s_waitcnt lgkmcnt(1)
	v_mfma_f32_16x16x32_f16 v[98:101], v[62:65], v[90:93], v[98:101]
	s_waitcnt lgkmcnt(0)
	v_mfma_f32_16x16x32_f16 v[52:55], v[62:65], v[110:113], v[52:55]
	global_load_dwordx4 v[62:65], v[0:1], off offset:1152
	v_mfma_f32_16x16x32_f16 v[102:105], v[74:77], v[90:93], v[102:105]
	v_mfma_f32_16x16x32_f16 v[24:27], v[74:77], v[110:113], v[24:27]
	v_mfma_f32_16x16x32_f16 v[114:117], v[118:121], v[90:93], v[114:117]
	v_mfma_f32_16x16x32_f16 v[40:43], v[118:121], v[110:113], v[40:43]
	v_mfma_f32_16x16x32_f16 v[70:73], v[122:125], v[90:93], v[70:73]
	global_load_dwordx4 v[90:93], v[2:3], off offset:1152
	global_load_dwordx4 v[130:133], v[4:5], off offset:1152
	global_load_dwordx4 v[138:141], v[14:15], off offset:1152
	global_load_dwordx4 v[74:77], v[10:11], off offset:1152
	global_load_dwordx4 v[142:145], v[12:13], off offset:1152
	global_load_dwordx4 v[154:157], v[8:9], off offset:1152
	global_load_dwordx4 v[158:161], v[6:7], off offset:1152
	s_waitcnt lgkmcnt(0)
	s_barrier
	v_mfma_f32_16x16x32_f16 v[48:51], v[122:125], v[110:113], v[48:51]
	ds_read_b128 v[58:61], v16 offset:32768
	ds_read_b128 v[106:109], v21
	s_waitcnt lgkmcnt(0)
	v_mfma_f32_16x16x32_f16 v[36:39], v[58:61], v[106:109], v[36:39]
	ds_read_b128 v[94:97], v16 offset:34816
	ds_read_b128 v[110:113], v21 offset:2048
	s_waitcnt lgkmcnt(0)
	v_mfma_f32_16x16x32_f16 v[66:69], v[58:61], v[110:113], v[66:69]
	ds_read_b128 v[118:121], v16 offset:36864
	v_mfma_f32_16x16x32_f16 v[44:47], v[94:97], v[106:109], v[44:47]
	ds_read_b128 v[122:125], v16 offset:38912
	v_mfma_f32_16x16x32_f16 v[78:81], v[94:97], v[110:113], v[78:81]
	s_waitcnt lgkmcnt(1)
	v_mfma_f32_16x16x32_f16 v[82:85], v[118:121], v[106:109], v[82:85]
	v_mfma_f32_16x16x32_f16 v[86:89], v[118:121], v[110:113], v[86:89]
	s_waitcnt lgkmcnt(0)
	v_mfma_f32_16x16x32_f16 v[28:31], v[122:125], v[106:109], v[28:31]
	ds_read_b128 v[106:109], v21 offset:4096
	v_mfma_f32_16x16x32_f16 v[32:35], v[122:125], v[110:113], v[32:35]
	ds_read_b128 v[110:113], v21 offset:6144
	s_waitcnt lgkmcnt(1)
	v_mfma_f32_16x16x32_f16 v[98:101], v[58:61], v[106:109], v[98:101]
	s_waitcnt lgkmcnt(0)
	v_mfma_f32_16x16x32_f16 v[52:55], v[58:61], v[110:113], v[52:55]
	ds_read_b128 v[58:61], v22 offset:32768
	v_mfma_f32_16x16x32_f16 v[102:105], v[94:97], v[106:109], v[102:105]
	v_mfma_f32_16x16x32_f16 v[24:27], v[94:97], v[110:113], v[24:27]
	ds_read_b128 v[94:97], v22 offset:34816
	v_mfma_f32_16x16x32_f16 v[114:117], v[118:121], v[106:109], v[114:117]
	s_waitcnt vmcnt(7)
	ds_write_b128 v17, v[62:65] offset:16384
	s_waitcnt vmcnt(6)
; #define GL_LOAD(s_, kt_) if (VAR != 1) { a##s_##0 = GL_A(0, kt_); a##s_##1 = GL_A(1, kt_); a##s_##2 = GL_A(2, kt_); a##s_##3 = GL_A(3, kt_); b##s_##0 = GL_B(0, kt_); b##s_##1 = GL_B(1, kt_); b##s_##2 = GL_B(2, kt_); b##s_##3 = GL_B(3, kt_); }
; #define LDS_STORE(s_, buf_) if (VAR != 2) { LDS_ST1(sA, 0, buf_, a##s_##0) LDS_ST1(sA, 1, buf_, a##s_##1) LDS_ST1(sA, 2, buf_, a##s_##2) LDS_ST1(sA, 3, buf_, a##s_##3) LDS_ST1(sB, 0, buf_, b##s_##0) LDS_ST1(sB, 1, buf_, b##s_##1) LDS_ST1(sB, 2, buf_, b##s_##2) LDS_ST1(sB, 3, buf_, b##s_##3) }
;     ...
;   GL_LOAD(0, 0)
;   GL_LOAD(1, 1)
;   LDS_STORE(0, 0)
;   if (VAR != 4) __syncthreads();
; #pragma unroll
;   for (int kt = 0; kt < nk; kt += 2) {
;     if (kt + 2 < nk) { GL_LOAD(0, kt + 2) }
;     MMA_TILE(0)
;     LDS_STORE(1, 1)
;     if (VAR != 4) __syncthreads();
;     if (kt + 3 < nk) { GL_LOAD(1, kt + 3) }
;     MMA_TILE(1)
;     if (kt + 2 < nk) { LDS_STORE(0, 0) }
;     if (VAR != 4) __syncthreads();
	ds_write_b128 v18, v[90:93] offset:16384
	v_mfma_f32_16x16x32_f16 v[40:43], v[118:121], v[110:113], v[40:43]
	ds_read_b128 v[118:121], v22 offset:36864
	s_waitcnt vmcnt(5)
	ds_write_b128 v19, v[130:133] offset:16384
	v_mfma_f32_16x16x32_f16 v[70:73], v[122:125], v[106:109], v[70:73]
	ds_read_b128 v[106:109], v23
	v_mfma_f32_16x16x32_f16 v[48:51], v[122:125], v[110:113], v[48:51]
	ds_read_b128 v[110:113], v23 offset:2048
	s_waitcnt lgkmcnt(1)
	v_mfma_f32_16x16x32_f16 v[36:39], v[58:61], v[106:109], v[36:39]
	ds_read_b128 v[122:125], v22 offset:38912
	s_waitcnt lgkmcnt(1)
	v_mfma_f32_16x16x32_f16 v[66:69], v[58:61], v[110:113], v[66:69]
	s_waitcnt vmcnt(4)
	ds_write_b128 v20, v[138:141] offset:16384
	v_mfma_f32_16x16x32_f16 v[44:47], v[94:97], v[106:109], v[44:47]
	s_waitcnt vmcnt(3)
	ds_write_b128 v17, v[74:77] offset:49152
	v_mfma_f32_16x16x32_f16 v[78:81], v[94:97], v[110:113], v[78:81]
	s_waitcnt vmcnt(2)
	ds_write_b128 v18, v[142:145] offset:49152
	v_mfma_f32_16x16x32_f16 v[82:85], v[118:121], v[106:109], v[82:85]
	s_waitcnt vmcnt(1)
	ds_write_b128 v19, v[154:157] offset:49152
	v_mfma_f32_16x16x32_f16 v[86:89], v[118:121], v[110:113], v[86:89]
	s_waitcnt vmcnt(0)
	ds_write_b128 v20, v[158:161] offset:49152
	s_waitcnt lgkmcnt(5)
	v_mfma_f32_16x16x32_f16 v[28:31], v[122:125], v[106:109], v[28:31]
	ds_read_b128 v[106:109], v23 offset:4096
	v_mfma_f32_16x16x32_f16 v[32:35], v[122:125], v[110:113], v[32:35]
	ds_read_b128 v[110:113], v23 offset:6144
	s_waitcnt lgkmcnt(1)
	v_mfma_f32_16x16x32_f16 v[98:101], v[58:61], v[106:109], v[98:101]
	s_waitcnt lgkmcnt(0)
	v_mfma_f32_16x16x32_f16 v[52:55], v[58:61], v[110:113], v[52:55]
	global_load_dwordx4 v[58:61], v[0:1], off offset:1280
	v_mfma_f32_16x16x32_f16 v[102:105], v[94:97], v[106:109], v[102:105]
	v_mfma_f32_16x16x32_f16 v[24:27], v[94:97], v[110:113], v[24:27]
	v_mfma_f32_16x16x32_f16 v[114:117], v[118:121], v[106:109], v[114:117]
	v_mfma_f32_16x16x32_f16 v[40:43], v[118:121], v[110:113], v[40:43]
	v_mfma_f32_16x16x32_f16 v[70:73], v[122:125], v[106:109], v[70:73]
	global_load_dwordx4 v[106:109], v[2:3], off offset:1280
	global_load_dwordx4 v[126:129], v[4:5], off offset:1280
	global_load_dwordx4 v[134:137], v[14:15], off offset:1280
	global_load_dwordx4 v[94:97], v[10:11], off offset:1280
	global_load_dwordx4 v[162:165], v[12:13], off offset:1280
	global_load_dwordx4 v[166:169], v[8:9], off offset:1280
	global_load_dwordx4 v[190:193], v[6:7], off offset:1280
	s_waitcnt lgkmcnt(0)
	s_barrier
	v_mfma_f32_16x16x32_f16 v[48:51], v[122:125], v[110:113], v[48:51]
	ds_read_b128 v[62:65], v16 offset:49152
	ds_read_b128 v[90:93], v21 offset:16384
	s_waitcnt lgkmcnt(0)
	v_mfma_f32_16x16x32_f16 v[36:39], v[62:65], v[90:93], v[36:39]
	ds_read_b128 v[74:77], v16 offset:51200
	ds_read_b128 v[110:113], v21 offset:18432
	s_waitcnt lgkmcnt(0)
	v_mfma_f32_16x16x32_f16 v[66:69], v[62:65], v[110:113], v[66:69]
	ds_read_b128 v[118:121], v16 offset:53248
	v_mfma_f32_16x16x32_f16 v[44:47], v[74:77], v[90:93], v[44:47]
	ds_read_b128 v[122:125], v16 offset:55296
	v_mfma_f32_16x16x32_f16 v[78:81], v[74:77], v[110:113], v[78:81]
	s_waitcnt lgkmcnt(1)
	v_mfma_f32_16x16x32_f16 v[82:85], v[118:121], v[90:93], v[82:85]
	v_mfma_f32_16x16x32_f16 v[86:89], v[118:121], v[110:113], v[86:89]
	s_waitcnt lgkmcnt(0)
	v_mfma_f32_16x16x32_f16 v[28:31], v[122:125], v[90:93], v[28:31]
	ds_read_b128 v[90:93], v21 offset:20480
	v_mfma_f32_16x16x32_f16 v[32:35], v[122:125], v[110:113], v[32:35]
	ds_read_b128 v[110:113], v21 offset:22528
	s_waitcnt lgkmcnt(1)
	v_mfma_f32_16x16x32_f16 v[98:101], v[62:65], v[90:93], v[98:101]
	s_waitcnt lgkmcnt(0)
	v_mfma_f32_16x16x32_f16 v[52:55], v[62:65], v[110:113], v[52:55]
	ds_read_b128 v[62:65], v22 offset:49152
	v_mfma_f32_16x16x32_f16 v[102:105], v[74:77], v[90:93], v[102:105]
	v_mfma_f32_16x16x32_f16 v[24:27], v[74:77], v[110:113], v[24:27]
	ds_read_b128 v[74:77], v22 offset:51200
	v_mfma_f32_16x16x32_f16 v[114:117], v[118:121], v[90:93], v[114:117]
	s_waitcnt vmcnt(7)
	ds_write_b128 v17, v[58:61]
	s_waitcnt vmcnt(6)
	ds_write_b128 v18, v[106:109]
	v_mfma_f32_16x16x32_f16 v[40:43], v[118:121], v[110:113], v[40:43]
	ds_read_b128 v[118:121], v22 offset:53248
	s_waitcnt vmcnt(5)
	ds_write_b128 v19, v[126:129]
	v_mfma_f32_16x16x32_f16 v[70:73], v[122:125], v[90:93], v[70:73]
	ds_read_b128 v[90:93], v23 offset:16384
	v_mfma_f32_16x16x32_f16 v[48:51], v[122:125], v[110:113], v[48:51]
	ds_read_b128 v[110:113], v23 offset:18432
	s_waitcnt lgkmcnt(1)
	v_mfma_f32_16x16x32_f16 v[36:39], v[62:65], v[90:93], v[36:39]
	ds_read_b128 v[122:125], v22 offset:55296
	s_waitcnt lgkmcnt(1)
	v_mfma_f32_16x16x32_f16 v[66:69], v[62:65], v[110:113], v[66:69]
	s_waitcnt vmcnt(4)
	ds_write_b128 v20, v[134:137]
	v_mfma_f32_16x16x32_f16 v[44:47], v[74:77], v[90:93], v[44:47]
	s_waitcnt vmcnt(3)
	ds_write_b128 v17, v[94:97] offset:32768
	v_mfma_f32_16x16x32_f16 v[78:81], v[74:77], v[110:113], v[78:81]
	s_waitcnt vmcnt(2)
	ds_write_b128 v18, v[162:165] offset:32768
	v_mfma_f32_16x16x32_f16 v[82:85], v[118:121], v[90:93], v[82:85]
	s_waitcnt vmcnt(1)
	ds_write_b128 v19, v[166:169] offset:32768
	v_mfma_f32_16x16x32_f16 v[86:89], v[118:121], v[110:113], v[86:89]
	s_waitcnt vmcnt(0)
	ds_write_b128 v20, v[190:193] offset:32768
	s_waitcnt lgkmcnt(5)
	v_mfma_f32_16x16x32_f16 v[28:31], v[122:125], v[90:93], v[28:31]
	ds_read_b128 v[90:93], v23 offset:20480
	v_mfma_f32_16x16x32_f16 v[32:35], v[122:125], v[110:113], v[32:35]
	ds_read_b128 v[110:113], v23 offset:22528
	s_waitcnt lgkmcnt(1)
	v_mfma_f32_16x16x32_f16 v[98:101], v[62:65], v[90:93], v[98:101]
	s_waitcnt lgkmcnt(0)
	v_mfma_f32_16x16x32_f16 v[52:55], v[62:65], v[110:113], v[52:55]
	global_load_dwordx4 v[62:65], v[0:1], off offset:1408
	v_mfma_f32_16x16x32_f16 v[102:105], v[74:77], v[90:93], v[102:105]
	v_mfma_f32_16x16x32_f16 v[24:27], v[74:77], v[110:113], v[24:27]
	v_mfma_f32_16x16x32_f16 v[114:117], v[118:121], v[90:93], v[114:117]
	v_mfma_f32_16x16x32_f16 v[40:43], v[118:121], v[110:113], v[40:43]
	v_mfma_f32_16x16x32_f16 v[70:73], v[122:125], v[90:93], v[70:73]
	global_load_dwordx4 v[90:93], v[2:3], off offset:1408
	global_load_dwordx4 v[130:133], v[4:5], off offset:1408
	global_load_dwordx4 v[138:141], v[14:15], off offset:1408
	global_load_dwordx4 v[74:77], v[10:11], off offset:1408
	global_load_dwordx4 v[142:145], v[12:13], off offset:1408
	global_load_dwordx4 v[154:157], v[8:9], off offset:1408
	global_load_dwordx4 v[158:161], v[6:7], off offset:1408
	s_waitcnt lgkmcnt(0)
	s_barrier
; #define GL_LOAD(s_, kt_) if (VAR != 1) { a##s_##0 = GL_A(0, kt_); a##s_##1 = GL_A(1, kt_); a##s_##2 = GL_A(2, kt_); a##s_##3 = GL_A(3, kt_); b##s_##0 = GL_B(0, kt_); b##s_##1 = GL_B(1, kt_); b##s_##2 = GL_B(2, kt_); b##s_##3 = GL_B(3, kt_); }
; #define LDS_STORE(s_, buf_) if (VAR != 2) { LDS_ST1(sA, 0, buf_, a##s_##0) LDS_ST1(sA, 1, buf_, a##s_##1) LDS_ST1(sA, 2, buf_, a##s_##2) LDS_ST1(sA, 3, buf_, a##s_##3) LDS_ST1(sB, 0, buf_, b##s_##0) LDS_ST1(sB, 1, buf_, b##s_##1) LDS_ST1(sB, 2, buf_, b##s_##2) LDS_ST1(sB, 3, buf_, b##s_##3) }
;     ...
;   GL_LOAD(0, 0)
;   GL_LOAD(1, 1)
;   LDS_STORE(0, 0)
;   if (VAR != 4) __syncthreads();
; #pragma unroll
;   for (int kt = 0; kt < nk; kt += 2) {
;     if (kt + 2 < nk) { GL_LOAD(0, kt + 2) }
;     MMA_TILE(0)
;     LDS_STORE(1, 1)
;     if (VAR != 4) __syncthreads();
;     if (kt + 3 < nk) { GL_LOAD(1, kt + 3) }
;     MMA_TILE(1)
;     if (kt + 2 < nk) { LDS_STORE(0, 0) }
;     if (VAR != 4) __syncthreads();
	v_mfma_f32_16x16x32_f16 v[48:51], v[122:125], v[110:113], v[48:51]
	ds_read_b128 v[58:61], v16 offset:32768
	ds_read_b128 v[106:109], v21
	s_waitcnt lgkmcnt(0)
	v_mfma_f32_16x16x32_f16 v[36:39], v[58:61], v[106:109], v[36:39]
	ds_read_b128 v[94:97], v16 offset:34816
	ds_read_b128 v[110:113], v21 offset:2048
	s_waitcnt lgkmcnt(0)
	v_mfma_f32_16x16x32_f16 v[66:69], v[58:61], v[110:113], v[66:69]
	ds_read_b128 v[118:121], v16 offset:36864
	v_mfma_f32_16x16x32_f16 v[44:47], v[94:97], v[106:109], v[44:47]
	ds_read_b128 v[122:125], v16 offset:38912
	v_mfma_f32_16x16x32_f16 v[78:81], v[94:97], v[110:113], v[78:81]
	s_waitcnt lgkmcnt(1)
	v_mfma_f32_16x16x32_f16 v[82:85], v[118:121], v[106:109], v[82:85]
	v_mfma_f32_16x16x32_f16 v[86:89], v[118:121], v[110:113], v[86:89]
	s_waitcnt lgkmcnt(0)
	v_mfma_f32_16x16x32_f16 v[28:31], v[122:125], v[106:109], v[28:31]
	ds_read_b128 v[106:109], v21 offset:4096
	v_mfma_f32_16x16x32_f16 v[32:35], v[122:125], v[110:113], v[32:35]
	ds_read_b128 v[110:113], v21 offset:6144
	s_waitcnt lgkmcnt(1)
	v_mfma_f32_16x16x32_f16 v[98:101], v[58:61], v[106:109], v[98:101]
	s_waitcnt lgkmcnt(0)
	v_mfma_f32_16x16x32_f16 v[52:55], v[58:61], v[110:113], v[52:55]
	ds_read_b128 v[58:61], v22 offset:32768
	v_mfma_f32_16x16x32_f16 v[102:105], v[94:97], v[106:109], v[102:105]
	v_mfma_f32_16x16x32_f16 v[24:27], v[94:97], v[110:113], v[24:27]
	ds_read_b128 v[94:97], v22 offset:34816
	v_mfma_f32_16x16x32_f16 v[114:117], v[118:121], v[106:109], v[114:117]
	s_waitcnt vmcnt(7)
	ds_write_b128 v17, v[62:65] offset:16384
	s_waitcnt vmcnt(6)
	ds_write_b128 v18, v[90:93] offset:16384
	v_mfma_f32_16x16x32_f16 v[40:43], v[118:121], v[110:113], v[40:43]
	ds_read_b128 v[118:121], v22 offset:36864
	s_waitcnt vmcnt(5)
	ds_write_b128 v19, v[130:133] offset:16384
	v_mfma_f32_16x16x32_f16 v[70:73], v[122:125], v[106:109], v[70:73]
	ds_read_b128 v[106:109], v23
	v_mfma_f32_16x16x32_f16 v[48:51], v[122:125], v[110:113], v[48:51]
	ds_read_b128 v[110:113], v23 offset:2048
	s_waitcnt lgkmcnt(1)
	v_mfma_f32_16x16x32_f16 v[36:39], v[58:61], v[106:109], v[36:39]
	ds_read_b128 v[122:125], v22 offset:38912
	s_waitcnt lgkmcnt(1)
	v_mfma_f32_16x16x32_f16 v[66:69], v[58:61], v[110:113], v[66:69]
	s_waitcnt vmcnt(4)
	ds_write_b128 v20, v[138:141] offset:16384
	v_mfma_f32_16x16x32_f16 v[44:47], v[94:97], v[106:109], v[44:47]
	s_waitcnt vmcnt(3)
	ds_write_b128 v17, v[74:77] offset:49152
	v_mfma_f32_16x16x32_f16 v[78:81], v[94:97], v[110:113], v[78:81]
	s_waitcnt vmcnt(2)
	ds_write_b128 v18, v[142:145] offset:49152
	v_mfma_f32_16x16x32_f16 v[82:85], v[118:121], v[106:109], v[82:85]
	s_waitcnt vmcnt(1)
	ds_write_b128 v19, v[154:157] offset:49152
	v_mfma_f32_16x16x32_f16 v[86:89], v[118:121], v[110:113], v[86:89]
	s_waitcnt vmcnt(0)
	ds_write_b128 v20, v[158:161] offset:49152
	s_waitcnt lgkmcnt(5)
	v_mfma_f32_16x16x32_f16 v[28:31], v[122:125], v[106:109], v[28:31]
	ds_read_b128 v[106:109], v23 offset:4096
	v_mfma_f32_16x16x32_f16 v[32:35], v[122:125], v[110:113], v[32:35]
	ds_read_b128 v[110:113], v23 offset:6144
	s_waitcnt lgkmcnt(1)
	v_mfma_f32_16x16x32_f16 v[98:101], v[58:61], v[106:109], v[98:101]
	s_waitcnt lgkmcnt(0)
	v_mfma_f32_16x16x32_f16 v[52:55], v[58:61], v[110:113], v[52:55]
	global_load_dwordx4 v[58:61], v[0:1], off offset:1536
	v_mfma_f32_16x16x32_f16 v[102:105], v[94:97], v[106:109], v[102:105]
	v_mfma_f32_16x16x32_f16 v[24:27], v[94:97], v[110:113], v[24:27]
	v_mfma_f32_16x16x32_f16 v[114:117], v[118:121], v[106:109], v[114:117]
	v_mfma_f32_16x16x32_f16 v[40:43], v[118:121], v[110:113], v[40:43]
	v_mfma_f32_16x16x32_f16 v[70:73], v[122:125], v[106:109], v[70:73]
	global_load_dwordx4 v[106:109], v[2:3], off offset:1536
	global_load_dwordx4 v[126:129], v[4:5], off offset:1536
	global_load_dwordx4 v[134:137], v[14:15], off offset:1536
	global_load_dwordx4 v[94:97], v[10:11], off offset:1536
	global_load_dwordx4 v[162:165], v[12:13], off offset:1536
	global_load_dwordx4 v[166:169], v[8:9], off offset:1536
	global_load_dwordx4 v[190:193], v[6:7], off offset:1536
	s_waitcnt lgkmcnt(0)
	s_barrier
	v_mfma_f32_16x16x32_f16 v[48:51], v[122:125], v[110:113], v[48:51]
	ds_read_b128 v[62:65], v16 offset:49152
	ds_read_b128 v[90:93], v21 offset:16384
	s_waitcnt lgkmcnt(0)
	v_mfma_f32_16x16x32_f16 v[36:39], v[62:65], v[90:93], v[36:39]
	ds_read_b128 v[74:77], v16 offset:51200
	ds_read_b128 v[110:113], v21 offset:18432
	s_waitcnt lgkmcnt(0)
	v_mfma_f32_16x16x32_f16 v[66:69], v[62:65], v[110:113], v[66:69]
	ds_read_b128 v[118:121], v16 offset:53248
	v_mfma_f32_16x16x32_f16 v[44:47], v[74:77], v[90:93], v[44:47]
	ds_read_b128 v[122:125], v16 offset:55296
	v_mfma_f32_16x16x32_f16 v[78:81], v[74:77], v[110:113], v[78:81]
	s_waitcnt lgkmcnt(1)
	v_mfma_f32_16x16x32_f16 v[82:85], v[118:121], v[90:93], v[82:85]
	v_mfma_f32_16x16x32_f16 v[86:89], v[118:121], v[110:113], v[86:89]
	s_waitcnt lgkmcnt(0)
	v_mfma_f32_16x16x32_f16 v[28:31], v[122:125], v[90:93], v[28:31]
	ds_read_b128 v[90:93], v21 offset:20480
	v_mfma_f32_16x16x32_f16 v[32:35], v[122:125], v[110:113], v[32:35]
	ds_read_b128 v[110:113], v21 offset:22528
	s_waitcnt lgkmcnt(1)
	v_mfma_f32_16x16x32_f16 v[98:101], v[62:65], v[90:93], v[98:101]
	s_waitcnt lgkmcnt(0)
	v_mfma_f32_16x16x32_f16 v[52:55], v[62:65], v[110:113], v[52:55]
	ds_read_b128 v[62:65], v22 offset:49152
	v_mfma_f32_16x16x32_f16 v[102:105], v[74:77], v[90:93], v[102:105]
	v_mfma_f32_16x16x32_f16 v[24:27], v[74:77], v[110:113], v[24:27]
	ds_read_b128 v[74:77], v22 offset:51200
	v_mfma_f32_16x16x32_f16 v[114:117], v[118:121], v[90:93], v[114:117]
	s_waitcnt vmcnt(7)
	ds_write_b128 v17, v[58:61]
	s_waitcnt vmcnt(6)
; #define GL_LOAD(s_, kt_) if (VAR != 1) { a##s_##0 = GL_A(0, kt_); a##s_##1 = GL_A(1, kt_); a##s_##2 = GL_A(2, kt_); a##s_##3 = GL_A(3, kt_); b##s_##0 = GL_B(0, kt_); b##s_##1 = GL_B(1, kt_); b##s_##2 = GL_B(2, kt_); b##s_##3 = GL_B(3, kt_); }
; #define LDS_STORE(s_, buf_) if (VAR != 2) { LDS_ST1(sA, 0, buf_, a##s_##0) LDS_ST1(sA, 1, buf_, a##s_##1) LDS_ST1(sA, 2, buf_, a##s_##2) LDS_ST1(sA, 3, buf_, a##s_##3) LDS_ST1(sB, 0, buf_, b##s_##0) LDS_ST1(sB, 1, buf_, b##s_##1) LDS_ST1(sB, 2, buf_, b##s_##2) LDS_ST1(sB, 3, buf_, b##s_##3) }
;     ...
;   GL_LOAD(0, 0)
;   GL_LOAD(1, 1)
;   LDS_STORE(0, 0)
;   if (VAR != 4) __syncthreads();
; #pragma unroll
;   for (int kt = 0; kt < nk; kt += 2) {
;     if (kt + 2 < nk) { GL_LOAD(0, kt + 2) }
;     MMA_TILE(0)
;     LDS_STORE(1, 1)
;     if (VAR != 4) __syncthreads();
;     if (kt + 3 < nk) { GL_LOAD(1, kt + 3) }
;     MMA_TILE(1)
;     if (kt + 2 < nk) { LDS_STORE(0, 0) }
;     if (VAR != 4) __syncthreads();
	ds_write_b128 v18, v[106:109]
	v_mfma_f32_16x16x32_f16 v[40:43], v[118:121], v[110:113], v[40:43]
	ds_read_b128 v[118:121], v22 offset:53248
	s_waitcnt vmcnt(5)
	ds_write_b128 v19, v[126:129]
	v_mfma_f32_16x16x32_f16 v[70:73], v[122:125], v[90:93], v[70:73]
	ds_read_b128 v[90:93], v23 offset:16384
	v_mfma_f32_16x16x32_f16 v[48:51], v[122:125], v[110:113], v[48:51]
	ds_read_b128 v[110:113], v23 offset:18432
	s_waitcnt lgkmcnt(1)
	v_mfma_f32_16x16x32_f16 v[36:39], v[62:65], v[90:93], v[36:39]
	ds_read_b128 v[122:125], v22 offset:55296
	s_waitcnt lgkmcnt(1)
	v_mfma_f32_16x16x32_f16 v[66:69], v[62:65], v[110:113], v[66:69]
	s_waitcnt vmcnt(4)
	ds_write_b128 v20, v[134:137]
	v_mfma_f32_16x16x32_f16 v[44:47], v[74:77], v[90:93], v[44:47]
	s_waitcnt vmcnt(3)
	ds_write_b128 v17, v[94:97] offset:32768
	v_mfma_f32_16x16x32_f16 v[78:81], v[74:77], v[110:113], v[78:81]
	s_waitcnt vmcnt(2)
	ds_write_b128 v18, v[162:165] offset:32768
	v_mfma_f32_16x16x32_f16 v[82:85], v[118:121], v[90:93], v[82:85]
	s_waitcnt vmcnt(1)
	ds_write_b128 v19, v[166:169] offset:32768
	v_mfma_f32_16x16x32_f16 v[86:89], v[118:121], v[110:113], v[86:89]
	s_waitcnt vmcnt(0)
	ds_write_b128 v20, v[190:193] offset:32768
	s_waitcnt lgkmcnt(5)
	v_mfma_f32_16x16x32_f16 v[28:31], v[122:125], v[90:93], v[28:31]
	ds_read_b128 v[90:93], v23 offset:20480
	v_mfma_f32_16x16x32_f16 v[32:35], v[122:125], v[110:113], v[32:35]
	ds_read_b128 v[110:113], v23 offset:22528
	s_waitcnt lgkmcnt(1)
	v_mfma_f32_16x16x32_f16 v[98:101], v[62:65], v[90:93], v[98:101]
	s_waitcnt lgkmcnt(0)
	v_mfma_f32_16x16x32_f16 v[52:55], v[62:65], v[110:113], v[52:55]
	global_load_dwordx4 v[62:65], v[0:1], off offset:1664
	v_mfma_f32_16x16x32_f16 v[102:105], v[74:77], v[90:93], v[102:105]
	v_mfma_f32_16x16x32_f16 v[24:27], v[74:77], v[110:113], v[24:27]
	v_mfma_f32_16x16x32_f16 v[114:117], v[118:121], v[90:93], v[114:117]
	v_mfma_f32_16x16x32_f16 v[40:43], v[118:121], v[110:113], v[40:43]
	v_mfma_f32_16x16x32_f16 v[70:73], v[122:125], v[90:93], v[70:73]
	global_load_dwordx4 v[90:93], v[2:3], off offset:1664
	global_load_dwordx4 v[130:133], v[4:5], off offset:1664
	global_load_dwordx4 v[138:141], v[14:15], off offset:1664
	global_load_dwordx4 v[74:77], v[10:11], off offset:1664
	global_load_dwordx4 v[142:145], v[12:13], off offset:1664
	global_load_dwordx4 v[154:157], v[8:9], off offset:1664
	global_load_dwordx4 v[158:161], v[6:7], off offset:1664
	s_waitcnt lgkmcnt(0)
	s_barrier
	v_mfma_f32_16x16x32_f16 v[48:51], v[122:125], v[110:113], v[48:51]
	ds_read_b128 v[58:61], v16 offset:32768
	ds_read_b128 v[106:109], v21
	s_waitcnt lgkmcnt(0)
	v_mfma_f32_16x16x32_f16 v[36:39], v[58:61], v[106:109], v[36:39]
	ds_read_b128 v[94:97], v16 offset:34816
	ds_read_b128 v[110:113], v21 offset:2048
	s_waitcnt lgkmcnt(0)
	v_mfma_f32_16x16x32_f16 v[66:69], v[58:61], v[110:113], v[66:69]
	ds_read_b128 v[118:121], v16 offset:36864
	v_mfma_f32_16x16x32_f16 v[44:47], v[94:97], v[106:109], v[44:47]
	ds_read_b128 v[122:125], v16 offset:38912
	v_mfma_f32_16x16x32_f16 v[78:81], v[94:97], v[110:113], v[78:81]
	s_waitcnt lgkmcnt(1)
	v_mfma_f32_16x16x32_f16 v[82:85], v[118:121], v[106:109], v[82:85]
	v_mfma_f32_16x16x32_f16 v[86:89], v[118:121], v[110:113], v[86:89]
	s_waitcnt lgkmcnt(0)
	v_mfma_f32_16x16x32_f16 v[28:31], v[122:125], v[106:109], v[28:31]
	ds_read_b128 v[106:109], v21 offset:4096
	v_mfma_f32_16x16x32_f16 v[32:35], v[122:125], v[110:113], v[32:35]
	ds_read_b128 v[110:113], v21 offset:6144
	s_waitcnt lgkmcnt(1)
	v_mfma_f32_16x16x32_f16 v[98:101], v[58:61], v[106:109], v[98:101]
	s_waitcnt lgkmcnt(0)
	v_mfma_f32_16x16x32_f16 v[52:55], v[58:61], v[110:113], v[52:55]
	ds_read_b128 v[58:61], v22 offset:32768
	v_mfma_f32_16x16x32_f16 v[102:105], v[94:97], v[106:109], v[102:105]
	v_mfma_f32_16x16x32_f16 v[24:27], v[94:97], v[110:113], v[24:27]
	ds_read_b128 v[94:97], v22 offset:34816
	v_mfma_f32_16x16x32_f16 v[114:117], v[118:121], v[106:109], v[114:117]
	s_waitcnt vmcnt(7)
	ds_write_b128 v17, v[62:65] offset:16384
	s_waitcnt vmcnt(6)
	ds_write_b128 v18, v[90:93] offset:16384
	v_mfma_f32_16x16x32_f16 v[40:43], v[118:121], v[110:113], v[40:43]
	ds_read_b128 v[118:121], v22 offset:36864
	s_waitcnt vmcnt(5)
	ds_write_b128 v19, v[130:133] offset:16384
	v_mfma_f32_16x16x32_f16 v[70:73], v[122:125], v[106:109], v[70:73]
	ds_read_b128 v[106:109], v23
	v_mfma_f32_16x16x32_f16 v[48:51], v[122:125], v[110:113], v[48:51]
	ds_read_b128 v[110:113], v23 offset:2048
	s_waitcnt lgkmcnt(1)
	v_mfma_f32_16x16x32_f16 v[36:39], v[58:61], v[106:109], v[36:39]
	ds_read_b128 v[122:125], v22 offset:38912
	s_waitcnt lgkmcnt(1)
	v_mfma_f32_16x16x32_f16 v[66:69], v[58:61], v[110:113], v[66:69]
	s_waitcnt vmcnt(4)
	ds_write_b128 v20, v[138:141] offset:16384
	v_mfma_f32_16x16x32_f16 v[44:47], v[94:97], v[106:109], v[44:47]
	s_waitcnt vmcnt(3)
	ds_write_b128 v17, v[74:77] offset:49152
	v_mfma_f32_16x16x32_f16 v[78:81], v[94:97], v[110:113], v[78:81]
	s_waitcnt vmcnt(2)
	ds_write_b128 v18, v[142:145] offset:49152
	v_mfma_f32_16x16x32_f16 v[82:85], v[118:121], v[106:109], v[82:85]
	s_waitcnt vmcnt(1)
	ds_write_b128 v19, v[154:157] offset:49152
	v_mfma_f32_16x16x32_f16 v[86:89], v[118:121], v[110:113], v[86:89]
	s_waitcnt vmcnt(0)
	ds_write_b128 v20, v[158:161] offset:49152
	s_waitcnt lgkmcnt(5)
	v_mfma_f32_16x16x32_f16 v[28:31], v[122:125], v[106:109], v[28:31]
	ds_read_b128 v[106:109], v23 offset:4096
	v_mfma_f32_16x16x32_f16 v[32:35], v[122:125], v[110:113], v[32:35]
	ds_read_b128 v[110:113], v23 offset:6144
	s_waitcnt lgkmcnt(1)
	v_mfma_f32_16x16x32_f16 v[98:101], v[58:61], v[106:109], v[98:101]
	s_waitcnt lgkmcnt(0)
	v_mfma_f32_16x16x32_f16 v[52:55], v[58:61], v[110:113], v[52:55]
	global_load_dwordx4 v[58:61], v[0:1], off offset:1792
	v_mfma_f32_16x16x32_f16 v[102:105], v[94:97], v[106:109], v[102:105]
	v_mfma_f32_16x16x32_f16 v[24:27], v[94:97], v[110:113], v[24:27]
	v_mfma_f32_16x16x32_f16 v[114:117], v[118:121], v[106:109], v[114:117]
	v_mfma_f32_16x16x32_f16 v[40:43], v[118:121], v[110:113], v[40:43]
	v_mfma_f32_16x16x32_f16 v[70:73], v[122:125], v[106:109], v[70:73]
	global_load_dwordx4 v[106:109], v[2:3], off offset:1792
	global_load_dwordx4 v[126:129], v[4:5], off offset:1792
	global_load_dwordx4 v[134:137], v[14:15], off offset:1792
	global_load_dwordx4 v[94:97], v[10:11], off offset:1792
	global_load_dwordx4 v[162:165], v[12:13], off offset:1792
	global_load_dwordx4 v[166:169], v[8:9], off offset:1792
	global_load_dwordx4 v[190:193], v[6:7], off offset:1792
	s_waitcnt lgkmcnt(0)
	s_barrier
; #define GL_LOAD(s_, kt_) if (VAR != 1) { a##s_##0 = GL_A(0, kt_); a##s_##1 = GL_A(1, kt_); a##s_##2 = GL_A(2, kt_); a##s_##3 = GL_A(3, kt_); b##s_##0 = GL_B(0, kt_); b##s_##1 = GL_B(1, kt_); b##s_##2 = GL_B(2, kt_); b##s_##3 = GL_B(3, kt_); }
; #define LDS_STORE(s_, buf_) if (VAR != 2) { LDS_ST1(sA, 0, buf_, a##s_##0) LDS_ST1(sA, 1, buf_, a##s_##1) LDS_ST1(sA, 2, buf_, a##s_##2) LDS_ST1(sA, 3, buf_, a##s_##3) LDS_ST1(sB, 0, buf_, b##s_##0) LDS_ST1(sB, 1, buf_, b##s_##1) LDS_ST1(sB, 2, buf_, b##s_##2) LDS_ST1(sB, 3, buf_, b##s_##3) }
;     ...
;   GL_LOAD(0, 0)
;   GL_LOAD(1, 1)
;   LDS_STORE(0, 0)
;   if (VAR != 4) __syncthreads();
; #pragma unroll
;   for (int kt = 0; kt < nk; kt += 2) {
;     if (kt + 2 < nk) { GL_LOAD(0, kt + 2) }
;     MMA_TILE(0)
;     LDS_STORE(1, 1)
;     if (VAR != 4) __syncthreads();
;     if (kt + 3 < nk) { GL_LOAD(1, kt + 3) }
;     MMA_TILE(1)
;     if (kt + 2 < nk) { LDS_STORE(0, 0) }
;     if (VAR != 4) __syncthreads();
	v_mfma_f32_16x16x32_f16 v[48:51], v[122:125], v[110:113], v[48:51]
	ds_read_b128 v[62:65], v16 offset:49152
	ds_read_b128 v[90:93], v21 offset:16384
	s_waitcnt lgkmcnt(0)
	v_mfma_f32_16x16x32_f16 v[36:39], v[62:65], v[90:93], v[36:39]
	ds_read_b128 v[74:77], v16 offset:51200
	ds_read_b128 v[110:113], v21 offset:18432
	s_waitcnt lgkmcnt(0)
	v_mfma_f32_16x16x32_f16 v[66:69], v[62:65], v[110:113], v[66:69]
	ds_read_b128 v[118:121], v16 offset:53248
	v_mfma_f32_16x16x32_f16 v[44:47], v[74:77], v[90:93], v[44:47]
	ds_read_b128 v[122:125], v16 offset:55296
	v_mfma_f32_16x16x32_f16 v[78:81], v[74:77], v[110:113], v[78:81]
	s_waitcnt lgkmcnt(1)
	v_mfma_f32_16x16x32_f16 v[82:85], v[118:121], v[90:93], v[82:85]
	v_mfma_f32_16x16x32_f16 v[86:89], v[118:121], v[110:113], v[86:89]
	s_waitcnt lgkmcnt(0)
	v_mfma_f32_16x16x32_f16 v[28:31], v[122:125], v[90:93], v[28:31]
	ds_read_b128 v[90:93], v21 offset:20480
	v_mfma_f32_16x16x32_f16 v[32:35], v[122:125], v[110:113], v[32:35]
	ds_read_b128 v[110:113], v21 offset:22528
	s_waitcnt lgkmcnt(1)
	v_mfma_f32_16x16x32_f16 v[98:101], v[62:65], v[90:93], v[98:101]
	s_waitcnt lgkmcnt(0)
	v_mfma_f32_16x16x32_f16 v[52:55], v[62:65], v[110:113], v[52:55]
	ds_read_b128 v[62:65], v22 offset:49152
	v_mfma_f32_16x16x32_f16 v[102:105], v[74:77], v[90:93], v[102:105]
	v_mfma_f32_16x16x32_f16 v[24:27], v[74:77], v[110:113], v[24:27]
	ds_read_b128 v[74:77], v22 offset:51200
	v_mfma_f32_16x16x32_f16 v[114:117], v[118:121], v[90:93], v[114:117]
	s_waitcnt vmcnt(7)
	ds_write_b128 v17, v[58:61]
	s_waitcnt vmcnt(6)
	ds_write_b128 v18, v[106:109]
	v_mfma_f32_16x16x32_f16 v[40:43], v[118:121], v[110:113], v[40:43]
	ds_read_b128 v[118:121], v22 offset:53248
	s_waitcnt vmcnt(5)
	ds_write_b128 v19, v[126:129]
	v_mfma_f32_16x16x32_f16 v[70:73], v[122:125], v[90:93], v[70:73]
	ds_read_b128 v[90:93], v23 offset:16384
	v_mfma_f32_16x16x32_f16 v[48:51], v[122:125], v[110:113], v[48:51]
	ds_read_b128 v[110:113], v23 offset:18432
	s_waitcnt lgkmcnt(1)
	v_mfma_f32_16x16x32_f16 v[36:39], v[62:65], v[90:93], v[36:39]
	ds_read_b128 v[122:125], v22 offset:55296
	s_waitcnt lgkmcnt(1)
	v_mfma_f32_16x16x32_f16 v[66:69], v[62:65], v[110:113], v[66:69]
	s_waitcnt vmcnt(4)
	ds_write_b128 v20, v[134:137]
	v_mfma_f32_16x16x32_f16 v[44:47], v[74:77], v[90:93], v[44:47]
	s_waitcnt vmcnt(3)
	ds_write_b128 v17, v[94:97] offset:32768
	v_mfma_f32_16x16x32_f16 v[78:81], v[74:77], v[110:113], v[78:81]
	s_waitcnt vmcnt(2)
	ds_write_b128 v18, v[162:165] offset:32768
	v_mfma_f32_16x16x32_f16 v[82:85], v[118:121], v[90:93], v[82:85]
	s_waitcnt vmcnt(1)
	ds_write_b128 v19, v[166:169] offset:32768
	v_mfma_f32_16x16x32_f16 v[86:89], v[118:121], v[110:113], v[86:89]
	s_waitcnt vmcnt(0)
	ds_write_b128 v20, v[190:193] offset:32768
	s_waitcnt lgkmcnt(5)
	v_mfma_f32_16x16x32_f16 v[28:31], v[122:125], v[90:93], v[28:31]
	ds_read_b128 v[90:93], v23 offset:20480
	v_mfma_f32_16x16x32_f16 v[32:35], v[122:125], v[110:113], v[32:35]
	ds_read_b128 v[110:113], v23 offset:22528
	s_waitcnt lgkmcnt(1)
	v_mfma_f32_16x16x32_f16 v[98:101], v[62:65], v[90:93], v[98:101]
	s_waitcnt lgkmcnt(0)
	v_mfma_f32_16x16x32_f16 v[52:55], v[62:65], v[110:113], v[52:55]
	global_load_dwordx4 v[62:65], v[0:1], off offset:1920
	v_mfma_f32_16x16x32_f16 v[102:105], v[74:77], v[90:93], v[102:105]
	v_mfma_f32_16x16x32_f16 v[24:27], v[74:77], v[110:113], v[24:27]
	v_mfma_f32_16x16x32_f16 v[114:117], v[118:121], v[90:93], v[114:117]
	v_mfma_f32_16x16x32_f16 v[40:43], v[118:121], v[110:113], v[40:43]
	v_mfma_f32_16x16x32_f16 v[70:73], v[122:125], v[90:93], v[70:73]
	global_load_dwordx4 v[90:93], v[2:3], off offset:1920
	global_load_dwordx4 v[130:133], v[4:5], off offset:1920
	global_load_dwordx4 v[138:141], v[14:15], off offset:1920
	global_load_dwordx4 v[74:77], v[10:11], off offset:1920
	global_load_dwordx4 v[142:145], v[12:13], off offset:1920
	global_load_dwordx4 v[154:157], v[8:9], off offset:1920
	global_load_dwordx4 v[158:161], v[6:7], off offset:1920
	s_waitcnt lgkmcnt(0)
	s_barrier
	v_mfma_f32_16x16x32_f16 v[48:51], v[122:125], v[110:113], v[48:51]
	ds_read_b128 v[58:61], v16 offset:32768
	ds_read_b128 v[106:109], v21
	s_waitcnt lgkmcnt(0)
	v_mfma_f32_16x16x32_f16 v[36:39], v[58:61], v[106:109], v[36:39]
	ds_read_b128 v[94:97], v16 offset:34816
	ds_read_b128 v[110:113], v21 offset:2048
	s_waitcnt lgkmcnt(0)
	v_mfma_f32_16x16x32_f16 v[66:69], v[58:61], v[110:113], v[66:69]
	ds_read_b128 v[118:121], v16 offset:36864
	v_mfma_f32_16x16x32_f16 v[44:47], v[94:97], v[106:109], v[44:47]
	ds_read_b128 v[122:125], v16 offset:38912
	v_mfma_f32_16x16x32_f16 v[78:81], v[94:97], v[110:113], v[78:81]
	s_waitcnt lgkmcnt(1)
	v_mfma_f32_16x16x32_f16 v[82:85], v[118:121], v[106:109], v[82:85]
	v_mfma_f32_16x16x32_f16 v[86:89], v[118:121], v[110:113], v[86:89]
	s_waitcnt lgkmcnt(0)
	v_mfma_f32_16x16x32_f16 v[28:31], v[122:125], v[106:109], v[28:31]
	ds_read_b128 v[106:109], v21 offset:4096
	v_mfma_f32_16x16x32_f16 v[32:35], v[122:125], v[110:113], v[32:35]
	ds_read_b128 v[110:113], v21 offset:6144
	s_waitcnt lgkmcnt(1)
	v_mfma_f32_16x16x32_f16 v[98:101], v[58:61], v[106:109], v[98:101]
	s_waitcnt lgkmcnt(0)
	v_mfma_f32_16x16x32_f16 v[52:55], v[58:61], v[110:113], v[52:55]
	ds_read_b128 v[58:61], v22 offset:32768
	v_mfma_f32_16x16x32_f16 v[102:105], v[94:97], v[106:109], v[102:105]
	v_mfma_f32_16x16x32_f16 v[24:27], v[94:97], v[110:113], v[24:27]
	ds_read_b128 v[94:97], v22 offset:34816
	v_mfma_f32_16x16x32_f16 v[114:117], v[118:121], v[106:109], v[114:117]
	s_waitcnt vmcnt(7)
	ds_write_b128 v17, v[62:65] offset:16384
	s_waitcnt vmcnt(6)
; #define GL_LOAD(s_, kt_) if (VAR != 1) { a##s_##0 = GL_A(0, kt_); a##s_##1 = GL_A(1, kt_); a##s_##2 = GL_A(2, kt_); a##s_##3 = GL_A(3, kt_); b##s_##0 = GL_B(0, kt_); b##s_##1 = GL_B(1, kt_); b##s_##2 = GL_B(2, kt_); b##s_##3 = GL_B(3, kt_); }
; #define LDS_STORE(s_, buf_) if (VAR != 2) { LDS_ST1(sA, 0, buf_, a##s_##0) LDS_ST1(sA, 1, buf_, a##s_##1) LDS_ST1(sA, 2, buf_, a##s_##2) LDS_ST1(sA, 3, buf_, a##s_##3) LDS_ST1(sB, 0, buf_, b##s_##0) LDS_ST1(sB, 1, buf_, b##s_##1) LDS_ST1(sB, 2, buf_, b##s_##2) LDS_ST1(sB, 3, buf_, b##s_##3) }
;     ...
;   GL_LOAD(0, 0)
;   GL_LOAD(1, 1)
;   LDS_STORE(0, 0)
;   if (VAR != 4) __syncthreads();
; #pragma unroll
;   for (int kt = 0; kt < nk; kt += 2) {
;     if (kt + 2 < nk) { GL_LOAD(0, kt + 2) }
;     MMA_TILE(0)
;     LDS_STORE(1, 1)
;     if (VAR != 4) __syncthreads();
;     if (kt + 3 < nk) { GL_LOAD(1, kt + 3) }
;     MMA_TILE(1)
;     if (kt + 2 < nk) { LDS_STORE(0, 0) }
;     if (VAR != 4) __syncthreads();
	ds_write_b128 v18, v[90:93] offset:16384
	v_mfma_f32_16x16x32_f16 v[40:43], v[118:121], v[110:113], v[40:43]
	ds_read_b128 v[118:121], v22 offset:36864
	s_waitcnt vmcnt(5)
	ds_write_b128 v19, v[130:133] offset:16384
	v_mfma_f32_16x16x32_f16 v[70:73], v[122:125], v[106:109], v[70:73]
	ds_read_b128 v[106:109], v23
	v_mfma_f32_16x16x32_f16 v[48:51], v[122:125], v[110:113], v[48:51]
	ds_read_b128 v[110:113], v23 offset:2048
	s_waitcnt lgkmcnt(1)
	v_mfma_f32_16x16x32_f16 v[36:39], v[58:61], v[106:109], v[36:39]
	ds_read_b128 v[122:125], v22 offset:38912
	s_waitcnt lgkmcnt(1)
	v_mfma_f32_16x16x32_f16 v[66:69], v[58:61], v[110:113], v[66:69]
	s_waitcnt vmcnt(4)
	ds_write_b128 v20, v[138:141] offset:16384
	v_mfma_f32_16x16x32_f16 v[44:47], v[94:97], v[106:109], v[44:47]
	s_waitcnt vmcnt(3)
	ds_write_b128 v17, v[74:77] offset:49152
	v_mfma_f32_16x16x32_f16 v[78:81], v[94:97], v[110:113], v[78:81]
	s_waitcnt vmcnt(2)
	ds_write_b128 v18, v[142:145] offset:49152
	v_mfma_f32_16x16x32_f16 v[82:85], v[118:121], v[106:109], v[82:85]
	s_waitcnt vmcnt(1)
	ds_write_b128 v19, v[154:157] offset:49152
	v_mfma_f32_16x16x32_f16 v[86:89], v[118:121], v[110:113], v[86:89]
	s_waitcnt vmcnt(0)
	ds_write_b128 v20, v[158:161] offset:49152
	s_waitcnt lgkmcnt(5)
	v_mfma_f32_16x16x32_f16 v[28:31], v[122:125], v[106:109], v[28:31]
	ds_read_b128 v[106:109], v23 offset:4096
	v_mfma_f32_16x16x32_f16 v[32:35], v[122:125], v[110:113], v[32:35]
	ds_read_b128 v[110:113], v23 offset:6144
	s_waitcnt lgkmcnt(1)
	v_mfma_f32_16x16x32_f16 v[98:101], v[58:61], v[106:109], v[98:101]
	s_waitcnt lgkmcnt(0)
	v_mfma_f32_16x16x32_f16 v[52:55], v[58:61], v[110:113], v[52:55]
	global_load_dwordx4 v[58:61], v[0:1], off offset:2048
	v_mfma_f32_16x16x32_f16 v[102:105], v[94:97], v[106:109], v[102:105]
	v_mfma_f32_16x16x32_f16 v[24:27], v[94:97], v[110:113], v[24:27]
	v_mfma_f32_16x16x32_f16 v[114:117], v[118:121], v[106:109], v[114:117]
	v_mfma_f32_16x16x32_f16 v[40:43], v[118:121], v[110:113], v[40:43]
	v_mfma_f32_16x16x32_f16 v[70:73], v[122:125], v[106:109], v[70:73]
	global_load_dwordx4 v[106:109], v[2:3], off offset:2048
	global_load_dwordx4 v[126:129], v[4:5], off offset:2048
	global_load_dwordx4 v[134:137], v[14:15], off offset:2048
	global_load_dwordx4 v[94:97], v[10:11], off offset:2048
	global_load_dwordx4 v[162:165], v[12:13], off offset:2048
	global_load_dwordx4 v[166:169], v[8:9], off offset:2048
	global_load_dwordx4 v[190:193], v[6:7], off offset:2048
	s_waitcnt lgkmcnt(0)
	s_barrier
	v_mfma_f32_16x16x32_f16 v[48:51], v[122:125], v[110:113], v[48:51]
	ds_read_b128 v[62:65], v16 offset:49152
	ds_read_b128 v[90:93], v21 offset:16384
	s_waitcnt lgkmcnt(0)
	v_mfma_f32_16x16x32_f16 v[36:39], v[62:65], v[90:93], v[36:39]
	ds_read_b128 v[74:77], v16 offset:51200
	ds_read_b128 v[110:113], v21 offset:18432
	s_waitcnt lgkmcnt(0)
	v_mfma_f32_16x16x32_f16 v[66:69], v[62:65], v[110:113], v[66:69]
	ds_read_b128 v[118:121], v16 offset:53248
	v_mfma_f32_16x16x32_f16 v[44:47], v[74:77], v[90:93], v[44:47]
	ds_read_b128 v[122:125], v16 offset:55296
	v_mfma_f32_16x16x32_f16 v[78:81], v[74:77], v[110:113], v[78:81]
	s_waitcnt lgkmcnt(1)
	v_mfma_f32_16x16x32_f16 v[82:85], v[118:121], v[90:93], v[82:85]
	v_mfma_f32_16x16x32_f16 v[86:89], v[118:121], v[110:113], v[86:89]
	s_waitcnt lgkmcnt(0)
	v_mfma_f32_16x16x32_f16 v[28:31], v[122:125], v[90:93], v[28:31]
	ds_read_b128 v[90:93], v21 offset:20480
	v_mfma_f32_16x16x32_f16 v[32:35], v[122:125], v[110:113], v[32:35]
	ds_read_b128 v[110:113], v21 offset:22528
	s_waitcnt lgkmcnt(1)
	v_mfma_f32_16x16x32_f16 v[98:101], v[62:65], v[90:93], v[98:101]
	s_waitcnt lgkmcnt(0)
	v_mfma_f32_16x16x32_f16 v[52:55], v[62:65], v[110:113], v[52:55]
	ds_read_b128 v[62:65], v22 offset:49152
	v_mfma_f32_16x16x32_f16 v[102:105], v[74:77], v[90:93], v[102:105]
	v_mfma_f32_16x16x32_f16 v[24:27], v[74:77], v[110:113], v[24:27]
	ds_read_b128 v[74:77], v22 offset:51200
	v_mfma_f32_16x16x32_f16 v[114:117], v[118:121], v[90:93], v[114:117]
	s_waitcnt vmcnt(7)
	ds_write_b128 v17, v[58:61]
	s_waitcnt vmcnt(6)
	ds_write_b128 v18, v[106:109]
	v_mfma_f32_16x16x32_f16 v[40:43], v[118:121], v[110:113], v[40:43]
	ds_read_b128 v[118:121], v22 offset:53248
	s_waitcnt vmcnt(5)
	ds_write_b128 v19, v[126:129]
	v_mfma_f32_16x16x32_f16 v[70:73], v[122:125], v[90:93], v[70:73]
	ds_read_b128 v[90:93], v23 offset:16384
	v_mfma_f32_16x16x32_f16 v[48:51], v[122:125], v[110:113], v[48:51]
	ds_read_b128 v[110:113], v23 offset:18432
	s_waitcnt lgkmcnt(1)
	v_mfma_f32_16x16x32_f16 v[36:39], v[62:65], v[90:93], v[36:39]
	ds_read_b128 v[122:125], v22 offset:55296
	s_waitcnt lgkmcnt(1)
	v_mfma_f32_16x16x32_f16 v[66:69], v[62:65], v[110:113], v[66:69]
	s_waitcnt vmcnt(4)
	ds_write_b128 v20, v[134:137]
	v_mfma_f32_16x16x32_f16 v[44:47], v[74:77], v[90:93], v[44:47]
	s_waitcnt vmcnt(3)
	ds_write_b128 v17, v[94:97] offset:32768
	v_mfma_f32_16x16x32_f16 v[78:81], v[74:77], v[110:113], v[78:81]
	s_waitcnt vmcnt(2)
	ds_write_b128 v18, v[162:165] offset:32768
	v_mfma_f32_16x16x32_f16 v[82:85], v[118:121], v[90:93], v[82:85]
	s_waitcnt vmcnt(1)
	ds_write_b128 v19, v[166:169] offset:32768
	v_mfma_f32_16x16x32_f16 v[86:89], v[118:121], v[110:113], v[86:89]
	s_waitcnt vmcnt(0)
	ds_write_b128 v20, v[190:193] offset:32768
	s_waitcnt lgkmcnt(5)
	v_mfma_f32_16x16x32_f16 v[28:31], v[122:125], v[90:93], v[28:31]
	ds_read_b128 v[90:93], v23 offset:20480
	v_mfma_f32_16x16x32_f16 v[32:35], v[122:125], v[110:113], v[32:35]
	ds_read_b128 v[110:113], v23 offset:22528
	s_waitcnt lgkmcnt(1)
	v_mfma_f32_16x16x32_f16 v[98:101], v[62:65], v[90:93], v[98:101]
	s_waitcnt lgkmcnt(0)
	v_mfma_f32_16x16x32_f16 v[52:55], v[62:65], v[110:113], v[52:55]
	global_load_dwordx4 v[62:65], v[0:1], off offset:2176
	v_mfma_f32_16x16x32_f16 v[102:105], v[74:77], v[90:93], v[102:105]
	v_mfma_f32_16x16x32_f16 v[24:27], v[74:77], v[110:113], v[24:27]
	v_mfma_f32_16x16x32_f16 v[114:117], v[118:121], v[90:93], v[114:117]
	v_mfma_f32_16x16x32_f16 v[40:43], v[118:121], v[110:113], v[40:43]
	v_mfma_f32_16x16x32_f16 v[70:73], v[122:125], v[90:93], v[70:73]
	global_load_dwordx4 v[90:93], v[2:3], off offset:2176
	global_load_dwordx4 v[130:133], v[4:5], off offset:2176
	global_load_dwordx4 v[138:141], v[14:15], off offset:2176
	global_load_dwordx4 v[74:77], v[10:11], off offset:2176
	global_load_dwordx4 v[142:145], v[12:13], off offset:2176
	global_load_dwordx4 v[154:157], v[8:9], off offset:2176
	global_load_dwordx4 v[158:161], v[6:7], off offset:2176
	s_waitcnt lgkmcnt(0)
	s_barrier
; #define GL_LOAD(s_, kt_) if (VAR != 1) { a##s_##0 = GL_A(0, kt_); a##s_##1 = GL_A(1, kt_); a##s_##2 = GL_A(2, kt_); a##s_##3 = GL_A(3, kt_); b##s_##0 = GL_B(0, kt_); b##s_##1 = GL_B(1, kt_); b##s_##2 = GL_B(2, kt_); b##s_##3 = GL_B(3, kt_); }
; #define LDS_STORE(s_, buf_) if (VAR != 2) { LDS_ST1(sA, 0, buf_, a##s_##0) LDS_ST1(sA, 1, buf_, a##s_##1) LDS_ST1(sA, 2, buf_, a##s_##2) LDS_ST1(sA, 3, buf_, a##s_##3) LDS_ST1(sB, 0, buf_, b##s_##0) LDS_ST1(sB, 1, buf_, b##s_##1) LDS_ST1(sB, 2, buf_, b##s_##2) LDS_ST1(sB, 3, buf_, b##s_##3) }
;     ...
;   GL_LOAD(0, 0)
;   GL_LOAD(1, 1)
;   LDS_STORE(0, 0)
;   if (VAR != 4) __syncthreads();
; #pragma unroll
;   for (int kt = 0; kt < nk; kt += 2) {
;     if (kt + 2 < nk) { GL_LOAD(0, kt + 2) }
;     MMA_TILE(0)
;     LDS_STORE(1, 1)
;     if (VAR != 4) __syncthreads();
;     if (kt + 3 < nk) { GL_LOAD(1, kt + 3) }
;     MMA_TILE(1)
;     if (kt + 2 < nk) { LDS_STORE(0, 0) }
;     if (VAR != 4) __syncthreads();
	v_mfma_f32_16x16x32_f16 v[48:51], v[122:125], v[110:113], v[48:51]
	ds_read_b128 v[58:61], v16 offset:32768
	ds_read_b128 v[106:109], v21
	s_waitcnt lgkmcnt(0)
	v_mfma_f32_16x16x32_f16 v[36:39], v[58:61], v[106:109], v[36:39]
	ds_read_b128 v[94:97], v16 offset:34816
	ds_read_b128 v[110:113], v21 offset:2048
	s_waitcnt lgkmcnt(0)
	v_mfma_f32_16x16x32_f16 v[66:69], v[58:61], v[110:113], v[66:69]
	ds_read_b128 v[118:121], v16 offset:36864
	v_mfma_f32_16x16x32_f16 v[44:47], v[94:97], v[106:109], v[44:47]
	ds_read_b128 v[122:125], v16 offset:38912
	v_mfma_f32_16x16x32_f16 v[78:81], v[94:97], v[110:113], v[78:81]
	s_waitcnt lgkmcnt(1)
	v_mfma_f32_16x16x32_f16 v[82:85], v[118:121], v[106:109], v[82:85]
	v_mfma_f32_16x16x32_f16 v[86:89], v[118:121], v[110:113], v[86:89]
	s_waitcnt lgkmcnt(0)
	v_mfma_f32_16x16x32_f16 v[28:31], v[122:125], v[106:109], v[28:31]
	ds_read_b128 v[106:109], v21 offset:4096
	v_mfma_f32_16x16x32_f16 v[32:35], v[122:125], v[110:113], v[32:35]
	ds_read_b128 v[110:113], v21 offset:6144
	s_waitcnt lgkmcnt(1)
	v_mfma_f32_16x16x32_f16 v[98:101], v[58:61], v[106:109], v[98:101]
	s_waitcnt lgkmcnt(0)
	v_mfma_f32_16x16x32_f16 v[52:55], v[58:61], v[110:113], v[52:55]
	ds_read_b128 v[58:61], v22 offset:32768
	v_mfma_f32_16x16x32_f16 v[102:105], v[94:97], v[106:109], v[102:105]
	v_mfma_f32_16x16x32_f16 v[24:27], v[94:97], v[110:113], v[24:27]
	ds_read_b128 v[94:97], v22 offset:34816
	v_mfma_f32_16x16x32_f16 v[114:117], v[118:121], v[106:109], v[114:117]
	s_waitcnt vmcnt(7)
	ds_write_b128 v17, v[62:65] offset:16384
	s_waitcnt vmcnt(6)
	ds_write_b128 v18, v[90:93] offset:16384
	v_mfma_f32_16x16x32_f16 v[40:43], v[118:121], v[110:113], v[40:43]
	ds_read_b128 v[118:121], v22 offset:36864
	s_waitcnt vmcnt(5)
	ds_write_b128 v19, v[130:133] offset:16384
	v_mfma_f32_16x16x32_f16 v[70:73], v[122:125], v[106:109], v[70:73]
	ds_read_b128 v[106:109], v23
	v_mfma_f32_16x16x32_f16 v[48:51], v[122:125], v[110:113], v[48:51]
	ds_read_b128 v[110:113], v23 offset:2048
	s_waitcnt lgkmcnt(1)
	v_mfma_f32_16x16x32_f16 v[36:39], v[58:61], v[106:109], v[36:39]
	ds_read_b128 v[122:125], v22 offset:38912
	s_waitcnt lgkmcnt(1)
	v_mfma_f32_16x16x32_f16 v[66:69], v[58:61], v[110:113], v[66:69]
	s_waitcnt vmcnt(4)
	ds_write_b128 v20, v[138:141] offset:16384
	v_mfma_f32_16x16x32_f16 v[44:47], v[94:97], v[106:109], v[44:47]
	s_waitcnt vmcnt(3)
	ds_write_b128 v17, v[74:77] offset:49152
	v_mfma_f32_16x16x32_f16 v[78:81], v[94:97], v[110:113], v[78:81]
	s_waitcnt vmcnt(2)
	ds_write_b128 v18, v[142:145] offset:49152
	v_mfma_f32_16x16x32_f16 v[82:85], v[118:121], v[106:109], v[82:85]
	s_waitcnt vmcnt(1)
	ds_write_b128 v19, v[154:157] offset:49152
	v_mfma_f32_16x16x32_f16 v[86:89], v[118:121], v[110:113], v[86:89]
	s_waitcnt vmcnt(0)
	ds_write_b128 v20, v[158:161] offset:49152
	s_waitcnt lgkmcnt(5)
	v_mfma_f32_16x16x32_f16 v[28:31], v[122:125], v[106:109], v[28:31]
	ds_read_b128 v[106:109], v23 offset:4096
	v_mfma_f32_16x16x32_f16 v[32:35], v[122:125], v[110:113], v[32:35]
	ds_read_b128 v[110:113], v23 offset:6144
	s_waitcnt lgkmcnt(1)
	v_mfma_f32_16x16x32_f16 v[98:101], v[58:61], v[106:109], v[98:101]
	s_waitcnt lgkmcnt(0)
	v_mfma_f32_16x16x32_f16 v[52:55], v[58:61], v[110:113], v[52:55]
	global_load_dwordx4 v[58:61], v[0:1], off offset:2304
	v_mfma_f32_16x16x32_f16 v[102:105], v[94:97], v[106:109], v[102:105]
	v_mfma_f32_16x16x32_f16 v[24:27], v[94:97], v[110:113], v[24:27]
	v_mfma_f32_16x16x32_f16 v[114:117], v[118:121], v[106:109], v[114:117]
	v_mfma_f32_16x16x32_f16 v[40:43], v[118:121], v[110:113], v[40:43]
	v_mfma_f32_16x16x32_f16 v[70:73], v[122:125], v[106:109], v[70:73]
	global_load_dwordx4 v[106:109], v[2:3], off offset:2304
	global_load_dwordx4 v[126:129], v[4:5], off offset:2304
	global_load_dwordx4 v[134:137], v[14:15], off offset:2304
	global_load_dwordx4 v[94:97], v[10:11], off offset:2304
	global_load_dwordx4 v[162:165], v[12:13], off offset:2304
	global_load_dwordx4 v[166:169], v[8:9], off offset:2304
	global_load_dwordx4 v[190:193], v[6:7], off offset:2304
	s_waitcnt lgkmcnt(0)
	s_barrier
	v_mfma_f32_16x16x32_f16 v[48:51], v[122:125], v[110:113], v[48:51]
	ds_read_b128 v[62:65], v16 offset:49152
	ds_read_b128 v[90:93], v21 offset:16384
	s_waitcnt lgkmcnt(0)
	v_mfma_f32_16x16x32_f16 v[36:39], v[62:65], v[90:93], v[36:39]
	ds_read_b128 v[74:77], v16 offset:51200
	ds_read_b128 v[110:113], v21 offset:18432
	s_waitcnt lgkmcnt(0)
	v_mfma_f32_16x16x32_f16 v[66:69], v[62:65], v[110:113], v[66:69]
	ds_read_b128 v[118:121], v16 offset:53248
	v_mfma_f32_16x16x32_f16 v[44:47], v[74:77], v[90:93], v[44:47]
	ds_read_b128 v[122:125], v16 offset:55296
	v_mfma_f32_16x16x32_f16 v[78:81], v[74:77], v[110:113], v[78:81]
	s_waitcnt lgkmcnt(1)
	v_mfma_f32_16x16x32_f16 v[82:85], v[118:121], v[90:93], v[82:85]
	v_mfma_f32_16x16x32_f16 v[86:89], v[118:121], v[110:113], v[86:89]
	s_waitcnt lgkmcnt(0)
	v_mfma_f32_16x16x32_f16 v[28:31], v[122:125], v[90:93], v[28:31]
	ds_read_b128 v[90:93], v21 offset:20480
	v_mfma_f32_16x16x32_f16 v[32:35], v[122:125], v[110:113], v[32:35]
	ds_read_b128 v[110:113], v21 offset:22528
	s_waitcnt lgkmcnt(1)
	v_mfma_f32_16x16x32_f16 v[98:101], v[62:65], v[90:93], v[98:101]
	s_waitcnt lgkmcnt(0)
	v_mfma_f32_16x16x32_f16 v[52:55], v[62:65], v[110:113], v[52:55]
	ds_read_b128 v[62:65], v22 offset:49152
	v_mfma_f32_16x16x32_f16 v[102:105], v[74:77], v[90:93], v[102:105]
	v_mfma_f32_16x16x32_f16 v[24:27], v[74:77], v[110:113], v[24:27]
	ds_read_b128 v[74:77], v22 offset:51200
	v_mfma_f32_16x16x32_f16 v[114:117], v[118:121], v[90:93], v[114:117]
	s_waitcnt vmcnt(7)
	ds_write_b128 v17, v[58:61]
	s_waitcnt vmcnt(6)
; #define GL_LOAD(s_, kt_) if (VAR != 1) { a##s_##0 = GL_A(0, kt_); a##s_##1 = GL_A(1, kt_); a##s_##2 = GL_A(2, kt_); a##s_##3 = GL_A(3, kt_); b##s_##0 = GL_B(0, kt_); b##s_##1 = GL_B(1, kt_); b##s_##2 = GL_B(2, kt_); b##s_##3 = GL_B(3, kt_); }
; #define LDS_STORE(s_, buf_) if (VAR != 2) { LDS_ST1(sA, 0, buf_, a##s_##0) LDS_ST1(sA, 1, buf_, a##s_##1) LDS_ST1(sA, 2, buf_, a##s_##2) LDS_ST1(sA, 3, buf_, a##s_##3) LDS_ST1(sB, 0, buf_, b##s_##0) LDS_ST1(sB, 1, buf_, b##s_##1) LDS_ST1(sB, 2, buf_, b##s_##2) LDS_ST1(sB, 3, buf_, b##s_##3) }
;     ...
;   GL_LOAD(0, 0)
;   GL_LOAD(1, 1)
;   LDS_STORE(0, 0)
;   if (VAR != 4) __syncthreads();
; #pragma unroll
;   for (int kt = 0; kt < nk; kt += 2) {
;     if (kt + 2 < nk) { GL_LOAD(0, kt + 2) }
;     MMA_TILE(0)
;     LDS_STORE(1, 1)
;     if (VAR != 4) __syncthreads();
;     if (kt + 3 < nk) { GL_LOAD(1, kt + 3) }
;     MMA_TILE(1)
;     if (kt + 2 < nk) { LDS_STORE(0, 0) }
;     if (VAR != 4) __syncthreads();
	ds_write_b128 v18, v[106:109]
	v_mfma_f32_16x16x32_f16 v[40:43], v[118:121], v[110:113], v[40:43]
	ds_read_b128 v[118:121], v22 offset:53248
	s_waitcnt vmcnt(5)
	ds_write_b128 v19, v[126:129]
	v_mfma_f32_16x16x32_f16 v[70:73], v[122:125], v[90:93], v[70:73]
	ds_read_b128 v[90:93], v23 offset:16384
	v_mfma_f32_16x16x32_f16 v[48:51], v[122:125], v[110:113], v[48:51]
	ds_read_b128 v[110:113], v23 offset:18432
	s_waitcnt lgkmcnt(1)
	v_mfma_f32_16x16x32_f16 v[36:39], v[62:65], v[90:93], v[36:39]
	ds_read_b128 v[122:125], v22 offset:55296
	s_waitcnt lgkmcnt(1)
	v_mfma_f32_16x16x32_f16 v[66:69], v[62:65], v[110:113], v[66:69]
	s_waitcnt vmcnt(4)
	ds_write_b128 v20, v[134:137]
	v_mfma_f32_16x16x32_f16 v[44:47], v[74:77], v[90:93], v[44:47]
	s_waitcnt vmcnt(3)
	ds_write_b128 v17, v[94:97] offset:32768
	v_mfma_f32_16x16x32_f16 v[78:81], v[74:77], v[110:113], v[78:81]
	s_waitcnt vmcnt(2)
	ds_write_b128 v18, v[162:165] offset:32768
	v_mfma_f32_16x16x32_f16 v[82:85], v[118:121], v[90:93], v[82:85]
	s_waitcnt vmcnt(1)
	ds_write_b128 v19, v[166:169] offset:32768
	v_mfma_f32_16x16x32_f16 v[86:89], v[118:121], v[110:113], v[86:89]
	s_waitcnt vmcnt(0)
	ds_write_b128 v20, v[190:193] offset:32768
	s_waitcnt lgkmcnt(5)
	v_mfma_f32_16x16x32_f16 v[28:31], v[122:125], v[90:93], v[28:31]
	ds_read_b128 v[90:93], v23 offset:20480
	v_mfma_f32_16x16x32_f16 v[32:35], v[122:125], v[110:113], v[32:35]
	ds_read_b128 v[110:113], v23 offset:22528
	s_waitcnt lgkmcnt(1)
	v_mfma_f32_16x16x32_f16 v[98:101], v[62:65], v[90:93], v[98:101]
	s_waitcnt lgkmcnt(0)
	v_mfma_f32_16x16x32_f16 v[52:55], v[62:65], v[110:113], v[52:55]
	global_load_dwordx4 v[62:65], v[0:1], off offset:2432
	v_mfma_f32_16x16x32_f16 v[102:105], v[74:77], v[90:93], v[102:105]
	v_mfma_f32_16x16x32_f16 v[24:27], v[74:77], v[110:113], v[24:27]
	v_mfma_f32_16x16x32_f16 v[114:117], v[118:121], v[90:93], v[114:117]
	v_mfma_f32_16x16x32_f16 v[40:43], v[118:121], v[110:113], v[40:43]
	v_mfma_f32_16x16x32_f16 v[70:73], v[122:125], v[90:93], v[70:73]
	global_load_dwordx4 v[90:93], v[2:3], off offset:2432
	global_load_dwordx4 v[130:133], v[4:5], off offset:2432
	global_load_dwordx4 v[138:141], v[14:15], off offset:2432
	global_load_dwordx4 v[74:77], v[10:11], off offset:2432
	global_load_dwordx4 v[142:145], v[12:13], off offset:2432
	global_load_dwordx4 v[154:157], v[8:9], off offset:2432
	global_load_dwordx4 v[158:161], v[6:7], off offset:2432
	s_waitcnt lgkmcnt(0)
	s_barrier
	v_mfma_f32_16x16x32_f16 v[48:51], v[122:125], v[110:113], v[48:51]
	ds_read_b128 v[58:61], v16 offset:32768
	ds_read_b128 v[106:109], v21
	s_waitcnt lgkmcnt(0)
	v_mfma_f32_16x16x32_f16 v[36:39], v[58:61], v[106:109], v[36:39]
	ds_read_b128 v[94:97], v16 offset:34816
	ds_read_b128 v[110:113], v21 offset:2048
	s_waitcnt lgkmcnt(0)
	v_mfma_f32_16x16x32_f16 v[66:69], v[58:61], v[110:113], v[66:69]
	ds_read_b128 v[118:121], v16 offset:36864
	v_mfma_f32_16x16x32_f16 v[44:47], v[94:97], v[106:109], v[44:47]
	ds_read_b128 v[122:125], v16 offset:38912
	v_mfma_f32_16x16x32_f16 v[78:81], v[94:97], v[110:113], v[78:81]
	s_waitcnt lgkmcnt(1)
	v_mfma_f32_16x16x32_f16 v[82:85], v[118:121], v[106:109], v[82:85]
	v_mfma_f32_16x16x32_f16 v[86:89], v[118:121], v[110:113], v[86:89]
	s_waitcnt lgkmcnt(0)
	v_mfma_f32_16x16x32_f16 v[28:31], v[122:125], v[106:109], v[28:31]
	ds_read_b128 v[106:109], v21 offset:4096
	v_mfma_f32_16x16x32_f16 v[32:35], v[122:125], v[110:113], v[32:35]
	ds_read_b128 v[110:113], v21 offset:6144
	s_waitcnt lgkmcnt(1)
	v_mfma_f32_16x16x32_f16 v[98:101], v[58:61], v[106:109], v[98:101]
	s_waitcnt lgkmcnt(0)
	v_mfma_f32_16x16x32_f16 v[52:55], v[58:61], v[110:113], v[52:55]
	ds_read_b128 v[58:61], v22 offset:32768
	v_mfma_f32_16x16x32_f16 v[102:105], v[94:97], v[106:109], v[102:105]
	v_mfma_f32_16x16x32_f16 v[24:27], v[94:97], v[110:113], v[24:27]
	ds_read_b128 v[94:97], v22 offset:34816
	v_mfma_f32_16x16x32_f16 v[114:117], v[118:121], v[106:109], v[114:117]
	s_waitcnt vmcnt(7)
	ds_write_b128 v17, v[62:65] offset:16384
	s_waitcnt vmcnt(6)
	ds_write_b128 v18, v[90:93] offset:16384
	v_mfma_f32_16x16x32_f16 v[40:43], v[118:121], v[110:113], v[40:43]
	ds_read_b128 v[118:121], v22 offset:36864
	s_waitcnt vmcnt(5)
	ds_write_b128 v19, v[130:133] offset:16384
	v_mfma_f32_16x16x32_f16 v[70:73], v[122:125], v[106:109], v[70:73]
	ds_read_b128 v[106:109], v23
	v_mfma_f32_16x16x32_f16 v[48:51], v[122:125], v[110:113], v[48:51]
	ds_read_b128 v[110:113], v23 offset:2048
	s_waitcnt lgkmcnt(1)
	v_mfma_f32_16x16x32_f16 v[36:39], v[58:61], v[106:109], v[36:39]
	ds_read_b128 v[122:125], v22 offset:38912
	s_waitcnt lgkmcnt(1)
	v_mfma_f32_16x16x32_f16 v[66:69], v[58:61], v[110:113], v[66:69]
	s_waitcnt vmcnt(4)
	ds_write_b128 v20, v[138:141] offset:16384
	v_mfma_f32_16x16x32_f16 v[44:47], v[94:97], v[106:109], v[44:47]
	s_waitcnt vmcnt(3)
	ds_write_b128 v17, v[74:77] offset:49152
	v_mfma_f32_16x16x32_f16 v[78:81], v[94:97], v[110:113], v[78:81]
	s_waitcnt vmcnt(2)
	ds_write_b128 v18, v[142:145] offset:49152
	v_mfma_f32_16x16x32_f16 v[82:85], v[118:121], v[106:109], v[82:85]
	s_waitcnt vmcnt(1)
	ds_write_b128 v19, v[154:157] offset:49152
	v_mfma_f32_16x16x32_f16 v[86:89], v[118:121], v[110:113], v[86:89]
	s_waitcnt vmcnt(0)
	ds_write_b128 v20, v[158:161] offset:49152
	s_waitcnt lgkmcnt(5)
	v_mfma_f32_16x16x32_f16 v[28:31], v[122:125], v[106:109], v[28:31]
	ds_read_b128 v[106:109], v23 offset:4096
	v_mfma_f32_16x16x32_f16 v[32:35], v[122:125], v[110:113], v[32:35]
	ds_read_b128 v[110:113], v23 offset:6144
	s_waitcnt lgkmcnt(1)
	v_mfma_f32_16x16x32_f16 v[98:101], v[58:61], v[106:109], v[98:101]
	s_waitcnt lgkmcnt(0)
	v_mfma_f32_16x16x32_f16 v[52:55], v[58:61], v[110:113], v[52:55]
	global_load_dwordx4 v[58:61], v[0:1], off offset:2560
	v_mfma_f32_16x16x32_f16 v[102:105], v[94:97], v[106:109], v[102:105]
	v_mfma_f32_16x16x32_f16 v[24:27], v[94:97], v[110:113], v[24:27]
	v_mfma_f32_16x16x32_f16 v[114:117], v[118:121], v[106:109], v[114:117]
	v_mfma_f32_16x16x32_f16 v[40:43], v[118:121], v[110:113], v[40:43]
	v_mfma_f32_16x16x32_f16 v[70:73], v[122:125], v[106:109], v[70:73]
	global_load_dwordx4 v[106:109], v[2:3], off offset:2560
	global_load_dwordx4 v[126:129], v[4:5], off offset:2560
	global_load_dwordx4 v[134:137], v[14:15], off offset:2560
	global_load_dwordx4 v[94:97], v[10:11], off offset:2560
	global_load_dwordx4 v[162:165], v[12:13], off offset:2560
	global_load_dwordx4 v[166:169], v[8:9], off offset:2560
	global_load_dwordx4 v[190:193], v[6:7], off offset:2560
	s_waitcnt lgkmcnt(0)
	s_barrier
; #define GL_LOAD(s_, kt_) if (VAR != 1) { a##s_##0 = GL_A(0, kt_); a##s_##1 = GL_A(1, kt_); a##s_##2 = GL_A(2, kt_); a##s_##3 = GL_A(3, kt_); b##s_##0 = GL_B(0, kt_); b##s_##1 = GL_B(1, kt_); b##s_##2 = GL_B(2, kt_); b##s_##3 = GL_B(3, kt_); }
; #define LDS_STORE(s_, buf_) if (VAR != 2) { LDS_ST1(sA, 0, buf_, a##s_##0) LDS_ST1(sA, 1, buf_, a##s_##1) LDS_ST1(sA, 2, buf_, a##s_##2) LDS_ST1(sA, 3, buf_, a##s_##3) LDS_ST1(sB, 0, buf_, b##s_##0) LDS_ST1(sB, 1, buf_, b##s_##1) LDS_ST1(sB, 2, buf_, b##s_##2) LDS_ST1(sB, 3, buf_, b##s_##3) }
;     ...
;   GL_LOAD(0, 0)
;   GL_LOAD(1, 1)
;   LDS_STORE(0, 0)
;   if (VAR != 4) __syncthreads();
; #pragma unroll
;   for (int kt = 0; kt < nk; kt += 2) {
;     if (kt + 2 < nk) { GL_LOAD(0, kt + 2) }
;     MMA_TILE(0)
;     LDS_STORE(1, 1)
;     if (VAR != 4) __syncthreads();
;     if (kt + 3 < nk) { GL_LOAD(1, kt + 3) }
;     MMA_TILE(1)
;     if (kt + 2 < nk) { LDS_STORE(0, 0) }
;     if (VAR != 4) __syncthreads();
	v_mfma_f32_16x16x32_f16 v[48:51], v[122:125], v[110:113], v[48:51]
	ds_read_b128 v[62:65], v16 offset:49152
	ds_read_b128 v[90:93], v21 offset:16384
	s_waitcnt lgkmcnt(0)
	v_mfma_f32_16x16x32_f16 v[36:39], v[62:65], v[90:93], v[36:39]
	ds_read_b128 v[74:77], v16 offset:51200
	ds_read_b128 v[110:113], v21 offset:18432
	s_waitcnt lgkmcnt(0)
	v_mfma_f32_16x16x32_f16 v[66:69], v[62:65], v[110:113], v[66:69]
	ds_read_b128 v[118:121], v16 offset:53248
	v_mfma_f32_16x16x32_f16 v[44:47], v[74:77], v[90:93], v[44:47]
	ds_read_b128 v[122:125], v16 offset:55296
	v_mfma_f32_16x16x32_f16 v[78:81], v[74:77], v[110:113], v[78:81]
	s_waitcnt lgkmcnt(1)
	v_mfma_f32_16x16x32_f16 v[82:85], v[118:121], v[90:93], v[82:85]
	v_mfma_f32_16x16x32_f16 v[86:89], v[118:121], v[110:113], v[86:89]
	s_waitcnt lgkmcnt(0)
	v_mfma_f32_16x16x32_f16 v[28:31], v[122:125], v[90:93], v[28:31]
	ds_read_b128 v[90:93], v21 offset:20480
	v_mfma_f32_16x16x32_f16 v[32:35], v[122:125], v[110:113], v[32:35]
	ds_read_b128 v[110:113], v21 offset:22528
	s_waitcnt lgkmcnt(1)
	v_mfma_f32_16x16x32_f16 v[98:101], v[62:65], v[90:93], v[98:101]
	s_waitcnt lgkmcnt(0)
	v_mfma_f32_16x16x32_f16 v[52:55], v[62:65], v[110:113], v[52:55]
	ds_read_b128 v[62:65], v22 offset:49152
	v_mfma_f32_16x16x32_f16 v[102:105], v[74:77], v[90:93], v[102:105]
	v_mfma_f32_16x16x32_f16 v[24:27], v[74:77], v[110:113], v[24:27]
	ds_read_b128 v[74:77], v22 offset:51200
	v_mfma_f32_16x16x32_f16 v[114:117], v[118:121], v[90:93], v[114:117]
	s_waitcnt vmcnt(7)
	ds_write_b128 v17, v[58:61]
	s_waitcnt vmcnt(6)
	ds_write_b128 v18, v[106:109]
	v_mfma_f32_16x16x32_f16 v[40:43], v[118:121], v[110:113], v[40:43]
	ds_read_b128 v[118:121], v22 offset:53248
	s_waitcnt vmcnt(5)
	ds_write_b128 v19, v[126:129]
	v_mfma_f32_16x16x32_f16 v[70:73], v[122:125], v[90:93], v[70:73]
	ds_read_b128 v[90:93], v23 offset:16384
	v_mfma_f32_16x16x32_f16 v[48:51], v[122:125], v[110:113], v[48:51]
	ds_read_b128 v[110:113], v23 offset:18432
	s_waitcnt lgkmcnt(1)
	v_mfma_f32_16x16x32_f16 v[36:39], v[62:65], v[90:93], v[36:39]
	ds_read_b128 v[122:125], v22 offset:55296
	s_waitcnt lgkmcnt(1)
	v_mfma_f32_16x16x32_f16 v[66:69], v[62:65], v[110:113], v[66:69]
	s_waitcnt vmcnt(4)
	ds_write_b128 v20, v[134:137]
	v_mfma_f32_16x16x32_f16 v[44:47], v[74:77], v[90:93], v[44:47]
	s_waitcnt vmcnt(3)
	ds_write_b128 v17, v[94:97] offset:32768
	v_mfma_f32_16x16x32_f16 v[78:81], v[74:77], v[110:113], v[78:81]
	s_waitcnt vmcnt(2)
	ds_write_b128 v18, v[162:165] offset:32768
	v_mfma_f32_16x16x32_f16 v[82:85], v[118:121], v[90:93], v[82:85]
	s_waitcnt vmcnt(1)
	ds_write_b128 v19, v[166:169] offset:32768
	v_mfma_f32_16x16x32_f16 v[86:89], v[118:121], v[110:113], v[86:89]
	s_waitcnt vmcnt(0)
	ds_write_b128 v20, v[190:193] offset:32768
	s_waitcnt lgkmcnt(5)
	v_mfma_f32_16x16x32_f16 v[28:31], v[122:125], v[90:93], v[28:31]
	ds_read_b128 v[90:93], v23 offset:20480
	v_mfma_f32_16x16x32_f16 v[32:35], v[122:125], v[110:113], v[32:35]
	ds_read_b128 v[110:113], v23 offset:22528
	s_waitcnt lgkmcnt(1)
	v_mfma_f32_16x16x32_f16 v[98:101], v[62:65], v[90:93], v[98:101]
	s_waitcnt lgkmcnt(0)
	v_mfma_f32_16x16x32_f16 v[52:55], v[62:65], v[110:113], v[52:55]
	global_load_dwordx4 v[62:65], v[0:1], off offset:2688
	v_mfma_f32_16x16x32_f16 v[102:105], v[74:77], v[90:93], v[102:105]
	v_mfma_f32_16x16x32_f16 v[24:27], v[74:77], v[110:113], v[24:27]
	v_mfma_f32_16x16x32_f16 v[114:117], v[118:121], v[90:93], v[114:117]
	v_mfma_f32_16x16x32_f16 v[40:43], v[118:121], v[110:113], v[40:43]
	v_mfma_f32_16x16x32_f16 v[70:73], v[122:125], v[90:93], v[70:73]
	global_load_dwordx4 v[90:93], v[2:3], off offset:2688
	global_load_dwordx4 v[130:133], v[4:5], off offset:2688
	global_load_dwordx4 v[138:141], v[14:15], off offset:2688
	global_load_dwordx4 v[74:77], v[10:11], off offset:2688
	global_load_dwordx4 v[142:145], v[12:13], off offset:2688
	global_load_dwordx4 v[154:157], v[8:9], off offset:2688
	global_load_dwordx4 v[158:161], v[6:7], off offset:2688
	s_waitcnt lgkmcnt(0)
	s_barrier
	v_mfma_f32_16x16x32_f16 v[48:51], v[122:125], v[110:113], v[48:51]
	ds_read_b128 v[58:61], v16 offset:32768
	ds_read_b128 v[106:109], v21
	s_waitcnt lgkmcnt(0)
	v_mfma_f32_16x16x32_f16 v[36:39], v[58:61], v[106:109], v[36:39]
	ds_read_b128 v[94:97], v16 offset:34816
	ds_read_b128 v[110:113], v21 offset:2048
	s_waitcnt lgkmcnt(0)
	v_mfma_f32_16x16x32_f16 v[66:69], v[58:61], v[110:113], v[66:69]
	ds_read_b128 v[118:121], v16 offset:36864
	v_mfma_f32_16x16x32_f16 v[44:47], v[94:97], v[106:109], v[44:47]
	ds_read_b128 v[122:125], v16 offset:38912
	v_mfma_f32_16x16x32_f16 v[78:81], v[94:97], v[110:113], v[78:81]
	s_waitcnt lgkmcnt(1)
	v_mfma_f32_16x16x32_f16 v[82:85], v[118:121], v[106:109], v[82:85]
	v_mfma_f32_16x16x32_f16 v[86:89], v[118:121], v[110:113], v[86:89]
	s_waitcnt lgkmcnt(0)
	v_mfma_f32_16x16x32_f16 v[28:31], v[122:125], v[106:109], v[28:31]
	ds_read_b128 v[106:109], v21 offset:4096
	v_mfma_f32_16x16x32_f16 v[32:35], v[122:125], v[110:113], v[32:35]
	ds_read_b128 v[110:113], v21 offset:6144
	s_waitcnt lgkmcnt(1)
	v_mfma_f32_16x16x32_f16 v[98:101], v[58:61], v[106:109], v[98:101]
	s_waitcnt lgkmcnt(0)
	v_mfma_f32_16x16x32_f16 v[52:55], v[58:61], v[110:113], v[52:55]
	ds_read_b128 v[58:61], v22 offset:32768
	v_mfma_f32_16x16x32_f16 v[102:105], v[94:97], v[106:109], v[102:105]
	v_mfma_f32_16x16x32_f16 v[24:27], v[94:97], v[110:113], v[24:27]
	ds_read_b128 v[94:97], v22 offset:34816
	v_mfma_f32_16x16x32_f16 v[114:117], v[118:121], v[106:109], v[114:117]
	s_waitcnt vmcnt(7)
	ds_write_b128 v17, v[62:65] offset:16384
	s_waitcnt vmcnt(6)
; #define GL_LOAD(s_, kt_) if (VAR != 1) { a##s_##0 = GL_A(0, kt_); a##s_##1 = GL_A(1, kt_); a##s_##2 = GL_A(2, kt_); a##s_##3 = GL_A(3, kt_); b##s_##0 = GL_B(0, kt_); b##s_##1 = GL_B(1, kt_); b##s_##2 = GL_B(2, kt_); b##s_##3 = GL_B(3, kt_); }
; #define LDS_STORE(s_, buf_) if (VAR != 2) { LDS_ST1(sA, 0, buf_, a##s_##0) LDS_ST1(sA, 1, buf_, a##s_##1) LDS_ST1(sA, 2, buf_, a##s_##2) LDS_ST1(sA, 3, buf_, a##s_##3) LDS_ST1(sB, 0, buf_, b##s_##0) LDS_ST1(sB, 1, buf_, b##s_##1) LDS_ST1(sB, 2, buf_, b##s_##2) LDS_ST1(sB, 3, buf_, b##s_##3) }
;     ...
;   GL_LOAD(0, 0)
;   GL_LOAD(1, 1)
;   LDS_STORE(0, 0)
;   if (VAR != 4) __syncthreads();
; #pragma unroll
;   for (int kt = 0; kt < nk; kt += 2) {
;     if (kt + 2 < nk) { GL_LOAD(0, kt + 2) }
;     MMA_TILE(0)
;     LDS_STORE(1, 1)
;     if (VAR != 4) __syncthreads();
;     if (kt + 3 < nk) { GL_LOAD(1, kt + 3) }
;     MMA_TILE(1)
;     if (kt + 2 < nk) { LDS_STORE(0, 0) }
;     if (VAR != 4) __syncthreads();
	ds_write_b128 v18, v[90:93] offset:16384
	v_mfma_f32_16x16x32_f16 v[40:43], v[118:121], v[110:113], v[40:43]
	ds_read_b128 v[118:121], v22 offset:36864
	s_waitcnt vmcnt(5)
	ds_write_b128 v19, v[130:133] offset:16384
	v_mfma_f32_16x16x32_f16 v[70:73], v[122:125], v[106:109], v[70:73]
	ds_read_b128 v[106:109], v23
	v_mfma_f32_16x16x32_f16 v[48:51], v[122:125], v[110:113], v[48:51]
	ds_read_b128 v[110:113], v23 offset:2048
	s_waitcnt lgkmcnt(1)
	v_mfma_f32_16x16x32_f16 v[36:39], v[58:61], v[106:109], v[36:39]
	ds_read_b128 v[122:125], v22 offset:38912
	s_waitcnt lgkmcnt(1)
	v_mfma_f32_16x16x32_f16 v[66:69], v[58:61], v[110:113], v[66:69]
	s_waitcnt vmcnt(4)
	ds_write_b128 v20, v[138:141] offset:16384
	v_mfma_f32_16x16x32_f16 v[44:47], v[94:97], v[106:109], v[44:47]
	s_waitcnt vmcnt(3)
	ds_write_b128 v17, v[74:77] offset:49152
	v_mfma_f32_16x16x32_f16 v[78:81], v[94:97], v[110:113], v[78:81]
	s_waitcnt vmcnt(2)
	ds_write_b128 v18, v[142:145] offset:49152
	v_mfma_f32_16x16x32_f16 v[82:85], v[118:121], v[106:109], v[82:85]
	s_waitcnt vmcnt(1)
	ds_write_b128 v19, v[154:157] offset:49152
	v_mfma_f32_16x16x32_f16 v[86:89], v[118:121], v[110:113], v[86:89]
	s_waitcnt vmcnt(0)
	ds_write_b128 v20, v[158:161] offset:49152
	s_waitcnt lgkmcnt(5)
	v_mfma_f32_16x16x32_f16 v[28:31], v[122:125], v[106:109], v[28:31]
	ds_read_b128 v[106:109], v23 offset:4096
	v_mfma_f32_16x16x32_f16 v[32:35], v[122:125], v[110:113], v[32:35]
	ds_read_b128 v[110:113], v23 offset:6144
	s_waitcnt lgkmcnt(1)
	v_mfma_f32_16x16x32_f16 v[98:101], v[58:61], v[106:109], v[98:101]
	s_waitcnt lgkmcnt(0)
	v_mfma_f32_16x16x32_f16 v[52:55], v[58:61], v[110:113], v[52:55]
	global_load_dwordx4 v[58:61], v[0:1], off offset:2816
	v_mfma_f32_16x16x32_f16 v[102:105], v[94:97], v[106:109], v[102:105]
	v_mfma_f32_16x16x32_f16 v[24:27], v[94:97], v[110:113], v[24:27]
	v_mfma_f32_16x16x32_f16 v[114:117], v[118:121], v[106:109], v[114:117]
	v_mfma_f32_16x16x32_f16 v[40:43], v[118:121], v[110:113], v[40:43]
	v_mfma_f32_16x16x32_f16 v[70:73], v[122:125], v[106:109], v[70:73]
	global_load_dwordx4 v[106:109], v[2:3], off offset:2816
	global_load_dwordx4 v[126:129], v[4:5], off offset:2816
	global_load_dwordx4 v[134:137], v[14:15], off offset:2816
	global_load_dwordx4 v[94:97], v[10:11], off offset:2816
	global_load_dwordx4 v[162:165], v[12:13], off offset:2816
	global_load_dwordx4 v[166:169], v[8:9], off offset:2816
	global_load_dwordx4 v[190:193], v[6:7], off offset:2816
	s_waitcnt lgkmcnt(0)
	s_barrier
	v_mfma_f32_16x16x32_f16 v[48:51], v[122:125], v[110:113], v[48:51]
	ds_read_b128 v[62:65], v16 offset:49152
	ds_read_b128 v[90:93], v21 offset:16384
	s_waitcnt lgkmcnt(0)
	v_mfma_f32_16x16x32_f16 v[36:39], v[62:65], v[90:93], v[36:39]
	ds_read_b128 v[74:77], v16 offset:51200
	ds_read_b128 v[110:113], v21 offset:18432
	s_waitcnt lgkmcnt(0)
	v_mfma_f32_16x16x32_f16 v[66:69], v[62:65], v[110:113], v[66:69]
	ds_read_b128 v[118:121], v16 offset:53248
	v_mfma_f32_16x16x32_f16 v[44:47], v[74:77], v[90:93], v[44:47]
	ds_read_b128 v[122:125], v16 offset:55296
	v_mfma_f32_16x16x32_f16 v[78:81], v[74:77], v[110:113], v[78:81]
	s_waitcnt lgkmcnt(1)
	v_mfma_f32_16x16x32_f16 v[82:85], v[118:121], v[90:93], v[82:85]
	v_mfma_f32_16x16x32_f16 v[86:89], v[118:121], v[110:113], v[86:89]
	s_waitcnt lgkmcnt(0)
	v_mfma_f32_16x16x32_f16 v[28:31], v[122:125], v[90:93], v[28:31]
	ds_read_b128 v[90:93], v21 offset:20480
	v_mfma_f32_16x16x32_f16 v[32:35], v[122:125], v[110:113], v[32:35]
	ds_read_b128 v[110:113], v21 offset:22528
	s_waitcnt lgkmcnt(1)
	v_mfma_f32_16x16x32_f16 v[98:101], v[62:65], v[90:93], v[98:101]
	s_waitcnt lgkmcnt(0)
	v_mfma_f32_16x16x32_f16 v[52:55], v[62:65], v[110:113], v[52:55]
	ds_read_b128 v[62:65], v22 offset:49152
	v_mfma_f32_16x16x32_f16 v[102:105], v[74:77], v[90:93], v[102:105]
	v_mfma_f32_16x16x32_f16 v[24:27], v[74:77], v[110:113], v[24:27]
	ds_read_b128 v[74:77], v22 offset:51200
	v_mfma_f32_16x16x32_f16 v[114:117], v[118:121], v[90:93], v[114:117]
	s_waitcnt vmcnt(7)
	ds_write_b128 v17, v[58:61]
	s_waitcnt vmcnt(6)
	ds_write_b128 v18, v[106:109]
	v_mfma_f32_16x16x32_f16 v[40:43], v[118:121], v[110:113], v[40:43]
	ds_read_b128 v[118:121], v22 offset:53248
	s_waitcnt vmcnt(5)
	ds_write_b128 v19, v[126:129]
	v_mfma_f32_16x16x32_f16 v[70:73], v[122:125], v[90:93], v[70:73]
	ds_read_b128 v[90:93], v23 offset:16384
	v_mfma_f32_16x16x32_f16 v[48:51], v[122:125], v[110:113], v[48:51]
	ds_read_b128 v[110:113], v23 offset:18432
	s_waitcnt lgkmcnt(1)
	v_mfma_f32_16x16x32_f16 v[36:39], v[62:65], v[90:93], v[36:39]
	ds_read_b128 v[122:125], v22 offset:55296
	s_waitcnt lgkmcnt(1)
	v_mfma_f32_16x16x32_f16 v[66:69], v[62:65], v[110:113], v[66:69]
	s_waitcnt vmcnt(4)
	ds_write_b128 v20, v[134:137]
	v_mfma_f32_16x16x32_f16 v[44:47], v[74:77], v[90:93], v[44:47]
	s_waitcnt vmcnt(3)
	ds_write_b128 v17, v[94:97] offset:32768
	v_mfma_f32_16x16x32_f16 v[78:81], v[74:77], v[110:113], v[78:81]
	s_waitcnt vmcnt(2)
	ds_write_b128 v18, v[162:165] offset:32768
	v_mfma_f32_16x16x32_f16 v[82:85], v[118:121], v[90:93], v[82:85]
	s_waitcnt vmcnt(1)
	ds_write_b128 v19, v[166:169] offset:32768
	v_mfma_f32_16x16x32_f16 v[86:89], v[118:121], v[110:113], v[86:89]
	s_waitcnt vmcnt(0)
	ds_write_b128 v20, v[190:193] offset:32768
	s_waitcnt lgkmcnt(5)
	v_mfma_f32_16x16x32_f16 v[28:31], v[122:125], v[90:93], v[28:31]
	ds_read_b128 v[90:93], v23 offset:20480
	v_mfma_f32_16x16x32_f16 v[32:35], v[122:125], v[110:113], v[32:35]
	ds_read_b128 v[110:113], v23 offset:22528
	s_waitcnt lgkmcnt(1)
	v_mfma_f32_16x16x32_f16 v[98:101], v[62:65], v[90:93], v[98:101]
	s_waitcnt lgkmcnt(0)
	v_mfma_f32_16x16x32_f16 v[52:55], v[62:65], v[110:113], v[52:55]
	global_load_dwordx4 v[62:65], v[0:1], off offset:2944
	v_mfma_f32_16x16x32_f16 v[102:105], v[74:77], v[90:93], v[102:105]
	v_mfma_f32_16x16x32_f16 v[24:27], v[74:77], v[110:113], v[24:27]
	v_mfma_f32_16x16x32_f16 v[114:117], v[118:121], v[90:93], v[114:117]
	v_mfma_f32_16x16x32_f16 v[40:43], v[118:121], v[110:113], v[40:43]
	v_mfma_f32_16x16x32_f16 v[70:73], v[122:125], v[90:93], v[70:73]
	global_load_dwordx4 v[90:93], v[2:3], off offset:2944
	global_load_dwordx4 v[130:133], v[4:5], off offset:2944
	global_load_dwordx4 v[138:141], v[14:15], off offset:2944
	global_load_dwordx4 v[74:77], v[10:11], off offset:2944
	global_load_dwordx4 v[142:145], v[12:13], off offset:2944
	global_load_dwordx4 v[154:157], v[8:9], off offset:2944
	global_load_dwordx4 v[158:161], v[6:7], off offset:2944
	s_waitcnt lgkmcnt(0)
	s_barrier
; #define GL_LOAD(s_, kt_) if (VAR != 1) { a##s_##0 = GL_A(0, kt_); a##s_##1 = GL_A(1, kt_); a##s_##2 = GL_A(2, kt_); a##s_##3 = GL_A(3, kt_); b##s_##0 = GL_B(0, kt_); b##s_##1 = GL_B(1, kt_); b##s_##2 = GL_B(2, kt_); b##s_##3 = GL_B(3, kt_); }
; #define LDS_STORE(s_, buf_) if (VAR != 2) { LDS_ST1(sA, 0, buf_, a##s_##0) LDS_ST1(sA, 1, buf_, a##s_##1) LDS_ST1(sA, 2, buf_, a##s_##2) LDS_ST1(sA, 3, buf_, a##s_##3) LDS_ST1(sB, 0, buf_, b##s_##0) LDS_ST1(sB, 1, buf_, b##s_##1) LDS_ST1(sB, 2, buf_, b##s_##2) LDS_ST1(sB, 3, buf_, b##s_##3) }
;     ...
;   GL_LOAD(0, 0)
;   GL_LOAD(1, 1)
;   LDS_STORE(0, 0)
;   if (VAR != 4) __syncthreads();
; #pragma unroll
;   for (int kt = 0; kt < nk; kt += 2) {
;     if (kt + 2 < nk) { GL_LOAD(0, kt + 2) }
;     MMA_TILE(0)
;     LDS_STORE(1, 1)
;     if (VAR != 4) __syncthreads();
;     if (kt + 3 < nk) { GL_LOAD(1, kt + 3) }
;     MMA_TILE(1)
;     if (kt + 2 < nk) { LDS_STORE(0, 0) }
;     if (VAR != 4) __syncthreads();
	v_mfma_f32_16x16x32_f16 v[48:51], v[122:125], v[110:113], v[48:51]
	ds_read_b128 v[58:61], v16 offset:32768
	ds_read_b128 v[106:109], v21
	s_waitcnt lgkmcnt(0)
	v_mfma_f32_16x16x32_f16 v[36:39], v[58:61], v[106:109], v[36:39]
	ds_read_b128 v[94:97], v16 offset:34816
	ds_read_b128 v[110:113], v21 offset:2048
	s_waitcnt lgkmcnt(0)
	v_mfma_f32_16x16x32_f16 v[66:69], v[58:61], v[110:113], v[66:69]
	ds_read_b128 v[118:121], v16 offset:36864
	v_mfma_f32_16x16x32_f16 v[44:47], v[94:97], v[106:109], v[44:47]
	ds_read_b128 v[122:125], v16 offset:38912
	v_mfma_f32_16x16x32_f16 v[78:81], v[94:97], v[110:113], v[78:81]
	s_waitcnt lgkmcnt(1)
	v_mfma_f32_16x16x32_f16 v[82:85], v[118:121], v[106:109], v[82:85]
	v_mfma_f32_16x16x32_f16 v[86:89], v[118:121], v[110:113], v[86:89]
	s_waitcnt lgkmcnt(0)
	v_mfma_f32_16x16x32_f16 v[28:31], v[122:125], v[106:109], v[28:31]
	ds_read_b128 v[106:109], v21 offset:4096
	v_mfma_f32_16x16x32_f16 v[32:35], v[122:125], v[110:113], v[32:35]
	ds_read_b128 v[110:113], v21 offset:6144
	s_waitcnt lgkmcnt(1)
	v_mfma_f32_16x16x32_f16 v[98:101], v[58:61], v[106:109], v[98:101]
	s_waitcnt lgkmcnt(0)
	v_mfma_f32_16x16x32_f16 v[52:55], v[58:61], v[110:113], v[52:55]
	ds_read_b128 v[58:61], v22 offset:32768
	v_mfma_f32_16x16x32_f16 v[102:105], v[94:97], v[106:109], v[102:105]
	v_mfma_f32_16x16x32_f16 v[24:27], v[94:97], v[110:113], v[24:27]
	ds_read_b128 v[94:97], v22 offset:34816
	v_mfma_f32_16x16x32_f16 v[114:117], v[118:121], v[106:109], v[114:117]
	s_waitcnt vmcnt(7)
	ds_write_b128 v17, v[62:65] offset:16384
	s_waitcnt vmcnt(6)
	ds_write_b128 v18, v[90:93] offset:16384
	v_mfma_f32_16x16x32_f16 v[40:43], v[118:121], v[110:113], v[40:43]
	ds_read_b128 v[118:121], v22 offset:36864
	s_waitcnt vmcnt(5)
	ds_write_b128 v19, v[130:133] offset:16384
	v_mfma_f32_16x16x32_f16 v[70:73], v[122:125], v[106:109], v[70:73]
	ds_read_b128 v[106:109], v23
	v_mfma_f32_16x16x32_f16 v[48:51], v[122:125], v[110:113], v[48:51]
	ds_read_b128 v[110:113], v23 offset:2048
	s_waitcnt lgkmcnt(1)
	v_mfma_f32_16x16x32_f16 v[36:39], v[58:61], v[106:109], v[36:39]
	ds_read_b128 v[122:125], v22 offset:38912
	s_waitcnt lgkmcnt(1)
	v_mfma_f32_16x16x32_f16 v[66:69], v[58:61], v[110:113], v[66:69]
	s_waitcnt vmcnt(4)
	ds_write_b128 v20, v[138:141] offset:16384
	v_mfma_f32_16x16x32_f16 v[44:47], v[94:97], v[106:109], v[44:47]
	s_waitcnt vmcnt(3)
	ds_write_b128 v17, v[74:77] offset:49152
	v_mfma_f32_16x16x32_f16 v[78:81], v[94:97], v[110:113], v[78:81]
	s_waitcnt vmcnt(2)
	ds_write_b128 v18, v[142:145] offset:49152
	v_mfma_f32_16x16x32_f16 v[82:85], v[118:121], v[106:109], v[82:85]
	s_waitcnt vmcnt(1)
	ds_write_b128 v19, v[154:157] offset:49152
	v_mfma_f32_16x16x32_f16 v[86:89], v[118:121], v[110:113], v[86:89]
	s_waitcnt vmcnt(0)
	ds_write_b128 v20, v[158:161] offset:49152
	s_waitcnt lgkmcnt(5)
	v_mfma_f32_16x16x32_f16 v[28:31], v[122:125], v[106:109], v[28:31]
	ds_read_b128 v[106:109], v23 offset:4096
	v_mfma_f32_16x16x32_f16 v[32:35], v[122:125], v[110:113], v[32:35]
	ds_read_b128 v[110:113], v23 offset:6144
	s_waitcnt lgkmcnt(1)
	v_mfma_f32_16x16x32_f16 v[98:101], v[58:61], v[106:109], v[98:101]
	s_waitcnt lgkmcnt(0)
	v_mfma_f32_16x16x32_f16 v[52:55], v[58:61], v[110:113], v[52:55]
	global_load_dwordx4 v[58:61], v[0:1], off offset:3072
	v_mfma_f32_16x16x32_f16 v[102:105], v[94:97], v[106:109], v[102:105]
	v_mfma_f32_16x16x32_f16 v[24:27], v[94:97], v[110:113], v[24:27]
	v_mfma_f32_16x16x32_f16 v[114:117], v[118:121], v[106:109], v[114:117]
	v_mfma_f32_16x16x32_f16 v[40:43], v[118:121], v[110:113], v[40:43]
	v_mfma_f32_16x16x32_f16 v[70:73], v[122:125], v[106:109], v[70:73]
	global_load_dwordx4 v[106:109], v[2:3], off offset:3072
	global_load_dwordx4 v[126:129], v[4:5], off offset:3072
	global_load_dwordx4 v[134:137], v[14:15], off offset:3072
	global_load_dwordx4 v[94:97], v[10:11], off offset:3072
	global_load_dwordx4 v[162:165], v[12:13], off offset:3072
	global_load_dwordx4 v[166:169], v[8:9], off offset:3072
	global_load_dwordx4 v[190:193], v[6:7], off offset:3072
	s_waitcnt lgkmcnt(0)
	s_barrier
	v_mfma_f32_16x16x32_f16 v[48:51], v[122:125], v[110:113], v[48:51]
	ds_read_b128 v[62:65], v16 offset:49152
	ds_read_b128 v[90:93], v21 offset:16384
	s_waitcnt lgkmcnt(0)
	v_mfma_f32_16x16x32_f16 v[36:39], v[62:65], v[90:93], v[36:39]
	ds_read_b128 v[74:77], v16 offset:51200
	ds_read_b128 v[110:113], v21 offset:18432
	s_waitcnt lgkmcnt(0)
	v_mfma_f32_16x16x32_f16 v[66:69], v[62:65], v[110:113], v[66:69]
	ds_read_b128 v[118:121], v16 offset:53248
	v_mfma_f32_16x16x32_f16 v[44:47], v[74:77], v[90:93], v[44:47]
	ds_read_b128 v[122:125], v16 offset:55296
	v_mfma_f32_16x16x32_f16 v[78:81], v[74:77], v[110:113], v[78:81]
	s_waitcnt lgkmcnt(1)
	v_mfma_f32_16x16x32_f16 v[82:85], v[118:121], v[90:93], v[82:85]
	v_mfma_f32_16x16x32_f16 v[86:89], v[118:121], v[110:113], v[86:89]
	s_waitcnt lgkmcnt(0)
	v_mfma_f32_16x16x32_f16 v[28:31], v[122:125], v[90:93], v[28:31]
	ds_read_b128 v[90:93], v21 offset:20480
	v_mfma_f32_16x16x32_f16 v[32:35], v[122:125], v[110:113], v[32:35]
	ds_read_b128 v[110:113], v21 offset:22528
	s_waitcnt lgkmcnt(1)
	v_mfma_f32_16x16x32_f16 v[98:101], v[62:65], v[90:93], v[98:101]
	s_waitcnt lgkmcnt(0)
	v_mfma_f32_16x16x32_f16 v[52:55], v[62:65], v[110:113], v[52:55]
	ds_read_b128 v[62:65], v22 offset:49152
	v_mfma_f32_16x16x32_f16 v[102:105], v[74:77], v[90:93], v[102:105]
	v_mfma_f32_16x16x32_f16 v[24:27], v[74:77], v[110:113], v[24:27]
	ds_read_b128 v[74:77], v22 offset:51200
	v_mfma_f32_16x16x32_f16 v[114:117], v[118:121], v[90:93], v[114:117]
	s_waitcnt vmcnt(7)
	ds_write_b128 v17, v[58:61]
	s_waitcnt vmcnt(6)
; #define GL_LOAD(s_, kt_) if (VAR != 1) { a##s_##0 = GL_A(0, kt_); a##s_##1 = GL_A(1, kt_); a##s_##2 = GL_A(2, kt_); a##s_##3 = GL_A(3, kt_); b##s_##0 = GL_B(0, kt_); b##s_##1 = GL_B(1, kt_); b##s_##2 = GL_B(2, kt_); b##s_##3 = GL_B(3, kt_); }
; #define LDS_STORE(s_, buf_) if (VAR != 2) { LDS_ST1(sA, 0, buf_, a##s_##0) LDS_ST1(sA, 1, buf_, a##s_##1) LDS_ST1(sA, 2, buf_, a##s_##2) LDS_ST1(sA, 3, buf_, a##s_##3) LDS_ST1(sB, 0, buf_, b##s_##0) LDS_ST1(sB, 1, buf_, b##s_##1) LDS_ST1(sB, 2, buf_, b##s_##2) LDS_ST1(sB, 3, buf_, b##s_##3) }
;     ...
;   GL_LOAD(0, 0)
;   GL_LOAD(1, 1)
;   LDS_STORE(0, 0)
;   if (VAR != 4) __syncthreads();
; #pragma unroll
;   for (int kt = 0; kt < nk; kt += 2) {
;     if (kt + 2 < nk) { GL_LOAD(0, kt + 2) }
;     MMA_TILE(0)
;     LDS_STORE(1, 1)
;     if (VAR != 4) __syncthreads();
;     if (kt + 3 < nk) { GL_LOAD(1, kt + 3) }
;     MMA_TILE(1)
;     if (kt + 2 < nk) { LDS_STORE(0, 0) }
;     if (VAR != 4) __syncthreads();
	ds_write_b128 v18, v[106:109]
	v_mfma_f32_16x16x32_f16 v[40:43], v[118:121], v[110:113], v[40:43]
	ds_read_b128 v[118:121], v22 offset:53248
	s_waitcnt vmcnt(5)
	ds_write_b128 v19, v[126:129]
	v_mfma_f32_16x16x32_f16 v[70:73], v[122:125], v[90:93], v[70:73]
	ds_read_b128 v[90:93], v23 offset:16384
	v_mfma_f32_16x16x32_f16 v[48:51], v[122:125], v[110:113], v[48:51]
	ds_read_b128 v[110:113], v23 offset:18432
	s_waitcnt lgkmcnt(1)
	v_mfma_f32_16x16x32_f16 v[36:39], v[62:65], v[90:93], v[36:39]
	ds_read_b128 v[122:125], v22 offset:55296
	s_waitcnt lgkmcnt(1)
	v_mfma_f32_16x16x32_f16 v[66:69], v[62:65], v[110:113], v[66:69]
	s_waitcnt vmcnt(4)
	ds_write_b128 v20, v[134:137]
	v_mfma_f32_16x16x32_f16 v[44:47], v[74:77], v[90:93], v[44:47]
	s_waitcnt vmcnt(3)
	ds_write_b128 v17, v[94:97] offset:32768
	v_mfma_f32_16x16x32_f16 v[78:81], v[74:77], v[110:113], v[78:81]
	s_waitcnt vmcnt(2)
	ds_write_b128 v18, v[162:165] offset:32768
	v_mfma_f32_16x16x32_f16 v[82:85], v[118:121], v[90:93], v[82:85]
	s_waitcnt vmcnt(1)
	ds_write_b128 v19, v[166:169] offset:32768
	v_mfma_f32_16x16x32_f16 v[86:89], v[118:121], v[110:113], v[86:89]
	s_waitcnt vmcnt(0)
	ds_write_b128 v20, v[190:193] offset:32768
	s_waitcnt lgkmcnt(5)
	v_mfma_f32_16x16x32_f16 v[28:31], v[122:125], v[90:93], v[28:31]
	ds_read_b128 v[90:93], v23 offset:20480
	v_mfma_f32_16x16x32_f16 v[32:35], v[122:125], v[110:113], v[32:35]
	ds_read_b128 v[110:113], v23 offset:22528
	s_waitcnt lgkmcnt(1)
	v_mfma_f32_16x16x32_f16 v[98:101], v[62:65], v[90:93], v[98:101]
	s_waitcnt lgkmcnt(0)
	v_mfma_f32_16x16x32_f16 v[52:55], v[62:65], v[110:113], v[52:55]
	global_load_dwordx4 v[62:65], v[0:1], off offset:3200
	v_mfma_f32_16x16x32_f16 v[102:105], v[74:77], v[90:93], v[102:105]
	v_mfma_f32_16x16x32_f16 v[24:27], v[74:77], v[110:113], v[24:27]
	v_mfma_f32_16x16x32_f16 v[114:117], v[118:121], v[90:93], v[114:117]
	v_mfma_f32_16x16x32_f16 v[40:43], v[118:121], v[110:113], v[40:43]
	v_mfma_f32_16x16x32_f16 v[70:73], v[122:125], v[90:93], v[70:73]
	global_load_dwordx4 v[90:93], v[2:3], off offset:3200
	global_load_dwordx4 v[130:133], v[4:5], off offset:3200
	global_load_dwordx4 v[138:141], v[14:15], off offset:3200
	global_load_dwordx4 v[74:77], v[10:11], off offset:3200
	global_load_dwordx4 v[142:145], v[12:13], off offset:3200
	global_load_dwordx4 v[154:157], v[8:9], off offset:3200
	global_load_dwordx4 v[158:161], v[6:7], off offset:3200
	s_waitcnt lgkmcnt(0)
	s_barrier
	v_mfma_f32_16x16x32_f16 v[48:51], v[122:125], v[110:113], v[48:51]
	ds_read_b128 v[58:61], v16 offset:32768
	ds_read_b128 v[106:109], v21
	s_waitcnt lgkmcnt(0)
	v_mfma_f32_16x16x32_f16 v[36:39], v[58:61], v[106:109], v[36:39]
	ds_read_b128 v[94:97], v16 offset:34816
	ds_read_b128 v[110:113], v21 offset:2048
	s_waitcnt lgkmcnt(0)
	v_mfma_f32_16x16x32_f16 v[66:69], v[58:61], v[110:113], v[66:69]
	ds_read_b128 v[118:121], v16 offset:36864
	v_mfma_f32_16x16x32_f16 v[44:47], v[94:97], v[106:109], v[44:47]
	ds_read_b128 v[122:125], v16 offset:38912
	v_mfma_f32_16x16x32_f16 v[78:81], v[94:97], v[110:113], v[78:81]
	s_waitcnt lgkmcnt(1)
	v_mfma_f32_16x16x32_f16 v[82:85], v[118:121], v[106:109], v[82:85]
	v_mfma_f32_16x16x32_f16 v[86:89], v[118:121], v[110:113], v[86:89]
	s_waitcnt lgkmcnt(0)
	v_mfma_f32_16x16x32_f16 v[28:31], v[122:125], v[106:109], v[28:31]
	ds_read_b128 v[106:109], v21 offset:4096
	v_mfma_f32_16x16x32_f16 v[32:35], v[122:125], v[110:113], v[32:35]
	ds_read_b128 v[110:113], v21 offset:6144
	s_waitcnt lgkmcnt(1)
	v_mfma_f32_16x16x32_f16 v[98:101], v[58:61], v[106:109], v[98:101]
	s_waitcnt lgkmcnt(0)
	v_mfma_f32_16x16x32_f16 v[52:55], v[58:61], v[110:113], v[52:55]
	ds_read_b128 v[58:61], v22 offset:32768
	v_mfma_f32_16x16x32_f16 v[102:105], v[94:97], v[106:109], v[102:105]
	v_mfma_f32_16x16x32_f16 v[24:27], v[94:97], v[110:113], v[24:27]
	ds_read_b128 v[94:97], v22 offset:34816
	v_mfma_f32_16x16x32_f16 v[114:117], v[118:121], v[106:109], v[114:117]
	s_waitcnt vmcnt(7)
	ds_write_b128 v17, v[62:65] offset:16384
	s_waitcnt vmcnt(6)
	ds_write_b128 v18, v[90:93] offset:16384
	v_mfma_f32_16x16x32_f16 v[40:43], v[118:121], v[110:113], v[40:43]
	ds_read_b128 v[118:121], v22 offset:36864
	s_waitcnt vmcnt(5)
	ds_write_b128 v19, v[130:133] offset:16384
	v_mfma_f32_16x16x32_f16 v[70:73], v[122:125], v[106:109], v[70:73]
	ds_read_b128 v[106:109], v23
	v_mfma_f32_16x16x32_f16 v[48:51], v[122:125], v[110:113], v[48:51]
	ds_read_b128 v[110:113], v23 offset:2048
	s_waitcnt lgkmcnt(1)
	v_mfma_f32_16x16x32_f16 v[36:39], v[58:61], v[106:109], v[36:39]
	ds_read_b128 v[122:125], v22 offset:38912
	s_waitcnt lgkmcnt(1)
	v_mfma_f32_16x16x32_f16 v[66:69], v[58:61], v[110:113], v[66:69]
	s_waitcnt vmcnt(4)
	ds_write_b128 v20, v[138:141] offset:16384
	v_mfma_f32_16x16x32_f16 v[44:47], v[94:97], v[106:109], v[44:47]
	s_waitcnt vmcnt(3)
	ds_write_b128 v17, v[74:77] offset:49152
	v_mfma_f32_16x16x32_f16 v[78:81], v[94:97], v[110:113], v[78:81]
	s_waitcnt vmcnt(2)
	ds_write_b128 v18, v[142:145] offset:49152
	v_mfma_f32_16x16x32_f16 v[82:85], v[118:121], v[106:109], v[82:85]
	s_waitcnt vmcnt(1)
	ds_write_b128 v19, v[154:157] offset:49152
	v_mfma_f32_16x16x32_f16 v[86:89], v[118:121], v[110:113], v[86:89]
	s_waitcnt vmcnt(0)
	ds_write_b128 v20, v[158:161] offset:49152
	s_waitcnt lgkmcnt(5)
	v_mfma_f32_16x16x32_f16 v[28:31], v[122:125], v[106:109], v[28:31]
	ds_read_b128 v[106:109], v23 offset:4096
	v_mfma_f32_16x16x32_f16 v[32:35], v[122:125], v[110:113], v[32:35]
	ds_read_b128 v[110:113], v23 offset:6144
	s_waitcnt lgkmcnt(1)
	v_mfma_f32_16x16x32_f16 v[98:101], v[58:61], v[106:109], v[98:101]
	s_waitcnt lgkmcnt(0)
	v_mfma_f32_16x16x32_f16 v[52:55], v[58:61], v[110:113], v[52:55]
	global_load_dwordx4 v[58:61], v[0:1], off offset:3328
	v_mfma_f32_16x16x32_f16 v[102:105], v[94:97], v[106:109], v[102:105]
	v_mfma_f32_16x16x32_f16 v[24:27], v[94:97], v[110:113], v[24:27]
	v_mfma_f32_16x16x32_f16 v[114:117], v[118:121], v[106:109], v[114:117]
	v_mfma_f32_16x16x32_f16 v[40:43], v[118:121], v[110:113], v[40:43]
	v_mfma_f32_16x16x32_f16 v[70:73], v[122:125], v[106:109], v[70:73]
	global_load_dwordx4 v[106:109], v[2:3], off offset:3328
	global_load_dwordx4 v[126:129], v[4:5], off offset:3328
	global_load_dwordx4 v[134:137], v[14:15], off offset:3328
	global_load_dwordx4 v[94:97], v[10:11], off offset:3328
	global_load_dwordx4 v[162:165], v[12:13], off offset:3328
	global_load_dwordx4 v[166:169], v[8:9], off offset:3328
	global_load_dwordx4 v[190:193], v[6:7], off offset:3328
	s_waitcnt lgkmcnt(0)
	s_barrier
; #define GL_LOAD(s_, kt_) if (VAR != 1) { a##s_##0 = GL_A(0, kt_); a##s_##1 = GL_A(1, kt_); a##s_##2 = GL_A(2, kt_); a##s_##3 = GL_A(3, kt_); b##s_##0 = GL_B(0, kt_); b##s_##1 = GL_B(1, kt_); b##s_##2 = GL_B(2, kt_); b##s_##3 = GL_B(3, kt_); }
; #define LDS_STORE(s_, buf_) if (VAR != 2) { LDS_ST1(sA, 0, buf_, a##s_##0) LDS_ST1(sA, 1, buf_, a##s_##1) LDS_ST1(sA, 2, buf_, a##s_##2) LDS_ST1(sA, 3, buf_, a##s_##3) LDS_ST1(sB, 0, buf_, b##s_##0) LDS_ST1(sB, 1, buf_, b##s_##1) LDS_ST1(sB, 2, buf_, b##s_##2) LDS_ST1(sB, 3, buf_, b##s_##3) }
;     ...
;   GL_LOAD(0, 0)
;   GL_LOAD(1, 1)
;   LDS_STORE(0, 0)
;   if (VAR != 4) __syncthreads();
; #pragma unroll
;   for (int kt = 0; kt < nk; kt += 2) {
;     if (kt + 2 < nk) { GL_LOAD(0, kt + 2) }
;     MMA_TILE(0)
;     LDS_STORE(1, 1)
;     if (VAR != 4) __syncthreads();
;     if (kt + 3 < nk) { GL_LOAD(1, kt + 3) }
;     MMA_TILE(1)
;     if (kt + 2 < nk) { LDS_STORE(0, 0) }
;     if (VAR != 4) __syncthreads();
	v_mfma_f32_16x16x32_f16 v[48:51], v[122:125], v[110:113], v[48:51]
	ds_read_b128 v[62:65], v16 offset:49152
	ds_read_b128 v[90:93], v21 offset:16384
	s_waitcnt lgkmcnt(0)
	v_mfma_f32_16x16x32_f16 v[36:39], v[62:65], v[90:93], v[36:39]
	ds_read_b128 v[74:77], v16 offset:51200
	ds_read_b128 v[110:113], v21 offset:18432
	s_waitcnt lgkmcnt(0)
	v_mfma_f32_16x16x32_f16 v[66:69], v[62:65], v[110:113], v[66:69]
	ds_read_b128 v[118:121], v16 offset:53248
	v_mfma_f32_16x16x32_f16 v[44:47], v[74:77], v[90:93], v[44:47]
	ds_read_b128 v[122:125], v16 offset:55296
	v_mfma_f32_16x16x32_f16 v[78:81], v[74:77], v[110:113], v[78:81]
	s_waitcnt lgkmcnt(1)
	v_mfma_f32_16x16x32_f16 v[82:85], v[118:121], v[90:93], v[82:85]
	v_mfma_f32_16x16x32_f16 v[86:89], v[118:121], v[110:113], v[86:89]
	s_waitcnt lgkmcnt(0)
	v_mfma_f32_16x16x32_f16 v[28:31], v[122:125], v[90:93], v[28:31]
	ds_read_b128 v[90:93], v21 offset:20480
	v_mfma_f32_16x16x32_f16 v[32:35], v[122:125], v[110:113], v[32:35]
	ds_read_b128 v[110:113], v21 offset:22528
	s_waitcnt lgkmcnt(1)
	v_mfma_f32_16x16x32_f16 v[98:101], v[62:65], v[90:93], v[98:101]
	s_waitcnt lgkmcnt(0)
	v_mfma_f32_16x16x32_f16 v[52:55], v[62:65], v[110:113], v[52:55]
	ds_read_b128 v[62:65], v22 offset:49152
	v_mfma_f32_16x16x32_f16 v[102:105], v[74:77], v[90:93], v[102:105]
	v_mfma_f32_16x16x32_f16 v[24:27], v[74:77], v[110:113], v[24:27]
	ds_read_b128 v[74:77], v22 offset:51200
	v_mfma_f32_16x16x32_f16 v[114:117], v[118:121], v[90:93], v[114:117]
	s_waitcnt vmcnt(7)
	ds_write_b128 v17, v[58:61]
	s_waitcnt vmcnt(6)
	ds_write_b128 v18, v[106:109]
	v_mfma_f32_16x16x32_f16 v[40:43], v[118:121], v[110:113], v[40:43]
	ds_read_b128 v[118:121], v22 offset:53248
	s_waitcnt vmcnt(5)
	ds_write_b128 v19, v[126:129]
	v_mfma_f32_16x16x32_f16 v[70:73], v[122:125], v[90:93], v[70:73]
	ds_read_b128 v[90:93], v23 offset:16384
	v_mfma_f32_16x16x32_f16 v[48:51], v[122:125], v[110:113], v[48:51]
	ds_read_b128 v[110:113], v23 offset:18432
	s_waitcnt lgkmcnt(1)
	v_mfma_f32_16x16x32_f16 v[36:39], v[62:65], v[90:93], v[36:39]
	ds_read_b128 v[122:125], v22 offset:55296
	s_waitcnt lgkmcnt(1)
	v_mfma_f32_16x16x32_f16 v[66:69], v[62:65], v[110:113], v[66:69]
	s_waitcnt vmcnt(4)
	ds_write_b128 v20, v[134:137]
	v_mfma_f32_16x16x32_f16 v[44:47], v[74:77], v[90:93], v[44:47]
	s_waitcnt vmcnt(3)
	ds_write_b128 v17, v[94:97] offset:32768
	v_mfma_f32_16x16x32_f16 v[78:81], v[74:77], v[110:113], v[78:81]
	s_waitcnt vmcnt(2)
	ds_write_b128 v18, v[162:165] offset:32768
	v_mfma_f32_16x16x32_f16 v[82:85], v[118:121], v[90:93], v[82:85]
	s_waitcnt vmcnt(1)
	ds_write_b128 v19, v[166:169] offset:32768
	v_mfma_f32_16x16x32_f16 v[86:89], v[118:121], v[110:113], v[86:89]
	s_waitcnt vmcnt(0)
	ds_write_b128 v20, v[190:193] offset:32768
	s_waitcnt lgkmcnt(5)
	v_mfma_f32_16x16x32_f16 v[28:31], v[122:125], v[90:93], v[28:31]
	ds_read_b128 v[90:93], v23 offset:20480
	v_mfma_f32_16x16x32_f16 v[32:35], v[122:125], v[110:113], v[32:35]
	ds_read_b128 v[110:113], v23 offset:22528
	s_waitcnt lgkmcnt(1)
	v_mfma_f32_16x16x32_f16 v[98:101], v[62:65], v[90:93], v[98:101]
	s_waitcnt lgkmcnt(0)
	v_mfma_f32_16x16x32_f16 v[52:55], v[62:65], v[110:113], v[52:55]
	global_load_dwordx4 v[62:65], v[0:1], off offset:3456
	v_mfma_f32_16x16x32_f16 v[102:105], v[74:77], v[90:93], v[102:105]
	v_mfma_f32_16x16x32_f16 v[24:27], v[74:77], v[110:113], v[24:27]
	v_mfma_f32_16x16x32_f16 v[114:117], v[118:121], v[90:93], v[114:117]
	v_mfma_f32_16x16x32_f16 v[40:43], v[118:121], v[110:113], v[40:43]
	v_mfma_f32_16x16x32_f16 v[70:73], v[122:125], v[90:93], v[70:73]
	global_load_dwordx4 v[90:93], v[2:3], off offset:3456
	global_load_dwordx4 v[130:133], v[4:5], off offset:3456
	global_load_dwordx4 v[138:141], v[14:15], off offset:3456
	global_load_dwordx4 v[74:77], v[10:11], off offset:3456
	global_load_dwordx4 v[142:145], v[12:13], off offset:3456
	global_load_dwordx4 v[154:157], v[8:9], off offset:3456
	global_load_dwordx4 v[158:161], v[6:7], off offset:3456
	s_waitcnt lgkmcnt(0)
	s_barrier
	v_mfma_f32_16x16x32_f16 v[48:51], v[122:125], v[110:113], v[48:51]
	ds_read_b128 v[58:61], v16 offset:32768
	ds_read_b128 v[106:109], v21
	s_waitcnt lgkmcnt(0)
	v_mfma_f32_16x16x32_f16 v[36:39], v[58:61], v[106:109], v[36:39]
	ds_read_b128 v[94:97], v16 offset:34816
	ds_read_b128 v[110:113], v21 offset:2048
	s_waitcnt lgkmcnt(0)
	v_mfma_f32_16x16x32_f16 v[66:69], v[58:61], v[110:113], v[66:69]
	ds_read_b128 v[118:121], v16 offset:36864
	v_mfma_f32_16x16x32_f16 v[44:47], v[94:97], v[106:109], v[44:47]
	ds_read_b128 v[122:125], v16 offset:38912
	v_mfma_f32_16x16x32_f16 v[78:81], v[94:97], v[110:113], v[78:81]
	s_waitcnt lgkmcnt(1)
	v_mfma_f32_16x16x32_f16 v[82:85], v[118:121], v[106:109], v[82:85]
	v_mfma_f32_16x16x32_f16 v[86:89], v[118:121], v[110:113], v[86:89]
	s_waitcnt lgkmcnt(0)
	v_mfma_f32_16x16x32_f16 v[28:31], v[122:125], v[106:109], v[28:31]
	ds_read_b128 v[106:109], v21 offset:4096
	v_mfma_f32_16x16x32_f16 v[32:35], v[122:125], v[110:113], v[32:35]
	ds_read_b128 v[110:113], v21 offset:6144
	s_waitcnt lgkmcnt(1)
	v_mfma_f32_16x16x32_f16 v[98:101], v[58:61], v[106:109], v[98:101]
	s_waitcnt lgkmcnt(0)
	v_mfma_f32_16x16x32_f16 v[52:55], v[58:61], v[110:113], v[52:55]
	ds_read_b128 v[58:61], v22 offset:32768
	v_mfma_f32_16x16x32_f16 v[102:105], v[94:97], v[106:109], v[102:105]
	v_mfma_f32_16x16x32_f16 v[24:27], v[94:97], v[110:113], v[24:27]
	ds_read_b128 v[94:97], v22 offset:34816
	v_mfma_f32_16x16x32_f16 v[114:117], v[118:121], v[106:109], v[114:117]
	s_waitcnt vmcnt(7)
	ds_write_b128 v17, v[62:65] offset:16384
	s_waitcnt vmcnt(6)
; #define GL_LOAD(s_, kt_) if (VAR != 1) { a##s_##0 = GL_A(0, kt_); a##s_##1 = GL_A(1, kt_); a##s_##2 = GL_A(2, kt_); a##s_##3 = GL_A(3, kt_); b##s_##0 = GL_B(0, kt_); b##s_##1 = GL_B(1, kt_); b##s_##2 = GL_B(2, kt_); b##s_##3 = GL_B(3, kt_); }
; #define LDS_STORE(s_, buf_) if (VAR != 2) { LDS_ST1(sA, 0, buf_, a##s_##0) LDS_ST1(sA, 1, buf_, a##s_##1) LDS_ST1(sA, 2, buf_, a##s_##2) LDS_ST1(sA, 3, buf_, a##s_##3) LDS_ST1(sB, 0, buf_, b##s_##0) LDS_ST1(sB, 1, buf_, b##s_##1) LDS_ST1(sB, 2, buf_, b##s_##2) LDS_ST1(sB, 3, buf_, b##s_##3) }
;     ...
;   GL_LOAD(0, 0)
;   GL_LOAD(1, 1)
;   LDS_STORE(0, 0)
;   if (VAR != 4) __syncthreads();
; #pragma unroll
;   for (int kt = 0; kt < nk; kt += 2) {
;     if (kt + 2 < nk) { GL_LOAD(0, kt + 2) }
;     MMA_TILE(0)
;     LDS_STORE(1, 1)
;     if (VAR != 4) __syncthreads();
;     if (kt + 3 < nk) { GL_LOAD(1, kt + 3) }
;     MMA_TILE(1)
;     if (kt + 2 < nk) { LDS_STORE(0, 0) }
;     if (VAR != 4) __syncthreads();
	ds_write_b128 v18, v[90:93] offset:16384
	v_mfma_f32_16x16x32_f16 v[40:43], v[118:121], v[110:113], v[40:43]
	ds_read_b128 v[118:121], v22 offset:36864
	s_waitcnt vmcnt(5)
	ds_write_b128 v19, v[130:133] offset:16384
	v_mfma_f32_16x16x32_f16 v[70:73], v[122:125], v[106:109], v[70:73]
	ds_read_b128 v[106:109], v23
	v_mfma_f32_16x16x32_f16 v[48:51], v[122:125], v[110:113], v[48:51]
	ds_read_b128 v[110:113], v23 offset:2048
	s_waitcnt lgkmcnt(1)
	v_mfma_f32_16x16x32_f16 v[36:39], v[58:61], v[106:109], v[36:39]
	ds_read_b128 v[122:125], v22 offset:38912
	s_waitcnt lgkmcnt(1)
	v_mfma_f32_16x16x32_f16 v[66:69], v[58:61], v[110:113], v[66:69]
	s_waitcnt vmcnt(4)
	ds_write_b128 v20, v[138:141] offset:16384
	v_mfma_f32_16x16x32_f16 v[44:47], v[94:97], v[106:109], v[44:47]
	s_waitcnt vmcnt(3)
	ds_write_b128 v17, v[74:77] offset:49152
	v_mfma_f32_16x16x32_f16 v[78:81], v[94:97], v[110:113], v[78:81]
	s_waitcnt vmcnt(2)
	ds_write_b128 v18, v[142:145] offset:49152
	v_mfma_f32_16x16x32_f16 v[82:85], v[118:121], v[106:109], v[82:85]
	s_waitcnt vmcnt(1)
	ds_write_b128 v19, v[154:157] offset:49152
	v_mfma_f32_16x16x32_f16 v[86:89], v[118:121], v[110:113], v[86:89]
	s_waitcnt vmcnt(0)
	ds_write_b128 v20, v[158:161] offset:49152
	s_waitcnt lgkmcnt(5)
	v_mfma_f32_16x16x32_f16 v[28:31], v[122:125], v[106:109], v[28:31]
	ds_read_b128 v[106:109], v23 offset:4096
	v_mfma_f32_16x16x32_f16 v[32:35], v[122:125], v[110:113], v[32:35]
	ds_read_b128 v[110:113], v23 offset:6144
	s_waitcnt lgkmcnt(1)
	v_mfma_f32_16x16x32_f16 v[98:101], v[58:61], v[106:109], v[98:101]
	s_waitcnt lgkmcnt(0)
	v_mfma_f32_16x16x32_f16 v[52:55], v[58:61], v[110:113], v[52:55]
	global_load_dwordx4 v[58:61], v[0:1], off offset:3584
	v_mfma_f32_16x16x32_f16 v[102:105], v[94:97], v[106:109], v[102:105]
	v_mfma_f32_16x16x32_f16 v[24:27], v[94:97], v[110:113], v[24:27]
	v_mfma_f32_16x16x32_f16 v[114:117], v[118:121], v[106:109], v[114:117]
	v_mfma_f32_16x16x32_f16 v[40:43], v[118:121], v[110:113], v[40:43]
	v_mfma_f32_16x16x32_f16 v[70:73], v[122:125], v[106:109], v[70:73]
	global_load_dwordx4 v[106:109], v[2:3], off offset:3584
	global_load_dwordx4 v[126:129], v[4:5], off offset:3584
	global_load_dwordx4 v[134:137], v[14:15], off offset:3584
	global_load_dwordx4 v[94:97], v[10:11], off offset:3584
	global_load_dwordx4 v[162:165], v[12:13], off offset:3584
	global_load_dwordx4 v[166:169], v[8:9], off offset:3584
	global_load_dwordx4 v[190:193], v[6:7], off offset:3584
	s_waitcnt lgkmcnt(0)
	s_barrier
	v_mfma_f32_16x16x32_f16 v[48:51], v[122:125], v[110:113], v[48:51]
	ds_read_b128 v[62:65], v16 offset:49152
	ds_read_b128 v[90:93], v21 offset:16384
	s_waitcnt lgkmcnt(0)
	v_mfma_f32_16x16x32_f16 v[36:39], v[62:65], v[90:93], v[36:39]
	ds_read_b128 v[74:77], v16 offset:51200
	ds_read_b128 v[110:113], v21 offset:18432
	s_waitcnt lgkmcnt(0)
	v_mfma_f32_16x16x32_f16 v[66:69], v[62:65], v[110:113], v[66:69]
	ds_read_b128 v[118:121], v16 offset:53248
	v_mfma_f32_16x16x32_f16 v[44:47], v[74:77], v[90:93], v[44:47]
	ds_read_b128 v[122:125], v16 offset:55296
	v_mfma_f32_16x16x32_f16 v[78:81], v[74:77], v[110:113], v[78:81]
	s_waitcnt lgkmcnt(1)
	v_mfma_f32_16x16x32_f16 v[82:85], v[118:121], v[90:93], v[82:85]
	v_mfma_f32_16x16x32_f16 v[86:89], v[118:121], v[110:113], v[86:89]
	s_waitcnt lgkmcnt(0)
	v_mfma_f32_16x16x32_f16 v[28:31], v[122:125], v[90:93], v[28:31]
	ds_read_b128 v[90:93], v21 offset:20480
	v_mfma_f32_16x16x32_f16 v[32:35], v[122:125], v[110:113], v[32:35]
	ds_read_b128 v[110:113], v21 offset:22528
	s_waitcnt lgkmcnt(1)
	v_mfma_f32_16x16x32_f16 v[98:101], v[62:65], v[90:93], v[98:101]
	s_waitcnt lgkmcnt(0)
	v_mfma_f32_16x16x32_f16 v[52:55], v[62:65], v[110:113], v[52:55]
	ds_read_b128 v[62:65], v22 offset:49152
	v_mfma_f32_16x16x32_f16 v[102:105], v[74:77], v[90:93], v[102:105]
	v_mfma_f32_16x16x32_f16 v[24:27], v[74:77], v[110:113], v[24:27]
	ds_read_b128 v[74:77], v22 offset:51200
	v_mfma_f32_16x16x32_f16 v[114:117], v[118:121], v[90:93], v[114:117]
	s_waitcnt vmcnt(7)
	ds_write_b128 v17, v[58:61]
	s_waitcnt vmcnt(6)
	ds_write_b128 v18, v[106:109]
	v_mfma_f32_16x16x32_f16 v[40:43], v[118:121], v[110:113], v[40:43]
	ds_read_b128 v[118:121], v22 offset:53248
	s_waitcnt vmcnt(5)
	ds_write_b128 v19, v[126:129]
	v_mfma_f32_16x16x32_f16 v[70:73], v[122:125], v[90:93], v[70:73]
	ds_read_b128 v[90:93], v23 offset:16384
	v_mfma_f32_16x16x32_f16 v[48:51], v[122:125], v[110:113], v[48:51]
	ds_read_b128 v[110:113], v23 offset:18432
	s_waitcnt lgkmcnt(1)
	v_mfma_f32_16x16x32_f16 v[36:39], v[62:65], v[90:93], v[36:39]
	ds_read_b128 v[122:125], v22 offset:55296
	s_waitcnt lgkmcnt(1)
	v_mfma_f32_16x16x32_f16 v[66:69], v[62:65], v[110:113], v[66:69]
	s_waitcnt vmcnt(4)
	ds_write_b128 v20, v[134:137]
	v_mfma_f32_16x16x32_f16 v[44:47], v[74:77], v[90:93], v[44:47]
	s_waitcnt vmcnt(3)
	ds_write_b128 v17, v[94:97] offset:32768
	v_mfma_f32_16x16x32_f16 v[78:81], v[74:77], v[110:113], v[78:81]
	s_waitcnt vmcnt(2)
	ds_write_b128 v18, v[162:165] offset:32768
	v_mfma_f32_16x16x32_f16 v[82:85], v[118:121], v[90:93], v[82:85]
	s_waitcnt vmcnt(1)
	ds_write_b128 v19, v[166:169] offset:32768
	v_mfma_f32_16x16x32_f16 v[86:89], v[118:121], v[110:113], v[86:89]
	s_waitcnt vmcnt(0)
	ds_write_b128 v20, v[190:193] offset:32768
	s_waitcnt lgkmcnt(5)
	v_mfma_f32_16x16x32_f16 v[28:31], v[122:125], v[90:93], v[28:31]
	ds_read_b128 v[90:93], v23 offset:20480
	v_mfma_f32_16x16x32_f16 v[32:35], v[122:125], v[110:113], v[32:35]
	ds_read_b128 v[110:113], v23 offset:22528
	s_waitcnt lgkmcnt(1)
	v_mfma_f32_16x16x32_f16 v[98:101], v[62:65], v[90:93], v[98:101]
	s_waitcnt lgkmcnt(0)
	v_mfma_f32_16x16x32_f16 v[52:55], v[62:65], v[110:113], v[52:55]
	global_load_dwordx4 v[62:65], v[0:1], off offset:3712
	v_mfma_f32_16x16x32_f16 v[102:105], v[74:77], v[90:93], v[102:105]
	v_mfma_f32_16x16x32_f16 v[24:27], v[74:77], v[110:113], v[24:27]
	v_mfma_f32_16x16x32_f16 v[114:117], v[118:121], v[90:93], v[114:117]
	v_mfma_f32_16x16x32_f16 v[40:43], v[118:121], v[110:113], v[40:43]
	v_mfma_f32_16x16x32_f16 v[70:73], v[122:125], v[90:93], v[70:73]
	global_load_dwordx4 v[90:93], v[2:3], off offset:3712
	global_load_dwordx4 v[130:133], v[4:5], off offset:3712
	global_load_dwordx4 v[138:141], v[14:15], off offset:3712
	global_load_dwordx4 v[74:77], v[10:11], off offset:3712
	global_load_dwordx4 v[142:145], v[12:13], off offset:3712
	global_load_dwordx4 v[154:157], v[8:9], off offset:3712
	global_load_dwordx4 v[158:161], v[6:7], off offset:3712
	s_waitcnt lgkmcnt(0)
	s_barrier
; #define GL_LOAD(s_, kt_) if (VAR != 1) { a##s_##0 = GL_A(0, kt_); a##s_##1 = GL_A(1, kt_); a##s_##2 = GL_A(2, kt_); a##s_##3 = GL_A(3, kt_); b##s_##0 = GL_B(0, kt_); b##s_##1 = GL_B(1, kt_); b##s_##2 = GL_B(2, kt_); b##s_##3 = GL_B(3, kt_); }
; #define LDS_STORE(s_, buf_) if (VAR != 2) { LDS_ST1(sA, 0, buf_, a##s_##0) LDS_ST1(sA, 1, buf_, a##s_##1) LDS_ST1(sA, 2, buf_, a##s_##2) LDS_ST1(sA, 3, buf_, a##s_##3) LDS_ST1(sB, 0, buf_, b##s_##0) LDS_ST1(sB, 1, buf_, b##s_##1) LDS_ST1(sB, 2, buf_, b##s_##2) LDS_ST1(sB, 3, buf_, b##s_##3) }
;     ...
;   GL_LOAD(0, 0)
;   GL_LOAD(1, 1)
;   LDS_STORE(0, 0)
;   if (VAR != 4) __syncthreads();
; #pragma unroll
;   for (int kt = 0; kt < nk; kt += 2) {
;     if (kt + 2 < nk) { GL_LOAD(0, kt + 2) }
;     MMA_TILE(0)
;     LDS_STORE(1, 1)
;     if (VAR != 4) __syncthreads();
;     if (kt + 3 < nk) { GL_LOAD(1, kt + 3) }
;     MMA_TILE(1)
;     if (kt + 2 < nk) { LDS_STORE(0, 0) }
;     if (VAR != 4) __syncthreads();
	v_mfma_f32_16x16x32_f16 v[48:51], v[122:125], v[110:113], v[48:51]
	ds_read_b128 v[58:61], v16 offset:32768
	ds_read_b128 v[106:109], v21
	s_waitcnt lgkmcnt(0)
	v_mfma_f32_16x16x32_f16 v[36:39], v[58:61], v[106:109], v[36:39]
	ds_read_b128 v[94:97], v16 offset:34816
	ds_read_b128 v[110:113], v21 offset:2048
	s_waitcnt lgkmcnt(0)
	v_mfma_f32_16x16x32_f16 v[66:69], v[58:61], v[110:113], v[66:69]
	ds_read_b128 v[118:121], v16 offset:36864
	v_mfma_f32_16x16x32_f16 v[44:47], v[94:97], v[106:109], v[44:47]
	ds_read_b128 v[122:125], v16 offset:38912
	v_mfma_f32_16x16x32_f16 v[78:81], v[94:97], v[110:113], v[78:81]
	s_waitcnt lgkmcnt(1)
	v_mfma_f32_16x16x32_f16 v[82:85], v[118:121], v[106:109], v[82:85]
	v_mfma_f32_16x16x32_f16 v[86:89], v[118:121], v[110:113], v[86:89]
	s_waitcnt lgkmcnt(0)
	v_mfma_f32_16x16x32_f16 v[28:31], v[122:125], v[106:109], v[28:31]
	ds_read_b128 v[106:109], v21 offset:4096
	v_mfma_f32_16x16x32_f16 v[32:35], v[122:125], v[110:113], v[32:35]
	ds_read_b128 v[110:113], v21 offset:6144
	s_waitcnt lgkmcnt(1)
	v_mfma_f32_16x16x32_f16 v[98:101], v[58:61], v[106:109], v[98:101]
	s_waitcnt lgkmcnt(0)
	v_mfma_f32_16x16x32_f16 v[52:55], v[58:61], v[110:113], v[52:55]
	ds_read_b128 v[58:61], v22 offset:32768
	v_mfma_f32_16x16x32_f16 v[102:105], v[94:97], v[106:109], v[102:105]
	v_mfma_f32_16x16x32_f16 v[24:27], v[94:97], v[110:113], v[24:27]
	ds_read_b128 v[94:97], v22 offset:34816
	v_mfma_f32_16x16x32_f16 v[114:117], v[118:121], v[106:109], v[114:117]
	s_waitcnt vmcnt(7)
	ds_write_b128 v17, v[62:65] offset:16384
	s_waitcnt vmcnt(6)
	ds_write_b128 v18, v[90:93] offset:16384
	v_mfma_f32_16x16x32_f16 v[40:43], v[118:121], v[110:113], v[40:43]
	ds_read_b128 v[118:121], v22 offset:36864
	s_waitcnt vmcnt(5)
	ds_write_b128 v19, v[130:133] offset:16384
	v_mfma_f32_16x16x32_f16 v[70:73], v[122:125], v[106:109], v[70:73]
	ds_read_b128 v[106:109], v23
	v_mfma_f32_16x16x32_f16 v[48:51], v[122:125], v[110:113], v[48:51]
	ds_read_b128 v[110:113], v23 offset:2048
	s_waitcnt lgkmcnt(1)
	v_mfma_f32_16x16x32_f16 v[36:39], v[58:61], v[106:109], v[36:39]
	ds_read_b128 v[122:125], v22 offset:38912
	s_waitcnt lgkmcnt(1)
	v_mfma_f32_16x16x32_f16 v[66:69], v[58:61], v[110:113], v[66:69]
	s_waitcnt vmcnt(4)
	ds_write_b128 v20, v[138:141] offset:16384
	v_mfma_f32_16x16x32_f16 v[44:47], v[94:97], v[106:109], v[44:47]
	s_waitcnt vmcnt(3)
	ds_write_b128 v17, v[74:77] offset:49152
	v_mfma_f32_16x16x32_f16 v[78:81], v[94:97], v[110:113], v[78:81]
	s_waitcnt vmcnt(2)
	ds_write_b128 v18, v[142:145] offset:49152
	v_mfma_f32_16x16x32_f16 v[82:85], v[118:121], v[106:109], v[82:85]
	s_waitcnt vmcnt(1)
	ds_write_b128 v19, v[154:157] offset:49152
	v_mfma_f32_16x16x32_f16 v[86:89], v[118:121], v[110:113], v[86:89]
	s_waitcnt vmcnt(0)
	ds_write_b128 v20, v[158:161] offset:49152
	s_waitcnt lgkmcnt(5)
	v_mfma_f32_16x16x32_f16 v[28:31], v[122:125], v[106:109], v[28:31]
	ds_read_b128 v[106:109], v23 offset:4096
	v_mfma_f32_16x16x32_f16 v[32:35], v[122:125], v[110:113], v[32:35]
	ds_read_b128 v[110:113], v23 offset:6144
	s_waitcnt lgkmcnt(1)
	v_mfma_f32_16x16x32_f16 v[98:101], v[58:61], v[106:109], v[98:101]
	s_waitcnt lgkmcnt(0)
	v_mfma_f32_16x16x32_f16 v[52:55], v[58:61], v[110:113], v[52:55]
	global_load_dwordx4 v[58:61], v[0:1], off offset:3840
	v_mfma_f32_16x16x32_f16 v[102:105], v[94:97], v[106:109], v[102:105]
	v_mfma_f32_16x16x32_f16 v[24:27], v[94:97], v[110:113], v[24:27]
	v_mfma_f32_16x16x32_f16 v[114:117], v[118:121], v[106:109], v[114:117]
	v_mfma_f32_16x16x32_f16 v[40:43], v[118:121], v[110:113], v[40:43]
	v_mfma_f32_16x16x32_f16 v[70:73], v[122:125], v[106:109], v[70:73]
	global_load_dwordx4 v[106:109], v[2:3], off offset:3840
	global_load_dwordx4 v[126:129], v[4:5], off offset:3840
	global_load_dwordx4 v[134:137], v[14:15], off offset:3840
	global_load_dwordx4 v[94:97], v[10:11], off offset:3840
	global_load_dwordx4 v[162:165], v[12:13], off offset:3840
	global_load_dwordx4 v[166:169], v[8:9], off offset:3840
	global_load_dwordx4 v[190:193], v[6:7], off offset:3840
	s_waitcnt lgkmcnt(0)
	s_barrier
	v_mfma_f32_16x16x32_f16 v[48:51], v[122:125], v[110:113], v[48:51]
	ds_read_b128 v[62:65], v16 offset:49152
	ds_read_b128 v[90:93], v21 offset:16384
	s_waitcnt lgkmcnt(0)
	v_mfma_f32_16x16x32_f16 v[36:39], v[62:65], v[90:93], v[36:39]
	ds_read_b128 v[74:77], v16 offset:51200
	ds_read_b128 v[110:113], v21 offset:18432
	s_waitcnt lgkmcnt(0)
	v_mfma_f32_16x16x32_f16 v[66:69], v[62:65], v[110:113], v[66:69]
	ds_read_b128 v[118:121], v16 offset:53248
	v_mfma_f32_16x16x32_f16 v[44:47], v[74:77], v[90:93], v[44:47]
	ds_read_b128 v[122:125], v16 offset:55296
	v_mfma_f32_16x16x32_f16 v[78:81], v[74:77], v[110:113], v[78:81]
	s_waitcnt lgkmcnt(1)
	v_mfma_f32_16x16x32_f16 v[82:85], v[118:121], v[90:93], v[82:85]
	v_mfma_f32_16x16x32_f16 v[86:89], v[118:121], v[110:113], v[86:89]
	s_waitcnt lgkmcnt(0)
	v_mfma_f32_16x16x32_f16 v[28:31], v[122:125], v[90:93], v[28:31]
	ds_read_b128 v[90:93], v21 offset:20480
	v_mfma_f32_16x16x32_f16 v[32:35], v[122:125], v[110:113], v[32:35]
	ds_read_b128 v[110:113], v21 offset:22528
	s_waitcnt lgkmcnt(1)
	v_mfma_f32_16x16x32_f16 v[98:101], v[62:65], v[90:93], v[98:101]
	s_waitcnt lgkmcnt(0)
	v_mfma_f32_16x16x32_f16 v[52:55], v[62:65], v[110:113], v[52:55]
	ds_read_b128 v[62:65], v22 offset:49152
	v_mfma_f32_16x16x32_f16 v[102:105], v[74:77], v[90:93], v[102:105]
	v_mfma_f32_16x16x32_f16 v[24:27], v[74:77], v[110:113], v[24:27]
	ds_read_b128 v[74:77], v22 offset:51200
	v_mfma_f32_16x16x32_f16 v[114:117], v[118:121], v[90:93], v[114:117]
	s_waitcnt vmcnt(7)
	ds_write_b128 v17, v[58:61]
	s_waitcnt vmcnt(6)
; #define GL_LOAD(s_, kt_) if (VAR != 1) { a##s_##0 = GL_A(0, kt_); a##s_##1 = GL_A(1, kt_); a##s_##2 = GL_A(2, kt_); a##s_##3 = GL_A(3, kt_); b##s_##0 = GL_B(0, kt_); b##s_##1 = GL_B(1, kt_); b##s_##2 = GL_B(2, kt_); b##s_##3 = GL_B(3, kt_); }
; #define LDS_STORE(s_, buf_) if (VAR != 2) { LDS_ST1(sA, 0, buf_, a##s_##0) LDS_ST1(sA, 1, buf_, a##s_##1) LDS_ST1(sA, 2, buf_, a##s_##2) LDS_ST1(sA, 3, buf_, a##s_##3) LDS_ST1(sB, 0, buf_, b##s_##0) LDS_ST1(sB, 1, buf_, b##s_##1) LDS_ST1(sB, 2, buf_, b##s_##2) LDS_ST1(sB, 3, buf_, b##s_##3) }
;     ...
;   GL_LOAD(0, 0)
;   GL_LOAD(1, 1)
;   LDS_STORE(0, 0)
;   if (VAR != 4) __syncthreads();
; #pragma unroll
;   for (int kt = 0; kt < nk; kt += 2) {
;     if (kt + 2 < nk) { GL_LOAD(0, kt + 2) }
;     MMA_TILE(0)
;     LDS_STORE(1, 1)
;     if (VAR != 4) __syncthreads();
;     if (kt + 3 < nk) { GL_LOAD(1, kt + 3) }
;     MMA_TILE(1)
;     if (kt + 2 < nk) { LDS_STORE(0, 0) }
;     if (VAR != 4) __syncthreads();
	ds_write_b128 v18, v[106:109]
	v_mfma_f32_16x16x32_f16 v[40:43], v[118:121], v[110:113], v[40:43]
	ds_read_b128 v[118:121], v22 offset:53248
	s_waitcnt vmcnt(5)
	ds_write_b128 v19, v[126:129]
	v_mfma_f32_16x16x32_f16 v[70:73], v[122:125], v[90:93], v[70:73]
	ds_read_b128 v[90:93], v23 offset:16384
	v_mfma_f32_16x16x32_f16 v[48:51], v[122:125], v[110:113], v[48:51]
	ds_read_b128 v[110:113], v23 offset:18432
	s_waitcnt lgkmcnt(1)
	v_mfma_f32_16x16x32_f16 v[36:39], v[62:65], v[90:93], v[36:39]
	ds_read_b128 v[122:125], v22 offset:55296
	s_waitcnt lgkmcnt(1)
	v_mfma_f32_16x16x32_f16 v[66:69], v[62:65], v[110:113], v[66:69]
	s_waitcnt vmcnt(4)
	ds_write_b128 v20, v[134:137]
	v_mfma_f32_16x16x32_f16 v[44:47], v[74:77], v[90:93], v[44:47]
	s_waitcnt vmcnt(3)
	ds_write_b128 v17, v[94:97] offset:32768
	v_mfma_f32_16x16x32_f16 v[78:81], v[74:77], v[110:113], v[78:81]
	s_waitcnt vmcnt(2)
	ds_write_b128 v18, v[162:165] offset:32768
	v_mfma_f32_16x16x32_f16 v[82:85], v[118:121], v[90:93], v[82:85]
	s_waitcnt vmcnt(1)
	ds_write_b128 v19, v[166:169] offset:32768
	v_mfma_f32_16x16x32_f16 v[86:89], v[118:121], v[110:113], v[86:89]
	s_waitcnt vmcnt(0)
	ds_write_b128 v20, v[190:193] offset:32768
	s_waitcnt lgkmcnt(5)
	v_mfma_f32_16x16x32_f16 v[28:31], v[122:125], v[90:93], v[28:31]
	ds_read_b128 v[90:93], v23 offset:20480
	v_mfma_f32_16x16x32_f16 v[32:35], v[122:125], v[110:113], v[32:35]
	ds_read_b128 v[110:113], v23 offset:22528
	s_waitcnt lgkmcnt(1)
	v_mfma_f32_16x16x32_f16 v[98:101], v[62:65], v[90:93], v[98:101]
	s_waitcnt lgkmcnt(0)
	v_mfma_f32_16x16x32_f16 v[52:55], v[62:65], v[110:113], v[52:55]
	global_load_dwordx4 v[62:65], v[0:1], off offset:3968
	global_load_dwordx4 v[0:3], v[2:3], off offset:3968
	v_mfma_f32_16x16x32_f16 v[102:105], v[74:77], v[90:93], v[102:105]
	v_mfma_f32_16x16x32_f16 v[24:27], v[74:77], v[110:113], v[24:27]
	v_mfma_f32_16x16x32_f16 v[114:117], v[118:121], v[90:93], v[114:117]
	v_mfma_f32_16x16x32_f16 v[40:43], v[118:121], v[110:113], v[40:43]
	v_mfma_f32_16x16x32_f16 v[70:73], v[122:125], v[90:93], v[70:73]
	global_load_dwordx4 v[90:93], v[4:5], off offset:3968
	global_load_dwordx4 v[130:133], v[14:15], off offset:3968
	global_load_dwordx4 v[74:77], v[10:11], off offset:3968
	global_load_dwordx4 v[10:13], v[12:13], off offset:3968
	global_load_dwordx4 v[138:141], v[8:9], off offset:3968
	global_load_dwordx4 v[4:7], v[6:7], off offset:3968
	s_waitcnt lgkmcnt(0)
	s_barrier
	ds_read_b128 v[58:61], v16 offset:32768
	v_mfma_f32_16x16x32_f16 v[48:51], v[122:125], v[110:113], v[48:51]
	ds_read_b128 v[94:97], v16 offset:34816
	ds_read_b128 v[106:109], v21
	ds_read_b128 v[110:113], v21 offset:2048
	ds_read_b128 v[118:121], v16 offset:36864
	ds_read_b128 v[122:125], v16 offset:38912
	s_waitcnt lgkmcnt(3)
	v_mfma_f32_16x16x32_f16 v[36:39], v[58:61], v[106:109], v[36:39]
	v_mfma_f32_16x16x32_f16 v[44:47], v[94:97], v[106:109], v[44:47]
	s_waitcnt lgkmcnt(1)
	v_mfma_f32_16x16x32_f16 v[82:85], v[118:121], v[106:109], v[82:85]
	s_waitcnt lgkmcnt(0)
	v_mfma_f32_16x16x32_f16 v[28:31], v[122:125], v[106:109], v[28:31]
	v_mfma_f32_16x16x32_f16 v[66:69], v[58:61], v[110:113], v[66:69]
	v_mfma_f32_16x16x32_f16 v[78:81], v[94:97], v[110:113], v[78:81]
	v_mfma_f32_16x16x32_f16 v[86:89], v[118:121], v[110:113], v[86:89]
	v_mfma_f32_16x16x32_f16 v[32:35], v[122:125], v[110:113], v[32:35]
	ds_read_b128 v[106:109], v21 offset:4096
	ds_read_b128 v[110:113], v21 offset:6144
	s_waitcnt lgkmcnt(1)
	v_mfma_f32_16x16x32_f16 v[98:101], v[58:61], v[106:109], v[98:101]
	v_mfma_f32_16x16x32_f16 v[102:105], v[94:97], v[106:109], v[102:105]
	v_mfma_f32_16x16x32_f16 v[114:117], v[118:121], v[106:109], v[114:117]
	v_mfma_f32_16x16x32_f16 v[70:73], v[122:125], v[106:109], v[70:73]
	s_waitcnt lgkmcnt(0)
	v_mfma_f32_16x16x32_f16 v[52:55], v[58:61], v[110:113], v[52:55]
	ds_read_b128 v[58:61], v22 offset:32768
	v_mfma_f32_16x16x32_f16 v[24:27], v[94:97], v[110:113], v[24:27]
	v_mfma_f32_16x16x32_f16 v[40:43], v[118:121], v[110:113], v[40:43]
	v_mfma_f32_16x16x32_f16 v[48:51], v[122:125], v[110:113], v[48:51]
	ds_read_b128 v[94:97], v22 offset:34816
	ds_read_b128 v[106:109], v23
	ds_read_b128 v[110:113], v23 offset:2048
	ds_read_b128 v[118:121], v22 offset:36864
	ds_read_b128 v[122:125], v22 offset:38912
	s_waitcnt lgkmcnt(3)
	v_mfma_f32_16x16x32_f16 v[36:39], v[58:61], v[106:109], v[36:39]
	v_mfma_f32_16x16x32_f16 v[44:47], v[94:97], v[106:109], v[44:47]
	s_waitcnt lgkmcnt(1)
	v_mfma_f32_16x16x32_f16 v[82:85], v[118:121], v[106:109], v[82:85]
	s_waitcnt lgkmcnt(0)
	v_mfma_f32_16x16x32_f16 v[28:31], v[122:125], v[106:109], v[28:31]
	v_mfma_f32_16x16x32_f16 v[66:69], v[58:61], v[110:113], v[66:69]
	v_mfma_f32_16x16x32_f16 v[78:81], v[94:97], v[110:113], v[78:81]
	v_mfma_f32_16x16x32_f16 v[86:89], v[118:121], v[110:113], v[86:89]
	v_mfma_f32_16x16x32_f16 v[32:35], v[122:125], v[110:113], v[32:35]
	ds_read_b128 v[106:109], v23 offset:4096
	ds_read_b128 v[110:113], v23 offset:6144
	s_waitcnt vmcnt(7)
	ds_write_b128 v17, v[62:65] offset:16384
	s_waitcnt vmcnt(6)
	ds_write_b128 v18, v[0:3] offset:16384
	s_waitcnt vmcnt(5)
	ds_write_b128 v19, v[90:93] offset:16384
	s_waitcnt vmcnt(4)
	ds_write_b128 v20, v[130:133] offset:16384
	s_waitcnt lgkmcnt(5)
	v_mfma_f32_16x16x32_f16 v[98:101], v[58:61], v[106:109], v[98:101]
	s_waitcnt vmcnt(3)
	ds_write_b128 v17, v[74:77] offset:49152
	s_waitcnt vmcnt(2)
	ds_write_b128 v18, v[10:13] offset:49152
	s_waitcnt vmcnt(1)
	ds_write_b128 v19, v[138:141] offset:49152
	s_waitcnt vmcnt(0)
	ds_write_b128 v20, v[4:7] offset:49152
	s_waitcnt lgkmcnt(0)
	s_barrier
; DI int TIDX() { int t = threadIdx.x; asm volatile("" : "+v"(t)); return t; }
; DI unsigned pack2(float lo, float hi) { f2_t v = {lo, hi}; h2_t b = __builtin_convertvector(v, h2_t); return __builtin_bit_cast(unsigned, b); }
; #define GL_LOAD(s_, kt_) if (VAR != 1) { a##s_##0 = GL_A(0, kt_); a##s_##1 = GL_A(1, kt_); a##s_##2 = GL_A(2, kt_); a##s_##3 = GL_A(3, kt_); b##s_##0 = GL_B(0, kt_); b##s_##1 = GL_B(1, kt_); b##s_##2 = GL_B(2, kt_); b##s_##3 = GL_B(3, kt_); }
; #define LDS_STORE(s_, buf_) if (VAR != 2) { LDS_ST1(sA, 0, buf_, a##s_##0) LDS_ST1(sA, 1, buf_, a##s_##1) LDS_ST1(sA, 2, buf_, a##s_##2) LDS_ST1(sA, 3, buf_, a##s_##3) LDS_ST1(sB, 0, buf_, b##s_##0) LDS_ST1(sB, 1, buf_, b##s_##1) LDS_ST1(sB, 2, buf_, b##s_##2) LDS_ST1(sB, 3, buf_, b##s_##3) }
;     ...
;   GL_LOAD(0, 0)
;   GL_LOAD(1, 1)
;   LDS_STORE(0, 0)
;   if (VAR != 4) __syncthreads();
; #pragma unroll
;   for (int kt = 0; kt < nk; kt += 2) {
;     if (kt + 2 < nk) { GL_LOAD(0, kt + 2) }
;     MMA_TILE(0)
;     LDS_STORE(1, 1)
;     if (VAR != 4) __syncthreads();
;     if (kt + 3 < nk) { GL_LOAD(1, kt + 3) }
;     MMA_TILE(1)
;     if (kt + 2 < nk) { LDS_STORE(0, 0) }
;     if (VAR != 4) __syncthreads();
; DI void epi_residual(const f32x4 (&v)[4][4], int row0, int col0, const float* xsrc, float* x, bf16_t* xb, float* ssq_out, bool write_xb, bool write_ssq) {
;   const int lane = TIDX() & 63, lr = lane & 15, g = lane >> 4;
; #pragma unroll
;   for (int mt = 0; mt < 4; ++mt) {
;     const int row = row0 + mt * 16 + lr;
;     float ss = 0.f;
; #pragma unroll
;     for (int nt = 0; nt < 4; ++nt) {
;       const int col = col0 + nt * 16 + 4 * g;
;       float4* px = (float4*)(x + (size_t)row * DM + col);
;       float4 o = *(const float4*)(xsrc + (size_t)row * DM + col);
;       o.x += v[mt][nt][0]; o.y += v[mt][nt][1]; o.z += v[mt][nt][2]; o.w += v[mt][nt][3];
;       *px = o;
;       ss += (o.x * o.x + o.y * o.y) + (o.z * o.z + o.w * o.w);
;       if (write_xb) *(uint2*)(xb + (size_t)row * DM + col) = make_uint2(pack2(o.x, o.y), pack2(o.z, o.w));
;     }
;     if (write_ssq) {
;       ss += __shfl_xor(ss, 16); ss += __shfl_xor(ss, 32);
;       if (g == 0) ssq_out[(size_t)row * 16 + (col0 >> 6)] = ss;
;     }
;   }
	v_mfma_f32_16x16x32_f16 v[52:55], v[58:61], v[110:113], v[52:55]
	ds_read_b128 v[4:7], v16 offset:49152
	v_add_u32_e32 v130, s4, v57
	v_mfma_f32_16x16x32_f16 v[0:3], v[118:121], v[110:113], v[40:43]
	v_readlane_b32 s4, v254, 45
	v_readlane_b32 s5, v254, 46
	v_mfma_f32_16x16x32_f16 v[8:11], v[122:125], v[110:113], v[48:51]
	ds_read_b128 v[12:15], v16 offset:51200
	ds_read_b128 v[40:43], v21 offset:16384
	s_nop 0
	ds_read_b128 v[48:51], v21 offset:18432
	ds_read_b128 v[58:61], v16 offset:53248
	ds_read_b128 v[16:19], v16 offset:55296
	v_mfma_f32_16x16x32_f16 v[102:105], v[94:97], v[106:109], v[102:105]
	v_mfma_f32_16x16x32_f16 v[114:117], v[118:121], v[106:109], v[114:117]
	v_mfma_f32_16x16x32_f16 v[70:73], v[122:125], v[106:109], v[70:73]
	v_mfma_f32_16x16x32_f16 v[24:27], v[94:97], v[110:113], v[24:27]
	s_waitcnt lgkmcnt(3)
	v_mfma_f32_16x16x32_f16 v[36:39], v[4:7], v[40:43], v[36:39]
	v_mfma_f32_16x16x32_f16 v[44:47], v[12:15], v[40:43], v[44:47]
	s_waitcnt lgkmcnt(1)
	v_mfma_f32_16x16x32_f16 v[62:65], v[58:61], v[40:43], v[82:85]
	s_waitcnt lgkmcnt(0)
	v_mfma_f32_16x16x32_f16 v[28:31], v[16:19], v[40:43], v[28:31]
	ds_read_b128 v[40:43], v21 offset:20480
	ds_read_b128 v[74:77], v21 offset:22528
	ds_read_b128 v[82:85], v23 offset:16384
	ds_read_b128 v[90:93], v23 offset:18432
	ds_read_b128 v[94:97], v22 offset:49152
	ds_read_b128 v[106:109], v22 offset:51200
	ds_read_b128 v[110:113], v23 offset:20480
	ds_read_b128 v[118:121], v23 offset:22528
	ds_read_b128 v[122:125], v22 offset:53248
	ds_read_b128 v[126:129], v22 offset:55296
	v_mfma_f32_16x16x32_f16 v[66:69], v[4:7], v[48:51], v[66:69]
	s_waitcnt lgkmcnt(0)
	s_barrier
	s_setprio 0
	v_mfma_f32_16x16x32_f16 v[78:81], v[12:15], v[48:51], v[78:81]
	v_mfma_f32_16x16x32_f16 v[20:23], v[58:61], v[48:51], v[86:89]
	v_mfma_f32_16x16x32_f16 v[32:35], v[16:19], v[48:51], v[32:35]
	v_mov_b32_e32 v49, v148
	v_or_b32_e32 v48, s10, v56
	v_and_or_b32 v50, v49, 15, v130
	v_bfe_u32 v134, v49, 4, 2
	v_ashrrev_i32_e32 v51, 31, v50
	v_mfma_f32_16x16x32_f16 v[86:89], v[4:7], v[40:43], v[98:101]
	v_lshl_or_b32 v135, v134, 2, v48
	v_lshrrev_b32_e32 v150, 4, v48
	v_lshl_add_u64 v[48:49], s[4:5], 0, v[150:151]
	v_mfma_f32_16x16x32_f16 v[98:101], v[12:15], v[40:43], v[102:105]
	v_lshlrev_b32_e32 v150, 2, v135
	v_readlane_b32 s4, v254, 43
	v_readlane_b32 s5, v254, 44
	v_mfma_f32_16x16x32_f16 v[102:105], v[58:61], v[40:43], v[114:117]
	v_cmp_eq_u32_e32 vcc, 0, v134
	s_nop 1
	v_lshlrev_b64 v[114:115], 12, v[50:51]
	v_lshl_add_u64 v[114:115], s[12:13], 0, v[114:115]
	v_lshl_add_u64 v[130:131], v[114:115], 0, v[150:151]
	v_mfma_f32_16x16x32_f16 v[70:73], v[16:19], v[40:43], v[70:73]
	global_load_dwordx4 v[40:43], v[130:131], off
	v_lshlrev_b64 v[114:115], 11, v[50:51]
	v_lshl_add_u64 v[132:133], s[4:5], 0, v[114:115]
	v_mfma_f32_16x16x32_f16 v[36:39], v[94:97], v[82:85], v[36:39]
	v_mfma_f32_16x16x32_f16 v[4:7], v[4:7], v[74:77], v[52:55]
	s_nop 2
	v_lshlrev_b32_e32 v52, 1, v135
	v_mov_b32_e32 v53, v151
	v_lshl_add_u64 v[54:55], v[132:133], 0, v[52:53]
	v_mfma_f32_16x16x32_f16 v[114:117], v[12:15], v[74:77], v[24:27]
	s_waitcnt vmcnt(0)
	v_pk_add_f32 v[36:37], v[36:37], v[40:41]
	v_pk_add_f32 v[38:39], v[38:39], v[42:43]
	v_cvt_pk_f16_f32 v40, v36, v37
	v_cvt_pk_f16_f32 v41, v38, v39
	global_store_dwordx4 v[130:131], v[36:39], off
	global_store_dwordx2 v[54:55], v[40:41], off
	global_load_dwordx4 v[24:27], v[130:131], off offset:64
	v_mfma_f32_16x16x32_f16 v[12:15], v[106:109], v[82:85], v[44:47]
	v_mfma_f32_16x16x32_f16 v[0:3], v[58:61], v[74:77], v[0:3]
	v_mfma_f32_16x16x32_f16 v[58:61], v[16:19], v[74:77], v[8:11]
	s_waitcnt vmcnt(0)
	s_nop 4
	v_pk_add_f32 v[12:13], v[12:13], v[24:25]
	v_pk_add_f32 v[14:15], v[14:15], v[26:27]
	v_cvt_pk_f16_f32 v24, v12, v13
	v_cvt_pk_f16_f32 v25, v14, v15
	global_store_dwordx4 v[130:131], v[12:15], off offset:64
	global_store_dwordx2 v[54:55], v[24:25], off offset:32
	global_load_dwordx4 v[8:11], v[130:131], off offset:128
	v_mfma_f32_16x16x32_f16 v[16:19], v[122:125], v[82:85], v[62:65]
	v_mul_f32_e64 v12, v12, v12
	v_mul_f32_e64 v13, v13, v13
	v_pk_mul_f32 v[14:15], v[14:15], v[14:15]
	v_add_f32_e32 v12, v12, v13
	v_mfma_f32_16x16x32_f16 v[44:47], v[94:97], v[90:93], v[66:69]
	v_add_f32_e32 v14, v14, v15
	v_add_f32_e32 v12, v12, v14
	s_waitcnt vmcnt(0)
	v_pk_add_f32 v[8:9], v[16:17], v[8:9]
	v_pk_add_f32 v[10:11], v[18:19], v[10:11]
	v_cvt_pk_f16_f32 v24, v8, v9
	v_cvt_pk_f16_f32 v25, v10, v11
	global_store_dwordx4 v[130:131], v[8:11], off offset:128
	global_store_dwordx2 v[54:55], v[24:25], off offset:64
	global_load_dwordx4 v[24:27], v[130:131], off offset:192
	v_mfma_f32_16x16x32_f16 v[16:19], v[126:129], v[82:85], v[28:31]
	v_mul_f32_e64 v66, v36, v36
	v_mul_f32_e64 v67, v37, v37
	v_pk_mul_f32 v[68:69], v[38:39], v[38:39]
	v_pk_mul_f32 v[8:9], v[8:9], v[8:9]
	v_pk_mul_f32 v[10:11], v[10:11], v[10:11]
	v_add_f32_e32 v8, v8, v9
	v_add_f32_e32 v10, v10, v11
	v_add_f32_e32 v8, v8, v10
	v_mfma_f32_16x16x32_f16 v[40:43], v[106:109], v[90:93], v[78:81]
	s_waitcnt vmcnt(0)
	v_pk_add_f32 v[62:63], v[16:17], v[24:25]
	v_add_f32_e32 v16, v68, v69
	v_add_f32_e32 v17, v66, v67
	v_pk_add_f32 v[64:65], v[18:19], v[26:27]
	v_add_f32_e32 v16, v17, v16
	v_pk_mul_f32 v[74:75], v[62:63], v[62:63]
	v_pk_mul_f32 v[76:77], v[64:65], v[64:65]
	v_add_f32_e32 v12, v16, v12
	v_add_f32_e32 v66, v12, v8
	v_mfma_f32_16x16x32_f16 v[12:15], v[94:97], v[118:121], v[4:7]
	global_store_dwordx4 v[130:131], v[62:65], off offset:192
	s_nop 1
	v_add_f32_e32 v4, v76, v77
	v_add_f32_e32 v5, v74, v75
	v_add_f32_e32 v4, v5, v4
	v_add_f32_e32 v66, v66, v4
	ds_bpermute_b32 v67, v189, v66
	v_cvt_pk_f16_f32 v62, v62, v63
	v_cvt_pk_f16_f32 v63, v64, v65
	global_store_dwordx2 v[54:55], v[62:63], off offset:96
	v_mfma_f32_16x16x32_f16 v[36:39], v[122:125], v[90:93], v[20:23]
	s_waitcnt lgkmcnt(0)
	v_add_f32_e32 v54, v66, v67
	ds_bpermute_b32 v55, v188, v54
	v_mfma_f32_16x16x32_f16 v[32:35], v[126:129], v[90:93], v[32:35]
	v_mfma_f32_16x16x32_f16 v[28:31], v[94:97], v[110:113], v[86:89]
	v_mfma_f32_16x16x32_f16 v[24:27], v[106:109], v[110:113], v[98:101]
	v_mfma_f32_16x16x32_f16 v[20:23], v[122:125], v[110:113], v[102:105]
	v_mfma_f32_16x16x32_f16 v[16:19], v[126:129], v[110:113], v[70:73]
	v_mfma_f32_16x16x32_f16 v[8:11], v[106:109], v[118:121], v[114:117]
	v_mfma_f32_16x16x32_f16 v[4:7], v[122:125], v[118:121], v[0:3]
	v_mfma_f32_16x16x32_f16 v[0:3], v[126:129], v[118:121], v[58:61]
	s_and_saveexec_b64 s[4:5], vcc
	s_cbranch_execz .LBB0_1374
	s_waitcnt lgkmcnt(0)
	v_add_f32_e32 v58, v54, v55
	v_lshlrev_b64 v[54:55], 6, v[50:51]
	v_lshl_add_u64 v[54:55], v[48:49], 0, v[54:55]
	global_store_dword v[54:55], v58, off

; DI int BIDX() { int b = blockIdx.x; asm volatile("" : "+s"(b)); return b; }
; #define GL_LOAD(s_, kt_) if (VAR != 1) { a##s_##0 = GL_A(0, kt_); a##s_##1 = GL_A(1, kt_); a##s_##2 = GL_A(2, kt_); a##s_##3 = GL_A(3, kt_); b##s_##0 = GL_B(0, kt_); b##s_##1 = GL_B(1, kt_); b##s_##2 = GL_B(2, kt_); b##s_##3 = GL_B(3, kt_); }
; #define LDS_STORE(s_, buf_) if (VAR != 2) { LDS_ST1(sA, 0, buf_, a##s_##0) LDS_ST1(sA, 1, buf_, a##s_##1) LDS_ST1(sA, 2, buf_, a##s_##2) LDS_ST1(sA, 3, buf_, a##s_##3) LDS_ST1(sB, 0, buf_, b##s_##0) LDS_ST1(sB, 1, buf_, b##s_##1) LDS_ST1(sB, 2, buf_, b##s_##2) LDS_ST1(sB, 3, buf_, b##s_##3) }
; DI int tile_groups(int MT, int NT) { return (MT >> 6) * ((NT + 7) >> 3) * 512; }
;     ...
;   GL_LOAD(0, 0)
;   GL_LOAD(1, 1)
;   LDS_STORE(0, 0)
;   if (VAR != 4) __syncthreads();
; #pragma unroll
;   for (int kt = 0; kt < nk; kt += 2) {
;     if (kt + 2 < nk) { GL_LOAD(0, kt + 2) }
;     MMA_TILE(0)
;     LDS_STORE(1, 1)
;     if (VAR != 4) __syncthreads();
;     if (kt + 3 < nk) { GL_LOAD(1, kt + 3) }
;     MMA_TILE(1)
; DI void phase_ple(const Params& P, int l, char* smem) {
;     ...
;   for (int vb = BIDX(); vb < tile_groups(128, 8); vb += gridDim.x) {
;     int tm, tn; if (!tile_of(vb, 128, 8, tm, tn)) continue;
;     const int m0 = tm * 128, n0 = tn * 128;
;     const int row0 = m0 + wm * 64, col0 = n0 + wn * 64;
;     uint4* park = (uint4*)(ws + OFF_VT) + ((size_t)BIDX() * 256 + tid) * 8;
;     {
;       f32x4 pp[4][4]; zero_acc(pp);
;       gemm_kloop<false, true, 4>(pp, pl + (size_t)m0 * PLE, PLE, W + WO_PP + (size_t)n0 * PLE, PLE, smem);
.LBB0_1435:
	s_ashr_i32 s1, s8, 3
	s_andn2_b32 s1, s1, 63
	s_and_b32 s2, s14, 56
	s_or_b32 s1, s1, s2
	s_bfe_u32 s2, s8, 0x30003
	s_or_b32 s1, s1, s2
	s_cmpk_gt_i32 s1, 0x7f
	s_cbranch_scc1 .LBB0_1434
	s_lshl_b32 s6, s1, 7
	v_readlane_b32 s1, v253, 0
	s_mov_b32 s16, s1
	s_ashr_i32 s17, s16, 31
	s_lshl_b64 s[16:17], s[16:17], 15
	s_ashr_i32 s7, s6, 31
	v_mov_b32_e32 v88, v148
	s_and_b32 s2, s13, 0x380
	v_lshl_add_u64 v[102:103], v[96:97], 0, s[16:17]
	s_lshl_b64 s[16:17], s[6:7], 9
	v_readlane_b32 s18, v254, 39
	v_readlane_b32 s19, v254, 40
	s_waitcnt vmcnt(5)
	v_ashrrev_i32_e32 v80, 3, v88
	s_add_u32 s16, s18, s16
	v_ashrrev_i32_e32 v81, 31, v80
	s_addc_u32 s17, s19, s17
	v_lshlrev_b32_e32 v0, 3, v88
	v_and_b32_e32 v91, 48, v88
	v_lshlrev_b64 v[16:17], 9, v[80:81]
	v_lshlrev_b32_e32 v81, 4, v88
	v_and_b32_e32 v90, 0x70, v0
	v_bitop3_b32 v170, v0, v91, s23 bitop3:0x6c
	s_waitcnt lgkmcnt(0)
	v_lshl_add_u64 v[0:1], s[16:17], 0, v[16:17]
	v_and_b32_e32 v150, 0x70, v81
	v_add_u32_e32 v82, 32, v80
	s_waitcnt vmcnt(4)
	v_add_u32_e32 v84, 64, v80
	v_add_u32_e32 v86, 0x60, v80
	s_lshl_b32 s1, s2, 9
	s_waitcnt vmcnt(1)
	v_lshl_add_u64 v[64:65], v[0:1], 0, v[150:151]
	v_ashrrev_i32_e32 v83, 31, v82
	v_ashrrev_i32_e32 v85, 31, v84
	v_ashrrev_i32_e32 v87, 31, v86
	s_add_u32 s18, s9, s1
	global_load_dwordx4 v[0:3], v[64:65], off
	v_lshlrev_b64 v[20:21], 9, v[82:83]
	v_lshlrev_b64 v[24:25], 9, v[84:85]
	v_lshlrev_b64 v[28:29], 9, v[86:87]
	s_addc_u32 s19, s10, 0
	v_lshl_add_u64 v[4:5], s[16:17], 0, v[20:21]
	v_lshl_add_u64 v[8:9], s[16:17], 0, v[24:25]
	v_lshl_add_u64 v[12:13], s[16:17], 0, v[28:29]
	v_lshl_add_u64 v[66:67], v[4:5], 0, v[150:151]
	s_waitcnt vmcnt(1)
	v_lshl_add_u64 v[68:69], v[8:9], 0, v[150:151]
	v_lshl_add_u64 v[70:71], v[12:13], 0, v[150:151]
	v_lshl_add_u64 v[16:17], s[18:19], 0, v[16:17]
	global_load_dwordx4 v[4:7], v[66:67], off
	global_load_dwordx4 v[8:11], v[68:69], off
	global_load_dwordx4 v[12:15], v[70:71], off
	v_lshl_add_u64 v[72:73], v[16:17], 0, v[150:151]
	v_lshl_add_u64 v[20:21], s[18:19], 0, v[20:21]
	global_load_dwordx4 v[16:19], v[72:73], off
	v_lshl_add_u64 v[74:75], v[20:21], 0, v[150:151]
	v_lshl_add_u64 v[24:25], s[18:19], 0, v[24:25]
	global_load_dwordx4 v[20:23], v[74:75], off
	v_lshl_add_u64 v[76:77], v[24:25], 0, v[150:151]
	global_load_dwordx4 v[24:27], v[76:77], off
	v_lshl_add_u64 v[28:29], s[18:19], 0, v[28:29]
	v_lshl_add_u64 v[78:79], v[28:29], 0, v[150:151]
	global_load_dwordx4 v[28:31], v[78:79], off
	global_load_dwordx4 v[32:35], v[64:65], off offset:128
	global_load_dwordx4 v[36:39], v[66:67], off offset:128
	global_load_dwordx4 v[40:43], v[68:69], off offset:128
	global_load_dwordx4 v[44:47], v[70:71], off offset:128
	global_load_dwordx4 v[48:51], v[72:73], off offset:128
	global_load_dwordx4 v[52:55], v[74:75], off offset:128
	global_load_dwordx4 v[56:59], v[76:77], off offset:128
	global_load_dwordx4 v[60:63], v[78:79], off offset:128
	v_bitop3_b32 v83, v81, s23, v88 bitop3:0x48
	v_lshl_or_b32 v80, v80, 7, v83
	v_and_b32_e32 v89, 15, v88
	v_lshl_or_b32 v81, v82, 7, v83
	v_lshl_or_b32 v82, v84, 7, v83
	v_lshl_or_b32 v83, v86, 7, v83
	v_xor_b32_e32 v171, 64, v170
	v_add_u32_e32 v123, s6, v122
	v_readlane_b32 s16, v254, 45
	v_readlane_b32 s17, v254, 46
	s_mov_b32 s18, 0x358637bd
	s_mov_b32 s1, 0x800000
	s_lshl_b64 s[6:7], s[6:7], 11
	s_waitcnt vmcnt(15)
	ds_write_b128 v80, v[0:3]
	v_lshrrev_b32_e32 v0, 1, v88
	v_and_or_b32 v0, v0, s24, v89
	v_lshlrev_b32_e32 v150, 7, v0
	v_lshlrev_b32_e32 v0, 7, v88
	v_and_b32_e32 v194, 0x2780, v0
	v_bitop3_b32 v84, v150, v90, v91 bitop3:0xf6
	v_or_b32_e32 v85, v194, v170
	s_waitcnt vmcnt(14)
	ds_write_b128 v81, v[4:7]
	s_waitcnt vmcnt(13)
	ds_write_b128 v82, v[8:11]
	s_waitcnt vmcnt(12)
	ds_write_b128 v83, v[12:15]
	s_waitcnt vmcnt(11)
	ds_write_b128 v80, v[16:19] offset:32768
	s_waitcnt vmcnt(10)
	ds_write_b128 v81, v[20:23] offset:32768
	s_waitcnt vmcnt(9)
	ds_write_b128 v82, v[24:27] offset:32768
	s_waitcnt vmcnt(8)
	ds_write_b128 v83, v[28:31] offset:32768
	s_waitcnt lgkmcnt(0)
	s_barrier
	s_setprio 1
	global_load_dwordx4 v[0:3], v[64:65], off offset:256
	global_load_dwordx4 v[4:7], v[66:67], off offset:256
	global_load_dwordx4 v[8:11], v[68:69], off offset:256
	global_load_dwordx4 v[12:15], v[70:71], off offset:256
	global_load_dwordx4 v[16:19], v[72:73], off offset:256
	global_load_dwordx4 v[20:23], v[74:75], off offset:256
	global_load_dwordx4 v[24:27], v[76:77], off offset:256
	global_load_dwordx4 v[28:31], v[78:79], off offset:256
	ds_read_b128 v[86:89], v84
	ds_read_b128 v[90:93], v85 offset:32768
	ds_read_b128 v[98:101], v84 offset:2048
	ds_read_b128 v[104:107], v85 offset:34816
	ds_read_b128 v[108:111], v84 offset:4096
	ds_read_b128 v[112:115], v85 offset:36864
	ds_read_b128 v[116:119], v84 offset:6144
	ds_read_b128 v[124:127], v85 offset:38912
	s_waitcnt lgkmcnt(6)
	v_mfma_f32_16x16x32_f16 v[128:131], v[90:93], v[86:89], 0
	s_waitcnt lgkmcnt(4)
	v_mfma_f32_16x16x32_f16 v[132:135], v[104:107], v[86:89], 0
	s_waitcnt lgkmcnt(2)
	v_mfma_f32_16x16x32_f16 v[136:139], v[112:115], v[86:89], 0
	s_waitcnt lgkmcnt(0)
	v_mfma_f32_16x16x32_f16 v[140:143], v[124:127], v[86:89], 0
	v_bitop3_b32 v86, v150, v170, 64 bitop3:0xf6
	v_or_b32_e32 v87, v194, v171
	v_mfma_f32_16x16x32_f16 v[144:147], v[90:93], v[98:101], 0
	v_mfma_f32_16x16x32_f16 v[154:157], v[104:107], v[98:101], 0
	v_mfma_f32_16x16x32_f16 v[158:161], v[112:115], v[98:101], 0
	v_mfma_f32_16x16x32_f16 v[98:101], v[124:127], v[98:101], 0
	v_mfma_f32_16x16x32_f16 v[162:165], v[90:93], v[108:111], 0
	v_mfma_f32_16x16x32_f16 v[166:169], v[104:107], v[108:111], 0
	v_mfma_f32_16x16x32_f16 v[190:193], v[112:115], v[108:111], 0
	v_mfma_f32_16x16x32_f16 v[108:111], v[124:127], v[108:111], 0
	v_mfma_f32_16x16x32_f16 v[88:91], v[90:93], v[116:119], 0
	v_mfma_f32_16x16x32_f16 v[92:95], v[104:107], v[116:119], 0
	v_mfma_f32_16x16x32_f16 v[104:107], v[112:115], v[116:119], 0
	v_mfma_f32_16x16x32_f16 v[112:115], v[124:127], v[116:119], 0
	ds_read_b128 v[116:119], v86
	ds_read_b128 v[124:127], v87 offset:32768
	ds_read_b128 v[194:197], v86 offset:2048
	ds_read_b128 v[198:201], v87 offset:34816
	ds_read_b128 v[202:205], v86 offset:4096
	ds_read_b128 v[206:209], v87 offset:36864
	ds_read_b128 v[210:213], v86 offset:6144
	ds_read_b128 v[220:223], v87 offset:38912
	s_waitcnt vmcnt(15)
	ds_write_b128 v80, v[32:35] offset:16384
	s_waitcnt vmcnt(14)
	ds_write_b128 v81, v[36:39] offset:16384
	s_waitcnt vmcnt(13)
	ds_write_b128 v82, v[40:43] offset:16384
	s_waitcnt vmcnt(12)
	ds_write_b128 v83, v[44:47] offset:16384
	s_waitcnt vmcnt(11)
	ds_write_b128 v80, v[48:51] offset:49152
	s_waitcnt vmcnt(10)
	ds_write_b128 v81, v[52:55] offset:49152
	s_waitcnt vmcnt(9)
	ds_write_b128 v82, v[56:59] offset:49152
	s_waitcnt vmcnt(8)
	ds_write_b128 v83, v[60:63] offset:49152
	s_waitcnt lgkmcnt(0)
	s_barrier
; #define GL_LOAD(s_, kt_) if (VAR != 1) { a##s_##0 = GL_A(0, kt_); a##s_##1 = GL_A(1, kt_); a##s_##2 = GL_A(2, kt_); a##s_##3 = GL_A(3, kt_); b##s_##0 = GL_B(0, kt_); b##s_##1 = GL_B(1, kt_); b##s_##2 = GL_B(2, kt_); b##s_##3 = GL_B(3, kt_); }
; #define LDS_STORE(s_, buf_) if (VAR != 2) { LDS_ST1(sA, 0, buf_, a##s_##0) LDS_ST1(sA, 1, buf_, a##s_##1) LDS_ST1(sA, 2, buf_, a##s_##2) LDS_ST1(sA, 3, buf_, a##s_##3) LDS_ST1(sB, 0, buf_, b##s_##0) LDS_ST1(sB, 1, buf_, b##s_##1) LDS_ST1(sB, 2, buf_, b##s_##2) LDS_ST1(sB, 3, buf_, b##s_##3) }
;     ...
;   GL_LOAD(0, 0)
;   GL_LOAD(1, 1)
;   LDS_STORE(0, 0)
;   if (VAR != 4) __syncthreads();
; #pragma unroll
;   for (int kt = 0; kt < nk; kt += 2) {
;     if (kt + 2 < nk) { GL_LOAD(0, kt + 2) }
;     MMA_TILE(0)
;     LDS_STORE(1, 1)
;     if (VAR != 4) __syncthreads();
;     if (kt + 3 < nk) { GL_LOAD(1, kt + 3) }
;     MMA_TILE(1)
;     if (kt + 2 < nk) { LDS_STORE(0, 0) }
;     if (VAR != 4) __syncthreads();
	v_mfma_f32_16x16x32_f16 v[128:131], v[124:127], v[116:119], v[128:131]
	global_load_dwordx4 v[32:35], v[64:65], off offset:384
	v_mfma_f32_16x16x32_f16 v[132:135], v[198:201], v[116:119], v[132:135]
	v_mfma_f32_16x16x32_f16 v[136:139], v[206:209], v[116:119], v[136:139]
	v_mfma_f32_16x16x32_f16 v[116:119], v[220:223], v[116:119], v[140:143]
	v_mfma_f32_16x16x32_f16 v[140:143], v[124:127], v[194:197], v[144:147]
	global_load_dwordx4 v[36:39], v[66:67], off offset:384
	ds_read_b128 v[64:67], v84 offset:16384
	global_load_dwordx4 v[40:43], v[68:69], off offset:384
	v_mfma_f32_16x16x32_f16 v[144:147], v[198:201], v[194:197], v[154:157]
	global_load_dwordx4 v[44:47], v[70:71], off offset:384
	v_mfma_f32_16x16x32_f16 v[154:157], v[206:209], v[194:197], v[158:161]
	v_mfma_f32_16x16x32_f16 v[158:161], v[124:127], v[202:205], v[162:165]
	ds_read_b128 v[68:71], v85 offset:49152
	global_load_dwordx4 v[48:51], v[72:73], off offset:384
	v_mfma_f32_16x16x32_f16 v[88:91], v[124:127], v[210:213], v[88:91]
	ds_read_b128 v[124:127], v84 offset:20480
	v_mfma_f32_16x16x32_f16 v[162:165], v[198:201], v[202:205], v[166:169]
	global_load_dwordx4 v[52:55], v[74:75], off offset:384
	v_mfma_f32_16x16x32_f16 v[92:95], v[198:201], v[210:213], v[92:95]
	ds_read_b128 v[72:75], v84 offset:18432
	ds_read_b128 v[198:201], v85 offset:55296
	global_load_dwordx4 v[56:59], v[76:77], off offset:384
	global_load_dwordx4 v[60:63], v[78:79], off offset:384
	v_mfma_f32_16x16x32_f16 v[98:101], v[220:223], v[194:197], v[98:101]
	ds_read_b128 v[76:79], v85 offset:51200
	v_mfma_f32_16x16x32_f16 v[166:169], v[206:209], v[202:205], v[190:193]
	s_nop 2
	ds_read_b128 v[190:193], v85 offset:53248
	v_mfma_f32_16x16x32_f16 v[104:107], v[206:209], v[210:213], v[104:107]
	ds_read_b128 v[194:197], v84 offset:22528
	v_mfma_f32_16x16x32_f16 v[108:111], v[220:223], v[202:205], v[108:111]
	s_waitcnt vmcnt(15)
	ds_write_b128 v80, v[0:3]
	v_mfma_f32_16x16x32_f16 v[112:115], v[220:223], v[210:213], v[112:115]
	s_waitcnt vmcnt(14)
	ds_write_b128 v81, v[4:7]
	s_waitcnt lgkmcnt(8)
	v_mfma_f32_16x16x32_f16 v[128:131], v[68:71], v[64:67], v[128:131]
	s_waitcnt vmcnt(13)
	ds_write_b128 v82, v[8:11]
	s_waitcnt lgkmcnt(5)
	v_mfma_f32_16x16x32_f16 v[132:135], v[76:79], v[64:67], v[132:135]
	s_waitcnt lgkmcnt(4)
	v_mfma_f32_16x16x32_f16 v[136:139], v[190:193], v[64:67], v[136:139]
	v_mfma_f32_16x16x32_f16 v[64:67], v[198:201], v[64:67], v[116:119]
	v_mfma_f32_16x16x32_f16 v[116:119], v[68:71], v[72:75], v[140:143]
	s_waitcnt vmcnt(12)
	ds_write_b128 v83, v[12:15]
	s_waitcnt vmcnt(11)
	ds_write_b128 v80, v[16:19] offset:32768
	v_mfma_f32_16x16x32_f16 v[140:143], v[76:79], v[72:75], v[144:147]
	s_waitcnt vmcnt(10)
	ds_write_b128 v81, v[20:23] offset:32768
	v_mfma_f32_16x16x32_f16 v[144:147], v[190:193], v[72:75], v[154:157]
	v_mfma_f32_16x16x32_f16 v[72:75], v[198:201], v[72:75], v[98:101]
	v_mfma_f32_16x16x32_f16 v[98:101], v[68:71], v[124:127], v[158:161]
	s_waitcnt vmcnt(9)
	ds_write_b128 v82, v[24:27] offset:32768
	s_waitcnt vmcnt(8)
	ds_write_b128 v83, v[28:31] offset:32768
	s_waitcnt lgkmcnt(8)
	v_mfma_f32_16x16x32_f16 v[68:71], v[68:71], v[194:197], v[88:91]
	v_mfma_f32_16x16x32_f16 v[154:157], v[76:79], v[124:127], v[162:165]
	s_nop 2
	ds_read_b128 v[162:165], v87 offset:51200
	v_mfma_f32_16x16x32_f16 v[76:79], v[76:79], v[194:197], v[92:95]
	v_mfma_f32_16x16x32_f16 v[158:161], v[190:193], v[124:127], v[166:169]
	s_nop 2
	ds_read_b128 v[166:169], v86 offset:20480
	v_mfma_f32_16x16x32_f16 v[88:91], v[190:193], v[194:197], v[104:107]
	s_nop 2
	ds_read_b128 v[104:107], v86 offset:16384
	ds_read_b128 v[190:193], v87 offset:53248
	v_mfma_f32_16x16x32_f16 v[108:111], v[198:201], v[124:127], v[108:111]
	ds_read_b128 v[124:127], v86 offset:18432
	v_mfma_f32_16x16x32_f16 v[92:95], v[198:201], v[194:197], v[112:115]
	s_nop 2
	ds_read_b128 v[112:115], v87 offset:49152
	ds_read_b128 v[194:197], v86 offset:22528
	ds_read_b128 v[198:201], v87 offset:55296
	s_waitcnt lgkmcnt(0)
	s_barrier
	ds_read_b128 v[0:3], v84
	ds_read_b128 v[4:7], v85 offset:32768
	ds_read_b128 v[8:11], v84 offset:2048
	ds_read_b128 v[12:15], v85 offset:34816
	ds_read_b128 v[16:19], v84 offset:4096
	ds_read_b128 v[20:23], v85 offset:36864
	ds_read_b128 v[24:27], v84 offset:6144
	ds_read_b128 v[28:31], v85 offset:38912
	v_mfma_f32_16x16x32_f16 v[128:131], v[112:115], v[104:107], v[128:131]
	v_mfma_f32_16x16x32_f16 v[132:135], v[162:165], v[104:107], v[132:135]
	v_mfma_f32_16x16x32_f16 v[136:139], v[190:193], v[104:107], v[136:139]
	v_mfma_f32_16x16x32_f16 v[64:67], v[198:201], v[104:107], v[64:67]
	v_mfma_f32_16x16x32_f16 v[104:107], v[112:115], v[124:127], v[116:119]
	v_mfma_f32_16x16x32_f16 v[116:119], v[162:165], v[124:127], v[140:143]
	v_mfma_f32_16x16x32_f16 v[140:143], v[190:193], v[124:127], v[144:147]
	v_mfma_f32_16x16x32_f16 v[72:75], v[198:201], v[124:127], v[72:75]
	v_mfma_f32_16x16x32_f16 v[98:101], v[112:115], v[166:169], v[98:101]
	v_mfma_f32_16x16x32_f16 v[124:127], v[162:165], v[166:169], v[154:157]
	v_mfma_f32_16x16x32_f16 v[144:147], v[190:193], v[166:169], v[158:161]
	v_mfma_f32_16x16x32_f16 v[108:111], v[198:201], v[166:169], v[108:111]
	v_mfma_f32_16x16x32_f16 v[68:71], v[112:115], v[194:197], v[68:71]
	v_mfma_f32_16x16x32_f16 v[76:79], v[162:165], v[194:197], v[76:79]
	v_mfma_f32_16x16x32_f16 v[88:91], v[190:193], v[194:197], v[88:91]
	v_mfma_f32_16x16x32_f16 v[92:95], v[198:201], v[194:197], v[92:95]
	s_waitcnt lgkmcnt(6)
	v_mfma_f32_16x16x32_f16 v[112:115], v[4:7], v[0:3], v[128:131]
	s_waitcnt lgkmcnt(4)
	v_mfma_f32_16x16x32_f16 v[128:131], v[12:15], v[0:3], v[132:135]
	s_waitcnt lgkmcnt(2)
; #define GL_LOAD(s_, kt_) if (VAR != 1) { a##s_##0 = GL_A(0, kt_); a##s_##1 = GL_A(1, kt_); a##s_##2 = GL_A(2, kt_); a##s_##3 = GL_A(3, kt_); b##s_##0 = GL_B(0, kt_); b##s_##1 = GL_B(1, kt_); b##s_##2 = GL_B(2, kt_); b##s_##3 = GL_B(3, kt_); }
; #define LDS_STORE(s_, buf_) if (VAR != 2) { LDS_ST1(sA, 0, buf_, a##s_##0) LDS_ST1(sA, 1, buf_, a##s_##1) LDS_ST1(sA, 2, buf_, a##s_##2) LDS_ST1(sA, 3, buf_, a##s_##3) LDS_ST1(sB, 0, buf_, b##s_##0) LDS_ST1(sB, 1, buf_, b##s_##1) LDS_ST1(sB, 2, buf_, b##s_##2) LDS_ST1(sB, 3, buf_, b##s_##3) }
;     ...
;   GL_LOAD(0, 0)
;   GL_LOAD(1, 1)
;   LDS_STORE(0, 0)
;   if (VAR != 4) __syncthreads();
; #pragma unroll
;   for (int kt = 0; kt < nk; kt += 2) {
;     if (kt + 2 < nk) { GL_LOAD(0, kt + 2) }
;     MMA_TILE(0)
;     LDS_STORE(1, 1)
;     if (VAR != 4) __syncthreads();
;     if (kt + 3 < nk) { GL_LOAD(1, kt + 3) }
;     MMA_TILE(1)
;     if (kt + 2 < nk) { LDS_STORE(0, 0) }
;     if (VAR != 4) __syncthreads();
	v_mfma_f32_16x16x32_f16 v[132:135], v[20:23], v[0:3], v[136:139]
	s_waitcnt lgkmcnt(0)
	v_mfma_f32_16x16x32_f16 v[0:3], v[28:31], v[0:3], v[64:67]
	v_mfma_f32_16x16x32_f16 v[64:67], v[4:7], v[8:11], v[104:107]
	v_mfma_f32_16x16x32_f16 v[104:107], v[12:15], v[8:11], v[116:119]
	v_mfma_f32_16x16x32_f16 v[116:119], v[20:23], v[8:11], v[140:143]
	v_mfma_f32_16x16x32_f16 v[8:11], v[28:31], v[8:11], v[72:75]
	v_mfma_f32_16x16x32_f16 v[72:75], v[4:7], v[16:19], v[98:101]
	v_mfma_f32_16x16x32_f16 v[98:101], v[12:15], v[16:19], v[124:127]
	v_mfma_f32_16x16x32_f16 v[124:127], v[20:23], v[16:19], v[144:147]
	v_mfma_f32_16x16x32_f16 v[16:19], v[28:31], v[16:19], v[108:111]
	v_mfma_f32_16x16x32_f16 v[4:7], v[4:7], v[24:27], v[68:71]
	v_mfma_f32_16x16x32_f16 v[12:15], v[12:15], v[24:27], v[76:79]
	v_mfma_f32_16x16x32_f16 v[20:23], v[20:23], v[24:27], v[88:91]
	v_mfma_f32_16x16x32_f16 v[24:27], v[28:31], v[24:27], v[92:95]
	ds_read_b128 v[28:31], v86
	ds_read_b128 v[68:71], v87 offset:32768
	ds_read_b128 v[76:79], v86 offset:2048
	ds_read_b128 v[88:91], v87 offset:34816
	ds_read_b128 v[92:95], v86 offset:4096
	ds_read_b128 v[108:111], v87 offset:36864
	ds_read_b128 v[136:139], v86 offset:6144
	ds_read_b128 v[140:143], v87 offset:38912
	s_waitcnt vmcnt(7)
	ds_write_b128 v80, v[32:35] offset:16384
	s_waitcnt vmcnt(6)
	ds_write_b128 v81, v[36:39] offset:16384
	s_waitcnt vmcnt(5)
	ds_write_b128 v82, v[40:43] offset:16384
	s_waitcnt vmcnt(4)
	ds_write_b128 v83, v[44:47] offset:16384
	s_waitcnt vmcnt(3)
	ds_write_b128 v80, v[48:51] offset:49152
	s_waitcnt vmcnt(2)
	ds_write_b128 v81, v[52:55] offset:49152
	s_waitcnt vmcnt(1)
	ds_write_b128 v82, v[56:59] offset:49152
	s_waitcnt vmcnt(0)
	ds_write_b128 v83, v[60:63] offset:49152
	s_waitcnt lgkmcnt(0)
	s_barrier
	ds_read_b128 v[32:35], v84 offset:16384
	ds_read_b128 v[36:39], v85 offset:49152
	ds_read_b128 v[40:43], v84 offset:18432
	ds_read_b128 v[44:47], v85 offset:51200
	ds_read_b128 v[48:51], v84 offset:20480
	ds_read_b128 v[52:55], v85 offset:53248
	ds_read_b128 v[56:59], v84 offset:22528
	ds_read_b128 v[60:63], v85 offset:55296
	v_mfma_f32_16x16x32_f16 v[112:115], v[68:71], v[28:31], v[112:115]
	v_mfma_f32_16x16x32_f16 v[128:131], v[88:91], v[28:31], v[128:131]
	v_mfma_f32_16x16x32_f16 v[132:135], v[108:111], v[28:31], v[132:135]
	v_mfma_f32_16x16x32_f16 v[0:3], v[140:143], v[28:31], v[0:3]
	v_mfma_f32_16x16x32_f16 v[28:31], v[68:71], v[76:79], v[64:67]
	v_mfma_f32_16x16x32_f16 v[64:67], v[88:91], v[76:79], v[104:107]
	v_mfma_f32_16x16x32_f16 v[104:107], v[108:111], v[76:79], v[116:119]
	v_mfma_f32_16x16x32_f16 v[8:11], v[140:143], v[76:79], v[8:11]
	v_mfma_f32_16x16x32_f16 v[72:75], v[68:71], v[92:95], v[72:75]
	v_mfma_f32_16x16x32_f16 v[76:79], v[88:91], v[92:95], v[98:101]
	v_mfma_f32_16x16x32_f16 v[98:101], v[108:111], v[92:95], v[124:127]
	v_mfma_f32_16x16x32_f16 v[16:19], v[140:143], v[92:95], v[16:19]
	v_mfma_f32_16x16x32_f16 v[4:7], v[68:71], v[136:139], v[4:7]
	v_mfma_f32_16x16x32_f16 v[12:15], v[88:91], v[136:139], v[12:15]
	v_mfma_f32_16x16x32_f16 v[20:23], v[108:111], v[136:139], v[20:23]
	v_mfma_f32_16x16x32_f16 v[24:27], v[140:143], v[136:139], v[24:27]
	s_waitcnt lgkmcnt(6)
	v_mfma_f32_16x16x32_f16 v[68:71], v[36:39], v[32:35], v[112:115]
	s_waitcnt lgkmcnt(4)
	v_mfma_f32_16x16x32_f16 v[80:83], v[44:47], v[32:35], v[128:131]
	s_waitcnt lgkmcnt(2)
	v_mfma_f32_16x16x32_f16 v[88:91], v[52:55], v[32:35], v[132:135]
	s_waitcnt lgkmcnt(0)
	v_mfma_f32_16x16x32_f16 v[0:3], v[60:63], v[32:35], v[0:3]
	v_mfma_f32_16x16x32_f16 v[28:31], v[36:39], v[40:43], v[28:31]
	v_mfma_f32_16x16x32_f16 v[32:35], v[44:47], v[40:43], v[64:67]
	v_mfma_f32_16x16x32_f16 v[64:67], v[52:55], v[40:43], v[104:107]
	v_mfma_f32_16x16x32_f16 v[8:11], v[60:63], v[40:43], v[8:11]
	v_mfma_f32_16x16x32_f16 v[40:43], v[36:39], v[48:51], v[72:75]
	v_mfma_f32_16x16x32_f16 v[72:75], v[44:47], v[48:51], v[76:79]
	v_mfma_f32_16x16x32_f16 v[76:79], v[52:55], v[48:51], v[98:101]
	v_mfma_f32_16x16x32_f16 v[16:19], v[60:63], v[48:51], v[16:19]
	v_mfma_f32_16x16x32_f16 v[4:7], v[36:39], v[56:59], v[4:7]
	v_mfma_f32_16x16x32_f16 v[12:15], v[44:47], v[56:59], v[12:15]
	v_mfma_f32_16x16x32_f16 v[20:23], v[52:55], v[56:59], v[20:23]
	v_mfma_f32_16x16x32_f16 v[24:27], v[60:63], v[56:59], v[24:27]
	ds_read_b128 v[36:39], v86 offset:16384
	ds_read_b128 v[44:47], v87 offset:49152
	ds_read_b128 v[48:51], v86 offset:18432
	ds_read_b128 v[52:55], v87 offset:51200
	ds_read_b128 v[56:59], v86 offset:20480
	ds_read_b128 v[60:63], v87 offset:53248
	ds_read_b128 v[92:95], v86 offset:22528
	ds_read_b128 v[84:87], v87 offset:55296
	s_waitcnt lgkmcnt(0)
	s_barrier
; DI unsigned pack2(float lo, float hi) { f2_t v = {lo, hi}; h2_t b = __builtin_convertvector(v, h2_t); return __builtin_bit_cast(unsigned, b); }
; DI void load_rstd(float (&rs)[4], const float* ssq, int row0, int lr) {
; #pragma unroll
;   for (int mt = 0; mt < 4; ++mt) {
;     const float4* q = (const float4*)(ssq + (size_t)(row0 + mt * 16 + lr) * 16);
;     const float4 a = q[0], b = q[1], c = q[2], d = q[3];
;     const float s = ((a.x + a.y) + (a.z + a.w)) + ((b.x + b.y) + (b.z + b.w)) + ((c.x + c.y) + (c.z + c.w)) + ((d.x + d.y) + (d.z + d.w));
;     rs[mt] = rsqrtf(s * (1.0f / 1024.0f) + EPS);
;   }
; }
; DI void phase_ple(const Params& P, int l, char* smem) {
;     ...
; #pragma unroll
;       for (int mt = 0; mt < 4; ++mt)
; #pragma unroll
;         for (int h = 0; h < 2; ++h)
;           park[mt * 2 + h] = make_uint4(pack2(pp[mt][2 * h][0], pp[mt][2 * h][1]), pack2(pp[mt][2 * h][2], pp[mt][2 * h][3]), pack2(pp[mt][2 * h + 1][0], pp[mt][2 * h + 1][1]), pack2(pp[mt][2 * h + 1][2], pp[mt][2 * h + 1][3]));
;     }
;     f32x4 acc[4][4]; zero_acc(acc);
;     float rs[4]; load_rstd(rs, ssq, row0, lr);
	v_mfma_f32_16x16x32_f16 v[68:71], v[44:47], v[36:39], v[68:71]
	v_mfma_f32_16x16x32_f16 v[80:83], v[52:55], v[36:39], v[80:83]
	v_mfma_f32_16x16x32_f16 v[0:3], v[84:87], v[36:39], v[0:3]
	v_mfma_f32_16x16x32_f16 v[28:31], v[44:47], v[48:51], v[28:31]
	v_mfma_f32_16x16x32_f16 v[32:35], v[52:55], v[48:51], v[32:35]
	v_mfma_f32_16x16x32_f16 v[88:91], v[60:63], v[36:39], v[88:91]
	v_mfma_f32_16x16x32_f16 v[36:39], v[60:63], v[48:51], v[64:67]
	v_mfma_f32_16x16x32_f16 v[8:11], v[84:87], v[48:51], v[8:11]
	v_mfma_f32_16x16x32_f16 v[40:43], v[44:47], v[56:59], v[40:43]
	v_mfma_f32_16x16x32_f16 v[48:51], v[52:55], v[56:59], v[72:75]
	v_mfma_f32_16x16x32_f16 v[64:67], v[60:63], v[56:59], v[76:79]
	s_nop 1
	v_mov_b32_e32 v72, v148
	v_mfma_f32_16x16x32_f16 v[16:19], v[84:87], v[56:59], v[16:19]
	v_mfma_f32_16x16x32_f16 v[4:7], v[44:47], v[92:95], v[4:7]
	v_cvt_pk_f16_f32 v44, v68, v69
	v_cvt_pk_f16_f32 v45, v70, v71
	v_cvt_pk_f16_f32 v46, v80, v81
	v_cvt_pk_f16_f32 v47, v82, v83
	v_mfma_f32_16x16x32_f16 v[12:15], v[52:55], v[92:95], v[12:15]
	global_store_dwordx4 v[102:103], v[44:47], off
	s_nop 1
	v_cvt_pk_f16_f32 v46, v0, v1
	v_cvt_pk_f16_f32 v47, v2, v3
	v_cvt_pk_f16_f32 v0, v28, v29
	v_cvt_pk_f16_f32 v1, v30, v31
	v_cvt_pk_f16_f32 v2, v32, v33
	v_cvt_pk_f16_f32 v3, v34, v35
	v_mfma_f32_16x16x32_f16 v[20:23], v[60:63], v[92:95], v[20:23]
	global_store_dwordx4 v[102:103], v[0:3], off offset:32
	v_cvt_pk_f16_f32 v44, v88, v89
	v_cvt_pk_f16_f32 v45, v90, v91
	v_mfma_f32_16x16x32_f16 v[24:27], v[84:87], v[92:95], v[24:27]
	v_cvt_pk_f16_f32 v0, v36, v37
	v_cvt_pk_f16_f32 v1, v38, v39
	v_cvt_pk_f16_f32 v2, v8, v9
	v_cvt_pk_f16_f32 v3, v10, v11
	global_store_dwordx4 v[102:103], v[0:3], off offset:48
	global_store_dwordx4 v[102:103], v[44:47], off offset:16
	s_nop 0
	v_cvt_pk_f16_f32 v0, v40, v41
	v_cvt_pk_f16_f32 v1, v42, v43
	v_cvt_pk_f16_f32 v2, v48, v49
	v_cvt_pk_f16_f32 v3, v50, v51
	global_store_dwordx4 v[102:103], v[0:3], off offset:64
	s_nop 1
	v_cvt_pk_f16_f32 v0, v64, v65
	v_cvt_pk_f16_f32 v1, v66, v67
	v_cvt_pk_f16_f32 v2, v16, v17
	v_cvt_pk_f16_f32 v3, v18, v19
	global_store_dwordx4 v[102:103], v[0:3], off offset:80
	s_nop 1
	v_cvt_pk_f16_f32 v0, v4, v5
	v_cvt_pk_f16_f32 v1, v6, v7
	v_cvt_pk_f16_f32 v2, v12, v13
	v_cvt_pk_f16_f32 v3, v14, v15
	global_store_dwordx4 v[102:103], v[0:3], off offset:96
	s_nop 1
	v_cvt_pk_f16_f32 v0, v20, v21
	v_cvt_pk_f16_f32 v1, v22, v23
	v_cvt_pk_f16_f32 v2, v24, v25
	v_cvt_pk_f16_f32 v3, v26, v27
	global_store_dwordx4 v[102:103], v[0:3], off offset:112
	s_nop 1
	v_or_b32_e32 v0, v123, v121
	v_ashrrev_i32_e32 v1, 31, v0
	v_lshlrev_b64 v[2:3], 6, v[0:1]
	v_lshl_add_u64 v[14:15], s[16:17], 0, v[2:3]
	global_load_dwordx4 v[2:5], v[14:15], off offset:32
	global_load_dwordx4 v[6:9], v[14:15], off offset:16
	global_load_dwordx4 v[10:13], v[14:15], off
	s_nop 0
	global_load_dwordx4 v[14:17], v[14:15], off offset:48
	s_waitcnt vmcnt(2)
	v_mov_b32_e32 v20, v7
	s_waitcnt vmcnt(1)
	v_mov_b32_e32 v18, v11
	v_mov_b32_e32 v19, v12
	v_mov_b32_e32 v21, v8
	v_mov_b32_e32 v11, v13
	v_mov_b32_e32 v7, v9
	v_mov_b32_e32 v8, v3
	v_pk_add_f32 v[10:11], v[18:19], v[10:11]
	v_pk_add_f32 v[6:7], v[20:21], v[6:7]
	v_pk_add_f32 v[2:3], v[2:3], v[8:9]
	v_mov_b32_e32 v8, v5
	v_pk_add_f32 v[10:11], v[10:11], v[10:11] op_sel:[0,1] op_sel_hi:[1,0]
	v_pk_add_f32 v[6:7], v[6:7], v[6:7] op_sel:[0,1] op_sel_hi:[1,0]
	v_pk_add_f32 v[4:5], v[4:5], v[8:9]
	s_waitcnt vmcnt(0)
	v_mov_b32_e32 v11, v14
	v_mov_b32_e32 v7, v15
	v_mov_b32_e32 v3, v16
	v_mov_b32_e32 v5, v17
	v_pk_add_f32 v[6:7], v[10:11], v[6:7]
	v_pk_add_f32 v[2:3], v[2:3], v[4:5]
	s_nop 0
	v_pk_add_f32 v[18:19], v[6:7], v[2:3]
	v_or_b32_e32 v2, 16, v0
	v_ashrrev_i32_e32 v3, 31, v2
	v_lshlrev_b64 v[2:3], 6, v[2:3]
	v_lshl_add_u64 v[14:15], s[16:17], 0, v[2:3]
	global_load_dwordx4 v[2:5], v[14:15], off offset:32
	global_load_dwordx4 v[6:9], v[14:15], off offset:16
	global_load_dwordx4 v[10:13], v[14:15], off
	s_nop 0
	global_load_dwordx4 v[14:17], v[14:15], off offset:48
	s_waitcnt vmcnt(2)
	v_mov_b32_e32 v22, v7
	s_waitcnt vmcnt(1)
	v_mov_b32_e32 v20, v11
	v_mov_b32_e32 v21, v12
	v_mov_b32_e32 v23, v8
	v_mov_b32_e32 v11, v13
	v_mov_b32_e32 v7, v9
	v_mov_b32_e32 v8, v3
	v_pk_add_f32 v[10:11], v[20:21], v[10:11]
	v_pk_add_f32 v[6:7], v[22:23], v[6:7]
	v_pk_add_f32 v[2:3], v[2:3], v[8:9]
	v_mov_b32_e32 v8, v5
	v_pk_add_f32 v[10:11], v[10:11], v[10:11] op_sel:[0,1] op_sel_hi:[1,0]
	v_pk_add_f32 v[6:7], v[6:7], v[6:7] op_sel:[0,1] op_sel_hi:[1,0]
	v_pk_add_f32 v[4:5], v[4:5], v[8:9]
	s_waitcnt vmcnt(0)
	v_mov_b32_e32 v11, v14
	v_mov_b32_e32 v7, v15
	v_mov_b32_e32 v3, v16
	v_mov_b32_e32 v5, v17
	v_pk_add_f32 v[6:7], v[10:11], v[6:7]
	v_pk_add_f32 v[2:3], v[2:3], v[4:5]
	v_mov_b32_e32 v5, v18
	v_pk_add_f32 v[2:3], v[6:7], v[2:3]
	s_nop 0
	v_mov_b32_e32 v4, v2
	v_mov_b32_e32 v18, v3
	v_pk_add_f32 v[4:5], v[4:5], v[18:19]
	v_mov_b64_e32 v[2:3], s[18:19]
	s_mov_b32 s18, 0x3a800000
	v_pk_fma_f32 v[100:101], v[4:5], s[18:19], v[2:3] op_sel_hi:[1,0,0]
	s_nop 0
	v_mul_f32_e32 v1, 0x4b800000, v101
	v_cmp_gt_f32_e32 vcc, s1, v101
	v_cmp_gt_f32_e64 s[44:45], s1, v100
	s_nop 0
	v_cndmask_b32_e32 v1, v101, v1, vcc
	v_rsq_f32_e32 v1, v1
	s_nop 0
	v_mul_f32_e32 v4, 0x45800000, v1
	v_cndmask_b32_e32 v101, v1, v4, vcc
	v_or_b32_e32 v4, 32, v0
	v_ashrrev_i32_e32 v5, 31, v4
	v_lshlrev_b64 v[4:5], 6, v[4:5]
	v_lshl_add_u64 v[16:17], s[16:17], 0, v[4:5]
	global_load_dwordx4 v[4:7], v[16:17], off offset:32
	global_load_dwordx4 v[8:11], v[16:17], off offset:16
	global_load_dwordx4 v[12:15], v[16:17], off
	s_nop 0
	global_load_dwordx4 v[16:19], v[16:17], off offset:48
	v_or_b32_e32 v0, 48, v0
	v_ashrrev_i32_e32 v1, 31, v0
	v_lshlrev_b64 v[0:1], 6, v[0:1]
	v_lshl_add_u64 v[0:1], s[16:17], 0, v[0:1]
	v_readlane_b32 s16, v254, 43
	v_readlane_b32 s17, v254, 44
	s_add_u32 s6, s16, s6
	s_addc_u32 s7, s17, s7
	s_waitcnt vmcnt(2)
; DI int TIDX() { int t = threadIdx.x; asm volatile("" : "+v"(t)); return t; }
; #define GL_LOAD(s_, kt_) if (VAR != 1) { a##s_##0 = GL_A(0, kt_); a##s_##1 = GL_A(1, kt_); a##s_##2 = GL_A(2, kt_); a##s_##3 = GL_A(3, kt_); b##s_##0 = GL_B(0, kt_); b##s_##1 = GL_B(1, kt_); b##s_##2 = GL_B(2, kt_); b##s_##3 = GL_B(3, kt_); }
; #define LDS_STORE(s_, buf_) if (VAR != 2) { LDS_ST1(sA, 0, buf_, a##s_##0) LDS_ST1(sA, 1, buf_, a##s_##1) LDS_ST1(sA, 2, buf_, a##s_##2) LDS_ST1(sA, 3, buf_, a##s_##3) LDS_ST1(sB, 0, buf_, b##s_##0) LDS_ST1(sB, 1, buf_, b##s_##1) LDS_ST1(sB, 2, buf_, b##s_##2) LDS_ST1(sB, 3, buf_, b##s_##3) }
;   const int tid = TIDX(), lane = tid & 63, wid = tid >> 6, wm = wid >> 1, wn = wid & 1, lr = lane & 15, g = lane >> 4;
;   char* sA = smem; char* sB = smem + 2 * LTILE;
;   uint4 a00 = {}, a01 = {}, a02 = {}, a03 = {}, b00 = {}, b01 = {}, b02 = {}, b03 = {}, a10 = {}, a11 = {}, a12 = {}, a13 = {}, b10 = {}, b11 = {}, b12 = {}, b13 = {};
;   constexpr int nk = NK;
;   const int sw0 = (g ^ ((lr >> 1) & 7)) << 4, sw1 = sw0 ^ 64;
;   const int r0 = tid >> 3, kc = tid & 7, kcs = kc ^ ((r0 >> 1) & 7);
;     ...
;   GL_LOAD(0, 0)
;   GL_LOAD(1, 1)
;   LDS_STORE(0, 0)
;   if (VAR != 4) __syncthreads();
; DI void load_rstd(float (&rs)[4], const float* ssq, int row0, int lr) {
; #pragma unroll
;   for (int mt = 0; mt < 4; ++mt) {
;     const float4* q = (const float4*)(ssq + (size_t)(row0 + mt * 16 + lr) * 16);
;     const float4 a = q[0], b = q[1], c = q[2], d = q[3];
;     const float s = ((a.x + a.y) + (a.z + a.w)) + ((b.x + b.y) + (b.z + b.w)) + ((c.x + c.y) + (c.z + c.w)) + ((d.x + d.y) + (d.z + d.w));
;     rs[mt] = rsqrtf(s * (1.0f / 1024.0f) + EPS);
;   }
; }
	v_mov_b32_e32 v22, v9
	s_waitcnt vmcnt(1)
	v_mov_b32_e32 v20, v13
	v_mov_b32_e32 v21, v14
	v_mov_b32_e32 v23, v10
	v_mov_b32_e32 v13, v15
	v_mov_b32_e32 v9, v11
	v_mov_b32_e32 v10, v5
	v_pk_add_f32 v[12:13], v[20:21], v[12:13]
	v_pk_add_f32 v[8:9], v[22:23], v[8:9]
	v_pk_add_f32 v[4:5], v[4:5], v[10:11]
	v_mov_b32_e32 v10, v7
	v_pk_add_f32 v[12:13], v[12:13], v[12:13] op_sel:[0,1] op_sel_hi:[1,0]
	v_pk_add_f32 v[8:9], v[8:9], v[8:9] op_sel:[0,1] op_sel_hi:[1,0]
	v_pk_add_f32 v[6:7], v[6:7], v[10:11]
	s_waitcnt vmcnt(0)
	v_mov_b32_e32 v13, v16
	v_mov_b32_e32 v9, v17
	v_mov_b32_e32 v5, v18
	v_mov_b32_e32 v7, v19
	v_pk_add_f32 v[8:9], v[12:13], v[8:9]
	v_pk_add_f32 v[4:5], v[4:5], v[6:7]
	s_nop 0
	v_pk_add_f32 v[20:21], v[8:9], v[4:5]
	global_load_dwordx4 v[4:7], v[0:1], off offset:32
	global_load_dwordx4 v[8:11], v[0:1], off offset:16
	global_load_dwordx4 v[12:15], v[0:1], off
	global_load_dwordx4 v[16:19], v[0:1], off offset:48
	s_waitcnt vmcnt(2)
	v_mov_b32_e32 v22, v9
	s_waitcnt vmcnt(1)
	v_mov_b32_e32 v0, v13
	v_mov_b32_e32 v1, v14
	v_mov_b32_e32 v23, v10
	v_mov_b32_e32 v13, v15
	v_mov_b32_e32 v9, v11
	v_mov_b32_e32 v10, v5
	v_pk_add_f32 v[0:1], v[0:1], v[12:13]
	v_pk_add_f32 v[8:9], v[22:23], v[8:9]
	v_pk_add_f32 v[4:5], v[4:5], v[10:11]
	v_mov_b32_e32 v10, v7
	v_pk_add_f32 v[0:1], v[0:1], v[0:1] op_sel:[0,1] op_sel_hi:[1,0]
	v_pk_add_f32 v[8:9], v[8:9], v[8:9] op_sel:[0,1] op_sel_hi:[1,0]
	v_pk_add_f32 v[6:7], v[6:7], v[10:11]
	s_waitcnt vmcnt(0)
	v_mov_b32_e32 v1, v16
	v_mov_b32_e32 v9, v17
	v_mov_b32_e32 v5, v18
	v_mov_b32_e32 v7, v19
	v_pk_add_f32 v[0:1], v[0:1], v[8:9]
	v_pk_add_f32 v[4:5], v[4:5], v[6:7]
	v_ashrrev_i32_e32 v64, 3, v72
	v_pk_add_f32 v[0:1], v[0:1], v[4:5]
	v_mov_b32_e32 v5, v20
	v_mov_b32_e32 v4, v0
	v_mov_b32_e32 v20, v1
	v_pk_add_f32 v[0:1], v[4:5], v[20:21]
	v_ashrrev_i32_e32 v65, 31, v64
	v_pk_fma_f32 v[98:99], v[0:1], s[18:19], v[2:3] op_sel_hi:[1,0,0]
	v_lshlrev_b32_e32 v0, 3, v72
	v_and_b32_e32 v75, 48, v72
	v_lshlrev_b64 v[16:17], 11, v[64:65]
	v_lshlrev_b32_e32 v65, 4, v72
	v_and_b32_e32 v74, 0x70, v0
	v_bitop3_b32 v129, v0, v75, s23 bitop3:0x6c
	v_lshl_add_u64 v[0:1], s[6:7], 0, v[16:17]
	v_and_b32_e32 v150, 0x70, v65
	v_add_u32_e32 v66, 32, v64
	v_add_u32_e32 v68, 64, v64
	v_add_u32_e32 v70, 0x60, v64
	v_cmp_gt_f32_e64 s[38:39], s1, v98
	v_cmp_gt_f32_e64 s[40:41], s1, v99
	s_lshl_b32 s1, s2, 11
	v_lshl_add_u64 v[104:105], v[0:1], 0, v[150:151]
	v_ashrrev_i32_e32 v67, 31, v66
	v_ashrrev_i32_e32 v69, 31, v68
	v_ashrrev_i32_e32 v71, 31, v70
	s_add_u32 s16, s11, s1
	global_load_dwordx4 v[0:3], v[104:105], off
	v_lshlrev_b64 v[20:21], 11, v[66:67]
	v_lshlrev_b64 v[24:25], 11, v[68:69]
	v_lshlrev_b64 v[28:29], 11, v[70:71]
	s_addc_u32 s17, s12, 0
	v_lshl_add_u64 v[4:5], s[6:7], 0, v[20:21]
	v_lshl_add_u64 v[8:9], s[6:7], 0, v[24:25]
	v_lshl_add_u64 v[12:13], s[6:7], 0, v[28:29]
	v_lshl_add_u64 v[106:107], v[4:5], 0, v[150:151]
	v_lshl_add_u64 v[108:109], v[8:9], 0, v[150:151]
	v_lshl_add_u64 v[110:111], v[12:13], 0, v[150:151]
	v_lshl_add_u64 v[16:17], s[16:17], 0, v[16:17]
	global_load_dwordx4 v[4:7], v[106:107], off
	global_load_dwordx4 v[8:11], v[108:109], off
	global_load_dwordx4 v[12:15], v[110:111], off
	v_lshl_add_u64 v[112:113], v[16:17], 0, v[150:151]
	v_lshl_add_u64 v[20:21], s[16:17], 0, v[20:21]
	global_load_dwordx4 v[16:19], v[112:113], off
	v_lshl_add_u64 v[114:115], v[20:21], 0, v[150:151]
	v_lshl_add_u64 v[24:25], s[16:17], 0, v[24:25]
	global_load_dwordx4 v[20:23], v[114:115], off
	v_lshl_add_u64 v[116:117], v[24:25], 0, v[150:151]
	global_load_dwordx4 v[24:27], v[116:117], off
	v_lshl_add_u64 v[28:29], s[16:17], 0, v[28:29]
	v_lshl_add_u64 v[118:119], v[28:29], 0, v[150:151]
	global_load_dwordx4 v[28:31], v[118:119], off
	global_load_dwordx4 v[32:35], v[104:105], off offset:128
	global_load_dwordx4 v[36:39], v[106:107], off offset:128
	global_load_dwordx4 v[40:43], v[108:109], off offset:128
	global_load_dwordx4 v[44:47], v[110:111], off offset:128
	global_load_dwordx4 v[48:51], v[112:113], off offset:128
	global_load_dwordx4 v[52:55], v[114:115], off offset:128
	global_load_dwordx4 v[56:59], v[116:117], off offset:128
	global_load_dwordx4 v[60:63], v[118:119], off offset:128
	v_bitop3_b32 v65, v65, s23, v72 bitop3:0x48
	v_lshl_or_b32 v126, v64, 7, v65
	v_and_b32_e32 v73, 15, v72
	v_lshl_or_b32 v124, v66, 7, v65
	v_lshl_or_b32 v125, v68, 7, v65
	v_lshl_or_b32 v127, v70, 7, v65
	v_xor_b32_e32 v130, 64, v129
	v_readlane_b32 s16, v254, 55
	v_readlane_b32 s6, v253, 11
	v_readlane_b32 s17, v254, 56
	v_readlane_b32 s7, v253, 12
	v_readlane_b32 s18, v254, 57
	v_readlane_b32 s19, v254, 58
	s_waitcnt vmcnt(15)
	ds_write_b128 v126, v[0:3]
	v_lshrrev_b32_e32 v0, 1, v72
	v_and_or_b32 v0, v0, s24, v73
	v_lshlrev_b32_e32 v150, 7, v0
	v_lshlrev_b32_e32 v0, 7, v72
	v_and_b32_e32 v170, 0x2780, v0
	v_bitop3_b32 v128, v150, v74, v75 bitop3:0xf6
	v_or_b32_e32 v131, v170, v129
	v_bitop3_b32 v129, v150, v129, 64 bitop3:0xf6
	v_or_b32_e32 v130, v170, v130
	s_waitcnt vmcnt(14)
	ds_write_b128 v124, v[4:7]
	s_waitcnt vmcnt(13)
	ds_write_b128 v125, v[8:11]
	s_waitcnt vmcnt(12)
	ds_write_b128 v127, v[12:15]
	s_waitcnt vmcnt(11)
	ds_write_b128 v126, v[16:19] offset:32768
	s_waitcnt vmcnt(10)
	ds_write_b128 v124, v[20:23] offset:32768
	s_waitcnt vmcnt(9)
	ds_write_b128 v125, v[24:27] offset:32768
	s_waitcnt vmcnt(8)
	ds_write_b128 v127, v[28:31] offset:32768
	s_waitcnt lgkmcnt(0)
	s_barrier
; #define GL_LOAD(s_, kt_) if (VAR != 1) { a##s_##0 = GL_A(0, kt_); a##s_##1 = GL_A(1, kt_); a##s_##2 = GL_A(2, kt_); a##s_##3 = GL_A(3, kt_); b##s_##0 = GL_B(0, kt_); b##s_##1 = GL_B(1, kt_); b##s_##2 = GL_B(2, kt_); b##s_##3 = GL_B(3, kt_); }
; #define LDS_STORE(s_, buf_) if (VAR != 2) { LDS_ST1(sA, 0, buf_, a##s_##0) LDS_ST1(sA, 1, buf_, a##s_##1) LDS_ST1(sA, 2, buf_, a##s_##2) LDS_ST1(sA, 3, buf_, a##s_##3) LDS_ST1(sB, 0, buf_, b##s_##0) LDS_ST1(sB, 1, buf_, b##s_##1) LDS_ST1(sB, 2, buf_, b##s_##2) LDS_ST1(sB, 3, buf_, b##s_##3) }
;     ...
;   GL_LOAD(0, 0)
;   GL_LOAD(1, 1)
;   LDS_STORE(0, 0)
;   if (VAR != 4) __syncthreads();
; #pragma unroll
;   for (int kt = 0; kt < nk; kt += 2) {
;     if (kt + 2 < nk) { GL_LOAD(0, kt + 2) }
;     MMA_TILE(0)
;     LDS_STORE(1, 1)
;     if (VAR != 4) __syncthreads();
;     if (kt + 3 < nk) { GL_LOAD(1, kt + 3) }
;     MMA_TILE(1)
;     if (kt + 2 < nk) { LDS_STORE(0, 0) }
;     if (VAR != 4) __syncthreads();
	global_load_dwordx4 v[0:3], v[104:105], off offset:256
	global_load_dwordx4 v[4:7], v[106:107], off offset:256
	global_load_dwordx4 v[8:11], v[108:109], off offset:256
	global_load_dwordx4 v[12:15], v[110:111], off offset:256
	global_load_dwordx4 v[16:19], v[112:113], off offset:256
	global_load_dwordx4 v[20:23], v[114:115], off offset:256
	global_load_dwordx4 v[24:27], v[116:117], off offset:256
	global_load_dwordx4 v[28:31], v[118:119], off offset:256
	ds_read_b128 v[64:67], v128
	ds_read_b128 v[68:71], v131 offset:32768
	ds_read_b128 v[72:75], v128 offset:2048
	ds_read_b128 v[76:79], v131 offset:34816
	ds_read_b128 v[80:83], v128 offset:4096
	ds_read_b128 v[84:87], v131 offset:36864
	ds_read_b128 v[88:91], v128 offset:6144
	ds_read_b128 v[92:95], v131 offset:38912
	s_waitcnt lgkmcnt(6)
	v_mfma_f32_16x16x32_f16 v[132:135], v[68:71], v[64:67], 0
	s_waitcnt lgkmcnt(4)
	v_mfma_f32_16x16x32_f16 v[136:139], v[76:79], v[64:67], 0
	s_waitcnt lgkmcnt(2)
	v_mfma_f32_16x16x32_f16 v[140:143], v[84:87], v[64:67], 0
	s_waitcnt lgkmcnt(0)
	v_mfma_f32_16x16x32_f16 v[64:67], v[92:95], v[64:67], 0
	v_mfma_f32_16x16x32_f16 v[144:147], v[68:71], v[72:75], 0
	v_mfma_f32_16x16x32_f16 v[154:157], v[76:79], v[72:75], 0
	v_mfma_f32_16x16x32_f16 v[158:161], v[84:87], v[72:75], 0
	v_mfma_f32_16x16x32_f16 v[72:75], v[92:95], v[72:75], 0
	v_mfma_f32_16x16x32_f16 v[162:165], v[68:71], v[80:83], 0
	v_mfma_f32_16x16x32_f16 v[166:169], v[76:79], v[80:83], 0
	v_mfma_f32_16x16x32_f16 v[190:193], v[84:87], v[80:83], 0
	v_mfma_f32_16x16x32_f16 v[80:83], v[92:95], v[80:83], 0
	v_mfma_f32_16x16x32_f16 v[68:71], v[68:71], v[88:91], 0
	v_mfma_f32_16x16x32_f16 v[76:79], v[76:79], v[88:91], 0
	v_mfma_f32_16x16x32_f16 v[84:87], v[84:87], v[88:91], 0
	v_mfma_f32_16x16x32_f16 v[88:91], v[92:95], v[88:91], 0
	ds_read_b128 v[92:95], v129
	ds_read_b128 v[194:197], v130 offset:32768
	ds_read_b128 v[198:201], v129 offset:2048
	ds_read_b128 v[202:205], v130 offset:34816
	ds_read_b128 v[206:209], v129 offset:4096
	ds_read_b128 v[210:213], v130 offset:36864
	ds_read_b128 v[220:223], v129 offset:6144
	ds_read_b128 v[224:227], v130 offset:38912
	s_waitcnt vmcnt(15)
	ds_write_b128 v126, v[32:35] offset:16384
	s_waitcnt vmcnt(14)
	ds_write_b128 v124, v[36:39] offset:16384
	s_waitcnt vmcnt(13)
	ds_write_b128 v125, v[40:43] offset:16384
	s_waitcnt vmcnt(12)
	ds_write_b128 v127, v[44:47] offset:16384
	s_waitcnt vmcnt(11)
	ds_write_b128 v126, v[48:51] offset:49152
	s_waitcnt vmcnt(10)
	ds_write_b128 v124, v[52:55] offset:49152
	s_waitcnt vmcnt(9)
	ds_write_b128 v125, v[56:59] offset:49152
	s_waitcnt vmcnt(8)
	ds_write_b128 v127, v[60:63] offset:49152
	s_waitcnt lgkmcnt(0)
	s_barrier
	v_mfma_f32_16x16x32_f16 v[132:135], v[194:197], v[92:95], v[132:135]
	global_load_dwordx4 v[32:35], v[104:105], off offset:384
	v_mfma_f32_16x16x32_f16 v[136:139], v[202:205], v[92:95], v[136:139]
	v_mfma_f32_16x16x32_f16 v[140:143], v[210:213], v[92:95], v[140:143]
	v_mfma_f32_16x16x32_f16 v[64:67], v[224:227], v[92:95], v[64:67]
	v_mfma_f32_16x16x32_f16 v[92:95], v[194:197], v[198:201], v[144:147]
	global_load_dwordx4 v[36:39], v[106:107], off offset:384
	global_load_dwordx4 v[40:43], v[108:109], off offset:384
	global_load_dwordx4 v[44:47], v[110:111], off offset:384
	v_mfma_f32_16x16x32_f16 v[144:147], v[202:205], v[198:201], v[154:157]
	global_load_dwordx4 v[48:51], v[112:113], off offset:384
	v_mfma_f32_16x16x32_f16 v[154:157], v[210:213], v[198:201], v[158:161]
	v_mfma_f32_16x16x32_f16 v[158:161], v[194:197], v[206:209], v[162:165]
	global_load_dwordx4 v[52:55], v[114:115], off offset:384
	global_load_dwordx4 v[56:59], v[116:117], off offset:384
	v_mfma_f32_16x16x32_f16 v[68:71], v[194:197], v[220:223], v[68:71]
	ds_read_b128 v[194:197], v131 offset:49152
	v_mfma_f32_16x16x32_f16 v[162:165], v[202:205], v[206:209], v[166:169]
	global_load_dwordx4 v[60:63], v[118:119], off offset:384
	v_mfma_f32_16x16x32_f16 v[76:79], v[202:205], v[220:223], v[76:79]
	ds_read_b128 v[202:205], v131 offset:51200
	v_mfma_f32_16x16x32_f16 v[72:75], v[224:227], v[198:201], v[72:75]
	ds_read_b128 v[198:201], v128 offset:18432
	v_mfma_f32_16x16x32_f16 v[166:169], v[210:213], v[206:209], v[190:193]
	s_nop 2
	ds_read_b128 v[190:193], v128 offset:16384
	v_mfma_f32_16x16x32_f16 v[84:87], v[210:213], v[220:223], v[84:87]
	ds_read_b128 v[210:213], v131 offset:53248
	v_mfma_f32_16x16x32_f16 v[80:83], v[224:227], v[206:209], v[80:83]
	ds_read_b128 v[206:209], v128 offset:20480
	v_mfma_f32_16x16x32_f16 v[88:91], v[224:227], v[220:223], v[88:91]
	ds_read_b128 v[220:223], v128 offset:22528
	s_waitcnt lgkmcnt(3)
	v_mfma_f32_16x16x32_f16 v[132:135], v[194:197], v[190:193], v[132:135]
	ds_read_b128 v[224:227], v131 offset:55296
	v_mfma_f32_16x16x32_f16 v[92:95], v[194:197], v[198:201], v[92:95]
	s_waitcnt vmcnt(15)
	ds_write_b128 v126, v[0:3]
	v_mfma_f32_16x16x32_f16 v[136:139], v[202:205], v[190:193], v[136:139]
	s_waitcnt vmcnt(14)
	ds_write_b128 v124, v[4:7]
	v_mfma_f32_16x16x32_f16 v[144:147], v[202:205], v[198:201], v[144:147]
	s_waitcnt vmcnt(13)
	ds_write_b128 v125, v[8:11]
	s_waitcnt lgkmcnt(5)
	v_mfma_f32_16x16x32_f16 v[158:161], v[194:197], v[206:209], v[158:161]
	s_waitcnt vmcnt(12)
	ds_write_b128 v127, v[12:15]
	s_waitcnt lgkmcnt(5)
	v_mfma_f32_16x16x32_f16 v[68:71], v[194:197], v[220:223], v[68:71]
	ds_read_b128 v[194:197], v130 offset:49152
	v_mfma_f32_16x16x32_f16 v[162:165], v[202:205], v[206:209], v[162:165]
	s_waitcnt vmcnt(11)
	ds_write_b128 v126, v[16:19] offset:32768
	v_mfma_f32_16x16x32_f16 v[76:79], v[202:205], v[220:223], v[76:79]
	ds_read_b128 v[202:205], v130 offset:51200
	v_mfma_f32_16x16x32_f16 v[140:143], v[210:213], v[190:193], v[140:143]
	s_waitcnt vmcnt(10)
	ds_write_b128 v124, v[20:23] offset:32768
	v_mfma_f32_16x16x32_f16 v[154:157], v[210:213], v[198:201], v[154:157]
	s_waitcnt vmcnt(9)
	ds_write_b128 v125, v[24:27] offset:32768
	s_waitcnt lgkmcnt(9)
	v_mfma_f32_16x16x32_f16 v[64:67], v[224:227], v[190:193], v[64:67]
	ds_read_b128 v[190:193], v129 offset:16384
	v_mfma_f32_16x16x32_f16 v[72:75], v[224:227], v[198:201], v[72:75]
	ds_read_b128 v[198:201], v129 offset:18432
	v_mfma_f32_16x16x32_f16 v[166:169], v[210:213], v[206:209], v[166:169]
	s_waitcnt vmcnt(8)
	ds_write_b128 v127, v[28:31] offset:32768
	v_mfma_f32_16x16x32_f16 v[84:87], v[210:213], v[220:223], v[84:87]
	ds_read_b128 v[210:213], v130 offset:53248
	v_mfma_f32_16x16x32_f16 v[80:83], v[224:227], v[206:209], v[80:83]
	ds_read_b128 v[206:209], v129 offset:20480
	v_mfma_f32_16x16x32_f16 v[88:91], v[224:227], v[220:223], v[88:91]
	ds_read_b128 v[220:223], v129 offset:22528
	ds_read_b128 v[224:227], v130 offset:55296
	s_waitcnt lgkmcnt(0)
	s_barrier
; #define GL_LOAD(s_, kt_) if (VAR != 1) { a##s_##0 = GL_A(0, kt_); a##s_##1 = GL_A(1, kt_); a##s_##2 = GL_A(2, kt_); a##s_##3 = GL_A(3, kt_); b##s_##0 = GL_B(0, kt_); b##s_##1 = GL_B(1, kt_); b##s_##2 = GL_B(2, kt_); b##s_##3 = GL_B(3, kt_); }
; #define LDS_STORE(s_, buf_) if (VAR != 2) { LDS_ST1(sA, 0, buf_, a##s_##0) LDS_ST1(sA, 1, buf_, a##s_##1) LDS_ST1(sA, 2, buf_, a##s_##2) LDS_ST1(sA, 3, buf_, a##s_##3) LDS_ST1(sB, 0, buf_, b##s_##0) LDS_ST1(sB, 1, buf_, b##s_##1) LDS_ST1(sB, 2, buf_, b##s_##2) LDS_ST1(sB, 3, buf_, b##s_##3) }
;     ...
;   GL_LOAD(0, 0)
;   GL_LOAD(1, 1)
;   LDS_STORE(0, 0)
;   if (VAR != 4) __syncthreads();
; #pragma unroll
;   for (int kt = 0; kt < nk; kt += 2) {
;     if (kt + 2 < nk) { GL_LOAD(0, kt + 2) }
;     MMA_TILE(0)
;     LDS_STORE(1, 1)
;     if (VAR != 4) __syncthreads();
;     if (kt + 3 < nk) { GL_LOAD(1, kt + 3) }
;     MMA_TILE(1)
;     if (kt + 2 < nk) { LDS_STORE(0, 0) }
;     if (VAR != 4) __syncthreads();
	v_mfma_f32_16x16x32_f16 v[132:135], v[194:197], v[190:193], v[132:135]
	global_load_dwordx4 v[0:3], v[104:105], off offset:512
	v_mfma_f32_16x16x32_f16 v[92:95], v[194:197], v[198:201], v[92:95]
	global_load_dwordx4 v[4:7], v[106:107], off offset:512
	v_mfma_f32_16x16x32_f16 v[136:139], v[202:205], v[190:193], v[136:139]
	global_load_dwordx4 v[8:11], v[108:109], off offset:512
	v_mfma_f32_16x16x32_f16 v[144:147], v[202:205], v[198:201], v[144:147]
	global_load_dwordx4 v[12:15], v[110:111], off offset:512
	v_mfma_f32_16x16x32_f16 v[158:161], v[194:197], v[206:209], v[158:161]
	global_load_dwordx4 v[16:19], v[112:113], off offset:512
	v_mfma_f32_16x16x32_f16 v[68:71], v[194:197], v[220:223], v[68:71]
	ds_read_b128 v[194:197], v131 offset:32768
	v_mfma_f32_16x16x32_f16 v[162:165], v[202:205], v[206:209], v[162:165]
	global_load_dwordx4 v[20:23], v[114:115], off offset:512
	v_mfma_f32_16x16x32_f16 v[76:79], v[202:205], v[220:223], v[76:79]
	ds_read_b128 v[202:205], v131 offset:34816
	v_mfma_f32_16x16x32_f16 v[140:143], v[210:213], v[190:193], v[140:143]
	global_load_dwordx4 v[24:27], v[116:117], off offset:512
	v_mfma_f32_16x16x32_f16 v[154:157], v[210:213], v[198:201], v[154:157]
	global_load_dwordx4 v[28:31], v[118:119], off offset:512
	v_mfma_f32_16x16x32_f16 v[64:67], v[224:227], v[190:193], v[64:67]
	ds_read_b128 v[190:193], v128
	v_mfma_f32_16x16x32_f16 v[72:75], v[224:227], v[198:201], v[72:75]
	ds_read_b128 v[198:201], v128 offset:2048
	v_mfma_f32_16x16x32_f16 v[166:169], v[210:213], v[206:209], v[166:169]
	v_mfma_f32_16x16x32_f16 v[84:87], v[210:213], v[220:223], v[84:87]
	ds_read_b128 v[210:213], v131 offset:36864
	v_mfma_f32_16x16x32_f16 v[80:83], v[224:227], v[206:209], v[80:83]
	ds_read_b128 v[206:209], v128 offset:4096
	v_mfma_f32_16x16x32_f16 v[88:91], v[224:227], v[220:223], v[88:91]
	ds_read_b128 v[220:223], v128 offset:6144
	s_waitcnt lgkmcnt(4)
	v_mfma_f32_16x16x32_f16 v[132:135], v[194:197], v[190:193], v[132:135]
	ds_read_b128 v[224:227], v131 offset:38912
	s_waitcnt lgkmcnt(4)
	v_mfma_f32_16x16x32_f16 v[92:95], v[194:197], v[198:201], v[92:95]
	s_waitcnt vmcnt(15)
	ds_write_b128 v126, v[32:35] offset:16384
	v_mfma_f32_16x16x32_f16 v[136:139], v[202:205], v[190:193], v[136:139]
	s_waitcnt vmcnt(14)
	ds_write_b128 v124, v[36:39] offset:16384
	v_mfma_f32_16x16x32_f16 v[144:147], v[202:205], v[198:201], v[144:147]
	s_waitcnt vmcnt(13)
	ds_write_b128 v125, v[40:43] offset:16384
	s_waitcnt lgkmcnt(5)
	v_mfma_f32_16x16x32_f16 v[158:161], v[194:197], v[206:209], v[158:161]
	s_waitcnt vmcnt(12)
	ds_write_b128 v127, v[44:47] offset:16384
	s_waitcnt lgkmcnt(5)
	v_mfma_f32_16x16x32_f16 v[68:71], v[194:197], v[220:223], v[68:71]
	ds_read_b128 v[194:197], v130 offset:32768
	v_mfma_f32_16x16x32_f16 v[162:165], v[202:205], v[206:209], v[162:165]
	s_waitcnt vmcnt(11)
	ds_write_b128 v126, v[48:51] offset:49152
	v_mfma_f32_16x16x32_f16 v[76:79], v[202:205], v[220:223], v[76:79]
	ds_read_b128 v[202:205], v130 offset:34816
	v_mfma_f32_16x16x32_f16 v[140:143], v[210:213], v[190:193], v[140:143]
	s_waitcnt vmcnt(10)
	ds_write_b128 v124, v[52:55] offset:49152
	v_mfma_f32_16x16x32_f16 v[154:157], v[210:213], v[198:201], v[154:157]
	s_waitcnt vmcnt(9)
	ds_write_b128 v125, v[56:59] offset:49152
	s_waitcnt lgkmcnt(9)
	v_mfma_f32_16x16x32_f16 v[64:67], v[224:227], v[190:193], v[64:67]
	ds_read_b128 v[190:193], v129
	v_mfma_f32_16x16x32_f16 v[72:75], v[224:227], v[198:201], v[72:75]
	ds_read_b128 v[198:201], v129 offset:2048
	v_mfma_f32_16x16x32_f16 v[166:169], v[210:213], v[206:209], v[166:169]
	s_waitcnt vmcnt(8)
	ds_write_b128 v127, v[60:63] offset:49152
	v_mfma_f32_16x16x32_f16 v[84:87], v[210:213], v[220:223], v[84:87]
	ds_read_b128 v[210:213], v130 offset:36864
	v_mfma_f32_16x16x32_f16 v[80:83], v[224:227], v[206:209], v[80:83]
	ds_read_b128 v[206:209], v129 offset:4096
	v_mfma_f32_16x16x32_f16 v[88:91], v[224:227], v[220:223], v[88:91]
	ds_read_b128 v[220:223], v129 offset:6144
	ds_read_b128 v[224:227], v130 offset:38912
	s_waitcnt lgkmcnt(0)
	s_barrier
	v_mfma_f32_16x16x32_f16 v[132:135], v[194:197], v[190:193], v[132:135]
	global_load_dwordx4 v[32:35], v[104:105], off offset:640
	v_mfma_f32_16x16x32_f16 v[92:95], v[194:197], v[198:201], v[92:95]
	global_load_dwordx4 v[36:39], v[106:107], off offset:640
	v_mfma_f32_16x16x32_f16 v[136:139], v[202:205], v[190:193], v[136:139]
	global_load_dwordx4 v[40:43], v[108:109], off offset:640
	v_mfma_f32_16x16x32_f16 v[144:147], v[202:205], v[198:201], v[144:147]
	global_load_dwordx4 v[44:47], v[110:111], off offset:640
	v_mfma_f32_16x16x32_f16 v[158:161], v[194:197], v[206:209], v[158:161]
	global_load_dwordx4 v[48:51], v[112:113], off offset:640
	v_mfma_f32_16x16x32_f16 v[68:71], v[194:197], v[220:223], v[68:71]
	ds_read_b128 v[194:197], v131 offset:49152
	v_mfma_f32_16x16x32_f16 v[162:165], v[202:205], v[206:209], v[162:165]
	global_load_dwordx4 v[52:55], v[114:115], off offset:640
	v_mfma_f32_16x16x32_f16 v[76:79], v[202:205], v[220:223], v[76:79]
	ds_read_b128 v[202:205], v131 offset:51200
	v_mfma_f32_16x16x32_f16 v[140:143], v[210:213], v[190:193], v[140:143]
	global_load_dwordx4 v[56:59], v[116:117], off offset:640
	v_mfma_f32_16x16x32_f16 v[154:157], v[210:213], v[198:201], v[154:157]
	global_load_dwordx4 v[60:63], v[118:119], off offset:640
	v_mfma_f32_16x16x32_f16 v[64:67], v[224:227], v[190:193], v[64:67]
	ds_read_b128 v[190:193], v128 offset:16384
	v_mfma_f32_16x16x32_f16 v[72:75], v[224:227], v[198:201], v[72:75]
	ds_read_b128 v[198:201], v128 offset:18432
	v_mfma_f32_16x16x32_f16 v[166:169], v[210:213], v[206:209], v[166:169]
	v_mfma_f32_16x16x32_f16 v[84:87], v[210:213], v[220:223], v[84:87]
	ds_read_b128 v[210:213], v131 offset:53248
	v_mfma_f32_16x16x32_f16 v[80:83], v[224:227], v[206:209], v[80:83]
	ds_read_b128 v[206:209], v128 offset:20480
	v_mfma_f32_16x16x32_f16 v[88:91], v[224:227], v[220:223], v[88:91]
	ds_read_b128 v[220:223], v128 offset:22528
	s_waitcnt lgkmcnt(4)
; #define GL_LOAD(s_, kt_) if (VAR != 1) { a##s_##0 = GL_A(0, kt_); a##s_##1 = GL_A(1, kt_); a##s_##2 = GL_A(2, kt_); a##s_##3 = GL_A(3, kt_); b##s_##0 = GL_B(0, kt_); b##s_##1 = GL_B(1, kt_); b##s_##2 = GL_B(2, kt_); b##s_##3 = GL_B(3, kt_); }
; #define LDS_STORE(s_, buf_) if (VAR != 2) { LDS_ST1(sA, 0, buf_, a##s_##0) LDS_ST1(sA, 1, buf_, a##s_##1) LDS_ST1(sA, 2, buf_, a##s_##2) LDS_ST1(sA, 3, buf_, a##s_##3) LDS_ST1(sB, 0, buf_, b##s_##0) LDS_ST1(sB, 1, buf_, b##s_##1) LDS_ST1(sB, 2, buf_, b##s_##2) LDS_ST1(sB, 3, buf_, b##s_##3) }
;     ...
;   GL_LOAD(0, 0)
;   GL_LOAD(1, 1)
;   LDS_STORE(0, 0)
;   if (VAR != 4) __syncthreads();
; #pragma unroll
;   for (int kt = 0; kt < nk; kt += 2) {
;     if (kt + 2 < nk) { GL_LOAD(0, kt + 2) }
;     MMA_TILE(0)
;     LDS_STORE(1, 1)
;     if (VAR != 4) __syncthreads();
;     if (kt + 3 < nk) { GL_LOAD(1, kt + 3) }
;     MMA_TILE(1)
;     if (kt + 2 < nk) { LDS_STORE(0, 0) }
;     if (VAR != 4) __syncthreads();
	v_mfma_f32_16x16x32_f16 v[132:135], v[194:197], v[190:193], v[132:135]
	ds_read_b128 v[224:227], v131 offset:55296
	s_waitcnt lgkmcnt(4)
	v_mfma_f32_16x16x32_f16 v[92:95], v[194:197], v[198:201], v[92:95]
	s_waitcnt vmcnt(15)
	ds_write_b128 v126, v[0:3]
	v_mfma_f32_16x16x32_f16 v[136:139], v[202:205], v[190:193], v[136:139]
	s_waitcnt vmcnt(14)
	ds_write_b128 v124, v[4:7]
	v_mfma_f32_16x16x32_f16 v[144:147], v[202:205], v[198:201], v[144:147]
	s_waitcnt vmcnt(13)
	ds_write_b128 v125, v[8:11]
	s_waitcnt lgkmcnt(5)
	v_mfma_f32_16x16x32_f16 v[158:161], v[194:197], v[206:209], v[158:161]
	s_waitcnt vmcnt(12)
	ds_write_b128 v127, v[12:15]
	s_waitcnt lgkmcnt(5)
	v_mfma_f32_16x16x32_f16 v[68:71], v[194:197], v[220:223], v[68:71]
	ds_read_b128 v[194:197], v130 offset:49152
	v_mfma_f32_16x16x32_f16 v[162:165], v[202:205], v[206:209], v[162:165]
	s_waitcnt vmcnt(11)
	ds_write_b128 v126, v[16:19] offset:32768
	v_mfma_f32_16x16x32_f16 v[76:79], v[202:205], v[220:223], v[76:79]
	ds_read_b128 v[202:205], v130 offset:51200
	v_mfma_f32_16x16x32_f16 v[140:143], v[210:213], v[190:193], v[140:143]
	s_waitcnt vmcnt(10)
	ds_write_b128 v124, v[20:23] offset:32768
	v_mfma_f32_16x16x32_f16 v[154:157], v[210:213], v[198:201], v[154:157]
	s_waitcnt vmcnt(9)
	ds_write_b128 v125, v[24:27] offset:32768
	s_waitcnt lgkmcnt(9)
	v_mfma_f32_16x16x32_f16 v[64:67], v[224:227], v[190:193], v[64:67]
	ds_read_b128 v[190:193], v129 offset:16384
	v_mfma_f32_16x16x32_f16 v[72:75], v[224:227], v[198:201], v[72:75]
	ds_read_b128 v[198:201], v129 offset:18432
	v_mfma_f32_16x16x32_f16 v[166:169], v[210:213], v[206:209], v[166:169]
	s_waitcnt vmcnt(8)
	ds_write_b128 v127, v[28:31] offset:32768
	v_mfma_f32_16x16x32_f16 v[84:87], v[210:213], v[220:223], v[84:87]
	ds_read_b128 v[210:213], v130 offset:53248
	v_mfma_f32_16x16x32_f16 v[80:83], v[224:227], v[206:209], v[80:83]
	ds_read_b128 v[206:209], v129 offset:20480
	v_mfma_f32_16x16x32_f16 v[88:91], v[224:227], v[220:223], v[88:91]
	ds_read_b128 v[220:223], v129 offset:22528
	ds_read_b128 v[224:227], v130 offset:55296
	s_waitcnt lgkmcnt(0)
	s_barrier
	v_mfma_f32_16x16x32_f16 v[132:135], v[194:197], v[190:193], v[132:135]
	global_load_dwordx4 v[0:3], v[104:105], off offset:768
	v_mfma_f32_16x16x32_f16 v[92:95], v[194:197], v[198:201], v[92:95]
	global_load_dwordx4 v[4:7], v[106:107], off offset:768
	v_mfma_f32_16x16x32_f16 v[136:139], v[202:205], v[190:193], v[136:139]
	global_load_dwordx4 v[8:11], v[108:109], off offset:768
	v_mfma_f32_16x16x32_f16 v[144:147], v[202:205], v[198:201], v[144:147]
	global_load_dwordx4 v[12:15], v[110:111], off offset:768
	v_mfma_f32_16x16x32_f16 v[158:161], v[194:197], v[206:209], v[158:161]
	global_load_dwordx4 v[16:19], v[112:113], off offset:768
	v_mfma_f32_16x16x32_f16 v[68:71], v[194:197], v[220:223], v[68:71]
	ds_read_b128 v[194:197], v131 offset:32768
	v_mfma_f32_16x16x32_f16 v[162:165], v[202:205], v[206:209], v[162:165]
	global_load_dwordx4 v[20:23], v[114:115], off offset:768
	v_mfma_f32_16x16x32_f16 v[76:79], v[202:205], v[220:223], v[76:79]
	ds_read_b128 v[202:205], v131 offset:34816
	v_mfma_f32_16x16x32_f16 v[140:143], v[210:213], v[190:193], v[140:143]
	global_load_dwordx4 v[24:27], v[116:117], off offset:768
	v_mfma_f32_16x16x32_f16 v[154:157], v[210:213], v[198:201], v[154:157]
	global_load_dwordx4 v[28:31], v[118:119], off offset:768
	v_mfma_f32_16x16x32_f16 v[64:67], v[224:227], v[190:193], v[64:67]
	ds_read_b128 v[190:193], v128
	v_mfma_f32_16x16x32_f16 v[72:75], v[224:227], v[198:201], v[72:75]
	ds_read_b128 v[198:201], v128 offset:2048
	v_mfma_f32_16x16x32_f16 v[166:169], v[210:213], v[206:209], v[166:169]
	v_mfma_f32_16x16x32_f16 v[84:87], v[210:213], v[220:223], v[84:87]
	ds_read_b128 v[210:213], v131 offset:36864
	v_mfma_f32_16x16x32_f16 v[80:83], v[224:227], v[206:209], v[80:83]
	ds_read_b128 v[206:209], v128 offset:4096
	v_mfma_f32_16x16x32_f16 v[88:91], v[224:227], v[220:223], v[88:91]
	ds_read_b128 v[220:223], v128 offset:6144
	s_waitcnt lgkmcnt(4)
	v_mfma_f32_16x16x32_f16 v[132:135], v[194:197], v[190:193], v[132:135]
	ds_read_b128 v[224:227], v131 offset:38912
	s_waitcnt lgkmcnt(4)
	v_mfma_f32_16x16x32_f16 v[92:95], v[194:197], v[198:201], v[92:95]
	s_waitcnt vmcnt(15)
	ds_write_b128 v126, v[32:35] offset:16384
	v_mfma_f32_16x16x32_f16 v[136:139], v[202:205], v[190:193], v[136:139]
	s_waitcnt vmcnt(14)
	ds_write_b128 v124, v[36:39] offset:16384
	v_mfma_f32_16x16x32_f16 v[144:147], v[202:205], v[198:201], v[144:147]
	s_waitcnt vmcnt(13)
	ds_write_b128 v125, v[40:43] offset:16384
	s_waitcnt lgkmcnt(5)
	v_mfma_f32_16x16x32_f16 v[158:161], v[194:197], v[206:209], v[158:161]
	s_waitcnt vmcnt(12)
	ds_write_b128 v127, v[44:47] offset:16384
	s_waitcnt lgkmcnt(5)
	v_mfma_f32_16x16x32_f16 v[68:71], v[194:197], v[220:223], v[68:71]
	ds_read_b128 v[194:197], v130 offset:32768
	v_mfma_f32_16x16x32_f16 v[162:165], v[202:205], v[206:209], v[162:165]
	s_waitcnt vmcnt(11)
	ds_write_b128 v126, v[48:51] offset:49152
	v_mfma_f32_16x16x32_f16 v[76:79], v[202:205], v[220:223], v[76:79]
	ds_read_b128 v[202:205], v130 offset:34816
	v_mfma_f32_16x16x32_f16 v[140:143], v[210:213], v[190:193], v[140:143]
	s_waitcnt vmcnt(10)
	ds_write_b128 v124, v[52:55] offset:49152
	v_mfma_f32_16x16x32_f16 v[154:157], v[210:213], v[198:201], v[154:157]
	s_waitcnt vmcnt(9)
	ds_write_b128 v125, v[56:59] offset:49152
	s_waitcnt lgkmcnt(9)
	v_mfma_f32_16x16x32_f16 v[64:67], v[224:227], v[190:193], v[64:67]
	ds_read_b128 v[190:193], v129
	v_mfma_f32_16x16x32_f16 v[72:75], v[224:227], v[198:201], v[72:75]
	ds_read_b128 v[198:201], v129 offset:2048
	v_mfma_f32_16x16x32_f16 v[166:169], v[210:213], v[206:209], v[166:169]
	s_waitcnt vmcnt(8)
	ds_write_b128 v127, v[60:63] offset:49152
	v_mfma_f32_16x16x32_f16 v[84:87], v[210:213], v[220:223], v[84:87]
	ds_read_b128 v[210:213], v130 offset:36864
	v_mfma_f32_16x16x32_f16 v[80:83], v[224:227], v[206:209], v[80:83]
	ds_read_b128 v[206:209], v129 offset:4096
	v_mfma_f32_16x16x32_f16 v[88:91], v[224:227], v[220:223], v[88:91]
	ds_read_b128 v[220:223], v129 offset:6144
	ds_read_b128 v[224:227], v130 offset:38912
	s_waitcnt lgkmcnt(0)
	s_barrier
; #define GL_LOAD(s_, kt_) if (VAR != 1) { a##s_##0 = GL_A(0, kt_); a##s_##1 = GL_A(1, kt_); a##s_##2 = GL_A(2, kt_); a##s_##3 = GL_A(3, kt_); b##s_##0 = GL_B(0, kt_); b##s_##1 = GL_B(1, kt_); b##s_##2 = GL_B(2, kt_); b##s_##3 = GL_B(3, kt_); }
; #define LDS_STORE(s_, buf_) if (VAR != 2) { LDS_ST1(sA, 0, buf_, a##s_##0) LDS_ST1(sA, 1, buf_, a##s_##1) LDS_ST1(sA, 2, buf_, a##s_##2) LDS_ST1(sA, 3, buf_, a##s_##3) LDS_ST1(sB, 0, buf_, b##s_##0) LDS_ST1(sB, 1, buf_, b##s_##1) LDS_ST1(sB, 2, buf_, b##s_##2) LDS_ST1(sB, 3, buf_, b##s_##3) }
;     ...
;   GL_LOAD(0, 0)
;   GL_LOAD(1, 1)
;   LDS_STORE(0, 0)
;   if (VAR != 4) __syncthreads();
; #pragma unroll
;   for (int kt = 0; kt < nk; kt += 2) {
;     if (kt + 2 < nk) { GL_LOAD(0, kt + 2) }
;     MMA_TILE(0)
;     LDS_STORE(1, 1)
;     if (VAR != 4) __syncthreads();
;     if (kt + 3 < nk) { GL_LOAD(1, kt + 3) }
;     MMA_TILE(1)
;     if (kt + 2 < nk) { LDS_STORE(0, 0) }
;     if (VAR != 4) __syncthreads();
	v_mfma_f32_16x16x32_f16 v[132:135], v[194:197], v[190:193], v[132:135]
	global_load_dwordx4 v[32:35], v[104:105], off offset:896
	v_mfma_f32_16x16x32_f16 v[92:95], v[194:197], v[198:201], v[92:95]
	global_load_dwordx4 v[36:39], v[106:107], off offset:896
	v_mfma_f32_16x16x32_f16 v[136:139], v[202:205], v[190:193], v[136:139]
	global_load_dwordx4 v[40:43], v[108:109], off offset:896
	v_mfma_f32_16x16x32_f16 v[144:147], v[202:205], v[198:201], v[144:147]
	global_load_dwordx4 v[44:47], v[110:111], off offset:896
	v_mfma_f32_16x16x32_f16 v[158:161], v[194:197], v[206:209], v[158:161]
	global_load_dwordx4 v[48:51], v[112:113], off offset:896
	v_mfma_f32_16x16x32_f16 v[68:71], v[194:197], v[220:223], v[68:71]
	ds_read_b128 v[194:197], v131 offset:49152
	v_mfma_f32_16x16x32_f16 v[162:165], v[202:205], v[206:209], v[162:165]
	global_load_dwordx4 v[52:55], v[114:115], off offset:896
	v_mfma_f32_16x16x32_f16 v[76:79], v[202:205], v[220:223], v[76:79]
	ds_read_b128 v[202:205], v131 offset:51200
	v_mfma_f32_16x16x32_f16 v[140:143], v[210:213], v[190:193], v[140:143]
	global_load_dwordx4 v[56:59], v[116:117], off offset:896
	v_mfma_f32_16x16x32_f16 v[154:157], v[210:213], v[198:201], v[154:157]
	global_load_dwordx4 v[60:63], v[118:119], off offset:896
	v_mfma_f32_16x16x32_f16 v[64:67], v[224:227], v[190:193], v[64:67]
	ds_read_b128 v[190:193], v128 offset:16384
	v_mfma_f32_16x16x32_f16 v[72:75], v[224:227], v[198:201], v[72:75]
	ds_read_b128 v[198:201], v128 offset:18432
	v_mfma_f32_16x16x32_f16 v[166:169], v[210:213], v[206:209], v[166:169]
	v_mfma_f32_16x16x32_f16 v[84:87], v[210:213], v[220:223], v[84:87]
	ds_read_b128 v[210:213], v131 offset:53248
	v_mfma_f32_16x16x32_f16 v[80:83], v[224:227], v[206:209], v[80:83]
	ds_read_b128 v[206:209], v128 offset:20480
	v_mfma_f32_16x16x32_f16 v[88:91], v[224:227], v[220:223], v[88:91]
	ds_read_b128 v[220:223], v128 offset:22528
	s_waitcnt lgkmcnt(4)
	v_mfma_f32_16x16x32_f16 v[132:135], v[194:197], v[190:193], v[132:135]
	ds_read_b128 v[224:227], v131 offset:55296
	s_waitcnt lgkmcnt(4)
	v_mfma_f32_16x16x32_f16 v[92:95], v[194:197], v[198:201], v[92:95]
	s_waitcnt vmcnt(15)
	ds_write_b128 v126, v[0:3]
	v_mfma_f32_16x16x32_f16 v[136:139], v[202:205], v[190:193], v[136:139]
	s_waitcnt vmcnt(14)
	ds_write_b128 v124, v[4:7]
	v_mfma_f32_16x16x32_f16 v[144:147], v[202:205], v[198:201], v[144:147]
	s_waitcnt vmcnt(13)
	ds_write_b128 v125, v[8:11]
	s_waitcnt lgkmcnt(5)
	v_mfma_f32_16x16x32_f16 v[158:161], v[194:197], v[206:209], v[158:161]
	s_waitcnt vmcnt(12)
	ds_write_b128 v127, v[12:15]
	s_waitcnt lgkmcnt(5)
	v_mfma_f32_16x16x32_f16 v[68:71], v[194:197], v[220:223], v[68:71]
	ds_read_b128 v[194:197], v130 offset:49152
	v_mfma_f32_16x16x32_f16 v[162:165], v[202:205], v[206:209], v[162:165]
	s_waitcnt vmcnt(11)
	ds_write_b128 v126, v[16:19] offset:32768
	v_mfma_f32_16x16x32_f16 v[76:79], v[202:205], v[220:223], v[76:79]
	ds_read_b128 v[202:205], v130 offset:51200
	v_mfma_f32_16x16x32_f16 v[140:143], v[210:213], v[190:193], v[140:143]
	s_waitcnt vmcnt(10)
	ds_write_b128 v124, v[20:23] offset:32768
	v_mfma_f32_16x16x32_f16 v[154:157], v[210:213], v[198:201], v[154:157]
	s_waitcnt vmcnt(9)
	ds_write_b128 v125, v[24:27] offset:32768
	s_waitcnt lgkmcnt(9)
	v_mfma_f32_16x16x32_f16 v[64:67], v[224:227], v[190:193], v[64:67]
	ds_read_b128 v[190:193], v129 offset:16384
	v_mfma_f32_16x16x32_f16 v[72:75], v[224:227], v[198:201], v[72:75]
	ds_read_b128 v[198:201], v129 offset:18432
	v_mfma_f32_16x16x32_f16 v[166:169], v[210:213], v[206:209], v[166:169]
	s_waitcnt vmcnt(8)
	ds_write_b128 v127, v[28:31] offset:32768
	v_mfma_f32_16x16x32_f16 v[84:87], v[210:213], v[220:223], v[84:87]
	ds_read_b128 v[210:213], v130 offset:53248
	v_mfma_f32_16x16x32_f16 v[80:83], v[224:227], v[206:209], v[80:83]
	ds_read_b128 v[206:209], v129 offset:20480
	v_mfma_f32_16x16x32_f16 v[88:91], v[224:227], v[220:223], v[88:91]
	ds_read_b128 v[220:223], v129 offset:22528
	ds_read_b128 v[224:227], v130 offset:55296
	s_waitcnt lgkmcnt(0)
	s_barrier
	v_mfma_f32_16x16x32_f16 v[132:135], v[194:197], v[190:193], v[132:135]
	global_load_dwordx4 v[0:3], v[104:105], off offset:1024
	v_mfma_f32_16x16x32_f16 v[92:95], v[194:197], v[198:201], v[92:95]
	global_load_dwordx4 v[4:7], v[106:107], off offset:1024
	v_mfma_f32_16x16x32_f16 v[136:139], v[202:205], v[190:193], v[136:139]
	global_load_dwordx4 v[8:11], v[108:109], off offset:1024
	v_mfma_f32_16x16x32_f16 v[144:147], v[202:205], v[198:201], v[144:147]
	global_load_dwordx4 v[12:15], v[110:111], off offset:1024
	v_mfma_f32_16x16x32_f16 v[158:161], v[194:197], v[206:209], v[158:161]
	global_load_dwordx4 v[16:19], v[112:113], off offset:1024
	v_mfma_f32_16x16x32_f16 v[68:71], v[194:197], v[220:223], v[68:71]
	ds_read_b128 v[194:197], v131 offset:32768
	v_mfma_f32_16x16x32_f16 v[162:165], v[202:205], v[206:209], v[162:165]
	global_load_dwordx4 v[20:23], v[114:115], off offset:1024
	v_mfma_f32_16x16x32_f16 v[76:79], v[202:205], v[220:223], v[76:79]
	ds_read_b128 v[202:205], v131 offset:34816
	v_mfma_f32_16x16x32_f16 v[140:143], v[210:213], v[190:193], v[140:143]
	global_load_dwordx4 v[24:27], v[116:117], off offset:1024
	v_mfma_f32_16x16x32_f16 v[154:157], v[210:213], v[198:201], v[154:157]
	global_load_dwordx4 v[28:31], v[118:119], off offset:1024
	v_mfma_f32_16x16x32_f16 v[64:67], v[224:227], v[190:193], v[64:67]
	ds_read_b128 v[190:193], v128
	v_mfma_f32_16x16x32_f16 v[72:75], v[224:227], v[198:201], v[72:75]
	ds_read_b128 v[198:201], v128 offset:2048
	v_mfma_f32_16x16x32_f16 v[166:169], v[210:213], v[206:209], v[166:169]
	v_mfma_f32_16x16x32_f16 v[84:87], v[210:213], v[220:223], v[84:87]
	ds_read_b128 v[210:213], v131 offset:36864
	v_mfma_f32_16x16x32_f16 v[80:83], v[224:227], v[206:209], v[80:83]
	ds_read_b128 v[206:209], v128 offset:4096
	v_mfma_f32_16x16x32_f16 v[88:91], v[224:227], v[220:223], v[88:91]
	ds_read_b128 v[220:223], v128 offset:6144
	s_waitcnt lgkmcnt(4)
; #define GL_LOAD(s_, kt_) if (VAR != 1) { a##s_##0 = GL_A(0, kt_); a##s_##1 = GL_A(1, kt_); a##s_##2 = GL_A(2, kt_); a##s_##3 = GL_A(3, kt_); b##s_##0 = GL_B(0, kt_); b##s_##1 = GL_B(1, kt_); b##s_##2 = GL_B(2, kt_); b##s_##3 = GL_B(3, kt_); }
; #define LDS_STORE(s_, buf_) if (VAR != 2) { LDS_ST1(sA, 0, buf_, a##s_##0) LDS_ST1(sA, 1, buf_, a##s_##1) LDS_ST1(sA, 2, buf_, a##s_##2) LDS_ST1(sA, 3, buf_, a##s_##3) LDS_ST1(sB, 0, buf_, b##s_##0) LDS_ST1(sB, 1, buf_, b##s_##1) LDS_ST1(sB, 2, buf_, b##s_##2) LDS_ST1(sB, 3, buf_, b##s_##3) }
;     ...
;   GL_LOAD(0, 0)
;   GL_LOAD(1, 1)
;   LDS_STORE(0, 0)
;   if (VAR != 4) __syncthreads();
; #pragma unroll
;   for (int kt = 0; kt < nk; kt += 2) {
;     if (kt + 2 < nk) { GL_LOAD(0, kt + 2) }
;     MMA_TILE(0)
;     LDS_STORE(1, 1)
;     if (VAR != 4) __syncthreads();
;     if (kt + 3 < nk) { GL_LOAD(1, kt + 3) }
;     MMA_TILE(1)
;     if (kt + 2 < nk) { LDS_STORE(0, 0) }
;     if (VAR != 4) __syncthreads();
	v_mfma_f32_16x16x32_f16 v[132:135], v[194:197], v[190:193], v[132:135]
	ds_read_b128 v[224:227], v131 offset:38912
	s_waitcnt lgkmcnt(4)
	v_mfma_f32_16x16x32_f16 v[92:95], v[194:197], v[198:201], v[92:95]
	s_waitcnt vmcnt(15)
	ds_write_b128 v126, v[32:35] offset:16384
	v_mfma_f32_16x16x32_f16 v[136:139], v[202:205], v[190:193], v[136:139]
	s_waitcnt vmcnt(14)
	ds_write_b128 v124, v[36:39] offset:16384
	v_mfma_f32_16x16x32_f16 v[144:147], v[202:205], v[198:201], v[144:147]
	s_waitcnt vmcnt(13)
	ds_write_b128 v125, v[40:43] offset:16384
	s_waitcnt lgkmcnt(5)
	v_mfma_f32_16x16x32_f16 v[158:161], v[194:197], v[206:209], v[158:161]
	s_waitcnt vmcnt(12)
	ds_write_b128 v127, v[44:47] offset:16384
	s_waitcnt lgkmcnt(5)
	v_mfma_f32_16x16x32_f16 v[68:71], v[194:197], v[220:223], v[68:71]
	ds_read_b128 v[194:197], v130 offset:32768
	v_mfma_f32_16x16x32_f16 v[162:165], v[202:205], v[206:209], v[162:165]
	s_waitcnt vmcnt(11)
	ds_write_b128 v126, v[48:51] offset:49152
	v_mfma_f32_16x16x32_f16 v[76:79], v[202:205], v[220:223], v[76:79]
	ds_read_b128 v[202:205], v130 offset:34816
	v_mfma_f32_16x16x32_f16 v[140:143], v[210:213], v[190:193], v[140:143]
	s_waitcnt vmcnt(10)
	ds_write_b128 v124, v[52:55] offset:49152
	v_mfma_f32_16x16x32_f16 v[154:157], v[210:213], v[198:201], v[154:157]
	s_waitcnt vmcnt(9)
	ds_write_b128 v125, v[56:59] offset:49152
	s_waitcnt lgkmcnt(9)
	v_mfma_f32_16x16x32_f16 v[64:67], v[224:227], v[190:193], v[64:67]
	ds_read_b128 v[190:193], v129
	v_mfma_f32_16x16x32_f16 v[72:75], v[224:227], v[198:201], v[72:75]
	ds_read_b128 v[198:201], v129 offset:2048
	v_mfma_f32_16x16x32_f16 v[166:169], v[210:213], v[206:209], v[166:169]
	s_waitcnt vmcnt(8)
	ds_write_b128 v127, v[60:63] offset:49152
	v_mfma_f32_16x16x32_f16 v[84:87], v[210:213], v[220:223], v[84:87]
	ds_read_b128 v[210:213], v130 offset:36864
	v_mfma_f32_16x16x32_f16 v[80:83], v[224:227], v[206:209], v[80:83]
	ds_read_b128 v[206:209], v129 offset:4096
	v_mfma_f32_16x16x32_f16 v[88:91], v[224:227], v[220:223], v[88:91]
	ds_read_b128 v[220:223], v129 offset:6144
	ds_read_b128 v[224:227], v130 offset:38912
	s_waitcnt lgkmcnt(0)
	s_barrier
	v_mfma_f32_16x16x32_f16 v[132:135], v[194:197], v[190:193], v[132:135]
	global_load_dwordx4 v[32:35], v[104:105], off offset:1152
	v_mfma_f32_16x16x32_f16 v[92:95], v[194:197], v[198:201], v[92:95]
	global_load_dwordx4 v[36:39], v[106:107], off offset:1152
	v_mfma_f32_16x16x32_f16 v[136:139], v[202:205], v[190:193], v[136:139]
	global_load_dwordx4 v[40:43], v[108:109], off offset:1152
	v_mfma_f32_16x16x32_f16 v[144:147], v[202:205], v[198:201], v[144:147]
	global_load_dwordx4 v[44:47], v[110:111], off offset:1152
	v_mfma_f32_16x16x32_f16 v[158:161], v[194:197], v[206:209], v[158:161]
	global_load_dwordx4 v[48:51], v[112:113], off offset:1152
	v_mfma_f32_16x16x32_f16 v[68:71], v[194:197], v[220:223], v[68:71]
	ds_read_b128 v[194:197], v131 offset:49152
	v_mfma_f32_16x16x32_f16 v[162:165], v[202:205], v[206:209], v[162:165]
	global_load_dwordx4 v[52:55], v[114:115], off offset:1152
	v_mfma_f32_16x16x32_f16 v[76:79], v[202:205], v[220:223], v[76:79]
	ds_read_b128 v[202:205], v131 offset:51200
	v_mfma_f32_16x16x32_f16 v[140:143], v[210:213], v[190:193], v[140:143]
	global_load_dwordx4 v[56:59], v[116:117], off offset:1152
	v_mfma_f32_16x16x32_f16 v[154:157], v[210:213], v[198:201], v[154:157]
	global_load_dwordx4 v[60:63], v[118:119], off offset:1152
	v_mfma_f32_16x16x32_f16 v[64:67], v[224:227], v[190:193], v[64:67]
	ds_read_b128 v[190:193], v128 offset:16384
	v_mfma_f32_16x16x32_f16 v[72:75], v[224:227], v[198:201], v[72:75]
	ds_read_b128 v[198:201], v128 offset:18432
	v_mfma_f32_16x16x32_f16 v[166:169], v[210:213], v[206:209], v[166:169]
	v_mfma_f32_16x16x32_f16 v[84:87], v[210:213], v[220:223], v[84:87]
	ds_read_b128 v[210:213], v131 offset:53248
	v_mfma_f32_16x16x32_f16 v[80:83], v[224:227], v[206:209], v[80:83]
	ds_read_b128 v[206:209], v128 offset:20480
	v_mfma_f32_16x16x32_f16 v[88:91], v[224:227], v[220:223], v[88:91]
	ds_read_b128 v[220:223], v128 offset:22528
	s_waitcnt lgkmcnt(4)
	v_mfma_f32_16x16x32_f16 v[132:135], v[194:197], v[190:193], v[132:135]
	ds_read_b128 v[224:227], v131 offset:55296
	s_waitcnt lgkmcnt(4)
	v_mfma_f32_16x16x32_f16 v[92:95], v[194:197], v[198:201], v[92:95]
	s_waitcnt vmcnt(15)
	ds_write_b128 v126, v[0:3]
	v_mfma_f32_16x16x32_f16 v[136:139], v[202:205], v[190:193], v[136:139]
	s_waitcnt vmcnt(14)
	ds_write_b128 v124, v[4:7]
	v_mfma_f32_16x16x32_f16 v[144:147], v[202:205], v[198:201], v[144:147]
	s_waitcnt vmcnt(13)
	ds_write_b128 v125, v[8:11]
	s_waitcnt lgkmcnt(5)
	v_mfma_f32_16x16x32_f16 v[158:161], v[194:197], v[206:209], v[158:161]
	s_waitcnt vmcnt(12)
	ds_write_b128 v127, v[12:15]
	s_waitcnt lgkmcnt(5)
	v_mfma_f32_16x16x32_f16 v[68:71], v[194:197], v[220:223], v[68:71]
	ds_read_b128 v[194:197], v130 offset:49152
	v_mfma_f32_16x16x32_f16 v[162:165], v[202:205], v[206:209], v[162:165]
	s_waitcnt vmcnt(11)
	ds_write_b128 v126, v[16:19] offset:32768
	v_mfma_f32_16x16x32_f16 v[76:79], v[202:205], v[220:223], v[76:79]
	ds_read_b128 v[202:205], v130 offset:51200
	v_mfma_f32_16x16x32_f16 v[140:143], v[210:213], v[190:193], v[140:143]
	s_waitcnt vmcnt(10)
	ds_write_b128 v124, v[20:23] offset:32768
	v_mfma_f32_16x16x32_f16 v[154:157], v[210:213], v[198:201], v[154:157]
	s_waitcnt vmcnt(9)
	ds_write_b128 v125, v[24:27] offset:32768
	s_waitcnt lgkmcnt(9)
	v_mfma_f32_16x16x32_f16 v[64:67], v[224:227], v[190:193], v[64:67]
	ds_read_b128 v[190:193], v129 offset:16384
	v_mfma_f32_16x16x32_f16 v[72:75], v[224:227], v[198:201], v[72:75]
	ds_read_b128 v[198:201], v129 offset:18432
	v_mfma_f32_16x16x32_f16 v[166:169], v[210:213], v[206:209], v[166:169]
	s_waitcnt vmcnt(8)
	ds_write_b128 v127, v[28:31] offset:32768
	v_mfma_f32_16x16x32_f16 v[84:87], v[210:213], v[220:223], v[84:87]
	ds_read_b128 v[210:213], v130 offset:53248
	v_mfma_f32_16x16x32_f16 v[80:83], v[224:227], v[206:209], v[80:83]
	ds_read_b128 v[206:209], v129 offset:20480
	v_mfma_f32_16x16x32_f16 v[88:91], v[224:227], v[220:223], v[88:91]
	ds_read_b128 v[220:223], v129 offset:22528
	ds_read_b128 v[224:227], v130 offset:55296
	s_waitcnt lgkmcnt(0)
	s_barrier
; #define GL_LOAD(s_, kt_) if (VAR != 1) { a##s_##0 = GL_A(0, kt_); a##s_##1 = GL_A(1, kt_); a##s_##2 = GL_A(2, kt_); a##s_##3 = GL_A(3, kt_); b##s_##0 = GL_B(0, kt_); b##s_##1 = GL_B(1, kt_); b##s_##2 = GL_B(2, kt_); b##s_##3 = GL_B(3, kt_); }
; #define LDS_STORE(s_, buf_) if (VAR != 2) { LDS_ST1(sA, 0, buf_, a##s_##0) LDS_ST1(sA, 1, buf_, a##s_##1) LDS_ST1(sA, 2, buf_, a##s_##2) LDS_ST1(sA, 3, buf_, a##s_##3) LDS_ST1(sB, 0, buf_, b##s_##0) LDS_ST1(sB, 1, buf_, b##s_##1) LDS_ST1(sB, 2, buf_, b##s_##2) LDS_ST1(sB, 3, buf_, b##s_##3) }
;     ...
;   GL_LOAD(0, 0)
;   GL_LOAD(1, 1)
;   LDS_STORE(0, 0)
;   if (VAR != 4) __syncthreads();
; #pragma unroll
;   for (int kt = 0; kt < nk; kt += 2) {
;     if (kt + 2 < nk) { GL_LOAD(0, kt + 2) }
;     MMA_TILE(0)
;     LDS_STORE(1, 1)
;     if (VAR != 4) __syncthreads();
;     if (kt + 3 < nk) { GL_LOAD(1, kt + 3) }
;     MMA_TILE(1)
;     if (kt + 2 < nk) { LDS_STORE(0, 0) }
;     if (VAR != 4) __syncthreads();
	v_mfma_f32_16x16x32_f16 v[132:135], v[194:197], v[190:193], v[132:135]
	global_load_dwordx4 v[0:3], v[104:105], off offset:1280
	v_mfma_f32_16x16x32_f16 v[92:95], v[194:197], v[198:201], v[92:95]
	global_load_dwordx4 v[4:7], v[106:107], off offset:1280
	v_mfma_f32_16x16x32_f16 v[136:139], v[202:205], v[190:193], v[136:139]
	global_load_dwordx4 v[8:11], v[108:109], off offset:1280
	v_mfma_f32_16x16x32_f16 v[144:147], v[202:205], v[198:201], v[144:147]
	global_load_dwordx4 v[12:15], v[110:111], off offset:1280
	v_mfma_f32_16x16x32_f16 v[158:161], v[194:197], v[206:209], v[158:161]
	global_load_dwordx4 v[16:19], v[112:113], off offset:1280
	v_mfma_f32_16x16x32_f16 v[68:71], v[194:197], v[220:223], v[68:71]
	ds_read_b128 v[194:197], v131 offset:32768
	v_mfma_f32_16x16x32_f16 v[162:165], v[202:205], v[206:209], v[162:165]
	global_load_dwordx4 v[20:23], v[114:115], off offset:1280
	v_mfma_f32_16x16x32_f16 v[76:79], v[202:205], v[220:223], v[76:79]
	ds_read_b128 v[202:205], v131 offset:34816
	v_mfma_f32_16x16x32_f16 v[140:143], v[210:213], v[190:193], v[140:143]
	global_load_dwordx4 v[24:27], v[116:117], off offset:1280
	v_mfma_f32_16x16x32_f16 v[154:157], v[210:213], v[198:201], v[154:157]
	global_load_dwordx4 v[28:31], v[118:119], off offset:1280
	v_mfma_f32_16x16x32_f16 v[64:67], v[224:227], v[190:193], v[64:67]
	ds_read_b128 v[190:193], v128
	v_mfma_f32_16x16x32_f16 v[72:75], v[224:227], v[198:201], v[72:75]
	ds_read_b128 v[198:201], v128 offset:2048
	v_mfma_f32_16x16x32_f16 v[166:169], v[210:213], v[206:209], v[166:169]
	v_mfma_f32_16x16x32_f16 v[84:87], v[210:213], v[220:223], v[84:87]
	ds_read_b128 v[210:213], v131 offset:36864
	v_mfma_f32_16x16x32_f16 v[80:83], v[224:227], v[206:209], v[80:83]
	ds_read_b128 v[206:209], v128 offset:4096
	v_mfma_f32_16x16x32_f16 v[88:91], v[224:227], v[220:223], v[88:91]
	ds_read_b128 v[220:223], v128 offset:6144
	s_waitcnt lgkmcnt(4)
	v_mfma_f32_16x16x32_f16 v[132:135], v[194:197], v[190:193], v[132:135]
	ds_read_b128 v[224:227], v131 offset:38912
	s_waitcnt lgkmcnt(4)
	v_mfma_f32_16x16x32_f16 v[92:95], v[194:197], v[198:201], v[92:95]
	s_waitcnt vmcnt(15)
	ds_write_b128 v126, v[32:35] offset:16384
	v_mfma_f32_16x16x32_f16 v[136:139], v[202:205], v[190:193], v[136:139]
	s_waitcnt vmcnt(14)
	ds_write_b128 v124, v[36:39] offset:16384
	v_mfma_f32_16x16x32_f16 v[144:147], v[202:205], v[198:201], v[144:147]
	s_waitcnt vmcnt(13)
	ds_write_b128 v125, v[40:43] offset:16384
	s_waitcnt lgkmcnt(5)
	v_mfma_f32_16x16x32_f16 v[158:161], v[194:197], v[206:209], v[158:161]
	s_waitcnt vmcnt(12)
	ds_write_b128 v127, v[44:47] offset:16384
	s_waitcnt lgkmcnt(5)
	v_mfma_f32_16x16x32_f16 v[68:71], v[194:197], v[220:223], v[68:71]
	ds_read_b128 v[194:197], v130 offset:32768
	v_mfma_f32_16x16x32_f16 v[162:165], v[202:205], v[206:209], v[162:165]
	s_waitcnt vmcnt(11)
	ds_write_b128 v126, v[48:51] offset:49152
	v_mfma_f32_16x16x32_f16 v[76:79], v[202:205], v[220:223], v[76:79]
	ds_read_b128 v[202:205], v130 offset:34816
	v_mfma_f32_16x16x32_f16 v[140:143], v[210:213], v[190:193], v[140:143]
	s_waitcnt vmcnt(10)
	ds_write_b128 v124, v[52:55] offset:49152
	v_mfma_f32_16x16x32_f16 v[154:157], v[210:213], v[198:201], v[154:157]
	s_waitcnt vmcnt(9)
	ds_write_b128 v125, v[56:59] offset:49152
	s_waitcnt lgkmcnt(9)
	v_mfma_f32_16x16x32_f16 v[64:67], v[224:227], v[190:193], v[64:67]
	ds_read_b128 v[190:193], v129
	v_mfma_f32_16x16x32_f16 v[72:75], v[224:227], v[198:201], v[72:75]
	ds_read_b128 v[198:201], v129 offset:2048
	v_mfma_f32_16x16x32_f16 v[166:169], v[210:213], v[206:209], v[166:169]
	s_waitcnt vmcnt(8)
	ds_write_b128 v127, v[60:63] offset:49152
	v_mfma_f32_16x16x32_f16 v[84:87], v[210:213], v[220:223], v[84:87]
	ds_read_b128 v[210:213], v130 offset:36864
	v_mfma_f32_16x16x32_f16 v[80:83], v[224:227], v[206:209], v[80:83]
	ds_read_b128 v[206:209], v129 offset:4096
	v_mfma_f32_16x16x32_f16 v[88:91], v[224:227], v[220:223], v[88:91]
	ds_read_b128 v[220:223], v129 offset:6144
	ds_read_b128 v[224:227], v130 offset:38912
	s_waitcnt lgkmcnt(0)
	s_barrier
	v_mfma_f32_16x16x32_f16 v[132:135], v[194:197], v[190:193], v[132:135]
	global_load_dwordx4 v[32:35], v[104:105], off offset:1408
	v_mfma_f32_16x16x32_f16 v[92:95], v[194:197], v[198:201], v[92:95]
	global_load_dwordx4 v[36:39], v[106:107], off offset:1408
	v_mfma_f32_16x16x32_f16 v[136:139], v[202:205], v[190:193], v[136:139]
	global_load_dwordx4 v[40:43], v[108:109], off offset:1408
	v_mfma_f32_16x16x32_f16 v[144:147], v[202:205], v[198:201], v[144:147]
	global_load_dwordx4 v[44:47], v[110:111], off offset:1408
	v_mfma_f32_16x16x32_f16 v[158:161], v[194:197], v[206:209], v[158:161]
	global_load_dwordx4 v[48:51], v[112:113], off offset:1408
	v_mfma_f32_16x16x32_f16 v[68:71], v[194:197], v[220:223], v[68:71]
	ds_read_b128 v[194:197], v131 offset:49152
	v_mfma_f32_16x16x32_f16 v[162:165], v[202:205], v[206:209], v[162:165]
	global_load_dwordx4 v[52:55], v[114:115], off offset:1408
	v_mfma_f32_16x16x32_f16 v[76:79], v[202:205], v[220:223], v[76:79]
	ds_read_b128 v[202:205], v131 offset:51200
	v_mfma_f32_16x16x32_f16 v[140:143], v[210:213], v[190:193], v[140:143]
	global_load_dwordx4 v[56:59], v[116:117], off offset:1408
	v_mfma_f32_16x16x32_f16 v[154:157], v[210:213], v[198:201], v[154:157]
	global_load_dwordx4 v[60:63], v[118:119], off offset:1408
	v_mfma_f32_16x16x32_f16 v[64:67], v[224:227], v[190:193], v[64:67]
	ds_read_b128 v[190:193], v128 offset:16384
	v_mfma_f32_16x16x32_f16 v[72:75], v[224:227], v[198:201], v[72:75]
	ds_read_b128 v[198:201], v128 offset:18432
	v_mfma_f32_16x16x32_f16 v[166:169], v[210:213], v[206:209], v[166:169]
	v_mfma_f32_16x16x32_f16 v[84:87], v[210:213], v[220:223], v[84:87]
	ds_read_b128 v[210:213], v131 offset:53248
	v_mfma_f32_16x16x32_f16 v[80:83], v[224:227], v[206:209], v[80:83]
	ds_read_b128 v[206:209], v128 offset:20480
	v_mfma_f32_16x16x32_f16 v[88:91], v[224:227], v[220:223], v[88:91]
	ds_read_b128 v[220:223], v128 offset:22528
	s_waitcnt lgkmcnt(4)
; #define GL_LOAD(s_, kt_) if (VAR != 1) { a##s_##0 = GL_A(0, kt_); a##s_##1 = GL_A(1, kt_); a##s_##2 = GL_A(2, kt_); a##s_##3 = GL_A(3, kt_); b##s_##0 = GL_B(0, kt_); b##s_##1 = GL_B(1, kt_); b##s_##2 = GL_B(2, kt_); b##s_##3 = GL_B(3, kt_); }
; #define LDS_STORE(s_, buf_) if (VAR != 2) { LDS_ST1(sA, 0, buf_, a##s_##0) LDS_ST1(sA, 1, buf_, a##s_##1) LDS_ST1(sA, 2, buf_, a##s_##2) LDS_ST1(sA, 3, buf_, a##s_##3) LDS_ST1(sB, 0, buf_, b##s_##0) LDS_ST1(sB, 1, buf_, b##s_##1) LDS_ST1(sB, 2, buf_, b##s_##2) LDS_ST1(sB, 3, buf_, b##s_##3) }
;     ...
;   GL_LOAD(0, 0)
;   GL_LOAD(1, 1)
;   LDS_STORE(0, 0)
;   if (VAR != 4) __syncthreads();
; #pragma unroll
;   for (int kt = 0; kt < nk; kt += 2) {
;     if (kt + 2 < nk) { GL_LOAD(0, kt + 2) }
;     MMA_TILE(0)
;     LDS_STORE(1, 1)
;     if (VAR != 4) __syncthreads();
;     if (kt + 3 < nk) { GL_LOAD(1, kt + 3) }
;     MMA_TILE(1)
;     if (kt + 2 < nk) { LDS_STORE(0, 0) }
;     if (VAR != 4) __syncthreads();
	v_mfma_f32_16x16x32_f16 v[132:135], v[194:197], v[190:193], v[132:135]
	ds_read_b128 v[224:227], v131 offset:55296
	s_waitcnt lgkmcnt(4)
	v_mfma_f32_16x16x32_f16 v[92:95], v[194:197], v[198:201], v[92:95]
	s_waitcnt vmcnt(15)
	ds_write_b128 v126, v[0:3]
	v_mfma_f32_16x16x32_f16 v[136:139], v[202:205], v[190:193], v[136:139]
	s_waitcnt vmcnt(14)
	ds_write_b128 v124, v[4:7]
	v_mfma_f32_16x16x32_f16 v[144:147], v[202:205], v[198:201], v[144:147]
	s_waitcnt vmcnt(13)
	ds_write_b128 v125, v[8:11]
	s_waitcnt lgkmcnt(5)
	v_mfma_f32_16x16x32_f16 v[158:161], v[194:197], v[206:209], v[158:161]
	s_waitcnt vmcnt(12)
	ds_write_b128 v127, v[12:15]
	s_waitcnt lgkmcnt(5)
	v_mfma_f32_16x16x32_f16 v[68:71], v[194:197], v[220:223], v[68:71]
	ds_read_b128 v[194:197], v130 offset:49152
	v_mfma_f32_16x16x32_f16 v[162:165], v[202:205], v[206:209], v[162:165]
	s_waitcnt vmcnt(11)
	ds_write_b128 v126, v[16:19] offset:32768
	v_mfma_f32_16x16x32_f16 v[76:79], v[202:205], v[220:223], v[76:79]
	ds_read_b128 v[202:205], v130 offset:51200
	v_mfma_f32_16x16x32_f16 v[140:143], v[210:213], v[190:193], v[140:143]
	s_waitcnt vmcnt(10)
	ds_write_b128 v124, v[20:23] offset:32768
	v_mfma_f32_16x16x32_f16 v[154:157], v[210:213], v[198:201], v[154:157]
	s_waitcnt vmcnt(9)
	ds_write_b128 v125, v[24:27] offset:32768
	s_waitcnt lgkmcnt(9)
	v_mfma_f32_16x16x32_f16 v[64:67], v[224:227], v[190:193], v[64:67]
	ds_read_b128 v[190:193], v129 offset:16384
	v_mfma_f32_16x16x32_f16 v[72:75], v[224:227], v[198:201], v[72:75]
	ds_read_b128 v[198:201], v129 offset:18432
	v_mfma_f32_16x16x32_f16 v[166:169], v[210:213], v[206:209], v[166:169]
	s_waitcnt vmcnt(8)
	ds_write_b128 v127, v[28:31] offset:32768
	v_mfma_f32_16x16x32_f16 v[84:87], v[210:213], v[220:223], v[84:87]
	ds_read_b128 v[210:213], v130 offset:53248
	v_mfma_f32_16x16x32_f16 v[80:83], v[224:227], v[206:209], v[80:83]
	ds_read_b128 v[206:209], v129 offset:20480
	v_mfma_f32_16x16x32_f16 v[88:91], v[224:227], v[220:223], v[88:91]
	ds_read_b128 v[220:223], v129 offset:22528
	s_waitcnt lgkmcnt(5)
	v_mfma_f32_16x16x32_f16 v[132:135], v[194:197], v[190:193], v[132:135]
	ds_read_b128 v[224:227], v130 offset:55296
	s_waitcnt lgkmcnt(0)
	s_barrier
	v_mfma_f32_16x16x32_f16 v[136:139], v[202:205], v[190:193], v[136:139]
	ds_read_b128 v[0:3], v128
	v_mfma_f32_16x16x32_f16 v[144:147], v[202:205], v[198:201], v[144:147]
	ds_read_b128 v[4:7], v131 offset:32768
	v_mfma_f32_16x16x32_f16 v[140:143], v[210:213], v[190:193], v[140:143]
	ds_read_b128 v[8:11], v128 offset:2048
	v_mfma_f32_16x16x32_f16 v[154:157], v[210:213], v[198:201], v[154:157]
	ds_read_b128 v[12:15], v131 offset:34816
	v_mfma_f32_16x16x32_f16 v[162:165], v[202:205], v[206:209], v[162:165]
	ds_read_b128 v[16:19], v128 offset:4096
	v_mfma_f32_16x16x32_f16 v[202:205], v[202:205], v[220:223], v[76:79]
	ds_read_b128 v[20:23], v131 offset:36864
	v_mfma_f32_16x16x32_f16 v[166:169], v[210:213], v[206:209], v[166:169]
	ds_read_b128 v[24:27], v128 offset:6144
	v_mfma_f32_16x16x32_f16 v[210:213], v[210:213], v[220:223], v[84:87]
	ds_read_b128 v[28:31], v131 offset:38912
	v_mfma_f32_16x16x32_f16 v[190:193], v[224:227], v[190:193], v[64:67]
	s_nop 2
	global_load_dwordx4 v[64:67], v[104:105], off offset:1536
	v_mfma_f32_16x16x32_f16 v[228:231], v[194:197], v[198:201], v[92:95]
	v_mfma_f32_16x16x32_f16 v[198:201], v[224:227], v[198:201], v[72:75]
	v_mfma_f32_16x16x32_f16 v[158:161], v[194:197], v[206:209], v[158:161]
	v_mfma_f32_16x16x32_f16 v[206:209], v[224:227], v[206:209], v[80:83]
	v_mfma_f32_16x16x32_f16 v[194:197], v[194:197], v[220:223], v[68:71]
	v_mfma_f32_16x16x32_f16 v[220:223], v[224:227], v[220:223], v[88:91]
	ds_read_b128 v[224:227], v130 offset:38912
	s_nop 0
	global_load_dwordx4 v[68:71], v[106:107], off offset:1536
	global_load_dwordx4 v[72:75], v[108:109], off offset:1536
	global_load_dwordx4 v[76:79], v[110:111], off offset:1536
	global_load_dwordx4 v[80:83], v[112:113], off offset:1536
	s_waitcnt lgkmcnt(7)
	v_mfma_f32_16x16x32_f16 v[132:135], v[4:7], v[0:3], v[132:135]
	global_load_dwordx4 v[84:87], v[114:115], off offset:1536
	s_waitcnt lgkmcnt(5)
	v_mfma_f32_16x16x32_f16 v[136:139], v[12:15], v[0:3], v[136:139]
	s_waitcnt lgkmcnt(3)
	v_mfma_f32_16x16x32_f16 v[140:143], v[20:23], v[0:3], v[140:143]
	s_waitcnt lgkmcnt(1)
	v_mfma_f32_16x16x32_f16 v[0:3], v[28:31], v[0:3], v[190:193]
	v_mfma_f32_16x16x32_f16 v[190:193], v[4:7], v[8:11], v[228:231]
	global_load_dwordx4 v[88:91], v[116:117], off offset:1536
	global_load_dwordx4 v[92:95], v[118:119], off offset:1536
	s_waitcnt vmcnt(15)
	ds_write_b128 v126, v[32:35] offset:16384
	s_waitcnt vmcnt(14)
	ds_write_b128 v124, v[36:39] offset:16384
	v_mfma_f32_16x16x32_f16 v[144:147], v[12:15], v[8:11], v[144:147]
	s_waitcnt vmcnt(13)
	ds_write_b128 v125, v[40:43] offset:16384
	v_mfma_f32_16x16x32_f16 v[158:161], v[4:7], v[16:19], v[158:161]
	s_waitcnt vmcnt(12)
	ds_write_b128 v127, v[44:47] offset:16384
	v_mfma_f32_16x16x32_f16 v[4:7], v[4:7], v[24:27], v[194:197]
	s_nop 2
	ds_read_b128 v[194:197], v130 offset:32768
	v_mfma_f32_16x16x32_f16 v[162:165], v[12:15], v[16:19], v[162:165]
	s_waitcnt vmcnt(11)
	ds_write_b128 v126, v[48:51] offset:49152
	v_mfma_f32_16x16x32_f16 v[12:15], v[12:15], v[24:27], v[202:205]
	s_nop 2
	ds_read_b128 v[202:205], v130 offset:34816
	s_waitcnt vmcnt(10)
	ds_write_b128 v124, v[52:55] offset:49152
	v_mfma_f32_16x16x32_f16 v[154:157], v[20:23], v[8:11], v[154:157]
	s_waitcnt vmcnt(9)
	ds_write_b128 v125, v[56:59] offset:49152
	s_waitcnt vmcnt(8)
	ds_write_b128 v127, v[60:63] offset:49152
	v_mfma_f32_16x16x32_f16 v[8:11], v[28:31], v[8:11], v[198:201]
	s_nop 2
	ds_read_b128 v[198:201], v129 offset:2048
	v_mfma_f32_16x16x32_f16 v[166:169], v[20:23], v[16:19], v[166:169]
	v_mfma_f32_16x16x32_f16 v[20:23], v[20:23], v[24:27], v[210:213]
	s_nop 2
	ds_read_b128 v[210:213], v130 offset:36864
	v_mfma_f32_16x16x32_f16 v[16:19], v[28:31], v[16:19], v[206:209]
	s_nop 2
	ds_read_b128 v[206:209], v129 offset:4096
	v_mfma_f32_16x16x32_f16 v[24:27], v[28:31], v[24:27], v[220:223]
	ds_read_b128 v[28:31], v129
	s_waitcnt lgkmcnt(0)
	v_mfma_f32_16x16x32_f16 v[132:135], v[194:197], v[28:31], v[132:135]
	ds_read_b128 v[220:223], v129 offset:6144
	s_waitcnt lgkmcnt(0)
	s_barrier
; #define GL_LOAD(s_, kt_) if (VAR != 1) { a##s_##0 = GL_A(0, kt_); a##s_##1 = GL_A(1, kt_); a##s_##2 = GL_A(2, kt_); a##s_##3 = GL_A(3, kt_); b##s_##0 = GL_B(0, kt_); b##s_##1 = GL_B(1, kt_); b##s_##2 = GL_B(2, kt_); b##s_##3 = GL_B(3, kt_); }
; #define LDS_STORE(s_, buf_) if (VAR != 2) { LDS_ST1(sA, 0, buf_, a##s_##0) LDS_ST1(sA, 1, buf_, a##s_##1) LDS_ST1(sA, 2, buf_, a##s_##2) LDS_ST1(sA, 3, buf_, a##s_##3) LDS_ST1(sB, 0, buf_, b##s_##0) LDS_ST1(sB, 1, buf_, b##s_##1) LDS_ST1(sB, 2, buf_, b##s_##2) LDS_ST1(sB, 3, buf_, b##s_##3) }
;     ...
;   GL_LOAD(0, 0)
;   GL_LOAD(1, 1)
;   LDS_STORE(0, 0)
;   if (VAR != 4) __syncthreads();
; #pragma unroll
;   for (int kt = 0; kt < nk; kt += 2) {
;     if (kt + 2 < nk) { GL_LOAD(0, kt + 2) }
;     MMA_TILE(0)
;     LDS_STORE(1, 1)
;     if (VAR != 4) __syncthreads();
;     if (kt + 3 < nk) { GL_LOAD(1, kt + 3) }
;     MMA_TILE(1)
;     if (kt + 2 < nk) { LDS_STORE(0, 0) }
;     if (VAR != 4) __syncthreads();
	v_mfma_f32_16x16x32_f16 v[136:139], v[202:205], v[28:31], v[136:139]
	ds_read_b128 v[32:35], v128 offset:16384
	v_mfma_f32_16x16x32_f16 v[144:147], v[202:205], v[198:201], v[144:147]
	ds_read_b128 v[36:39], v131 offset:49152
	v_mfma_f32_16x16x32_f16 v[140:143], v[210:213], v[28:31], v[140:143]
	ds_read_b128 v[40:43], v128 offset:18432
	v_mfma_f32_16x16x32_f16 v[154:157], v[210:213], v[198:201], v[154:157]
	ds_read_b128 v[44:47], v131 offset:51200
	v_mfma_f32_16x16x32_f16 v[162:165], v[202:205], v[206:209], v[162:165]
	ds_read_b128 v[48:51], v128 offset:20480
	v_mfma_f32_16x16x32_f16 v[202:205], v[202:205], v[220:223], v[12:15]
	ds_read_b128 v[52:55], v131 offset:53248
	v_mfma_f32_16x16x32_f16 v[166:169], v[210:213], v[206:209], v[166:169]
	ds_read_b128 v[56:59], v128 offset:22528
	v_mfma_f32_16x16x32_f16 v[210:213], v[210:213], v[220:223], v[20:23]
	ds_read_b128 v[60:63], v131 offset:55296
	v_mfma_f32_16x16x32_f16 v[228:231], v[224:227], v[28:31], v[0:3]
	global_load_dwordx4 v[28:31], v[104:105], off offset:1664
	v_mfma_f32_16x16x32_f16 v[190:193], v[194:197], v[198:201], v[190:193]
	v_mfma_f32_16x16x32_f16 v[198:201], v[224:227], v[198:201], v[8:11]
	v_mfma_f32_16x16x32_f16 v[158:161], v[194:197], v[206:209], v[158:161]
	v_mfma_f32_16x16x32_f16 v[206:209], v[224:227], v[206:209], v[16:19]
	v_mfma_f32_16x16x32_f16 v[194:197], v[194:197], v[220:223], v[4:7]
	v_mfma_f32_16x16x32_f16 v[220:223], v[224:227], v[220:223], v[24:27]
	ds_read_b128 v[224:227], v130 offset:55296
	s_nop 1
	global_load_dwordx4 v[24:27], v[106:107], off offset:1664
	global_load_dwordx4 v[12:15], v[108:109], off offset:1664
	global_load_dwordx4 v[16:19], v[110:111], off offset:1664
	global_load_dwordx4 v[20:23], v[112:113], off offset:1664
	s_waitcnt lgkmcnt(7)
	v_mfma_f32_16x16x32_f16 v[132:135], v[36:39], v[32:35], v[132:135]
	global_load_dwordx4 v[0:3], v[114:115], off offset:1664
	s_waitcnt lgkmcnt(6)
	v_mfma_f32_16x16x32_f16 v[190:193], v[36:39], v[40:43], v[190:193]
	global_load_dwordx4 v[4:7], v[116:117], off offset:1664
	s_waitcnt lgkmcnt(5)
	v_mfma_f32_16x16x32_f16 v[136:139], v[44:47], v[32:35], v[136:139]
	global_load_dwordx4 v[8:11], v[118:119], off offset:1664
	v_mfma_f32_16x16x32_f16 v[144:147], v[44:47], v[40:43], v[144:147]
	s_waitcnt vmcnt(15)
	ds_write_b128 v126, v[64:67]
	s_waitcnt lgkmcnt(5)
	v_mfma_f32_16x16x32_f16 v[158:161], v[36:39], v[48:51], v[158:161]
	s_waitcnt vmcnt(14)
	ds_write_b128 v124, v[68:71]
	s_waitcnt lgkmcnt(4)
	v_mfma_f32_16x16x32_f16 v[36:39], v[36:39], v[56:59], v[194:197]
	s_nop 2
	ds_read_b128 v[194:197], v130 offset:49152
	v_mfma_f32_16x16x32_f16 v[162:165], v[44:47], v[48:51], v[162:165]
	s_waitcnt vmcnt(13)
	ds_write_b128 v125, v[72:75]
	v_mfma_f32_16x16x32_f16 v[44:47], v[44:47], v[56:59], v[202:205]
	s_nop 2
	ds_read_b128 v[202:205], v130 offset:51200
	v_mfma_f32_16x16x32_f16 v[140:143], v[52:55], v[32:35], v[140:143]
	s_waitcnt vmcnt(12)
	ds_write_b128 v127, v[76:79]
	v_mfma_f32_16x16x32_f16 v[154:157], v[52:55], v[40:43], v[154:157]
	s_waitcnt vmcnt(11)
	ds_write_b128 v126, v[80:83] offset:32768
	s_waitcnt lgkmcnt(8)
	v_mfma_f32_16x16x32_f16 v[32:35], v[60:63], v[32:35], v[228:231]
	s_waitcnt vmcnt(10)
	ds_write_b128 v124, v[84:87] offset:32768
	v_mfma_f32_16x16x32_f16 v[40:43], v[60:63], v[40:43], v[198:201]
	s_nop 2
	ds_read_b128 v[198:201], v129 offset:18432
	v_mfma_f32_16x16x32_f16 v[166:169], v[52:55], v[48:51], v[166:169]
	s_waitcnt vmcnt(9)
	ds_write_b128 v125, v[88:91] offset:32768
	v_mfma_f32_16x16x32_f16 v[52:55], v[52:55], v[56:59], v[210:213]
	s_nop 2
	ds_read_b128 v[210:213], v130 offset:53248
	v_mfma_f32_16x16x32_f16 v[48:51], v[60:63], v[48:51], v[206:209]
	s_nop 2
	ds_read_b128 v[206:209], v129 offset:20480
	v_mfma_f32_16x16x32_f16 v[56:59], v[60:63], v[56:59], v[220:223]
	ds_read_b128 v[60:63], v129 offset:16384
	s_waitcnt lgkmcnt(0)
	v_mfma_f32_16x16x32_f16 v[132:135], v[194:197], v[60:63], v[132:135]
	ds_read_b128 v[220:223], v129 offset:22528
	s_waitcnt vmcnt(8)
	ds_write_b128 v127, v[92:95] offset:32768
	s_waitcnt lgkmcnt(0)
	s_barrier
	v_mfma_f32_16x16x32_f16 v[136:139], v[202:205], v[60:63], v[136:139]
	ds_read_b128 v[64:67], v128
	v_mfma_f32_16x16x32_f16 v[144:147], v[202:205], v[198:201], v[144:147]
	ds_read_b128 v[68:71], v131 offset:32768
	v_mfma_f32_16x16x32_f16 v[140:143], v[210:213], v[60:63], v[140:143]
	ds_read_b128 v[72:75], v128 offset:2048
	v_mfma_f32_16x16x32_f16 v[154:157], v[210:213], v[198:201], v[154:157]
	ds_read_b128 v[76:79], v131 offset:34816
	v_mfma_f32_16x16x32_f16 v[162:165], v[202:205], v[206:209], v[162:165]
	ds_read_b128 v[80:83], v128 offset:4096
	v_mfma_f32_16x16x32_f16 v[202:205], v[202:205], v[220:223], v[44:47]
	ds_read_b128 v[84:87], v131 offset:36864
	v_mfma_f32_16x16x32_f16 v[166:169], v[210:213], v[206:209], v[166:169]
	ds_read_b128 v[88:91], v128 offset:6144
	v_mfma_f32_16x16x32_f16 v[210:213], v[210:213], v[220:223], v[52:55]
	ds_read_b128 v[92:95], v131 offset:38912
	v_mfma_f32_16x16x32_f16 v[228:231], v[224:227], v[60:63], v[32:35]
	s_nop 0
	global_load_dwordx4 v[52:55], v[104:105], off offset:1792
	v_mfma_f32_16x16x32_f16 v[190:193], v[194:197], v[198:201], v[190:193]
	v_mfma_f32_16x16x32_f16 v[198:201], v[224:227], v[198:201], v[40:43]
	v_mfma_f32_16x16x32_f16 v[158:161], v[194:197], v[206:209], v[158:161]
	v_mfma_f32_16x16x32_f16 v[206:209], v[224:227], v[206:209], v[48:51]
	s_waitcnt vmcnt(8)
	ds_write_b128 v126, v[28:31] offset:16384
	s_waitcnt vmcnt(7)
; #define GL_LOAD(s_, kt_) if (VAR != 1) { a##s_##0 = GL_A(0, kt_); a##s_##1 = GL_A(1, kt_); a##s_##2 = GL_A(2, kt_); a##s_##3 = GL_A(3, kt_); b##s_##0 = GL_B(0, kt_); b##s_##1 = GL_B(1, kt_); b##s_##2 = GL_B(2, kt_); b##s_##3 = GL_B(3, kt_); }
; #define LDS_STORE(s_, buf_) if (VAR != 2) { LDS_ST1(sA, 0, buf_, a##s_##0) LDS_ST1(sA, 1, buf_, a##s_##1) LDS_ST1(sA, 2, buf_, a##s_##2) LDS_ST1(sA, 3, buf_, a##s_##3) LDS_ST1(sB, 0, buf_, b##s_##0) LDS_ST1(sB, 1, buf_, b##s_##1) LDS_ST1(sB, 2, buf_, b##s_##2) LDS_ST1(sB, 3, buf_, b##s_##3) }
;     ...
;   GL_LOAD(0, 0)
;   GL_LOAD(1, 1)
;   LDS_STORE(0, 0)
;   if (VAR != 4) __syncthreads();
; #pragma unroll
;   for (int kt = 0; kt < nk; kt += 2) {
;     if (kt + 2 < nk) { GL_LOAD(0, kt + 2) }
;     MMA_TILE(0)
;     LDS_STORE(1, 1)
;     if (VAR != 4) __syncthreads();
;     if (kt + 3 < nk) { GL_LOAD(1, kt + 3) }
;     MMA_TILE(1)
;     if (kt + 2 < nk) { LDS_STORE(0, 0) }
;     if (VAR != 4) __syncthreads();
	ds_write_b128 v124, v[24:27] offset:16384
	v_mfma_f32_16x16x32_f16 v[194:197], v[194:197], v[220:223], v[36:39]
	v_mfma_f32_16x16x32_f16 v[220:223], v[224:227], v[220:223], v[56:59]
	ds_read_b128 v[224:227], v130 offset:38912
	s_nop 1
	global_load_dwordx4 v[56:59], v[106:107], off offset:1792
	global_load_dwordx4 v[60:63], v[108:109], off offset:1792
	global_load_dwordx4 v[40:43], v[110:111], off offset:1792
	global_load_dwordx4 v[44:47], v[112:113], off offset:1792
	s_waitcnt lgkmcnt(9)
	v_mfma_f32_16x16x32_f16 v[132:135], v[68:71], v[64:67], v[132:135]
	global_load_dwordx4 v[48:51], v[114:115], off offset:1792
	s_waitcnt lgkmcnt(8)
	v_mfma_f32_16x16x32_f16 v[190:193], v[68:71], v[72:75], v[190:193]
	global_load_dwordx4 v[32:35], v[116:117], off offset:1792
	s_waitcnt lgkmcnt(7)
	v_mfma_f32_16x16x32_f16 v[136:139], v[76:79], v[64:67], v[136:139]
	global_load_dwordx4 v[36:39], v[118:119], off offset:1792
	v_mfma_f32_16x16x32_f16 v[144:147], v[76:79], v[72:75], v[144:147]
	s_waitcnt vmcnt(13)
	ds_write_b128 v125, v[12:15] offset:16384
	s_waitcnt lgkmcnt(7)
	v_mfma_f32_16x16x32_f16 v[158:161], v[68:71], v[80:83], v[158:161]
	s_waitcnt vmcnt(12)
	ds_write_b128 v127, v[16:19] offset:16384
	s_waitcnt lgkmcnt(6)
	v_mfma_f32_16x16x32_f16 v[68:71], v[68:71], v[88:91], v[194:197]
	s_nop 2
	ds_read_b128 v[194:197], v130 offset:32768
	v_mfma_f32_16x16x32_f16 v[162:165], v[76:79], v[80:83], v[162:165]
	s_waitcnt vmcnt(11)
	ds_write_b128 v126, v[20:23] offset:49152
	v_mfma_f32_16x16x32_f16 v[76:79], v[76:79], v[88:91], v[202:205]
	s_nop 2
	ds_read_b128 v[202:205], v130 offset:34816
	v_mfma_f32_16x16x32_f16 v[140:143], v[84:87], v[64:67], v[140:143]
	s_waitcnt vmcnt(10)
	ds_write_b128 v124, v[0:3] offset:49152
	v_mfma_f32_16x16x32_f16 v[154:157], v[84:87], v[72:75], v[154:157]
	s_waitcnt vmcnt(9)
	ds_write_b128 v125, v[4:7] offset:49152
	s_waitcnt lgkmcnt(10)
	v_mfma_f32_16x16x32_f16 v[64:67], v[92:95], v[64:67], v[228:231]
	s_waitcnt vmcnt(8)
	ds_write_b128 v127, v[8:11] offset:49152
	v_mfma_f32_16x16x32_f16 v[72:75], v[92:95], v[72:75], v[198:201]
	s_nop 2
	ds_read_b128 v[198:201], v129 offset:2048
	v_mfma_f32_16x16x32_f16 v[166:169], v[84:87], v[80:83], v[166:169]
	v_mfma_f32_16x16x32_f16 v[84:87], v[84:87], v[88:91], v[210:213]
	s_nop 2
	ds_read_b128 v[210:213], v130 offset:36864
	v_mfma_f32_16x16x32_f16 v[80:83], v[92:95], v[80:83], v[206:209]
	s_nop 2
	ds_read_b128 v[206:209], v129 offset:4096
	v_mfma_f32_16x16x32_f16 v[88:91], v[92:95], v[88:91], v[220:223]
	ds_read_b128 v[92:95], v129
	s_nop 1
	ds_read_b128 v[220:223], v129 offset:6144
	s_waitcnt lgkmcnt(0)
	s_barrier
	v_mfma_f32_16x16x32_f16 v[132:135], v[194:197], v[92:95], v[132:135]
	global_load_dwordx4 v[24:27], v[104:105], off offset:1920
	v_mfma_f32_16x16x32_f16 v[136:139], v[202:205], v[92:95], v[136:139]
	v_mfma_f32_16x16x32_f16 v[140:143], v[210:213], v[92:95], v[140:143]
	v_mfma_f32_16x16x32_f16 v[64:67], v[224:227], v[92:95], v[64:67]
	v_mfma_f32_16x16x32_f16 v[92:95], v[194:197], v[198:201], v[190:193]
	s_nop 2
	ds_read_b128 v[190:193], v128 offset:20480
	global_load_dwordx4 v[28:31], v[106:107], off offset:1920
	ds_read_b128 v[104:107], v128 offset:16384
	v_mfma_f32_16x16x32_f16 v[144:147], v[202:205], v[198:201], v[144:147]
	global_load_dwordx4 v[12:15], v[108:109], off offset:1920
	v_mfma_f32_16x16x32_f16 v[158:161], v[194:197], v[206:209], v[158:161]
	global_load_dwordx4 v[16:19], v[110:111], off offset:1920
	v_mfma_f32_16x16x32_f16 v[68:71], v[194:197], v[220:223], v[68:71]
	ds_read_b128 v[108:111], v131 offset:49152
	v_mfma_f32_16x16x32_f16 v[162:165], v[202:205], v[206:209], v[162:165]
	ds_read_b128 v[194:197], v131 offset:53248
	v_mfma_f32_16x16x32_f16 v[76:79], v[202:205], v[220:223], v[76:79]
	ds_read_b128 v[202:205], v131 offset:55296
	global_load_dwordx4 v[20:23], v[112:113], off offset:1920
	v_mfma_f32_16x16x32_f16 v[154:157], v[210:213], v[198:201], v[154:157]
	global_load_dwordx4 v[0:3], v[114:115], off offset:1920
	ds_read_b128 v[112:115], v128 offset:18432
	v_mfma_f32_16x16x32_f16 v[72:75], v[224:227], v[198:201], v[72:75]
	ds_read_b128 v[198:201], v128 offset:22528
	v_mfma_f32_16x16x32_f16 v[166:169], v[210:213], v[206:209], v[166:169]
	global_load_dwordx4 v[4:7], v[116:117], off offset:1920
	v_mfma_f32_16x16x32_f16 v[84:87], v[210:213], v[220:223], v[84:87]
	global_load_dwordx4 v[8:11], v[118:119], off offset:1920
	v_mfma_f32_16x16x32_f16 v[80:83], v[224:227], v[206:209], v[80:83]
	ds_read_b128 v[116:119], v131 offset:51200
	v_mfma_f32_16x16x32_f16 v[88:91], v[224:227], v[220:223], v[88:91]
	s_waitcnt vmcnt(15)
	ds_write_b128 v126, v[52:55]
	s_waitcnt lgkmcnt(6)
	v_mfma_f32_16x16x32_f16 v[132:135], v[108:111], v[104:107], v[132:135]
	s_waitcnt vmcnt(14)
	ds_write_b128 v124, v[56:59]
	s_waitcnt lgkmcnt(4)
	v_mfma_f32_16x16x32_f16 v[92:95], v[108:111], v[112:115], v[92:95]
	s_waitcnt vmcnt(13)
	ds_write_b128 v125, v[60:63]
	s_waitcnt lgkmcnt(3)
	v_mfma_f32_16x16x32_f16 v[136:139], v[116:119], v[104:107], v[136:139]
	s_waitcnt vmcnt(12)
	ds_write_b128 v127, v[40:43]
	v_mfma_f32_16x16x32_f16 v[140:143], v[194:197], v[104:107], v[140:143]
	v_mfma_f32_16x16x32_f16 v[64:67], v[202:205], v[104:107], v[64:67]
	v_mfma_f32_16x16x32_f16 v[104:107], v[116:119], v[112:115], v[144:147]
	s_waitcnt vmcnt(11)
	ds_write_b128 v126, v[44:47] offset:32768
	v_mfma_f32_16x16x32_f16 v[144:147], v[194:197], v[112:115], v[154:157]
	v_mfma_f32_16x16x32_f16 v[72:75], v[202:205], v[112:115], v[72:75]
	v_mfma_f32_16x16x32_f16 v[112:115], v[108:111], v[190:193], v[158:161]
	s_waitcnt vmcnt(10)
	ds_write_b128 v124, v[48:51] offset:32768
	s_waitcnt vmcnt(9)
	ds_write_b128 v125, v[32:35] offset:32768
	v_mfma_f32_16x16x32_f16 v[68:71], v[108:111], v[198:201], v[68:71]
	ds_read_b128 v[108:111], v129 offset:16384
	v_mfma_f32_16x16x32_f16 v[154:157], v[116:119], v[190:193], v[162:165]
	s_nop 2
	ds_read_b128 v[162:165], v129 offset:18432
	v_mfma_f32_16x16x32_f16 v[76:79], v[116:119], v[198:201], v[76:79]
	ds_read_b128 v[116:119], v130 offset:49152
	s_waitcnt vmcnt(8)
	ds_write_b128 v127, v[36:39] offset:32768
	v_mfma_f32_16x16x32_f16 v[158:161], v[194:197], v[190:193], v[166:169]
	s_nop 2
	ds_read_b128 v[166:169], v130 offset:51200
	v_mfma_f32_16x16x32_f16 v[84:87], v[194:197], v[198:201], v[84:87]
	ds_read_b128 v[194:197], v130 offset:53248
	v_mfma_f32_16x16x32_f16 v[80:83], v[202:205], v[190:193], v[80:83]
	ds_read_b128 v[190:193], v129 offset:20480
	v_mfma_f32_16x16x32_f16 v[88:91], v[202:205], v[198:201], v[88:91]
	ds_read_b128 v[198:201], v129 offset:22528
	s_waitcnt lgkmcnt(5)
	v_mfma_f32_16x16x32_f16 v[132:135], v[116:119], v[108:111], v[132:135]
	ds_read_b128 v[202:205], v130 offset:55296
	s_waitcnt lgkmcnt(0)
	s_barrier
; #define GL_LOAD(s_, kt_) if (VAR != 1) { a##s_##0 = GL_A(0, kt_); a##s_##1 = GL_A(1, kt_); a##s_##2 = GL_A(2, kt_); a##s_##3 = GL_A(3, kt_); b##s_##0 = GL_B(0, kt_); b##s_##1 = GL_B(1, kt_); b##s_##2 = GL_B(2, kt_); b##s_##3 = GL_B(3, kt_); }
; #define LDS_STORE(s_, buf_) if (VAR != 2) { LDS_ST1(sA, 0, buf_, a##s_##0) LDS_ST1(sA, 1, buf_, a##s_##1) LDS_ST1(sA, 2, buf_, a##s_##2) LDS_ST1(sA, 3, buf_, a##s_##3) LDS_ST1(sB, 0, buf_, b##s_##0) LDS_ST1(sB, 1, buf_, b##s_##1) LDS_ST1(sB, 2, buf_, b##s_##2) LDS_ST1(sB, 3, buf_, b##s_##3) }
;     ...
;   GL_LOAD(0, 0)
;   GL_LOAD(1, 1)
;   LDS_STORE(0, 0)
;   if (VAR != 4) __syncthreads();
; #pragma unroll
;   for (int kt = 0; kt < nk; kt += 2) {
;     if (kt + 2 < nk) { GL_LOAD(0, kt + 2) }
;     MMA_TILE(0)
;     LDS_STORE(1, 1)
;     if (VAR != 4) __syncthreads();
;     if (kt + 3 < nk) { GL_LOAD(1, kt + 3) }
;     MMA_TILE(1)
;     if (kt + 2 < nk) { LDS_STORE(0, 0) }
;     if (VAR != 4) __syncthreads();
	ds_read_b128 v[32:35], v128
	ds_read_b128 v[36:39], v131 offset:32768
	ds_read_b128 v[40:43], v128 offset:2048
	ds_read_b128 v[44:47], v131 offset:34816
	ds_read_b128 v[48:51], v128 offset:4096
	ds_read_b128 v[52:55], v131 offset:36864
	ds_read_b128 v[56:59], v128 offset:6144
	ds_read_b128 v[60:63], v131 offset:38912
	v_mfma_f32_16x16x32_f16 v[136:139], v[166:169], v[108:111], v[136:139]
	v_mfma_f32_16x16x32_f16 v[140:143], v[194:197], v[108:111], v[140:143]
	v_mfma_f32_16x16x32_f16 v[64:67], v[202:205], v[108:111], v[64:67]
	v_mfma_f32_16x16x32_f16 v[92:95], v[116:119], v[162:165], v[92:95]
	v_mfma_f32_16x16x32_f16 v[104:107], v[166:169], v[162:165], v[104:107]
	v_mfma_f32_16x16x32_f16 v[108:111], v[194:197], v[162:165], v[144:147]
	v_mfma_f32_16x16x32_f16 v[72:75], v[202:205], v[162:165], v[72:75]
	v_mfma_f32_16x16x32_f16 v[112:115], v[116:119], v[190:193], v[112:115]
	v_mfma_f32_16x16x32_f16 v[144:147], v[166:169], v[190:193], v[154:157]
	v_mfma_f32_16x16x32_f16 v[154:157], v[194:197], v[190:193], v[158:161]
	v_mfma_f32_16x16x32_f16 v[80:83], v[202:205], v[190:193], v[80:83]
	v_mfma_f32_16x16x32_f16 v[68:71], v[116:119], v[198:201], v[68:71]
	v_mfma_f32_16x16x32_f16 v[76:79], v[166:169], v[198:201], v[76:79]
	v_mfma_f32_16x16x32_f16 v[84:87], v[194:197], v[198:201], v[84:87]
	v_mfma_f32_16x16x32_f16 v[88:91], v[202:205], v[198:201], v[88:91]
	s_waitcnt lgkmcnt(6)
	v_mfma_f32_16x16x32_f16 v[116:119], v[36:39], v[32:35], v[132:135]
	s_waitcnt lgkmcnt(4)
	v_mfma_f32_16x16x32_f16 v[132:135], v[44:47], v[32:35], v[136:139]
	s_waitcnt lgkmcnt(2)
	v_mfma_f32_16x16x32_f16 v[136:139], v[52:55], v[32:35], v[140:143]
	s_waitcnt lgkmcnt(0)
	v_mfma_f32_16x16x32_f16 v[32:35], v[60:63], v[32:35], v[64:67]
	v_mfma_f32_16x16x32_f16 v[64:67], v[36:39], v[40:43], v[92:95]
	v_mfma_f32_16x16x32_f16 v[92:95], v[44:47], v[40:43], v[104:107]
	v_mfma_f32_16x16x32_f16 v[104:107], v[52:55], v[40:43], v[108:111]
	v_mfma_f32_16x16x32_f16 v[40:43], v[60:63], v[40:43], v[72:75]
	v_mfma_f32_16x16x32_f16 v[72:75], v[36:39], v[48:51], v[112:115]
	v_mfma_f32_16x16x32_f16 v[108:111], v[44:47], v[48:51], v[144:147]
	v_mfma_f32_16x16x32_f16 v[112:115], v[52:55], v[48:51], v[154:157]
	v_mfma_f32_16x16x32_f16 v[48:51], v[60:63], v[48:51], v[80:83]
	v_mfma_f32_16x16x32_f16 v[36:39], v[36:39], v[56:59], v[68:71]
	v_mfma_f32_16x16x32_f16 v[44:47], v[44:47], v[56:59], v[76:79]
	v_mfma_f32_16x16x32_f16 v[52:55], v[52:55], v[56:59], v[84:87]
	v_mfma_f32_16x16x32_f16 v[56:59], v[60:63], v[56:59], v[88:91]
	ds_read_b128 v[60:63], v129
	ds_read_b128 v[68:71], v130 offset:32768
	ds_read_b128 v[76:79], v129 offset:2048
	ds_read_b128 v[80:83], v130 offset:34816
	ds_read_b128 v[84:87], v129 offset:4096
	ds_read_b128 v[88:91], v130 offset:36864
	ds_read_b128 v[140:143], v129 offset:6144
	ds_read_b128 v[144:147], v130 offset:38912
	s_waitcnt vmcnt(7)
	ds_write_b128 v126, v[24:27] offset:16384
	s_waitcnt vmcnt(6)
	ds_write_b128 v124, v[28:31] offset:16384
	s_waitcnt vmcnt(5)
	ds_write_b128 v125, v[12:15] offset:16384
	s_waitcnt vmcnt(4)
	ds_write_b128 v127, v[16:19] offset:16384
	s_waitcnt vmcnt(3)
	ds_write_b128 v126, v[20:23] offset:49152
	s_waitcnt vmcnt(2)
	ds_write_b128 v124, v[0:3] offset:49152
	s_waitcnt vmcnt(1)
	ds_write_b128 v125, v[4:7] offset:49152
	s_waitcnt vmcnt(0)
	ds_write_b128 v127, v[8:11] offset:49152
	s_waitcnt lgkmcnt(0)
	v_mfma_f32_16x16x32_f16 v[116:119], v[68:71], v[60:63], v[116:119]
	s_barrier
	ds_read_b128 v[0:3], v128 offset:16384
	ds_read_b128 v[4:7], v131 offset:49152
	ds_read_b128 v[8:11], v128 offset:18432
	ds_read_b128 v[12:15], v131 offset:51200
	ds_read_b128 v[16:19], v128 offset:20480
	ds_read_b128 v[20:23], v131 offset:53248
	ds_read_b128 v[24:27], v128 offset:22528
	ds_read_b128 v[28:31], v131 offset:55296
	v_mfma_f32_16x16x32_f16 v[132:135], v[80:83], v[60:63], v[132:135]
	v_mfma_f32_16x16x32_f16 v[136:139], v[88:91], v[60:63], v[136:139]
	v_mfma_f32_16x16x32_f16 v[32:35], v[144:147], v[60:63], v[32:35]
	v_mfma_f32_16x16x32_f16 v[60:63], v[68:71], v[76:79], v[64:67]
	v_mfma_f32_16x16x32_f16 v[64:67], v[80:83], v[76:79], v[92:95]
	v_mfma_f32_16x16x32_f16 v[92:95], v[88:91], v[76:79], v[104:107]
	v_mfma_f32_16x16x32_f16 v[40:43], v[144:147], v[76:79], v[40:43]
	v_mfma_f32_16x16x32_f16 v[72:75], v[68:71], v[84:87], v[72:75]
	v_mfma_f32_16x16x32_f16 v[76:79], v[80:83], v[84:87], v[108:111]
	v_mfma_f32_16x16x32_f16 v[104:107], v[88:91], v[84:87], v[112:115]
	v_mfma_f32_16x16x32_f16 v[48:51], v[144:147], v[84:87], v[48:51]
	v_mfma_f32_16x16x32_f16 v[36:39], v[68:71], v[140:143], v[36:39]
	v_mfma_f32_16x16x32_f16 v[44:47], v[80:83], v[140:143], v[44:47]
	v_mfma_f32_16x16x32_f16 v[52:55], v[88:91], v[140:143], v[52:55]
	v_mfma_f32_16x16x32_f16 v[56:59], v[144:147], v[140:143], v[56:59]
	s_waitcnt lgkmcnt(6)
	v_mfma_f32_16x16x32_f16 v[68:71], v[4:7], v[0:3], v[116:119]
	s_waitcnt lgkmcnt(4)
	v_mfma_f32_16x16x32_f16 v[80:83], v[12:15], v[0:3], v[132:135]
	s_waitcnt lgkmcnt(2)
	v_mfma_f32_16x16x32_f16 v[84:87], v[20:23], v[0:3], v[136:139]
	s_waitcnt lgkmcnt(0)
	v_mfma_f32_16x16x32_f16 v[0:3], v[28:31], v[0:3], v[32:35]
	v_mfma_f32_16x16x32_f16 v[32:35], v[4:7], v[8:11], v[60:63]
	v_mfma_f32_16x16x32_f16 v[60:63], v[12:15], v[8:11], v[64:67]
	v_mfma_f32_16x16x32_f16 v[64:67], v[20:23], v[8:11], v[92:95]
	v_mfma_f32_16x16x32_f16 v[8:11], v[28:31], v[8:11], v[40:43]
	v_mfma_f32_16x16x32_f16 v[40:43], v[4:7], v[16:19], v[72:75]
	v_mfma_f32_16x16x32_f16 v[72:75], v[12:15], v[16:19], v[76:79]
	v_mfma_f32_16x16x32_f16 v[92:95], v[20:23], v[16:19], v[104:107]
	v_mfma_f32_16x16x32_f16 v[16:19], v[28:31], v[16:19], v[48:51]
	v_mfma_f32_16x16x32_f16 v[4:7], v[4:7], v[24:27], v[36:39]
	v_mfma_f32_16x16x32_f16 v[12:15], v[12:15], v[24:27], v[44:47]
	v_mfma_f32_16x16x32_f16 v[52:55], v[20:23], v[24:27], v[52:55]
	v_mfma_f32_16x16x32_f16 v[28:31], v[28:31], v[24:27], v[56:59]
	ds_read_b128 v[20:23], v129 offset:16384
	ds_read_b128 v[104:107], v130 offset:49152
	ds_read_b128 v[24:27], v129 offset:18432
	ds_read_b128 v[108:111], v130 offset:51200
	ds_read_b128 v[112:115], v129 offset:20480
	ds_read_b128 v[116:119], v130 offset:53248
	ds_read_b128 v[124:127], v129 offset:22528
	ds_read_b128 v[128:131], v130 offset:55296
	s_waitcnt lgkmcnt(0)
	s_barrier
; DI int TIDX() { int t = threadIdx.x; asm volatile("" : "+v"(t)); return t; }
; DI unsigned pack2(float lo, float hi) { f2_t v = {lo, hi}; h2_t b = __builtin_convertvector(v, h2_t); return __builtin_bit_cast(unsigned, b); }
; DI float lo_f(unsigned u) { return (float)(__builtin_bit_cast(h2_t, u)[0]); }
; DI float hi_f(unsigned u) { return (float)(__builtin_bit_cast(h2_t, u)[1]); }
; DI float sigmoidf_(float x) { return 1.0f / (1.0f + __expf(-x)); }
; DI void epi_residual(const f32x4 (&v)[4][4], int row0, int col0, const float* xsrc, float* x, bf16_t* xb, float* ssq_out, bool write_xb, bool write_ssq) {
;   const int lane = TIDX() & 63, lr = lane & 15, g = lane >> 4;
; #pragma unroll
;   for (int mt = 0; mt < 4; ++mt) {
;     const int row = row0 + mt * 16 + lr;
;     float ss = 0.f;
; #pragma unroll
;     for (int nt = 0; nt < 4; ++nt) {
;       const int col = col0 + nt * 16 + 4 * g;
;       float4* px = (float4*)(x + (size_t)row * DM + col);
;       float4 o = *(const float4*)(xsrc + (size_t)row * DM + col);
;       o.x += v[mt][nt][0]; o.y += v[mt][nt][1]; o.z += v[mt][nt][2]; o.w += v[mt][nt][3];
;       *px = o;
;       ss += (o.x * o.x + o.y * o.y) + (o.z * o.z + o.w * o.w);
;       if (write_xb) *(uint2*)(xb + (size_t)row * DM + col) = make_uint2(pack2(o.x, o.y), pack2(o.z, o.w));
;     }
; DI void phase_ple(const Params& P, int l, char* smem) {
;     ...
; #pragma unroll
;     for (int mt = 0; mt < 4; ++mt)
; #pragma unroll
;       for (int h = 0; h < 2; ++h) {
;         const uint4 q = park[mt * 2 + h];
;         acc[mt][2 * h][0] = sigmoidf_(acc[mt][2 * h][0] * rs[mt]) * lo_f(q.x);
;         acc[mt][2 * h][1] = sigmoidf_(acc[mt][2 * h][1] * rs[mt]) * hi_f(q.x);
;         acc[mt][2 * h][2] = sigmoidf_(acc[mt][2 * h][2] * rs[mt]) * lo_f(q.y);
;         acc[mt][2 * h][3] = sigmoidf_(acc[mt][2 * h][3] * rs[mt]) * hi_f(q.y);
;         acc[mt][2 * h + 1][0] = sigmoidf_(acc[mt][2 * h + 1][0] * rs[mt]) * lo_f(q.z);
;         acc[mt][2 * h + 1][1] = sigmoidf_(acc[mt][2 * h + 1][1] * rs[mt]) * hi_f(q.z);
;         acc[mt][2 * h + 1][2] = sigmoidf_(acc[mt][2 * h + 1][2] * rs[mt]) * lo_f(q.w);
;         acc[mt][2 * h + 1][3] = sigmoidf_(acc[mt][2 * h + 1][3] * rs[mt]) * hi_f(q.w);
;       }
;     epi_residual(acc, row0, col0, P.out, P.out, xb2, ssq_out, l + 1 < DEPTH, l + 1 < DEPTH);
	s_setprio 0
	v_mfma_f32_16x16x32_f16 v[132:135], v[104:107], v[20:23], v[68:71]
	v_mfma_f32_16x16x32_f16 v[88:91], v[108:111], v[20:23], v[80:83]
	v_mfma_f32_16x16x32_f16 v[84:87], v[116:119], v[20:23], v[84:87]
	v_mfma_f32_16x16x32_f16 v[76:79], v[128:131], v[20:23], v[0:3]
	v_mfma_f32_16x16x32_f16 v[20:23], v[104:107], v[124:127], v[4:7]
	s_nop 3
	v_mul_f32_e32 v4, v101, v132
	v_mul_f32_e32 v4, 0xbfb8aa3b, v4
	v_mfma_f32_16x16x32_f16 v[36:39], v[108:111], v[112:115], v[72:75]
	s_nop 2
	v_exp_f32_e32 v72, v4
	v_mul_f32_e32 v4, v101, v133
	v_mul_f32_e32 v4, 0xbfb8aa3b, v4
	v_exp_f32_e32 v73, v4
	v_mul_f32_e32 v4, v101, v134
	v_mul_f32_e32 v4, 0xbfb8aa3b, v4
	v_mfma_f32_16x16x32_f16 v[60:63], v[108:111], v[24:27], v[60:63]
	v_mov_b32_e32 v74, v148
	v_pk_add_f32 v[72:73], v[72:73], 1.0 op_sel_hi:[1,0]
	v_mfma_f32_16x16x32_f16 v[12:15], v[108:111], v[124:127], v[12:15]
	v_exp_f32_e32 v110, v4
	v_mul_f32_e32 v4, v101, v135
	v_mul_f32_e32 v4, 0xbfb8aa3b, v4
	v_mfma_f32_16x16x32_f16 v[68:71], v[104:107], v[24:27], v[32:35]
	v_exp_f32_e32 v111, v4
	s_nop 0
	v_pk_add_f32 v[110:111], v[110:111], 1.0 op_sel_hi:[1,0]
	v_mfma_f32_16x16x32_f16 v[56:59], v[116:119], v[24:27], v[64:67]
	v_mfma_f32_16x16x32_f16 v[48:51], v[128:131], v[24:27], v[8:11]
	v_mfma_f32_16x16x32_f16 v[44:47], v[104:107], v[112:115], v[40:43]
	v_mfma_f32_16x16x32_f16 v[32:35], v[116:119], v[112:115], v[92:95]
	v_mfma_f32_16x16x32_f16 v[24:27], v[128:131], v[112:115], v[16:19]
	v_or_b32_e32 v114, s2, v120
	v_mfma_f32_16x16x32_f16 v[8:11], v[116:119], v[124:127], v[52:55]
	s_nop 2
	global_load_dwordx4 v[52:55], v[102:103], off offset:48
	global_load_dwordx4 v[64:67], v[102:103], off offset:32
	global_load_dwordx4 v[80:83], v[102:103], off offset:16
	global_load_dwordx4 v[92:95], v[102:103], off
	s_waitcnt vmcnt(0)
	v_cvt_f32_f16_e32 v116, v92
	v_mfma_f32_16x16x32_f16 v[0:3], v[128:131], v[124:127], v[28:31]
	global_load_dwordx4 v[4:7], v[102:103], off offset:112
	global_load_dwordx4 v[16:19], v[102:103], off offset:96
	s_nop 0
	global_load_dwordx4 v[28:31], v[102:103], off offset:80
	global_load_dwordx4 v[40:43], v[102:103], off offset:64
	v_cvt_f32_f16_sdwa v117, v92 dst_sel:DWORD dst_unused:UNUSED_PAD src0_sel:WORD_1
	v_and_or_b32 v104, v74, 15, v123
	v_bfe_u32 v115, v74, 4, 2
	v_ashrrev_i32_e32 v105, 31, v104
	v_lshl_or_b32 v118, v115, 2, v114
	v_lshlrev_b64 v[74:75], 12, v[104:105]
	v_lshlrev_b64 v[102:103], 11, v[104:105]
	v_lshl_add_u64 v[74:75], s[16:17], 0, v[74:75]
	v_lshl_add_u64 v[106:107], s[6:7], 0, v[102:103]
	v_lshlrev_b32_e32 v102, 2, v118
	v_mov_b32_e32 v103, v151
	v_lshl_add_u64 v[108:109], v[74:75], 0, v[102:103]
	v_div_scale_f32 v74, s[6:7], v73, v73, 1.0
	v_rcp_f32_e32 v75, v74
	v_div_scale_f32 v92, s[6:7], v111, v111, 1.0
	v_fma_f32 v103, -v74, v75, 1.0
	v_fmac_f32_e32 v75, v103, v75
	v_div_scale_f32 v103, vcc, 1.0, v73, 1.0
	v_mul_f32_e32 v112, v103, v75
	v_fma_f32 v113, -v74, v112, v103
	v_fmac_f32_e32 v112, v113, v75
	v_fma_f32 v74, -v74, v112, v103
	v_div_fmas_f32 v74, v74, v75, v112
	v_div_fixup_f32 v113, v74, v73, 1.0
	v_div_scale_f32 v73, s[6:7], v72, v72, 1.0
	v_rcp_f32_e32 v74, v73
	s_nop 0
	v_fma_f32 v75, -v73, v74, 1.0
	v_fmac_f32_e32 v74, v75, v74
	v_div_scale_f32 v75, vcc, 1.0, v72, 1.0
	v_mul_f32_e32 v103, v75, v74
	v_fma_f32 v112, -v73, v103, v75
	v_fmac_f32_e32 v103, v112, v74
	v_fma_f32 v73, -v73, v103, v75
	v_div_fmas_f32 v73, v73, v74, v103
	v_div_fixup_f32 v112, v73, v72, 1.0
	global_load_dwordx4 v[72:75], v[108:109], off
	v_rcp_f32_e32 v103, v92
	s_waitcnt vmcnt(0)
	v_pk_fma_f32 v[72:73], v[112:113], v[116:117], v[72:73]
	v_fma_f32 v112, -v92, v103, 1.0
	v_fmac_f32_e32 v103, v112, v103
	v_div_scale_f32 v112, vcc, 1.0, v111, 1.0
	v_mul_f32_e32 v113, v112, v103
	v_fma_f32 v116, -v92, v113, v112
	v_fmac_f32_e32 v113, v116, v103
	v_fma_f32 v92, -v92, v113, v112
	v_div_fmas_f32 v92, v92, v103, v113
	v_div_fixup_f32 v111, v92, v111, 1.0
	v_div_scale_f32 v92, s[6:7], v110, v110, 1.0
	v_rcp_f32_e32 v103, v92
	s_nop 0
	v_fma_f32 v112, -v92, v103, 1.0
	v_fmac_f32_e32 v103, v112, v103
	v_div_scale_f32 v112, vcc, 1.0, v110, 1.0
	v_mul_f32_e32 v113, v112, v103
	v_fma_f32 v116, -v92, v113, v112
	v_fmac_f32_e32 v113, v116, v103
	v_fma_f32 v92, -v92, v113, v112
	v_div_fmas_f32 v92, v92, v103, v113
	v_div_fixup_f32 v110, v92, v110, 1.0
	v_cvt_f32_f16_e32 v92, v93
	v_cvt_f32_f16_sdwa v93, v93 dst_sel:DWORD dst_unused:UNUSED_PAD src0_sel:WORD_1
	s_andn2_b64 vcc, exec, s[4:5]
	v_pk_fma_f32 v[74:75], v[110:111], v[92:93], v[74:75]
	v_cndmask_b32_e64 v92, 0, 1, s[4:5]
	v_cmp_ne_u32_e64 s[42:43], 1, v92
	v_lshlrev_b32_e32 v92, 1, v118
	global_store_dwordx4 v[108:109], v[72:75], off
	s_cbranch_vccnz .LBB0_1438
	v_mov_b32_e32 v93, v151
	v_cvt_pk_f16_f32 v110, v72, v73
	v_cvt_pk_f16_f32 v111, v74, v75
	v_lshl_add_u64 v[112:113], v[106:107], 0, v[92:93]
	global_store_dwordx2 v[112:113], v[110:111], off

; __global__ void __launch_bounds__(256, 2) fwd_megakernel(Params P) {
;   __shared__ __attribute__((aligned(16))) char smem[SMEM_TOTAL];
;   __shared__ uint4 xb_words;
	.amdhsa_kernel _Z14fwd_megakernel6Params
		.amdhsa_group_segment_fixed_size 74064
		.amdhsa_private_segment_fixed_size 0
		.amdhsa_kernarg_size 592
		.amdhsa_user_sgpr_count 2
		.amdhsa_user_sgpr_dispatch_ptr 0
		.amdhsa_user_sgpr_queue_ptr 0
		.amdhsa_user_sgpr_kernarg_segment_ptr 1
		.amdhsa_user_sgpr_dispatch_id 0
		.amdhsa_user_sgpr_kernarg_preload_length 0
		.amdhsa_user_sgpr_kernarg_preload_offset 0
		.amdhsa_user_sgpr_private_segment_size 0
		.amdhsa_uses_dynamic_stack 0
		.amdhsa_enable_private_segment 0
		.amdhsa_system_sgpr_workgroup_id_x 1
		.amdhsa_system_sgpr_workgroup_id_y 0
		.amdhsa_system_sgpr_workgroup_id_z 0
		.amdhsa_system_sgpr_workgroup_info 0
		.amdhsa_system_vgpr_workitem_id 2
		.amdhsa_next_free_vgpr 255
		.amdhsa_next_free_sgpr 102
		.amdhsa_accum_offset 256
		.amdhsa_reserve_vcc 1
		.amdhsa_float_round_mode_32 0
		.amdhsa_float_round_mode_16_64 0
		.amdhsa_float_denorm_mode_32 3
		.amdhsa_float_denorm_mode_16_64 3
		.amdhsa_dx10_clamp 1
		.amdhsa_ieee_mode 1
		.amdhsa_fp16_overflow 0
		.amdhsa_tg_split 0
		.amdhsa_exception_fp_ieee_invalid_op 0
		.amdhsa_exception_fp_denorm_src 0
		.amdhsa_exception_fp_ieee_div_zero 0
		.amdhsa_exception_fp_ieee_overflow 0
		.amdhsa_exception_fp_ieee_underflow 0
		.amdhsa_exception_fp_ieee_inexact 0
		.amdhsa_exception_int_div_zero 0
	.end_amdhsa_kernel

; __global__ void __launch_bounds__(256, 2) fwd_megakernel(Params P) {
;   __shared__ __attribute__((aligned(16))) char smem[SMEM_TOTAL];
;   __shared__ uint4 xb_words;
amdhsa.kernels:
  - .agpr_count:     0
    .args:
      - .offset:         0
        .size:           336
        .value_kind:     by_value
      - .offset:         336
        .size:           4
        .value_kind:     hidden_block_count_x
      - .offset:         340
        .size:           4
        .value_kind:     hidden_block_count_y
      - .offset:         344
        .size:           4
        .value_kind:     hidden_block_count_z
      - .offset:         348
        .size:           2
        .value_kind:     hidden_group_size_x
      - .offset:         350
        .size:           2
        .value_kind:     hidden_group_size_y
      - .offset:         352
        .size:           2
        .value_kind:     hidden_group_size_z
      - .offset:         354
        .size:           2
        .value_kind:     hidden_remainder_x
      - .offset:         356
        .size:           2
        .value_kind:     hidden_remainder_y
      - .offset:         358
        .size:           2
        .value_kind:     hidden_remainder_z
      - .offset:         376
        .size:           8
        .value_kind:     hidden_global_offset_x
      - .offset:         384
        .size:           8
        .value_kind:     hidden_global_offset_y
      - .offset:         392
        .size:           8
        .value_kind:     hidden_global_offset_z
      - .offset:         400
        .size:           2
        .value_kind:     hidden_grid_dims
      - .offset:         424
        .size:           8
        .value_kind:     hidden_multigrid_sync_arg
    .group_segment_fixed_size: 74064
    .kernarg_segment_align: 8
    .kernarg_segment_size: 592
    .language:       OpenCL C
    .language_version:
      - 2
      - 0
    .max_flat_workgroup_size: 256
    .name:           _Z14fwd_megakernel6Params
    .private_segment_fixed_size: 0
    .sgpr_count:     108
    .sgpr_spill_count: 170
    .symbol:         _Z14fwd_megakernel6Params.kd
    .uniform_work_group_size: 1
    .uses_dynamic_stack: false
    .vgpr_count:     255
    .vgpr_spill_count: 0
    .wavefront_size: 64
